# pipelined dil loop + padded dil-4 table + conflict-free K readback swizzle
# baseline (speedup 1.0000x reference)
; #define LAS __attribute__((address_space(3)))
; #define GAS __attribute__((address_space(1)))
; __device__ __forceinline__ void dil_unit(LAS unsigned char* lds, bf16_t* proj, int seq, int hd, int T0, int rho) {
;     int tid_ = threadIdx.x; asm volatile("" : "+v"(tid_));
;     const int tid = tid_, lane = tid & 63, r32 = lane & 31, hi = lane >> 5, wid = __builtin_amdgcn_readfirstlane(tid >> 6);
;     bf16_t* base = proj + (size_t)seq * SEQ * NIN;
;     LAS unsigned char* wbuf = lds + wid * 4096;
;     const LAS unsigned char* vp = wbuf + ((lane >> 4) & 1) * 32 + (lane & 3) * 8 + (4 * hi + ((lane & 15) >> 2)) * 64;
;     const int P0 = T0 + rho;
;     bf16x8 qr[4];
; #pragma unroll
;     for (int ks = 0; ks < 4; ++ks) qr[ks] = *(const GAS bf16x8*)(base + (size_t)(P0 + 16 * r32) * NIN + PC_LQ + hd * 64 + 16 * ks + 8 * hi);
;     f32x16 o0 = {}, o1 = {}; float l = 0.f;
;     const bool bound = (T0 < 1024) || (T0 >= 15360);
; __device__ __forceinline__ void attn_phase(unsigned char* ws, int l, LAS unsigned char* lds, int G) {
;     ...
;         const int sh = bu >> 6, rem = bu & 63, T0 = (rem >> 1) * 512, rho = (rem & 1) * 8 + wid;
.LBB0_554:
	s_lshr_b32 s82, s33, 8
	s_mul_i32 s82, s82, 13
	s_add_i32 s82, s82, s33
	s_ashr_i32 s2, s33, 6
	s_mul_hi_i32 s7, s2, 0x2aaaaaab
	s_lshl_b32 s3, s82, 8
	s_lshr_b32 s8, s7, 31
	s_and_b32 s6, s3, 0x3e00
	s_lshl_b32 s3, s82, 3
	s_add_i32 s7, s7, s8
	s_and_b32 s3, s3, 8
	s_mul_i32 s8, s7, 6
	s_add_i32 s3, s3, s64
	s_sub_i32 s8, s2, s8
	s_mul_hi_i32 s2, s7, 0x6000000
	s_mul_i32 s7, s7, 0x6000000
	v_mov_b32_e32 v2, v154
	s_add_u32 s56, s48, s7
	s_addc_u32 s57, s49, s2
	v_and_b32_e32 v105, 31, v2
	s_add_i32 s76, s3, s6
	v_lshl_add_u32 v3, v105, 4, s76
	v_mov_b64_e32 v[0:1], s[56:57]
	s_lshl_b32 s58, s8, 6
	v_bfe_u32 v106, v2, 5, 1
	v_mad_u64_u32 v[0:1], s[2:3], v3, s65, v[0:1]
	s_ashr_i32 s59, s58, 31
	v_lshl_add_u64 v[0:1], s[58:59], 1, v[0:1]
	v_lshlrev_b32_e32 v80, 4, v106
	v_lshl_add_u64 v[0:1], v[0:1], 0, v[80:81]
	global_load_dwordx4 v[48:51], v[0:1], off offset:1280
	global_load_dwordx4 v[52:55], v[0:1], off offset:1312
	global_load_dwordx4 v[56:59], v[0:1], off offset:1344
	global_load_dwordx4 v[60:63], v[0:1], off offset:1376
	v_readfirstlane_b32 s2, v2
	s_lshl_b32 s2, s2, 6
	s_and_b32 s2, s2, 0xfffff000
	v_lshlrev_b32_e32 v0, 1, v2
	v_lshlrev_b32_e32 v104, 3, v2
	v_lshlrev_b32_e32 v107, 2, v106
	v_lshrrev_b32_e32 v1, 2, v2
	v_and_b32_e32 v103, 63, v2
	v_and_b32_e32 v0, 32, v0
	v_and_b32_e32 v98, 24, v104
	v_and_or_b32 v1, v1, 3, v107
	s_add_i32 s77, s2, 0
	v_lshlrev_b32_e32 v108, 6, v1
	v_lshlrev_b32_e32 v1, 3, v106
	v_add3_u32 v109, s77, v0, v98
	s_addk_i32 s6, 0xc400
	v_lshrrev_b32_e32 v110, 2, v103
	v_lshlrev_b32_e32 v0, 4, v103
	s_mov_b64 s[2:3], -1
	s_cmp_gt_u32 s6, 0xffffc7ff
	v_lshlrev_b32_e32 v100, 1, v98
	s_mul_i32 s6, s8, 0x1c00
	v_lshlrev_b32_e32 v82, 1, v1
	v_or_b32_e32 v111, 16, v110
	v_add_u32_e32 v112, s77, v0
	s_cbranch_scc0 .LBB0_558
	s_movk_i32 s100, 0x1800
	s_add_i32 s101, s6, 0x15c00
	s_lshl_b32 s90, s58, 1
	s_add_u32 s82, s56, s90
	s_addc_u32 s83, s57, 0
	s_add_u32 s82, s82, 0x1200
	s_addc_u32 s83, s83, 0
	s_sub_i32 s90, s76, 64
	s_mul_i32 s90, s90, 0x1800
	s_add_u32 s84, s82, s90
	s_addc_u32 s85, s83, 0
	s_sub_i32 s90, s76, 256
	s_mul_i32 s90, s90, 0x1800
	s_add_u32 s86, s82, s90
	s_addc_u32 s87, s83, 0
	s_sub_i32 s90, s76, 1024
	s_mul_i32 s90, s90, 0x1800
	s_add_u32 s88, s82, s90
	s_addc_u32 s89, s83, 0
	v_lshlrev_b32_e32 v153, 1, v98
	v_mad_u32_u24 v80, v105, s100, v82
	v_mad_u32_u24 v100, v110, s100, v153
	v_add_u32_e32 v149, 0x18000, v100
	v_lshlrev_b32_e32 v83, 2, v105
	v_mad_u32_u24 v83, v83, s100, v82
	v_lshlrev_b32_e32 v101, 2, v110
	v_mad_u32_u24 v101, v101, s100, v153
	v_add_u32_e32 v150, 0x60000, v101
	v_lshlrev_b32_e32 v99, 4, v105
	v_mad_u32_u24 v99, v99, s100, v82
	v_lshlrev_b32_e32 v148, 4, v110
	v_mad_u32_u24 v148, v148, s100, v153
	v_add_u32_e32 v151, 0x180000, v148
	v_lshrrev_b32_e32 v249, 3, v103
	v_and_b32_e32 v250, 7, v103
	v_lshlrev_b32_e32 v250, 4, v250
	v_add_u32_e32 v235, 0, v249
	v_mad_u32_u24 v235, v235, s100, v250
	v_add_u32_e32 v236, 8, v249
	v_mad_u32_u24 v236, v236, s100, v250
	v_add_u32_e32 v237, 16, v249
	v_mad_u32_u24 v237, v237, s100, v250
	v_add_u32_e32 v238, 24, v249
	v_mad_u32_u24 v238, v238, s100, v250
	v_add_u32_e32 v239, 0, v249
	v_lshlrev_b32_e32 v239, 2, v239
	v_mad_u32_u24 v239, v239, s100, v250
	v_add_u32_e32 v240, 8, v249
	v_lshlrev_b32_e32 v240, 2, v240
	v_mad_u32_u24 v240, v240, s100, v250
	v_add_u32_e32 v241, 16, v249
	v_lshlrev_b32_e32 v241, 2, v241
	v_mad_u32_u24 v241, v241, s100, v250
	v_add_u32_e32 v242, 24, v249
	v_lshlrev_b32_e32 v242, 2, v242
	v_mad_u32_u24 v242, v242, s100, v250
	v_add_u32_e32 v243, 0, v249
	v_lshlrev_b32_e32 v243, 4, v243
	v_mad_u32_u24 v243, v243, s100, v250
	v_add_u32_e32 v244, 8, v249
	v_lshlrev_b32_e32 v244, 4, v244
	v_mad_u32_u24 v244, v244, s100, v250
	v_add_u32_e32 v245, 16, v249
	v_lshlrev_b32_e32 v245, 4, v245
	v_mad_u32_u24 v245, v245, s100, v250
	v_add_u32_e32 v246, 24, v249
	v_lshlrev_b32_e32 v246, 4, v246
	v_mad_u32_u24 v246, v246, s100, v250
	v_and_b32_e32 v247, 7, v249
	v_lshlrev_b32_e32 v247, 4, v247
	v_xor_b32_e32 v247, v247, v112
	v_xor_b32_e32 v111, 16, v247
	v_and_b32_e32 v153, 7, v105
	v_lshrrev_b32_e32 v248, 4, v105
	v_xor_b32_e32 v153, v153, v248
	v_or_b32_e32 v248, 0, v106
	v_xor_b32_e32 v248, v248, v153
	v_lshlrev_b32_e32 v248, 4, v248
	v_lshl_add_u32 v248, v105, 7, v248
	v_add_u32_e32 v248, s77, v248
	v_or_b32_e32 v249, 2, v106
	v_xor_b32_e32 v249, v249, v153
	v_lshlrev_b32_e32 v249, 4, v249
	v_lshl_add_u32 v249, v105, 7, v249
	v_add_u32_e32 v249, s77, v249
	v_or_b32_e32 v250, 4, v106
	v_xor_b32_e32 v250, v250, v153
	v_lshlrev_b32_e32 v250, 4, v250
	v_lshl_add_u32 v250, v105, 7, v250
	v_add_u32_e32 v250, s77, v250
	v_or_b32_e32 v251, 6, v106
	v_xor_b32_e32 v251, v251, v153
	v_lshlrev_b32_e32 v251, 4, v251
	v_lshl_add_u32 v251, v105, 7, v251
	v_add_u32_e32 v251, s77, v251
	v_lshlrev_b32_e32 v153, 1, v98
	v_mul_u32_u24_e32 v228, 17, v105
	v_sub_u32_e32 v228, v107, v228
	s_mul_i32 s90, s58, 153
	s_lshr_b32 s90, s90, 1
	s_add_i32 s90, s90, 34876
	v_lshl_add_u32 v228, v228, 2, s90
	v_mul_u32_u24_e32 v229, 5, v105
	v_sub_u32_e32 v229, v107, v229
	v_add_u32_e32 v229, v229, v106
	s_mul_i32 s90, s58, 30
	s_add_i32 s90, s90, 66156
	v_lshl_add_u32 v229, v229, 2, s90
	v_sub_u32_e32 v230, v107, v105
	s_add_i32 s90, s101, 6364
	v_lshl_add_u32 v230, v230, 2, s90
	v_add_u32_e32 v231, v109, v108
	v_mov_b64_e32 v[232:233], 0
	v_mov_b64_e32 v[0:1], 0
	v_mov_b64_e32 v[2:3], 0
	v_mov_b64_e32 v[4:5], 0
	v_mov_b64_e32 v[6:7], 0
	v_mov_b64_e32 v[8:9], 0
	v_mov_b64_e32 v[10:11], 0
	v_mov_b64_e32 v[12:13], 0
	v_mov_b64_e32 v[14:15], 0
	v_mov_b64_e32 v[16:17], 0
	v_mov_b64_e32 v[18:19], 0
	v_mov_b64_e32 v[20:21], 0
	v_mov_b64_e32 v[22:23], 0
	v_mov_b64_e32 v[24:25], 0
	v_mov_b64_e32 v[26:27], 0
	v_mov_b64_e32 v[28:29], 0
	v_mov_b64_e32 v[30:31], 0
	global_load_dwordx4 v[116:119], v235, s[84:85]
	global_load_dwordx4 v[120:123], v236, s[84:85]
	global_load_dwordx4 v[124:127], v237, s[84:85]
	global_load_dwordx4 v[128:131], v238, s[84:85]
	global_load_dwordx4 v[132:135], v100, s[84:85] offset:768
	global_load_dwordx4 v[136:139], v149, s[84:85] offset:768
	global_load_dwordx4 v[140:143], v100, s[84:85] offset:832
	global_load_dwordx4 v[144:147], v149, s[84:85] offset:832
	s_add_u32 s84, s84, 0x30000
	s_addc_u32 s85, s85, 0
	global_load_dwordx4 v[156:159], v235, s[84:85]
	global_load_dwordx4 v[160:163], v236, s[84:85]
	global_load_dwordx4 v[164:167], v237, s[84:85]
	global_load_dwordx4 v[168:171], v238, s[84:85]
	global_load_dwordx4 v[172:175], v100, s[84:85] offset:768
	global_load_dwordx4 v[176:179], v149, s[84:85] offset:768
	global_load_dwordx4 v[180:183], v100, s[84:85] offset:832
	global_load_dwordx4 v[184:187], v149, s[84:85] offset:832
	s_add_u32 s84, s84, 0x30000
	s_addc_u32 s85, s85, 0
	v_mov_b32_e32 v115, v228
	ds_read2_b32 v[32:33], v115 offset0:0 offset1:1
	ds_read2_b32 v[34:35], v115 offset0:2 offset1:3
	ds_read2_b32 v[36:37], v115 offset0:8 offset1:9
	ds_read2_b32 v[38:39], v115 offset0:10 offset1:11
	ds_read2_b32 v[40:41], v115 offset0:17 offset1:18
	ds_read2_b32 v[42:43], v115 offset0:19 offset1:20
	ds_read2_b32 v[44:45], v115 offset0:25 offset1:26
	ds_read2_b32 v[46:47], v115 offset0:27 offset1:28
	s_waitcnt vmcnt(8)
	ds_write_b128 v247, v[116:119]
	ds_write_b128 v247, v[120:123] offset:1024
	ds_write_b128 v111, v[124:127] offset:2048
	ds_write_b128 v111, v[128:131] offset:3072
	ds_read_b128 v[116:119], v248
	ds_read_b128 v[120:123], v249
	ds_read_b128 v[124:127], v250
	ds_read_b128 v[128:131], v251
	ds_write_b128 v112, v[132:135]
	ds_write_b128 v112, v[136:139] offset:1024
	ds_write_b128 v112, v[140:143] offset:2048
	ds_write_b128 v112, v[144:147] offset:3072
	s_waitcnt lgkmcnt(4)
	v_mfma_f32_32x32x16_bf16 v[32:47], v[116:119], v[48:51], v[32:47]
	v_mfma_f32_32x32x16_bf16 v[32:47], v[120:123], v[52:55], v[32:47]
	v_mfma_f32_32x32x16_bf16 v[32:47], v[124:127], v[56:59], v[32:47]
	v_mfma_f32_32x32x16_bf16 v[32:47], v[128:131], v[60:63], v[32:47]
	ds_read2_b32 v[188:189], v115 offset0:34 offset1:35
	ds_read2_b32 v[190:191], v115 offset0:36 offset1:37
	ds_read2_b32 v[192:193], v115 offset0:42 offset1:43
	ds_read2_b32 v[194:195], v115 offset0:44 offset1:45
	ds_read2_b32 v[196:197], v115 offset0:51 offset1:52
	ds_read2_b32 v[198:199], v115 offset0:53 offset1:54
	ds_read2_b32 v[200:201], v115 offset0:59 offset1:60
	ds_read2_b32 v[202:203], v115 offset0:61 offset1:62
	global_load_dwordx4 v[116:119], v235, s[84:85]
	global_load_dwordx4 v[120:123], v236, s[84:85]
	global_load_dwordx4 v[124:127], v237, s[84:85]
	global_load_dwordx4 v[128:131], v238, s[84:85]
	global_load_dwordx4 v[132:135], v100, s[84:85] offset:768
	global_load_dwordx4 v[136:139], v149, s[84:85] offset:768
	global_load_dwordx4 v[140:143], v100, s[84:85] offset:832
	global_load_dwordx4 v[144:147], v149, s[84:85] offset:832
	s_add_u32 s84, s84, 0x30000
	s_addc_u32 s85, s85, 0
	ds_read_b64_tr_b16 v[72:73], v231
	ds_read_b64_tr_b16 v[74:75], v231 offset:512
	ds_read_b64_tr_b16 v[76:77], v231 offset:2048
	ds_read_b64_tr_b16 v[78:79], v231 offset:2560
	ds_read_b64_tr_b16 v[220:221], v231 offset:1024
	ds_read_b64_tr_b16 v[222:223], v231 offset:1536
	ds_read_b64_tr_b16 v[224:225], v231 offset:3072
	ds_read_b64_tr_b16 v[226:227], v231 offset:3584
	s_waitcnt vmcnt(8)
	ds_write_b128 v247, v[156:159]
	ds_write_b128 v247, v[160:163] offset:1024
	ds_write_b128 v111, v[164:167] offset:2048
	ds_write_b128 v111, v[168:171] offset:3072
	ds_read_b128 v[156:159], v248
	ds_read_b128 v[160:163], v249
	ds_read_b128 v[164:167], v250
	ds_read_b128 v[168:171], v251
	ds_write_b128 v112, v[172:175]
	ds_write_b128 v112, v[176:179] offset:1024
	ds_write_b128 v112, v[180:183] offset:2048
	ds_write_b128 v112, v[184:187] offset:3072
	v_exp_f32_e32 v32, v32
	v_exp_f32_e32 v33, v33
	v_exp_f32_e32 v34, v34
	v_exp_f32_e32 v35, v35
	v_exp_f32_e32 v36, v36
	v_exp_f32_e32 v37, v37
	s_waitcnt lgkmcnt(4)
	v_mfma_f32_32x32x16_bf16 v[188:203], v[156:159], v[48:51], v[188:203]
	v_exp_f32_e32 v38, v38
	v_exp_f32_e32 v39, v39
	v_mfma_f32_32x32x16_bf16 v[188:203], v[160:163], v[52:55], v[188:203]
	v_exp_f32_e32 v40, v40
	v_exp_f32_e32 v41, v41
	v_exp_f32_e32 v42, v42
	v_mfma_f32_32x32x16_bf16 v[188:203], v[164:167], v[56:59], v[188:203]
	v_exp_f32_e32 v43, v43
	v_exp_f32_e32 v44, v44
	v_mfma_f32_32x32x16_bf16 v[188:203], v[168:171], v[60:63], v[188:203]
	v_exp_f32_e32 v45, v45
	v_exp_f32_e32 v46, v46
	v_exp_f32_e32 v47, v47
	v_cvt_pk_bf16_f32 v64, v32, v33
	v_cvt_pk_bf16_f32 v65, v34, v35
	v_cvt_pk_bf16_f32 v66, v36, v37
	v_cvt_pk_bf16_f32 v67, v38, v39
	v_cvt_pk_bf16_f32 v68, v40, v41
	v_cvt_pk_bf16_f32 v69, v42, v43
	v_cvt_pk_bf16_f32 v70, v44, v45
	v_cvt_pk_bf16_f32 v71, v46, v47
	v_pk_add_f32 v[232:233], v[232:233], v[32:33]
	v_pk_add_f32 v[232:233], v[232:233], v[34:35]
	v_pk_add_f32 v[232:233], v[232:233], v[36:37]
	v_pk_add_f32 v[232:233], v[232:233], v[38:39]
	v_pk_add_f32 v[232:233], v[232:233], v[40:41]
	v_pk_add_f32 v[232:233], v[232:233], v[42:43]
	v_pk_add_f32 v[232:233], v[232:233], v[44:45]
	v_pk_add_f32 v[232:233], v[232:233], v[46:47]
	ds_read2_b32 v[32:33], v115 offset0:68 offset1:69
	ds_read2_b32 v[34:35], v115 offset0:70 offset1:71
	ds_read2_b32 v[36:37], v115 offset0:76 offset1:77
	ds_read2_b32 v[38:39], v115 offset0:78 offset1:79
	ds_read2_b32 v[40:41], v115 offset0:85 offset1:86
	ds_read2_b32 v[42:43], v115 offset0:87 offset1:88
	ds_read2_b32 v[44:45], v115 offset0:93 offset1:94
	ds_read2_b32 v[46:47], v115 offset0:95 offset1:96
	v_mfma_f32_32x32x16_bf16 v[0:15], v[64:67], v[72:75], v[0:15]
	v_mfma_f32_32x32x16_bf16 v[16:31], v[64:67], v[76:79], v[16:31]
	v_mfma_f32_32x32x16_bf16 v[0:15], v[68:71], v[220:223], v[0:15]
	v_mfma_f32_32x32x16_bf16 v[16:31], v[68:71], v[224:227], v[16:31]
	global_load_dwordx4 v[156:159], v235, s[84:85]
	global_load_dwordx4 v[160:163], v236, s[84:85]
	global_load_dwordx4 v[164:167], v237, s[84:85]
	global_load_dwordx4 v[168:171], v238, s[84:85]
	global_load_dwordx4 v[172:175], v100, s[84:85] offset:768
	global_load_dwordx4 v[176:179], v149, s[84:85] offset:768
	global_load_dwordx4 v[180:183], v100, s[84:85] offset:832
	global_load_dwordx4 v[184:187], v149, s[84:85] offset:832
	s_add_u32 s84, s84, 0x30000
	s_addc_u32 s85, s85, 0
	ds_read_b64_tr_b16 v[72:73], v231
	ds_read_b64_tr_b16 v[74:75], v231 offset:512
	ds_read_b64_tr_b16 v[76:77], v231 offset:2048
	ds_read_b64_tr_b16 v[78:79], v231 offset:2560
	ds_read_b64_tr_b16 v[220:221], v231 offset:1024
	ds_read_b64_tr_b16 v[222:223], v231 offset:1536
	ds_read_b64_tr_b16 v[224:225], v231 offset:3072
	ds_read_b64_tr_b16 v[226:227], v231 offset:3584
	s_waitcnt vmcnt(8)
	ds_write_b128 v247, v[116:119]
	ds_write_b128 v247, v[120:123] offset:1024
	ds_write_b128 v111, v[124:127] offset:2048
	ds_write_b128 v111, v[128:131] offset:3072
	ds_read_b128 v[116:119], v248
	ds_read_b128 v[120:123], v249
	ds_read_b128 v[124:127], v250
	ds_read_b128 v[128:131], v251
	ds_write_b128 v112, v[132:135]
	ds_write_b128 v112, v[136:139] offset:1024
	ds_write_b128 v112, v[140:143] offset:2048
	ds_write_b128 v112, v[144:147] offset:3072
	v_exp_f32_e32 v188, v188
	v_exp_f32_e32 v189, v189
	v_exp_f32_e32 v190, v190
	v_exp_f32_e32 v191, v191
	v_exp_f32_e32 v192, v192
	v_exp_f32_e32 v193, v193
	s_waitcnt lgkmcnt(4)
	v_mfma_f32_32x32x16_bf16 v[32:47], v[116:119], v[48:51], v[32:47]
	v_exp_f32_e32 v194, v194
	v_exp_f32_e32 v195, v195
	v_mfma_f32_32x32x16_bf16 v[32:47], v[120:123], v[52:55], v[32:47]
	v_exp_f32_e32 v196, v196
	v_exp_f32_e32 v197, v197
	v_exp_f32_e32 v198, v198
	v_mfma_f32_32x32x16_bf16 v[32:47], v[124:127], v[56:59], v[32:47]
	v_exp_f32_e32 v199, v199
	v_exp_f32_e32 v200, v200
	v_mfma_f32_32x32x16_bf16 v[32:47], v[128:131], v[60:63], v[32:47]
	v_exp_f32_e32 v201, v201
	v_exp_f32_e32 v202, v202
	v_exp_f32_e32 v203, v203
	v_cvt_pk_bf16_f32 v64, v188, v189
	v_cvt_pk_bf16_f32 v65, v190, v191
	v_cvt_pk_bf16_f32 v66, v192, v193
	v_cvt_pk_bf16_f32 v67, v194, v195
	v_cvt_pk_bf16_f32 v68, v196, v197
	v_cvt_pk_bf16_f32 v69, v198, v199
	v_cvt_pk_bf16_f32 v70, v200, v201
	v_cvt_pk_bf16_f32 v71, v202, v203
	v_pk_add_f32 v[232:233], v[232:233], v[188:189]
	v_pk_add_f32 v[232:233], v[232:233], v[190:191]
	v_pk_add_f32 v[232:233], v[232:233], v[192:193]
	v_pk_add_f32 v[232:233], v[232:233], v[194:195]
	v_pk_add_f32 v[232:233], v[232:233], v[196:197]
	v_pk_add_f32 v[232:233], v[232:233], v[198:199]
	v_pk_add_f32 v[232:233], v[232:233], v[200:201]
	v_pk_add_f32 v[232:233], v[232:233], v[202:203]
	ds_read2_b32 v[188:189], v115 offset0:102 offset1:103
	ds_read2_b32 v[190:191], v115 offset0:104 offset1:105
	ds_read2_b32 v[192:193], v115 offset0:110 offset1:111
	ds_read2_b32 v[194:195], v115 offset0:112 offset1:113
	ds_read2_b32 v[196:197], v115 offset0:119 offset1:120
	ds_read2_b32 v[198:199], v115 offset0:121 offset1:122
	ds_read2_b32 v[200:201], v115 offset0:127 offset1:128
	ds_read2_b32 v[202:203], v115 offset0:129 offset1:130
	v_mfma_f32_32x32x16_bf16 v[0:15], v[64:67], v[72:75], v[0:15]
	v_mfma_f32_32x32x16_bf16 v[16:31], v[64:67], v[76:79], v[16:31]
	v_mfma_f32_32x32x16_bf16 v[0:15], v[68:71], v[220:223], v[0:15]
	v_mfma_f32_32x32x16_bf16 v[16:31], v[68:71], v[224:227], v[16:31]
	global_load_dwordx4 v[116:119], v235, s[84:85]
	global_load_dwordx4 v[120:123], v236, s[84:85]
	global_load_dwordx4 v[124:127], v237, s[84:85]
	global_load_dwordx4 v[128:131], v238, s[84:85]
	global_load_dwordx4 v[132:135], v100, s[84:85] offset:768
	global_load_dwordx4 v[136:139], v149, s[84:85] offset:768
	global_load_dwordx4 v[140:143], v100, s[84:85] offset:832
	global_load_dwordx4 v[144:147], v149, s[84:85] offset:832
	s_add_u32 s84, s84, 0x30000
	s_addc_u32 s85, s85, 0
	ds_read_b64_tr_b16 v[72:73], v231
	ds_read_b64_tr_b16 v[74:75], v231 offset:512
	ds_read_b64_tr_b16 v[76:77], v231 offset:2048
	ds_read_b64_tr_b16 v[78:79], v231 offset:2560
	ds_read_b64_tr_b16 v[220:221], v231 offset:1024
	ds_read_b64_tr_b16 v[222:223], v231 offset:1536
	ds_read_b64_tr_b16 v[224:225], v231 offset:3072
	ds_read_b64_tr_b16 v[226:227], v231 offset:3584
	s_waitcnt vmcnt(8)
	ds_write_b128 v247, v[156:159]
	ds_write_b128 v247, v[160:163] offset:1024
	ds_write_b128 v111, v[164:167] offset:2048
	ds_write_b128 v111, v[168:171] offset:3072
	ds_read_b128 v[156:159], v248
	ds_read_b128 v[160:163], v249
	ds_read_b128 v[164:167], v250
	ds_read_b128 v[168:171], v251
	ds_write_b128 v112, v[172:175]
	ds_write_b128 v112, v[176:179] offset:1024
	ds_write_b128 v112, v[180:183] offset:2048
	ds_write_b128 v112, v[184:187] offset:3072
	v_exp_f32_e32 v32, v32
	v_exp_f32_e32 v33, v33
	v_exp_f32_e32 v34, v34
	v_exp_f32_e32 v35, v35
	v_exp_f32_e32 v36, v36
	v_exp_f32_e32 v37, v37
	s_waitcnt lgkmcnt(4)
	v_mfma_f32_32x32x16_bf16 v[188:203], v[156:159], v[48:51], v[188:203]
	v_exp_f32_e32 v38, v38
	v_exp_f32_e32 v39, v39
	v_mfma_f32_32x32x16_bf16 v[188:203], v[160:163], v[52:55], v[188:203]
	v_exp_f32_e32 v40, v40
	v_exp_f32_e32 v41, v41
	v_exp_f32_e32 v42, v42
	v_mfma_f32_32x32x16_bf16 v[188:203], v[164:167], v[56:59], v[188:203]
	v_exp_f32_e32 v43, v43
	v_exp_f32_e32 v44, v44
	v_mfma_f32_32x32x16_bf16 v[188:203], v[168:171], v[60:63], v[188:203]
	v_exp_f32_e32 v45, v45
	v_exp_f32_e32 v46, v46
	v_exp_f32_e32 v47, v47
	v_cvt_pk_bf16_f32 v64, v32, v33
	v_cvt_pk_bf16_f32 v65, v34, v35
	v_cvt_pk_bf16_f32 v66, v36, v37
	v_cvt_pk_bf16_f32 v67, v38, v39
	v_cvt_pk_bf16_f32 v68, v40, v41
	v_cvt_pk_bf16_f32 v69, v42, v43
	v_cvt_pk_bf16_f32 v70, v44, v45
	v_cvt_pk_bf16_f32 v71, v46, v47
	v_pk_add_f32 v[232:233], v[232:233], v[32:33]
	v_pk_add_f32 v[232:233], v[232:233], v[34:35]
	v_pk_add_f32 v[232:233], v[232:233], v[36:37]
	v_pk_add_f32 v[232:233], v[232:233], v[38:39]
	v_pk_add_f32 v[232:233], v[232:233], v[40:41]
	v_pk_add_f32 v[232:233], v[232:233], v[42:43]
	v_pk_add_f32 v[232:233], v[232:233], v[44:45]
	v_pk_add_f32 v[232:233], v[232:233], v[46:47]
	ds_read2_b32 v[32:33], v115 offset0:136 offset1:137
	ds_read2_b32 v[34:35], v115 offset0:138 offset1:139
	ds_read2_b32 v[36:37], v115 offset0:144 offset1:145
	ds_read2_b32 v[38:39], v115 offset0:146 offset1:147
	ds_read2_b32 v[40:41], v115 offset0:153 offset1:154
	ds_read2_b32 v[42:43], v115 offset0:155 offset1:156
	ds_read2_b32 v[44:45], v115 offset0:161 offset1:162
	ds_read2_b32 v[46:47], v115 offset0:163 offset1:164
	v_mfma_f32_32x32x16_bf16 v[0:15], v[64:67], v[72:75], v[0:15]
	v_mfma_f32_32x32x16_bf16 v[16:31], v[64:67], v[76:79], v[16:31]
	v_mfma_f32_32x32x16_bf16 v[0:15], v[68:71], v[220:223], v[0:15]
	v_mfma_f32_32x32x16_bf16 v[16:31], v[68:71], v[224:227], v[16:31]
	global_load_dwordx4 v[156:159], v235, s[84:85]
	global_load_dwordx4 v[160:163], v236, s[84:85]
	global_load_dwordx4 v[164:167], v237, s[84:85]
	global_load_dwordx4 v[168:171], v238, s[84:85]
	global_load_dwordx4 v[172:175], v100, s[84:85] offset:768
	global_load_dwordx4 v[176:179], v149, s[84:85] offset:768
	global_load_dwordx4 v[180:183], v100, s[84:85] offset:832
	global_load_dwordx4 v[184:187], v149, s[84:85] offset:832
	s_add_u32 s84, s84, 0x30000
	s_addc_u32 s85, s85, 0
	ds_read_b64_tr_b16 v[72:73], v231
	ds_read_b64_tr_b16 v[74:75], v231 offset:512
	ds_read_b64_tr_b16 v[76:77], v231 offset:2048
	ds_read_b64_tr_b16 v[78:79], v231 offset:2560
	ds_read_b64_tr_b16 v[220:221], v231 offset:1024
	ds_read_b64_tr_b16 v[222:223], v231 offset:1536
	ds_read_b64_tr_b16 v[224:225], v231 offset:3072
	ds_read_b64_tr_b16 v[226:227], v231 offset:3584
	s_waitcnt vmcnt(8)
	ds_write_b128 v247, v[116:119]
	ds_write_b128 v247, v[120:123] offset:1024
	ds_write_b128 v111, v[124:127] offset:2048
	ds_write_b128 v111, v[128:131] offset:3072
	ds_read_b128 v[116:119], v248
	ds_read_b128 v[120:123], v249
	ds_read_b128 v[124:127], v250
	ds_read_b128 v[128:131], v251
	ds_write_b128 v112, v[132:135]
	ds_write_b128 v112, v[136:139] offset:1024
	ds_write_b128 v112, v[140:143] offset:2048
	ds_write_b128 v112, v[144:147] offset:3072
	v_exp_f32_e32 v188, v188
	v_exp_f32_e32 v189, v189
	v_exp_f32_e32 v190, v190
	v_exp_f32_e32 v191, v191
	v_exp_f32_e32 v192, v192
	v_exp_f32_e32 v193, v193
	s_waitcnt lgkmcnt(4)
	v_mfma_f32_32x32x16_bf16 v[32:47], v[116:119], v[48:51], v[32:47]
	v_exp_f32_e32 v194, v194
	v_exp_f32_e32 v195, v195
	v_mfma_f32_32x32x16_bf16 v[32:47], v[120:123], v[52:55], v[32:47]
	v_exp_f32_e32 v196, v196
	v_exp_f32_e32 v197, v197
	v_exp_f32_e32 v198, v198
	v_mfma_f32_32x32x16_bf16 v[32:47], v[124:127], v[56:59], v[32:47]
	v_exp_f32_e32 v199, v199
	v_exp_f32_e32 v200, v200
	v_mfma_f32_32x32x16_bf16 v[32:47], v[128:131], v[60:63], v[32:47]
	v_exp_f32_e32 v201, v201
	v_exp_f32_e32 v202, v202
	v_exp_f32_e32 v203, v203
	v_cvt_pk_bf16_f32 v64, v188, v189
	v_cvt_pk_bf16_f32 v65, v190, v191
	v_cvt_pk_bf16_f32 v66, v192, v193
	v_cvt_pk_bf16_f32 v67, v194, v195
	v_cvt_pk_bf16_f32 v68, v196, v197
	v_cvt_pk_bf16_f32 v69, v198, v199
	v_cvt_pk_bf16_f32 v70, v200, v201
	v_cvt_pk_bf16_f32 v71, v202, v203
	v_pk_add_f32 v[232:233], v[232:233], v[188:189]
	v_pk_add_f32 v[232:233], v[232:233], v[190:191]
	v_pk_add_f32 v[232:233], v[232:233], v[192:193]
	v_pk_add_f32 v[232:233], v[232:233], v[194:195]
	v_pk_add_f32 v[232:233], v[232:233], v[196:197]
	v_pk_add_f32 v[232:233], v[232:233], v[198:199]
	v_pk_add_f32 v[232:233], v[232:233], v[200:201]
	v_pk_add_f32 v[232:233], v[232:233], v[202:203]
	ds_read2_b32 v[188:189], v115 offset0:170 offset1:171
	ds_read2_b32 v[190:191], v115 offset0:172 offset1:173
	ds_read2_b32 v[192:193], v115 offset0:178 offset1:179
	ds_read2_b32 v[194:195], v115 offset0:180 offset1:181
	ds_read2_b32 v[196:197], v115 offset0:187 offset1:188
	ds_read2_b32 v[198:199], v115 offset0:189 offset1:190
	ds_read2_b32 v[200:201], v115 offset0:195 offset1:196
	ds_read2_b32 v[202:203], v115 offset0:197 offset1:198
	v_mfma_f32_32x32x16_bf16 v[0:15], v[64:67], v[72:75], v[0:15]
	v_mfma_f32_32x32x16_bf16 v[16:31], v[64:67], v[76:79], v[16:31]
	v_mfma_f32_32x32x16_bf16 v[0:15], v[68:71], v[220:223], v[0:15]
	v_mfma_f32_32x32x16_bf16 v[16:31], v[68:71], v[224:227], v[16:31]
	global_load_dwordx4 v[116:119], v235, s[84:85]
	global_load_dwordx4 v[120:123], v236, s[84:85]
	global_load_dwordx4 v[124:127], v237, s[84:85]
	global_load_dwordx4 v[128:131], v238, s[84:85]
	global_load_dwordx4 v[132:135], v100, s[84:85] offset:768
	global_load_dwordx4 v[136:139], v149, s[84:85] offset:768
	global_load_dwordx4 v[140:143], v100, s[84:85] offset:832
	global_load_dwordx4 v[144:147], v149, s[84:85] offset:832
	s_add_u32 s84, s84, 0x30000
	s_addc_u32 s85, s85, 0
	ds_read_b64_tr_b16 v[72:73], v231
	ds_read_b64_tr_b16 v[74:75], v231 offset:512
	ds_read_b64_tr_b16 v[76:77], v231 offset:2048
	ds_read_b64_tr_b16 v[78:79], v231 offset:2560
	ds_read_b64_tr_b16 v[220:221], v231 offset:1024
	ds_read_b64_tr_b16 v[222:223], v231 offset:1536
	ds_read_b64_tr_b16 v[224:225], v231 offset:3072
	ds_read_b64_tr_b16 v[226:227], v231 offset:3584
	s_waitcnt vmcnt(8)
	ds_write_b128 v247, v[156:159]
	ds_write_b128 v247, v[160:163] offset:1024
	ds_write_b128 v111, v[164:167] offset:2048
	ds_write_b128 v111, v[168:171] offset:3072
	ds_read_b128 v[156:159], v248
	ds_read_b128 v[160:163], v249
	ds_read_b128 v[164:167], v250
	ds_read_b128 v[168:171], v251
	ds_write_b128 v112, v[172:175]
	ds_write_b128 v112, v[176:179] offset:1024
	ds_write_b128 v112, v[180:183] offset:2048
	ds_write_b128 v112, v[184:187] offset:3072
	v_exp_f32_e32 v32, v32
	v_exp_f32_e32 v33, v33
	v_exp_f32_e32 v34, v34
	v_exp_f32_e32 v35, v35
	v_exp_f32_e32 v36, v36
	v_exp_f32_e32 v37, v37
	s_waitcnt lgkmcnt(4)
	v_mfma_f32_32x32x16_bf16 v[188:203], v[156:159], v[48:51], v[188:203]
	v_exp_f32_e32 v38, v38
	v_exp_f32_e32 v39, v39
	v_mfma_f32_32x32x16_bf16 v[188:203], v[160:163], v[52:55], v[188:203]
	v_exp_f32_e32 v40, v40
	v_exp_f32_e32 v41, v41
	v_exp_f32_e32 v42, v42
	v_mfma_f32_32x32x16_bf16 v[188:203], v[164:167], v[56:59], v[188:203]
	v_exp_f32_e32 v43, v43
	v_exp_f32_e32 v44, v44
	v_mfma_f32_32x32x16_bf16 v[188:203], v[168:171], v[60:63], v[188:203]
	v_exp_f32_e32 v45, v45
	v_exp_f32_e32 v46, v46
	v_exp_f32_e32 v47, v47
	v_cvt_pk_bf16_f32 v64, v32, v33
	v_cvt_pk_bf16_f32 v65, v34, v35
	v_cvt_pk_bf16_f32 v66, v36, v37
	v_cvt_pk_bf16_f32 v67, v38, v39
	v_cvt_pk_bf16_f32 v68, v40, v41
	v_cvt_pk_bf16_f32 v69, v42, v43
	v_cvt_pk_bf16_f32 v70, v44, v45
	v_cvt_pk_bf16_f32 v71, v46, v47
	v_pk_add_f32 v[232:233], v[232:233], v[32:33]
	v_pk_add_f32 v[232:233], v[232:233], v[34:35]
	v_pk_add_f32 v[232:233], v[232:233], v[36:37]
	v_pk_add_f32 v[232:233], v[232:233], v[38:39]
	v_pk_add_f32 v[232:233], v[232:233], v[40:41]
	v_pk_add_f32 v[232:233], v[232:233], v[42:43]
	v_pk_add_f32 v[232:233], v[232:233], v[44:45]
	v_pk_add_f32 v[232:233], v[232:233], v[46:47]
	ds_read2_b32 v[32:33], v115 offset0:204 offset1:205
	ds_read2_b32 v[34:35], v115 offset0:206 offset1:207
	ds_read2_b32 v[36:37], v115 offset0:212 offset1:213
	ds_read2_b32 v[38:39], v115 offset0:214 offset1:215
	ds_read2_b32 v[40:41], v115 offset0:221 offset1:222
	ds_read2_b32 v[42:43], v115 offset0:223 offset1:224
	ds_read2_b32 v[44:45], v115 offset0:229 offset1:230
	ds_read2_b32 v[46:47], v115 offset0:231 offset1:232
	v_mfma_f32_32x32x16_bf16 v[0:15], v[64:67], v[72:75], v[0:15]
	v_mfma_f32_32x32x16_bf16 v[16:31], v[64:67], v[76:79], v[16:31]
	v_mfma_f32_32x32x16_bf16 v[0:15], v[68:71], v[220:223], v[0:15]
	v_mfma_f32_32x32x16_bf16 v[16:31], v[68:71], v[224:227], v[16:31]
	global_load_dwordx4 v[156:159], v235, s[84:85]
	global_load_dwordx4 v[160:163], v236, s[84:85]
	global_load_dwordx4 v[164:167], v237, s[84:85]
	global_load_dwordx4 v[168:171], v238, s[84:85]
	global_load_dwordx4 v[172:175], v100, s[84:85] offset:768
	global_load_dwordx4 v[176:179], v149, s[84:85] offset:768
	global_load_dwordx4 v[180:183], v100, s[84:85] offset:832
	global_load_dwordx4 v[184:187], v149, s[84:85] offset:832
	s_add_u32 s84, s84, 0x30000
	s_addc_u32 s85, s85, 0
	ds_read_b64_tr_b16 v[72:73], v231
	ds_read_b64_tr_b16 v[74:75], v231 offset:512
	ds_read_b64_tr_b16 v[76:77], v231 offset:2048
	ds_read_b64_tr_b16 v[78:79], v231 offset:2560
	ds_read_b64_tr_b16 v[220:221], v231 offset:1024
	ds_read_b64_tr_b16 v[222:223], v231 offset:1536
	ds_read_b64_tr_b16 v[224:225], v231 offset:3072
	ds_read_b64_tr_b16 v[226:227], v231 offset:3584
	s_waitcnt vmcnt(8)
	ds_write_b128 v247, v[116:119]
	ds_write_b128 v247, v[120:123] offset:1024
	ds_write_b128 v111, v[124:127] offset:2048
	ds_write_b128 v111, v[128:131] offset:3072
	ds_read_b128 v[116:119], v248
	ds_read_b128 v[120:123], v249
	ds_read_b128 v[124:127], v250
	ds_read_b128 v[128:131], v251
	ds_write_b128 v112, v[132:135]
	ds_write_b128 v112, v[136:139] offset:1024
	ds_write_b128 v112, v[140:143] offset:2048
	ds_write_b128 v112, v[144:147] offset:3072
	v_exp_f32_e32 v188, v188
	v_exp_f32_e32 v189, v189
	v_exp_f32_e32 v190, v190
	v_exp_f32_e32 v191, v191
	v_exp_f32_e32 v192, v192
	v_exp_f32_e32 v193, v193
	s_waitcnt lgkmcnt(4)
	v_mfma_f32_32x32x16_bf16 v[32:47], v[116:119], v[48:51], v[32:47]
	v_exp_f32_e32 v194, v194
	v_exp_f32_e32 v195, v195
	v_mfma_f32_32x32x16_bf16 v[32:47], v[120:123], v[52:55], v[32:47]
	v_exp_f32_e32 v196, v196
	v_exp_f32_e32 v197, v197
	v_exp_f32_e32 v198, v198
	v_mfma_f32_32x32x16_bf16 v[32:47], v[124:127], v[56:59], v[32:47]
	v_exp_f32_e32 v199, v199
	v_exp_f32_e32 v200, v200
	v_mfma_f32_32x32x16_bf16 v[32:47], v[128:131], v[60:63], v[32:47]
	v_exp_f32_e32 v201, v201
	v_exp_f32_e32 v202, v202
	v_exp_f32_e32 v203, v203
	v_cvt_pk_bf16_f32 v64, v188, v189
	v_cvt_pk_bf16_f32 v65, v190, v191
	v_cvt_pk_bf16_f32 v66, v192, v193
	v_cvt_pk_bf16_f32 v67, v194, v195
	v_cvt_pk_bf16_f32 v68, v196, v197
	v_cvt_pk_bf16_f32 v69, v198, v199
	v_cvt_pk_bf16_f32 v70, v200, v201
	v_cvt_pk_bf16_f32 v71, v202, v203
	v_pk_add_f32 v[232:233], v[232:233], v[188:189]
	v_pk_add_f32 v[232:233], v[232:233], v[190:191]
	v_pk_add_f32 v[232:233], v[232:233], v[192:193]
	v_pk_add_f32 v[232:233], v[232:233], v[194:195]
	v_pk_add_f32 v[232:233], v[232:233], v[196:197]
	v_pk_add_f32 v[232:233], v[232:233], v[198:199]
	v_pk_add_f32 v[232:233], v[232:233], v[200:201]
	v_pk_add_f32 v[232:233], v[232:233], v[202:203]
	v_add_u32_e32 v115, 952, v115
	ds_read2_b32 v[188:189], v115 offset0:0 offset1:1
	ds_read2_b32 v[190:191], v115 offset0:2 offset1:3
	ds_read2_b32 v[192:193], v115 offset0:8 offset1:9
	ds_read2_b32 v[194:195], v115 offset0:10 offset1:11
	ds_read2_b32 v[196:197], v115 offset0:17 offset1:18
	ds_read2_b32 v[198:199], v115 offset0:19 offset1:20
	ds_read2_b32 v[200:201], v115 offset0:25 offset1:26
	ds_read2_b32 v[202:203], v115 offset0:27 offset1:28
	v_mfma_f32_32x32x16_bf16 v[0:15], v[64:67], v[72:75], v[0:15]
	v_mfma_f32_32x32x16_bf16 v[16:31], v[64:67], v[76:79], v[16:31]
	v_mfma_f32_32x32x16_bf16 v[0:15], v[68:71], v[220:223], v[0:15]
	v_mfma_f32_32x32x16_bf16 v[16:31], v[68:71], v[224:227], v[16:31]
	global_load_dwordx4 v[116:119], v235, s[84:85]
	global_load_dwordx4 v[120:123], v236, s[84:85]
	global_load_dwordx4 v[124:127], v237, s[84:85]
	global_load_dwordx4 v[128:131], v238, s[84:85]
	global_load_dwordx4 v[132:135], v100, s[84:85] offset:768
	global_load_dwordx4 v[136:139], v149, s[84:85] offset:768
	global_load_dwordx4 v[140:143], v100, s[84:85] offset:832
	global_load_dwordx4 v[144:147], v149, s[84:85] offset:832
	s_add_u32 s84, s84, 0x30000
	s_addc_u32 s85, s85, 0
	ds_read_b64_tr_b16 v[72:73], v231
	ds_read_b64_tr_b16 v[74:75], v231 offset:512
	ds_read_b64_tr_b16 v[76:77], v231 offset:2048
	ds_read_b64_tr_b16 v[78:79], v231 offset:2560
	ds_read_b64_tr_b16 v[220:221], v231 offset:1024
	ds_read_b64_tr_b16 v[222:223], v231 offset:1536
	ds_read_b64_tr_b16 v[224:225], v231 offset:3072
	ds_read_b64_tr_b16 v[226:227], v231 offset:3584
	s_waitcnt vmcnt(8)
	ds_write_b128 v247, v[156:159]
	ds_write_b128 v247, v[160:163] offset:1024
	ds_write_b128 v111, v[164:167] offset:2048
	ds_write_b128 v111, v[168:171] offset:3072
	ds_read_b128 v[156:159], v248
	ds_read_b128 v[160:163], v249
	ds_read_b128 v[164:167], v250
	ds_read_b128 v[168:171], v251
	ds_write_b128 v112, v[172:175]
	ds_write_b128 v112, v[176:179] offset:1024
	ds_write_b128 v112, v[180:183] offset:2048
	ds_write_b128 v112, v[184:187] offset:3072
	v_exp_f32_e32 v32, v32
	v_exp_f32_e32 v33, v33
	v_exp_f32_e32 v34, v34
	v_exp_f32_e32 v35, v35
	v_exp_f32_e32 v36, v36
	v_exp_f32_e32 v37, v37
	s_waitcnt lgkmcnt(4)
	v_mfma_f32_32x32x16_bf16 v[188:203], v[156:159], v[48:51], v[188:203]
	v_exp_f32_e32 v38, v38
	v_exp_f32_e32 v39, v39
	v_mfma_f32_32x32x16_bf16 v[188:203], v[160:163], v[52:55], v[188:203]
	v_exp_f32_e32 v40, v40
	v_exp_f32_e32 v41, v41
	v_exp_f32_e32 v42, v42
	v_mfma_f32_32x32x16_bf16 v[188:203], v[164:167], v[56:59], v[188:203]
	v_exp_f32_e32 v43, v43
	v_exp_f32_e32 v44, v44
	v_mfma_f32_32x32x16_bf16 v[188:203], v[168:171], v[60:63], v[188:203]
	v_exp_f32_e32 v45, v45
	v_exp_f32_e32 v46, v46
	v_exp_f32_e32 v47, v47
	v_cvt_pk_bf16_f32 v64, v32, v33
	v_cvt_pk_bf16_f32 v65, v34, v35
	v_cvt_pk_bf16_f32 v66, v36, v37
	v_cvt_pk_bf16_f32 v67, v38, v39
	v_cvt_pk_bf16_f32 v68, v40, v41
	v_cvt_pk_bf16_f32 v69, v42, v43
	v_cvt_pk_bf16_f32 v70, v44, v45
	v_cvt_pk_bf16_f32 v71, v46, v47
	v_pk_add_f32 v[232:233], v[232:233], v[32:33]
	v_pk_add_f32 v[232:233], v[232:233], v[34:35]
	v_pk_add_f32 v[232:233], v[232:233], v[36:37]
	v_pk_add_f32 v[232:233], v[232:233], v[38:39]
	v_pk_add_f32 v[232:233], v[232:233], v[40:41]
	v_pk_add_f32 v[232:233], v[232:233], v[42:43]
	v_pk_add_f32 v[232:233], v[232:233], v[44:45]
	v_pk_add_f32 v[232:233], v[232:233], v[46:47]
	ds_read2_b32 v[32:33], v115 offset0:34 offset1:35
	ds_read2_b32 v[34:35], v115 offset0:36 offset1:37
	ds_read2_b32 v[36:37], v115 offset0:42 offset1:43
	ds_read2_b32 v[38:39], v115 offset0:44 offset1:45
	ds_read2_b32 v[40:41], v115 offset0:51 offset1:52
	ds_read2_b32 v[42:43], v115 offset0:53 offset1:54
	ds_read2_b32 v[44:45], v115 offset0:59 offset1:60
	ds_read2_b32 v[46:47], v115 offset0:61 offset1:62
	v_mfma_f32_32x32x16_bf16 v[0:15], v[64:67], v[72:75], v[0:15]
	v_mfma_f32_32x32x16_bf16 v[16:31], v[64:67], v[76:79], v[16:31]
	v_mfma_f32_32x32x16_bf16 v[0:15], v[68:71], v[220:223], v[0:15]
	v_mfma_f32_32x32x16_bf16 v[16:31], v[68:71], v[224:227], v[16:31]
	global_load_dwordx4 v[156:159], v235, s[84:85]
	global_load_dwordx4 v[160:163], v236, s[84:85]
	global_load_dwordx4 v[164:167], v237, s[84:85]
	global_load_dwordx4 v[168:171], v238, s[84:85]
	global_load_dwordx4 v[172:175], v100, s[84:85] offset:768
	global_load_dwordx4 v[176:179], v149, s[84:85] offset:768
	global_load_dwordx4 v[180:183], v100, s[84:85] offset:832
	global_load_dwordx4 v[184:187], v149, s[84:85] offset:832
	s_add_u32 s84, s84, 0x30000
	s_addc_u32 s85, s85, 0
	ds_read_b64_tr_b16 v[72:73], v231
	ds_read_b64_tr_b16 v[74:75], v231 offset:512
	ds_read_b64_tr_b16 v[76:77], v231 offset:2048
	ds_read_b64_tr_b16 v[78:79], v231 offset:2560
	ds_read_b64_tr_b16 v[220:221], v231 offset:1024
	ds_read_b64_tr_b16 v[222:223], v231 offset:1536
	ds_read_b64_tr_b16 v[224:225], v231 offset:3072
	ds_read_b64_tr_b16 v[226:227], v231 offset:3584
	s_waitcnt vmcnt(8)
	ds_write_b128 v247, v[116:119]
	ds_write_b128 v247, v[120:123] offset:1024
	ds_write_b128 v111, v[124:127] offset:2048
	ds_write_b128 v111, v[128:131] offset:3072
	ds_read_b128 v[116:119], v248
	ds_read_b128 v[120:123], v249
	ds_read_b128 v[124:127], v250
	ds_read_b128 v[128:131], v251
	ds_write_b128 v112, v[132:135]
	ds_write_b128 v112, v[136:139] offset:1024
	ds_write_b128 v112, v[140:143] offset:2048
	ds_write_b128 v112, v[144:147] offset:3072
	v_exp_f32_e32 v188, v188
	v_exp_f32_e32 v189, v189
	v_exp_f32_e32 v190, v190
	v_exp_f32_e32 v191, v191
	v_exp_f32_e32 v192, v192
	v_exp_f32_e32 v193, v193
	s_waitcnt lgkmcnt(4)
	v_mfma_f32_32x32x16_bf16 v[32:47], v[116:119], v[48:51], v[32:47]
	v_exp_f32_e32 v194, v194
	v_exp_f32_e32 v195, v195
	v_mfma_f32_32x32x16_bf16 v[32:47], v[120:123], v[52:55], v[32:47]
	v_exp_f32_e32 v196, v196
	v_exp_f32_e32 v197, v197
	v_exp_f32_e32 v198, v198
	v_mfma_f32_32x32x16_bf16 v[32:47], v[124:127], v[56:59], v[32:47]
	v_exp_f32_e32 v199, v199
	v_exp_f32_e32 v200, v200
	v_mfma_f32_32x32x16_bf16 v[32:47], v[128:131], v[60:63], v[32:47]
	v_exp_f32_e32 v201, v201
	v_exp_f32_e32 v202, v202
	v_exp_f32_e32 v203, v203
	v_cvt_pk_bf16_f32 v64, v188, v189
	v_cvt_pk_bf16_f32 v65, v190, v191
	v_cvt_pk_bf16_f32 v66, v192, v193
	v_cvt_pk_bf16_f32 v67, v194, v195
	v_cvt_pk_bf16_f32 v68, v196, v197
	v_cvt_pk_bf16_f32 v69, v198, v199
	v_cvt_pk_bf16_f32 v70, v200, v201
	v_cvt_pk_bf16_f32 v71, v202, v203
	v_pk_add_f32 v[232:233], v[232:233], v[188:189]
	v_pk_add_f32 v[232:233], v[232:233], v[190:191]
	v_pk_add_f32 v[232:233], v[232:233], v[192:193]
	v_pk_add_f32 v[232:233], v[232:233], v[194:195]
	v_pk_add_f32 v[232:233], v[232:233], v[196:197]
	v_pk_add_f32 v[232:233], v[232:233], v[198:199]
	v_pk_add_f32 v[232:233], v[232:233], v[200:201]
	v_pk_add_f32 v[232:233], v[232:233], v[202:203]
	ds_read2_b32 v[188:189], v115 offset0:68 offset1:69
	ds_read2_b32 v[190:191], v115 offset0:70 offset1:71
	ds_read2_b32 v[192:193], v115 offset0:76 offset1:77
	ds_read2_b32 v[194:195], v115 offset0:78 offset1:79
	ds_read2_b32 v[196:197], v115 offset0:85 offset1:86
	ds_read2_b32 v[198:199], v115 offset0:87 offset1:88
	ds_read2_b32 v[200:201], v115 offset0:93 offset1:94
	ds_read2_b32 v[202:203], v115 offset0:95 offset1:96
	v_mfma_f32_32x32x16_bf16 v[0:15], v[64:67], v[72:75], v[0:15]
	v_mfma_f32_32x32x16_bf16 v[16:31], v[64:67], v[76:79], v[16:31]
	v_mfma_f32_32x32x16_bf16 v[0:15], v[68:71], v[220:223], v[0:15]
	v_mfma_f32_32x32x16_bf16 v[16:31], v[68:71], v[224:227], v[16:31]
	global_load_dwordx4 v[116:119], v235, s[84:85]
	global_load_dwordx4 v[120:123], v236, s[84:85]
	global_load_dwordx4 v[124:127], v237, s[84:85]
	global_load_dwordx4 v[128:131], v238, s[84:85]
	global_load_dwordx4 v[132:135], v100, s[84:85] offset:768
	global_load_dwordx4 v[136:139], v149, s[84:85] offset:768
	global_load_dwordx4 v[140:143], v100, s[84:85] offset:832
	global_load_dwordx4 v[144:147], v149, s[84:85] offset:832
	s_add_u32 s84, s84, 0x30000
	s_addc_u32 s85, s85, 0
	ds_read_b64_tr_b16 v[72:73], v231
	ds_read_b64_tr_b16 v[74:75], v231 offset:512
	ds_read_b64_tr_b16 v[76:77], v231 offset:2048
	ds_read_b64_tr_b16 v[78:79], v231 offset:2560
	ds_read_b64_tr_b16 v[220:221], v231 offset:1024
	ds_read_b64_tr_b16 v[222:223], v231 offset:1536
	ds_read_b64_tr_b16 v[224:225], v231 offset:3072
	ds_read_b64_tr_b16 v[226:227], v231 offset:3584
	s_waitcnt vmcnt(8)
	ds_write_b128 v247, v[156:159]
	ds_write_b128 v247, v[160:163] offset:1024
	ds_write_b128 v111, v[164:167] offset:2048
	ds_write_b128 v111, v[168:171] offset:3072
	ds_read_b128 v[156:159], v248
	ds_read_b128 v[160:163], v249
	ds_read_b128 v[164:167], v250
	ds_read_b128 v[168:171], v251
	ds_write_b128 v112, v[172:175]
	ds_write_b128 v112, v[176:179] offset:1024
	ds_write_b128 v112, v[180:183] offset:2048
	ds_write_b128 v112, v[184:187] offset:3072
	v_exp_f32_e32 v32, v32
	v_exp_f32_e32 v33, v33
	v_exp_f32_e32 v34, v34
	v_exp_f32_e32 v35, v35
	v_exp_f32_e32 v36, v36
	v_exp_f32_e32 v37, v37
	s_waitcnt lgkmcnt(4)
	v_mfma_f32_32x32x16_bf16 v[188:203], v[156:159], v[48:51], v[188:203]
	v_exp_f32_e32 v38, v38
	v_exp_f32_e32 v39, v39
	v_mfma_f32_32x32x16_bf16 v[188:203], v[160:163], v[52:55], v[188:203]
	v_exp_f32_e32 v40, v40
	v_exp_f32_e32 v41, v41
	v_exp_f32_e32 v42, v42
	v_mfma_f32_32x32x16_bf16 v[188:203], v[164:167], v[56:59], v[188:203]
	v_exp_f32_e32 v43, v43
	v_exp_f32_e32 v44, v44
	v_mfma_f32_32x32x16_bf16 v[188:203], v[168:171], v[60:63], v[188:203]
	v_exp_f32_e32 v45, v45
	v_exp_f32_e32 v46, v46
	v_exp_f32_e32 v47, v47
	v_cvt_pk_bf16_f32 v64, v32, v33
	v_cvt_pk_bf16_f32 v65, v34, v35
	v_cvt_pk_bf16_f32 v66, v36, v37
	v_cvt_pk_bf16_f32 v67, v38, v39
	v_cvt_pk_bf16_f32 v68, v40, v41
	v_cvt_pk_bf16_f32 v69, v42, v43
	v_cvt_pk_bf16_f32 v70, v44, v45
	v_cvt_pk_bf16_f32 v71, v46, v47
	v_pk_add_f32 v[232:233], v[232:233], v[32:33]
	v_pk_add_f32 v[232:233], v[232:233], v[34:35]
	v_pk_add_f32 v[232:233], v[232:233], v[36:37]
	v_pk_add_f32 v[232:233], v[232:233], v[38:39]
	v_pk_add_f32 v[232:233], v[232:233], v[40:41]
	v_pk_add_f32 v[232:233], v[232:233], v[42:43]
	v_pk_add_f32 v[232:233], v[232:233], v[44:45]
	v_pk_add_f32 v[232:233], v[232:233], v[46:47]
	ds_read2_b32 v[32:33], v115 offset0:102 offset1:103
	ds_read2_b32 v[34:35], v115 offset0:104 offset1:105
	ds_read2_b32 v[36:37], v115 offset0:110 offset1:111
	ds_read2_b32 v[38:39], v115 offset0:112 offset1:113
	ds_read2_b32 v[40:41], v115 offset0:119 offset1:120
	ds_read2_b32 v[42:43], v115 offset0:121 offset1:122
	ds_read2_b32 v[44:45], v115 offset0:127 offset1:128
	ds_read2_b32 v[46:47], v115 offset0:129 offset1:130
	v_mfma_f32_32x32x16_bf16 v[0:15], v[64:67], v[72:75], v[0:15]
	v_mfma_f32_32x32x16_bf16 v[16:31], v[64:67], v[76:79], v[16:31]
	v_mfma_f32_32x32x16_bf16 v[0:15], v[68:71], v[220:223], v[0:15]
	v_mfma_f32_32x32x16_bf16 v[16:31], v[68:71], v[224:227], v[16:31]
	global_load_dwordx4 v[156:159], v235, s[84:85]
	global_load_dwordx4 v[160:163], v236, s[84:85]
	global_load_dwordx4 v[164:167], v237, s[84:85]
	global_load_dwordx4 v[168:171], v238, s[84:85]
	global_load_dwordx4 v[172:175], v100, s[84:85] offset:768
	global_load_dwordx4 v[176:179], v149, s[84:85] offset:768
	global_load_dwordx4 v[180:183], v100, s[84:85] offset:832
	global_load_dwordx4 v[184:187], v149, s[84:85] offset:832
	s_add_u32 s84, s84, 0x30000
	s_addc_u32 s85, s85, 0
	ds_read_b64_tr_b16 v[72:73], v231
	ds_read_b64_tr_b16 v[74:75], v231 offset:512
	ds_read_b64_tr_b16 v[76:77], v231 offset:2048
	ds_read_b64_tr_b16 v[78:79], v231 offset:2560
	ds_read_b64_tr_b16 v[220:221], v231 offset:1024
	ds_read_b64_tr_b16 v[222:223], v231 offset:1536
	ds_read_b64_tr_b16 v[224:225], v231 offset:3072
	ds_read_b64_tr_b16 v[226:227], v231 offset:3584
	s_waitcnt vmcnt(8)
	ds_write_b128 v247, v[116:119]
	ds_write_b128 v247, v[120:123] offset:1024
	ds_write_b128 v111, v[124:127] offset:2048
	ds_write_b128 v111, v[128:131] offset:3072
	ds_read_b128 v[116:119], v248
	ds_read_b128 v[120:123], v249
	ds_read_b128 v[124:127], v250
	ds_read_b128 v[128:131], v251
	ds_write_b128 v112, v[132:135]
	ds_write_b128 v112, v[136:139] offset:1024
	ds_write_b128 v112, v[140:143] offset:2048
	ds_write_b128 v112, v[144:147] offset:3072
	v_exp_f32_e32 v188, v188
	v_exp_f32_e32 v189, v189
	v_exp_f32_e32 v190, v190
	v_exp_f32_e32 v191, v191
	v_exp_f32_e32 v192, v192
	v_exp_f32_e32 v193, v193
	s_waitcnt lgkmcnt(4)
	v_mfma_f32_32x32x16_bf16 v[32:47], v[116:119], v[48:51], v[32:47]
	v_exp_f32_e32 v194, v194
	v_exp_f32_e32 v195, v195
	v_mfma_f32_32x32x16_bf16 v[32:47], v[120:123], v[52:55], v[32:47]
	v_exp_f32_e32 v196, v196
	v_exp_f32_e32 v197, v197
	v_exp_f32_e32 v198, v198
	v_mfma_f32_32x32x16_bf16 v[32:47], v[124:127], v[56:59], v[32:47]
	v_exp_f32_e32 v199, v199
	v_exp_f32_e32 v200, v200
	v_mfma_f32_32x32x16_bf16 v[32:47], v[128:131], v[60:63], v[32:47]
	v_exp_f32_e32 v201, v201
	v_exp_f32_e32 v202, v202
	v_exp_f32_e32 v203, v203
	v_cvt_pk_bf16_f32 v64, v188, v189
	v_cvt_pk_bf16_f32 v65, v190, v191
	v_cvt_pk_bf16_f32 v66, v192, v193
	v_cvt_pk_bf16_f32 v67, v194, v195
	v_cvt_pk_bf16_f32 v68, v196, v197
	v_cvt_pk_bf16_f32 v69, v198, v199
	v_cvt_pk_bf16_f32 v70, v200, v201
	v_cvt_pk_bf16_f32 v71, v202, v203
	v_pk_add_f32 v[232:233], v[232:233], v[188:189]
	v_pk_add_f32 v[232:233], v[232:233], v[190:191]
	v_pk_add_f32 v[232:233], v[232:233], v[192:193]
	v_pk_add_f32 v[232:233], v[232:233], v[194:195]
	v_pk_add_f32 v[232:233], v[232:233], v[196:197]
	v_pk_add_f32 v[232:233], v[232:233], v[198:199]
	v_pk_add_f32 v[232:233], v[232:233], v[200:201]
	v_pk_add_f32 v[232:233], v[232:233], v[202:203]
	ds_read2_b32 v[188:189], v115 offset0:136 offset1:137
	ds_read2_b32 v[190:191], v115 offset0:138 offset1:139
	ds_read2_b32 v[192:193], v115 offset0:144 offset1:145
	ds_read2_b32 v[194:195], v115 offset0:146 offset1:147
	ds_read2_b32 v[196:197], v115 offset0:153 offset1:154
	ds_read2_b32 v[198:199], v115 offset0:155 offset1:156
	ds_read2_b32 v[200:201], v115 offset0:161 offset1:162
	ds_read2_b32 v[202:203], v115 offset0:163 offset1:164
	v_mfma_f32_32x32x16_bf16 v[0:15], v[64:67], v[72:75], v[0:15]
	v_mfma_f32_32x32x16_bf16 v[16:31], v[64:67], v[76:79], v[16:31]
	v_mfma_f32_32x32x16_bf16 v[0:15], v[68:71], v[220:223], v[0:15]
	v_mfma_f32_32x32x16_bf16 v[16:31], v[68:71], v[224:227], v[16:31]
	global_load_dwordx4 v[116:119], v235, s[84:85]
	global_load_dwordx4 v[120:123], v236, s[84:85]
	global_load_dwordx4 v[124:127], v237, s[84:85]
	global_load_dwordx4 v[128:131], v238, s[84:85]
	global_load_dwordx4 v[132:135], v100, s[84:85] offset:768
	global_load_dwordx4 v[136:139], v149, s[84:85] offset:768
	global_load_dwordx4 v[140:143], v100, s[84:85] offset:832
	global_load_dwordx4 v[144:147], v149, s[84:85] offset:832
	s_add_u32 s84, s84, 0x30000
	s_addc_u32 s85, s85, 0
	ds_read_b64_tr_b16 v[72:73], v231
	ds_read_b64_tr_b16 v[74:75], v231 offset:512
	ds_read_b64_tr_b16 v[76:77], v231 offset:2048
	ds_read_b64_tr_b16 v[78:79], v231 offset:2560
	ds_read_b64_tr_b16 v[220:221], v231 offset:1024
	ds_read_b64_tr_b16 v[222:223], v231 offset:1536
	ds_read_b64_tr_b16 v[224:225], v231 offset:3072
	ds_read_b64_tr_b16 v[226:227], v231 offset:3584
	s_waitcnt vmcnt(8)
	ds_write_b128 v247, v[156:159]
	ds_write_b128 v247, v[160:163] offset:1024
	ds_write_b128 v111, v[164:167] offset:2048
	ds_write_b128 v111, v[168:171] offset:3072
	ds_read_b128 v[156:159], v248
	ds_read_b128 v[160:163], v249
	ds_read_b128 v[164:167], v250
	ds_read_b128 v[168:171], v251
	ds_write_b128 v112, v[172:175]
	ds_write_b128 v112, v[176:179] offset:1024
	ds_write_b128 v112, v[180:183] offset:2048
	ds_write_b128 v112, v[184:187] offset:3072
	v_exp_f32_e32 v32, v32
	v_exp_f32_e32 v33, v33
	v_exp_f32_e32 v34, v34
	v_exp_f32_e32 v35, v35
	v_exp_f32_e32 v36, v36
	v_exp_f32_e32 v37, v37
	s_waitcnt lgkmcnt(4)
	v_mfma_f32_32x32x16_bf16 v[188:203], v[156:159], v[48:51], v[188:203]
	v_exp_f32_e32 v38, v38
	v_exp_f32_e32 v39, v39
	v_mfma_f32_32x32x16_bf16 v[188:203], v[160:163], v[52:55], v[188:203]
	v_exp_f32_e32 v40, v40
	v_exp_f32_e32 v41, v41
	v_exp_f32_e32 v42, v42
	v_mfma_f32_32x32x16_bf16 v[188:203], v[164:167], v[56:59], v[188:203]
	v_exp_f32_e32 v43, v43
	v_exp_f32_e32 v44, v44
	v_mfma_f32_32x32x16_bf16 v[188:203], v[168:171], v[60:63], v[188:203]
	v_exp_f32_e32 v45, v45
	v_exp_f32_e32 v46, v46
	v_exp_f32_e32 v47, v47
	v_cvt_pk_bf16_f32 v64, v32, v33
	v_cvt_pk_bf16_f32 v65, v34, v35
	v_cvt_pk_bf16_f32 v66, v36, v37
	v_cvt_pk_bf16_f32 v67, v38, v39
	v_cvt_pk_bf16_f32 v68, v40, v41
	v_cvt_pk_bf16_f32 v69, v42, v43
	v_cvt_pk_bf16_f32 v70, v44, v45
	v_cvt_pk_bf16_f32 v71, v46, v47
	v_pk_add_f32 v[232:233], v[232:233], v[32:33]
	v_pk_add_f32 v[232:233], v[232:233], v[34:35]
	v_pk_add_f32 v[232:233], v[232:233], v[36:37]
	v_pk_add_f32 v[232:233], v[232:233], v[38:39]
	v_pk_add_f32 v[232:233], v[232:233], v[40:41]
	v_pk_add_f32 v[232:233], v[232:233], v[42:43]
	v_pk_add_f32 v[232:233], v[232:233], v[44:45]
	v_pk_add_f32 v[232:233], v[232:233], v[46:47]
	ds_read2_b32 v[32:33], v115 offset0:170 offset1:171
	ds_read2_b32 v[34:35], v115 offset0:172 offset1:173
	ds_read2_b32 v[36:37], v115 offset0:178 offset1:179
	ds_read2_b32 v[38:39], v115 offset0:180 offset1:181
	ds_read2_b32 v[40:41], v115 offset0:187 offset1:188
	ds_read2_b32 v[42:43], v115 offset0:189 offset1:190
	ds_read2_b32 v[44:45], v115 offset0:195 offset1:196
	ds_read2_b32 v[46:47], v115 offset0:197 offset1:198
	v_mfma_f32_32x32x16_bf16 v[0:15], v[64:67], v[72:75], v[0:15]
	v_mfma_f32_32x32x16_bf16 v[16:31], v[64:67], v[76:79], v[16:31]
	v_mfma_f32_32x32x16_bf16 v[0:15], v[68:71], v[220:223], v[0:15]
	v_mfma_f32_32x32x16_bf16 v[16:31], v[68:71], v[224:227], v[16:31]
	global_load_dwordx4 v[156:159], v235, s[84:85]
	global_load_dwordx4 v[160:163], v236, s[84:85]
	global_load_dwordx4 v[164:167], v237, s[84:85]
	global_load_dwordx4 v[168:171], v238, s[84:85]
	global_load_dwordx4 v[172:175], v100, s[84:85] offset:768
	global_load_dwordx4 v[176:179], v149, s[84:85] offset:768
	global_load_dwordx4 v[180:183], v100, s[84:85] offset:832
	global_load_dwordx4 v[184:187], v149, s[84:85] offset:832
	s_add_u32 s84, s84, 0x30000
	s_addc_u32 s85, s85, 0
	ds_read_b64_tr_b16 v[72:73], v231
	ds_read_b64_tr_b16 v[74:75], v231 offset:512
	ds_read_b64_tr_b16 v[76:77], v231 offset:2048
	ds_read_b64_tr_b16 v[78:79], v231 offset:2560
	ds_read_b64_tr_b16 v[220:221], v231 offset:1024
	ds_read_b64_tr_b16 v[222:223], v231 offset:1536
	ds_read_b64_tr_b16 v[224:225], v231 offset:3072
	ds_read_b64_tr_b16 v[226:227], v231 offset:3584
	s_waitcnt vmcnt(8)
	ds_write_b128 v247, v[116:119]
	ds_write_b128 v247, v[120:123] offset:1024
	ds_write_b128 v111, v[124:127] offset:2048
	ds_write_b128 v111, v[128:131] offset:3072
	ds_read_b128 v[116:119], v248
	ds_read_b128 v[120:123], v249
	ds_read_b128 v[124:127], v250
	ds_read_b128 v[128:131], v251
	ds_write_b128 v112, v[132:135]
	ds_write_b128 v112, v[136:139] offset:1024
	ds_write_b128 v112, v[140:143] offset:2048
	ds_write_b128 v112, v[144:147] offset:3072
	v_exp_f32_e32 v188, v188
	v_exp_f32_e32 v189, v189
	v_exp_f32_e32 v190, v190
	v_exp_f32_e32 v191, v191
	v_exp_f32_e32 v192, v192
	v_exp_f32_e32 v193, v193
	s_waitcnt lgkmcnt(4)
	v_mfma_f32_32x32x16_bf16 v[32:47], v[116:119], v[48:51], v[32:47]
	v_exp_f32_e32 v194, v194
	v_exp_f32_e32 v195, v195
	v_mfma_f32_32x32x16_bf16 v[32:47], v[120:123], v[52:55], v[32:47]
	v_exp_f32_e32 v196, v196
	v_exp_f32_e32 v197, v197
	v_exp_f32_e32 v198, v198
	v_mfma_f32_32x32x16_bf16 v[32:47], v[124:127], v[56:59], v[32:47]
	v_exp_f32_e32 v199, v199
	v_exp_f32_e32 v200, v200
	v_mfma_f32_32x32x16_bf16 v[32:47], v[128:131], v[60:63], v[32:47]
	v_exp_f32_e32 v201, v201
	v_exp_f32_e32 v202, v202
	v_exp_f32_e32 v203, v203
	v_cvt_pk_bf16_f32 v64, v188, v189
	v_cvt_pk_bf16_f32 v65, v190, v191
	v_cvt_pk_bf16_f32 v66, v192, v193
	v_cvt_pk_bf16_f32 v67, v194, v195
	v_cvt_pk_bf16_f32 v68, v196, v197
	v_cvt_pk_bf16_f32 v69, v198, v199
	v_cvt_pk_bf16_f32 v70, v200, v201
	v_cvt_pk_bf16_f32 v71, v202, v203
	v_pk_add_f32 v[232:233], v[232:233], v[188:189]
	v_pk_add_f32 v[232:233], v[232:233], v[190:191]
	v_pk_add_f32 v[232:233], v[232:233], v[192:193]
	v_pk_add_f32 v[232:233], v[232:233], v[194:195]
	v_pk_add_f32 v[232:233], v[232:233], v[196:197]
	v_pk_add_f32 v[232:233], v[232:233], v[198:199]
	v_pk_add_f32 v[232:233], v[232:233], v[200:201]
	v_pk_add_f32 v[232:233], v[232:233], v[202:203]
	ds_read2_b32 v[188:189], v115 offset0:204 offset1:205
	ds_read2_b32 v[190:191], v115 offset0:206 offset1:207
	ds_read2_b32 v[192:193], v115 offset0:212 offset1:213
	ds_read2_b32 v[194:195], v115 offset0:214 offset1:215
	ds_read2_b32 v[196:197], v115 offset0:221 offset1:222
	ds_read2_b32 v[198:199], v115 offset0:223 offset1:224
	ds_read2_b32 v[200:201], v115 offset0:229 offset1:230
	ds_read2_b32 v[202:203], v115 offset0:231 offset1:232
	v_mfma_f32_32x32x16_bf16 v[0:15], v[64:67], v[72:75], v[0:15]
	v_mfma_f32_32x32x16_bf16 v[16:31], v[64:67], v[76:79], v[16:31]
	v_mfma_f32_32x32x16_bf16 v[0:15], v[68:71], v[220:223], v[0:15]
	v_mfma_f32_32x32x16_bf16 v[16:31], v[68:71], v[224:227], v[16:31]
	global_load_dwordx4 v[116:119], v235, s[84:85]
	global_load_dwordx4 v[120:123], v236, s[84:85]
	global_load_dwordx4 v[124:127], v237, s[84:85]
	global_load_dwordx4 v[128:131], v238, s[84:85]
	global_load_dwordx4 v[132:135], v100, s[84:85] offset:768
	global_load_dwordx4 v[136:139], v149, s[84:85] offset:768
	global_load_dwordx4 v[140:143], v100, s[84:85] offset:832
	global_load_dwordx4 v[144:147], v149, s[84:85] offset:832
	s_add_u32 s84, s84, 0x30000
	s_addc_u32 s85, s85, 0
	ds_read_b64_tr_b16 v[72:73], v231
	ds_read_b64_tr_b16 v[74:75], v231 offset:512
	ds_read_b64_tr_b16 v[76:77], v231 offset:2048
	ds_read_b64_tr_b16 v[78:79], v231 offset:2560
	ds_read_b64_tr_b16 v[220:221], v231 offset:1024
	ds_read_b64_tr_b16 v[222:223], v231 offset:1536
	ds_read_b64_tr_b16 v[224:225], v231 offset:3072
	ds_read_b64_tr_b16 v[226:227], v231 offset:3584
	s_waitcnt vmcnt(8)
	ds_write_b128 v247, v[156:159]
	ds_write_b128 v247, v[160:163] offset:1024
	ds_write_b128 v111, v[164:167] offset:2048
	ds_write_b128 v111, v[168:171] offset:3072
	ds_read_b128 v[156:159], v248
	ds_read_b128 v[160:163], v249
	ds_read_b128 v[164:167], v250
	ds_read_b128 v[168:171], v251
	ds_write_b128 v112, v[172:175]
	ds_write_b128 v112, v[176:179] offset:1024
	ds_write_b128 v112, v[180:183] offset:2048
	ds_write_b128 v112, v[184:187] offset:3072
	v_exp_f32_e32 v32, v32
	v_exp_f32_e32 v33, v33
	v_exp_f32_e32 v34, v34
	v_exp_f32_e32 v35, v35
	v_exp_f32_e32 v36, v36
	v_exp_f32_e32 v37, v37
	s_waitcnt lgkmcnt(4)
	v_mfma_f32_32x32x16_bf16 v[188:203], v[156:159], v[48:51], v[188:203]
	v_exp_f32_e32 v38, v38
	v_exp_f32_e32 v39, v39
	v_mfma_f32_32x32x16_bf16 v[188:203], v[160:163], v[52:55], v[188:203]
	v_exp_f32_e32 v40, v40
	v_exp_f32_e32 v41, v41
	v_exp_f32_e32 v42, v42
	v_mfma_f32_32x32x16_bf16 v[188:203], v[164:167], v[56:59], v[188:203]
	v_exp_f32_e32 v43, v43
	v_exp_f32_e32 v44, v44
	v_mfma_f32_32x32x16_bf16 v[188:203], v[168:171], v[60:63], v[188:203]
	v_exp_f32_e32 v45, v45
	v_exp_f32_e32 v46, v46
	v_exp_f32_e32 v47, v47
	v_cvt_pk_bf16_f32 v64, v32, v33
	v_cvt_pk_bf16_f32 v65, v34, v35
	v_cvt_pk_bf16_f32 v66, v36, v37
	v_cvt_pk_bf16_f32 v67, v38, v39
	v_cvt_pk_bf16_f32 v68, v40, v41
	v_cvt_pk_bf16_f32 v69, v42, v43
	v_cvt_pk_bf16_f32 v70, v44, v45
	v_cvt_pk_bf16_f32 v71, v46, v47
	v_pk_add_f32 v[232:233], v[232:233], v[32:33]
	v_pk_add_f32 v[232:233], v[232:233], v[34:35]
	v_pk_add_f32 v[232:233], v[232:233], v[36:37]
	v_pk_add_f32 v[232:233], v[232:233], v[38:39]
	v_pk_add_f32 v[232:233], v[232:233], v[40:41]
	v_pk_add_f32 v[232:233], v[232:233], v[42:43]
	v_pk_add_f32 v[232:233], v[232:233], v[44:45]
	v_pk_add_f32 v[232:233], v[232:233], v[46:47]
	v_add_u32_e32 v115, 952, v115
	ds_read2_b32 v[32:33], v115 offset0:0 offset1:1
	ds_read2_b32 v[34:35], v115 offset0:2 offset1:3
	ds_read2_b32 v[36:37], v115 offset0:8 offset1:9
	ds_read2_b32 v[38:39], v115 offset0:10 offset1:11
	ds_read2_b32 v[40:41], v115 offset0:17 offset1:18
	ds_read2_b32 v[42:43], v115 offset0:19 offset1:20
	ds_read2_b32 v[44:45], v115 offset0:25 offset1:26
	ds_read2_b32 v[46:47], v115 offset0:27 offset1:28
	v_mfma_f32_32x32x16_bf16 v[0:15], v[64:67], v[72:75], v[0:15]
	v_mfma_f32_32x32x16_bf16 v[16:31], v[64:67], v[76:79], v[16:31]
	v_mfma_f32_32x32x16_bf16 v[0:15], v[68:71], v[220:223], v[0:15]
	v_mfma_f32_32x32x16_bf16 v[16:31], v[68:71], v[224:227], v[16:31]
	global_load_dwordx4 v[156:159], v235, s[84:85]
	global_load_dwordx4 v[160:163], v236, s[84:85]
	global_load_dwordx4 v[164:167], v237, s[84:85]
	global_load_dwordx4 v[168:171], v238, s[84:85]
	global_load_dwordx4 v[172:175], v100, s[84:85] offset:768
	global_load_dwordx4 v[176:179], v149, s[84:85] offset:768
	global_load_dwordx4 v[180:183], v100, s[84:85] offset:832
	global_load_dwordx4 v[184:187], v149, s[84:85] offset:832
	s_add_u32 s84, s84, 0x30000
	s_addc_u32 s85, s85, 0
	ds_read_b64_tr_b16 v[72:73], v231
	ds_read_b64_tr_b16 v[74:75], v231 offset:512
	ds_read_b64_tr_b16 v[76:77], v231 offset:2048
	ds_read_b64_tr_b16 v[78:79], v231 offset:2560
	ds_read_b64_tr_b16 v[220:221], v231 offset:1024
	ds_read_b64_tr_b16 v[222:223], v231 offset:1536
	ds_read_b64_tr_b16 v[224:225], v231 offset:3072
	ds_read_b64_tr_b16 v[226:227], v231 offset:3584
	s_waitcnt vmcnt(8)
	ds_write_b128 v247, v[116:119]
	ds_write_b128 v247, v[120:123] offset:1024
	ds_write_b128 v111, v[124:127] offset:2048
	ds_write_b128 v111, v[128:131] offset:3072
	ds_read_b128 v[116:119], v248
	ds_read_b128 v[120:123], v249
	ds_read_b128 v[124:127], v250
	ds_read_b128 v[128:131], v251
	ds_write_b128 v112, v[132:135]
	ds_write_b128 v112, v[136:139] offset:1024
	ds_write_b128 v112, v[140:143] offset:2048
	ds_write_b128 v112, v[144:147] offset:3072
	v_exp_f32_e32 v188, v188
	v_exp_f32_e32 v189, v189
	v_exp_f32_e32 v190, v190
	v_exp_f32_e32 v191, v191
	v_exp_f32_e32 v192, v192
	v_exp_f32_e32 v193, v193
	s_waitcnt lgkmcnt(4)
	v_mfma_f32_32x32x16_bf16 v[32:47], v[116:119], v[48:51], v[32:47]
	v_exp_f32_e32 v194, v194
	v_exp_f32_e32 v195, v195
	v_mfma_f32_32x32x16_bf16 v[32:47], v[120:123], v[52:55], v[32:47]
	v_exp_f32_e32 v196, v196
	v_exp_f32_e32 v197, v197
	v_exp_f32_e32 v198, v198
	v_mfma_f32_32x32x16_bf16 v[32:47], v[124:127], v[56:59], v[32:47]
	v_exp_f32_e32 v199, v199
	v_exp_f32_e32 v200, v200
	v_mfma_f32_32x32x16_bf16 v[32:47], v[128:131], v[60:63], v[32:47]
	v_exp_f32_e32 v201, v201
	v_exp_f32_e32 v202, v202
	v_exp_f32_e32 v203, v203
	v_cvt_pk_bf16_f32 v64, v188, v189
	v_cvt_pk_bf16_f32 v65, v190, v191
	v_cvt_pk_bf16_f32 v66, v192, v193
	v_cvt_pk_bf16_f32 v67, v194, v195
	v_cvt_pk_bf16_f32 v68, v196, v197
	v_cvt_pk_bf16_f32 v69, v198, v199
	v_cvt_pk_bf16_f32 v70, v200, v201
	v_cvt_pk_bf16_f32 v71, v202, v203
	v_pk_add_f32 v[232:233], v[232:233], v[188:189]
	v_pk_add_f32 v[232:233], v[232:233], v[190:191]
	v_pk_add_f32 v[232:233], v[232:233], v[192:193]
	v_pk_add_f32 v[232:233], v[232:233], v[194:195]
	v_pk_add_f32 v[232:233], v[232:233], v[196:197]
	v_pk_add_f32 v[232:233], v[232:233], v[198:199]
	v_pk_add_f32 v[232:233], v[232:233], v[200:201]
	v_pk_add_f32 v[232:233], v[232:233], v[202:203]
	ds_read2_b32 v[188:189], v115 offset0:34 offset1:35
	ds_read2_b32 v[190:191], v115 offset0:36 offset1:37
	ds_read2_b32 v[192:193], v115 offset0:42 offset1:43
	ds_read2_b32 v[194:195], v115 offset0:44 offset1:45
	ds_read2_b32 v[196:197], v115 offset0:51 offset1:52
	ds_read2_b32 v[198:199], v115 offset0:53 offset1:54
	ds_read2_b32 v[200:201], v115 offset0:59 offset1:60
	ds_read2_b32 v[202:203], v115 offset0:61 offset1:62
	v_mfma_f32_32x32x16_bf16 v[0:15], v[64:67], v[72:75], v[0:15]
	v_mfma_f32_32x32x16_bf16 v[16:31], v[64:67], v[76:79], v[16:31]
	v_mfma_f32_32x32x16_bf16 v[0:15], v[68:71], v[220:223], v[0:15]
	v_mfma_f32_32x32x16_bf16 v[16:31], v[68:71], v[224:227], v[16:31]
	global_load_dwordx4 v[116:119], v235, s[84:85]
	global_load_dwordx4 v[120:123], v236, s[84:85]
	global_load_dwordx4 v[124:127], v237, s[84:85]
	global_load_dwordx4 v[128:131], v238, s[84:85]
	global_load_dwordx4 v[132:135], v100, s[84:85] offset:768
	global_load_dwordx4 v[136:139], v149, s[84:85] offset:768
	global_load_dwordx4 v[140:143], v100, s[84:85] offset:832
	global_load_dwordx4 v[144:147], v149, s[84:85] offset:832
	s_add_u32 s84, s84, 0x30000
	s_addc_u32 s85, s85, 0
	ds_read_b64_tr_b16 v[72:73], v231
	ds_read_b64_tr_b16 v[74:75], v231 offset:512
	ds_read_b64_tr_b16 v[76:77], v231 offset:2048
	ds_read_b64_tr_b16 v[78:79], v231 offset:2560
	ds_read_b64_tr_b16 v[220:221], v231 offset:1024
	ds_read_b64_tr_b16 v[222:223], v231 offset:1536
	ds_read_b64_tr_b16 v[224:225], v231 offset:3072
	ds_read_b64_tr_b16 v[226:227], v231 offset:3584
	s_waitcnt vmcnt(8)
	ds_write_b128 v247, v[156:159]
	ds_write_b128 v247, v[160:163] offset:1024
	ds_write_b128 v111, v[164:167] offset:2048
	ds_write_b128 v111, v[168:171] offset:3072
	ds_read_b128 v[156:159], v248
	ds_read_b128 v[160:163], v249
	ds_read_b128 v[164:167], v250
	ds_read_b128 v[168:171], v251
	ds_write_b128 v112, v[172:175]
	ds_write_b128 v112, v[176:179] offset:1024
	ds_write_b128 v112, v[180:183] offset:2048
	ds_write_b128 v112, v[184:187] offset:3072
	v_exp_f32_e32 v32, v32
	v_exp_f32_e32 v33, v33
	v_exp_f32_e32 v34, v34
	v_exp_f32_e32 v35, v35
	v_exp_f32_e32 v36, v36
	v_exp_f32_e32 v37, v37
	s_waitcnt lgkmcnt(4)
	v_mfma_f32_32x32x16_bf16 v[188:203], v[156:159], v[48:51], v[188:203]
	v_exp_f32_e32 v38, v38
	v_exp_f32_e32 v39, v39
	v_mfma_f32_32x32x16_bf16 v[188:203], v[160:163], v[52:55], v[188:203]
	v_exp_f32_e32 v40, v40
	v_exp_f32_e32 v41, v41
	v_exp_f32_e32 v42, v42
	v_mfma_f32_32x32x16_bf16 v[188:203], v[164:167], v[56:59], v[188:203]
	v_exp_f32_e32 v43, v43
	v_exp_f32_e32 v44, v44
	v_mfma_f32_32x32x16_bf16 v[188:203], v[168:171], v[60:63], v[188:203]
	v_exp_f32_e32 v45, v45
	v_exp_f32_e32 v46, v46
	v_exp_f32_e32 v47, v47
	v_cvt_pk_bf16_f32 v64, v32, v33
	v_cvt_pk_bf16_f32 v65, v34, v35
	v_cvt_pk_bf16_f32 v66, v36, v37
	v_cvt_pk_bf16_f32 v67, v38, v39
	v_cvt_pk_bf16_f32 v68, v40, v41
	v_cvt_pk_bf16_f32 v69, v42, v43
	v_cvt_pk_bf16_f32 v70, v44, v45
	v_cvt_pk_bf16_f32 v71, v46, v47
	v_pk_add_f32 v[232:233], v[232:233], v[32:33]
	v_pk_add_f32 v[232:233], v[232:233], v[34:35]
	v_pk_add_f32 v[232:233], v[232:233], v[36:37]
	v_pk_add_f32 v[232:233], v[232:233], v[38:39]
	v_pk_add_f32 v[232:233], v[232:233], v[40:41]
	v_pk_add_f32 v[232:233], v[232:233], v[42:43]
	v_pk_add_f32 v[232:233], v[232:233], v[44:45]
	v_pk_add_f32 v[232:233], v[232:233], v[46:47]
	ds_read2_b32 v[32:33], v115 offset0:68 offset1:69
	ds_read2_b32 v[34:35], v115 offset0:70 offset1:71
	ds_read2_b32 v[36:37], v115 offset0:76 offset1:77
	ds_read2_b32 v[38:39], v115 offset0:78 offset1:79
	ds_read2_b32 v[40:41], v115 offset0:85 offset1:86
	ds_read2_b32 v[42:43], v115 offset0:87 offset1:88
	ds_read2_b32 v[44:45], v115 offset0:93 offset1:94
	ds_read2_b32 v[46:47], v115 offset0:95 offset1:96
	v_mfma_f32_32x32x16_bf16 v[0:15], v[64:67], v[72:75], v[0:15]
	v_mfma_f32_32x32x16_bf16 v[16:31], v[64:67], v[76:79], v[16:31]
	v_mfma_f32_32x32x16_bf16 v[0:15], v[68:71], v[220:223], v[0:15]
	v_mfma_f32_32x32x16_bf16 v[16:31], v[68:71], v[224:227], v[16:31]
	global_load_dwordx4 v[156:159], v235, s[84:85]
	global_load_dwordx4 v[160:163], v236, s[84:85]
	global_load_dwordx4 v[164:167], v237, s[84:85]
	global_load_dwordx4 v[168:171], v238, s[84:85]
	global_load_dwordx4 v[172:175], v100, s[84:85] offset:768
	global_load_dwordx4 v[176:179], v149, s[84:85] offset:768
	global_load_dwordx4 v[180:183], v100, s[84:85] offset:832
	global_load_dwordx4 v[184:187], v149, s[84:85] offset:832
	s_add_u32 s84, s84, 0x30000
	s_addc_u32 s85, s85, 0
	ds_read_b64_tr_b16 v[72:73], v231
	ds_read_b64_tr_b16 v[74:75], v231 offset:512
	ds_read_b64_tr_b16 v[76:77], v231 offset:2048
	ds_read_b64_tr_b16 v[78:79], v231 offset:2560
	ds_read_b64_tr_b16 v[220:221], v231 offset:1024
	ds_read_b64_tr_b16 v[222:223], v231 offset:1536
	ds_read_b64_tr_b16 v[224:225], v231 offset:3072
	ds_read_b64_tr_b16 v[226:227], v231 offset:3584
	s_waitcnt vmcnt(8)
	ds_write_b128 v247, v[116:119]
	ds_write_b128 v247, v[120:123] offset:1024
	ds_write_b128 v111, v[124:127] offset:2048
	ds_write_b128 v111, v[128:131] offset:3072
	ds_read_b128 v[116:119], v248
	ds_read_b128 v[120:123], v249
	ds_read_b128 v[124:127], v250
	ds_read_b128 v[128:131], v251
	ds_write_b128 v112, v[132:135]
	ds_write_b128 v112, v[136:139] offset:1024
	ds_write_b128 v112, v[140:143] offset:2048
	ds_write_b128 v112, v[144:147] offset:3072
	v_exp_f32_e32 v188, v188
	v_exp_f32_e32 v189, v189
	v_exp_f32_e32 v190, v190
	v_exp_f32_e32 v191, v191
	v_exp_f32_e32 v192, v192
	v_exp_f32_e32 v193, v193
	s_waitcnt lgkmcnt(4)
	v_mfma_f32_32x32x16_bf16 v[32:47], v[116:119], v[48:51], v[32:47]
	v_exp_f32_e32 v194, v194
	v_exp_f32_e32 v195, v195
	v_mfma_f32_32x32x16_bf16 v[32:47], v[120:123], v[52:55], v[32:47]
	v_exp_f32_e32 v196, v196
	v_exp_f32_e32 v197, v197
	v_exp_f32_e32 v198, v198
	v_mfma_f32_32x32x16_bf16 v[32:47], v[124:127], v[56:59], v[32:47]
	v_exp_f32_e32 v199, v199
	v_exp_f32_e32 v200, v200
	v_mfma_f32_32x32x16_bf16 v[32:47], v[128:131], v[60:63], v[32:47]
	v_exp_f32_e32 v201, v201
	v_exp_f32_e32 v202, v202
	v_exp_f32_e32 v203, v203
	v_cvt_pk_bf16_f32 v64, v188, v189
	v_cvt_pk_bf16_f32 v65, v190, v191
	v_cvt_pk_bf16_f32 v66, v192, v193
	v_cvt_pk_bf16_f32 v67, v194, v195
	v_cvt_pk_bf16_f32 v68, v196, v197
	v_cvt_pk_bf16_f32 v69, v198, v199
	v_cvt_pk_bf16_f32 v70, v200, v201
	v_cvt_pk_bf16_f32 v71, v202, v203
	v_pk_add_f32 v[232:233], v[232:233], v[188:189]
	v_pk_add_f32 v[232:233], v[232:233], v[190:191]
	v_pk_add_f32 v[232:233], v[232:233], v[192:193]
	v_pk_add_f32 v[232:233], v[232:233], v[194:195]
	v_pk_add_f32 v[232:233], v[232:233], v[196:197]
	v_pk_add_f32 v[232:233], v[232:233], v[198:199]
	v_pk_add_f32 v[232:233], v[232:233], v[200:201]
	v_pk_add_f32 v[232:233], v[232:233], v[202:203]
	ds_read2_b32 v[188:189], v115 offset0:102 offset1:103
	ds_read2_b32 v[190:191], v115 offset0:104 offset1:105
	ds_read2_b32 v[192:193], v115 offset0:110 offset1:111
	ds_read2_b32 v[194:195], v115 offset0:112 offset1:113
	ds_read2_b32 v[196:197], v115 offset0:119 offset1:120
	ds_read2_b32 v[198:199], v115 offset0:121 offset1:122
	ds_read2_b32 v[200:201], v115 offset0:127 offset1:128
	ds_read2_b32 v[202:203], v115 offset0:129 offset1:130
	v_mfma_f32_32x32x16_bf16 v[0:15], v[64:67], v[72:75], v[0:15]
	v_mfma_f32_32x32x16_bf16 v[16:31], v[64:67], v[76:79], v[16:31]
	v_mfma_f32_32x32x16_bf16 v[0:15], v[68:71], v[220:223], v[0:15]
	v_mfma_f32_32x32x16_bf16 v[16:31], v[68:71], v[224:227], v[16:31]
	global_load_dwordx4 v[116:119], v235, s[84:85]
	global_load_dwordx4 v[120:123], v236, s[84:85]
	global_load_dwordx4 v[124:127], v237, s[84:85]
	global_load_dwordx4 v[128:131], v238, s[84:85]
	global_load_dwordx4 v[132:135], v100, s[84:85] offset:768
	global_load_dwordx4 v[136:139], v149, s[84:85] offset:768
	global_load_dwordx4 v[140:143], v100, s[84:85] offset:832
	global_load_dwordx4 v[144:147], v149, s[84:85] offset:832
	s_add_u32 s84, s84, 0x30000
	s_addc_u32 s85, s85, 0
	ds_read_b64_tr_b16 v[72:73], v231
	ds_read_b64_tr_b16 v[74:75], v231 offset:512
	ds_read_b64_tr_b16 v[76:77], v231 offset:2048
	ds_read_b64_tr_b16 v[78:79], v231 offset:2560
	ds_read_b64_tr_b16 v[220:221], v231 offset:1024
	ds_read_b64_tr_b16 v[222:223], v231 offset:1536
	ds_read_b64_tr_b16 v[224:225], v231 offset:3072
	ds_read_b64_tr_b16 v[226:227], v231 offset:3584
	s_waitcnt vmcnt(8)
	ds_write_b128 v247, v[156:159]
	ds_write_b128 v247, v[160:163] offset:1024
	ds_write_b128 v111, v[164:167] offset:2048
	ds_write_b128 v111, v[168:171] offset:3072
	ds_read_b128 v[156:159], v248
	ds_read_b128 v[160:163], v249
	ds_read_b128 v[164:167], v250
	ds_read_b128 v[168:171], v251
	ds_write_b128 v112, v[172:175]
	ds_write_b128 v112, v[176:179] offset:1024
	ds_write_b128 v112, v[180:183] offset:2048
	ds_write_b128 v112, v[184:187] offset:3072
	v_exp_f32_e32 v32, v32
	v_exp_f32_e32 v33, v33
	v_exp_f32_e32 v34, v34
	v_exp_f32_e32 v35, v35
	v_exp_f32_e32 v36, v36
	v_exp_f32_e32 v37, v37
	s_waitcnt lgkmcnt(4)
	v_mfma_f32_32x32x16_bf16 v[188:203], v[156:159], v[48:51], v[188:203]
	v_exp_f32_e32 v38, v38
	v_exp_f32_e32 v39, v39
	v_mfma_f32_32x32x16_bf16 v[188:203], v[160:163], v[52:55], v[188:203]
	v_exp_f32_e32 v40, v40
	v_exp_f32_e32 v41, v41
	v_exp_f32_e32 v42, v42
	v_mfma_f32_32x32x16_bf16 v[188:203], v[164:167], v[56:59], v[188:203]
	v_exp_f32_e32 v43, v43
	v_exp_f32_e32 v44, v44
	v_mfma_f32_32x32x16_bf16 v[188:203], v[168:171], v[60:63], v[188:203]
	v_exp_f32_e32 v45, v45
	v_exp_f32_e32 v46, v46
	v_exp_f32_e32 v47, v47
	v_cvt_pk_bf16_f32 v64, v32, v33
	v_cvt_pk_bf16_f32 v65, v34, v35
	v_cvt_pk_bf16_f32 v66, v36, v37
	v_cvt_pk_bf16_f32 v67, v38, v39
	v_cvt_pk_bf16_f32 v68, v40, v41
	v_cvt_pk_bf16_f32 v69, v42, v43
	v_cvt_pk_bf16_f32 v70, v44, v45
	v_cvt_pk_bf16_f32 v71, v46, v47
	v_pk_add_f32 v[232:233], v[232:233], v[32:33]
	v_pk_add_f32 v[232:233], v[232:233], v[34:35]
	v_pk_add_f32 v[232:233], v[232:233], v[36:37]
	v_pk_add_f32 v[232:233], v[232:233], v[38:39]
	v_pk_add_f32 v[232:233], v[232:233], v[40:41]
	v_pk_add_f32 v[232:233], v[232:233], v[42:43]
	v_pk_add_f32 v[232:233], v[232:233], v[44:45]
	v_pk_add_f32 v[232:233], v[232:233], v[46:47]
	ds_read2_b32 v[32:33], v115 offset0:136 offset1:137
	ds_read2_b32 v[34:35], v115 offset0:138 offset1:139
	ds_read2_b32 v[36:37], v115 offset0:144 offset1:145
	ds_read2_b32 v[38:39], v115 offset0:146 offset1:147
	ds_read2_b32 v[40:41], v115 offset0:153 offset1:154
	ds_read2_b32 v[42:43], v115 offset0:155 offset1:156
	ds_read2_b32 v[44:45], v115 offset0:161 offset1:162
	ds_read2_b32 v[46:47], v115 offset0:163 offset1:164
	v_mfma_f32_32x32x16_bf16 v[0:15], v[64:67], v[72:75], v[0:15]
	v_mfma_f32_32x32x16_bf16 v[16:31], v[64:67], v[76:79], v[16:31]
	v_mfma_f32_32x32x16_bf16 v[0:15], v[68:71], v[220:223], v[0:15]
	v_mfma_f32_32x32x16_bf16 v[16:31], v[68:71], v[224:227], v[16:31]
	global_load_dwordx4 v[156:159], v235, s[84:85]
	global_load_dwordx4 v[160:163], v236, s[84:85]
	global_load_dwordx4 v[164:167], v237, s[84:85]
	global_load_dwordx4 v[168:171], v238, s[84:85]
	global_load_dwordx4 v[172:175], v100, s[84:85] offset:768
	global_load_dwordx4 v[176:179], v149, s[84:85] offset:768
	global_load_dwordx4 v[180:183], v100, s[84:85] offset:832
	global_load_dwordx4 v[184:187], v149, s[84:85] offset:832
	ds_read_b64_tr_b16 v[72:73], v231
	ds_read_b64_tr_b16 v[74:75], v231 offset:512
	ds_read_b64_tr_b16 v[76:77], v231 offset:2048
	ds_read_b64_tr_b16 v[78:79], v231 offset:2560
	ds_read_b64_tr_b16 v[220:221], v231 offset:1024
	ds_read_b64_tr_b16 v[222:223], v231 offset:1536
	ds_read_b64_tr_b16 v[224:225], v231 offset:3072
	ds_read_b64_tr_b16 v[226:227], v231 offset:3584
	s_waitcnt vmcnt(8)
	ds_write_b128 v247, v[116:119]
	ds_write_b128 v247, v[120:123] offset:1024
	ds_write_b128 v111, v[124:127] offset:2048
	ds_write_b128 v111, v[128:131] offset:3072
	ds_read_b128 v[116:119], v248
	ds_read_b128 v[120:123], v249
	ds_read_b128 v[124:127], v250
	ds_read_b128 v[128:131], v251
	ds_write_b128 v112, v[132:135]
	ds_write_b128 v112, v[136:139] offset:1024
	ds_write_b128 v112, v[140:143] offset:2048
	ds_write_b128 v112, v[144:147] offset:3072
	v_exp_f32_e32 v188, v188
	v_exp_f32_e32 v189, v189
	v_exp_f32_e32 v190, v190
	v_exp_f32_e32 v191, v191
	v_exp_f32_e32 v192, v192
	v_exp_f32_e32 v193, v193
	s_waitcnt lgkmcnt(4)
	v_mfma_f32_32x32x16_bf16 v[32:47], v[116:119], v[48:51], v[32:47]
	v_exp_f32_e32 v194, v194
	v_exp_f32_e32 v195, v195
	v_mfma_f32_32x32x16_bf16 v[32:47], v[120:123], v[52:55], v[32:47]
	v_exp_f32_e32 v196, v196
	v_exp_f32_e32 v197, v197
	v_exp_f32_e32 v198, v198
	v_mfma_f32_32x32x16_bf16 v[32:47], v[124:127], v[56:59], v[32:47]
	v_exp_f32_e32 v199, v199
	v_exp_f32_e32 v200, v200
	v_mfma_f32_32x32x16_bf16 v[32:47], v[128:131], v[60:63], v[32:47]
	v_exp_f32_e32 v201, v201
	v_exp_f32_e32 v202, v202
	v_exp_f32_e32 v203, v203
	v_cvt_pk_bf16_f32 v64, v188, v189
	v_cvt_pk_bf16_f32 v65, v190, v191
	v_cvt_pk_bf16_f32 v66, v192, v193
	v_cvt_pk_bf16_f32 v67, v194, v195
	v_cvt_pk_bf16_f32 v68, v196, v197
	v_cvt_pk_bf16_f32 v69, v198, v199
	v_cvt_pk_bf16_f32 v70, v200, v201
	v_cvt_pk_bf16_f32 v71, v202, v203
	v_pk_add_f32 v[232:233], v[232:233], v[188:189]
	v_pk_add_f32 v[232:233], v[232:233], v[190:191]
	v_pk_add_f32 v[232:233], v[232:233], v[192:193]
	v_pk_add_f32 v[232:233], v[232:233], v[194:195]
	v_pk_add_f32 v[232:233], v[232:233], v[196:197]
	v_pk_add_f32 v[232:233], v[232:233], v[198:199]
	v_pk_add_f32 v[232:233], v[232:233], v[200:201]
	v_pk_add_f32 v[232:233], v[232:233], v[202:203]
	ds_read2_b32 v[188:189], v115 offset0:170 offset1:171
	ds_read2_b32 v[190:191], v115 offset0:172 offset1:173
	ds_read2_b32 v[192:193], v115 offset0:178 offset1:179
	ds_read2_b32 v[194:195], v115 offset0:180 offset1:181
	ds_read2_b32 v[196:197], v115 offset0:187 offset1:188
	ds_read2_b32 v[198:199], v115 offset0:189 offset1:190
	ds_read2_b32 v[200:201], v115 offset0:195 offset1:196
	ds_read2_b32 v[202:203], v115 offset0:197 offset1:198
	v_mfma_f32_32x32x16_bf16 v[0:15], v[64:67], v[72:75], v[0:15]
	v_mfma_f32_32x32x16_bf16 v[16:31], v[64:67], v[76:79], v[16:31]
	v_mfma_f32_32x32x16_bf16 v[0:15], v[68:71], v[220:223], v[0:15]
	v_mfma_f32_32x32x16_bf16 v[16:31], v[68:71], v[224:227], v[16:31]
	global_load_dwordx4 v[116:119], v239, s[86:87]
	global_load_dwordx4 v[120:123], v240, s[86:87]
	global_load_dwordx4 v[124:127], v241, s[86:87]
	global_load_dwordx4 v[128:131], v242, s[86:87]
	global_load_dwordx4 v[132:135], v101, s[86:87] offset:768
	global_load_dwordx4 v[136:139], v150, s[86:87] offset:768
	global_load_dwordx4 v[140:143], v101, s[86:87] offset:832
	global_load_dwordx4 v[144:147], v150, s[86:87] offset:832
	s_add_u32 s86, s86, 0xc0000
	s_addc_u32 s87, s87, 0
	ds_read_b64_tr_b16 v[72:73], v231
	ds_read_b64_tr_b16 v[74:75], v231 offset:512
	ds_read_b64_tr_b16 v[76:77], v231 offset:2048
	ds_read_b64_tr_b16 v[78:79], v231 offset:2560
	ds_read_b64_tr_b16 v[220:221], v231 offset:1024
	ds_read_b64_tr_b16 v[222:223], v231 offset:1536
	ds_read_b64_tr_b16 v[224:225], v231 offset:3072
	ds_read_b64_tr_b16 v[226:227], v231 offset:3584
	s_waitcnt vmcnt(8)
	ds_write_b128 v247, v[156:159]
	ds_write_b128 v247, v[160:163] offset:1024
	ds_write_b128 v111, v[164:167] offset:2048
	ds_write_b128 v111, v[168:171] offset:3072
	ds_read_b128 v[156:159], v248
	ds_read_b128 v[160:163], v249
	ds_read_b128 v[164:167], v250
	ds_read_b128 v[168:171], v251
	ds_write_b128 v112, v[172:175]
	ds_write_b128 v112, v[176:179] offset:1024
	ds_write_b128 v112, v[180:183] offset:2048
	ds_write_b128 v112, v[184:187] offset:3072
	v_exp_f32_e32 v32, v32
	v_exp_f32_e32 v33, v33
	v_exp_f32_e32 v34, v34
	v_exp_f32_e32 v35, v35
	v_exp_f32_e32 v36, v36
	v_exp_f32_e32 v37, v37
	s_waitcnt lgkmcnt(4)
	v_mfma_f32_32x32x16_bf16 v[188:203], v[156:159], v[48:51], v[188:203]
	v_exp_f32_e32 v38, v38
	v_exp_f32_e32 v39, v39
	v_mfma_f32_32x32x16_bf16 v[188:203], v[160:163], v[52:55], v[188:203]
	v_exp_f32_e32 v40, v40
	v_exp_f32_e32 v41, v41
	v_exp_f32_e32 v42, v42
	v_mfma_f32_32x32x16_bf16 v[188:203], v[164:167], v[56:59], v[188:203]
	v_exp_f32_e32 v43, v43
	v_exp_f32_e32 v44, v44
	v_mfma_f32_32x32x16_bf16 v[188:203], v[168:171], v[60:63], v[188:203]
	v_exp_f32_e32 v45, v45
	v_exp_f32_e32 v46, v46
	v_exp_f32_e32 v47, v47
	v_cvt_pk_bf16_f32 v64, v32, v33
	v_cvt_pk_bf16_f32 v65, v34, v35
	v_cvt_pk_bf16_f32 v66, v36, v37
	v_cvt_pk_bf16_f32 v67, v38, v39
	v_cvt_pk_bf16_f32 v68, v40, v41
	v_cvt_pk_bf16_f32 v69, v42, v43
	v_cvt_pk_bf16_f32 v70, v44, v45
	v_cvt_pk_bf16_f32 v71, v46, v47
	v_pk_add_f32 v[232:233], v[232:233], v[32:33]
	v_pk_add_f32 v[232:233], v[232:233], v[34:35]
	v_pk_add_f32 v[232:233], v[232:233], v[36:37]
	v_pk_add_f32 v[232:233], v[232:233], v[38:39]
	v_pk_add_f32 v[232:233], v[232:233], v[40:41]
	v_pk_add_f32 v[232:233], v[232:233], v[42:43]
	v_pk_add_f32 v[232:233], v[232:233], v[44:45]
	v_pk_add_f32 v[232:233], v[232:233], v[46:47]
	v_mov_b32_e32 v115, v229
	ds_read2_b32 v[32:33], v115 offset0:0 offset1:1
	ds_read2_b32 v[34:35], v115 offset0:2 offset1:3
	ds_read2_b32 v[36:37], v115 offset0:10 offset1:11
	ds_read2_b32 v[38:39], v115 offset0:12 offset1:13
	ds_read2_b32 v[40:41], v115 offset0:20 offset1:21
	ds_read2_b32 v[42:43], v115 offset0:22 offset1:23
	ds_read2_b32 v[44:45], v115 offset0:30 offset1:31
	ds_read2_b32 v[46:47], v115 offset0:32 offset1:33
	v_mfma_f32_32x32x16_bf16 v[0:15], v[64:67], v[72:75], v[0:15]
	v_mfma_f32_32x32x16_bf16 v[16:31], v[64:67], v[76:79], v[16:31]
	v_mfma_f32_32x32x16_bf16 v[0:15], v[68:71], v[220:223], v[0:15]
	v_mfma_f32_32x32x16_bf16 v[16:31], v[68:71], v[224:227], v[16:31]
	global_load_dwordx4 v[156:159], v239, s[86:87]
	global_load_dwordx4 v[160:163], v240, s[86:87]
	global_load_dwordx4 v[164:167], v241, s[86:87]
	global_load_dwordx4 v[168:171], v242, s[86:87]
	global_load_dwordx4 v[172:175], v101, s[86:87] offset:768
	global_load_dwordx4 v[176:179], v150, s[86:87] offset:768
	global_load_dwordx4 v[180:183], v101, s[86:87] offset:832
	global_load_dwordx4 v[184:187], v150, s[86:87] offset:832
	s_add_u32 s86, s86, 0xc0000
	s_addc_u32 s87, s87, 0
	ds_read_b64_tr_b16 v[72:73], v231
	ds_read_b64_tr_b16 v[74:75], v231 offset:512
	ds_read_b64_tr_b16 v[76:77], v231 offset:2048
	ds_read_b64_tr_b16 v[78:79], v231 offset:2560
	ds_read_b64_tr_b16 v[220:221], v231 offset:1024
	ds_read_b64_tr_b16 v[222:223], v231 offset:1536
	ds_read_b64_tr_b16 v[224:225], v231 offset:3072
	ds_read_b64_tr_b16 v[226:227], v231 offset:3584
	s_waitcnt vmcnt(8)
	ds_write_b128 v247, v[116:119]
	ds_write_b128 v247, v[120:123] offset:1024
	ds_write_b128 v111, v[124:127] offset:2048
	ds_write_b128 v111, v[128:131] offset:3072
	ds_read_b128 v[116:119], v248
	ds_read_b128 v[120:123], v249
	ds_read_b128 v[124:127], v250
	ds_read_b128 v[128:131], v251
	ds_write_b128 v112, v[132:135]
	ds_write_b128 v112, v[136:139] offset:1024
	ds_write_b128 v112, v[140:143] offset:2048
	ds_write_b128 v112, v[144:147] offset:3072
	v_exp_f32_e32 v188, v188
	v_exp_f32_e32 v189, v189
	v_exp_f32_e32 v190, v190
	v_exp_f32_e32 v191, v191
	v_exp_f32_e32 v192, v192
	v_exp_f32_e32 v193, v193
	s_waitcnt lgkmcnt(4)
	v_mfma_f32_32x32x16_bf16 v[32:47], v[116:119], v[48:51], v[32:47]
	v_exp_f32_e32 v194, v194
	v_exp_f32_e32 v195, v195
	v_mfma_f32_32x32x16_bf16 v[32:47], v[120:123], v[52:55], v[32:47]
	v_exp_f32_e32 v196, v196
	v_exp_f32_e32 v197, v197
	v_exp_f32_e32 v198, v198
	v_mfma_f32_32x32x16_bf16 v[32:47], v[124:127], v[56:59], v[32:47]
	v_exp_f32_e32 v199, v199
	v_exp_f32_e32 v200, v200
	v_mfma_f32_32x32x16_bf16 v[32:47], v[128:131], v[60:63], v[32:47]
	v_exp_f32_e32 v201, v201
	v_exp_f32_e32 v202, v202
	v_exp_f32_e32 v203, v203
	v_cvt_pk_bf16_f32 v64, v188, v189
	v_cvt_pk_bf16_f32 v65, v190, v191
	v_cvt_pk_bf16_f32 v66, v192, v193
	v_cvt_pk_bf16_f32 v67, v194, v195
	v_cvt_pk_bf16_f32 v68, v196, v197
	v_cvt_pk_bf16_f32 v69, v198, v199
	v_cvt_pk_bf16_f32 v70, v200, v201
	v_cvt_pk_bf16_f32 v71, v202, v203
	v_pk_add_f32 v[232:233], v[232:233], v[188:189]
	v_pk_add_f32 v[232:233], v[232:233], v[190:191]
	v_pk_add_f32 v[232:233], v[232:233], v[192:193]
	v_pk_add_f32 v[232:233], v[232:233], v[194:195]
	v_pk_add_f32 v[232:233], v[232:233], v[196:197]
	v_pk_add_f32 v[232:233], v[232:233], v[198:199]
	v_pk_add_f32 v[232:233], v[232:233], v[200:201]
	v_pk_add_f32 v[232:233], v[232:233], v[202:203]
	ds_read2_b32 v[188:189], v115 offset0:40 offset1:41
	ds_read2_b32 v[190:191], v115 offset0:42 offset1:43
	ds_read2_b32 v[192:193], v115 offset0:50 offset1:51
	ds_read2_b32 v[194:195], v115 offset0:52 offset1:53
	ds_read2_b32 v[196:197], v115 offset0:60 offset1:61
	ds_read2_b32 v[198:199], v115 offset0:62 offset1:63
	ds_read2_b32 v[200:201], v115 offset0:70 offset1:71
	ds_read2_b32 v[202:203], v115 offset0:72 offset1:73
	v_mfma_f32_32x32x16_bf16 v[0:15], v[64:67], v[72:75], v[0:15]
	v_mfma_f32_32x32x16_bf16 v[16:31], v[64:67], v[76:79], v[16:31]
	v_mfma_f32_32x32x16_bf16 v[0:15], v[68:71], v[220:223], v[0:15]
	v_mfma_f32_32x32x16_bf16 v[16:31], v[68:71], v[224:227], v[16:31]
	global_load_dwordx4 v[116:119], v239, s[86:87]
	global_load_dwordx4 v[120:123], v240, s[86:87]
	global_load_dwordx4 v[124:127], v241, s[86:87]
	global_load_dwordx4 v[128:131], v242, s[86:87]
	global_load_dwordx4 v[132:135], v101, s[86:87] offset:768
	global_load_dwordx4 v[136:139], v150, s[86:87] offset:768
	global_load_dwordx4 v[140:143], v101, s[86:87] offset:832
	global_load_dwordx4 v[144:147], v150, s[86:87] offset:832
	s_add_u32 s86, s86, 0xc0000
	s_addc_u32 s87, s87, 0
	ds_read_b64_tr_b16 v[72:73], v231
	ds_read_b64_tr_b16 v[74:75], v231 offset:512
	ds_read_b64_tr_b16 v[76:77], v231 offset:2048
	ds_read_b64_tr_b16 v[78:79], v231 offset:2560
	ds_read_b64_tr_b16 v[220:221], v231 offset:1024
	ds_read_b64_tr_b16 v[222:223], v231 offset:1536
	ds_read_b64_tr_b16 v[224:225], v231 offset:3072
	ds_read_b64_tr_b16 v[226:227], v231 offset:3584
	s_waitcnt vmcnt(8)
	ds_write_b128 v247, v[156:159]
	ds_write_b128 v247, v[160:163] offset:1024
	ds_write_b128 v111, v[164:167] offset:2048
	ds_write_b128 v111, v[168:171] offset:3072
	ds_read_b128 v[156:159], v248
	ds_read_b128 v[160:163], v249
	ds_read_b128 v[164:167], v250
	ds_read_b128 v[168:171], v251
	ds_write_b128 v112, v[172:175]
	ds_write_b128 v112, v[176:179] offset:1024
	ds_write_b128 v112, v[180:183] offset:2048
	ds_write_b128 v112, v[184:187] offset:3072
	v_exp_f32_e32 v32, v32
	v_exp_f32_e32 v33, v33
	v_exp_f32_e32 v34, v34
	v_exp_f32_e32 v35, v35
	v_exp_f32_e32 v36, v36
	v_exp_f32_e32 v37, v37
	s_waitcnt lgkmcnt(4)
	v_mfma_f32_32x32x16_bf16 v[188:203], v[156:159], v[48:51], v[188:203]
	v_exp_f32_e32 v38, v38
	v_exp_f32_e32 v39, v39
	v_mfma_f32_32x32x16_bf16 v[188:203], v[160:163], v[52:55], v[188:203]
	v_exp_f32_e32 v40, v40
	v_exp_f32_e32 v41, v41
	v_exp_f32_e32 v42, v42
	v_mfma_f32_32x32x16_bf16 v[188:203], v[164:167], v[56:59], v[188:203]
	v_exp_f32_e32 v43, v43
	v_exp_f32_e32 v44, v44
	v_mfma_f32_32x32x16_bf16 v[188:203], v[168:171], v[60:63], v[188:203]
	v_exp_f32_e32 v45, v45
	v_exp_f32_e32 v46, v46
	v_exp_f32_e32 v47, v47
	v_cvt_pk_bf16_f32 v64, v32, v33
	v_cvt_pk_bf16_f32 v65, v34, v35
	v_cvt_pk_bf16_f32 v66, v36, v37
	v_cvt_pk_bf16_f32 v67, v38, v39
	v_cvt_pk_bf16_f32 v68, v40, v41
	v_cvt_pk_bf16_f32 v69, v42, v43
	v_cvt_pk_bf16_f32 v70, v44, v45
	v_cvt_pk_bf16_f32 v71, v46, v47
	v_pk_add_f32 v[232:233], v[232:233], v[32:33]
	v_pk_add_f32 v[232:233], v[232:233], v[34:35]
	v_pk_add_f32 v[232:233], v[232:233], v[36:37]
	v_pk_add_f32 v[232:233], v[232:233], v[38:39]
	v_pk_add_f32 v[232:233], v[232:233], v[40:41]
	v_pk_add_f32 v[232:233], v[232:233], v[42:43]
	v_pk_add_f32 v[232:233], v[232:233], v[44:45]
	v_pk_add_f32 v[232:233], v[232:233], v[46:47]
	ds_read2_b32 v[32:33], v115 offset0:80 offset1:81
	ds_read2_b32 v[34:35], v115 offset0:82 offset1:83
	ds_read2_b32 v[36:37], v115 offset0:90 offset1:91
	ds_read2_b32 v[38:39], v115 offset0:92 offset1:93
	ds_read2_b32 v[40:41], v115 offset0:100 offset1:101
	ds_read2_b32 v[42:43], v115 offset0:102 offset1:103
	ds_read2_b32 v[44:45], v115 offset0:110 offset1:111
	ds_read2_b32 v[46:47], v115 offset0:112 offset1:113
	v_mfma_f32_32x32x16_bf16 v[0:15], v[64:67], v[72:75], v[0:15]
	v_mfma_f32_32x32x16_bf16 v[16:31], v[64:67], v[76:79], v[16:31]
	v_mfma_f32_32x32x16_bf16 v[0:15], v[68:71], v[220:223], v[0:15]
	v_mfma_f32_32x32x16_bf16 v[16:31], v[68:71], v[224:227], v[16:31]
	global_load_dwordx4 v[156:159], v239, s[86:87]
	global_load_dwordx4 v[160:163], v240, s[86:87]
	global_load_dwordx4 v[164:167], v241, s[86:87]
	global_load_dwordx4 v[168:171], v242, s[86:87]
	global_load_dwordx4 v[172:175], v101, s[86:87] offset:768
	global_load_dwordx4 v[176:179], v150, s[86:87] offset:768
	global_load_dwordx4 v[180:183], v101, s[86:87] offset:832
	global_load_dwordx4 v[184:187], v150, s[86:87] offset:832
	s_add_u32 s86, s86, 0xc0000
	s_addc_u32 s87, s87, 0
	ds_read_b64_tr_b16 v[72:73], v231
	ds_read_b64_tr_b16 v[74:75], v231 offset:512
	ds_read_b64_tr_b16 v[76:77], v231 offset:2048
	ds_read_b64_tr_b16 v[78:79], v231 offset:2560
	ds_read_b64_tr_b16 v[220:221], v231 offset:1024
	ds_read_b64_tr_b16 v[222:223], v231 offset:1536
	ds_read_b64_tr_b16 v[224:225], v231 offset:3072
	ds_read_b64_tr_b16 v[226:227], v231 offset:3584
	s_waitcnt vmcnt(8)
	ds_write_b128 v247, v[116:119]
	ds_write_b128 v247, v[120:123] offset:1024
	ds_write_b128 v111, v[124:127] offset:2048
	ds_write_b128 v111, v[128:131] offset:3072
	ds_read_b128 v[116:119], v248
	ds_read_b128 v[120:123], v249
	ds_read_b128 v[124:127], v250
	ds_read_b128 v[128:131], v251
	ds_write_b128 v112, v[132:135]
	ds_write_b128 v112, v[136:139] offset:1024
	ds_write_b128 v112, v[140:143] offset:2048
	ds_write_b128 v112, v[144:147] offset:3072
	v_exp_f32_e32 v188, v188
	v_exp_f32_e32 v189, v189
	v_exp_f32_e32 v190, v190
	v_exp_f32_e32 v191, v191
	v_exp_f32_e32 v192, v192
	v_exp_f32_e32 v193, v193
	s_waitcnt lgkmcnt(4)
	v_mfma_f32_32x32x16_bf16 v[32:47], v[116:119], v[48:51], v[32:47]
	v_exp_f32_e32 v194, v194
	v_exp_f32_e32 v195, v195
	v_mfma_f32_32x32x16_bf16 v[32:47], v[120:123], v[52:55], v[32:47]
	v_exp_f32_e32 v196, v196
	v_exp_f32_e32 v197, v197
	v_exp_f32_e32 v198, v198
	v_mfma_f32_32x32x16_bf16 v[32:47], v[124:127], v[56:59], v[32:47]
	v_exp_f32_e32 v199, v199
	v_exp_f32_e32 v200, v200
	v_mfma_f32_32x32x16_bf16 v[32:47], v[128:131], v[60:63], v[32:47]
	v_exp_f32_e32 v201, v201
	v_exp_f32_e32 v202, v202
	v_exp_f32_e32 v203, v203
	v_cvt_pk_bf16_f32 v64, v188, v189
	v_cvt_pk_bf16_f32 v65, v190, v191
	v_cvt_pk_bf16_f32 v66, v192, v193
	v_cvt_pk_bf16_f32 v67, v194, v195
	v_cvt_pk_bf16_f32 v68, v196, v197
	v_cvt_pk_bf16_f32 v69, v198, v199
	v_cvt_pk_bf16_f32 v70, v200, v201
	v_cvt_pk_bf16_f32 v71, v202, v203
	v_pk_add_f32 v[232:233], v[232:233], v[188:189]
	v_pk_add_f32 v[232:233], v[232:233], v[190:191]
	v_pk_add_f32 v[232:233], v[232:233], v[192:193]
	v_pk_add_f32 v[232:233], v[232:233], v[194:195]
	v_pk_add_f32 v[232:233], v[232:233], v[196:197]
	v_pk_add_f32 v[232:233], v[232:233], v[198:199]
	v_pk_add_f32 v[232:233], v[232:233], v[200:201]
	v_pk_add_f32 v[232:233], v[232:233], v[202:203]
	ds_read2_b32 v[188:189], v115 offset0:120 offset1:121
	ds_read2_b32 v[190:191], v115 offset0:122 offset1:123
	ds_read2_b32 v[192:193], v115 offset0:130 offset1:131
	ds_read2_b32 v[194:195], v115 offset0:132 offset1:133
	ds_read2_b32 v[196:197], v115 offset0:140 offset1:141
	ds_read2_b32 v[198:199], v115 offset0:142 offset1:143
	ds_read2_b32 v[200:201], v115 offset0:150 offset1:151
	ds_read2_b32 v[202:203], v115 offset0:152 offset1:153
	v_mfma_f32_32x32x16_bf16 v[0:15], v[64:67], v[72:75], v[0:15]
	v_mfma_f32_32x32x16_bf16 v[16:31], v[64:67], v[76:79], v[16:31]
	v_mfma_f32_32x32x16_bf16 v[0:15], v[68:71], v[220:223], v[0:15]
	v_mfma_f32_32x32x16_bf16 v[16:31], v[68:71], v[224:227], v[16:31]
	global_load_dwordx4 v[116:119], v239, s[86:87]
	global_load_dwordx4 v[120:123], v240, s[86:87]
	global_load_dwordx4 v[124:127], v241, s[86:87]
	global_load_dwordx4 v[128:131], v242, s[86:87]
	global_load_dwordx4 v[132:135], v101, s[86:87] offset:768
	global_load_dwordx4 v[136:139], v150, s[86:87] offset:768
	global_load_dwordx4 v[140:143], v101, s[86:87] offset:832
	global_load_dwordx4 v[144:147], v150, s[86:87] offset:832
	s_add_u32 s86, s86, 0xc0000
	s_addc_u32 s87, s87, 0
	ds_read_b64_tr_b16 v[72:73], v231
	ds_read_b64_tr_b16 v[74:75], v231 offset:512
	ds_read_b64_tr_b16 v[76:77], v231 offset:2048
	ds_read_b64_tr_b16 v[78:79], v231 offset:2560
	ds_read_b64_tr_b16 v[220:221], v231 offset:1024
	ds_read_b64_tr_b16 v[222:223], v231 offset:1536
	ds_read_b64_tr_b16 v[224:225], v231 offset:3072
	ds_read_b64_tr_b16 v[226:227], v231 offset:3584
	s_waitcnt vmcnt(8)
	ds_write_b128 v247, v[156:159]
	ds_write_b128 v247, v[160:163] offset:1024
	ds_write_b128 v111, v[164:167] offset:2048
	ds_write_b128 v111, v[168:171] offset:3072
	ds_read_b128 v[156:159], v248
	ds_read_b128 v[160:163], v249
	ds_read_b128 v[164:167], v250
	ds_read_b128 v[168:171], v251
	ds_write_b128 v112, v[172:175]
	ds_write_b128 v112, v[176:179] offset:1024
	ds_write_b128 v112, v[180:183] offset:2048
	ds_write_b128 v112, v[184:187] offset:3072
	v_exp_f32_e32 v32, v32
	v_exp_f32_e32 v33, v33
	v_exp_f32_e32 v34, v34
	v_exp_f32_e32 v35, v35
	v_exp_f32_e32 v36, v36
	v_exp_f32_e32 v37, v37
	s_waitcnt lgkmcnt(4)
	v_mfma_f32_32x32x16_bf16 v[188:203], v[156:159], v[48:51], v[188:203]
	v_exp_f32_e32 v38, v38
	v_exp_f32_e32 v39, v39
	v_mfma_f32_32x32x16_bf16 v[188:203], v[160:163], v[52:55], v[188:203]
	v_exp_f32_e32 v40, v40
	v_exp_f32_e32 v41, v41
	v_exp_f32_e32 v42, v42
	v_mfma_f32_32x32x16_bf16 v[188:203], v[164:167], v[56:59], v[188:203]
	v_exp_f32_e32 v43, v43
	v_exp_f32_e32 v44, v44
	v_mfma_f32_32x32x16_bf16 v[188:203], v[168:171], v[60:63], v[188:203]
	v_exp_f32_e32 v45, v45
	v_exp_f32_e32 v46, v46
	v_exp_f32_e32 v47, v47
	v_cvt_pk_bf16_f32 v64, v32, v33
	v_cvt_pk_bf16_f32 v65, v34, v35
	v_cvt_pk_bf16_f32 v66, v36, v37
	v_cvt_pk_bf16_f32 v67, v38, v39
	v_cvt_pk_bf16_f32 v68, v40, v41
	v_cvt_pk_bf16_f32 v69, v42, v43
	v_cvt_pk_bf16_f32 v70, v44, v45
	v_cvt_pk_bf16_f32 v71, v46, v47
	v_pk_add_f32 v[232:233], v[232:233], v[32:33]
	v_pk_add_f32 v[232:233], v[232:233], v[34:35]
	v_pk_add_f32 v[232:233], v[232:233], v[36:37]
	v_pk_add_f32 v[232:233], v[232:233], v[38:39]
	v_pk_add_f32 v[232:233], v[232:233], v[40:41]
	v_pk_add_f32 v[232:233], v[232:233], v[42:43]
	v_pk_add_f32 v[232:233], v[232:233], v[44:45]
	v_pk_add_f32 v[232:233], v[232:233], v[46:47]
	v_add_u32_e32 v115, 640, v115
	ds_read2_b32 v[32:33], v115 offset0:0 offset1:1
	ds_read2_b32 v[34:35], v115 offset0:2 offset1:3
	ds_read2_b32 v[36:37], v115 offset0:10 offset1:11
	ds_read2_b32 v[38:39], v115 offset0:12 offset1:13
	ds_read2_b32 v[40:41], v115 offset0:20 offset1:21
	ds_read2_b32 v[42:43], v115 offset0:22 offset1:23
	ds_read2_b32 v[44:45], v115 offset0:30 offset1:31
	ds_read2_b32 v[46:47], v115 offset0:32 offset1:33
	v_mfma_f32_32x32x16_bf16 v[0:15], v[64:67], v[72:75], v[0:15]
	v_mfma_f32_32x32x16_bf16 v[16:31], v[64:67], v[76:79], v[16:31]
	v_mfma_f32_32x32x16_bf16 v[0:15], v[68:71], v[220:223], v[0:15]
	v_mfma_f32_32x32x16_bf16 v[16:31], v[68:71], v[224:227], v[16:31]
	global_load_dwordx4 v[156:159], v239, s[86:87]
	global_load_dwordx4 v[160:163], v240, s[86:87]
	global_load_dwordx4 v[164:167], v241, s[86:87]
	global_load_dwordx4 v[168:171], v242, s[86:87]
	global_load_dwordx4 v[172:175], v101, s[86:87] offset:768
	global_load_dwordx4 v[176:179], v150, s[86:87] offset:768
	global_load_dwordx4 v[180:183], v101, s[86:87] offset:832
	global_load_dwordx4 v[184:187], v150, s[86:87] offset:832
	s_add_u32 s86, s86, 0xc0000
	s_addc_u32 s87, s87, 0
	ds_read_b64_tr_b16 v[72:73], v231
	ds_read_b64_tr_b16 v[74:75], v231 offset:512
	ds_read_b64_tr_b16 v[76:77], v231 offset:2048
	ds_read_b64_tr_b16 v[78:79], v231 offset:2560
	ds_read_b64_tr_b16 v[220:221], v231 offset:1024
	ds_read_b64_tr_b16 v[222:223], v231 offset:1536
	ds_read_b64_tr_b16 v[224:225], v231 offset:3072
	ds_read_b64_tr_b16 v[226:227], v231 offset:3584
	s_waitcnt vmcnt(8)
	ds_write_b128 v247, v[116:119]
	ds_write_b128 v247, v[120:123] offset:1024
	ds_write_b128 v111, v[124:127] offset:2048
	ds_write_b128 v111, v[128:131] offset:3072
	ds_read_b128 v[116:119], v248
	ds_read_b128 v[120:123], v249
	ds_read_b128 v[124:127], v250
	ds_read_b128 v[128:131], v251
	ds_write_b128 v112, v[132:135]
	ds_write_b128 v112, v[136:139] offset:1024
	ds_write_b128 v112, v[140:143] offset:2048
	ds_write_b128 v112, v[144:147] offset:3072
	v_exp_f32_e32 v188, v188
	v_exp_f32_e32 v189, v189
	v_exp_f32_e32 v190, v190
	v_exp_f32_e32 v191, v191
	v_exp_f32_e32 v192, v192
	v_exp_f32_e32 v193, v193
	s_waitcnt lgkmcnt(4)
	v_mfma_f32_32x32x16_bf16 v[32:47], v[116:119], v[48:51], v[32:47]
	v_exp_f32_e32 v194, v194
	v_exp_f32_e32 v195, v195
	v_mfma_f32_32x32x16_bf16 v[32:47], v[120:123], v[52:55], v[32:47]
	v_exp_f32_e32 v196, v196
	v_exp_f32_e32 v197, v197
	v_exp_f32_e32 v198, v198
	v_mfma_f32_32x32x16_bf16 v[32:47], v[124:127], v[56:59], v[32:47]
	v_exp_f32_e32 v199, v199
	v_exp_f32_e32 v200, v200
	v_mfma_f32_32x32x16_bf16 v[32:47], v[128:131], v[60:63], v[32:47]
	v_exp_f32_e32 v201, v201
	v_exp_f32_e32 v202, v202
	v_exp_f32_e32 v203, v203
	v_cvt_pk_bf16_f32 v64, v188, v189
	v_cvt_pk_bf16_f32 v65, v190, v191
	v_cvt_pk_bf16_f32 v66, v192, v193
	v_cvt_pk_bf16_f32 v67, v194, v195
	v_cvt_pk_bf16_f32 v68, v196, v197
	v_cvt_pk_bf16_f32 v69, v198, v199
	v_cvt_pk_bf16_f32 v70, v200, v201
	v_cvt_pk_bf16_f32 v71, v202, v203
	v_pk_add_f32 v[232:233], v[232:233], v[188:189]
	v_pk_add_f32 v[232:233], v[232:233], v[190:191]
	v_pk_add_f32 v[232:233], v[232:233], v[192:193]
	v_pk_add_f32 v[232:233], v[232:233], v[194:195]
	v_pk_add_f32 v[232:233], v[232:233], v[196:197]
	v_pk_add_f32 v[232:233], v[232:233], v[198:199]
	v_pk_add_f32 v[232:233], v[232:233], v[200:201]
	v_pk_add_f32 v[232:233], v[232:233], v[202:203]
	ds_read2_b32 v[188:189], v115 offset0:40 offset1:41
	ds_read2_b32 v[190:191], v115 offset0:42 offset1:43
	ds_read2_b32 v[192:193], v115 offset0:50 offset1:51
	ds_read2_b32 v[194:195], v115 offset0:52 offset1:53
	ds_read2_b32 v[196:197], v115 offset0:60 offset1:61
	ds_read2_b32 v[198:199], v115 offset0:62 offset1:63
	ds_read2_b32 v[200:201], v115 offset0:70 offset1:71
	ds_read2_b32 v[202:203], v115 offset0:72 offset1:73
	v_mfma_f32_32x32x16_bf16 v[0:15], v[64:67], v[72:75], v[0:15]
	v_mfma_f32_32x32x16_bf16 v[16:31], v[64:67], v[76:79], v[16:31]
	v_mfma_f32_32x32x16_bf16 v[0:15], v[68:71], v[220:223], v[0:15]
	v_mfma_f32_32x32x16_bf16 v[16:31], v[68:71], v[224:227], v[16:31]
	global_load_dwordx4 v[116:119], v239, s[86:87]
	global_load_dwordx4 v[120:123], v240, s[86:87]
	global_load_dwordx4 v[124:127], v241, s[86:87]
	global_load_dwordx4 v[128:131], v242, s[86:87]
	global_load_dwordx4 v[132:135], v101, s[86:87] offset:768
	global_load_dwordx4 v[136:139], v150, s[86:87] offset:768
	global_load_dwordx4 v[140:143], v101, s[86:87] offset:832
	global_load_dwordx4 v[144:147], v150, s[86:87] offset:832
	s_add_u32 s86, s86, 0xc0000
	s_addc_u32 s87, s87, 0
	ds_read_b64_tr_b16 v[72:73], v231
	ds_read_b64_tr_b16 v[74:75], v231 offset:512
	ds_read_b64_tr_b16 v[76:77], v231 offset:2048
	ds_read_b64_tr_b16 v[78:79], v231 offset:2560
	ds_read_b64_tr_b16 v[220:221], v231 offset:1024
	ds_read_b64_tr_b16 v[222:223], v231 offset:1536
	ds_read_b64_tr_b16 v[224:225], v231 offset:3072
	ds_read_b64_tr_b16 v[226:227], v231 offset:3584
	s_waitcnt vmcnt(8)
	ds_write_b128 v247, v[156:159]
	ds_write_b128 v247, v[160:163] offset:1024
	ds_write_b128 v111, v[164:167] offset:2048
	ds_write_b128 v111, v[168:171] offset:3072
	ds_read_b128 v[156:159], v248
	ds_read_b128 v[160:163], v249
	ds_read_b128 v[164:167], v250
	ds_read_b128 v[168:171], v251
	ds_write_b128 v112, v[172:175]
	ds_write_b128 v112, v[176:179] offset:1024
	ds_write_b128 v112, v[180:183] offset:2048
	ds_write_b128 v112, v[184:187] offset:3072
	v_exp_f32_e32 v32, v32
	v_exp_f32_e32 v33, v33
	v_exp_f32_e32 v34, v34
	v_exp_f32_e32 v35, v35
	v_exp_f32_e32 v36, v36
	v_exp_f32_e32 v37, v37
	s_waitcnt lgkmcnt(4)
	v_mfma_f32_32x32x16_bf16 v[188:203], v[156:159], v[48:51], v[188:203]
	v_exp_f32_e32 v38, v38
	v_exp_f32_e32 v39, v39
	v_mfma_f32_32x32x16_bf16 v[188:203], v[160:163], v[52:55], v[188:203]
	v_exp_f32_e32 v40, v40
	v_exp_f32_e32 v41, v41
	v_exp_f32_e32 v42, v42
	v_mfma_f32_32x32x16_bf16 v[188:203], v[164:167], v[56:59], v[188:203]
	v_exp_f32_e32 v43, v43
	v_exp_f32_e32 v44, v44
	v_mfma_f32_32x32x16_bf16 v[188:203], v[168:171], v[60:63], v[188:203]
	v_exp_f32_e32 v45, v45
	v_exp_f32_e32 v46, v46
	v_exp_f32_e32 v47, v47
	v_cvt_pk_bf16_f32 v64, v32, v33
	v_cvt_pk_bf16_f32 v65, v34, v35
	v_cvt_pk_bf16_f32 v66, v36, v37
	v_cvt_pk_bf16_f32 v67, v38, v39
	v_cvt_pk_bf16_f32 v68, v40, v41
	v_cvt_pk_bf16_f32 v69, v42, v43
	v_cvt_pk_bf16_f32 v70, v44, v45
	v_cvt_pk_bf16_f32 v71, v46, v47
	v_pk_add_f32 v[232:233], v[232:233], v[32:33]
	v_pk_add_f32 v[232:233], v[232:233], v[34:35]
	v_pk_add_f32 v[232:233], v[232:233], v[36:37]
	v_pk_add_f32 v[232:233], v[232:233], v[38:39]
	v_pk_add_f32 v[232:233], v[232:233], v[40:41]
	v_pk_add_f32 v[232:233], v[232:233], v[42:43]
	v_pk_add_f32 v[232:233], v[232:233], v[44:45]
	v_pk_add_f32 v[232:233], v[232:233], v[46:47]
	ds_read2_b32 v[32:33], v115 offset0:80 offset1:81
	ds_read2_b32 v[34:35], v115 offset0:82 offset1:83
	ds_read2_b32 v[36:37], v115 offset0:90 offset1:91
	ds_read2_b32 v[38:39], v115 offset0:92 offset1:93
	ds_read2_b32 v[40:41], v115 offset0:100 offset1:101
	ds_read2_b32 v[42:43], v115 offset0:102 offset1:103
	ds_read2_b32 v[44:45], v115 offset0:110 offset1:111
	ds_read2_b32 v[46:47], v115 offset0:112 offset1:113
	v_mfma_f32_32x32x16_bf16 v[0:15], v[64:67], v[72:75], v[0:15]
	v_mfma_f32_32x32x16_bf16 v[16:31], v[64:67], v[76:79], v[16:31]
	v_mfma_f32_32x32x16_bf16 v[0:15], v[68:71], v[220:223], v[0:15]
	v_mfma_f32_32x32x16_bf16 v[16:31], v[68:71], v[224:227], v[16:31]
	global_load_dwordx4 v[156:159], v239, s[86:87]
	global_load_dwordx4 v[160:163], v240, s[86:87]
	global_load_dwordx4 v[164:167], v241, s[86:87]
	global_load_dwordx4 v[168:171], v242, s[86:87]
	global_load_dwordx4 v[172:175], v101, s[86:87] offset:768
	global_load_dwordx4 v[176:179], v150, s[86:87] offset:768
	global_load_dwordx4 v[180:183], v101, s[86:87] offset:832
	global_load_dwordx4 v[184:187], v150, s[86:87] offset:832
	ds_read_b64_tr_b16 v[72:73], v231
	ds_read_b64_tr_b16 v[74:75], v231 offset:512
	ds_read_b64_tr_b16 v[76:77], v231 offset:2048
	ds_read_b64_tr_b16 v[78:79], v231 offset:2560
	ds_read_b64_tr_b16 v[220:221], v231 offset:1024
	ds_read_b64_tr_b16 v[222:223], v231 offset:1536
	ds_read_b64_tr_b16 v[224:225], v231 offset:3072
	ds_read_b64_tr_b16 v[226:227], v231 offset:3584
	s_waitcnt vmcnt(8)
	ds_write_b128 v247, v[116:119]
	ds_write_b128 v247, v[120:123] offset:1024
	ds_write_b128 v111, v[124:127] offset:2048
	ds_write_b128 v111, v[128:131] offset:3072
	ds_read_b128 v[116:119], v248
	ds_read_b128 v[120:123], v249
	ds_read_b128 v[124:127], v250
	ds_read_b128 v[128:131], v251
	ds_write_b128 v112, v[132:135]
	ds_write_b128 v112, v[136:139] offset:1024
	ds_write_b128 v112, v[140:143] offset:2048
	ds_write_b128 v112, v[144:147] offset:3072
	v_exp_f32_e32 v188, v188
	v_exp_f32_e32 v189, v189
	v_exp_f32_e32 v190, v190
	v_exp_f32_e32 v191, v191
	v_exp_f32_e32 v192, v192
	v_exp_f32_e32 v193, v193
	s_waitcnt lgkmcnt(4)
	v_mfma_f32_32x32x16_bf16 v[32:47], v[116:119], v[48:51], v[32:47]
	v_exp_f32_e32 v194, v194
	v_exp_f32_e32 v195, v195
	v_mfma_f32_32x32x16_bf16 v[32:47], v[120:123], v[52:55], v[32:47]
	v_exp_f32_e32 v196, v196
	v_exp_f32_e32 v197, v197
	v_exp_f32_e32 v198, v198
	v_mfma_f32_32x32x16_bf16 v[32:47], v[124:127], v[56:59], v[32:47]
	v_exp_f32_e32 v199, v199
	v_exp_f32_e32 v200, v200
	v_mfma_f32_32x32x16_bf16 v[32:47], v[128:131], v[60:63], v[32:47]
	v_exp_f32_e32 v201, v201
	v_exp_f32_e32 v202, v202
	v_exp_f32_e32 v203, v203
	v_cvt_pk_bf16_f32 v64, v188, v189
	v_cvt_pk_bf16_f32 v65, v190, v191
	v_cvt_pk_bf16_f32 v66, v192, v193
	v_cvt_pk_bf16_f32 v67, v194, v195
	v_cvt_pk_bf16_f32 v68, v196, v197
	v_cvt_pk_bf16_f32 v69, v198, v199
	v_cvt_pk_bf16_f32 v70, v200, v201
	v_cvt_pk_bf16_f32 v71, v202, v203
	v_pk_add_f32 v[232:233], v[232:233], v[188:189]
	v_pk_add_f32 v[232:233], v[232:233], v[190:191]
	v_pk_add_f32 v[232:233], v[232:233], v[192:193]
	v_pk_add_f32 v[232:233], v[232:233], v[194:195]
	v_pk_add_f32 v[232:233], v[232:233], v[196:197]
	v_pk_add_f32 v[232:233], v[232:233], v[198:199]
	v_pk_add_f32 v[232:233], v[232:233], v[200:201]
	v_pk_add_f32 v[232:233], v[232:233], v[202:203]
	ds_read2_b32 v[188:189], v115 offset0:120 offset1:121
	ds_read2_b32 v[190:191], v115 offset0:122 offset1:123
	ds_read2_b32 v[192:193], v115 offset0:130 offset1:131
	ds_read2_b32 v[194:195], v115 offset0:132 offset1:133
	ds_read2_b32 v[196:197], v115 offset0:140 offset1:141
	ds_read2_b32 v[198:199], v115 offset0:142 offset1:143
	ds_read2_b32 v[200:201], v115 offset0:150 offset1:151
	ds_read2_b32 v[202:203], v115 offset0:152 offset1:153
	v_mfma_f32_32x32x16_bf16 v[0:15], v[64:67], v[72:75], v[0:15]
	v_mfma_f32_32x32x16_bf16 v[16:31], v[64:67], v[76:79], v[16:31]
	v_mfma_f32_32x32x16_bf16 v[0:15], v[68:71], v[220:223], v[0:15]
	v_mfma_f32_32x32x16_bf16 v[16:31], v[68:71], v[224:227], v[16:31]
	global_load_dwordx4 v[116:119], v243, s[88:89]
	global_load_dwordx4 v[120:123], v244, s[88:89]
	global_load_dwordx4 v[124:127], v245, s[88:89]
	global_load_dwordx4 v[128:131], v246, s[88:89]
	global_load_dwordx4 v[132:135], v148, s[88:89] offset:768
	global_load_dwordx4 v[136:139], v151, s[88:89] offset:768
	global_load_dwordx4 v[140:143], v148, s[88:89] offset:832
	global_load_dwordx4 v[144:147], v151, s[88:89] offset:832
	s_add_u32 s88, s88, 0x300000
	s_addc_u32 s89, s89, 0
	ds_read_b64_tr_b16 v[72:73], v231
	ds_read_b64_tr_b16 v[74:75], v231 offset:512
	ds_read_b64_tr_b16 v[76:77], v231 offset:2048
	ds_read_b64_tr_b16 v[78:79], v231 offset:2560
	ds_read_b64_tr_b16 v[220:221], v231 offset:1024
	ds_read_b64_tr_b16 v[222:223], v231 offset:1536
	ds_read_b64_tr_b16 v[224:225], v231 offset:3072
	ds_read_b64_tr_b16 v[226:227], v231 offset:3584
	s_waitcnt vmcnt(8)
	ds_write_b128 v247, v[156:159]
	ds_write_b128 v247, v[160:163] offset:1024
	ds_write_b128 v111, v[164:167] offset:2048
	ds_write_b128 v111, v[168:171] offset:3072
	ds_read_b128 v[156:159], v248
	ds_read_b128 v[160:163], v249
	ds_read_b128 v[164:167], v250
	ds_read_b128 v[168:171], v251
	ds_write_b128 v112, v[172:175]
	ds_write_b128 v112, v[176:179] offset:1024
	ds_write_b128 v112, v[180:183] offset:2048
	ds_write_b128 v112, v[184:187] offset:3072
	v_exp_f32_e32 v32, v32
	v_exp_f32_e32 v33, v33
	v_exp_f32_e32 v34, v34
	v_exp_f32_e32 v35, v35
	v_exp_f32_e32 v36, v36
	v_exp_f32_e32 v37, v37
	s_waitcnt lgkmcnt(4)
	v_mfma_f32_32x32x16_bf16 v[188:203], v[156:159], v[48:51], v[188:203]
	v_exp_f32_e32 v38, v38
	v_exp_f32_e32 v39, v39
	v_mfma_f32_32x32x16_bf16 v[188:203], v[160:163], v[52:55], v[188:203]
	v_exp_f32_e32 v40, v40
	v_exp_f32_e32 v41, v41
	v_exp_f32_e32 v42, v42
	v_mfma_f32_32x32x16_bf16 v[188:203], v[164:167], v[56:59], v[188:203]
	v_exp_f32_e32 v43, v43
	v_exp_f32_e32 v44, v44
	v_mfma_f32_32x32x16_bf16 v[188:203], v[168:171], v[60:63], v[188:203]
	v_exp_f32_e32 v45, v45
	v_exp_f32_e32 v46, v46
	v_exp_f32_e32 v47, v47
	v_cvt_pk_bf16_f32 v64, v32, v33
	v_cvt_pk_bf16_f32 v65, v34, v35
	v_cvt_pk_bf16_f32 v66, v36, v37
	v_cvt_pk_bf16_f32 v67, v38, v39
	v_cvt_pk_bf16_f32 v68, v40, v41
	v_cvt_pk_bf16_f32 v69, v42, v43
	v_cvt_pk_bf16_f32 v70, v44, v45
	v_cvt_pk_bf16_f32 v71, v46, v47
	v_pk_add_f32 v[232:233], v[232:233], v[32:33]
	v_pk_add_f32 v[232:233], v[232:233], v[34:35]
	v_pk_add_f32 v[232:233], v[232:233], v[36:37]
	v_pk_add_f32 v[232:233], v[232:233], v[38:39]
	v_pk_add_f32 v[232:233], v[232:233], v[40:41]
	v_pk_add_f32 v[232:233], v[232:233], v[42:43]
	v_pk_add_f32 v[232:233], v[232:233], v[44:45]
	v_pk_add_f32 v[232:233], v[232:233], v[46:47]
	v_mov_b32_e32 v115, v230
	ds_read2_b32 v[32:33], v115 offset0:0 offset1:1
	ds_read2_b32 v[34:35], v115 offset0:2 offset1:3
	ds_read2_b32 v[36:37], v115 offset0:8 offset1:9
	ds_read2_b32 v[38:39], v115 offset0:10 offset1:11
	ds_read2_b32 v[40:41], v115 offset0:16 offset1:17
	ds_read2_b32 v[42:43], v115 offset0:18 offset1:19
	ds_read2_b32 v[44:45], v115 offset0:24 offset1:25
	ds_read2_b32 v[46:47], v115 offset0:26 offset1:27
	v_mfma_f32_32x32x16_bf16 v[0:15], v[64:67], v[72:75], v[0:15]
	v_mfma_f32_32x32x16_bf16 v[16:31], v[64:67], v[76:79], v[16:31]
	v_mfma_f32_32x32x16_bf16 v[0:15], v[68:71], v[220:223], v[0:15]
	v_mfma_f32_32x32x16_bf16 v[16:31], v[68:71], v[224:227], v[16:31]
	global_load_dwordx4 v[156:159], v243, s[88:89]
	global_load_dwordx4 v[160:163], v244, s[88:89]
	global_load_dwordx4 v[164:167], v245, s[88:89]
	global_load_dwordx4 v[168:171], v246, s[88:89]
	global_load_dwordx4 v[172:175], v148, s[88:89] offset:768
	global_load_dwordx4 v[176:179], v151, s[88:89] offset:768
	global_load_dwordx4 v[180:183], v148, s[88:89] offset:832
	global_load_dwordx4 v[184:187], v151, s[88:89] offset:832
	s_add_u32 s88, s88, 0x300000
	s_addc_u32 s89, s89, 0
	ds_read_b64_tr_b16 v[72:73], v231
	ds_read_b64_tr_b16 v[74:75], v231 offset:512
	ds_read_b64_tr_b16 v[76:77], v231 offset:2048
	ds_read_b64_tr_b16 v[78:79], v231 offset:2560
	ds_read_b64_tr_b16 v[220:221], v231 offset:1024
	ds_read_b64_tr_b16 v[222:223], v231 offset:1536
	ds_read_b64_tr_b16 v[224:225], v231 offset:3072
	ds_read_b64_tr_b16 v[226:227], v231 offset:3584
	s_waitcnt vmcnt(8)
	ds_write_b128 v247, v[116:119]
	ds_write_b128 v247, v[120:123] offset:1024
	ds_write_b128 v111, v[124:127] offset:2048
	ds_write_b128 v111, v[128:131] offset:3072
	ds_read_b128 v[116:119], v248
	ds_read_b128 v[120:123], v249
	ds_read_b128 v[124:127], v250
	ds_read_b128 v[128:131], v251
	ds_write_b128 v112, v[132:135]
	ds_write_b128 v112, v[136:139] offset:1024
	ds_write_b128 v112, v[140:143] offset:2048
	ds_write_b128 v112, v[144:147] offset:3072
	v_exp_f32_e32 v188, v188
	v_exp_f32_e32 v189, v189
	v_exp_f32_e32 v190, v190
	v_exp_f32_e32 v191, v191
	v_exp_f32_e32 v192, v192
	v_exp_f32_e32 v193, v193
	s_waitcnt lgkmcnt(4)
	v_mfma_f32_32x32x16_bf16 v[32:47], v[116:119], v[48:51], v[32:47]
	v_exp_f32_e32 v194, v194
	v_exp_f32_e32 v195, v195
	v_mfma_f32_32x32x16_bf16 v[32:47], v[120:123], v[52:55], v[32:47]
	v_exp_f32_e32 v196, v196
	v_exp_f32_e32 v197, v197
	v_exp_f32_e32 v198, v198
	v_mfma_f32_32x32x16_bf16 v[32:47], v[124:127], v[56:59], v[32:47]
	v_exp_f32_e32 v199, v199
	v_exp_f32_e32 v200, v200
	v_mfma_f32_32x32x16_bf16 v[32:47], v[128:131], v[60:63], v[32:47]
	v_exp_f32_e32 v201, v201
	v_exp_f32_e32 v202, v202
	v_exp_f32_e32 v203, v203
	v_cvt_pk_bf16_f32 v64, v188, v189
	v_cvt_pk_bf16_f32 v65, v190, v191
	v_cvt_pk_bf16_f32 v66, v192, v193
	v_cvt_pk_bf16_f32 v67, v194, v195
	v_cvt_pk_bf16_f32 v68, v196, v197
	v_cvt_pk_bf16_f32 v69, v198, v199
	v_cvt_pk_bf16_f32 v70, v200, v201
	v_cvt_pk_bf16_f32 v71, v202, v203
	v_pk_add_f32 v[232:233], v[232:233], v[188:189]
	v_pk_add_f32 v[232:233], v[232:233], v[190:191]
	v_pk_add_f32 v[232:233], v[232:233], v[192:193]
	v_pk_add_f32 v[232:233], v[232:233], v[194:195]
	v_pk_add_f32 v[232:233], v[232:233], v[196:197]
	v_pk_add_f32 v[232:233], v[232:233], v[198:199]
	v_pk_add_f32 v[232:233], v[232:233], v[200:201]
	v_pk_add_f32 v[232:233], v[232:233], v[202:203]
	ds_read2_b32 v[188:189], v115 offset0:32 offset1:33
	ds_read2_b32 v[190:191], v115 offset0:34 offset1:35
	ds_read2_b32 v[192:193], v115 offset0:40 offset1:41
	ds_read2_b32 v[194:195], v115 offset0:42 offset1:43
	ds_read2_b32 v[196:197], v115 offset0:48 offset1:49
	ds_read2_b32 v[198:199], v115 offset0:50 offset1:51
	ds_read2_b32 v[200:201], v115 offset0:56 offset1:57
	ds_read2_b32 v[202:203], v115 offset0:58 offset1:59
	v_mfma_f32_32x32x16_bf16 v[0:15], v[64:67], v[72:75], v[0:15]
	v_mfma_f32_32x32x16_bf16 v[16:31], v[64:67], v[76:79], v[16:31]
	v_mfma_f32_32x32x16_bf16 v[0:15], v[68:71], v[220:223], v[0:15]
	v_mfma_f32_32x32x16_bf16 v[16:31], v[68:71], v[224:227], v[16:31]
	global_load_dwordx4 v[116:119], v243, s[88:89]
	global_load_dwordx4 v[120:123], v244, s[88:89]
	global_load_dwordx4 v[124:127], v245, s[88:89]
	global_load_dwordx4 v[128:131], v246, s[88:89]
	global_load_dwordx4 v[132:135], v148, s[88:89] offset:768
	global_load_dwordx4 v[136:139], v151, s[88:89] offset:768
	global_load_dwordx4 v[140:143], v148, s[88:89] offset:832
	global_load_dwordx4 v[144:147], v151, s[88:89] offset:832
	s_add_u32 s88, s88, 0x300000
	s_addc_u32 s89, s89, 0
	ds_read_b64_tr_b16 v[72:73], v231
	ds_read_b64_tr_b16 v[74:75], v231 offset:512
	ds_read_b64_tr_b16 v[76:77], v231 offset:2048
	ds_read_b64_tr_b16 v[78:79], v231 offset:2560
	ds_read_b64_tr_b16 v[220:221], v231 offset:1024
	ds_read_b64_tr_b16 v[222:223], v231 offset:1536
	ds_read_b64_tr_b16 v[224:225], v231 offset:3072
	ds_read_b64_tr_b16 v[226:227], v231 offset:3584
	s_waitcnt vmcnt(8)
	ds_write_b128 v247, v[156:159]
	ds_write_b128 v247, v[160:163] offset:1024
	ds_write_b128 v111, v[164:167] offset:2048
	ds_write_b128 v111, v[168:171] offset:3072
	ds_read_b128 v[156:159], v248
	ds_read_b128 v[160:163], v249
	ds_read_b128 v[164:167], v250
	ds_read_b128 v[168:171], v251
	ds_write_b128 v112, v[172:175]
	ds_write_b128 v112, v[176:179] offset:1024
	ds_write_b128 v112, v[180:183] offset:2048
	ds_write_b128 v112, v[184:187] offset:3072
	v_exp_f32_e32 v32, v32
	v_exp_f32_e32 v33, v33
	v_exp_f32_e32 v34, v34
	v_exp_f32_e32 v35, v35
	v_exp_f32_e32 v36, v36
	v_exp_f32_e32 v37, v37
	s_waitcnt lgkmcnt(4)
	v_mfma_f32_32x32x16_bf16 v[188:203], v[156:159], v[48:51], v[188:203]
	v_exp_f32_e32 v38, v38
	v_exp_f32_e32 v39, v39
	v_mfma_f32_32x32x16_bf16 v[188:203], v[160:163], v[52:55], v[188:203]
	v_exp_f32_e32 v40, v40
	v_exp_f32_e32 v41, v41
	v_exp_f32_e32 v42, v42
	v_mfma_f32_32x32x16_bf16 v[188:203], v[164:167], v[56:59], v[188:203]
	v_exp_f32_e32 v43, v43
	v_exp_f32_e32 v44, v44
	v_mfma_f32_32x32x16_bf16 v[188:203], v[168:171], v[60:63], v[188:203]
	v_exp_f32_e32 v45, v45
	v_exp_f32_e32 v46, v46
	v_exp_f32_e32 v47, v47
	v_cvt_pk_bf16_f32 v64, v32, v33
	v_cvt_pk_bf16_f32 v65, v34, v35
	v_cvt_pk_bf16_f32 v66, v36, v37
	v_cvt_pk_bf16_f32 v67, v38, v39
	v_cvt_pk_bf16_f32 v68, v40, v41
	v_cvt_pk_bf16_f32 v69, v42, v43
	v_cvt_pk_bf16_f32 v70, v44, v45
	v_cvt_pk_bf16_f32 v71, v46, v47
	v_pk_add_f32 v[232:233], v[232:233], v[32:33]
	v_pk_add_f32 v[232:233], v[232:233], v[34:35]
	v_pk_add_f32 v[232:233], v[232:233], v[36:37]
	v_pk_add_f32 v[232:233], v[232:233], v[38:39]
	v_pk_add_f32 v[232:233], v[232:233], v[40:41]
	v_pk_add_f32 v[232:233], v[232:233], v[42:43]
	v_pk_add_f32 v[232:233], v[232:233], v[44:45]
	v_pk_add_f32 v[232:233], v[232:233], v[46:47]
	ds_read2_b32 v[32:33], v115 offset0:64 offset1:65
	ds_read2_b32 v[34:35], v115 offset0:66 offset1:67
	ds_read2_b32 v[36:37], v115 offset0:72 offset1:73
	ds_read2_b32 v[38:39], v115 offset0:74 offset1:75
	ds_read2_b32 v[40:41], v115 offset0:80 offset1:81
	ds_read2_b32 v[42:43], v115 offset0:82 offset1:83
	ds_read2_b32 v[44:45], v115 offset0:88 offset1:89
	ds_read2_b32 v[46:47], v115 offset0:90 offset1:91
	v_mfma_f32_32x32x16_bf16 v[0:15], v[64:67], v[72:75], v[0:15]
	v_mfma_f32_32x32x16_bf16 v[16:31], v[64:67], v[76:79], v[16:31]
	v_mfma_f32_32x32x16_bf16 v[0:15], v[68:71], v[220:223], v[0:15]
	v_mfma_f32_32x32x16_bf16 v[16:31], v[68:71], v[224:227], v[16:31]
	global_load_dwordx4 v[156:159], v243, s[88:89]
	global_load_dwordx4 v[160:163], v244, s[88:89]
	global_load_dwordx4 v[164:167], v245, s[88:89]
	global_load_dwordx4 v[168:171], v246, s[88:89]
	global_load_dwordx4 v[172:175], v148, s[88:89] offset:768
	global_load_dwordx4 v[176:179], v151, s[88:89] offset:768
	global_load_dwordx4 v[180:183], v148, s[88:89] offset:832
	global_load_dwordx4 v[184:187], v151, s[88:89] offset:832
	s_add_u32 s88, s88, 0x300000
	s_addc_u32 s89, s89, 0
	ds_read_b64_tr_b16 v[72:73], v231
	ds_read_b64_tr_b16 v[74:75], v231 offset:512
	ds_read_b64_tr_b16 v[76:77], v231 offset:2048
	ds_read_b64_tr_b16 v[78:79], v231 offset:2560
	ds_read_b64_tr_b16 v[220:221], v231 offset:1024
	ds_read_b64_tr_b16 v[222:223], v231 offset:1536
	ds_read_b64_tr_b16 v[224:225], v231 offset:3072
	ds_read_b64_tr_b16 v[226:227], v231 offset:3584
	s_waitcnt vmcnt(8)
	ds_write_b128 v247, v[116:119]
	ds_write_b128 v247, v[120:123] offset:1024
	ds_write_b128 v111, v[124:127] offset:2048
	ds_write_b128 v111, v[128:131] offset:3072
	ds_read_b128 v[116:119], v248
	ds_read_b128 v[120:123], v249
	ds_read_b128 v[124:127], v250
	ds_read_b128 v[128:131], v251
	ds_write_b128 v112, v[132:135]
	ds_write_b128 v112, v[136:139] offset:1024
	ds_write_b128 v112, v[140:143] offset:2048
	ds_write_b128 v112, v[144:147] offset:3072
	v_exp_f32_e32 v188, v188
	v_exp_f32_e32 v189, v189
	v_exp_f32_e32 v190, v190
	v_exp_f32_e32 v191, v191
	v_exp_f32_e32 v192, v192
	v_exp_f32_e32 v193, v193
	s_waitcnt lgkmcnt(4)
	v_mfma_f32_32x32x16_bf16 v[32:47], v[116:119], v[48:51], v[32:47]
	v_exp_f32_e32 v194, v194
	v_exp_f32_e32 v195, v195
	v_mfma_f32_32x32x16_bf16 v[32:47], v[120:123], v[52:55], v[32:47]
	v_exp_f32_e32 v196, v196
	v_exp_f32_e32 v197, v197
	v_exp_f32_e32 v198, v198
	v_mfma_f32_32x32x16_bf16 v[32:47], v[124:127], v[56:59], v[32:47]
	v_exp_f32_e32 v199, v199
	v_exp_f32_e32 v200, v200
	v_mfma_f32_32x32x16_bf16 v[32:47], v[128:131], v[60:63], v[32:47]
	v_exp_f32_e32 v201, v201
	v_exp_f32_e32 v202, v202
	v_exp_f32_e32 v203, v203
	v_cvt_pk_bf16_f32 v64, v188, v189
	v_cvt_pk_bf16_f32 v65, v190, v191
	v_cvt_pk_bf16_f32 v66, v192, v193
	v_cvt_pk_bf16_f32 v67, v194, v195
	v_cvt_pk_bf16_f32 v68, v196, v197
	v_cvt_pk_bf16_f32 v69, v198, v199
	v_cvt_pk_bf16_f32 v70, v200, v201
	v_cvt_pk_bf16_f32 v71, v202, v203
	v_pk_add_f32 v[232:233], v[232:233], v[188:189]
	v_pk_add_f32 v[232:233], v[232:233], v[190:191]
	v_pk_add_f32 v[232:233], v[232:233], v[192:193]
	v_pk_add_f32 v[232:233], v[232:233], v[194:195]
	v_pk_add_f32 v[232:233], v[232:233], v[196:197]
	v_pk_add_f32 v[232:233], v[232:233], v[198:199]
	v_pk_add_f32 v[232:233], v[232:233], v[200:201]
	v_pk_add_f32 v[232:233], v[232:233], v[202:203]
	ds_read2_b32 v[188:189], v115 offset0:96 offset1:97
	ds_read2_b32 v[190:191], v115 offset0:98 offset1:99
	ds_read2_b32 v[192:193], v115 offset0:104 offset1:105
	ds_read2_b32 v[194:195], v115 offset0:106 offset1:107
	ds_read2_b32 v[196:197], v115 offset0:112 offset1:113
	ds_read2_b32 v[198:199], v115 offset0:114 offset1:115
	ds_read2_b32 v[200:201], v115 offset0:120 offset1:121
	ds_read2_b32 v[202:203], v115 offset0:122 offset1:123
	v_mfma_f32_32x32x16_bf16 v[0:15], v[64:67], v[72:75], v[0:15]
	v_mfma_f32_32x32x16_bf16 v[16:31], v[64:67], v[76:79], v[16:31]
	v_mfma_f32_32x32x16_bf16 v[0:15], v[68:71], v[220:223], v[0:15]
	v_mfma_f32_32x32x16_bf16 v[16:31], v[68:71], v[224:227], v[16:31]
	global_load_dwordx4 v[116:119], v243, s[88:89]
	global_load_dwordx4 v[120:123], v244, s[88:89]
	global_load_dwordx4 v[124:127], v245, s[88:89]
	global_load_dwordx4 v[128:131], v246, s[88:89]
	global_load_dwordx4 v[132:135], v148, s[88:89] offset:768
	global_load_dwordx4 v[136:139], v151, s[88:89] offset:768
	global_load_dwordx4 v[140:143], v148, s[88:89] offset:832
	global_load_dwordx4 v[144:147], v151, s[88:89] offset:832
	ds_read_b64_tr_b16 v[72:73], v231
	ds_read_b64_tr_b16 v[74:75], v231 offset:512
	ds_read_b64_tr_b16 v[76:77], v231 offset:2048
	ds_read_b64_tr_b16 v[78:79], v231 offset:2560
	ds_read_b64_tr_b16 v[220:221], v231 offset:1024
	ds_read_b64_tr_b16 v[222:223], v231 offset:1536
	ds_read_b64_tr_b16 v[224:225], v231 offset:3072
	ds_read_b64_tr_b16 v[226:227], v231 offset:3584
	s_waitcnt vmcnt(8)
	ds_write_b128 v247, v[156:159]
	ds_write_b128 v247, v[160:163] offset:1024
	ds_write_b128 v111, v[164:167] offset:2048
	ds_write_b128 v111, v[168:171] offset:3072
	ds_read_b128 v[156:159], v248
	ds_read_b128 v[160:163], v249
	ds_read_b128 v[164:167], v250
	ds_read_b128 v[168:171], v251
	ds_write_b128 v112, v[172:175]
	ds_write_b128 v112, v[176:179] offset:1024
	ds_write_b128 v112, v[180:183] offset:2048
	ds_write_b128 v112, v[184:187] offset:3072
	v_exp_f32_e32 v32, v32
	v_exp_f32_e32 v33, v33
	v_exp_f32_e32 v34, v34
	v_exp_f32_e32 v35, v35
	v_exp_f32_e32 v36, v36
	v_exp_f32_e32 v37, v37
	s_waitcnt lgkmcnt(4)
	v_mfma_f32_32x32x16_bf16 v[188:203], v[156:159], v[48:51], v[188:203]
	v_exp_f32_e32 v38, v38
	v_exp_f32_e32 v39, v39
	v_mfma_f32_32x32x16_bf16 v[188:203], v[160:163], v[52:55], v[188:203]
	v_exp_f32_e32 v40, v40
	v_exp_f32_e32 v41, v41
	v_exp_f32_e32 v42, v42
	v_mfma_f32_32x32x16_bf16 v[188:203], v[164:167], v[56:59], v[188:203]
	v_exp_f32_e32 v43, v43
	v_exp_f32_e32 v44, v44
	v_mfma_f32_32x32x16_bf16 v[188:203], v[168:171], v[60:63], v[188:203]
	v_exp_f32_e32 v45, v45
	v_exp_f32_e32 v46, v46
	v_exp_f32_e32 v47, v47
	v_cvt_pk_bf16_f32 v64, v32, v33
	v_cvt_pk_bf16_f32 v65, v34, v35
	v_cvt_pk_bf16_f32 v66, v36, v37
	v_cvt_pk_bf16_f32 v67, v38, v39
	v_cvt_pk_bf16_f32 v68, v40, v41
	v_cvt_pk_bf16_f32 v69, v42, v43
	v_cvt_pk_bf16_f32 v70, v44, v45
	v_cvt_pk_bf16_f32 v71, v46, v47
	v_pk_add_f32 v[232:233], v[232:233], v[32:33]
	v_pk_add_f32 v[232:233], v[232:233], v[34:35]
	v_pk_add_f32 v[232:233], v[232:233], v[36:37]
	v_pk_add_f32 v[232:233], v[232:233], v[38:39]
	v_pk_add_f32 v[232:233], v[232:233], v[40:41]
	v_pk_add_f32 v[232:233], v[232:233], v[42:43]
	v_pk_add_f32 v[232:233], v[232:233], v[44:45]
	v_pk_add_f32 v[232:233], v[232:233], v[46:47]
	ds_read2_b32 v[32:33], v115 offset0:128 offset1:129
	ds_read2_b32 v[34:35], v115 offset0:130 offset1:131
	ds_read2_b32 v[36:37], v115 offset0:136 offset1:137
	ds_read2_b32 v[38:39], v115 offset0:138 offset1:139
	ds_read2_b32 v[40:41], v115 offset0:144 offset1:145
	ds_read2_b32 v[42:43], v115 offset0:146 offset1:147
	ds_read2_b32 v[44:45], v115 offset0:152 offset1:153
	ds_read2_b32 v[46:47], v115 offset0:154 offset1:155
	v_mfma_f32_32x32x16_bf16 v[0:15], v[64:67], v[72:75], v[0:15]
	v_mfma_f32_32x32x16_bf16 v[16:31], v[64:67], v[76:79], v[16:31]
	v_mfma_f32_32x32x16_bf16 v[0:15], v[68:71], v[220:223], v[0:15]
	v_mfma_f32_32x32x16_bf16 v[16:31], v[68:71], v[224:227], v[16:31]
	ds_read_b64_tr_b16 v[72:73], v231
	ds_read_b64_tr_b16 v[74:75], v231 offset:512
	ds_read_b64_tr_b16 v[76:77], v231 offset:2048
	ds_read_b64_tr_b16 v[78:79], v231 offset:2560
	ds_read_b64_tr_b16 v[220:221], v231 offset:1024
	ds_read_b64_tr_b16 v[222:223], v231 offset:1536
	ds_read_b64_tr_b16 v[224:225], v231 offset:3072
	ds_read_b64_tr_b16 v[226:227], v231 offset:3584
	s_waitcnt vmcnt(0)
; __device__ __forceinline__ int crow(int r, int hi) { return (r & 3) + 8 * (r >> 2) + 4 * hi; }
; __device__ __forceinline__ void dil_unit(LAS unsigned char* lds, bf16_t* proj, int seq, int hd, int T0, int rho) {
;     ...
;     l += __shfl_xor(l, 32);
; #pragma unroll
;     for (int rr = 0; rr < 16; ++rr) {
;         const int j = crow(rr, hi);
;         const float il = __builtin_amdgcn_rcpf(__shfl(l, j));
	ds_write_b128 v247, v[116:119]
	ds_write_b128 v247, v[120:123] offset:1024
	ds_write_b128 v111, v[124:127] offset:2048
	ds_write_b128 v111, v[128:131] offset:3072
	ds_read_b128 v[116:119], v248
	ds_read_b128 v[120:123], v249
	ds_read_b128 v[124:127], v250
	ds_read_b128 v[128:131], v251
	ds_write_b128 v112, v[132:135]
	ds_write_b128 v112, v[136:139] offset:1024
	ds_write_b128 v112, v[140:143] offset:2048
	ds_write_b128 v112, v[144:147] offset:3072
	v_exp_f32_e32 v188, v188
	v_exp_f32_e32 v189, v189
	v_exp_f32_e32 v190, v190
	v_exp_f32_e32 v191, v191
	v_exp_f32_e32 v192, v192
	v_exp_f32_e32 v193, v193
	s_waitcnt lgkmcnt(4)
	v_mfma_f32_32x32x16_bf16 v[32:47], v[116:119], v[48:51], v[32:47]
	v_exp_f32_e32 v194, v194
	v_exp_f32_e32 v195, v195
	v_mfma_f32_32x32x16_bf16 v[32:47], v[120:123], v[52:55], v[32:47]
	v_exp_f32_e32 v196, v196
	v_exp_f32_e32 v197, v197
	v_exp_f32_e32 v198, v198
	v_mfma_f32_32x32x16_bf16 v[32:47], v[124:127], v[56:59], v[32:47]
	v_exp_f32_e32 v199, v199
	v_exp_f32_e32 v200, v200
	v_mfma_f32_32x32x16_bf16 v[32:47], v[128:131], v[60:63], v[32:47]
	v_exp_f32_e32 v201, v201
	v_exp_f32_e32 v202, v202
	v_exp_f32_e32 v203, v203
	v_cvt_pk_bf16_f32 v64, v188, v189
	v_cvt_pk_bf16_f32 v65, v190, v191
	v_cvt_pk_bf16_f32 v66, v192, v193
	v_cvt_pk_bf16_f32 v67, v194, v195
	v_cvt_pk_bf16_f32 v68, v196, v197
	v_cvt_pk_bf16_f32 v69, v198, v199
	v_cvt_pk_bf16_f32 v70, v200, v201
	v_cvt_pk_bf16_f32 v71, v202, v203
	v_pk_add_f32 v[232:233], v[232:233], v[188:189]
	v_pk_add_f32 v[232:233], v[232:233], v[190:191]
	v_pk_add_f32 v[232:233], v[232:233], v[192:193]
	v_pk_add_f32 v[232:233], v[232:233], v[194:195]
	v_pk_add_f32 v[232:233], v[232:233], v[196:197]
	v_pk_add_f32 v[232:233], v[232:233], v[198:199]
	v_pk_add_f32 v[232:233], v[232:233], v[200:201]
	v_pk_add_f32 v[232:233], v[232:233], v[202:203]
	v_mfma_f32_32x32x16_bf16 v[0:15], v[64:67], v[72:75], v[0:15]
	v_mfma_f32_32x32x16_bf16 v[16:31], v[64:67], v[76:79], v[16:31]
	v_mfma_f32_32x32x16_bf16 v[0:15], v[68:71], v[220:223], v[0:15]
	v_mfma_f32_32x32x16_bf16 v[16:31], v[68:71], v[224:227], v[16:31]
	ds_read_b64_tr_b16 v[72:73], v231
	ds_read_b64_tr_b16 v[74:75], v231 offset:512
	ds_read_b64_tr_b16 v[76:77], v231 offset:2048
	ds_read_b64_tr_b16 v[78:79], v231 offset:2560
	ds_read_b64_tr_b16 v[220:221], v231 offset:1024
	ds_read_b64_tr_b16 v[222:223], v231 offset:1536
	ds_read_b64_tr_b16 v[224:225], v231 offset:3072
	ds_read_b64_tr_b16 v[226:227], v231 offset:3584
	s_waitcnt lgkmcnt(0)
	v_exp_f32_e32 v32, v32
	v_exp_f32_e32 v33, v33
	v_exp_f32_e32 v34, v34
	v_exp_f32_e32 v35, v35
	v_exp_f32_e32 v36, v36
	v_exp_f32_e32 v37, v37
	v_exp_f32_e32 v38, v38
	v_exp_f32_e32 v39, v39
	v_exp_f32_e32 v40, v40
	v_exp_f32_e32 v41, v41
	v_exp_f32_e32 v42, v42
	v_exp_f32_e32 v43, v43
	v_exp_f32_e32 v44, v44
	v_exp_f32_e32 v45, v45
	v_exp_f32_e32 v46, v46
	v_exp_f32_e32 v47, v47
	v_cvt_pk_bf16_f32 v64, v32, v33
	v_cvt_pk_bf16_f32 v65, v34, v35
	v_cvt_pk_bf16_f32 v66, v36, v37
	v_cvt_pk_bf16_f32 v67, v38, v39
	v_cvt_pk_bf16_f32 v68, v40, v41
	v_cvt_pk_bf16_f32 v69, v42, v43
	v_cvt_pk_bf16_f32 v70, v44, v45
	v_cvt_pk_bf16_f32 v71, v46, v47
	v_pk_add_f32 v[232:233], v[232:233], v[32:33]
	v_pk_add_f32 v[232:233], v[232:233], v[34:35]
	v_pk_add_f32 v[232:233], v[232:233], v[36:37]
	v_pk_add_f32 v[232:233], v[232:233], v[38:39]
	v_pk_add_f32 v[232:233], v[232:233], v[40:41]
	v_pk_add_f32 v[232:233], v[232:233], v[42:43]
	v_pk_add_f32 v[232:233], v[232:233], v[44:45]
	v_pk_add_f32 v[232:233], v[232:233], v[46:47]
	v_mfma_f32_32x32x16_bf16 v[0:15], v[64:67], v[72:75], v[0:15]
	v_mfma_f32_32x32x16_bf16 v[16:31], v[64:67], v[76:79], v[16:31]
	v_mfma_f32_32x32x16_bf16 v[0:15], v[68:71], v[220:223], v[0:15]
	v_mfma_f32_32x32x16_bf16 v[16:31], v[68:71], v[224:227], v[16:31]
	v_add_f32_e32 v113, v232, v233
	v_or_b32_e32 v114, 1, v107
	v_or_b32_e32 v97, 2, v107
	v_or_b32_e32 v96, 3, v107
	v_or_b32_e32 v95, 8, v107
	v_or_b32_e32 v94, 9, v107
	v_or_b32_e32 v93, 10, v107
	v_or_b32_e32 v92, 11, v107
	v_or_b32_e32 v91, 16, v107
	v_or_b32_e32 v90, 17, v107
	v_or_b32_e32 v89, 18, v107
	v_or_b32_e32 v88, 19, v107
	v_or_b32_e32 v87, 24, v107
	v_or_b32_e32 v86, 25, v107
	v_or_b32_e32 v85, 26, v107
	v_or_b32_e32 v84, 27, v107
	s_nop 11
	s_branch .LBB0_553
; #define LAS __attribute__((address_space(3)))
; #define GAS __attribute__((address_space(1)))
; __device__ __forceinline__ void dil_unit(LAS unsigned char* lds, bf16_t* proj, int seq, int hd, int T0, int rho) {
;     ...
;     const int tid = tid_, lane = tid & 63, r32 = lane & 31, hi = lane >> 5, wid = __builtin_amdgcn_readfirstlane(tid >> 6);
;     bf16_t* base = proj + (size_t)seq * SEQ * NIN;
;     LAS unsigned char* wbuf = lds + wid * 4096;
;     const LAS unsigned char* vp = wbuf + ((lane >> 4) & 1) * 32 + (lane & 3) * 8 + (4 * hi + ((lane & 15) >> 2)) * 64;
;     const int P0 = T0 + rho;
;     bf16x8 qr[4];
; #pragma unroll
;     for (int ks = 0; ks < 4; ++ks) qr[ks] = *(const GAS bf16x8*)(base + (size_t)(P0 + 16 * r32) * NIN + PC_LQ + hd * 64 + 16 * ks + 8 * hi);
;     f32x16 o0 = {}, o1 = {}; float l = 0.f;
;     const bool bound = (T0 < 1024) || (T0 >= 15360);
.LBB0_558:
	s_movk_i32 s100, 0x1800
	s_add_i32 s101, s6, 0x15c00
	s_lshl_b32 s90, s58, 1
	s_add_u32 s82, s56, s90
	s_addc_u32 s83, s57, 0
	s_add_u32 s82, s82, 0x1200
	s_addc_u32 s83, s83, 0
	s_sub_i32 s90, s76, 64
	s_mul_i32 s90, s90, 0x1800
	s_add_u32 s84, s82, s90
	s_addc_u32 s85, s83, 0
	s_sub_i32 s90, s76, 256
	s_mul_i32 s90, s90, 0x1800
	s_add_u32 s86, s82, s90
	s_addc_u32 s87, s83, 0
	s_sub_i32 s90, s76, 1024
	s_mul_i32 s90, s90, 0x1800
	s_add_u32 s88, s82, s90
	s_addc_u32 s89, s83, 0
	v_lshlrev_b32_e32 v153, 1, v98
	v_mad_u32_u24 v80, v105, s100, v82
	v_mad_u32_u24 v100, v110, s100, v153
	v_add_u32_e32 v149, 0x18000, v100
	v_lshlrev_b32_e32 v83, 2, v105
	v_mad_u32_u24 v83, v83, s100, v82
	v_lshlrev_b32_e32 v101, 2, v110
	v_mad_u32_u24 v101, v101, s100, v153
	v_add_u32_e32 v150, 0x60000, v101
	v_lshlrev_b32_e32 v99, 4, v105
	v_mad_u32_u24 v99, v99, s100, v82
	v_lshlrev_b32_e32 v148, 4, v110
	v_mad_u32_u24 v148, v148, s100, v153
	v_add_u32_e32 v151, 0x180000, v148
	v_lshrrev_b32_e32 v249, 3, v103
	v_and_b32_e32 v250, 7, v103
	v_lshlrev_b32_e32 v250, 4, v250
	v_add_u32_e32 v235, 0, v249
	v_add_u32_e32 v236, 8, v249
	v_add_u32_e32 v237, 16, v249
	v_add_u32_e32 v238, 24, v249
	v_add_u32_e32 v239, 0, v249
	v_lshlrev_b32_e32 v239, 2, v239
	v_add_u32_e32 v240, 8, v249
	v_lshlrev_b32_e32 v240, 2, v240
	v_add_u32_e32 v241, 16, v249
	v_lshlrev_b32_e32 v241, 2, v241
	v_add_u32_e32 v242, 24, v249
	v_lshlrev_b32_e32 v242, 2, v242
	v_add_u32_e32 v243, 0, v249
	v_lshlrev_b32_e32 v243, 4, v243
	v_add_u32_e32 v244, 8, v249
	v_lshlrev_b32_e32 v244, 4, v244
	v_add_u32_e32 v245, 16, v249
	v_lshlrev_b32_e32 v245, 4, v245
	v_add_u32_e32 v246, 24, v249
	v_lshlrev_b32_e32 v246, 4, v246
	v_mov_b32_e32 v252, v250
	v_mov_b32_e32 v100, v110
	v_add_u32_e32 v149, 16, v100
	v_lshlrev_b32_e32 v101, 2, v110
	v_add_u32_e32 v150, 64, v101
	v_lshlrev_b32_e32 v148, 4, v110
	v_add_u32_e32 v151, 256, v148
	s_mov_b32 s98, 0x4000
	s_mov_b32 s99, 0x3fff
	v_and_b32_e32 v247, 7, v249
	v_lshlrev_b32_e32 v247, 4, v247
	v_xor_b32_e32 v247, v247, v112
	v_xor_b32_e32 v111, 16, v247
	v_and_b32_e32 v153, 7, v105
	v_lshrrev_b32_e32 v248, 4, v105
	v_xor_b32_e32 v153, v153, v248
	v_or_b32_e32 v248, 0, v106
	v_xor_b32_e32 v248, v248, v153
	v_lshlrev_b32_e32 v248, 4, v248
	v_lshl_add_u32 v248, v105, 7, v248
	v_add_u32_e32 v248, s77, v248
	v_or_b32_e32 v249, 2, v106
	v_xor_b32_e32 v249, v249, v153
	v_lshlrev_b32_e32 v249, 4, v249
	v_lshl_add_u32 v249, v105, 7, v249
	v_add_u32_e32 v249, s77, v249
	v_or_b32_e32 v250, 4, v106
	v_xor_b32_e32 v250, v250, v153
	v_lshlrev_b32_e32 v250, 4, v250
	v_lshl_add_u32 v250, v105, 7, v250
	v_add_u32_e32 v250, s77, v250
	v_or_b32_e32 v251, 6, v106
	v_xor_b32_e32 v251, v251, v153
	v_lshlrev_b32_e32 v251, 4, v251
	v_lshl_add_u32 v251, v105, 7, v251
	v_add_u32_e32 v251, s77, v251
	v_lshlrev_b32_e32 v153, 1, v98
	v_mul_u32_u24_e32 v228, 17, v105
	v_sub_u32_e32 v228, v107, v228
	s_mul_i32 s90, s58, 153
	s_lshr_b32 s90, s90, 1
	s_add_i32 s90, s90, 34876
	v_lshl_add_u32 v228, v228, 2, s90
	v_mul_u32_u24_e32 v229, 5, v105
	v_sub_u32_e32 v229, v107, v229
	v_add_u32_e32 v229, v229, v106
	s_mul_i32 s90, s58, 30
	s_add_i32 s90, s90, 66156
	v_lshl_add_u32 v229, v229, 2, s90
	v_sub_u32_e32 v230, v107, v105
	s_add_i32 s90, s101, 6364
	v_lshl_add_u32 v230, v230, 2, s90
	v_add_u32_e32 v231, v109, v108
	v_mov_b64_e32 v[232:233], 0
	v_mov_b64_e32 v[0:1], 0
	v_mov_b64_e32 v[2:3], 0
	v_mov_b64_e32 v[4:5], 0
	v_mov_b64_e32 v[6:7], 0
	v_mov_b64_e32 v[8:9], 0
	v_mov_b64_e32 v[10:11], 0
	v_mov_b64_e32 v[12:13], 0
	v_mov_b64_e32 v[14:15], 0
	v_mov_b64_e32 v[16:17], 0
	v_mov_b64_e32 v[18:19], 0
	v_mov_b64_e32 v[20:21], 0
	v_mov_b64_e32 v[22:23], 0
	v_mov_b64_e32 v[24:25], 0
	v_mov_b64_e32 v[26:27], 0
	v_mov_b64_e32 v[28:29], 0
	v_mov_b64_e32 v[30:31], 0
	s_add_i32 s90, s76, -64
	v_add_u32_e32 v80, s90, v235
	v_add_u32_e32 v83, s90, v236
	v_add_u32_e32 v99, s90, v237
	v_add_u32_e32 v253, s90, v238
	v_add_u32_e32 v254, s90, v100
	v_add_u32_e32 v255, s90, v149
	v_med3_i32 v80, v80, 0, s99
	v_med3_i32 v83, v83, 0, s99
	v_med3_i32 v99, v99, 0, s99
	v_med3_i32 v253, v253, 0, s99
	v_med3_i32 v254, v254, 0, s99
	v_med3_i32 v255, v255, 0, s99
	v_mad_u32_u24 v80, v80, s100, v252
	v_mad_u32_u24 v83, v83, s100, v252
	v_mad_u32_u24 v99, v99, s100, v252
	v_mad_u32_u24 v253, v253, s100, v252
	v_mad_u32_u24 v254, v254, s100, v153
	v_mad_u32_u24 v255, v255, s100, v153
	global_load_dwordx4 v[116:119], v80, s[82:83]
	global_load_dwordx4 v[120:123], v83, s[82:83]
	global_load_dwordx4 v[124:127], v99, s[82:83]
	global_load_dwordx4 v[128:131], v253, s[82:83]
	global_load_dwordx4 v[132:135], v254, s[82:83] offset:768
	global_load_dwordx4 v[136:139], v255, s[82:83] offset:768
	global_load_dwordx4 v[140:143], v254, s[82:83] offset:832
	global_load_dwordx4 v[144:147], v255, s[82:83] offset:832
	s_add_i32 s90, s76, -32
	v_add_u32_e32 v80, s90, v235
	v_add_u32_e32 v83, s90, v236
	v_add_u32_e32 v99, s90, v237
	v_add_u32_e32 v253, s90, v238
	v_add_u32_e32 v254, s90, v100
	v_add_u32_e32 v255, s90, v149
	v_med3_i32 v80, v80, 0, s99
	v_med3_i32 v83, v83, 0, s99
	v_med3_i32 v99, v99, 0, s99
	v_med3_i32 v253, v253, 0, s99
	v_med3_i32 v254, v254, 0, s99
	v_med3_i32 v255, v255, 0, s99
	v_mad_u32_u24 v80, v80, s100, v252
	v_mad_u32_u24 v83, v83, s100, v252
	v_mad_u32_u24 v99, v99, s100, v252
	v_mad_u32_u24 v253, v253, s100, v252
	v_mad_u32_u24 v254, v254, s100, v153
	v_mad_u32_u24 v255, v255, s100, v153
	global_load_dwordx4 v[156:159], v80, s[82:83]
	global_load_dwordx4 v[160:163], v83, s[82:83]
	global_load_dwordx4 v[164:167], v99, s[82:83]
	global_load_dwordx4 v[168:171], v253, s[82:83]
	global_load_dwordx4 v[172:175], v254, s[82:83] offset:768
	global_load_dwordx4 v[176:179], v255, s[82:83] offset:768
	global_load_dwordx4 v[180:183], v254, s[82:83] offset:832
	global_load_dwordx4 v[184:187], v255, s[82:83] offset:832
	v_mov_b32_e32 v115, v228
	ds_read2_b32 v[32:33], v115 offset0:0 offset1:1
	ds_read2_b32 v[34:35], v115 offset0:2 offset1:3
	ds_read2_b32 v[36:37], v115 offset0:8 offset1:9
	ds_read2_b32 v[38:39], v115 offset0:10 offset1:11
	ds_read2_b32 v[40:41], v115 offset0:17 offset1:18
	ds_read2_b32 v[42:43], v115 offset0:19 offset1:20
	ds_read2_b32 v[44:45], v115 offset0:25 offset1:26
	ds_read2_b32 v[46:47], v115 offset0:27 offset1:28
	s_waitcnt vmcnt(8)
	ds_write_b128 v247, v[116:119]
	ds_write_b128 v247, v[120:123] offset:1024
	ds_write_b128 v111, v[124:127] offset:2048
	ds_write_b128 v111, v[128:131] offset:3072
	ds_read_b128 v[116:119], v248
	ds_read_b128 v[120:123], v249
	ds_read_b128 v[124:127], v250
	ds_read_b128 v[128:131], v251
	ds_write_b128 v112, v[132:135]
	ds_write_b128 v112, v[136:139] offset:1024
	ds_write_b128 v112, v[140:143] offset:2048
	ds_write_b128 v112, v[144:147] offset:3072
	s_waitcnt lgkmcnt(4)
	v_mfma_f32_32x32x16_bf16 v[32:47], v[116:119], v[48:51], v[32:47]
	v_mfma_f32_32x32x16_bf16 v[32:47], v[120:123], v[52:55], v[32:47]
	v_mfma_f32_32x32x16_bf16 v[32:47], v[124:127], v[56:59], v[32:47]
	v_mfma_f32_32x32x16_bf16 v[32:47], v[128:131], v[60:63], v[32:47]
	ds_read2_b32 v[188:189], v115 offset0:34 offset1:35
	ds_read2_b32 v[190:191], v115 offset0:36 offset1:37
	ds_read2_b32 v[192:193], v115 offset0:42 offset1:43
	ds_read2_b32 v[194:195], v115 offset0:44 offset1:45
	ds_read2_b32 v[196:197], v115 offset0:51 offset1:52
	ds_read2_b32 v[198:199], v115 offset0:53 offset1:54
	ds_read2_b32 v[200:201], v115 offset0:59 offset1:60
	ds_read2_b32 v[202:203], v115 offset0:61 offset1:62
	s_add_i32 s90, s76, 0
	v_add_u32_e32 v80, s90, v235
	v_add_u32_e32 v83, s90, v236
	v_add_u32_e32 v99, s90, v237
	v_add_u32_e32 v253, s90, v238
	v_add_u32_e32 v254, s90, v100
	v_add_u32_e32 v255, s90, v149
	v_med3_i32 v80, v80, 0, s99
	v_med3_i32 v83, v83, 0, s99
	v_med3_i32 v99, v99, 0, s99
	v_med3_i32 v253, v253, 0, s99
	v_med3_i32 v254, v254, 0, s99
	v_med3_i32 v255, v255, 0, s99
	v_mad_u32_u24 v80, v80, s100, v252
	v_mad_u32_u24 v83, v83, s100, v252
	v_mad_u32_u24 v99, v99, s100, v252
	v_mad_u32_u24 v253, v253, s100, v252
	v_mad_u32_u24 v254, v254, s100, v153
	v_mad_u32_u24 v255, v255, s100, v153
	global_load_dwordx4 v[116:119], v80, s[82:83]
	global_load_dwordx4 v[120:123], v83, s[82:83]
	global_load_dwordx4 v[124:127], v99, s[82:83]
	global_load_dwordx4 v[128:131], v253, s[82:83]
	global_load_dwordx4 v[132:135], v254, s[82:83] offset:768
	global_load_dwordx4 v[136:139], v255, s[82:83] offset:768
	global_load_dwordx4 v[140:143], v254, s[82:83] offset:832
	global_load_dwordx4 v[144:147], v255, s[82:83] offset:832
	ds_read_b64_tr_b16 v[72:73], v231
	ds_read_b64_tr_b16 v[74:75], v231 offset:512
	ds_read_b64_tr_b16 v[76:77], v231 offset:2048
	ds_read_b64_tr_b16 v[78:79], v231 offset:2560
	ds_read_b64_tr_b16 v[220:221], v231 offset:1024
	ds_read_b64_tr_b16 v[222:223], v231 offset:1536
	ds_read_b64_tr_b16 v[224:225], v231 offset:3072
	ds_read_b64_tr_b16 v[226:227], v231 offset:3584
	s_waitcnt vmcnt(8)
	ds_write_b128 v247, v[156:159]
	ds_write_b128 v247, v[160:163] offset:1024
	ds_write_b128 v111, v[164:167] offset:2048
	ds_write_b128 v111, v[168:171] offset:3072
	ds_read_b128 v[156:159], v248
	ds_read_b128 v[160:163], v249
	ds_read_b128 v[164:167], v250
	ds_read_b128 v[168:171], v251
	ds_write_b128 v112, v[172:175]
	ds_write_b128 v112, v[176:179] offset:1024
	ds_write_b128 v112, v[180:183] offset:2048
	ds_write_b128 v112, v[184:187] offset:3072
	v_exp_f32_e32 v32, v32
	v_exp_f32_e32 v33, v33
	v_exp_f32_e32 v34, v34
	v_exp_f32_e32 v35, v35
	v_exp_f32_e32 v36, v36
	v_exp_f32_e32 v37, v37
	s_waitcnt lgkmcnt(4)
	v_mfma_f32_32x32x16_bf16 v[188:203], v[156:159], v[48:51], v[188:203]
	v_exp_f32_e32 v38, v38
	v_exp_f32_e32 v39, v39
	v_mfma_f32_32x32x16_bf16 v[188:203], v[160:163], v[52:55], v[188:203]
	v_exp_f32_e32 v40, v40
	v_exp_f32_e32 v41, v41
	v_exp_f32_e32 v42, v42
	v_mfma_f32_32x32x16_bf16 v[188:203], v[164:167], v[56:59], v[188:203]
	v_exp_f32_e32 v43, v43
	v_exp_f32_e32 v44, v44
	v_mfma_f32_32x32x16_bf16 v[188:203], v[168:171], v[60:63], v[188:203]
	v_exp_f32_e32 v45, v45
	v_exp_f32_e32 v46, v46
	v_exp_f32_e32 v47, v47
	s_add_i32 s90, s76, -64
	v_add_u32_e32 v84, s90, v107
	v_add_u32_e32 v85, 0, v84
	v_add_u32_e32 v86, 1, v84
	v_add_u32_e32 v87, 2, v84
	v_add_u32_e32 v88, 3, v84
	v_cmp_gt_u32_e64 s[30:31], s98, v85
	v_cmp_gt_u32_e64 s[36:37], s98, v86
	v_cmp_gt_u32_e64 s[78:79], s98, v87
	v_cmp_gt_u32_e64 s[50:51], s98, v88
	v_cndmask_b32_e64 v32, 0, v32, s[30:31]
	v_add_u32_e32 v85, 8, v84
	v_cmp_gt_u32_e64 s[30:31], s98, v85
	v_cndmask_b32_e64 v33, 0, v33, s[36:37]
	v_add_u32_e32 v86, 9, v84
	v_cmp_gt_u32_e64 s[36:37], s98, v86
	v_cndmask_b32_e64 v34, 0, v34, s[78:79]
	v_add_u32_e32 v87, 10, v84
	v_cmp_gt_u32_e64 s[78:79], s98, v87
	v_cndmask_b32_e64 v35, 0, v35, s[50:51]
	v_add_u32_e32 v88, 11, v84
	v_cmp_gt_u32_e64 s[50:51], s98, v88
	v_cndmask_b32_e64 v36, 0, v36, s[30:31]
	v_add_u32_e32 v85, 16, v84
	v_cmp_gt_u32_e64 s[30:31], s98, v85
	v_cndmask_b32_e64 v37, 0, v37, s[36:37]
	v_add_u32_e32 v86, 17, v84
	v_cmp_gt_u32_e64 s[36:37], s98, v86
	v_cndmask_b32_e64 v38, 0, v38, s[78:79]
	v_add_u32_e32 v87, 18, v84
	v_cmp_gt_u32_e64 s[78:79], s98, v87
	v_cndmask_b32_e64 v39, 0, v39, s[50:51]
	v_add_u32_e32 v88, 19, v84
	v_cmp_gt_u32_e64 s[50:51], s98, v88
	v_cndmask_b32_e64 v40, 0, v40, s[30:31]
	v_add_u32_e32 v85, 24, v84
	v_cmp_gt_u32_e64 s[30:31], s98, v85
	v_cndmask_b32_e64 v41, 0, v41, s[36:37]
	v_add_u32_e32 v86, 25, v84
	v_cmp_gt_u32_e64 s[36:37], s98, v86
	v_cndmask_b32_e64 v42, 0, v42, s[78:79]
	v_add_u32_e32 v87, 26, v84
	v_cmp_gt_u32_e64 s[78:79], s98, v87
	v_cndmask_b32_e64 v43, 0, v43, s[50:51]
	v_add_u32_e32 v88, 27, v84
	v_cmp_gt_u32_e64 s[50:51], s98, v88
	v_nop
	v_cndmask_b32_e64 v44, 0, v44, s[30:31]
	v_cndmask_b32_e64 v45, 0, v45, s[36:37]
	v_cndmask_b32_e64 v46, 0, v46, s[78:79]
	v_cndmask_b32_e64 v47, 0, v47, s[50:51]
	v_cvt_pk_bf16_f32 v64, v32, v33
	v_cvt_pk_bf16_f32 v65, v34, v35
	v_cvt_pk_bf16_f32 v66, v36, v37
	v_cvt_pk_bf16_f32 v67, v38, v39
	v_cvt_pk_bf16_f32 v68, v40, v41
	v_cvt_pk_bf16_f32 v69, v42, v43
	v_cvt_pk_bf16_f32 v70, v44, v45
	v_cvt_pk_bf16_f32 v71, v46, v47
	v_pk_add_f32 v[232:233], v[232:233], v[32:33]
	v_pk_add_f32 v[232:233], v[232:233], v[34:35]
	v_pk_add_f32 v[232:233], v[232:233], v[36:37]
	v_pk_add_f32 v[232:233], v[232:233], v[38:39]
	v_pk_add_f32 v[232:233], v[232:233], v[40:41]
	v_pk_add_f32 v[232:233], v[232:233], v[42:43]
	v_pk_add_f32 v[232:233], v[232:233], v[44:45]
	v_pk_add_f32 v[232:233], v[232:233], v[46:47]
	ds_read2_b32 v[32:33], v115 offset0:68 offset1:69
	ds_read2_b32 v[34:35], v115 offset0:70 offset1:71
	ds_read2_b32 v[36:37], v115 offset0:76 offset1:77
	ds_read2_b32 v[38:39], v115 offset0:78 offset1:79
	ds_read2_b32 v[40:41], v115 offset0:85 offset1:86
	ds_read2_b32 v[42:43], v115 offset0:87 offset1:88
	ds_read2_b32 v[44:45], v115 offset0:93 offset1:94
	ds_read2_b32 v[46:47], v115 offset0:95 offset1:96
	v_mfma_f32_32x32x16_bf16 v[0:15], v[64:67], v[72:75], v[0:15]
	v_mfma_f32_32x32x16_bf16 v[16:31], v[64:67], v[76:79], v[16:31]
	v_mfma_f32_32x32x16_bf16 v[0:15], v[68:71], v[220:223], v[0:15]
	v_mfma_f32_32x32x16_bf16 v[16:31], v[68:71], v[224:227], v[16:31]
	s_add_i32 s90, s76, 32
	v_add_u32_e32 v80, s90, v235
	v_add_u32_e32 v83, s90, v236
	v_add_u32_e32 v99, s90, v237
	v_add_u32_e32 v253, s90, v238
	v_add_u32_e32 v254, s90, v100
	v_add_u32_e32 v255, s90, v149
	v_med3_i32 v80, v80, 0, s99
	v_med3_i32 v83, v83, 0, s99
	v_med3_i32 v99, v99, 0, s99
	v_med3_i32 v253, v253, 0, s99
	v_med3_i32 v254, v254, 0, s99
	v_med3_i32 v255, v255, 0, s99
	v_mad_u32_u24 v80, v80, s100, v252
	v_mad_u32_u24 v83, v83, s100, v252
	v_mad_u32_u24 v99, v99, s100, v252
	v_mad_u32_u24 v253, v253, s100, v252
	v_mad_u32_u24 v254, v254, s100, v153
	v_mad_u32_u24 v255, v255, s100, v153
	global_load_dwordx4 v[156:159], v80, s[82:83]
	global_load_dwordx4 v[160:163], v83, s[82:83]
	global_load_dwordx4 v[164:167], v99, s[82:83]
	global_load_dwordx4 v[168:171], v253, s[82:83]
	global_load_dwordx4 v[172:175], v254, s[82:83] offset:768
	global_load_dwordx4 v[176:179], v255, s[82:83] offset:768
	global_load_dwordx4 v[180:183], v254, s[82:83] offset:832
	global_load_dwordx4 v[184:187], v255, s[82:83] offset:832
	ds_read_b64_tr_b16 v[72:73], v231
	ds_read_b64_tr_b16 v[74:75], v231 offset:512
	ds_read_b64_tr_b16 v[76:77], v231 offset:2048
	ds_read_b64_tr_b16 v[78:79], v231 offset:2560
	ds_read_b64_tr_b16 v[220:221], v231 offset:1024
	ds_read_b64_tr_b16 v[222:223], v231 offset:1536
	ds_read_b64_tr_b16 v[224:225], v231 offset:3072
	ds_read_b64_tr_b16 v[226:227], v231 offset:3584
	s_waitcnt vmcnt(8)
	ds_write_b128 v247, v[116:119]
	ds_write_b128 v247, v[120:123] offset:1024
	ds_write_b128 v111, v[124:127] offset:2048
	ds_write_b128 v111, v[128:131] offset:3072
	ds_read_b128 v[116:119], v248
	ds_read_b128 v[120:123], v249
	ds_read_b128 v[124:127], v250
	ds_read_b128 v[128:131], v251
	ds_write_b128 v112, v[132:135]
	ds_write_b128 v112, v[136:139] offset:1024
	ds_write_b128 v112, v[140:143] offset:2048
	ds_write_b128 v112, v[144:147] offset:3072
	v_exp_f32_e32 v188, v188
	v_exp_f32_e32 v189, v189
	v_exp_f32_e32 v190, v190
	v_exp_f32_e32 v191, v191
	v_exp_f32_e32 v192, v192
	v_exp_f32_e32 v193, v193
	s_waitcnt lgkmcnt(4)
	v_mfma_f32_32x32x16_bf16 v[32:47], v[116:119], v[48:51], v[32:47]
	v_exp_f32_e32 v194, v194
	v_exp_f32_e32 v195, v195
	v_mfma_f32_32x32x16_bf16 v[32:47], v[120:123], v[52:55], v[32:47]
	v_exp_f32_e32 v196, v196
	v_exp_f32_e32 v197, v197
	v_exp_f32_e32 v198, v198
	v_mfma_f32_32x32x16_bf16 v[32:47], v[124:127], v[56:59], v[32:47]
	v_exp_f32_e32 v199, v199
	v_exp_f32_e32 v200, v200
	v_mfma_f32_32x32x16_bf16 v[32:47], v[128:131], v[60:63], v[32:47]
	v_exp_f32_e32 v201, v201
	v_exp_f32_e32 v202, v202
	v_exp_f32_e32 v203, v203
	s_add_i32 s90, s76, -32
	v_add_u32_e32 v84, s90, v107
	v_add_u32_e32 v85, 0, v84
	v_add_u32_e32 v86, 1, v84
	v_add_u32_e32 v87, 2, v84
	v_add_u32_e32 v88, 3, v84
	v_cmp_gt_u32_e64 s[30:31], s98, v85
	v_cmp_gt_u32_e64 s[36:37], s98, v86
	v_cmp_gt_u32_e64 s[78:79], s98, v87
	v_cmp_gt_u32_e64 s[50:51], s98, v88
	v_cndmask_b32_e64 v188, 0, v188, s[30:31]
	v_add_u32_e32 v85, 8, v84
	v_cmp_gt_u32_e64 s[30:31], s98, v85
	v_cndmask_b32_e64 v189, 0, v189, s[36:37]
	v_add_u32_e32 v86, 9, v84
	v_cmp_gt_u32_e64 s[36:37], s98, v86
	v_cndmask_b32_e64 v190, 0, v190, s[78:79]
	v_add_u32_e32 v87, 10, v84
	v_cmp_gt_u32_e64 s[78:79], s98, v87
	v_cndmask_b32_e64 v191, 0, v191, s[50:51]
	v_add_u32_e32 v88, 11, v84
	v_cmp_gt_u32_e64 s[50:51], s98, v88
	v_cndmask_b32_e64 v192, 0, v192, s[30:31]
	v_add_u32_e32 v85, 16, v84
	v_cmp_gt_u32_e64 s[30:31], s98, v85
	v_cndmask_b32_e64 v193, 0, v193, s[36:37]
	v_add_u32_e32 v86, 17, v84
	v_cmp_gt_u32_e64 s[36:37], s98, v86
	v_cndmask_b32_e64 v194, 0, v194, s[78:79]
	v_add_u32_e32 v87, 18, v84
	v_cmp_gt_u32_e64 s[78:79], s98, v87
	v_cndmask_b32_e64 v195, 0, v195, s[50:51]
	v_add_u32_e32 v88, 19, v84
	v_cmp_gt_u32_e64 s[50:51], s98, v88
	v_cndmask_b32_e64 v196, 0, v196, s[30:31]
	v_add_u32_e32 v85, 24, v84
	v_cmp_gt_u32_e64 s[30:31], s98, v85
	v_cndmask_b32_e64 v197, 0, v197, s[36:37]
	v_add_u32_e32 v86, 25, v84
	v_cmp_gt_u32_e64 s[36:37], s98, v86
	v_cndmask_b32_e64 v198, 0, v198, s[78:79]
	v_add_u32_e32 v87, 26, v84
	v_cmp_gt_u32_e64 s[78:79], s98, v87
	v_cndmask_b32_e64 v199, 0, v199, s[50:51]
	v_add_u32_e32 v88, 27, v84
	v_cmp_gt_u32_e64 s[50:51], s98, v88
	v_nop
	v_cndmask_b32_e64 v200, 0, v200, s[30:31]
	v_cndmask_b32_e64 v201, 0, v201, s[36:37]
	v_cndmask_b32_e64 v202, 0, v202, s[78:79]
	v_cndmask_b32_e64 v203, 0, v203, s[50:51]
	v_cvt_pk_bf16_f32 v64, v188, v189
	v_cvt_pk_bf16_f32 v65, v190, v191
	v_cvt_pk_bf16_f32 v66, v192, v193
	v_cvt_pk_bf16_f32 v67, v194, v195
	v_cvt_pk_bf16_f32 v68, v196, v197
	v_cvt_pk_bf16_f32 v69, v198, v199
	v_cvt_pk_bf16_f32 v70, v200, v201
	v_cvt_pk_bf16_f32 v71, v202, v203
	v_pk_add_f32 v[232:233], v[232:233], v[188:189]
	v_pk_add_f32 v[232:233], v[232:233], v[190:191]
	v_pk_add_f32 v[232:233], v[232:233], v[192:193]
	v_pk_add_f32 v[232:233], v[232:233], v[194:195]
	v_pk_add_f32 v[232:233], v[232:233], v[196:197]
	v_pk_add_f32 v[232:233], v[232:233], v[198:199]
	v_pk_add_f32 v[232:233], v[232:233], v[200:201]
	v_pk_add_f32 v[232:233], v[232:233], v[202:203]
	ds_read2_b32 v[188:189], v115 offset0:102 offset1:103
	ds_read2_b32 v[190:191], v115 offset0:104 offset1:105
	ds_read2_b32 v[192:193], v115 offset0:110 offset1:111
	ds_read2_b32 v[194:195], v115 offset0:112 offset1:113
	ds_read2_b32 v[196:197], v115 offset0:119 offset1:120
	ds_read2_b32 v[198:199], v115 offset0:121 offset1:122
	ds_read2_b32 v[200:201], v115 offset0:127 offset1:128
	ds_read2_b32 v[202:203], v115 offset0:129 offset1:130
	v_mfma_f32_32x32x16_bf16 v[0:15], v[64:67], v[72:75], v[0:15]
	v_mfma_f32_32x32x16_bf16 v[16:31], v[64:67], v[76:79], v[16:31]
	v_mfma_f32_32x32x16_bf16 v[0:15], v[68:71], v[220:223], v[0:15]
	v_mfma_f32_32x32x16_bf16 v[16:31], v[68:71], v[224:227], v[16:31]
	s_add_i32 s90, s76, 64
	v_add_u32_e32 v80, s90, v235
	v_add_u32_e32 v83, s90, v236
	v_add_u32_e32 v99, s90, v237
	v_add_u32_e32 v253, s90, v238
	v_add_u32_e32 v254, s90, v100
	v_add_u32_e32 v255, s90, v149
	v_med3_i32 v80, v80, 0, s99
	v_med3_i32 v83, v83, 0, s99
	v_med3_i32 v99, v99, 0, s99
	v_med3_i32 v253, v253, 0, s99
	v_med3_i32 v254, v254, 0, s99
	v_med3_i32 v255, v255, 0, s99
	v_mad_u32_u24 v80, v80, s100, v252
	v_mad_u32_u24 v83, v83, s100, v252
	v_mad_u32_u24 v99, v99, s100, v252
	v_mad_u32_u24 v253, v253, s100, v252
	v_mad_u32_u24 v254, v254, s100, v153
	v_mad_u32_u24 v255, v255, s100, v153
	global_load_dwordx4 v[116:119], v80, s[82:83]
	global_load_dwordx4 v[120:123], v83, s[82:83]
	global_load_dwordx4 v[124:127], v99, s[82:83]
	global_load_dwordx4 v[128:131], v253, s[82:83]
	global_load_dwordx4 v[132:135], v254, s[82:83] offset:768
	global_load_dwordx4 v[136:139], v255, s[82:83] offset:768
	global_load_dwordx4 v[140:143], v254, s[82:83] offset:832
	global_load_dwordx4 v[144:147], v255, s[82:83] offset:832
	ds_read_b64_tr_b16 v[72:73], v231
	ds_read_b64_tr_b16 v[74:75], v231 offset:512
	ds_read_b64_tr_b16 v[76:77], v231 offset:2048
	ds_read_b64_tr_b16 v[78:79], v231 offset:2560
	ds_read_b64_tr_b16 v[220:221], v231 offset:1024
	ds_read_b64_tr_b16 v[222:223], v231 offset:1536
	ds_read_b64_tr_b16 v[224:225], v231 offset:3072
	ds_read_b64_tr_b16 v[226:227], v231 offset:3584
	s_waitcnt vmcnt(8)
	ds_write_b128 v247, v[156:159]
	ds_write_b128 v247, v[160:163] offset:1024
	ds_write_b128 v111, v[164:167] offset:2048
	ds_write_b128 v111, v[168:171] offset:3072
	ds_read_b128 v[156:159], v248
	ds_read_b128 v[160:163], v249
	ds_read_b128 v[164:167], v250
	ds_read_b128 v[168:171], v251
	ds_write_b128 v112, v[172:175]
	ds_write_b128 v112, v[176:179] offset:1024
	ds_write_b128 v112, v[180:183] offset:2048
	ds_write_b128 v112, v[184:187] offset:3072
	v_exp_f32_e32 v32, v32
	v_exp_f32_e32 v33, v33
	v_exp_f32_e32 v34, v34
	v_exp_f32_e32 v35, v35
	v_exp_f32_e32 v36, v36
	v_exp_f32_e32 v37, v37
	s_waitcnt lgkmcnt(4)
	v_mfma_f32_32x32x16_bf16 v[188:203], v[156:159], v[48:51], v[188:203]
	v_exp_f32_e32 v38, v38
	v_exp_f32_e32 v39, v39
	v_mfma_f32_32x32x16_bf16 v[188:203], v[160:163], v[52:55], v[188:203]
	v_exp_f32_e32 v40, v40
	v_exp_f32_e32 v41, v41
	v_exp_f32_e32 v42, v42
	v_mfma_f32_32x32x16_bf16 v[188:203], v[164:167], v[56:59], v[188:203]
	v_exp_f32_e32 v43, v43
	v_exp_f32_e32 v44, v44
	v_mfma_f32_32x32x16_bf16 v[188:203], v[168:171], v[60:63], v[188:203]
	v_exp_f32_e32 v45, v45
	v_exp_f32_e32 v46, v46
	v_exp_f32_e32 v47, v47
	s_add_i32 s90, s76, 0
	v_add_u32_e32 v84, s90, v107
	v_add_u32_e32 v85, 0, v84
	v_add_u32_e32 v86, 1, v84
	v_add_u32_e32 v87, 2, v84
	v_add_u32_e32 v88, 3, v84
	v_cmp_gt_u32_e64 s[30:31], s98, v85
	v_cmp_gt_u32_e64 s[36:37], s98, v86
	v_cmp_gt_u32_e64 s[78:79], s98, v87
	v_cmp_gt_u32_e64 s[50:51], s98, v88
	v_cndmask_b32_e64 v32, 0, v32, s[30:31]
	v_add_u32_e32 v85, 8, v84
	v_cmp_gt_u32_e64 s[30:31], s98, v85
	v_cndmask_b32_e64 v33, 0, v33, s[36:37]
	v_add_u32_e32 v86, 9, v84
	v_cmp_gt_u32_e64 s[36:37], s98, v86
	v_cndmask_b32_e64 v34, 0, v34, s[78:79]
	v_add_u32_e32 v87, 10, v84
	v_cmp_gt_u32_e64 s[78:79], s98, v87
	v_cndmask_b32_e64 v35, 0, v35, s[50:51]
	v_add_u32_e32 v88, 11, v84
	v_cmp_gt_u32_e64 s[50:51], s98, v88
	v_cndmask_b32_e64 v36, 0, v36, s[30:31]
	v_add_u32_e32 v85, 16, v84
	v_cmp_gt_u32_e64 s[30:31], s98, v85
	v_cndmask_b32_e64 v37, 0, v37, s[36:37]
	v_add_u32_e32 v86, 17, v84
	v_cmp_gt_u32_e64 s[36:37], s98, v86
	v_cndmask_b32_e64 v38, 0, v38, s[78:79]
	v_add_u32_e32 v87, 18, v84
	v_cmp_gt_u32_e64 s[78:79], s98, v87
	v_cndmask_b32_e64 v39, 0, v39, s[50:51]
	v_add_u32_e32 v88, 19, v84
	v_cmp_gt_u32_e64 s[50:51], s98, v88
	v_cndmask_b32_e64 v40, 0, v40, s[30:31]
	v_add_u32_e32 v85, 24, v84
	v_cmp_gt_u32_e64 s[30:31], s98, v85
	v_cndmask_b32_e64 v41, 0, v41, s[36:37]
	v_add_u32_e32 v86, 25, v84
	v_cmp_gt_u32_e64 s[36:37], s98, v86
	v_cndmask_b32_e64 v42, 0, v42, s[78:79]
	v_add_u32_e32 v87, 26, v84
	v_cmp_gt_u32_e64 s[78:79], s98, v87
	v_cndmask_b32_e64 v43, 0, v43, s[50:51]
	v_add_u32_e32 v88, 27, v84
	v_cmp_gt_u32_e64 s[50:51], s98, v88
	v_nop
	v_cndmask_b32_e64 v44, 0, v44, s[30:31]
	v_cndmask_b32_e64 v45, 0, v45, s[36:37]
	v_cndmask_b32_e64 v46, 0, v46, s[78:79]
	v_cndmask_b32_e64 v47, 0, v47, s[50:51]
	v_cvt_pk_bf16_f32 v64, v32, v33
	v_cvt_pk_bf16_f32 v65, v34, v35
	v_cvt_pk_bf16_f32 v66, v36, v37
	v_cvt_pk_bf16_f32 v67, v38, v39
	v_cvt_pk_bf16_f32 v68, v40, v41
	v_cvt_pk_bf16_f32 v69, v42, v43
	v_cvt_pk_bf16_f32 v70, v44, v45
	v_cvt_pk_bf16_f32 v71, v46, v47
	v_pk_add_f32 v[232:233], v[232:233], v[32:33]
	v_pk_add_f32 v[232:233], v[232:233], v[34:35]
	v_pk_add_f32 v[232:233], v[232:233], v[36:37]
	v_pk_add_f32 v[232:233], v[232:233], v[38:39]
	v_pk_add_f32 v[232:233], v[232:233], v[40:41]
	v_pk_add_f32 v[232:233], v[232:233], v[42:43]
	v_pk_add_f32 v[232:233], v[232:233], v[44:45]
	v_pk_add_f32 v[232:233], v[232:233], v[46:47]
	ds_read2_b32 v[32:33], v115 offset0:136 offset1:137
	ds_read2_b32 v[34:35], v115 offset0:138 offset1:139
	ds_read2_b32 v[36:37], v115 offset0:144 offset1:145
	ds_read2_b32 v[38:39], v115 offset0:146 offset1:147
	ds_read2_b32 v[40:41], v115 offset0:153 offset1:154
	ds_read2_b32 v[42:43], v115 offset0:155 offset1:156
	ds_read2_b32 v[44:45], v115 offset0:161 offset1:162
	ds_read2_b32 v[46:47], v115 offset0:163 offset1:164
	v_mfma_f32_32x32x16_bf16 v[0:15], v[64:67], v[72:75], v[0:15]
	v_mfma_f32_32x32x16_bf16 v[16:31], v[64:67], v[76:79], v[16:31]
	v_mfma_f32_32x32x16_bf16 v[0:15], v[68:71], v[220:223], v[0:15]
	v_mfma_f32_32x32x16_bf16 v[16:31], v[68:71], v[224:227], v[16:31]
	s_add_i32 s90, s76, 96
	v_add_u32_e32 v80, s90, v235
	v_add_u32_e32 v83, s90, v236
	v_add_u32_e32 v99, s90, v237
	v_add_u32_e32 v253, s90, v238
	v_add_u32_e32 v254, s90, v100
	v_add_u32_e32 v255, s90, v149
	v_med3_i32 v80, v80, 0, s99
	v_med3_i32 v83, v83, 0, s99
	v_med3_i32 v99, v99, 0, s99
	v_med3_i32 v253, v253, 0, s99
	v_med3_i32 v254, v254, 0, s99
	v_med3_i32 v255, v255, 0, s99
	v_mad_u32_u24 v80, v80, s100, v252
	v_mad_u32_u24 v83, v83, s100, v252
	v_mad_u32_u24 v99, v99, s100, v252
	v_mad_u32_u24 v253, v253, s100, v252
	v_mad_u32_u24 v254, v254, s100, v153
	v_mad_u32_u24 v255, v255, s100, v153
	global_load_dwordx4 v[156:159], v80, s[82:83]
	global_load_dwordx4 v[160:163], v83, s[82:83]
	global_load_dwordx4 v[164:167], v99, s[82:83]
	global_load_dwordx4 v[168:171], v253, s[82:83]
	global_load_dwordx4 v[172:175], v254, s[82:83] offset:768
	global_load_dwordx4 v[176:179], v255, s[82:83] offset:768
	global_load_dwordx4 v[180:183], v254, s[82:83] offset:832
	global_load_dwordx4 v[184:187], v255, s[82:83] offset:832
	ds_read_b64_tr_b16 v[72:73], v231
	ds_read_b64_tr_b16 v[74:75], v231 offset:512
	ds_read_b64_tr_b16 v[76:77], v231 offset:2048
	ds_read_b64_tr_b16 v[78:79], v231 offset:2560
	ds_read_b64_tr_b16 v[220:221], v231 offset:1024
	ds_read_b64_tr_b16 v[222:223], v231 offset:1536
	ds_read_b64_tr_b16 v[224:225], v231 offset:3072
	ds_read_b64_tr_b16 v[226:227], v231 offset:3584
	s_waitcnt vmcnt(8)
	ds_write_b128 v247, v[116:119]
	ds_write_b128 v247, v[120:123] offset:1024
	ds_write_b128 v111, v[124:127] offset:2048
	ds_write_b128 v111, v[128:131] offset:3072
	ds_read_b128 v[116:119], v248
	ds_read_b128 v[120:123], v249
	ds_read_b128 v[124:127], v250
	ds_read_b128 v[128:131], v251
	ds_write_b128 v112, v[132:135]
	ds_write_b128 v112, v[136:139] offset:1024
	ds_write_b128 v112, v[140:143] offset:2048
	ds_write_b128 v112, v[144:147] offset:3072
	v_exp_f32_e32 v188, v188
	v_exp_f32_e32 v189, v189
	v_exp_f32_e32 v190, v190
	v_exp_f32_e32 v191, v191
	v_exp_f32_e32 v192, v192
	v_exp_f32_e32 v193, v193
	s_waitcnt lgkmcnt(4)
	v_mfma_f32_32x32x16_bf16 v[32:47], v[116:119], v[48:51], v[32:47]
	v_exp_f32_e32 v194, v194
	v_exp_f32_e32 v195, v195
	v_mfma_f32_32x32x16_bf16 v[32:47], v[120:123], v[52:55], v[32:47]
	v_exp_f32_e32 v196, v196
	v_exp_f32_e32 v197, v197
	v_exp_f32_e32 v198, v198
	v_mfma_f32_32x32x16_bf16 v[32:47], v[124:127], v[56:59], v[32:47]
	v_exp_f32_e32 v199, v199
	v_exp_f32_e32 v200, v200
	v_mfma_f32_32x32x16_bf16 v[32:47], v[128:131], v[60:63], v[32:47]
	v_exp_f32_e32 v201, v201
	v_exp_f32_e32 v202, v202
	v_exp_f32_e32 v203, v203
	s_add_i32 s90, s76, 32
	v_add_u32_e32 v84, s90, v107
	v_add_u32_e32 v85, 0, v84
	v_add_u32_e32 v86, 1, v84
	v_add_u32_e32 v87, 2, v84
	v_add_u32_e32 v88, 3, v84
	v_cmp_gt_u32_e64 s[30:31], s98, v85
	v_cmp_gt_u32_e64 s[36:37], s98, v86
	v_cmp_gt_u32_e64 s[78:79], s98, v87
	v_cmp_gt_u32_e64 s[50:51], s98, v88
	v_cndmask_b32_e64 v188, 0, v188, s[30:31]
	v_add_u32_e32 v85, 8, v84
	v_cmp_gt_u32_e64 s[30:31], s98, v85
	v_cndmask_b32_e64 v189, 0, v189, s[36:37]
	v_add_u32_e32 v86, 9, v84
	v_cmp_gt_u32_e64 s[36:37], s98, v86
	v_cndmask_b32_e64 v190, 0, v190, s[78:79]
	v_add_u32_e32 v87, 10, v84
	v_cmp_gt_u32_e64 s[78:79], s98, v87
	v_cndmask_b32_e64 v191, 0, v191, s[50:51]
	v_add_u32_e32 v88, 11, v84
	v_cmp_gt_u32_e64 s[50:51], s98, v88
	v_cndmask_b32_e64 v192, 0, v192, s[30:31]
	v_add_u32_e32 v85, 16, v84
	v_cmp_gt_u32_e64 s[30:31], s98, v85
	v_cndmask_b32_e64 v193, 0, v193, s[36:37]
	v_add_u32_e32 v86, 17, v84
	v_cmp_gt_u32_e64 s[36:37], s98, v86
	v_cndmask_b32_e64 v194, 0, v194, s[78:79]
	v_add_u32_e32 v87, 18, v84
	v_cmp_gt_u32_e64 s[78:79], s98, v87
	v_cndmask_b32_e64 v195, 0, v195, s[50:51]
	v_add_u32_e32 v88, 19, v84
	v_cmp_gt_u32_e64 s[50:51], s98, v88
	v_cndmask_b32_e64 v196, 0, v196, s[30:31]
	v_add_u32_e32 v85, 24, v84
	v_cmp_gt_u32_e64 s[30:31], s98, v85
	v_cndmask_b32_e64 v197, 0, v197, s[36:37]
	v_add_u32_e32 v86, 25, v84
	v_cmp_gt_u32_e64 s[36:37], s98, v86
	v_cndmask_b32_e64 v198, 0, v198, s[78:79]
	v_add_u32_e32 v87, 26, v84
	v_cmp_gt_u32_e64 s[78:79], s98, v87
	v_cndmask_b32_e64 v199, 0, v199, s[50:51]
	v_add_u32_e32 v88, 27, v84
	v_cmp_gt_u32_e64 s[50:51], s98, v88
	v_nop
	v_cndmask_b32_e64 v200, 0, v200, s[30:31]
	v_cndmask_b32_e64 v201, 0, v201, s[36:37]
	v_cndmask_b32_e64 v202, 0, v202, s[78:79]
	v_cndmask_b32_e64 v203, 0, v203, s[50:51]
	v_cvt_pk_bf16_f32 v64, v188, v189
	v_cvt_pk_bf16_f32 v65, v190, v191
	v_cvt_pk_bf16_f32 v66, v192, v193
	v_cvt_pk_bf16_f32 v67, v194, v195
	v_cvt_pk_bf16_f32 v68, v196, v197
	v_cvt_pk_bf16_f32 v69, v198, v199
	v_cvt_pk_bf16_f32 v70, v200, v201
	v_cvt_pk_bf16_f32 v71, v202, v203
	v_pk_add_f32 v[232:233], v[232:233], v[188:189]
	v_pk_add_f32 v[232:233], v[232:233], v[190:191]
	v_pk_add_f32 v[232:233], v[232:233], v[192:193]
	v_pk_add_f32 v[232:233], v[232:233], v[194:195]
	v_pk_add_f32 v[232:233], v[232:233], v[196:197]
	v_pk_add_f32 v[232:233], v[232:233], v[198:199]
	v_pk_add_f32 v[232:233], v[232:233], v[200:201]
	v_pk_add_f32 v[232:233], v[232:233], v[202:203]
	ds_read2_b32 v[188:189], v115 offset0:170 offset1:171
	ds_read2_b32 v[190:191], v115 offset0:172 offset1:173
	ds_read2_b32 v[192:193], v115 offset0:178 offset1:179
	ds_read2_b32 v[194:195], v115 offset0:180 offset1:181
	ds_read2_b32 v[196:197], v115 offset0:187 offset1:188
	ds_read2_b32 v[198:199], v115 offset0:189 offset1:190
	ds_read2_b32 v[200:201], v115 offset0:195 offset1:196
	ds_read2_b32 v[202:203], v115 offset0:197 offset1:198
	v_mfma_f32_32x32x16_bf16 v[0:15], v[64:67], v[72:75], v[0:15]
	v_mfma_f32_32x32x16_bf16 v[16:31], v[64:67], v[76:79], v[16:31]
	v_mfma_f32_32x32x16_bf16 v[0:15], v[68:71], v[220:223], v[0:15]
	v_mfma_f32_32x32x16_bf16 v[16:31], v[68:71], v[224:227], v[16:31]
	s_add_i32 s90, s76, 128
	v_add_u32_e32 v80, s90, v235
	v_add_u32_e32 v83, s90, v236
	v_add_u32_e32 v99, s90, v237
	v_add_u32_e32 v253, s90, v238
	v_add_u32_e32 v254, s90, v100
	v_add_u32_e32 v255, s90, v149
	v_med3_i32 v80, v80, 0, s99
	v_med3_i32 v83, v83, 0, s99
	v_med3_i32 v99, v99, 0, s99
	v_med3_i32 v253, v253, 0, s99
	v_med3_i32 v254, v254, 0, s99
	v_med3_i32 v255, v255, 0, s99
	v_mad_u32_u24 v80, v80, s100, v252
	v_mad_u32_u24 v83, v83, s100, v252
	v_mad_u32_u24 v99, v99, s100, v252
	v_mad_u32_u24 v253, v253, s100, v252
	v_mad_u32_u24 v254, v254, s100, v153
	v_mad_u32_u24 v255, v255, s100, v153
	global_load_dwordx4 v[116:119], v80, s[82:83]
	global_load_dwordx4 v[120:123], v83, s[82:83]
	global_load_dwordx4 v[124:127], v99, s[82:83]
	global_load_dwordx4 v[128:131], v253, s[82:83]
	global_load_dwordx4 v[132:135], v254, s[82:83] offset:768
	global_load_dwordx4 v[136:139], v255, s[82:83] offset:768
	global_load_dwordx4 v[140:143], v254, s[82:83] offset:832
	global_load_dwordx4 v[144:147], v255, s[82:83] offset:832
	ds_read_b64_tr_b16 v[72:73], v231
	ds_read_b64_tr_b16 v[74:75], v231 offset:512
	ds_read_b64_tr_b16 v[76:77], v231 offset:2048
	ds_read_b64_tr_b16 v[78:79], v231 offset:2560
	ds_read_b64_tr_b16 v[220:221], v231 offset:1024
	ds_read_b64_tr_b16 v[222:223], v231 offset:1536
	ds_read_b64_tr_b16 v[224:225], v231 offset:3072
	ds_read_b64_tr_b16 v[226:227], v231 offset:3584
	s_waitcnt vmcnt(8)
	ds_write_b128 v247, v[156:159]
	ds_write_b128 v247, v[160:163] offset:1024
	ds_write_b128 v111, v[164:167] offset:2048
	ds_write_b128 v111, v[168:171] offset:3072
	ds_read_b128 v[156:159], v248
	ds_read_b128 v[160:163], v249
	ds_read_b128 v[164:167], v250
	ds_read_b128 v[168:171], v251
	ds_write_b128 v112, v[172:175]
	ds_write_b128 v112, v[176:179] offset:1024
	ds_write_b128 v112, v[180:183] offset:2048
	ds_write_b128 v112, v[184:187] offset:3072
	v_exp_f32_e32 v32, v32
	v_exp_f32_e32 v33, v33
	v_exp_f32_e32 v34, v34
	v_exp_f32_e32 v35, v35
	v_exp_f32_e32 v36, v36
	v_exp_f32_e32 v37, v37
	s_waitcnt lgkmcnt(4)
	v_mfma_f32_32x32x16_bf16 v[188:203], v[156:159], v[48:51], v[188:203]
	v_exp_f32_e32 v38, v38
	v_exp_f32_e32 v39, v39
	v_mfma_f32_32x32x16_bf16 v[188:203], v[160:163], v[52:55], v[188:203]
	v_exp_f32_e32 v40, v40
	v_exp_f32_e32 v41, v41
	v_exp_f32_e32 v42, v42
	v_mfma_f32_32x32x16_bf16 v[188:203], v[164:167], v[56:59], v[188:203]
	v_exp_f32_e32 v43, v43
	v_exp_f32_e32 v44, v44
	v_mfma_f32_32x32x16_bf16 v[188:203], v[168:171], v[60:63], v[188:203]
	v_exp_f32_e32 v45, v45
	v_exp_f32_e32 v46, v46
	v_exp_f32_e32 v47, v47
	s_add_i32 s90, s76, 64
	v_add_u32_e32 v84, s90, v107
	v_add_u32_e32 v85, 0, v84
	v_add_u32_e32 v86, 1, v84
	v_add_u32_e32 v87, 2, v84
	v_add_u32_e32 v88, 3, v84
	v_cmp_gt_u32_e64 s[30:31], s98, v85
	v_cmp_gt_u32_e64 s[36:37], s98, v86
	v_cmp_gt_u32_e64 s[78:79], s98, v87
	v_cmp_gt_u32_e64 s[50:51], s98, v88
	v_cndmask_b32_e64 v32, 0, v32, s[30:31]
	v_add_u32_e32 v85, 8, v84
	v_cmp_gt_u32_e64 s[30:31], s98, v85
	v_cndmask_b32_e64 v33, 0, v33, s[36:37]
	v_add_u32_e32 v86, 9, v84
	v_cmp_gt_u32_e64 s[36:37], s98, v86
	v_cndmask_b32_e64 v34, 0, v34, s[78:79]
	v_add_u32_e32 v87, 10, v84
	v_cmp_gt_u32_e64 s[78:79], s98, v87
	v_cndmask_b32_e64 v35, 0, v35, s[50:51]
	v_add_u32_e32 v88, 11, v84
	v_cmp_gt_u32_e64 s[50:51], s98, v88
	v_cndmask_b32_e64 v36, 0, v36, s[30:31]
	v_add_u32_e32 v85, 16, v84
	v_cmp_gt_u32_e64 s[30:31], s98, v85
	v_cndmask_b32_e64 v37, 0, v37, s[36:37]
	v_add_u32_e32 v86, 17, v84
	v_cmp_gt_u32_e64 s[36:37], s98, v86
	v_cndmask_b32_e64 v38, 0, v38, s[78:79]
	v_add_u32_e32 v87, 18, v84
	v_cmp_gt_u32_e64 s[78:79], s98, v87
	v_cndmask_b32_e64 v39, 0, v39, s[50:51]
	v_add_u32_e32 v88, 19, v84
	v_cmp_gt_u32_e64 s[50:51], s98, v88
	v_cndmask_b32_e64 v40, 0, v40, s[30:31]
	v_add_u32_e32 v85, 24, v84
	v_cmp_gt_u32_e64 s[30:31], s98, v85
	v_cndmask_b32_e64 v41, 0, v41, s[36:37]
	v_add_u32_e32 v86, 25, v84
	v_cmp_gt_u32_e64 s[36:37], s98, v86
	v_cndmask_b32_e64 v42, 0, v42, s[78:79]
	v_add_u32_e32 v87, 26, v84
	v_cmp_gt_u32_e64 s[78:79], s98, v87
	v_cndmask_b32_e64 v43, 0, v43, s[50:51]
	v_add_u32_e32 v88, 27, v84
	v_cmp_gt_u32_e64 s[50:51], s98, v88
	v_nop
	v_cndmask_b32_e64 v44, 0, v44, s[30:31]
	v_cndmask_b32_e64 v45, 0, v45, s[36:37]
	v_cndmask_b32_e64 v46, 0, v46, s[78:79]
	v_cndmask_b32_e64 v47, 0, v47, s[50:51]
	v_cvt_pk_bf16_f32 v64, v32, v33
	v_cvt_pk_bf16_f32 v65, v34, v35
	v_cvt_pk_bf16_f32 v66, v36, v37
	v_cvt_pk_bf16_f32 v67, v38, v39
	v_cvt_pk_bf16_f32 v68, v40, v41
	v_cvt_pk_bf16_f32 v69, v42, v43
	v_cvt_pk_bf16_f32 v70, v44, v45
	v_cvt_pk_bf16_f32 v71, v46, v47
	v_pk_add_f32 v[232:233], v[232:233], v[32:33]
	v_pk_add_f32 v[232:233], v[232:233], v[34:35]
	v_pk_add_f32 v[232:233], v[232:233], v[36:37]
	v_pk_add_f32 v[232:233], v[232:233], v[38:39]
	v_pk_add_f32 v[232:233], v[232:233], v[40:41]
	v_pk_add_f32 v[232:233], v[232:233], v[42:43]
	v_pk_add_f32 v[232:233], v[232:233], v[44:45]
	v_pk_add_f32 v[232:233], v[232:233], v[46:47]
	ds_read2_b32 v[32:33], v115 offset0:204 offset1:205
	ds_read2_b32 v[34:35], v115 offset0:206 offset1:207
	ds_read2_b32 v[36:37], v115 offset0:212 offset1:213
	ds_read2_b32 v[38:39], v115 offset0:214 offset1:215
	ds_read2_b32 v[40:41], v115 offset0:221 offset1:222
	ds_read2_b32 v[42:43], v115 offset0:223 offset1:224
	ds_read2_b32 v[44:45], v115 offset0:229 offset1:230
	ds_read2_b32 v[46:47], v115 offset0:231 offset1:232
	v_mfma_f32_32x32x16_bf16 v[0:15], v[64:67], v[72:75], v[0:15]
	v_mfma_f32_32x32x16_bf16 v[16:31], v[64:67], v[76:79], v[16:31]
	v_mfma_f32_32x32x16_bf16 v[0:15], v[68:71], v[220:223], v[0:15]
	v_mfma_f32_32x32x16_bf16 v[16:31], v[68:71], v[224:227], v[16:31]
	s_add_i32 s90, s76, 160
	v_add_u32_e32 v80, s90, v235
	v_add_u32_e32 v83, s90, v236
	v_add_u32_e32 v99, s90, v237
	v_add_u32_e32 v253, s90, v238
	v_add_u32_e32 v254, s90, v100
	v_add_u32_e32 v255, s90, v149
	v_med3_i32 v80, v80, 0, s99
	v_med3_i32 v83, v83, 0, s99
	v_med3_i32 v99, v99, 0, s99
	v_med3_i32 v253, v253, 0, s99
	v_med3_i32 v254, v254, 0, s99
	v_med3_i32 v255, v255, 0, s99
	v_mad_u32_u24 v80, v80, s100, v252
	v_mad_u32_u24 v83, v83, s100, v252
	v_mad_u32_u24 v99, v99, s100, v252
	v_mad_u32_u24 v253, v253, s100, v252
	v_mad_u32_u24 v254, v254, s100, v153
	v_mad_u32_u24 v255, v255, s100, v153
	global_load_dwordx4 v[156:159], v80, s[82:83]
	global_load_dwordx4 v[160:163], v83, s[82:83]
	global_load_dwordx4 v[164:167], v99, s[82:83]
	global_load_dwordx4 v[168:171], v253, s[82:83]
	global_load_dwordx4 v[172:175], v254, s[82:83] offset:768
	global_load_dwordx4 v[176:179], v255, s[82:83] offset:768
	global_load_dwordx4 v[180:183], v254, s[82:83] offset:832
	global_load_dwordx4 v[184:187], v255, s[82:83] offset:832
	ds_read_b64_tr_b16 v[72:73], v231
	ds_read_b64_tr_b16 v[74:75], v231 offset:512
	ds_read_b64_tr_b16 v[76:77], v231 offset:2048
	ds_read_b64_tr_b16 v[78:79], v231 offset:2560
	ds_read_b64_tr_b16 v[220:221], v231 offset:1024
	ds_read_b64_tr_b16 v[222:223], v231 offset:1536
	ds_read_b64_tr_b16 v[224:225], v231 offset:3072
	ds_read_b64_tr_b16 v[226:227], v231 offset:3584
	s_waitcnt vmcnt(8)
	ds_write_b128 v247, v[116:119]
	ds_write_b128 v247, v[120:123] offset:1024
	ds_write_b128 v111, v[124:127] offset:2048
	ds_write_b128 v111, v[128:131] offset:3072
	ds_read_b128 v[116:119], v248
	ds_read_b128 v[120:123], v249
	ds_read_b128 v[124:127], v250
	ds_read_b128 v[128:131], v251
	ds_write_b128 v112, v[132:135]
	ds_write_b128 v112, v[136:139] offset:1024
	ds_write_b128 v112, v[140:143] offset:2048
	ds_write_b128 v112, v[144:147] offset:3072
	v_exp_f32_e32 v188, v188
	v_exp_f32_e32 v189, v189
	v_exp_f32_e32 v190, v190
	v_exp_f32_e32 v191, v191
	v_exp_f32_e32 v192, v192
	v_exp_f32_e32 v193, v193
	s_waitcnt lgkmcnt(4)
	v_mfma_f32_32x32x16_bf16 v[32:47], v[116:119], v[48:51], v[32:47]
	v_exp_f32_e32 v194, v194
	v_exp_f32_e32 v195, v195
	v_mfma_f32_32x32x16_bf16 v[32:47], v[120:123], v[52:55], v[32:47]
	v_exp_f32_e32 v196, v196
	v_exp_f32_e32 v197, v197
	v_exp_f32_e32 v198, v198
	v_mfma_f32_32x32x16_bf16 v[32:47], v[124:127], v[56:59], v[32:47]
	v_exp_f32_e32 v199, v199
	v_exp_f32_e32 v200, v200
	v_mfma_f32_32x32x16_bf16 v[32:47], v[128:131], v[60:63], v[32:47]
	v_exp_f32_e32 v201, v201
	v_exp_f32_e32 v202, v202
	v_exp_f32_e32 v203, v203
	s_add_i32 s90, s76, 96
	v_add_u32_e32 v84, s90, v107
	v_add_u32_e32 v85, 0, v84
	v_add_u32_e32 v86, 1, v84
	v_add_u32_e32 v87, 2, v84
	v_add_u32_e32 v88, 3, v84
	v_cmp_gt_u32_e64 s[30:31], s98, v85
	v_cmp_gt_u32_e64 s[36:37], s98, v86
	v_cmp_gt_u32_e64 s[78:79], s98, v87
	v_cmp_gt_u32_e64 s[50:51], s98, v88
	v_cndmask_b32_e64 v188, 0, v188, s[30:31]
	v_add_u32_e32 v85, 8, v84
	v_cmp_gt_u32_e64 s[30:31], s98, v85
	v_cndmask_b32_e64 v189, 0, v189, s[36:37]
	v_add_u32_e32 v86, 9, v84
	v_cmp_gt_u32_e64 s[36:37], s98, v86
	v_cndmask_b32_e64 v190, 0, v190, s[78:79]
	v_add_u32_e32 v87, 10, v84
	v_cmp_gt_u32_e64 s[78:79], s98, v87
	v_cndmask_b32_e64 v191, 0, v191, s[50:51]
	v_add_u32_e32 v88, 11, v84
	v_cmp_gt_u32_e64 s[50:51], s98, v88
	v_cndmask_b32_e64 v192, 0, v192, s[30:31]
	v_add_u32_e32 v85, 16, v84
	v_cmp_gt_u32_e64 s[30:31], s98, v85
	v_cndmask_b32_e64 v193, 0, v193, s[36:37]
	v_add_u32_e32 v86, 17, v84
	v_cmp_gt_u32_e64 s[36:37], s98, v86
	v_cndmask_b32_e64 v194, 0, v194, s[78:79]
	v_add_u32_e32 v87, 18, v84
	v_cmp_gt_u32_e64 s[78:79], s98, v87
	v_cndmask_b32_e64 v195, 0, v195, s[50:51]
	v_add_u32_e32 v88, 19, v84
	v_cmp_gt_u32_e64 s[50:51], s98, v88
	v_cndmask_b32_e64 v196, 0, v196, s[30:31]
	v_add_u32_e32 v85, 24, v84
	v_cmp_gt_u32_e64 s[30:31], s98, v85
	v_cndmask_b32_e64 v197, 0, v197, s[36:37]
	v_add_u32_e32 v86, 25, v84
	v_cmp_gt_u32_e64 s[36:37], s98, v86
	v_cndmask_b32_e64 v198, 0, v198, s[78:79]
	v_add_u32_e32 v87, 26, v84
	v_cmp_gt_u32_e64 s[78:79], s98, v87
	v_cndmask_b32_e64 v199, 0, v199, s[50:51]
	v_add_u32_e32 v88, 27, v84
	v_cmp_gt_u32_e64 s[50:51], s98, v88
	v_nop
	v_cndmask_b32_e64 v200, 0, v200, s[30:31]
	v_cndmask_b32_e64 v201, 0, v201, s[36:37]
	v_cndmask_b32_e64 v202, 0, v202, s[78:79]
	v_cndmask_b32_e64 v203, 0, v203, s[50:51]
	v_cvt_pk_bf16_f32 v64, v188, v189
	v_cvt_pk_bf16_f32 v65, v190, v191
	v_cvt_pk_bf16_f32 v66, v192, v193
	v_cvt_pk_bf16_f32 v67, v194, v195
	v_cvt_pk_bf16_f32 v68, v196, v197
	v_cvt_pk_bf16_f32 v69, v198, v199
	v_cvt_pk_bf16_f32 v70, v200, v201
	v_cvt_pk_bf16_f32 v71, v202, v203
	v_pk_add_f32 v[232:233], v[232:233], v[188:189]
	v_pk_add_f32 v[232:233], v[232:233], v[190:191]
	v_pk_add_f32 v[232:233], v[232:233], v[192:193]
	v_pk_add_f32 v[232:233], v[232:233], v[194:195]
	v_pk_add_f32 v[232:233], v[232:233], v[196:197]
	v_pk_add_f32 v[232:233], v[232:233], v[198:199]
	v_pk_add_f32 v[232:233], v[232:233], v[200:201]
	v_pk_add_f32 v[232:233], v[232:233], v[202:203]
	v_add_u32_e32 v115, 952, v115
	ds_read2_b32 v[188:189], v115 offset0:0 offset1:1
	ds_read2_b32 v[190:191], v115 offset0:2 offset1:3
	ds_read2_b32 v[192:193], v115 offset0:8 offset1:9
	ds_read2_b32 v[194:195], v115 offset0:10 offset1:11
	ds_read2_b32 v[196:197], v115 offset0:17 offset1:18
	ds_read2_b32 v[198:199], v115 offset0:19 offset1:20
	ds_read2_b32 v[200:201], v115 offset0:25 offset1:26
	ds_read2_b32 v[202:203], v115 offset0:27 offset1:28
	v_mfma_f32_32x32x16_bf16 v[0:15], v[64:67], v[72:75], v[0:15]
	v_mfma_f32_32x32x16_bf16 v[16:31], v[64:67], v[76:79], v[16:31]
	v_mfma_f32_32x32x16_bf16 v[0:15], v[68:71], v[220:223], v[0:15]
	v_mfma_f32_32x32x16_bf16 v[16:31], v[68:71], v[224:227], v[16:31]
	s_add_i32 s90, s76, 192
	v_add_u32_e32 v80, s90, v235
	v_add_u32_e32 v83, s90, v236
	v_add_u32_e32 v99, s90, v237
	v_add_u32_e32 v253, s90, v238
	v_add_u32_e32 v254, s90, v100
	v_add_u32_e32 v255, s90, v149
	v_med3_i32 v80, v80, 0, s99
	v_med3_i32 v83, v83, 0, s99
	v_med3_i32 v99, v99, 0, s99
	v_med3_i32 v253, v253, 0, s99
	v_med3_i32 v254, v254, 0, s99
	v_med3_i32 v255, v255, 0, s99
	v_mad_u32_u24 v80, v80, s100, v252
	v_mad_u32_u24 v83, v83, s100, v252
	v_mad_u32_u24 v99, v99, s100, v252
	v_mad_u32_u24 v253, v253, s100, v252
	v_mad_u32_u24 v254, v254, s100, v153
	v_mad_u32_u24 v255, v255, s100, v153
	global_load_dwordx4 v[116:119], v80, s[82:83]
	global_load_dwordx4 v[120:123], v83, s[82:83]
	global_load_dwordx4 v[124:127], v99, s[82:83]
	global_load_dwordx4 v[128:131], v253, s[82:83]
	global_load_dwordx4 v[132:135], v254, s[82:83] offset:768
	global_load_dwordx4 v[136:139], v255, s[82:83] offset:768
	global_load_dwordx4 v[140:143], v254, s[82:83] offset:832
	global_load_dwordx4 v[144:147], v255, s[82:83] offset:832
	ds_read_b64_tr_b16 v[72:73], v231
	ds_read_b64_tr_b16 v[74:75], v231 offset:512
	ds_read_b64_tr_b16 v[76:77], v231 offset:2048
	ds_read_b64_tr_b16 v[78:79], v231 offset:2560
	ds_read_b64_tr_b16 v[220:221], v231 offset:1024
	ds_read_b64_tr_b16 v[222:223], v231 offset:1536
	ds_read_b64_tr_b16 v[224:225], v231 offset:3072
	ds_read_b64_tr_b16 v[226:227], v231 offset:3584
	s_waitcnt vmcnt(8)
	ds_write_b128 v247, v[156:159]
	ds_write_b128 v247, v[160:163] offset:1024
	ds_write_b128 v111, v[164:167] offset:2048
	ds_write_b128 v111, v[168:171] offset:3072
	ds_read_b128 v[156:159], v248
	ds_read_b128 v[160:163], v249
	ds_read_b128 v[164:167], v250
	ds_read_b128 v[168:171], v251
	ds_write_b128 v112, v[172:175]
	ds_write_b128 v112, v[176:179] offset:1024
	ds_write_b128 v112, v[180:183] offset:2048
	ds_write_b128 v112, v[184:187] offset:3072
	v_exp_f32_e32 v32, v32
	v_exp_f32_e32 v33, v33
	v_exp_f32_e32 v34, v34
	v_exp_f32_e32 v35, v35
	v_exp_f32_e32 v36, v36
	v_exp_f32_e32 v37, v37
	s_waitcnt lgkmcnt(4)
	v_mfma_f32_32x32x16_bf16 v[188:203], v[156:159], v[48:51], v[188:203]
	v_exp_f32_e32 v38, v38
	v_exp_f32_e32 v39, v39
	v_mfma_f32_32x32x16_bf16 v[188:203], v[160:163], v[52:55], v[188:203]
	v_exp_f32_e32 v40, v40
	v_exp_f32_e32 v41, v41
	v_exp_f32_e32 v42, v42
	v_mfma_f32_32x32x16_bf16 v[188:203], v[164:167], v[56:59], v[188:203]
	v_exp_f32_e32 v43, v43
	v_exp_f32_e32 v44, v44
	v_mfma_f32_32x32x16_bf16 v[188:203], v[168:171], v[60:63], v[188:203]
	v_exp_f32_e32 v45, v45
	v_exp_f32_e32 v46, v46
	v_exp_f32_e32 v47, v47
	s_add_i32 s90, s76, 128
	v_add_u32_e32 v84, s90, v107
	v_add_u32_e32 v85, 0, v84
	v_add_u32_e32 v86, 1, v84
	v_add_u32_e32 v87, 2, v84
	v_add_u32_e32 v88, 3, v84
	v_cmp_gt_u32_e64 s[30:31], s98, v85
	v_cmp_gt_u32_e64 s[36:37], s98, v86
	v_cmp_gt_u32_e64 s[78:79], s98, v87
	v_cmp_gt_u32_e64 s[50:51], s98, v88
	v_cndmask_b32_e64 v32, 0, v32, s[30:31]
	v_add_u32_e32 v85, 8, v84
	v_cmp_gt_u32_e64 s[30:31], s98, v85
	v_cndmask_b32_e64 v33, 0, v33, s[36:37]
	v_add_u32_e32 v86, 9, v84
	v_cmp_gt_u32_e64 s[36:37], s98, v86
	v_cndmask_b32_e64 v34, 0, v34, s[78:79]
	v_add_u32_e32 v87, 10, v84
	v_cmp_gt_u32_e64 s[78:79], s98, v87
	v_cndmask_b32_e64 v35, 0, v35, s[50:51]
	v_add_u32_e32 v88, 11, v84
	v_cmp_gt_u32_e64 s[50:51], s98, v88
	v_cndmask_b32_e64 v36, 0, v36, s[30:31]
	v_add_u32_e32 v85, 16, v84
	v_cmp_gt_u32_e64 s[30:31], s98, v85
	v_cndmask_b32_e64 v37, 0, v37, s[36:37]
	v_add_u32_e32 v86, 17, v84
	v_cmp_gt_u32_e64 s[36:37], s98, v86
	v_cndmask_b32_e64 v38, 0, v38, s[78:79]
	v_add_u32_e32 v87, 18, v84
	v_cmp_gt_u32_e64 s[78:79], s98, v87
	v_cndmask_b32_e64 v39, 0, v39, s[50:51]
	v_add_u32_e32 v88, 19, v84
	v_cmp_gt_u32_e64 s[50:51], s98, v88
	v_cndmask_b32_e64 v40, 0, v40, s[30:31]
	v_add_u32_e32 v85, 24, v84
	v_cmp_gt_u32_e64 s[30:31], s98, v85
	v_cndmask_b32_e64 v41, 0, v41, s[36:37]
	v_add_u32_e32 v86, 25, v84
	v_cmp_gt_u32_e64 s[36:37], s98, v86
	v_cndmask_b32_e64 v42, 0, v42, s[78:79]
	v_add_u32_e32 v87, 26, v84
	v_cmp_gt_u32_e64 s[78:79], s98, v87
	v_cndmask_b32_e64 v43, 0, v43, s[50:51]
	v_add_u32_e32 v88, 27, v84
	v_cmp_gt_u32_e64 s[50:51], s98, v88
	v_nop
	v_cndmask_b32_e64 v44, 0, v44, s[30:31]
	v_cndmask_b32_e64 v45, 0, v45, s[36:37]
	v_cndmask_b32_e64 v46, 0, v46, s[78:79]
	v_cndmask_b32_e64 v47, 0, v47, s[50:51]
	v_cvt_pk_bf16_f32 v64, v32, v33
	v_cvt_pk_bf16_f32 v65, v34, v35
	v_cvt_pk_bf16_f32 v66, v36, v37
	v_cvt_pk_bf16_f32 v67, v38, v39
	v_cvt_pk_bf16_f32 v68, v40, v41
	v_cvt_pk_bf16_f32 v69, v42, v43
	v_cvt_pk_bf16_f32 v70, v44, v45
	v_cvt_pk_bf16_f32 v71, v46, v47
	v_pk_add_f32 v[232:233], v[232:233], v[32:33]
	v_pk_add_f32 v[232:233], v[232:233], v[34:35]
	v_pk_add_f32 v[232:233], v[232:233], v[36:37]
	v_pk_add_f32 v[232:233], v[232:233], v[38:39]
	v_pk_add_f32 v[232:233], v[232:233], v[40:41]
	v_pk_add_f32 v[232:233], v[232:233], v[42:43]
	v_pk_add_f32 v[232:233], v[232:233], v[44:45]
	v_pk_add_f32 v[232:233], v[232:233], v[46:47]
	ds_read2_b32 v[32:33], v115 offset0:34 offset1:35
	ds_read2_b32 v[34:35], v115 offset0:36 offset1:37
	ds_read2_b32 v[36:37], v115 offset0:42 offset1:43
	ds_read2_b32 v[38:39], v115 offset0:44 offset1:45
	ds_read2_b32 v[40:41], v115 offset0:51 offset1:52
	ds_read2_b32 v[42:43], v115 offset0:53 offset1:54
	ds_read2_b32 v[44:45], v115 offset0:59 offset1:60
	ds_read2_b32 v[46:47], v115 offset0:61 offset1:62
	v_mfma_f32_32x32x16_bf16 v[0:15], v[64:67], v[72:75], v[0:15]
	v_mfma_f32_32x32x16_bf16 v[16:31], v[64:67], v[76:79], v[16:31]
	v_mfma_f32_32x32x16_bf16 v[0:15], v[68:71], v[220:223], v[0:15]
	v_mfma_f32_32x32x16_bf16 v[16:31], v[68:71], v[224:227], v[16:31]
	s_add_i32 s90, s76, 224
	v_add_u32_e32 v80, s90, v235
	v_add_u32_e32 v83, s90, v236
	v_add_u32_e32 v99, s90, v237
	v_add_u32_e32 v253, s90, v238
	v_add_u32_e32 v254, s90, v100
	v_add_u32_e32 v255, s90, v149
	v_med3_i32 v80, v80, 0, s99
	v_med3_i32 v83, v83, 0, s99
	v_med3_i32 v99, v99, 0, s99
	v_med3_i32 v253, v253, 0, s99
	v_med3_i32 v254, v254, 0, s99
	v_med3_i32 v255, v255, 0, s99
	v_mad_u32_u24 v80, v80, s100, v252
	v_mad_u32_u24 v83, v83, s100, v252
	v_mad_u32_u24 v99, v99, s100, v252
	v_mad_u32_u24 v253, v253, s100, v252
	v_mad_u32_u24 v254, v254, s100, v153
	v_mad_u32_u24 v255, v255, s100, v153
	global_load_dwordx4 v[156:159], v80, s[82:83]
	global_load_dwordx4 v[160:163], v83, s[82:83]
	global_load_dwordx4 v[164:167], v99, s[82:83]
	global_load_dwordx4 v[168:171], v253, s[82:83]
	global_load_dwordx4 v[172:175], v254, s[82:83] offset:768
	global_load_dwordx4 v[176:179], v255, s[82:83] offset:768
	global_load_dwordx4 v[180:183], v254, s[82:83] offset:832
	global_load_dwordx4 v[184:187], v255, s[82:83] offset:832
	ds_read_b64_tr_b16 v[72:73], v231
	ds_read_b64_tr_b16 v[74:75], v231 offset:512
	ds_read_b64_tr_b16 v[76:77], v231 offset:2048
	ds_read_b64_tr_b16 v[78:79], v231 offset:2560
	ds_read_b64_tr_b16 v[220:221], v231 offset:1024
	ds_read_b64_tr_b16 v[222:223], v231 offset:1536
	ds_read_b64_tr_b16 v[224:225], v231 offset:3072
	ds_read_b64_tr_b16 v[226:227], v231 offset:3584
	s_waitcnt vmcnt(8)
	ds_write_b128 v247, v[116:119]
	ds_write_b128 v247, v[120:123] offset:1024
	ds_write_b128 v111, v[124:127] offset:2048
	ds_write_b128 v111, v[128:131] offset:3072
	ds_read_b128 v[116:119], v248
	ds_read_b128 v[120:123], v249
	ds_read_b128 v[124:127], v250
	ds_read_b128 v[128:131], v251
	ds_write_b128 v112, v[132:135]
	ds_write_b128 v112, v[136:139] offset:1024
	ds_write_b128 v112, v[140:143] offset:2048
	ds_write_b128 v112, v[144:147] offset:3072
	v_exp_f32_e32 v188, v188
	v_exp_f32_e32 v189, v189
	v_exp_f32_e32 v190, v190
	v_exp_f32_e32 v191, v191
	v_exp_f32_e32 v192, v192
	v_exp_f32_e32 v193, v193
	s_waitcnt lgkmcnt(4)
	v_mfma_f32_32x32x16_bf16 v[32:47], v[116:119], v[48:51], v[32:47]
	v_exp_f32_e32 v194, v194
	v_exp_f32_e32 v195, v195
	v_mfma_f32_32x32x16_bf16 v[32:47], v[120:123], v[52:55], v[32:47]
	v_exp_f32_e32 v196, v196
	v_exp_f32_e32 v197, v197
	v_exp_f32_e32 v198, v198
	v_mfma_f32_32x32x16_bf16 v[32:47], v[124:127], v[56:59], v[32:47]
	v_exp_f32_e32 v199, v199
	v_exp_f32_e32 v200, v200
	v_mfma_f32_32x32x16_bf16 v[32:47], v[128:131], v[60:63], v[32:47]
	v_exp_f32_e32 v201, v201
	v_exp_f32_e32 v202, v202
	v_exp_f32_e32 v203, v203
	s_add_i32 s90, s76, 160
	v_add_u32_e32 v84, s90, v107
	v_add_u32_e32 v85, 0, v84
	v_add_u32_e32 v86, 1, v84
	v_add_u32_e32 v87, 2, v84
	v_add_u32_e32 v88, 3, v84
	v_cmp_gt_u32_e64 s[30:31], s98, v85
	v_cmp_gt_u32_e64 s[36:37], s98, v86
	v_cmp_gt_u32_e64 s[78:79], s98, v87
	v_cmp_gt_u32_e64 s[50:51], s98, v88
	v_cndmask_b32_e64 v188, 0, v188, s[30:31]
	v_add_u32_e32 v85, 8, v84
	v_cmp_gt_u32_e64 s[30:31], s98, v85
	v_cndmask_b32_e64 v189, 0, v189, s[36:37]
	v_add_u32_e32 v86, 9, v84
	v_cmp_gt_u32_e64 s[36:37], s98, v86
	v_cndmask_b32_e64 v190, 0, v190, s[78:79]
	v_add_u32_e32 v87, 10, v84
	v_cmp_gt_u32_e64 s[78:79], s98, v87
	v_cndmask_b32_e64 v191, 0, v191, s[50:51]
	v_add_u32_e32 v88, 11, v84
	v_cmp_gt_u32_e64 s[50:51], s98, v88
	v_cndmask_b32_e64 v192, 0, v192, s[30:31]
	v_add_u32_e32 v85, 16, v84
	v_cmp_gt_u32_e64 s[30:31], s98, v85
	v_cndmask_b32_e64 v193, 0, v193, s[36:37]
	v_add_u32_e32 v86, 17, v84
	v_cmp_gt_u32_e64 s[36:37], s98, v86
	v_cndmask_b32_e64 v194, 0, v194, s[78:79]
	v_add_u32_e32 v87, 18, v84
	v_cmp_gt_u32_e64 s[78:79], s98, v87
	v_cndmask_b32_e64 v195, 0, v195, s[50:51]
	v_add_u32_e32 v88, 19, v84
	v_cmp_gt_u32_e64 s[50:51], s98, v88
	v_cndmask_b32_e64 v196, 0, v196, s[30:31]
	v_add_u32_e32 v85, 24, v84
	v_cmp_gt_u32_e64 s[30:31], s98, v85
	v_cndmask_b32_e64 v197, 0, v197, s[36:37]
	v_add_u32_e32 v86, 25, v84
	v_cmp_gt_u32_e64 s[36:37], s98, v86
	v_cndmask_b32_e64 v198, 0, v198, s[78:79]
	v_add_u32_e32 v87, 26, v84
	v_cmp_gt_u32_e64 s[78:79], s98, v87
	v_cndmask_b32_e64 v199, 0, v199, s[50:51]
	v_add_u32_e32 v88, 27, v84
	v_cmp_gt_u32_e64 s[50:51], s98, v88
	v_nop
	v_cndmask_b32_e64 v200, 0, v200, s[30:31]
	v_cndmask_b32_e64 v201, 0, v201, s[36:37]
	v_cndmask_b32_e64 v202, 0, v202, s[78:79]
	v_cndmask_b32_e64 v203, 0, v203, s[50:51]
	v_cvt_pk_bf16_f32 v64, v188, v189
	v_cvt_pk_bf16_f32 v65, v190, v191
	v_cvt_pk_bf16_f32 v66, v192, v193
	v_cvt_pk_bf16_f32 v67, v194, v195
	v_cvt_pk_bf16_f32 v68, v196, v197
	v_cvt_pk_bf16_f32 v69, v198, v199
	v_cvt_pk_bf16_f32 v70, v200, v201
	v_cvt_pk_bf16_f32 v71, v202, v203
	v_pk_add_f32 v[232:233], v[232:233], v[188:189]
	v_pk_add_f32 v[232:233], v[232:233], v[190:191]
	v_pk_add_f32 v[232:233], v[232:233], v[192:193]
	v_pk_add_f32 v[232:233], v[232:233], v[194:195]
	v_pk_add_f32 v[232:233], v[232:233], v[196:197]
	v_pk_add_f32 v[232:233], v[232:233], v[198:199]
	v_pk_add_f32 v[232:233], v[232:233], v[200:201]
	v_pk_add_f32 v[232:233], v[232:233], v[202:203]
	ds_read2_b32 v[188:189], v115 offset0:68 offset1:69
	ds_read2_b32 v[190:191], v115 offset0:70 offset1:71
	ds_read2_b32 v[192:193], v115 offset0:76 offset1:77
	ds_read2_b32 v[194:195], v115 offset0:78 offset1:79
	ds_read2_b32 v[196:197], v115 offset0:85 offset1:86
	ds_read2_b32 v[198:199], v115 offset0:87 offset1:88
	ds_read2_b32 v[200:201], v115 offset0:93 offset1:94
	ds_read2_b32 v[202:203], v115 offset0:95 offset1:96
	v_mfma_f32_32x32x16_bf16 v[0:15], v[64:67], v[72:75], v[0:15]
	v_mfma_f32_32x32x16_bf16 v[16:31], v[64:67], v[76:79], v[16:31]
	v_mfma_f32_32x32x16_bf16 v[0:15], v[68:71], v[220:223], v[0:15]
	v_mfma_f32_32x32x16_bf16 v[16:31], v[68:71], v[224:227], v[16:31]
	s_add_i32 s90, s76, 256
	v_add_u32_e32 v80, s90, v235
	v_add_u32_e32 v83, s90, v236
	v_add_u32_e32 v99, s90, v237
	v_add_u32_e32 v253, s90, v238
	v_add_u32_e32 v254, s90, v100
	v_add_u32_e32 v255, s90, v149
	v_med3_i32 v80, v80, 0, s99
	v_med3_i32 v83, v83, 0, s99
	v_med3_i32 v99, v99, 0, s99
	v_med3_i32 v253, v253, 0, s99
	v_med3_i32 v254, v254, 0, s99
	v_med3_i32 v255, v255, 0, s99
	v_mad_u32_u24 v80, v80, s100, v252
	v_mad_u32_u24 v83, v83, s100, v252
	v_mad_u32_u24 v99, v99, s100, v252
	v_mad_u32_u24 v253, v253, s100, v252
	v_mad_u32_u24 v254, v254, s100, v153
	v_mad_u32_u24 v255, v255, s100, v153
	global_load_dwordx4 v[116:119], v80, s[82:83]
	global_load_dwordx4 v[120:123], v83, s[82:83]
	global_load_dwordx4 v[124:127], v99, s[82:83]
	global_load_dwordx4 v[128:131], v253, s[82:83]
	global_load_dwordx4 v[132:135], v254, s[82:83] offset:768
	global_load_dwordx4 v[136:139], v255, s[82:83] offset:768
	global_load_dwordx4 v[140:143], v254, s[82:83] offset:832
	global_load_dwordx4 v[144:147], v255, s[82:83] offset:832
	ds_read_b64_tr_b16 v[72:73], v231
	ds_read_b64_tr_b16 v[74:75], v231 offset:512
	ds_read_b64_tr_b16 v[76:77], v231 offset:2048
	ds_read_b64_tr_b16 v[78:79], v231 offset:2560
	ds_read_b64_tr_b16 v[220:221], v231 offset:1024
	ds_read_b64_tr_b16 v[222:223], v231 offset:1536
	ds_read_b64_tr_b16 v[224:225], v231 offset:3072
	ds_read_b64_tr_b16 v[226:227], v231 offset:3584
	s_waitcnt vmcnt(8)
	ds_write_b128 v247, v[156:159]
	ds_write_b128 v247, v[160:163] offset:1024
	ds_write_b128 v111, v[164:167] offset:2048
	ds_write_b128 v111, v[168:171] offset:3072
	ds_read_b128 v[156:159], v248
	ds_read_b128 v[160:163], v249
	ds_read_b128 v[164:167], v250
	ds_read_b128 v[168:171], v251
	ds_write_b128 v112, v[172:175]
	ds_write_b128 v112, v[176:179] offset:1024
	ds_write_b128 v112, v[180:183] offset:2048
	ds_write_b128 v112, v[184:187] offset:3072
	v_exp_f32_e32 v32, v32
	v_exp_f32_e32 v33, v33
	v_exp_f32_e32 v34, v34
	v_exp_f32_e32 v35, v35
	v_exp_f32_e32 v36, v36
	v_exp_f32_e32 v37, v37
	s_waitcnt lgkmcnt(4)
	v_mfma_f32_32x32x16_bf16 v[188:203], v[156:159], v[48:51], v[188:203]
	v_exp_f32_e32 v38, v38
	v_exp_f32_e32 v39, v39
	v_mfma_f32_32x32x16_bf16 v[188:203], v[160:163], v[52:55], v[188:203]
	v_exp_f32_e32 v40, v40
	v_exp_f32_e32 v41, v41
	v_exp_f32_e32 v42, v42
	v_mfma_f32_32x32x16_bf16 v[188:203], v[164:167], v[56:59], v[188:203]
	v_exp_f32_e32 v43, v43
	v_exp_f32_e32 v44, v44
	v_mfma_f32_32x32x16_bf16 v[188:203], v[168:171], v[60:63], v[188:203]
	v_exp_f32_e32 v45, v45
	v_exp_f32_e32 v46, v46
	v_exp_f32_e32 v47, v47
	s_add_i32 s90, s76, 192
	v_add_u32_e32 v84, s90, v107
	v_add_u32_e32 v85, 0, v84
	v_add_u32_e32 v86, 1, v84
	v_add_u32_e32 v87, 2, v84
	v_add_u32_e32 v88, 3, v84
	v_cmp_gt_u32_e64 s[30:31], s98, v85
	v_cmp_gt_u32_e64 s[36:37], s98, v86
	v_cmp_gt_u32_e64 s[78:79], s98, v87
	v_cmp_gt_u32_e64 s[50:51], s98, v88
	v_cndmask_b32_e64 v32, 0, v32, s[30:31]
	v_add_u32_e32 v85, 8, v84
	v_cmp_gt_u32_e64 s[30:31], s98, v85
	v_cndmask_b32_e64 v33, 0, v33, s[36:37]
	v_add_u32_e32 v86, 9, v84
	v_cmp_gt_u32_e64 s[36:37], s98, v86
	v_cndmask_b32_e64 v34, 0, v34, s[78:79]
	v_add_u32_e32 v87, 10, v84
	v_cmp_gt_u32_e64 s[78:79], s98, v87
	v_cndmask_b32_e64 v35, 0, v35, s[50:51]
	v_add_u32_e32 v88, 11, v84
	v_cmp_gt_u32_e64 s[50:51], s98, v88
	v_cndmask_b32_e64 v36, 0, v36, s[30:31]
	v_add_u32_e32 v85, 16, v84
	v_cmp_gt_u32_e64 s[30:31], s98, v85
	v_cndmask_b32_e64 v37, 0, v37, s[36:37]
	v_add_u32_e32 v86, 17, v84
	v_cmp_gt_u32_e64 s[36:37], s98, v86
	v_cndmask_b32_e64 v38, 0, v38, s[78:79]
	v_add_u32_e32 v87, 18, v84
	v_cmp_gt_u32_e64 s[78:79], s98, v87
	v_cndmask_b32_e64 v39, 0, v39, s[50:51]
	v_add_u32_e32 v88, 19, v84
	v_cmp_gt_u32_e64 s[50:51], s98, v88
	v_cndmask_b32_e64 v40, 0, v40, s[30:31]
	v_add_u32_e32 v85, 24, v84
	v_cmp_gt_u32_e64 s[30:31], s98, v85
	v_cndmask_b32_e64 v41, 0, v41, s[36:37]
	v_add_u32_e32 v86, 25, v84
	v_cmp_gt_u32_e64 s[36:37], s98, v86
	v_cndmask_b32_e64 v42, 0, v42, s[78:79]
	v_add_u32_e32 v87, 26, v84
	v_cmp_gt_u32_e64 s[78:79], s98, v87
	v_cndmask_b32_e64 v43, 0, v43, s[50:51]
	v_add_u32_e32 v88, 27, v84
	v_cmp_gt_u32_e64 s[50:51], s98, v88
	v_nop
	v_cndmask_b32_e64 v44, 0, v44, s[30:31]
	v_cndmask_b32_e64 v45, 0, v45, s[36:37]
	v_cndmask_b32_e64 v46, 0, v46, s[78:79]
	v_cndmask_b32_e64 v47, 0, v47, s[50:51]
	v_cvt_pk_bf16_f32 v64, v32, v33
	v_cvt_pk_bf16_f32 v65, v34, v35
	v_cvt_pk_bf16_f32 v66, v36, v37
	v_cvt_pk_bf16_f32 v67, v38, v39
	v_cvt_pk_bf16_f32 v68, v40, v41
	v_cvt_pk_bf16_f32 v69, v42, v43
	v_cvt_pk_bf16_f32 v70, v44, v45
	v_cvt_pk_bf16_f32 v71, v46, v47
	v_pk_add_f32 v[232:233], v[232:233], v[32:33]
	v_pk_add_f32 v[232:233], v[232:233], v[34:35]
	v_pk_add_f32 v[232:233], v[232:233], v[36:37]
	v_pk_add_f32 v[232:233], v[232:233], v[38:39]
	v_pk_add_f32 v[232:233], v[232:233], v[40:41]
	v_pk_add_f32 v[232:233], v[232:233], v[42:43]
	v_pk_add_f32 v[232:233], v[232:233], v[44:45]
	v_pk_add_f32 v[232:233], v[232:233], v[46:47]
	ds_read2_b32 v[32:33], v115 offset0:102 offset1:103
	ds_read2_b32 v[34:35], v115 offset0:104 offset1:105
	ds_read2_b32 v[36:37], v115 offset0:110 offset1:111
	ds_read2_b32 v[38:39], v115 offset0:112 offset1:113
	ds_read2_b32 v[40:41], v115 offset0:119 offset1:120
	ds_read2_b32 v[42:43], v115 offset0:121 offset1:122
	ds_read2_b32 v[44:45], v115 offset0:127 offset1:128
	ds_read2_b32 v[46:47], v115 offset0:129 offset1:130
	v_mfma_f32_32x32x16_bf16 v[0:15], v[64:67], v[72:75], v[0:15]
	v_mfma_f32_32x32x16_bf16 v[16:31], v[64:67], v[76:79], v[16:31]
	v_mfma_f32_32x32x16_bf16 v[0:15], v[68:71], v[220:223], v[0:15]
	v_mfma_f32_32x32x16_bf16 v[16:31], v[68:71], v[224:227], v[16:31]
	s_add_i32 s90, s76, 288
	v_add_u32_e32 v80, s90, v235
	v_add_u32_e32 v83, s90, v236
	v_add_u32_e32 v99, s90, v237
	v_add_u32_e32 v253, s90, v238
	v_add_u32_e32 v254, s90, v100
	v_add_u32_e32 v255, s90, v149
	v_med3_i32 v80, v80, 0, s99
	v_med3_i32 v83, v83, 0, s99
	v_med3_i32 v99, v99, 0, s99
	v_med3_i32 v253, v253, 0, s99
	v_med3_i32 v254, v254, 0, s99
	v_med3_i32 v255, v255, 0, s99
	v_mad_u32_u24 v80, v80, s100, v252
	v_mad_u32_u24 v83, v83, s100, v252
	v_mad_u32_u24 v99, v99, s100, v252
	v_mad_u32_u24 v253, v253, s100, v252
	v_mad_u32_u24 v254, v254, s100, v153
	v_mad_u32_u24 v255, v255, s100, v153
	global_load_dwordx4 v[156:159], v80, s[82:83]
	global_load_dwordx4 v[160:163], v83, s[82:83]
	global_load_dwordx4 v[164:167], v99, s[82:83]
	global_load_dwordx4 v[168:171], v253, s[82:83]
	global_load_dwordx4 v[172:175], v254, s[82:83] offset:768
	global_load_dwordx4 v[176:179], v255, s[82:83] offset:768
	global_load_dwordx4 v[180:183], v254, s[82:83] offset:832
	global_load_dwordx4 v[184:187], v255, s[82:83] offset:832
	ds_read_b64_tr_b16 v[72:73], v231
	ds_read_b64_tr_b16 v[74:75], v231 offset:512
	ds_read_b64_tr_b16 v[76:77], v231 offset:2048
	ds_read_b64_tr_b16 v[78:79], v231 offset:2560
	ds_read_b64_tr_b16 v[220:221], v231 offset:1024
	ds_read_b64_tr_b16 v[222:223], v231 offset:1536
	ds_read_b64_tr_b16 v[224:225], v231 offset:3072
	ds_read_b64_tr_b16 v[226:227], v231 offset:3584
	s_waitcnt vmcnt(8)
	ds_write_b128 v247, v[116:119]
	ds_write_b128 v247, v[120:123] offset:1024
	ds_write_b128 v111, v[124:127] offset:2048
	ds_write_b128 v111, v[128:131] offset:3072
	ds_read_b128 v[116:119], v248
	ds_read_b128 v[120:123], v249
	ds_read_b128 v[124:127], v250
	ds_read_b128 v[128:131], v251
	ds_write_b128 v112, v[132:135]
	ds_write_b128 v112, v[136:139] offset:1024
	ds_write_b128 v112, v[140:143] offset:2048
	ds_write_b128 v112, v[144:147] offset:3072
	v_exp_f32_e32 v188, v188
	v_exp_f32_e32 v189, v189
	v_exp_f32_e32 v190, v190
	v_exp_f32_e32 v191, v191
	v_exp_f32_e32 v192, v192
	v_exp_f32_e32 v193, v193
	s_waitcnt lgkmcnt(4)
	v_mfma_f32_32x32x16_bf16 v[32:47], v[116:119], v[48:51], v[32:47]
	v_exp_f32_e32 v194, v194
	v_exp_f32_e32 v195, v195
	v_mfma_f32_32x32x16_bf16 v[32:47], v[120:123], v[52:55], v[32:47]
	v_exp_f32_e32 v196, v196
	v_exp_f32_e32 v197, v197
	v_exp_f32_e32 v198, v198
	v_mfma_f32_32x32x16_bf16 v[32:47], v[124:127], v[56:59], v[32:47]
	v_exp_f32_e32 v199, v199
	v_exp_f32_e32 v200, v200
	v_mfma_f32_32x32x16_bf16 v[32:47], v[128:131], v[60:63], v[32:47]
	v_exp_f32_e32 v201, v201
	v_exp_f32_e32 v202, v202
	v_exp_f32_e32 v203, v203
	s_add_i32 s90, s76, 224
	v_add_u32_e32 v84, s90, v107
	v_add_u32_e32 v85, 0, v84
	v_add_u32_e32 v86, 1, v84
	v_add_u32_e32 v87, 2, v84
	v_add_u32_e32 v88, 3, v84
	v_cmp_gt_u32_e64 s[30:31], s98, v85
	v_cmp_gt_u32_e64 s[36:37], s98, v86
	v_cmp_gt_u32_e64 s[78:79], s98, v87
	v_cmp_gt_u32_e64 s[50:51], s98, v88
	v_cndmask_b32_e64 v188, 0, v188, s[30:31]
	v_add_u32_e32 v85, 8, v84
	v_cmp_gt_u32_e64 s[30:31], s98, v85
	v_cndmask_b32_e64 v189, 0, v189, s[36:37]
	v_add_u32_e32 v86, 9, v84
	v_cmp_gt_u32_e64 s[36:37], s98, v86
	v_cndmask_b32_e64 v190, 0, v190, s[78:79]
	v_add_u32_e32 v87, 10, v84
	v_cmp_gt_u32_e64 s[78:79], s98, v87
	v_cndmask_b32_e64 v191, 0, v191, s[50:51]
	v_add_u32_e32 v88, 11, v84
	v_cmp_gt_u32_e64 s[50:51], s98, v88
	v_cndmask_b32_e64 v192, 0, v192, s[30:31]
	v_add_u32_e32 v85, 16, v84
	v_cmp_gt_u32_e64 s[30:31], s98, v85
	v_cndmask_b32_e64 v193, 0, v193, s[36:37]
	v_add_u32_e32 v86, 17, v84
	v_cmp_gt_u32_e64 s[36:37], s98, v86
	v_cndmask_b32_e64 v194, 0, v194, s[78:79]
	v_add_u32_e32 v87, 18, v84
	v_cmp_gt_u32_e64 s[78:79], s98, v87
	v_cndmask_b32_e64 v195, 0, v195, s[50:51]
	v_add_u32_e32 v88, 19, v84
	v_cmp_gt_u32_e64 s[50:51], s98, v88
	v_cndmask_b32_e64 v196, 0, v196, s[30:31]
	v_add_u32_e32 v85, 24, v84
	v_cmp_gt_u32_e64 s[30:31], s98, v85
	v_cndmask_b32_e64 v197, 0, v197, s[36:37]
	v_add_u32_e32 v86, 25, v84
	v_cmp_gt_u32_e64 s[36:37], s98, v86
	v_cndmask_b32_e64 v198, 0, v198, s[78:79]
	v_add_u32_e32 v87, 26, v84
	v_cmp_gt_u32_e64 s[78:79], s98, v87
	v_cndmask_b32_e64 v199, 0, v199, s[50:51]
	v_add_u32_e32 v88, 27, v84
	v_cmp_gt_u32_e64 s[50:51], s98, v88
	v_nop
	v_cndmask_b32_e64 v200, 0, v200, s[30:31]
	v_cndmask_b32_e64 v201, 0, v201, s[36:37]
	v_cndmask_b32_e64 v202, 0, v202, s[78:79]
	v_cndmask_b32_e64 v203, 0, v203, s[50:51]
	v_cvt_pk_bf16_f32 v64, v188, v189
	v_cvt_pk_bf16_f32 v65, v190, v191
	v_cvt_pk_bf16_f32 v66, v192, v193
	v_cvt_pk_bf16_f32 v67, v194, v195
	v_cvt_pk_bf16_f32 v68, v196, v197
	v_cvt_pk_bf16_f32 v69, v198, v199
	v_cvt_pk_bf16_f32 v70, v200, v201
	v_cvt_pk_bf16_f32 v71, v202, v203
	v_pk_add_f32 v[232:233], v[232:233], v[188:189]
	v_pk_add_f32 v[232:233], v[232:233], v[190:191]
	v_pk_add_f32 v[232:233], v[232:233], v[192:193]
	v_pk_add_f32 v[232:233], v[232:233], v[194:195]
	v_pk_add_f32 v[232:233], v[232:233], v[196:197]
	v_pk_add_f32 v[232:233], v[232:233], v[198:199]
	v_pk_add_f32 v[232:233], v[232:233], v[200:201]
	v_pk_add_f32 v[232:233], v[232:233], v[202:203]
	ds_read2_b32 v[188:189], v115 offset0:136 offset1:137
	ds_read2_b32 v[190:191], v115 offset0:138 offset1:139
	ds_read2_b32 v[192:193], v115 offset0:144 offset1:145
	ds_read2_b32 v[194:195], v115 offset0:146 offset1:147
	ds_read2_b32 v[196:197], v115 offset0:153 offset1:154
	ds_read2_b32 v[198:199], v115 offset0:155 offset1:156
	ds_read2_b32 v[200:201], v115 offset0:161 offset1:162
	ds_read2_b32 v[202:203], v115 offset0:163 offset1:164
	v_mfma_f32_32x32x16_bf16 v[0:15], v[64:67], v[72:75], v[0:15]
	v_mfma_f32_32x32x16_bf16 v[16:31], v[64:67], v[76:79], v[16:31]
	v_mfma_f32_32x32x16_bf16 v[0:15], v[68:71], v[220:223], v[0:15]
	v_mfma_f32_32x32x16_bf16 v[16:31], v[68:71], v[224:227], v[16:31]
	s_add_i32 s90, s76, 320
	v_add_u32_e32 v80, s90, v235
	v_add_u32_e32 v83, s90, v236
	v_add_u32_e32 v99, s90, v237
	v_add_u32_e32 v253, s90, v238
	v_add_u32_e32 v254, s90, v100
	v_add_u32_e32 v255, s90, v149
	v_med3_i32 v80, v80, 0, s99
	v_med3_i32 v83, v83, 0, s99
	v_med3_i32 v99, v99, 0, s99
	v_med3_i32 v253, v253, 0, s99
	v_med3_i32 v254, v254, 0, s99
	v_med3_i32 v255, v255, 0, s99
	v_mad_u32_u24 v80, v80, s100, v252
	v_mad_u32_u24 v83, v83, s100, v252
	v_mad_u32_u24 v99, v99, s100, v252
	v_mad_u32_u24 v253, v253, s100, v252
	v_mad_u32_u24 v254, v254, s100, v153
	v_mad_u32_u24 v255, v255, s100, v153
	global_load_dwordx4 v[116:119], v80, s[82:83]
	global_load_dwordx4 v[120:123], v83, s[82:83]
	global_load_dwordx4 v[124:127], v99, s[82:83]
	global_load_dwordx4 v[128:131], v253, s[82:83]
	global_load_dwordx4 v[132:135], v254, s[82:83] offset:768
	global_load_dwordx4 v[136:139], v255, s[82:83] offset:768
	global_load_dwordx4 v[140:143], v254, s[82:83] offset:832
	global_load_dwordx4 v[144:147], v255, s[82:83] offset:832
	ds_read_b64_tr_b16 v[72:73], v231
	ds_read_b64_tr_b16 v[74:75], v231 offset:512
	ds_read_b64_tr_b16 v[76:77], v231 offset:2048
	ds_read_b64_tr_b16 v[78:79], v231 offset:2560
	ds_read_b64_tr_b16 v[220:221], v231 offset:1024
	ds_read_b64_tr_b16 v[222:223], v231 offset:1536
	ds_read_b64_tr_b16 v[224:225], v231 offset:3072
	ds_read_b64_tr_b16 v[226:227], v231 offset:3584
	s_waitcnt vmcnt(8)
	ds_write_b128 v247, v[156:159]
	ds_write_b128 v247, v[160:163] offset:1024
	ds_write_b128 v111, v[164:167] offset:2048
	ds_write_b128 v111, v[168:171] offset:3072
	ds_read_b128 v[156:159], v248
	ds_read_b128 v[160:163], v249
	ds_read_b128 v[164:167], v250
	ds_read_b128 v[168:171], v251
	ds_write_b128 v112, v[172:175]
	ds_write_b128 v112, v[176:179] offset:1024
	ds_write_b128 v112, v[180:183] offset:2048
	ds_write_b128 v112, v[184:187] offset:3072
	v_exp_f32_e32 v32, v32
	v_exp_f32_e32 v33, v33
	v_exp_f32_e32 v34, v34
	v_exp_f32_e32 v35, v35
	v_exp_f32_e32 v36, v36
	v_exp_f32_e32 v37, v37
	s_waitcnt lgkmcnt(4)
	v_mfma_f32_32x32x16_bf16 v[188:203], v[156:159], v[48:51], v[188:203]
	v_exp_f32_e32 v38, v38
	v_exp_f32_e32 v39, v39
	v_mfma_f32_32x32x16_bf16 v[188:203], v[160:163], v[52:55], v[188:203]
	v_exp_f32_e32 v40, v40
	v_exp_f32_e32 v41, v41
	v_exp_f32_e32 v42, v42
	v_mfma_f32_32x32x16_bf16 v[188:203], v[164:167], v[56:59], v[188:203]
	v_exp_f32_e32 v43, v43
	v_exp_f32_e32 v44, v44
	v_mfma_f32_32x32x16_bf16 v[188:203], v[168:171], v[60:63], v[188:203]
	v_exp_f32_e32 v45, v45
	v_exp_f32_e32 v46, v46
	v_exp_f32_e32 v47, v47
	s_add_i32 s90, s76, 256
	v_add_u32_e32 v84, s90, v107
	v_add_u32_e32 v85, 0, v84
	v_add_u32_e32 v86, 1, v84
	v_add_u32_e32 v87, 2, v84
	v_add_u32_e32 v88, 3, v84
	v_cmp_gt_u32_e64 s[30:31], s98, v85
	v_cmp_gt_u32_e64 s[36:37], s98, v86
	v_cmp_gt_u32_e64 s[78:79], s98, v87
	v_cmp_gt_u32_e64 s[50:51], s98, v88
	v_cndmask_b32_e64 v32, 0, v32, s[30:31]
	v_add_u32_e32 v85, 8, v84
	v_cmp_gt_u32_e64 s[30:31], s98, v85
	v_cndmask_b32_e64 v33, 0, v33, s[36:37]
	v_add_u32_e32 v86, 9, v84
	v_cmp_gt_u32_e64 s[36:37], s98, v86
	v_cndmask_b32_e64 v34, 0, v34, s[78:79]
	v_add_u32_e32 v87, 10, v84
	v_cmp_gt_u32_e64 s[78:79], s98, v87
	v_cndmask_b32_e64 v35, 0, v35, s[50:51]
	v_add_u32_e32 v88, 11, v84
	v_cmp_gt_u32_e64 s[50:51], s98, v88
	v_cndmask_b32_e64 v36, 0, v36, s[30:31]
	v_add_u32_e32 v85, 16, v84
	v_cmp_gt_u32_e64 s[30:31], s98, v85
	v_cndmask_b32_e64 v37, 0, v37, s[36:37]
	v_add_u32_e32 v86, 17, v84
	v_cmp_gt_u32_e64 s[36:37], s98, v86
	v_cndmask_b32_e64 v38, 0, v38, s[78:79]
	v_add_u32_e32 v87, 18, v84
	v_cmp_gt_u32_e64 s[78:79], s98, v87
	v_cndmask_b32_e64 v39, 0, v39, s[50:51]
	v_add_u32_e32 v88, 19, v84
	v_cmp_gt_u32_e64 s[50:51], s98, v88
	v_cndmask_b32_e64 v40, 0, v40, s[30:31]
	v_add_u32_e32 v85, 24, v84
	v_cmp_gt_u32_e64 s[30:31], s98, v85
	v_cndmask_b32_e64 v41, 0, v41, s[36:37]
	v_add_u32_e32 v86, 25, v84
	v_cmp_gt_u32_e64 s[36:37], s98, v86
	v_cndmask_b32_e64 v42, 0, v42, s[78:79]
	v_add_u32_e32 v87, 26, v84
	v_cmp_gt_u32_e64 s[78:79], s98, v87
	v_cndmask_b32_e64 v43, 0, v43, s[50:51]
	v_add_u32_e32 v88, 27, v84
	v_cmp_gt_u32_e64 s[50:51], s98, v88
	v_nop
	v_cndmask_b32_e64 v44, 0, v44, s[30:31]
	v_cndmask_b32_e64 v45, 0, v45, s[36:37]
	v_cndmask_b32_e64 v46, 0, v46, s[78:79]
	v_cndmask_b32_e64 v47, 0, v47, s[50:51]
	v_cvt_pk_bf16_f32 v64, v32, v33
	v_cvt_pk_bf16_f32 v65, v34, v35
	v_cvt_pk_bf16_f32 v66, v36, v37
	v_cvt_pk_bf16_f32 v67, v38, v39
	v_cvt_pk_bf16_f32 v68, v40, v41
	v_cvt_pk_bf16_f32 v69, v42, v43
	v_cvt_pk_bf16_f32 v70, v44, v45
	v_cvt_pk_bf16_f32 v71, v46, v47
	v_pk_add_f32 v[232:233], v[232:233], v[32:33]
	v_pk_add_f32 v[232:233], v[232:233], v[34:35]
	v_pk_add_f32 v[232:233], v[232:233], v[36:37]
	v_pk_add_f32 v[232:233], v[232:233], v[38:39]
	v_pk_add_f32 v[232:233], v[232:233], v[40:41]
	v_pk_add_f32 v[232:233], v[232:233], v[42:43]
	v_pk_add_f32 v[232:233], v[232:233], v[44:45]
	v_pk_add_f32 v[232:233], v[232:233], v[46:47]
	ds_read2_b32 v[32:33], v115 offset0:170 offset1:171
	ds_read2_b32 v[34:35], v115 offset0:172 offset1:173
	ds_read2_b32 v[36:37], v115 offset0:178 offset1:179
	ds_read2_b32 v[38:39], v115 offset0:180 offset1:181
	ds_read2_b32 v[40:41], v115 offset0:187 offset1:188
	ds_read2_b32 v[42:43], v115 offset0:189 offset1:190
	ds_read2_b32 v[44:45], v115 offset0:195 offset1:196
	ds_read2_b32 v[46:47], v115 offset0:197 offset1:198
	v_mfma_f32_32x32x16_bf16 v[0:15], v[64:67], v[72:75], v[0:15]
	v_mfma_f32_32x32x16_bf16 v[16:31], v[64:67], v[76:79], v[16:31]
	v_mfma_f32_32x32x16_bf16 v[0:15], v[68:71], v[220:223], v[0:15]
	v_mfma_f32_32x32x16_bf16 v[16:31], v[68:71], v[224:227], v[16:31]
	s_add_i32 s90, s76, 352
	v_add_u32_e32 v80, s90, v235
	v_add_u32_e32 v83, s90, v236
	v_add_u32_e32 v99, s90, v237
	v_add_u32_e32 v253, s90, v238
	v_add_u32_e32 v254, s90, v100
	v_add_u32_e32 v255, s90, v149
	v_med3_i32 v80, v80, 0, s99
	v_med3_i32 v83, v83, 0, s99
	v_med3_i32 v99, v99, 0, s99
	v_med3_i32 v253, v253, 0, s99
	v_med3_i32 v254, v254, 0, s99
	v_med3_i32 v255, v255, 0, s99
	v_mad_u32_u24 v80, v80, s100, v252
	v_mad_u32_u24 v83, v83, s100, v252
	v_mad_u32_u24 v99, v99, s100, v252
	v_mad_u32_u24 v253, v253, s100, v252
	v_mad_u32_u24 v254, v254, s100, v153
	v_mad_u32_u24 v255, v255, s100, v153
	global_load_dwordx4 v[156:159], v80, s[82:83]
	global_load_dwordx4 v[160:163], v83, s[82:83]
	global_load_dwordx4 v[164:167], v99, s[82:83]
	global_load_dwordx4 v[168:171], v253, s[82:83]
	global_load_dwordx4 v[172:175], v254, s[82:83] offset:768
	global_load_dwordx4 v[176:179], v255, s[82:83] offset:768
	global_load_dwordx4 v[180:183], v254, s[82:83] offset:832
	global_load_dwordx4 v[184:187], v255, s[82:83] offset:832
	ds_read_b64_tr_b16 v[72:73], v231
	ds_read_b64_tr_b16 v[74:75], v231 offset:512
	ds_read_b64_tr_b16 v[76:77], v231 offset:2048
	ds_read_b64_tr_b16 v[78:79], v231 offset:2560
	ds_read_b64_tr_b16 v[220:221], v231 offset:1024
	ds_read_b64_tr_b16 v[222:223], v231 offset:1536
	ds_read_b64_tr_b16 v[224:225], v231 offset:3072
	ds_read_b64_tr_b16 v[226:227], v231 offset:3584
	s_waitcnt vmcnt(8)
	ds_write_b128 v247, v[116:119]
	ds_write_b128 v247, v[120:123] offset:1024
	ds_write_b128 v111, v[124:127] offset:2048
	ds_write_b128 v111, v[128:131] offset:3072
	ds_read_b128 v[116:119], v248
	ds_read_b128 v[120:123], v249
	ds_read_b128 v[124:127], v250
	ds_read_b128 v[128:131], v251
	ds_write_b128 v112, v[132:135]
	ds_write_b128 v112, v[136:139] offset:1024
	ds_write_b128 v112, v[140:143] offset:2048
	ds_write_b128 v112, v[144:147] offset:3072
	v_exp_f32_e32 v188, v188
	v_exp_f32_e32 v189, v189
	v_exp_f32_e32 v190, v190
	v_exp_f32_e32 v191, v191
	v_exp_f32_e32 v192, v192
	v_exp_f32_e32 v193, v193
	s_waitcnt lgkmcnt(4)
	v_mfma_f32_32x32x16_bf16 v[32:47], v[116:119], v[48:51], v[32:47]
	v_exp_f32_e32 v194, v194
	v_exp_f32_e32 v195, v195
	v_mfma_f32_32x32x16_bf16 v[32:47], v[120:123], v[52:55], v[32:47]
	v_exp_f32_e32 v196, v196
	v_exp_f32_e32 v197, v197
	v_exp_f32_e32 v198, v198
	v_mfma_f32_32x32x16_bf16 v[32:47], v[124:127], v[56:59], v[32:47]
	v_exp_f32_e32 v199, v199
	v_exp_f32_e32 v200, v200
	v_mfma_f32_32x32x16_bf16 v[32:47], v[128:131], v[60:63], v[32:47]
	v_exp_f32_e32 v201, v201
	v_exp_f32_e32 v202, v202
	v_exp_f32_e32 v203, v203
	s_add_i32 s90, s76, 288
	v_add_u32_e32 v84, s90, v107
	v_add_u32_e32 v85, 0, v84
	v_add_u32_e32 v86, 1, v84
	v_add_u32_e32 v87, 2, v84
	v_add_u32_e32 v88, 3, v84
	v_cmp_gt_u32_e64 s[30:31], s98, v85
	v_cmp_gt_u32_e64 s[36:37], s98, v86
	v_cmp_gt_u32_e64 s[78:79], s98, v87
	v_cmp_gt_u32_e64 s[50:51], s98, v88
	v_cndmask_b32_e64 v188, 0, v188, s[30:31]
	v_add_u32_e32 v85, 8, v84
	v_cmp_gt_u32_e64 s[30:31], s98, v85
	v_cndmask_b32_e64 v189, 0, v189, s[36:37]
	v_add_u32_e32 v86, 9, v84
	v_cmp_gt_u32_e64 s[36:37], s98, v86
	v_cndmask_b32_e64 v190, 0, v190, s[78:79]
	v_add_u32_e32 v87, 10, v84
	v_cmp_gt_u32_e64 s[78:79], s98, v87
	v_cndmask_b32_e64 v191, 0, v191, s[50:51]
	v_add_u32_e32 v88, 11, v84
	v_cmp_gt_u32_e64 s[50:51], s98, v88
	v_cndmask_b32_e64 v192, 0, v192, s[30:31]
	v_add_u32_e32 v85, 16, v84
	v_cmp_gt_u32_e64 s[30:31], s98, v85
	v_cndmask_b32_e64 v193, 0, v193, s[36:37]
	v_add_u32_e32 v86, 17, v84
	v_cmp_gt_u32_e64 s[36:37], s98, v86
	v_cndmask_b32_e64 v194, 0, v194, s[78:79]
	v_add_u32_e32 v87, 18, v84
	v_cmp_gt_u32_e64 s[78:79], s98, v87
	v_cndmask_b32_e64 v195, 0, v195, s[50:51]
	v_add_u32_e32 v88, 19, v84
	v_cmp_gt_u32_e64 s[50:51], s98, v88
	v_cndmask_b32_e64 v196, 0, v196, s[30:31]
	v_add_u32_e32 v85, 24, v84
	v_cmp_gt_u32_e64 s[30:31], s98, v85
	v_cndmask_b32_e64 v197, 0, v197, s[36:37]
	v_add_u32_e32 v86, 25, v84
	v_cmp_gt_u32_e64 s[36:37], s98, v86
	v_cndmask_b32_e64 v198, 0, v198, s[78:79]
	v_add_u32_e32 v87, 26, v84
	v_cmp_gt_u32_e64 s[78:79], s98, v87
	v_cndmask_b32_e64 v199, 0, v199, s[50:51]
	v_add_u32_e32 v88, 27, v84
	v_cmp_gt_u32_e64 s[50:51], s98, v88
	v_nop
	v_cndmask_b32_e64 v200, 0, v200, s[30:31]
	v_cndmask_b32_e64 v201, 0, v201, s[36:37]
	v_cndmask_b32_e64 v202, 0, v202, s[78:79]
	v_cndmask_b32_e64 v203, 0, v203, s[50:51]
	v_cvt_pk_bf16_f32 v64, v188, v189
	v_cvt_pk_bf16_f32 v65, v190, v191
	v_cvt_pk_bf16_f32 v66, v192, v193
	v_cvt_pk_bf16_f32 v67, v194, v195
	v_cvt_pk_bf16_f32 v68, v196, v197
	v_cvt_pk_bf16_f32 v69, v198, v199
	v_cvt_pk_bf16_f32 v70, v200, v201
	v_cvt_pk_bf16_f32 v71, v202, v203
	v_pk_add_f32 v[232:233], v[232:233], v[188:189]
	v_pk_add_f32 v[232:233], v[232:233], v[190:191]
	v_pk_add_f32 v[232:233], v[232:233], v[192:193]
	v_pk_add_f32 v[232:233], v[232:233], v[194:195]
	v_pk_add_f32 v[232:233], v[232:233], v[196:197]
	v_pk_add_f32 v[232:233], v[232:233], v[198:199]
	v_pk_add_f32 v[232:233], v[232:233], v[200:201]
	v_pk_add_f32 v[232:233], v[232:233], v[202:203]
	ds_read2_b32 v[188:189], v115 offset0:204 offset1:205
	ds_read2_b32 v[190:191], v115 offset0:206 offset1:207
	ds_read2_b32 v[192:193], v115 offset0:212 offset1:213
	ds_read2_b32 v[194:195], v115 offset0:214 offset1:215
	ds_read2_b32 v[196:197], v115 offset0:221 offset1:222
	ds_read2_b32 v[198:199], v115 offset0:223 offset1:224
	ds_read2_b32 v[200:201], v115 offset0:229 offset1:230
	ds_read2_b32 v[202:203], v115 offset0:231 offset1:232
	v_mfma_f32_32x32x16_bf16 v[0:15], v[64:67], v[72:75], v[0:15]
	v_mfma_f32_32x32x16_bf16 v[16:31], v[64:67], v[76:79], v[16:31]
	v_mfma_f32_32x32x16_bf16 v[0:15], v[68:71], v[220:223], v[0:15]
	v_mfma_f32_32x32x16_bf16 v[16:31], v[68:71], v[224:227], v[16:31]
	s_add_i32 s90, s76, 384
	v_add_u32_e32 v80, s90, v235
	v_add_u32_e32 v83, s90, v236
	v_add_u32_e32 v99, s90, v237
	v_add_u32_e32 v253, s90, v238
	v_add_u32_e32 v254, s90, v100
	v_add_u32_e32 v255, s90, v149
	v_med3_i32 v80, v80, 0, s99
	v_med3_i32 v83, v83, 0, s99
	v_med3_i32 v99, v99, 0, s99
	v_med3_i32 v253, v253, 0, s99
	v_med3_i32 v254, v254, 0, s99
	v_med3_i32 v255, v255, 0, s99
	v_mad_u32_u24 v80, v80, s100, v252
	v_mad_u32_u24 v83, v83, s100, v252
	v_mad_u32_u24 v99, v99, s100, v252
	v_mad_u32_u24 v253, v253, s100, v252
	v_mad_u32_u24 v254, v254, s100, v153
	v_mad_u32_u24 v255, v255, s100, v153
	global_load_dwordx4 v[116:119], v80, s[82:83]
	global_load_dwordx4 v[120:123], v83, s[82:83]
	global_load_dwordx4 v[124:127], v99, s[82:83]
	global_load_dwordx4 v[128:131], v253, s[82:83]
	global_load_dwordx4 v[132:135], v254, s[82:83] offset:768
	global_load_dwordx4 v[136:139], v255, s[82:83] offset:768
	global_load_dwordx4 v[140:143], v254, s[82:83] offset:832
	global_load_dwordx4 v[144:147], v255, s[82:83] offset:832
	ds_read_b64_tr_b16 v[72:73], v231
	ds_read_b64_tr_b16 v[74:75], v231 offset:512
	ds_read_b64_tr_b16 v[76:77], v231 offset:2048
	ds_read_b64_tr_b16 v[78:79], v231 offset:2560
	ds_read_b64_tr_b16 v[220:221], v231 offset:1024
	ds_read_b64_tr_b16 v[222:223], v231 offset:1536
	ds_read_b64_tr_b16 v[224:225], v231 offset:3072
	ds_read_b64_tr_b16 v[226:227], v231 offset:3584
	s_waitcnt vmcnt(8)
	ds_write_b128 v247, v[156:159]
	ds_write_b128 v247, v[160:163] offset:1024
	ds_write_b128 v111, v[164:167] offset:2048
	ds_write_b128 v111, v[168:171] offset:3072
	ds_read_b128 v[156:159], v248
	ds_read_b128 v[160:163], v249
	ds_read_b128 v[164:167], v250
	ds_read_b128 v[168:171], v251
	ds_write_b128 v112, v[172:175]
	ds_write_b128 v112, v[176:179] offset:1024
	ds_write_b128 v112, v[180:183] offset:2048
	ds_write_b128 v112, v[184:187] offset:3072
	v_exp_f32_e32 v32, v32
	v_exp_f32_e32 v33, v33
	v_exp_f32_e32 v34, v34
	v_exp_f32_e32 v35, v35
	v_exp_f32_e32 v36, v36
	v_exp_f32_e32 v37, v37
	s_waitcnt lgkmcnt(4)
	v_mfma_f32_32x32x16_bf16 v[188:203], v[156:159], v[48:51], v[188:203]
	v_exp_f32_e32 v38, v38
	v_exp_f32_e32 v39, v39
	v_mfma_f32_32x32x16_bf16 v[188:203], v[160:163], v[52:55], v[188:203]
	v_exp_f32_e32 v40, v40
	v_exp_f32_e32 v41, v41
	v_exp_f32_e32 v42, v42
	v_mfma_f32_32x32x16_bf16 v[188:203], v[164:167], v[56:59], v[188:203]
	v_exp_f32_e32 v43, v43
	v_exp_f32_e32 v44, v44
	v_mfma_f32_32x32x16_bf16 v[188:203], v[168:171], v[60:63], v[188:203]
	v_exp_f32_e32 v45, v45
	v_exp_f32_e32 v46, v46
	v_exp_f32_e32 v47, v47
	s_add_i32 s90, s76, 320
	v_add_u32_e32 v84, s90, v107
	v_add_u32_e32 v85, 0, v84
	v_add_u32_e32 v86, 1, v84
	v_add_u32_e32 v87, 2, v84
	v_add_u32_e32 v88, 3, v84
	v_cmp_gt_u32_e64 s[30:31], s98, v85
	v_cmp_gt_u32_e64 s[36:37], s98, v86
	v_cmp_gt_u32_e64 s[78:79], s98, v87
	v_cmp_gt_u32_e64 s[50:51], s98, v88
	v_cndmask_b32_e64 v32, 0, v32, s[30:31]
	v_add_u32_e32 v85, 8, v84
	v_cmp_gt_u32_e64 s[30:31], s98, v85
	v_cndmask_b32_e64 v33, 0, v33, s[36:37]
	v_add_u32_e32 v86, 9, v84
	v_cmp_gt_u32_e64 s[36:37], s98, v86
	v_cndmask_b32_e64 v34, 0, v34, s[78:79]
	v_add_u32_e32 v87, 10, v84
	v_cmp_gt_u32_e64 s[78:79], s98, v87
	v_cndmask_b32_e64 v35, 0, v35, s[50:51]
	v_add_u32_e32 v88, 11, v84
	v_cmp_gt_u32_e64 s[50:51], s98, v88
	v_cndmask_b32_e64 v36, 0, v36, s[30:31]
	v_add_u32_e32 v85, 16, v84
	v_cmp_gt_u32_e64 s[30:31], s98, v85
	v_cndmask_b32_e64 v37, 0, v37, s[36:37]
	v_add_u32_e32 v86, 17, v84
	v_cmp_gt_u32_e64 s[36:37], s98, v86
	v_cndmask_b32_e64 v38, 0, v38, s[78:79]
	v_add_u32_e32 v87, 18, v84
	v_cmp_gt_u32_e64 s[78:79], s98, v87
	v_cndmask_b32_e64 v39, 0, v39, s[50:51]
	v_add_u32_e32 v88, 19, v84
	v_cmp_gt_u32_e64 s[50:51], s98, v88
	v_cndmask_b32_e64 v40, 0, v40, s[30:31]
	v_add_u32_e32 v85, 24, v84
	v_cmp_gt_u32_e64 s[30:31], s98, v85
	v_cndmask_b32_e64 v41, 0, v41, s[36:37]
	v_add_u32_e32 v86, 25, v84
	v_cmp_gt_u32_e64 s[36:37], s98, v86
	v_cndmask_b32_e64 v42, 0, v42, s[78:79]
	v_add_u32_e32 v87, 26, v84
	v_cmp_gt_u32_e64 s[78:79], s98, v87
	v_cndmask_b32_e64 v43, 0, v43, s[50:51]
	v_add_u32_e32 v88, 27, v84
	v_cmp_gt_u32_e64 s[50:51], s98, v88
	v_nop
	v_cndmask_b32_e64 v44, 0, v44, s[30:31]
	v_cndmask_b32_e64 v45, 0, v45, s[36:37]
	v_cndmask_b32_e64 v46, 0, v46, s[78:79]
	v_cndmask_b32_e64 v47, 0, v47, s[50:51]
	v_cvt_pk_bf16_f32 v64, v32, v33
	v_cvt_pk_bf16_f32 v65, v34, v35
	v_cvt_pk_bf16_f32 v66, v36, v37
	v_cvt_pk_bf16_f32 v67, v38, v39
	v_cvt_pk_bf16_f32 v68, v40, v41
	v_cvt_pk_bf16_f32 v69, v42, v43
	v_cvt_pk_bf16_f32 v70, v44, v45
	v_cvt_pk_bf16_f32 v71, v46, v47
	v_pk_add_f32 v[232:233], v[232:233], v[32:33]
	v_pk_add_f32 v[232:233], v[232:233], v[34:35]
	v_pk_add_f32 v[232:233], v[232:233], v[36:37]
	v_pk_add_f32 v[232:233], v[232:233], v[38:39]
	v_pk_add_f32 v[232:233], v[232:233], v[40:41]
	v_pk_add_f32 v[232:233], v[232:233], v[42:43]
	v_pk_add_f32 v[232:233], v[232:233], v[44:45]
	v_pk_add_f32 v[232:233], v[232:233], v[46:47]
	v_add_u32_e32 v115, 952, v115
	ds_read2_b32 v[32:33], v115 offset0:0 offset1:1
	ds_read2_b32 v[34:35], v115 offset0:2 offset1:3
	ds_read2_b32 v[36:37], v115 offset0:8 offset1:9
	ds_read2_b32 v[38:39], v115 offset0:10 offset1:11
	ds_read2_b32 v[40:41], v115 offset0:17 offset1:18
	ds_read2_b32 v[42:43], v115 offset0:19 offset1:20
	ds_read2_b32 v[44:45], v115 offset0:25 offset1:26
	ds_read2_b32 v[46:47], v115 offset0:27 offset1:28
	v_mfma_f32_32x32x16_bf16 v[0:15], v[64:67], v[72:75], v[0:15]
	v_mfma_f32_32x32x16_bf16 v[16:31], v[64:67], v[76:79], v[16:31]
	v_mfma_f32_32x32x16_bf16 v[0:15], v[68:71], v[220:223], v[0:15]
	v_mfma_f32_32x32x16_bf16 v[16:31], v[68:71], v[224:227], v[16:31]
	s_add_i32 s90, s76, 416
	v_add_u32_e32 v80, s90, v235
	v_add_u32_e32 v83, s90, v236
	v_add_u32_e32 v99, s90, v237
	v_add_u32_e32 v253, s90, v238
	v_add_u32_e32 v254, s90, v100
	v_add_u32_e32 v255, s90, v149
	v_med3_i32 v80, v80, 0, s99
	v_med3_i32 v83, v83, 0, s99
	v_med3_i32 v99, v99, 0, s99
	v_med3_i32 v253, v253, 0, s99
	v_med3_i32 v254, v254, 0, s99
	v_med3_i32 v255, v255, 0, s99
	v_mad_u32_u24 v80, v80, s100, v252
	v_mad_u32_u24 v83, v83, s100, v252
	v_mad_u32_u24 v99, v99, s100, v252
	v_mad_u32_u24 v253, v253, s100, v252
	v_mad_u32_u24 v254, v254, s100, v153
	v_mad_u32_u24 v255, v255, s100, v153
	global_load_dwordx4 v[156:159], v80, s[82:83]
	global_load_dwordx4 v[160:163], v83, s[82:83]
	global_load_dwordx4 v[164:167], v99, s[82:83]
	global_load_dwordx4 v[168:171], v253, s[82:83]
	global_load_dwordx4 v[172:175], v254, s[82:83] offset:768
	global_load_dwordx4 v[176:179], v255, s[82:83] offset:768
	global_load_dwordx4 v[180:183], v254, s[82:83] offset:832
	global_load_dwordx4 v[184:187], v255, s[82:83] offset:832
	ds_read_b64_tr_b16 v[72:73], v231
	ds_read_b64_tr_b16 v[74:75], v231 offset:512
	ds_read_b64_tr_b16 v[76:77], v231 offset:2048
	ds_read_b64_tr_b16 v[78:79], v231 offset:2560
	ds_read_b64_tr_b16 v[220:221], v231 offset:1024
	ds_read_b64_tr_b16 v[222:223], v231 offset:1536
	ds_read_b64_tr_b16 v[224:225], v231 offset:3072
	ds_read_b64_tr_b16 v[226:227], v231 offset:3584
	s_waitcnt vmcnt(8)
	ds_write_b128 v247, v[116:119]
	ds_write_b128 v247, v[120:123] offset:1024
	ds_write_b128 v111, v[124:127] offset:2048
	ds_write_b128 v111, v[128:131] offset:3072
	ds_read_b128 v[116:119], v248
	ds_read_b128 v[120:123], v249
	ds_read_b128 v[124:127], v250
	ds_read_b128 v[128:131], v251
	ds_write_b128 v112, v[132:135]
	ds_write_b128 v112, v[136:139] offset:1024
	ds_write_b128 v112, v[140:143] offset:2048
	ds_write_b128 v112, v[144:147] offset:3072
	v_exp_f32_e32 v188, v188
	v_exp_f32_e32 v189, v189
	v_exp_f32_e32 v190, v190
	v_exp_f32_e32 v191, v191
	v_exp_f32_e32 v192, v192
	v_exp_f32_e32 v193, v193
	s_waitcnt lgkmcnt(4)
	v_mfma_f32_32x32x16_bf16 v[32:47], v[116:119], v[48:51], v[32:47]
	v_exp_f32_e32 v194, v194
	v_exp_f32_e32 v195, v195
	v_mfma_f32_32x32x16_bf16 v[32:47], v[120:123], v[52:55], v[32:47]
	v_exp_f32_e32 v196, v196
	v_exp_f32_e32 v197, v197
	v_exp_f32_e32 v198, v198
	v_mfma_f32_32x32x16_bf16 v[32:47], v[124:127], v[56:59], v[32:47]
	v_exp_f32_e32 v199, v199
	v_exp_f32_e32 v200, v200
	v_mfma_f32_32x32x16_bf16 v[32:47], v[128:131], v[60:63], v[32:47]
	v_exp_f32_e32 v201, v201
	v_exp_f32_e32 v202, v202
	v_exp_f32_e32 v203, v203
	s_add_i32 s90, s76, 352
	v_add_u32_e32 v84, s90, v107
	v_add_u32_e32 v85, 0, v84
	v_add_u32_e32 v86, 1, v84
	v_add_u32_e32 v87, 2, v84
	v_add_u32_e32 v88, 3, v84
	v_cmp_gt_u32_e64 s[30:31], s98, v85
	v_cmp_gt_u32_e64 s[36:37], s98, v86
	v_cmp_gt_u32_e64 s[78:79], s98, v87
	v_cmp_gt_u32_e64 s[50:51], s98, v88
	v_cndmask_b32_e64 v188, 0, v188, s[30:31]
	v_add_u32_e32 v85, 8, v84
	v_cmp_gt_u32_e64 s[30:31], s98, v85
	v_cndmask_b32_e64 v189, 0, v189, s[36:37]
	v_add_u32_e32 v86, 9, v84
	v_cmp_gt_u32_e64 s[36:37], s98, v86
	v_cndmask_b32_e64 v190, 0, v190, s[78:79]
	v_add_u32_e32 v87, 10, v84
	v_cmp_gt_u32_e64 s[78:79], s98, v87
	v_cndmask_b32_e64 v191, 0, v191, s[50:51]
	v_add_u32_e32 v88, 11, v84
	v_cmp_gt_u32_e64 s[50:51], s98, v88
	v_cndmask_b32_e64 v192, 0, v192, s[30:31]
	v_add_u32_e32 v85, 16, v84
	v_cmp_gt_u32_e64 s[30:31], s98, v85
	v_cndmask_b32_e64 v193, 0, v193, s[36:37]
	v_add_u32_e32 v86, 17, v84
	v_cmp_gt_u32_e64 s[36:37], s98, v86
	v_cndmask_b32_e64 v194, 0, v194, s[78:79]
	v_add_u32_e32 v87, 18, v84
	v_cmp_gt_u32_e64 s[78:79], s98, v87
	v_cndmask_b32_e64 v195, 0, v195, s[50:51]
	v_add_u32_e32 v88, 19, v84
	v_cmp_gt_u32_e64 s[50:51], s98, v88
	v_cndmask_b32_e64 v196, 0, v196, s[30:31]
	v_add_u32_e32 v85, 24, v84
	v_cmp_gt_u32_e64 s[30:31], s98, v85
	v_cndmask_b32_e64 v197, 0, v197, s[36:37]
	v_add_u32_e32 v86, 25, v84
	v_cmp_gt_u32_e64 s[36:37], s98, v86
	v_cndmask_b32_e64 v198, 0, v198, s[78:79]
	v_add_u32_e32 v87, 26, v84
	v_cmp_gt_u32_e64 s[78:79], s98, v87
	v_cndmask_b32_e64 v199, 0, v199, s[50:51]
	v_add_u32_e32 v88, 27, v84
	v_cmp_gt_u32_e64 s[50:51], s98, v88
	v_nop
	v_cndmask_b32_e64 v200, 0, v200, s[30:31]
	v_cndmask_b32_e64 v201, 0, v201, s[36:37]
	v_cndmask_b32_e64 v202, 0, v202, s[78:79]
	v_cndmask_b32_e64 v203, 0, v203, s[50:51]
	v_cvt_pk_bf16_f32 v64, v188, v189
	v_cvt_pk_bf16_f32 v65, v190, v191
	v_cvt_pk_bf16_f32 v66, v192, v193
	v_cvt_pk_bf16_f32 v67, v194, v195
	v_cvt_pk_bf16_f32 v68, v196, v197
	v_cvt_pk_bf16_f32 v69, v198, v199
	v_cvt_pk_bf16_f32 v70, v200, v201
	v_cvt_pk_bf16_f32 v71, v202, v203
	v_pk_add_f32 v[232:233], v[232:233], v[188:189]
	v_pk_add_f32 v[232:233], v[232:233], v[190:191]
	v_pk_add_f32 v[232:233], v[232:233], v[192:193]
	v_pk_add_f32 v[232:233], v[232:233], v[194:195]
	v_pk_add_f32 v[232:233], v[232:233], v[196:197]
	v_pk_add_f32 v[232:233], v[232:233], v[198:199]
	v_pk_add_f32 v[232:233], v[232:233], v[200:201]
	v_pk_add_f32 v[232:233], v[232:233], v[202:203]
	ds_read2_b32 v[188:189], v115 offset0:34 offset1:35
	ds_read2_b32 v[190:191], v115 offset0:36 offset1:37
	ds_read2_b32 v[192:193], v115 offset0:42 offset1:43
	ds_read2_b32 v[194:195], v115 offset0:44 offset1:45
	ds_read2_b32 v[196:197], v115 offset0:51 offset1:52
	ds_read2_b32 v[198:199], v115 offset0:53 offset1:54
	ds_read2_b32 v[200:201], v115 offset0:59 offset1:60
	ds_read2_b32 v[202:203], v115 offset0:61 offset1:62
	v_mfma_f32_32x32x16_bf16 v[0:15], v[64:67], v[72:75], v[0:15]
	v_mfma_f32_32x32x16_bf16 v[16:31], v[64:67], v[76:79], v[16:31]
	v_mfma_f32_32x32x16_bf16 v[0:15], v[68:71], v[220:223], v[0:15]
	v_mfma_f32_32x32x16_bf16 v[16:31], v[68:71], v[224:227], v[16:31]
	s_add_i32 s90, s76, 448
	v_add_u32_e32 v80, s90, v235
	v_add_u32_e32 v83, s90, v236
	v_add_u32_e32 v99, s90, v237
	v_add_u32_e32 v253, s90, v238
	v_add_u32_e32 v254, s90, v100
	v_add_u32_e32 v255, s90, v149
	v_med3_i32 v80, v80, 0, s99
	v_med3_i32 v83, v83, 0, s99
	v_med3_i32 v99, v99, 0, s99
	v_med3_i32 v253, v253, 0, s99
	v_med3_i32 v254, v254, 0, s99
	v_med3_i32 v255, v255, 0, s99
	v_mad_u32_u24 v80, v80, s100, v252
	v_mad_u32_u24 v83, v83, s100, v252
	v_mad_u32_u24 v99, v99, s100, v252
	v_mad_u32_u24 v253, v253, s100, v252
	v_mad_u32_u24 v254, v254, s100, v153
	v_mad_u32_u24 v255, v255, s100, v153
	global_load_dwordx4 v[116:119], v80, s[82:83]
	global_load_dwordx4 v[120:123], v83, s[82:83]
	global_load_dwordx4 v[124:127], v99, s[82:83]
	global_load_dwordx4 v[128:131], v253, s[82:83]
	global_load_dwordx4 v[132:135], v254, s[82:83] offset:768
	global_load_dwordx4 v[136:139], v255, s[82:83] offset:768
	global_load_dwordx4 v[140:143], v254, s[82:83] offset:832
	global_load_dwordx4 v[144:147], v255, s[82:83] offset:832
	ds_read_b64_tr_b16 v[72:73], v231
	ds_read_b64_tr_b16 v[74:75], v231 offset:512
	ds_read_b64_tr_b16 v[76:77], v231 offset:2048
	ds_read_b64_tr_b16 v[78:79], v231 offset:2560
	ds_read_b64_tr_b16 v[220:221], v231 offset:1024
	ds_read_b64_tr_b16 v[222:223], v231 offset:1536
	ds_read_b64_tr_b16 v[224:225], v231 offset:3072
	ds_read_b64_tr_b16 v[226:227], v231 offset:3584
	s_waitcnt vmcnt(8)
	ds_write_b128 v247, v[156:159]
	ds_write_b128 v247, v[160:163] offset:1024
	ds_write_b128 v111, v[164:167] offset:2048
	ds_write_b128 v111, v[168:171] offset:3072
	ds_read_b128 v[156:159], v248
	ds_read_b128 v[160:163], v249
	ds_read_b128 v[164:167], v250
	ds_read_b128 v[168:171], v251
	ds_write_b128 v112, v[172:175]
	ds_write_b128 v112, v[176:179] offset:1024
	ds_write_b128 v112, v[180:183] offset:2048
	ds_write_b128 v112, v[184:187] offset:3072
	v_exp_f32_e32 v32, v32
	v_exp_f32_e32 v33, v33
	v_exp_f32_e32 v34, v34
	v_exp_f32_e32 v35, v35
	v_exp_f32_e32 v36, v36
	v_exp_f32_e32 v37, v37
	s_waitcnt lgkmcnt(4)
	v_mfma_f32_32x32x16_bf16 v[188:203], v[156:159], v[48:51], v[188:203]
	v_exp_f32_e32 v38, v38
	v_exp_f32_e32 v39, v39
	v_mfma_f32_32x32x16_bf16 v[188:203], v[160:163], v[52:55], v[188:203]
	v_exp_f32_e32 v40, v40
	v_exp_f32_e32 v41, v41
	v_exp_f32_e32 v42, v42
	v_mfma_f32_32x32x16_bf16 v[188:203], v[164:167], v[56:59], v[188:203]
	v_exp_f32_e32 v43, v43
	v_exp_f32_e32 v44, v44
	v_mfma_f32_32x32x16_bf16 v[188:203], v[168:171], v[60:63], v[188:203]
	v_exp_f32_e32 v45, v45
	v_exp_f32_e32 v46, v46
	v_exp_f32_e32 v47, v47
	s_add_i32 s90, s76, 384
	v_add_u32_e32 v84, s90, v107
	v_add_u32_e32 v85, 0, v84
	v_add_u32_e32 v86, 1, v84
	v_add_u32_e32 v87, 2, v84
	v_add_u32_e32 v88, 3, v84
	v_cmp_gt_u32_e64 s[30:31], s98, v85
	v_cmp_gt_u32_e64 s[36:37], s98, v86
	v_cmp_gt_u32_e64 s[78:79], s98, v87
	v_cmp_gt_u32_e64 s[50:51], s98, v88
	v_cndmask_b32_e64 v32, 0, v32, s[30:31]
	v_add_u32_e32 v85, 8, v84
	v_cmp_gt_u32_e64 s[30:31], s98, v85
	v_cndmask_b32_e64 v33, 0, v33, s[36:37]
	v_add_u32_e32 v86, 9, v84
	v_cmp_gt_u32_e64 s[36:37], s98, v86
	v_cndmask_b32_e64 v34, 0, v34, s[78:79]
	v_add_u32_e32 v87, 10, v84
	v_cmp_gt_u32_e64 s[78:79], s98, v87
	v_cndmask_b32_e64 v35, 0, v35, s[50:51]
	v_add_u32_e32 v88, 11, v84
	v_cmp_gt_u32_e64 s[50:51], s98, v88
	v_cndmask_b32_e64 v36, 0, v36, s[30:31]
	v_add_u32_e32 v85, 16, v84
	v_cmp_gt_u32_e64 s[30:31], s98, v85
	v_cndmask_b32_e64 v37, 0, v37, s[36:37]
	v_add_u32_e32 v86, 17, v84
	v_cmp_gt_u32_e64 s[36:37], s98, v86
	v_cndmask_b32_e64 v38, 0, v38, s[78:79]
	v_add_u32_e32 v87, 18, v84
	v_cmp_gt_u32_e64 s[78:79], s98, v87
	v_cndmask_b32_e64 v39, 0, v39, s[50:51]
	v_add_u32_e32 v88, 19, v84
	v_cmp_gt_u32_e64 s[50:51], s98, v88
	v_cndmask_b32_e64 v40, 0, v40, s[30:31]
	v_add_u32_e32 v85, 24, v84
	v_cmp_gt_u32_e64 s[30:31], s98, v85
	v_cndmask_b32_e64 v41, 0, v41, s[36:37]
	v_add_u32_e32 v86, 25, v84
	v_cmp_gt_u32_e64 s[36:37], s98, v86
	v_cndmask_b32_e64 v42, 0, v42, s[78:79]
	v_add_u32_e32 v87, 26, v84
	v_cmp_gt_u32_e64 s[78:79], s98, v87
	v_cndmask_b32_e64 v43, 0, v43, s[50:51]
	v_add_u32_e32 v88, 27, v84
	v_cmp_gt_u32_e64 s[50:51], s98, v88
	v_nop
	v_cndmask_b32_e64 v44, 0, v44, s[30:31]
	v_cndmask_b32_e64 v45, 0, v45, s[36:37]
	v_cndmask_b32_e64 v46, 0, v46, s[78:79]
	v_cndmask_b32_e64 v47, 0, v47, s[50:51]
	v_cvt_pk_bf16_f32 v64, v32, v33
	v_cvt_pk_bf16_f32 v65, v34, v35
	v_cvt_pk_bf16_f32 v66, v36, v37
	v_cvt_pk_bf16_f32 v67, v38, v39
	v_cvt_pk_bf16_f32 v68, v40, v41
	v_cvt_pk_bf16_f32 v69, v42, v43
	v_cvt_pk_bf16_f32 v70, v44, v45
	v_cvt_pk_bf16_f32 v71, v46, v47
	v_pk_add_f32 v[232:233], v[232:233], v[32:33]
	v_pk_add_f32 v[232:233], v[232:233], v[34:35]
	v_pk_add_f32 v[232:233], v[232:233], v[36:37]
	v_pk_add_f32 v[232:233], v[232:233], v[38:39]
	v_pk_add_f32 v[232:233], v[232:233], v[40:41]
	v_pk_add_f32 v[232:233], v[232:233], v[42:43]
	v_pk_add_f32 v[232:233], v[232:233], v[44:45]
	v_pk_add_f32 v[232:233], v[232:233], v[46:47]
	ds_read2_b32 v[32:33], v115 offset0:68 offset1:69
	ds_read2_b32 v[34:35], v115 offset0:70 offset1:71
	ds_read2_b32 v[36:37], v115 offset0:76 offset1:77
	ds_read2_b32 v[38:39], v115 offset0:78 offset1:79
	ds_read2_b32 v[40:41], v115 offset0:85 offset1:86
	ds_read2_b32 v[42:43], v115 offset0:87 offset1:88
	ds_read2_b32 v[44:45], v115 offset0:93 offset1:94
	ds_read2_b32 v[46:47], v115 offset0:95 offset1:96
	v_mfma_f32_32x32x16_bf16 v[0:15], v[64:67], v[72:75], v[0:15]
	v_mfma_f32_32x32x16_bf16 v[16:31], v[64:67], v[76:79], v[16:31]
	v_mfma_f32_32x32x16_bf16 v[0:15], v[68:71], v[220:223], v[0:15]
	v_mfma_f32_32x32x16_bf16 v[16:31], v[68:71], v[224:227], v[16:31]
	s_add_i32 s90, s76, 480
	v_add_u32_e32 v80, s90, v235
	v_add_u32_e32 v83, s90, v236
	v_add_u32_e32 v99, s90, v237
	v_add_u32_e32 v253, s90, v238
	v_add_u32_e32 v254, s90, v100
	v_add_u32_e32 v255, s90, v149
	v_med3_i32 v80, v80, 0, s99
	v_med3_i32 v83, v83, 0, s99
	v_med3_i32 v99, v99, 0, s99
	v_med3_i32 v253, v253, 0, s99
	v_med3_i32 v254, v254, 0, s99
	v_med3_i32 v255, v255, 0, s99
	v_mad_u32_u24 v80, v80, s100, v252
	v_mad_u32_u24 v83, v83, s100, v252
	v_mad_u32_u24 v99, v99, s100, v252
	v_mad_u32_u24 v253, v253, s100, v252
	v_mad_u32_u24 v254, v254, s100, v153
	v_mad_u32_u24 v255, v255, s100, v153
	global_load_dwordx4 v[156:159], v80, s[82:83]
	global_load_dwordx4 v[160:163], v83, s[82:83]
	global_load_dwordx4 v[164:167], v99, s[82:83]
	global_load_dwordx4 v[168:171], v253, s[82:83]
	global_load_dwordx4 v[172:175], v254, s[82:83] offset:768
	global_load_dwordx4 v[176:179], v255, s[82:83] offset:768
	global_load_dwordx4 v[180:183], v254, s[82:83] offset:832
	global_load_dwordx4 v[184:187], v255, s[82:83] offset:832
	ds_read_b64_tr_b16 v[72:73], v231
	ds_read_b64_tr_b16 v[74:75], v231 offset:512
	ds_read_b64_tr_b16 v[76:77], v231 offset:2048
	ds_read_b64_tr_b16 v[78:79], v231 offset:2560
	ds_read_b64_tr_b16 v[220:221], v231 offset:1024
	ds_read_b64_tr_b16 v[222:223], v231 offset:1536
	ds_read_b64_tr_b16 v[224:225], v231 offset:3072
	ds_read_b64_tr_b16 v[226:227], v231 offset:3584
	s_waitcnt vmcnt(8)
	ds_write_b128 v247, v[116:119]
	ds_write_b128 v247, v[120:123] offset:1024
	ds_write_b128 v111, v[124:127] offset:2048
	ds_write_b128 v111, v[128:131] offset:3072
	ds_read_b128 v[116:119], v248
	ds_read_b128 v[120:123], v249
	ds_read_b128 v[124:127], v250
	ds_read_b128 v[128:131], v251
	ds_write_b128 v112, v[132:135]
	ds_write_b128 v112, v[136:139] offset:1024
	ds_write_b128 v112, v[140:143] offset:2048
	ds_write_b128 v112, v[144:147] offset:3072
	v_exp_f32_e32 v188, v188
	v_exp_f32_e32 v189, v189
	v_exp_f32_e32 v190, v190
	v_exp_f32_e32 v191, v191
	v_exp_f32_e32 v192, v192
	v_exp_f32_e32 v193, v193
	s_waitcnt lgkmcnt(4)
	v_mfma_f32_32x32x16_bf16 v[32:47], v[116:119], v[48:51], v[32:47]
	v_exp_f32_e32 v194, v194
	v_exp_f32_e32 v195, v195
	v_mfma_f32_32x32x16_bf16 v[32:47], v[120:123], v[52:55], v[32:47]
	v_exp_f32_e32 v196, v196
	v_exp_f32_e32 v197, v197
	v_exp_f32_e32 v198, v198
	v_mfma_f32_32x32x16_bf16 v[32:47], v[124:127], v[56:59], v[32:47]
	v_exp_f32_e32 v199, v199
	v_exp_f32_e32 v200, v200
	v_mfma_f32_32x32x16_bf16 v[32:47], v[128:131], v[60:63], v[32:47]
	v_exp_f32_e32 v201, v201
	v_exp_f32_e32 v202, v202
	v_exp_f32_e32 v203, v203
	s_add_i32 s90, s76, 416
	v_add_u32_e32 v84, s90, v107
	v_add_u32_e32 v85, 0, v84
	v_add_u32_e32 v86, 1, v84
	v_add_u32_e32 v87, 2, v84
	v_add_u32_e32 v88, 3, v84
	v_cmp_gt_u32_e64 s[30:31], s98, v85
	v_cmp_gt_u32_e64 s[36:37], s98, v86
	v_cmp_gt_u32_e64 s[78:79], s98, v87
	v_cmp_gt_u32_e64 s[50:51], s98, v88
	v_cndmask_b32_e64 v188, 0, v188, s[30:31]
	v_add_u32_e32 v85, 8, v84
	v_cmp_gt_u32_e64 s[30:31], s98, v85
	v_cndmask_b32_e64 v189, 0, v189, s[36:37]
	v_add_u32_e32 v86, 9, v84
	v_cmp_gt_u32_e64 s[36:37], s98, v86
	v_cndmask_b32_e64 v190, 0, v190, s[78:79]
	v_add_u32_e32 v87, 10, v84
	v_cmp_gt_u32_e64 s[78:79], s98, v87
	v_cndmask_b32_e64 v191, 0, v191, s[50:51]
	v_add_u32_e32 v88, 11, v84
	v_cmp_gt_u32_e64 s[50:51], s98, v88
	v_cndmask_b32_e64 v192, 0, v192, s[30:31]
	v_add_u32_e32 v85, 16, v84
	v_cmp_gt_u32_e64 s[30:31], s98, v85
	v_cndmask_b32_e64 v193, 0, v193, s[36:37]
	v_add_u32_e32 v86, 17, v84
	v_cmp_gt_u32_e64 s[36:37], s98, v86
	v_cndmask_b32_e64 v194, 0, v194, s[78:79]
	v_add_u32_e32 v87, 18, v84
	v_cmp_gt_u32_e64 s[78:79], s98, v87
	v_cndmask_b32_e64 v195, 0, v195, s[50:51]
	v_add_u32_e32 v88, 19, v84
	v_cmp_gt_u32_e64 s[50:51], s98, v88
	v_cndmask_b32_e64 v196, 0, v196, s[30:31]
	v_add_u32_e32 v85, 24, v84
	v_cmp_gt_u32_e64 s[30:31], s98, v85
	v_cndmask_b32_e64 v197, 0, v197, s[36:37]
	v_add_u32_e32 v86, 25, v84
	v_cmp_gt_u32_e64 s[36:37], s98, v86
	v_cndmask_b32_e64 v198, 0, v198, s[78:79]
	v_add_u32_e32 v87, 26, v84
	v_cmp_gt_u32_e64 s[78:79], s98, v87
	v_cndmask_b32_e64 v199, 0, v199, s[50:51]
	v_add_u32_e32 v88, 27, v84
	v_cmp_gt_u32_e64 s[50:51], s98, v88
	v_nop
	v_cndmask_b32_e64 v200, 0, v200, s[30:31]
	v_cndmask_b32_e64 v201, 0, v201, s[36:37]
	v_cndmask_b32_e64 v202, 0, v202, s[78:79]
	v_cndmask_b32_e64 v203, 0, v203, s[50:51]
	v_cvt_pk_bf16_f32 v64, v188, v189
	v_cvt_pk_bf16_f32 v65, v190, v191
	v_cvt_pk_bf16_f32 v66, v192, v193
	v_cvt_pk_bf16_f32 v67, v194, v195
	v_cvt_pk_bf16_f32 v68, v196, v197
	v_cvt_pk_bf16_f32 v69, v198, v199
	v_cvt_pk_bf16_f32 v70, v200, v201
	v_cvt_pk_bf16_f32 v71, v202, v203
	v_pk_add_f32 v[232:233], v[232:233], v[188:189]
	v_pk_add_f32 v[232:233], v[232:233], v[190:191]
	v_pk_add_f32 v[232:233], v[232:233], v[192:193]
	v_pk_add_f32 v[232:233], v[232:233], v[194:195]
	v_pk_add_f32 v[232:233], v[232:233], v[196:197]
	v_pk_add_f32 v[232:233], v[232:233], v[198:199]
	v_pk_add_f32 v[232:233], v[232:233], v[200:201]
	v_pk_add_f32 v[232:233], v[232:233], v[202:203]
	ds_read2_b32 v[188:189], v115 offset0:102 offset1:103
	ds_read2_b32 v[190:191], v115 offset0:104 offset1:105
	ds_read2_b32 v[192:193], v115 offset0:110 offset1:111
	ds_read2_b32 v[194:195], v115 offset0:112 offset1:113
	ds_read2_b32 v[196:197], v115 offset0:119 offset1:120
	ds_read2_b32 v[198:199], v115 offset0:121 offset1:122
	ds_read2_b32 v[200:201], v115 offset0:127 offset1:128
	ds_read2_b32 v[202:203], v115 offset0:129 offset1:130
	v_mfma_f32_32x32x16_bf16 v[0:15], v[64:67], v[72:75], v[0:15]
	v_mfma_f32_32x32x16_bf16 v[16:31], v[64:67], v[76:79], v[16:31]
	v_mfma_f32_32x32x16_bf16 v[0:15], v[68:71], v[220:223], v[0:15]
	v_mfma_f32_32x32x16_bf16 v[16:31], v[68:71], v[224:227], v[16:31]
	s_add_i32 s90, s76, 512
	v_add_u32_e32 v80, s90, v235
	v_add_u32_e32 v83, s90, v236
	v_add_u32_e32 v99, s90, v237
	v_add_u32_e32 v253, s90, v238
	v_add_u32_e32 v254, s90, v100
	v_add_u32_e32 v255, s90, v149
	v_med3_i32 v80, v80, 0, s99
	v_med3_i32 v83, v83, 0, s99
	v_med3_i32 v99, v99, 0, s99
	v_med3_i32 v253, v253, 0, s99
	v_med3_i32 v254, v254, 0, s99
	v_med3_i32 v255, v255, 0, s99
	v_mad_u32_u24 v80, v80, s100, v252
	v_mad_u32_u24 v83, v83, s100, v252
	v_mad_u32_u24 v99, v99, s100, v252
	v_mad_u32_u24 v253, v253, s100, v252
	v_mad_u32_u24 v254, v254, s100, v153
	v_mad_u32_u24 v255, v255, s100, v153
	global_load_dwordx4 v[116:119], v80, s[82:83]
	global_load_dwordx4 v[120:123], v83, s[82:83]
	global_load_dwordx4 v[124:127], v99, s[82:83]
	global_load_dwordx4 v[128:131], v253, s[82:83]
	global_load_dwordx4 v[132:135], v254, s[82:83] offset:768
	global_load_dwordx4 v[136:139], v255, s[82:83] offset:768
	global_load_dwordx4 v[140:143], v254, s[82:83] offset:832
	global_load_dwordx4 v[144:147], v255, s[82:83] offset:832
	ds_read_b64_tr_b16 v[72:73], v231
	ds_read_b64_tr_b16 v[74:75], v231 offset:512
	ds_read_b64_tr_b16 v[76:77], v231 offset:2048
	ds_read_b64_tr_b16 v[78:79], v231 offset:2560
	ds_read_b64_tr_b16 v[220:221], v231 offset:1024
	ds_read_b64_tr_b16 v[222:223], v231 offset:1536
	ds_read_b64_tr_b16 v[224:225], v231 offset:3072
	ds_read_b64_tr_b16 v[226:227], v231 offset:3584
	s_waitcnt vmcnt(8)
	ds_write_b128 v247, v[156:159]
	ds_write_b128 v247, v[160:163] offset:1024
	ds_write_b128 v111, v[164:167] offset:2048
	ds_write_b128 v111, v[168:171] offset:3072
	ds_read_b128 v[156:159], v248
	ds_read_b128 v[160:163], v249
	ds_read_b128 v[164:167], v250
	ds_read_b128 v[168:171], v251
	ds_write_b128 v112, v[172:175]
	ds_write_b128 v112, v[176:179] offset:1024
	ds_write_b128 v112, v[180:183] offset:2048
	ds_write_b128 v112, v[184:187] offset:3072
	v_exp_f32_e32 v32, v32
	v_exp_f32_e32 v33, v33
	v_exp_f32_e32 v34, v34
	v_exp_f32_e32 v35, v35
	v_exp_f32_e32 v36, v36
	v_exp_f32_e32 v37, v37
	s_waitcnt lgkmcnt(4)
	v_mfma_f32_32x32x16_bf16 v[188:203], v[156:159], v[48:51], v[188:203]
	v_exp_f32_e32 v38, v38
	v_exp_f32_e32 v39, v39
	v_mfma_f32_32x32x16_bf16 v[188:203], v[160:163], v[52:55], v[188:203]
	v_exp_f32_e32 v40, v40
	v_exp_f32_e32 v41, v41
	v_exp_f32_e32 v42, v42
	v_mfma_f32_32x32x16_bf16 v[188:203], v[164:167], v[56:59], v[188:203]
	v_exp_f32_e32 v43, v43
	v_exp_f32_e32 v44, v44
	v_mfma_f32_32x32x16_bf16 v[188:203], v[168:171], v[60:63], v[188:203]
	v_exp_f32_e32 v45, v45
	v_exp_f32_e32 v46, v46
	v_exp_f32_e32 v47, v47
	s_add_i32 s90, s76, 448
	v_add_u32_e32 v84, s90, v107
	v_add_u32_e32 v85, 0, v84
	v_add_u32_e32 v86, 1, v84
	v_add_u32_e32 v87, 2, v84
	v_add_u32_e32 v88, 3, v84
	v_cmp_gt_u32_e64 s[30:31], s98, v85
	v_cmp_gt_u32_e64 s[36:37], s98, v86
	v_cmp_gt_u32_e64 s[78:79], s98, v87
	v_cmp_gt_u32_e64 s[50:51], s98, v88
	v_cndmask_b32_e64 v32, 0, v32, s[30:31]
	v_add_u32_e32 v85, 8, v84
	v_cmp_gt_u32_e64 s[30:31], s98, v85
	v_cndmask_b32_e64 v33, 0, v33, s[36:37]
	v_add_u32_e32 v86, 9, v84
	v_cmp_gt_u32_e64 s[36:37], s98, v86
	v_cndmask_b32_e64 v34, 0, v34, s[78:79]
	v_add_u32_e32 v87, 10, v84
	v_cmp_gt_u32_e64 s[78:79], s98, v87
	v_cndmask_b32_e64 v35, 0, v35, s[50:51]
	v_add_u32_e32 v88, 11, v84
	v_cmp_gt_u32_e64 s[50:51], s98, v88
	v_cndmask_b32_e64 v36, 0, v36, s[30:31]
	v_add_u32_e32 v85, 16, v84
	v_cmp_gt_u32_e64 s[30:31], s98, v85
	v_cndmask_b32_e64 v37, 0, v37, s[36:37]
	v_add_u32_e32 v86, 17, v84
	v_cmp_gt_u32_e64 s[36:37], s98, v86
	v_cndmask_b32_e64 v38, 0, v38, s[78:79]
	v_add_u32_e32 v87, 18, v84
	v_cmp_gt_u32_e64 s[78:79], s98, v87
	v_cndmask_b32_e64 v39, 0, v39, s[50:51]
	v_add_u32_e32 v88, 19, v84
	v_cmp_gt_u32_e64 s[50:51], s98, v88
	v_cndmask_b32_e64 v40, 0, v40, s[30:31]
	v_add_u32_e32 v85, 24, v84
	v_cmp_gt_u32_e64 s[30:31], s98, v85
	v_cndmask_b32_e64 v41, 0, v41, s[36:37]
	v_add_u32_e32 v86, 25, v84
	v_cmp_gt_u32_e64 s[36:37], s98, v86
	v_cndmask_b32_e64 v42, 0, v42, s[78:79]
	v_add_u32_e32 v87, 26, v84
	v_cmp_gt_u32_e64 s[78:79], s98, v87
	v_cndmask_b32_e64 v43, 0, v43, s[50:51]
	v_add_u32_e32 v88, 27, v84
	v_cmp_gt_u32_e64 s[50:51], s98, v88
	v_nop
	v_cndmask_b32_e64 v44, 0, v44, s[30:31]
	v_cndmask_b32_e64 v45, 0, v45, s[36:37]
	v_cndmask_b32_e64 v46, 0, v46, s[78:79]
	v_cndmask_b32_e64 v47, 0, v47, s[50:51]
	v_cvt_pk_bf16_f32 v64, v32, v33
	v_cvt_pk_bf16_f32 v65, v34, v35
	v_cvt_pk_bf16_f32 v66, v36, v37
	v_cvt_pk_bf16_f32 v67, v38, v39
	v_cvt_pk_bf16_f32 v68, v40, v41
	v_cvt_pk_bf16_f32 v69, v42, v43
	v_cvt_pk_bf16_f32 v70, v44, v45
	v_cvt_pk_bf16_f32 v71, v46, v47
	v_pk_add_f32 v[232:233], v[232:233], v[32:33]
	v_pk_add_f32 v[232:233], v[232:233], v[34:35]
	v_pk_add_f32 v[232:233], v[232:233], v[36:37]
	v_pk_add_f32 v[232:233], v[232:233], v[38:39]
	v_pk_add_f32 v[232:233], v[232:233], v[40:41]
	v_pk_add_f32 v[232:233], v[232:233], v[42:43]
	v_pk_add_f32 v[232:233], v[232:233], v[44:45]
	v_pk_add_f32 v[232:233], v[232:233], v[46:47]
	ds_read2_b32 v[32:33], v115 offset0:136 offset1:137
	ds_read2_b32 v[34:35], v115 offset0:138 offset1:139
	ds_read2_b32 v[36:37], v115 offset0:144 offset1:145
	ds_read2_b32 v[38:39], v115 offset0:146 offset1:147
	ds_read2_b32 v[40:41], v115 offset0:153 offset1:154
	ds_read2_b32 v[42:43], v115 offset0:155 offset1:156
	ds_read2_b32 v[44:45], v115 offset0:161 offset1:162
	ds_read2_b32 v[46:47], v115 offset0:163 offset1:164
	v_mfma_f32_32x32x16_bf16 v[0:15], v[64:67], v[72:75], v[0:15]
	v_mfma_f32_32x32x16_bf16 v[16:31], v[64:67], v[76:79], v[16:31]
	v_mfma_f32_32x32x16_bf16 v[0:15], v[68:71], v[220:223], v[0:15]
	v_mfma_f32_32x32x16_bf16 v[16:31], v[68:71], v[224:227], v[16:31]
	s_add_i32 s90, s76, 544
	v_add_u32_e32 v80, s90, v235
	v_add_u32_e32 v83, s90, v236
	v_add_u32_e32 v99, s90, v237
	v_add_u32_e32 v253, s90, v238
	v_add_u32_e32 v254, s90, v100
	v_add_u32_e32 v255, s90, v149
	v_med3_i32 v80, v80, 0, s99
	v_med3_i32 v83, v83, 0, s99
	v_med3_i32 v99, v99, 0, s99
	v_med3_i32 v253, v253, 0, s99
	v_med3_i32 v254, v254, 0, s99
	v_med3_i32 v255, v255, 0, s99
	v_mad_u32_u24 v80, v80, s100, v252
	v_mad_u32_u24 v83, v83, s100, v252
	v_mad_u32_u24 v99, v99, s100, v252
	v_mad_u32_u24 v253, v253, s100, v252
	v_mad_u32_u24 v254, v254, s100, v153
	v_mad_u32_u24 v255, v255, s100, v153
	global_load_dwordx4 v[156:159], v80, s[82:83]
	global_load_dwordx4 v[160:163], v83, s[82:83]
	global_load_dwordx4 v[164:167], v99, s[82:83]
	global_load_dwordx4 v[168:171], v253, s[82:83]
	global_load_dwordx4 v[172:175], v254, s[82:83] offset:768
	global_load_dwordx4 v[176:179], v255, s[82:83] offset:768
	global_load_dwordx4 v[180:183], v254, s[82:83] offset:832
	global_load_dwordx4 v[184:187], v255, s[82:83] offset:832
	ds_read_b64_tr_b16 v[72:73], v231
	ds_read_b64_tr_b16 v[74:75], v231 offset:512
	ds_read_b64_tr_b16 v[76:77], v231 offset:2048
	ds_read_b64_tr_b16 v[78:79], v231 offset:2560
	ds_read_b64_tr_b16 v[220:221], v231 offset:1024
	ds_read_b64_tr_b16 v[222:223], v231 offset:1536
	ds_read_b64_tr_b16 v[224:225], v231 offset:3072
	ds_read_b64_tr_b16 v[226:227], v231 offset:3584
	s_waitcnt vmcnt(8)
	ds_write_b128 v247, v[116:119]
	ds_write_b128 v247, v[120:123] offset:1024
	ds_write_b128 v111, v[124:127] offset:2048
	ds_write_b128 v111, v[128:131] offset:3072
	ds_read_b128 v[116:119], v248
	ds_read_b128 v[120:123], v249
	ds_read_b128 v[124:127], v250
	ds_read_b128 v[128:131], v251
	ds_write_b128 v112, v[132:135]
	ds_write_b128 v112, v[136:139] offset:1024
	ds_write_b128 v112, v[140:143] offset:2048
	ds_write_b128 v112, v[144:147] offset:3072
	v_exp_f32_e32 v188, v188
	v_exp_f32_e32 v189, v189
	v_exp_f32_e32 v190, v190
	v_exp_f32_e32 v191, v191
	v_exp_f32_e32 v192, v192
	v_exp_f32_e32 v193, v193
	s_waitcnt lgkmcnt(4)
	v_mfma_f32_32x32x16_bf16 v[32:47], v[116:119], v[48:51], v[32:47]
	v_exp_f32_e32 v194, v194
	v_exp_f32_e32 v195, v195
	v_mfma_f32_32x32x16_bf16 v[32:47], v[120:123], v[52:55], v[32:47]
	v_exp_f32_e32 v196, v196
	v_exp_f32_e32 v197, v197
	v_exp_f32_e32 v198, v198
	v_mfma_f32_32x32x16_bf16 v[32:47], v[124:127], v[56:59], v[32:47]
	v_exp_f32_e32 v199, v199
	v_exp_f32_e32 v200, v200
	v_mfma_f32_32x32x16_bf16 v[32:47], v[128:131], v[60:63], v[32:47]
	v_exp_f32_e32 v201, v201
	v_exp_f32_e32 v202, v202
	v_exp_f32_e32 v203, v203
	s_add_i32 s90, s76, 480
	v_add_u32_e32 v84, s90, v107
	v_add_u32_e32 v85, 0, v84
	v_add_u32_e32 v86, 1, v84
	v_add_u32_e32 v87, 2, v84
	v_add_u32_e32 v88, 3, v84
	v_cmp_gt_u32_e64 s[30:31], s98, v85
	v_cmp_gt_u32_e64 s[36:37], s98, v86
	v_cmp_gt_u32_e64 s[78:79], s98, v87
	v_cmp_gt_u32_e64 s[50:51], s98, v88
	v_cndmask_b32_e64 v188, 0, v188, s[30:31]
	v_add_u32_e32 v85, 8, v84
	v_cmp_gt_u32_e64 s[30:31], s98, v85
	v_cndmask_b32_e64 v189, 0, v189, s[36:37]
	v_add_u32_e32 v86, 9, v84
	v_cmp_gt_u32_e64 s[36:37], s98, v86
	v_cndmask_b32_e64 v190, 0, v190, s[78:79]
	v_add_u32_e32 v87, 10, v84
	v_cmp_gt_u32_e64 s[78:79], s98, v87
	v_cndmask_b32_e64 v191, 0, v191, s[50:51]
	v_add_u32_e32 v88, 11, v84
	v_cmp_gt_u32_e64 s[50:51], s98, v88
	v_cndmask_b32_e64 v192, 0, v192, s[30:31]
	v_add_u32_e32 v85, 16, v84
	v_cmp_gt_u32_e64 s[30:31], s98, v85
	v_cndmask_b32_e64 v193, 0, v193, s[36:37]
	v_add_u32_e32 v86, 17, v84
	v_cmp_gt_u32_e64 s[36:37], s98, v86
	v_cndmask_b32_e64 v194, 0, v194, s[78:79]
	v_add_u32_e32 v87, 18, v84
	v_cmp_gt_u32_e64 s[78:79], s98, v87
	v_cndmask_b32_e64 v195, 0, v195, s[50:51]
	v_add_u32_e32 v88, 19, v84
	v_cmp_gt_u32_e64 s[50:51], s98, v88
	v_cndmask_b32_e64 v196, 0, v196, s[30:31]
	v_add_u32_e32 v85, 24, v84
	v_cmp_gt_u32_e64 s[30:31], s98, v85
	v_cndmask_b32_e64 v197, 0, v197, s[36:37]
	v_add_u32_e32 v86, 25, v84
	v_cmp_gt_u32_e64 s[36:37], s98, v86
	v_cndmask_b32_e64 v198, 0, v198, s[78:79]
	v_add_u32_e32 v87, 26, v84
	v_cmp_gt_u32_e64 s[78:79], s98, v87
	v_cndmask_b32_e64 v199, 0, v199, s[50:51]
	v_add_u32_e32 v88, 27, v84
	v_cmp_gt_u32_e64 s[50:51], s98, v88
	v_nop
	v_cndmask_b32_e64 v200, 0, v200, s[30:31]
	v_cndmask_b32_e64 v201, 0, v201, s[36:37]
	v_cndmask_b32_e64 v202, 0, v202, s[78:79]
	v_cndmask_b32_e64 v203, 0, v203, s[50:51]
	v_cvt_pk_bf16_f32 v64, v188, v189
	v_cvt_pk_bf16_f32 v65, v190, v191
	v_cvt_pk_bf16_f32 v66, v192, v193
	v_cvt_pk_bf16_f32 v67, v194, v195
	v_cvt_pk_bf16_f32 v68, v196, v197
	v_cvt_pk_bf16_f32 v69, v198, v199
	v_cvt_pk_bf16_f32 v70, v200, v201
	v_cvt_pk_bf16_f32 v71, v202, v203
	v_pk_add_f32 v[232:233], v[232:233], v[188:189]
	v_pk_add_f32 v[232:233], v[232:233], v[190:191]
	v_pk_add_f32 v[232:233], v[232:233], v[192:193]
	v_pk_add_f32 v[232:233], v[232:233], v[194:195]
	v_pk_add_f32 v[232:233], v[232:233], v[196:197]
	v_pk_add_f32 v[232:233], v[232:233], v[198:199]
	v_pk_add_f32 v[232:233], v[232:233], v[200:201]
	v_pk_add_f32 v[232:233], v[232:233], v[202:203]
	ds_read2_b32 v[188:189], v115 offset0:170 offset1:171
	ds_read2_b32 v[190:191], v115 offset0:172 offset1:173
	ds_read2_b32 v[192:193], v115 offset0:178 offset1:179
	ds_read2_b32 v[194:195], v115 offset0:180 offset1:181
	ds_read2_b32 v[196:197], v115 offset0:187 offset1:188
	ds_read2_b32 v[198:199], v115 offset0:189 offset1:190
	ds_read2_b32 v[200:201], v115 offset0:195 offset1:196
	ds_read2_b32 v[202:203], v115 offset0:197 offset1:198
	v_mfma_f32_32x32x16_bf16 v[0:15], v[64:67], v[72:75], v[0:15]
	v_mfma_f32_32x32x16_bf16 v[16:31], v[64:67], v[76:79], v[16:31]
	v_mfma_f32_32x32x16_bf16 v[0:15], v[68:71], v[220:223], v[0:15]
	v_mfma_f32_32x32x16_bf16 v[16:31], v[68:71], v[224:227], v[16:31]
	s_add_i32 s90, s76, -256
	v_add_u32_e32 v80, s90, v239
	v_add_u32_e32 v83, s90, v240
	v_add_u32_e32 v99, s90, v241
	v_add_u32_e32 v253, s90, v242
	v_add_u32_e32 v254, s90, v101
	v_add_u32_e32 v255, s90, v150
	v_med3_i32 v80, v80, 0, s99
	v_med3_i32 v83, v83, 0, s99
	v_med3_i32 v99, v99, 0, s99
	v_med3_i32 v253, v253, 0, s99
	v_med3_i32 v254, v254, 0, s99
	v_med3_i32 v255, v255, 0, s99
	v_mad_u32_u24 v80, v80, s100, v252
	v_mad_u32_u24 v83, v83, s100, v252
	v_mad_u32_u24 v99, v99, s100, v252
	v_mad_u32_u24 v253, v253, s100, v252
	v_mad_u32_u24 v254, v254, s100, v153
	v_mad_u32_u24 v255, v255, s100, v153
	global_load_dwordx4 v[116:119], v80, s[82:83]
	global_load_dwordx4 v[120:123], v83, s[82:83]
	global_load_dwordx4 v[124:127], v99, s[82:83]
	global_load_dwordx4 v[128:131], v253, s[82:83]
	global_load_dwordx4 v[132:135], v254, s[82:83] offset:768
	global_load_dwordx4 v[136:139], v255, s[82:83] offset:768
	global_load_dwordx4 v[140:143], v254, s[82:83] offset:832
	global_load_dwordx4 v[144:147], v255, s[82:83] offset:832
	ds_read_b64_tr_b16 v[72:73], v231
	ds_read_b64_tr_b16 v[74:75], v231 offset:512
	ds_read_b64_tr_b16 v[76:77], v231 offset:2048
	ds_read_b64_tr_b16 v[78:79], v231 offset:2560
	ds_read_b64_tr_b16 v[220:221], v231 offset:1024
	ds_read_b64_tr_b16 v[222:223], v231 offset:1536
	ds_read_b64_tr_b16 v[224:225], v231 offset:3072
	ds_read_b64_tr_b16 v[226:227], v231 offset:3584
	s_waitcnt vmcnt(8)
	ds_write_b128 v247, v[156:159]
	ds_write_b128 v247, v[160:163] offset:1024
	ds_write_b128 v111, v[164:167] offset:2048
	ds_write_b128 v111, v[168:171] offset:3072
	ds_read_b128 v[156:159], v248
	ds_read_b128 v[160:163], v249
	ds_read_b128 v[164:167], v250
	ds_read_b128 v[168:171], v251
	ds_write_b128 v112, v[172:175]
	ds_write_b128 v112, v[176:179] offset:1024
	ds_write_b128 v112, v[180:183] offset:2048
	ds_write_b128 v112, v[184:187] offset:3072
	v_exp_f32_e32 v32, v32
	v_exp_f32_e32 v33, v33
	v_exp_f32_e32 v34, v34
	v_exp_f32_e32 v35, v35
	v_exp_f32_e32 v36, v36
	v_exp_f32_e32 v37, v37
	s_waitcnt lgkmcnt(4)
	v_mfma_f32_32x32x16_bf16 v[188:203], v[156:159], v[48:51], v[188:203]
	v_exp_f32_e32 v38, v38
	v_exp_f32_e32 v39, v39
	v_mfma_f32_32x32x16_bf16 v[188:203], v[160:163], v[52:55], v[188:203]
	v_exp_f32_e32 v40, v40
	v_exp_f32_e32 v41, v41
	v_exp_f32_e32 v42, v42
	v_mfma_f32_32x32x16_bf16 v[188:203], v[164:167], v[56:59], v[188:203]
	v_exp_f32_e32 v43, v43
	v_exp_f32_e32 v44, v44
	v_mfma_f32_32x32x16_bf16 v[188:203], v[168:171], v[60:63], v[188:203]
	v_exp_f32_e32 v45, v45
	v_exp_f32_e32 v46, v46
	v_exp_f32_e32 v47, v47
	s_add_i32 s90, s76, 512
	v_add_u32_e32 v84, s90, v107
	v_add_u32_e32 v85, 0, v84
	v_add_u32_e32 v86, 1, v84
	v_add_u32_e32 v87, 2, v84
	v_add_u32_e32 v88, 3, v84
	v_cmp_gt_u32_e64 s[30:31], s98, v85
	v_cmp_gt_u32_e64 s[36:37], s98, v86
	v_cmp_gt_u32_e64 s[78:79], s98, v87
	v_cmp_gt_u32_e64 s[50:51], s98, v88
	v_cndmask_b32_e64 v32, 0, v32, s[30:31]
	v_add_u32_e32 v85, 8, v84
	v_cmp_gt_u32_e64 s[30:31], s98, v85
	v_cndmask_b32_e64 v33, 0, v33, s[36:37]
	v_add_u32_e32 v86, 9, v84
	v_cmp_gt_u32_e64 s[36:37], s98, v86
	v_cndmask_b32_e64 v34, 0, v34, s[78:79]
	v_add_u32_e32 v87, 10, v84
	v_cmp_gt_u32_e64 s[78:79], s98, v87
	v_cndmask_b32_e64 v35, 0, v35, s[50:51]
	v_add_u32_e32 v88, 11, v84
	v_cmp_gt_u32_e64 s[50:51], s98, v88
	v_cndmask_b32_e64 v36, 0, v36, s[30:31]
	v_add_u32_e32 v85, 16, v84
	v_cmp_gt_u32_e64 s[30:31], s98, v85
	v_cndmask_b32_e64 v37, 0, v37, s[36:37]
	v_add_u32_e32 v86, 17, v84
	v_cmp_gt_u32_e64 s[36:37], s98, v86
	v_cndmask_b32_e64 v38, 0, v38, s[78:79]
	v_add_u32_e32 v87, 18, v84
	v_cmp_gt_u32_e64 s[78:79], s98, v87
	v_cndmask_b32_e64 v39, 0, v39, s[50:51]
	v_add_u32_e32 v88, 19, v84
	v_cmp_gt_u32_e64 s[50:51], s98, v88
	v_cndmask_b32_e64 v40, 0, v40, s[30:31]
	v_add_u32_e32 v85, 24, v84
	v_cmp_gt_u32_e64 s[30:31], s98, v85
	v_cndmask_b32_e64 v41, 0, v41, s[36:37]
	v_add_u32_e32 v86, 25, v84
	v_cmp_gt_u32_e64 s[36:37], s98, v86
	v_cndmask_b32_e64 v42, 0, v42, s[78:79]
	v_add_u32_e32 v87, 26, v84
	v_cmp_gt_u32_e64 s[78:79], s98, v87
	v_cndmask_b32_e64 v43, 0, v43, s[50:51]
	v_add_u32_e32 v88, 27, v84
	v_cmp_gt_u32_e64 s[50:51], s98, v88
	v_nop
	v_cndmask_b32_e64 v44, 0, v44, s[30:31]
	v_cndmask_b32_e64 v45, 0, v45, s[36:37]
	v_cndmask_b32_e64 v46, 0, v46, s[78:79]
	v_cndmask_b32_e64 v47, 0, v47, s[50:51]
	v_cvt_pk_bf16_f32 v64, v32, v33
	v_cvt_pk_bf16_f32 v65, v34, v35
	v_cvt_pk_bf16_f32 v66, v36, v37
	v_cvt_pk_bf16_f32 v67, v38, v39
	v_cvt_pk_bf16_f32 v68, v40, v41
	v_cvt_pk_bf16_f32 v69, v42, v43
	v_cvt_pk_bf16_f32 v70, v44, v45
	v_cvt_pk_bf16_f32 v71, v46, v47
	v_pk_add_f32 v[232:233], v[232:233], v[32:33]
	v_pk_add_f32 v[232:233], v[232:233], v[34:35]
	v_pk_add_f32 v[232:233], v[232:233], v[36:37]
	v_pk_add_f32 v[232:233], v[232:233], v[38:39]
	v_pk_add_f32 v[232:233], v[232:233], v[40:41]
	v_pk_add_f32 v[232:233], v[232:233], v[42:43]
	v_pk_add_f32 v[232:233], v[232:233], v[44:45]
	v_pk_add_f32 v[232:233], v[232:233], v[46:47]
	v_mov_b32_e32 v115, v229
	ds_read2_b32 v[32:33], v115 offset0:0 offset1:1
	ds_read2_b32 v[34:35], v115 offset0:2 offset1:3
	ds_read2_b32 v[36:37], v115 offset0:10 offset1:11
	ds_read2_b32 v[38:39], v115 offset0:12 offset1:13
	ds_read2_b32 v[40:41], v115 offset0:20 offset1:21
	ds_read2_b32 v[42:43], v115 offset0:22 offset1:23
	ds_read2_b32 v[44:45], v115 offset0:30 offset1:31
	ds_read2_b32 v[46:47], v115 offset0:32 offset1:33
	v_mfma_f32_32x32x16_bf16 v[0:15], v[64:67], v[72:75], v[0:15]
	v_mfma_f32_32x32x16_bf16 v[16:31], v[64:67], v[76:79], v[16:31]
	v_mfma_f32_32x32x16_bf16 v[0:15], v[68:71], v[220:223], v[0:15]
	v_mfma_f32_32x32x16_bf16 v[16:31], v[68:71], v[224:227], v[16:31]
	s_add_i32 s90, s76, -128
	v_add_u32_e32 v80, s90, v239
	v_add_u32_e32 v83, s90, v240
	v_add_u32_e32 v99, s90, v241
	v_add_u32_e32 v253, s90, v242
	v_add_u32_e32 v254, s90, v101
	v_add_u32_e32 v255, s90, v150
	v_med3_i32 v80, v80, 0, s99
	v_med3_i32 v83, v83, 0, s99
	v_med3_i32 v99, v99, 0, s99
	v_med3_i32 v253, v253, 0, s99
	v_med3_i32 v254, v254, 0, s99
	v_med3_i32 v255, v255, 0, s99
	v_mad_u32_u24 v80, v80, s100, v252
	v_mad_u32_u24 v83, v83, s100, v252
	v_mad_u32_u24 v99, v99, s100, v252
	v_mad_u32_u24 v253, v253, s100, v252
	v_mad_u32_u24 v254, v254, s100, v153
	v_mad_u32_u24 v255, v255, s100, v153
	global_load_dwordx4 v[156:159], v80, s[82:83]
	global_load_dwordx4 v[160:163], v83, s[82:83]
	global_load_dwordx4 v[164:167], v99, s[82:83]
	global_load_dwordx4 v[168:171], v253, s[82:83]
	global_load_dwordx4 v[172:175], v254, s[82:83] offset:768
	global_load_dwordx4 v[176:179], v255, s[82:83] offset:768
	global_load_dwordx4 v[180:183], v254, s[82:83] offset:832
	global_load_dwordx4 v[184:187], v255, s[82:83] offset:832
	ds_read_b64_tr_b16 v[72:73], v231
	ds_read_b64_tr_b16 v[74:75], v231 offset:512
	ds_read_b64_tr_b16 v[76:77], v231 offset:2048
	ds_read_b64_tr_b16 v[78:79], v231 offset:2560
	ds_read_b64_tr_b16 v[220:221], v231 offset:1024
	ds_read_b64_tr_b16 v[222:223], v231 offset:1536
	ds_read_b64_tr_b16 v[224:225], v231 offset:3072
	ds_read_b64_tr_b16 v[226:227], v231 offset:3584
	s_waitcnt vmcnt(8)
	ds_write_b128 v247, v[116:119]
	ds_write_b128 v247, v[120:123] offset:1024
	ds_write_b128 v111, v[124:127] offset:2048
	ds_write_b128 v111, v[128:131] offset:3072
	ds_read_b128 v[116:119], v248
	ds_read_b128 v[120:123], v249
	ds_read_b128 v[124:127], v250
	ds_read_b128 v[128:131], v251
	ds_write_b128 v112, v[132:135]
	ds_write_b128 v112, v[136:139] offset:1024
	ds_write_b128 v112, v[140:143] offset:2048
	ds_write_b128 v112, v[144:147] offset:3072
	v_exp_f32_e32 v188, v188
	v_exp_f32_e32 v189, v189
	v_exp_f32_e32 v190, v190
	v_exp_f32_e32 v191, v191
	v_exp_f32_e32 v192, v192
	v_exp_f32_e32 v193, v193
	s_waitcnt lgkmcnt(4)
	v_mfma_f32_32x32x16_bf16 v[32:47], v[116:119], v[48:51], v[32:47]
	v_exp_f32_e32 v194, v194
	v_exp_f32_e32 v195, v195
	v_mfma_f32_32x32x16_bf16 v[32:47], v[120:123], v[52:55], v[32:47]
	v_exp_f32_e32 v196, v196
	v_exp_f32_e32 v197, v197
	v_exp_f32_e32 v198, v198
	v_mfma_f32_32x32x16_bf16 v[32:47], v[124:127], v[56:59], v[32:47]
	v_exp_f32_e32 v199, v199
	v_exp_f32_e32 v200, v200
	v_mfma_f32_32x32x16_bf16 v[32:47], v[128:131], v[60:63], v[32:47]
	v_exp_f32_e32 v201, v201
	v_exp_f32_e32 v202, v202
	v_exp_f32_e32 v203, v203
	s_add_i32 s90, s76, 544
	v_add_u32_e32 v84, s90, v107
	v_add_u32_e32 v85, 0, v84
	v_add_u32_e32 v86, 1, v84
	v_add_u32_e32 v87, 2, v84
	v_add_u32_e32 v88, 3, v84
	v_cmp_gt_u32_e64 s[30:31], s98, v85
	v_cmp_gt_u32_e64 s[36:37], s98, v86
	v_cmp_gt_u32_e64 s[78:79], s98, v87
	v_cmp_gt_u32_e64 s[50:51], s98, v88
	v_cndmask_b32_e64 v188, 0, v188, s[30:31]
	v_add_u32_e32 v85, 8, v84
	v_cmp_gt_u32_e64 s[30:31], s98, v85
	v_cndmask_b32_e64 v189, 0, v189, s[36:37]
	v_add_u32_e32 v86, 9, v84
	v_cmp_gt_u32_e64 s[36:37], s98, v86
	v_cndmask_b32_e64 v190, 0, v190, s[78:79]
	v_add_u32_e32 v87, 10, v84
	v_cmp_gt_u32_e64 s[78:79], s98, v87
	v_cndmask_b32_e64 v191, 0, v191, s[50:51]
	v_add_u32_e32 v88, 11, v84
	v_cmp_gt_u32_e64 s[50:51], s98, v88
	v_cndmask_b32_e64 v192, 0, v192, s[30:31]
	v_add_u32_e32 v85, 16, v84
	v_cmp_gt_u32_e64 s[30:31], s98, v85
	v_cndmask_b32_e64 v193, 0, v193, s[36:37]
	v_add_u32_e32 v86, 17, v84
	v_cmp_gt_u32_e64 s[36:37], s98, v86
	v_cndmask_b32_e64 v194, 0, v194, s[78:79]
	v_add_u32_e32 v87, 18, v84
	v_cmp_gt_u32_e64 s[78:79], s98, v87
	v_cndmask_b32_e64 v195, 0, v195, s[50:51]
	v_add_u32_e32 v88, 19, v84
	v_cmp_gt_u32_e64 s[50:51], s98, v88
	v_cndmask_b32_e64 v196, 0, v196, s[30:31]
	v_add_u32_e32 v85, 24, v84
	v_cmp_gt_u32_e64 s[30:31], s98, v85
	v_cndmask_b32_e64 v197, 0, v197, s[36:37]
	v_add_u32_e32 v86, 25, v84
	v_cmp_gt_u32_e64 s[36:37], s98, v86
	v_cndmask_b32_e64 v198, 0, v198, s[78:79]
	v_add_u32_e32 v87, 26, v84
	v_cmp_gt_u32_e64 s[78:79], s98, v87
	v_cndmask_b32_e64 v199, 0, v199, s[50:51]
	v_add_u32_e32 v88, 27, v84
	v_cmp_gt_u32_e64 s[50:51], s98, v88
	v_nop
	v_cndmask_b32_e64 v200, 0, v200, s[30:31]
	v_cndmask_b32_e64 v201, 0, v201, s[36:37]
	v_cndmask_b32_e64 v202, 0, v202, s[78:79]
	v_cndmask_b32_e64 v203, 0, v203, s[50:51]
	v_cvt_pk_bf16_f32 v64, v188, v189
	v_cvt_pk_bf16_f32 v65, v190, v191
	v_cvt_pk_bf16_f32 v66, v192, v193
	v_cvt_pk_bf16_f32 v67, v194, v195
	v_cvt_pk_bf16_f32 v68, v196, v197
	v_cvt_pk_bf16_f32 v69, v198, v199
	v_cvt_pk_bf16_f32 v70, v200, v201
	v_cvt_pk_bf16_f32 v71, v202, v203
	v_pk_add_f32 v[232:233], v[232:233], v[188:189]
	v_pk_add_f32 v[232:233], v[232:233], v[190:191]
	v_pk_add_f32 v[232:233], v[232:233], v[192:193]
	v_pk_add_f32 v[232:233], v[232:233], v[194:195]
	v_pk_add_f32 v[232:233], v[232:233], v[196:197]
	v_pk_add_f32 v[232:233], v[232:233], v[198:199]
	v_pk_add_f32 v[232:233], v[232:233], v[200:201]
	v_pk_add_f32 v[232:233], v[232:233], v[202:203]
	ds_read2_b32 v[188:189], v115 offset0:40 offset1:41
	ds_read2_b32 v[190:191], v115 offset0:42 offset1:43
	ds_read2_b32 v[192:193], v115 offset0:50 offset1:51
	ds_read2_b32 v[194:195], v115 offset0:52 offset1:53
	ds_read2_b32 v[196:197], v115 offset0:60 offset1:61
	ds_read2_b32 v[198:199], v115 offset0:62 offset1:63
	ds_read2_b32 v[200:201], v115 offset0:70 offset1:71
	ds_read2_b32 v[202:203], v115 offset0:72 offset1:73
	v_mfma_f32_32x32x16_bf16 v[0:15], v[64:67], v[72:75], v[0:15]
	v_mfma_f32_32x32x16_bf16 v[16:31], v[64:67], v[76:79], v[16:31]
	v_mfma_f32_32x32x16_bf16 v[0:15], v[68:71], v[220:223], v[0:15]
	v_mfma_f32_32x32x16_bf16 v[16:31], v[68:71], v[224:227], v[16:31]
	s_add_i32 s90, s76, 0
	v_add_u32_e32 v80, s90, v239
	v_add_u32_e32 v83, s90, v240
	v_add_u32_e32 v99, s90, v241
	v_add_u32_e32 v253, s90, v242
	v_add_u32_e32 v254, s90, v101
	v_add_u32_e32 v255, s90, v150
	v_med3_i32 v80, v80, 0, s99
	v_med3_i32 v83, v83, 0, s99
	v_med3_i32 v99, v99, 0, s99
	v_med3_i32 v253, v253, 0, s99
	v_med3_i32 v254, v254, 0, s99
	v_med3_i32 v255, v255, 0, s99
	v_mad_u32_u24 v80, v80, s100, v252
	v_mad_u32_u24 v83, v83, s100, v252
	v_mad_u32_u24 v99, v99, s100, v252
	v_mad_u32_u24 v253, v253, s100, v252
	v_mad_u32_u24 v254, v254, s100, v153
	v_mad_u32_u24 v255, v255, s100, v153
	global_load_dwordx4 v[116:119], v80, s[82:83]
	global_load_dwordx4 v[120:123], v83, s[82:83]
	global_load_dwordx4 v[124:127], v99, s[82:83]
	global_load_dwordx4 v[128:131], v253, s[82:83]
	global_load_dwordx4 v[132:135], v254, s[82:83] offset:768
	global_load_dwordx4 v[136:139], v255, s[82:83] offset:768
	global_load_dwordx4 v[140:143], v254, s[82:83] offset:832
	global_load_dwordx4 v[144:147], v255, s[82:83] offset:832
	ds_read_b64_tr_b16 v[72:73], v231
	ds_read_b64_tr_b16 v[74:75], v231 offset:512
	ds_read_b64_tr_b16 v[76:77], v231 offset:2048
	ds_read_b64_tr_b16 v[78:79], v231 offset:2560
	ds_read_b64_tr_b16 v[220:221], v231 offset:1024
	ds_read_b64_tr_b16 v[222:223], v231 offset:1536
	ds_read_b64_tr_b16 v[224:225], v231 offset:3072
	ds_read_b64_tr_b16 v[226:227], v231 offset:3584
	s_waitcnt vmcnt(8)
	ds_write_b128 v247, v[156:159]
	ds_write_b128 v247, v[160:163] offset:1024
	ds_write_b128 v111, v[164:167] offset:2048
	ds_write_b128 v111, v[168:171] offset:3072
	ds_read_b128 v[156:159], v248
	ds_read_b128 v[160:163], v249
	ds_read_b128 v[164:167], v250
	ds_read_b128 v[168:171], v251
	ds_write_b128 v112, v[172:175]
	ds_write_b128 v112, v[176:179] offset:1024
	ds_write_b128 v112, v[180:183] offset:2048
	ds_write_b128 v112, v[184:187] offset:3072
	v_exp_f32_e32 v32, v32
	v_exp_f32_e32 v33, v33
	v_exp_f32_e32 v34, v34
	v_exp_f32_e32 v35, v35
	v_exp_f32_e32 v36, v36
	v_exp_f32_e32 v37, v37
	s_waitcnt lgkmcnt(4)
	v_mfma_f32_32x32x16_bf16 v[188:203], v[156:159], v[48:51], v[188:203]
	v_exp_f32_e32 v38, v38
	v_exp_f32_e32 v39, v39
	v_mfma_f32_32x32x16_bf16 v[188:203], v[160:163], v[52:55], v[188:203]
	v_exp_f32_e32 v40, v40
	v_exp_f32_e32 v41, v41
	v_exp_f32_e32 v42, v42
	v_mfma_f32_32x32x16_bf16 v[188:203], v[164:167], v[56:59], v[188:203]
	v_exp_f32_e32 v43, v43
	v_exp_f32_e32 v44, v44
	v_mfma_f32_32x32x16_bf16 v[188:203], v[168:171], v[60:63], v[188:203]
	v_exp_f32_e32 v45, v45
	v_exp_f32_e32 v46, v46
	v_exp_f32_e32 v47, v47
	s_add_i32 s90, s76, -256
	v_lshlrev_b32_e32 v84, 2, v107
	v_add_u32_e32 v84, s90, v84
	v_add_u32_e32 v85, 0, v84
	v_add_u32_e32 v86, 4, v84
	v_add_u32_e32 v87, 8, v84
	v_add_u32_e32 v88, 12, v84
	v_cmp_gt_u32_e64 s[30:31], s98, v85
	v_cmp_gt_u32_e64 s[36:37], s98, v86
	v_cmp_gt_u32_e64 s[78:79], s98, v87
	v_cmp_gt_u32_e64 s[50:51], s98, v88
	v_cndmask_b32_e64 v32, 0, v32, s[30:31]
	v_add_u32_e32 v85, 32, v84
	v_cmp_gt_u32_e64 s[30:31], s98, v85
	v_cndmask_b32_e64 v33, 0, v33, s[36:37]
	v_add_u32_e32 v86, 36, v84
	v_cmp_gt_u32_e64 s[36:37], s98, v86
	v_cndmask_b32_e64 v34, 0, v34, s[78:79]
	v_add_u32_e32 v87, 40, v84
	v_cmp_gt_u32_e64 s[78:79], s98, v87
	v_cndmask_b32_e64 v35, 0, v35, s[50:51]
	v_add_u32_e32 v88, 44, v84
	v_cmp_gt_u32_e64 s[50:51], s98, v88
	v_cndmask_b32_e64 v36, 0, v36, s[30:31]
	v_add_u32_e32 v85, 64, v84
	v_cmp_gt_u32_e64 s[30:31], s98, v85
	v_cndmask_b32_e64 v37, 0, v37, s[36:37]
	v_add_u32_e32 v86, 68, v84
	v_cmp_gt_u32_e64 s[36:37], s98, v86
	v_cndmask_b32_e64 v38, 0, v38, s[78:79]
	v_add_u32_e32 v87, 72, v84
	v_cmp_gt_u32_e64 s[78:79], s98, v87
	v_cndmask_b32_e64 v39, 0, v39, s[50:51]
	v_add_u32_e32 v88, 76, v84
	v_cmp_gt_u32_e64 s[50:51], s98, v88
	v_cndmask_b32_e64 v40, 0, v40, s[30:31]
	v_add_u32_e32 v85, 96, v84
	v_cmp_gt_u32_e64 s[30:31], s98, v85
	v_cndmask_b32_e64 v41, 0, v41, s[36:37]
	v_add_u32_e32 v86, 100, v84
	v_cmp_gt_u32_e64 s[36:37], s98, v86
	v_cndmask_b32_e64 v42, 0, v42, s[78:79]
	v_add_u32_e32 v87, 104, v84
	v_cmp_gt_u32_e64 s[78:79], s98, v87
	v_cndmask_b32_e64 v43, 0, v43, s[50:51]
	v_add_u32_e32 v88, 108, v84
	v_cmp_gt_u32_e64 s[50:51], s98, v88
	v_nop
	v_cndmask_b32_e64 v44, 0, v44, s[30:31]
	v_cndmask_b32_e64 v45, 0, v45, s[36:37]
	v_cndmask_b32_e64 v46, 0, v46, s[78:79]
	v_cndmask_b32_e64 v47, 0, v47, s[50:51]
	v_cvt_pk_bf16_f32 v64, v32, v33
	v_cvt_pk_bf16_f32 v65, v34, v35
	v_cvt_pk_bf16_f32 v66, v36, v37
	v_cvt_pk_bf16_f32 v67, v38, v39
	v_cvt_pk_bf16_f32 v68, v40, v41
	v_cvt_pk_bf16_f32 v69, v42, v43
	v_cvt_pk_bf16_f32 v70, v44, v45
	v_cvt_pk_bf16_f32 v71, v46, v47
	v_pk_add_f32 v[232:233], v[232:233], v[32:33]
	v_pk_add_f32 v[232:233], v[232:233], v[34:35]
	v_pk_add_f32 v[232:233], v[232:233], v[36:37]
	v_pk_add_f32 v[232:233], v[232:233], v[38:39]
	v_pk_add_f32 v[232:233], v[232:233], v[40:41]
	v_pk_add_f32 v[232:233], v[232:233], v[42:43]
	v_pk_add_f32 v[232:233], v[232:233], v[44:45]
	v_pk_add_f32 v[232:233], v[232:233], v[46:47]
	ds_read2_b32 v[32:33], v115 offset0:80 offset1:81
	ds_read2_b32 v[34:35], v115 offset0:82 offset1:83
	ds_read2_b32 v[36:37], v115 offset0:90 offset1:91
	ds_read2_b32 v[38:39], v115 offset0:92 offset1:93
	ds_read2_b32 v[40:41], v115 offset0:100 offset1:101
	ds_read2_b32 v[42:43], v115 offset0:102 offset1:103
	ds_read2_b32 v[44:45], v115 offset0:110 offset1:111
	ds_read2_b32 v[46:47], v115 offset0:112 offset1:113
	v_mfma_f32_32x32x16_bf16 v[0:15], v[64:67], v[72:75], v[0:15]
	v_mfma_f32_32x32x16_bf16 v[16:31], v[64:67], v[76:79], v[16:31]
	v_mfma_f32_32x32x16_bf16 v[0:15], v[68:71], v[220:223], v[0:15]
	v_mfma_f32_32x32x16_bf16 v[16:31], v[68:71], v[224:227], v[16:31]
	s_add_i32 s90, s76, 128
	v_add_u32_e32 v80, s90, v239
	v_add_u32_e32 v83, s90, v240
	v_add_u32_e32 v99, s90, v241
	v_add_u32_e32 v253, s90, v242
	v_add_u32_e32 v254, s90, v101
	v_add_u32_e32 v255, s90, v150
	v_med3_i32 v80, v80, 0, s99
	v_med3_i32 v83, v83, 0, s99
	v_med3_i32 v99, v99, 0, s99
	v_med3_i32 v253, v253, 0, s99
	v_med3_i32 v254, v254, 0, s99
	v_med3_i32 v255, v255, 0, s99
	v_mad_u32_u24 v80, v80, s100, v252
	v_mad_u32_u24 v83, v83, s100, v252
	v_mad_u32_u24 v99, v99, s100, v252
	v_mad_u32_u24 v253, v253, s100, v252
	v_mad_u32_u24 v254, v254, s100, v153
	v_mad_u32_u24 v255, v255, s100, v153
	global_load_dwordx4 v[156:159], v80, s[82:83]
	global_load_dwordx4 v[160:163], v83, s[82:83]
	global_load_dwordx4 v[164:167], v99, s[82:83]
	global_load_dwordx4 v[168:171], v253, s[82:83]
	global_load_dwordx4 v[172:175], v254, s[82:83] offset:768
	global_load_dwordx4 v[176:179], v255, s[82:83] offset:768
	global_load_dwordx4 v[180:183], v254, s[82:83] offset:832
	global_load_dwordx4 v[184:187], v255, s[82:83] offset:832
	ds_read_b64_tr_b16 v[72:73], v231
	ds_read_b64_tr_b16 v[74:75], v231 offset:512
	ds_read_b64_tr_b16 v[76:77], v231 offset:2048
	ds_read_b64_tr_b16 v[78:79], v231 offset:2560
	ds_read_b64_tr_b16 v[220:221], v231 offset:1024
	ds_read_b64_tr_b16 v[222:223], v231 offset:1536
	ds_read_b64_tr_b16 v[224:225], v231 offset:3072
	ds_read_b64_tr_b16 v[226:227], v231 offset:3584
	s_waitcnt vmcnt(8)
	ds_write_b128 v247, v[116:119]
	ds_write_b128 v247, v[120:123] offset:1024
	ds_write_b128 v111, v[124:127] offset:2048
	ds_write_b128 v111, v[128:131] offset:3072
	ds_read_b128 v[116:119], v248
	ds_read_b128 v[120:123], v249
	ds_read_b128 v[124:127], v250
	ds_read_b128 v[128:131], v251
	ds_write_b128 v112, v[132:135]
	ds_write_b128 v112, v[136:139] offset:1024
	ds_write_b128 v112, v[140:143] offset:2048
	ds_write_b128 v112, v[144:147] offset:3072
	v_exp_f32_e32 v188, v188
	v_exp_f32_e32 v189, v189
	v_exp_f32_e32 v190, v190
	v_exp_f32_e32 v191, v191
	v_exp_f32_e32 v192, v192
	v_exp_f32_e32 v193, v193
	s_waitcnt lgkmcnt(4)
	v_mfma_f32_32x32x16_bf16 v[32:47], v[116:119], v[48:51], v[32:47]
	v_exp_f32_e32 v194, v194
	v_exp_f32_e32 v195, v195
	v_mfma_f32_32x32x16_bf16 v[32:47], v[120:123], v[52:55], v[32:47]
	v_exp_f32_e32 v196, v196
	v_exp_f32_e32 v197, v197
	v_exp_f32_e32 v198, v198
	v_mfma_f32_32x32x16_bf16 v[32:47], v[124:127], v[56:59], v[32:47]
	v_exp_f32_e32 v199, v199
	v_exp_f32_e32 v200, v200
	v_mfma_f32_32x32x16_bf16 v[32:47], v[128:131], v[60:63], v[32:47]
	v_exp_f32_e32 v201, v201
	v_exp_f32_e32 v202, v202
	v_exp_f32_e32 v203, v203
	s_add_i32 s90, s76, -128
	v_lshlrev_b32_e32 v84, 2, v107
	v_add_u32_e32 v84, s90, v84
	v_add_u32_e32 v85, 0, v84
	v_add_u32_e32 v86, 4, v84
	v_add_u32_e32 v87, 8, v84
	v_add_u32_e32 v88, 12, v84
	v_cmp_gt_u32_e64 s[30:31], s98, v85
	v_cmp_gt_u32_e64 s[36:37], s98, v86
	v_cmp_gt_u32_e64 s[78:79], s98, v87
	v_cmp_gt_u32_e64 s[50:51], s98, v88
	v_cndmask_b32_e64 v188, 0, v188, s[30:31]
	v_add_u32_e32 v85, 32, v84
	v_cmp_gt_u32_e64 s[30:31], s98, v85
	v_cndmask_b32_e64 v189, 0, v189, s[36:37]
	v_add_u32_e32 v86, 36, v84
	v_cmp_gt_u32_e64 s[36:37], s98, v86
	v_cndmask_b32_e64 v190, 0, v190, s[78:79]
	v_add_u32_e32 v87, 40, v84
	v_cmp_gt_u32_e64 s[78:79], s98, v87
	v_cndmask_b32_e64 v191, 0, v191, s[50:51]
	v_add_u32_e32 v88, 44, v84
	v_cmp_gt_u32_e64 s[50:51], s98, v88
	v_cndmask_b32_e64 v192, 0, v192, s[30:31]
	v_add_u32_e32 v85, 64, v84
	v_cmp_gt_u32_e64 s[30:31], s98, v85
	v_cndmask_b32_e64 v193, 0, v193, s[36:37]
	v_add_u32_e32 v86, 68, v84
	v_cmp_gt_u32_e64 s[36:37], s98, v86
	v_cndmask_b32_e64 v194, 0, v194, s[78:79]
	v_add_u32_e32 v87, 72, v84
	v_cmp_gt_u32_e64 s[78:79], s98, v87
	v_cndmask_b32_e64 v195, 0, v195, s[50:51]
	v_add_u32_e32 v88, 76, v84
	v_cmp_gt_u32_e64 s[50:51], s98, v88
	v_cndmask_b32_e64 v196, 0, v196, s[30:31]
	v_add_u32_e32 v85, 96, v84
	v_cmp_gt_u32_e64 s[30:31], s98, v85
	v_cndmask_b32_e64 v197, 0, v197, s[36:37]
	v_add_u32_e32 v86, 100, v84
	v_cmp_gt_u32_e64 s[36:37], s98, v86
	v_cndmask_b32_e64 v198, 0, v198, s[78:79]
	v_add_u32_e32 v87, 104, v84
	v_cmp_gt_u32_e64 s[78:79], s98, v87
	v_cndmask_b32_e64 v199, 0, v199, s[50:51]
	v_add_u32_e32 v88, 108, v84
	v_cmp_gt_u32_e64 s[50:51], s98, v88
	v_nop
	v_cndmask_b32_e64 v200, 0, v200, s[30:31]
	v_cndmask_b32_e64 v201, 0, v201, s[36:37]
	v_cndmask_b32_e64 v202, 0, v202, s[78:79]
	v_cndmask_b32_e64 v203, 0, v203, s[50:51]
	v_cvt_pk_bf16_f32 v64, v188, v189
	v_cvt_pk_bf16_f32 v65, v190, v191
	v_cvt_pk_bf16_f32 v66, v192, v193
	v_cvt_pk_bf16_f32 v67, v194, v195
	v_cvt_pk_bf16_f32 v68, v196, v197
	v_cvt_pk_bf16_f32 v69, v198, v199
	v_cvt_pk_bf16_f32 v70, v200, v201
	v_cvt_pk_bf16_f32 v71, v202, v203
	v_pk_add_f32 v[232:233], v[232:233], v[188:189]
	v_pk_add_f32 v[232:233], v[232:233], v[190:191]
	v_pk_add_f32 v[232:233], v[232:233], v[192:193]
	v_pk_add_f32 v[232:233], v[232:233], v[194:195]
	v_pk_add_f32 v[232:233], v[232:233], v[196:197]
	v_pk_add_f32 v[232:233], v[232:233], v[198:199]
	v_pk_add_f32 v[232:233], v[232:233], v[200:201]
	v_pk_add_f32 v[232:233], v[232:233], v[202:203]
	ds_read2_b32 v[188:189], v115 offset0:120 offset1:121
	ds_read2_b32 v[190:191], v115 offset0:122 offset1:123
	ds_read2_b32 v[192:193], v115 offset0:130 offset1:131
	ds_read2_b32 v[194:195], v115 offset0:132 offset1:133
	ds_read2_b32 v[196:197], v115 offset0:140 offset1:141
	ds_read2_b32 v[198:199], v115 offset0:142 offset1:143
	ds_read2_b32 v[200:201], v115 offset0:150 offset1:151
	ds_read2_b32 v[202:203], v115 offset0:152 offset1:153
	v_mfma_f32_32x32x16_bf16 v[0:15], v[64:67], v[72:75], v[0:15]
	v_mfma_f32_32x32x16_bf16 v[16:31], v[64:67], v[76:79], v[16:31]
	v_mfma_f32_32x32x16_bf16 v[0:15], v[68:71], v[220:223], v[0:15]
	v_mfma_f32_32x32x16_bf16 v[16:31], v[68:71], v[224:227], v[16:31]
	s_add_i32 s90, s76, 256
	v_add_u32_e32 v80, s90, v239
	v_add_u32_e32 v83, s90, v240
	v_add_u32_e32 v99, s90, v241
	v_add_u32_e32 v253, s90, v242
	v_add_u32_e32 v254, s90, v101
	v_add_u32_e32 v255, s90, v150
	v_med3_i32 v80, v80, 0, s99
	v_med3_i32 v83, v83, 0, s99
	v_med3_i32 v99, v99, 0, s99
	v_med3_i32 v253, v253, 0, s99
	v_med3_i32 v254, v254, 0, s99
	v_med3_i32 v255, v255, 0, s99
	v_mad_u32_u24 v80, v80, s100, v252
	v_mad_u32_u24 v83, v83, s100, v252
	v_mad_u32_u24 v99, v99, s100, v252
	v_mad_u32_u24 v253, v253, s100, v252
	v_mad_u32_u24 v254, v254, s100, v153
	v_mad_u32_u24 v255, v255, s100, v153
	global_load_dwordx4 v[116:119], v80, s[82:83]
	global_load_dwordx4 v[120:123], v83, s[82:83]
	global_load_dwordx4 v[124:127], v99, s[82:83]
	global_load_dwordx4 v[128:131], v253, s[82:83]
	global_load_dwordx4 v[132:135], v254, s[82:83] offset:768
	global_load_dwordx4 v[136:139], v255, s[82:83] offset:768
	global_load_dwordx4 v[140:143], v254, s[82:83] offset:832
	global_load_dwordx4 v[144:147], v255, s[82:83] offset:832
	ds_read_b64_tr_b16 v[72:73], v231
	ds_read_b64_tr_b16 v[74:75], v231 offset:512
	ds_read_b64_tr_b16 v[76:77], v231 offset:2048
	ds_read_b64_tr_b16 v[78:79], v231 offset:2560
	ds_read_b64_tr_b16 v[220:221], v231 offset:1024
	ds_read_b64_tr_b16 v[222:223], v231 offset:1536
	ds_read_b64_tr_b16 v[224:225], v231 offset:3072
	ds_read_b64_tr_b16 v[226:227], v231 offset:3584
	s_waitcnt vmcnt(8)
	ds_write_b128 v247, v[156:159]
	ds_write_b128 v247, v[160:163] offset:1024
	ds_write_b128 v111, v[164:167] offset:2048
	ds_write_b128 v111, v[168:171] offset:3072
	ds_read_b128 v[156:159], v248
	ds_read_b128 v[160:163], v249
	ds_read_b128 v[164:167], v250
	ds_read_b128 v[168:171], v251
	ds_write_b128 v112, v[172:175]
	ds_write_b128 v112, v[176:179] offset:1024
	ds_write_b128 v112, v[180:183] offset:2048
	ds_write_b128 v112, v[184:187] offset:3072
	v_exp_f32_e32 v32, v32
	v_exp_f32_e32 v33, v33
	v_exp_f32_e32 v34, v34
	v_exp_f32_e32 v35, v35
	v_exp_f32_e32 v36, v36
	v_exp_f32_e32 v37, v37
	s_waitcnt lgkmcnt(4)
	v_mfma_f32_32x32x16_bf16 v[188:203], v[156:159], v[48:51], v[188:203]
	v_exp_f32_e32 v38, v38
	v_exp_f32_e32 v39, v39
	v_mfma_f32_32x32x16_bf16 v[188:203], v[160:163], v[52:55], v[188:203]
	v_exp_f32_e32 v40, v40
	v_exp_f32_e32 v41, v41
	v_exp_f32_e32 v42, v42
	v_mfma_f32_32x32x16_bf16 v[188:203], v[164:167], v[56:59], v[188:203]
	v_exp_f32_e32 v43, v43
	v_exp_f32_e32 v44, v44
	v_mfma_f32_32x32x16_bf16 v[188:203], v[168:171], v[60:63], v[188:203]
	v_exp_f32_e32 v45, v45
	v_exp_f32_e32 v46, v46
	v_exp_f32_e32 v47, v47
	s_add_i32 s90, s76, 0
	v_lshlrev_b32_e32 v84, 2, v107
	v_add_u32_e32 v84, s90, v84
	v_add_u32_e32 v85, 0, v84
	v_add_u32_e32 v86, 4, v84
	v_add_u32_e32 v87, 8, v84
	v_add_u32_e32 v88, 12, v84
	v_cmp_gt_u32_e64 s[30:31], s98, v85
	v_cmp_gt_u32_e64 s[36:37], s98, v86
	v_cmp_gt_u32_e64 s[78:79], s98, v87
	v_cmp_gt_u32_e64 s[50:51], s98, v88
	v_cndmask_b32_e64 v32, 0, v32, s[30:31]
	v_add_u32_e32 v85, 32, v84
	v_cmp_gt_u32_e64 s[30:31], s98, v85
	v_cndmask_b32_e64 v33, 0, v33, s[36:37]
	v_add_u32_e32 v86, 36, v84
	v_cmp_gt_u32_e64 s[36:37], s98, v86
	v_cndmask_b32_e64 v34, 0, v34, s[78:79]
	v_add_u32_e32 v87, 40, v84
	v_cmp_gt_u32_e64 s[78:79], s98, v87
	v_cndmask_b32_e64 v35, 0, v35, s[50:51]
	v_add_u32_e32 v88, 44, v84
	v_cmp_gt_u32_e64 s[50:51], s98, v88
	v_cndmask_b32_e64 v36, 0, v36, s[30:31]
	v_add_u32_e32 v85, 64, v84
	v_cmp_gt_u32_e64 s[30:31], s98, v85
	v_cndmask_b32_e64 v37, 0, v37, s[36:37]
	v_add_u32_e32 v86, 68, v84
	v_cmp_gt_u32_e64 s[36:37], s98, v86
	v_cndmask_b32_e64 v38, 0, v38, s[78:79]
	v_add_u32_e32 v87, 72, v84
	v_cmp_gt_u32_e64 s[78:79], s98, v87
	v_cndmask_b32_e64 v39, 0, v39, s[50:51]
	v_add_u32_e32 v88, 76, v84
	v_cmp_gt_u32_e64 s[50:51], s98, v88
	v_cndmask_b32_e64 v40, 0, v40, s[30:31]
	v_add_u32_e32 v85, 96, v84
	v_cmp_gt_u32_e64 s[30:31], s98, v85
	v_cndmask_b32_e64 v41, 0, v41, s[36:37]
	v_add_u32_e32 v86, 100, v84
	v_cmp_gt_u32_e64 s[36:37], s98, v86
	v_cndmask_b32_e64 v42, 0, v42, s[78:79]
	v_add_u32_e32 v87, 104, v84
	v_cmp_gt_u32_e64 s[78:79], s98, v87
	v_cndmask_b32_e64 v43, 0, v43, s[50:51]
	v_add_u32_e32 v88, 108, v84
	v_cmp_gt_u32_e64 s[50:51], s98, v88
	v_nop
	v_cndmask_b32_e64 v44, 0, v44, s[30:31]
	v_cndmask_b32_e64 v45, 0, v45, s[36:37]
	v_cndmask_b32_e64 v46, 0, v46, s[78:79]
	v_cndmask_b32_e64 v47, 0, v47, s[50:51]
	v_cvt_pk_bf16_f32 v64, v32, v33
	v_cvt_pk_bf16_f32 v65, v34, v35
	v_cvt_pk_bf16_f32 v66, v36, v37
	v_cvt_pk_bf16_f32 v67, v38, v39
	v_cvt_pk_bf16_f32 v68, v40, v41
	v_cvt_pk_bf16_f32 v69, v42, v43
	v_cvt_pk_bf16_f32 v70, v44, v45
	v_cvt_pk_bf16_f32 v71, v46, v47
	v_pk_add_f32 v[232:233], v[232:233], v[32:33]
	v_pk_add_f32 v[232:233], v[232:233], v[34:35]
	v_pk_add_f32 v[232:233], v[232:233], v[36:37]
	v_pk_add_f32 v[232:233], v[232:233], v[38:39]
	v_pk_add_f32 v[232:233], v[232:233], v[40:41]
	v_pk_add_f32 v[232:233], v[232:233], v[42:43]
	v_pk_add_f32 v[232:233], v[232:233], v[44:45]
	v_pk_add_f32 v[232:233], v[232:233], v[46:47]
	v_add_u32_e32 v115, 640, v115
	ds_read2_b32 v[32:33], v115 offset0:0 offset1:1
	ds_read2_b32 v[34:35], v115 offset0:2 offset1:3
	ds_read2_b32 v[36:37], v115 offset0:10 offset1:11
	ds_read2_b32 v[38:39], v115 offset0:12 offset1:13
	ds_read2_b32 v[40:41], v115 offset0:20 offset1:21
	ds_read2_b32 v[42:43], v115 offset0:22 offset1:23
	ds_read2_b32 v[44:45], v115 offset0:30 offset1:31
	ds_read2_b32 v[46:47], v115 offset0:32 offset1:33
	v_mfma_f32_32x32x16_bf16 v[0:15], v[64:67], v[72:75], v[0:15]
	v_mfma_f32_32x32x16_bf16 v[16:31], v[64:67], v[76:79], v[16:31]
	v_mfma_f32_32x32x16_bf16 v[0:15], v[68:71], v[220:223], v[0:15]
	v_mfma_f32_32x32x16_bf16 v[16:31], v[68:71], v[224:227], v[16:31]
	s_add_i32 s90, s76, 384
	v_add_u32_e32 v80, s90, v239
	v_add_u32_e32 v83, s90, v240
	v_add_u32_e32 v99, s90, v241
	v_add_u32_e32 v253, s90, v242
	v_add_u32_e32 v254, s90, v101
	v_add_u32_e32 v255, s90, v150
	v_med3_i32 v80, v80, 0, s99
	v_med3_i32 v83, v83, 0, s99
	v_med3_i32 v99, v99, 0, s99
	v_med3_i32 v253, v253, 0, s99
	v_med3_i32 v254, v254, 0, s99
	v_med3_i32 v255, v255, 0, s99
	v_mad_u32_u24 v80, v80, s100, v252
	v_mad_u32_u24 v83, v83, s100, v252
	v_mad_u32_u24 v99, v99, s100, v252
	v_mad_u32_u24 v253, v253, s100, v252
	v_mad_u32_u24 v254, v254, s100, v153
	v_mad_u32_u24 v255, v255, s100, v153
	global_load_dwordx4 v[156:159], v80, s[82:83]
	global_load_dwordx4 v[160:163], v83, s[82:83]
	global_load_dwordx4 v[164:167], v99, s[82:83]
	global_load_dwordx4 v[168:171], v253, s[82:83]
	global_load_dwordx4 v[172:175], v254, s[82:83] offset:768
	global_load_dwordx4 v[176:179], v255, s[82:83] offset:768
	global_load_dwordx4 v[180:183], v254, s[82:83] offset:832
	global_load_dwordx4 v[184:187], v255, s[82:83] offset:832
	ds_read_b64_tr_b16 v[72:73], v231
	ds_read_b64_tr_b16 v[74:75], v231 offset:512
	ds_read_b64_tr_b16 v[76:77], v231 offset:2048
	ds_read_b64_tr_b16 v[78:79], v231 offset:2560
	ds_read_b64_tr_b16 v[220:221], v231 offset:1024
	ds_read_b64_tr_b16 v[222:223], v231 offset:1536
	ds_read_b64_tr_b16 v[224:225], v231 offset:3072
	ds_read_b64_tr_b16 v[226:227], v231 offset:3584
	s_waitcnt vmcnt(8)
	ds_write_b128 v247, v[116:119]
	ds_write_b128 v247, v[120:123] offset:1024
	ds_write_b128 v111, v[124:127] offset:2048
	ds_write_b128 v111, v[128:131] offset:3072
	ds_read_b128 v[116:119], v248
	ds_read_b128 v[120:123], v249
	ds_read_b128 v[124:127], v250
	ds_read_b128 v[128:131], v251
	ds_write_b128 v112, v[132:135]
	ds_write_b128 v112, v[136:139] offset:1024
	ds_write_b128 v112, v[140:143] offset:2048
	ds_write_b128 v112, v[144:147] offset:3072
	v_exp_f32_e32 v188, v188
	v_exp_f32_e32 v189, v189
	v_exp_f32_e32 v190, v190
	v_exp_f32_e32 v191, v191
	v_exp_f32_e32 v192, v192
	v_exp_f32_e32 v193, v193
	s_waitcnt lgkmcnt(4)
	v_mfma_f32_32x32x16_bf16 v[32:47], v[116:119], v[48:51], v[32:47]
	v_exp_f32_e32 v194, v194
	v_exp_f32_e32 v195, v195
	v_mfma_f32_32x32x16_bf16 v[32:47], v[120:123], v[52:55], v[32:47]
	v_exp_f32_e32 v196, v196
	v_exp_f32_e32 v197, v197
	v_exp_f32_e32 v198, v198
	v_mfma_f32_32x32x16_bf16 v[32:47], v[124:127], v[56:59], v[32:47]
	v_exp_f32_e32 v199, v199
	v_exp_f32_e32 v200, v200
	v_mfma_f32_32x32x16_bf16 v[32:47], v[128:131], v[60:63], v[32:47]
	v_exp_f32_e32 v201, v201
	v_exp_f32_e32 v202, v202
	v_exp_f32_e32 v203, v203
	s_add_i32 s90, s76, 128
	v_lshlrev_b32_e32 v84, 2, v107
	v_add_u32_e32 v84, s90, v84
	v_add_u32_e32 v85, 0, v84
	v_add_u32_e32 v86, 4, v84
	v_add_u32_e32 v87, 8, v84
	v_add_u32_e32 v88, 12, v84
	v_cmp_gt_u32_e64 s[30:31], s98, v85
	v_cmp_gt_u32_e64 s[36:37], s98, v86
	v_cmp_gt_u32_e64 s[78:79], s98, v87
	v_cmp_gt_u32_e64 s[50:51], s98, v88
	v_cndmask_b32_e64 v188, 0, v188, s[30:31]
	v_add_u32_e32 v85, 32, v84
	v_cmp_gt_u32_e64 s[30:31], s98, v85
	v_cndmask_b32_e64 v189, 0, v189, s[36:37]
	v_add_u32_e32 v86, 36, v84
	v_cmp_gt_u32_e64 s[36:37], s98, v86
	v_cndmask_b32_e64 v190, 0, v190, s[78:79]
	v_add_u32_e32 v87, 40, v84
	v_cmp_gt_u32_e64 s[78:79], s98, v87
	v_cndmask_b32_e64 v191, 0, v191, s[50:51]
	v_add_u32_e32 v88, 44, v84
	v_cmp_gt_u32_e64 s[50:51], s98, v88
	v_cndmask_b32_e64 v192, 0, v192, s[30:31]
	v_add_u32_e32 v85, 64, v84
	v_cmp_gt_u32_e64 s[30:31], s98, v85
	v_cndmask_b32_e64 v193, 0, v193, s[36:37]
	v_add_u32_e32 v86, 68, v84
	v_cmp_gt_u32_e64 s[36:37], s98, v86
	v_cndmask_b32_e64 v194, 0, v194, s[78:79]
	v_add_u32_e32 v87, 72, v84
	v_cmp_gt_u32_e64 s[78:79], s98, v87
	v_cndmask_b32_e64 v195, 0, v195, s[50:51]
	v_add_u32_e32 v88, 76, v84
	v_cmp_gt_u32_e64 s[50:51], s98, v88
	v_cndmask_b32_e64 v196, 0, v196, s[30:31]
	v_add_u32_e32 v85, 96, v84
	v_cmp_gt_u32_e64 s[30:31], s98, v85
	v_cndmask_b32_e64 v197, 0, v197, s[36:37]
	v_add_u32_e32 v86, 100, v84
	v_cmp_gt_u32_e64 s[36:37], s98, v86
	v_cndmask_b32_e64 v198, 0, v198, s[78:79]
	v_add_u32_e32 v87, 104, v84
	v_cmp_gt_u32_e64 s[78:79], s98, v87
	v_cndmask_b32_e64 v199, 0, v199, s[50:51]
	v_add_u32_e32 v88, 108, v84
	v_cmp_gt_u32_e64 s[50:51], s98, v88
	v_nop
	v_cndmask_b32_e64 v200, 0, v200, s[30:31]
	v_cndmask_b32_e64 v201, 0, v201, s[36:37]
	v_cndmask_b32_e64 v202, 0, v202, s[78:79]
	v_cndmask_b32_e64 v203, 0, v203, s[50:51]
	v_cvt_pk_bf16_f32 v64, v188, v189
	v_cvt_pk_bf16_f32 v65, v190, v191
	v_cvt_pk_bf16_f32 v66, v192, v193
	v_cvt_pk_bf16_f32 v67, v194, v195
	v_cvt_pk_bf16_f32 v68, v196, v197
	v_cvt_pk_bf16_f32 v69, v198, v199
	v_cvt_pk_bf16_f32 v70, v200, v201
	v_cvt_pk_bf16_f32 v71, v202, v203
	v_pk_add_f32 v[232:233], v[232:233], v[188:189]
	v_pk_add_f32 v[232:233], v[232:233], v[190:191]
	v_pk_add_f32 v[232:233], v[232:233], v[192:193]
	v_pk_add_f32 v[232:233], v[232:233], v[194:195]
	v_pk_add_f32 v[232:233], v[232:233], v[196:197]
	v_pk_add_f32 v[232:233], v[232:233], v[198:199]
	v_pk_add_f32 v[232:233], v[232:233], v[200:201]
	v_pk_add_f32 v[232:233], v[232:233], v[202:203]
	ds_read2_b32 v[188:189], v115 offset0:40 offset1:41
	ds_read2_b32 v[190:191], v115 offset0:42 offset1:43
	ds_read2_b32 v[192:193], v115 offset0:50 offset1:51
	ds_read2_b32 v[194:195], v115 offset0:52 offset1:53
	ds_read2_b32 v[196:197], v115 offset0:60 offset1:61
	ds_read2_b32 v[198:199], v115 offset0:62 offset1:63
	ds_read2_b32 v[200:201], v115 offset0:70 offset1:71
	ds_read2_b32 v[202:203], v115 offset0:72 offset1:73
	v_mfma_f32_32x32x16_bf16 v[0:15], v[64:67], v[72:75], v[0:15]
	v_mfma_f32_32x32x16_bf16 v[16:31], v[64:67], v[76:79], v[16:31]
	v_mfma_f32_32x32x16_bf16 v[0:15], v[68:71], v[220:223], v[0:15]
	v_mfma_f32_32x32x16_bf16 v[16:31], v[68:71], v[224:227], v[16:31]
	s_add_i32 s90, s76, 512
	v_add_u32_e32 v80, s90, v239
	v_add_u32_e32 v83, s90, v240
	v_add_u32_e32 v99, s90, v241
	v_add_u32_e32 v253, s90, v242
	v_add_u32_e32 v254, s90, v101
	v_add_u32_e32 v255, s90, v150
	v_med3_i32 v80, v80, 0, s99
	v_med3_i32 v83, v83, 0, s99
	v_med3_i32 v99, v99, 0, s99
	v_med3_i32 v253, v253, 0, s99
	v_med3_i32 v254, v254, 0, s99
	v_med3_i32 v255, v255, 0, s99
	v_mad_u32_u24 v80, v80, s100, v252
	v_mad_u32_u24 v83, v83, s100, v252
	v_mad_u32_u24 v99, v99, s100, v252
	v_mad_u32_u24 v253, v253, s100, v252
	v_mad_u32_u24 v254, v254, s100, v153
	v_mad_u32_u24 v255, v255, s100, v153
	global_load_dwordx4 v[116:119], v80, s[82:83]
	global_load_dwordx4 v[120:123], v83, s[82:83]
	global_load_dwordx4 v[124:127], v99, s[82:83]
	global_load_dwordx4 v[128:131], v253, s[82:83]
	global_load_dwordx4 v[132:135], v254, s[82:83] offset:768
	global_load_dwordx4 v[136:139], v255, s[82:83] offset:768
	global_load_dwordx4 v[140:143], v254, s[82:83] offset:832
	global_load_dwordx4 v[144:147], v255, s[82:83] offset:832
	ds_read_b64_tr_b16 v[72:73], v231
	ds_read_b64_tr_b16 v[74:75], v231 offset:512
	ds_read_b64_tr_b16 v[76:77], v231 offset:2048
	ds_read_b64_tr_b16 v[78:79], v231 offset:2560
	ds_read_b64_tr_b16 v[220:221], v231 offset:1024
	ds_read_b64_tr_b16 v[222:223], v231 offset:1536
	ds_read_b64_tr_b16 v[224:225], v231 offset:3072
	ds_read_b64_tr_b16 v[226:227], v231 offset:3584
	s_waitcnt vmcnt(8)
	ds_write_b128 v247, v[156:159]
	ds_write_b128 v247, v[160:163] offset:1024
	ds_write_b128 v111, v[164:167] offset:2048
	ds_write_b128 v111, v[168:171] offset:3072
	ds_read_b128 v[156:159], v248
	ds_read_b128 v[160:163], v249
	ds_read_b128 v[164:167], v250
	ds_read_b128 v[168:171], v251
	ds_write_b128 v112, v[172:175]
	ds_write_b128 v112, v[176:179] offset:1024
	ds_write_b128 v112, v[180:183] offset:2048
	ds_write_b128 v112, v[184:187] offset:3072
	v_exp_f32_e32 v32, v32
	v_exp_f32_e32 v33, v33
	v_exp_f32_e32 v34, v34
	v_exp_f32_e32 v35, v35
	v_exp_f32_e32 v36, v36
	v_exp_f32_e32 v37, v37
	s_waitcnt lgkmcnt(4)
	v_mfma_f32_32x32x16_bf16 v[188:203], v[156:159], v[48:51], v[188:203]
	v_exp_f32_e32 v38, v38
	v_exp_f32_e32 v39, v39
	v_mfma_f32_32x32x16_bf16 v[188:203], v[160:163], v[52:55], v[188:203]
	v_exp_f32_e32 v40, v40
	v_exp_f32_e32 v41, v41
	v_exp_f32_e32 v42, v42
	v_mfma_f32_32x32x16_bf16 v[188:203], v[164:167], v[56:59], v[188:203]
	v_exp_f32_e32 v43, v43
	v_exp_f32_e32 v44, v44
	v_mfma_f32_32x32x16_bf16 v[188:203], v[168:171], v[60:63], v[188:203]
	v_exp_f32_e32 v45, v45
	v_exp_f32_e32 v46, v46
	v_exp_f32_e32 v47, v47
	s_add_i32 s90, s76, 256
	v_lshlrev_b32_e32 v84, 2, v107
	v_add_u32_e32 v84, s90, v84
	v_add_u32_e32 v85, 0, v84
	v_add_u32_e32 v86, 4, v84
	v_add_u32_e32 v87, 8, v84
	v_add_u32_e32 v88, 12, v84
	v_cmp_gt_u32_e64 s[30:31], s98, v85
	v_cmp_gt_u32_e64 s[36:37], s98, v86
	v_cmp_gt_u32_e64 s[78:79], s98, v87
	v_cmp_gt_u32_e64 s[50:51], s98, v88
	v_cndmask_b32_e64 v32, 0, v32, s[30:31]
	v_add_u32_e32 v85, 32, v84
	v_cmp_gt_u32_e64 s[30:31], s98, v85
	v_cndmask_b32_e64 v33, 0, v33, s[36:37]
	v_add_u32_e32 v86, 36, v84
	v_cmp_gt_u32_e64 s[36:37], s98, v86
	v_cndmask_b32_e64 v34, 0, v34, s[78:79]
	v_add_u32_e32 v87, 40, v84
	v_cmp_gt_u32_e64 s[78:79], s98, v87
	v_cndmask_b32_e64 v35, 0, v35, s[50:51]
	v_add_u32_e32 v88, 44, v84
	v_cmp_gt_u32_e64 s[50:51], s98, v88
	v_cndmask_b32_e64 v36, 0, v36, s[30:31]
	v_add_u32_e32 v85, 64, v84
	v_cmp_gt_u32_e64 s[30:31], s98, v85
	v_cndmask_b32_e64 v37, 0, v37, s[36:37]
	v_add_u32_e32 v86, 68, v84
	v_cmp_gt_u32_e64 s[36:37], s98, v86
	v_cndmask_b32_e64 v38, 0, v38, s[78:79]
	v_add_u32_e32 v87, 72, v84
	v_cmp_gt_u32_e64 s[78:79], s98, v87
	v_cndmask_b32_e64 v39, 0, v39, s[50:51]
	v_add_u32_e32 v88, 76, v84
	v_cmp_gt_u32_e64 s[50:51], s98, v88
	v_cndmask_b32_e64 v40, 0, v40, s[30:31]
	v_add_u32_e32 v85, 96, v84
	v_cmp_gt_u32_e64 s[30:31], s98, v85
	v_cndmask_b32_e64 v41, 0, v41, s[36:37]
	v_add_u32_e32 v86, 100, v84
	v_cmp_gt_u32_e64 s[36:37], s98, v86
	v_cndmask_b32_e64 v42, 0, v42, s[78:79]
	v_add_u32_e32 v87, 104, v84
	v_cmp_gt_u32_e64 s[78:79], s98, v87
	v_cndmask_b32_e64 v43, 0, v43, s[50:51]
	v_add_u32_e32 v88, 108, v84
	v_cmp_gt_u32_e64 s[50:51], s98, v88
	v_nop
	v_cndmask_b32_e64 v44, 0, v44, s[30:31]
	v_cndmask_b32_e64 v45, 0, v45, s[36:37]
	v_cndmask_b32_e64 v46, 0, v46, s[78:79]
	v_cndmask_b32_e64 v47, 0, v47, s[50:51]
	v_cvt_pk_bf16_f32 v64, v32, v33
	v_cvt_pk_bf16_f32 v65, v34, v35
	v_cvt_pk_bf16_f32 v66, v36, v37
	v_cvt_pk_bf16_f32 v67, v38, v39
	v_cvt_pk_bf16_f32 v68, v40, v41
	v_cvt_pk_bf16_f32 v69, v42, v43
	v_cvt_pk_bf16_f32 v70, v44, v45
	v_cvt_pk_bf16_f32 v71, v46, v47
	v_pk_add_f32 v[232:233], v[232:233], v[32:33]
	v_pk_add_f32 v[232:233], v[232:233], v[34:35]
	v_pk_add_f32 v[232:233], v[232:233], v[36:37]
	v_pk_add_f32 v[232:233], v[232:233], v[38:39]
	v_pk_add_f32 v[232:233], v[232:233], v[40:41]
	v_pk_add_f32 v[232:233], v[232:233], v[42:43]
	v_pk_add_f32 v[232:233], v[232:233], v[44:45]
	v_pk_add_f32 v[232:233], v[232:233], v[46:47]
	ds_read2_b32 v[32:33], v115 offset0:80 offset1:81
	ds_read2_b32 v[34:35], v115 offset0:82 offset1:83
	ds_read2_b32 v[36:37], v115 offset0:90 offset1:91
	ds_read2_b32 v[38:39], v115 offset0:92 offset1:93
	ds_read2_b32 v[40:41], v115 offset0:100 offset1:101
	ds_read2_b32 v[42:43], v115 offset0:102 offset1:103
	ds_read2_b32 v[44:45], v115 offset0:110 offset1:111
	ds_read2_b32 v[46:47], v115 offset0:112 offset1:113
	v_mfma_f32_32x32x16_bf16 v[0:15], v[64:67], v[72:75], v[0:15]
	v_mfma_f32_32x32x16_bf16 v[16:31], v[64:67], v[76:79], v[16:31]
	v_mfma_f32_32x32x16_bf16 v[0:15], v[68:71], v[220:223], v[0:15]
	v_mfma_f32_32x32x16_bf16 v[16:31], v[68:71], v[224:227], v[16:31]
	s_add_i32 s90, s76, 640
	v_add_u32_e32 v80, s90, v239
	v_add_u32_e32 v83, s90, v240
	v_add_u32_e32 v99, s90, v241
	v_add_u32_e32 v253, s90, v242
	v_add_u32_e32 v254, s90, v101
	v_add_u32_e32 v255, s90, v150
	v_med3_i32 v80, v80, 0, s99
	v_med3_i32 v83, v83, 0, s99
	v_med3_i32 v99, v99, 0, s99
	v_med3_i32 v253, v253, 0, s99
	v_med3_i32 v254, v254, 0, s99
	v_med3_i32 v255, v255, 0, s99
	v_mad_u32_u24 v80, v80, s100, v252
	v_mad_u32_u24 v83, v83, s100, v252
	v_mad_u32_u24 v99, v99, s100, v252
	v_mad_u32_u24 v253, v253, s100, v252
	v_mad_u32_u24 v254, v254, s100, v153
	v_mad_u32_u24 v255, v255, s100, v153
	global_load_dwordx4 v[156:159], v80, s[82:83]
	global_load_dwordx4 v[160:163], v83, s[82:83]
	global_load_dwordx4 v[164:167], v99, s[82:83]
	global_load_dwordx4 v[168:171], v253, s[82:83]
	global_load_dwordx4 v[172:175], v254, s[82:83] offset:768
	global_load_dwordx4 v[176:179], v255, s[82:83] offset:768
	global_load_dwordx4 v[180:183], v254, s[82:83] offset:832
	global_load_dwordx4 v[184:187], v255, s[82:83] offset:832
	ds_read_b64_tr_b16 v[72:73], v231
	ds_read_b64_tr_b16 v[74:75], v231 offset:512
	ds_read_b64_tr_b16 v[76:77], v231 offset:2048
	ds_read_b64_tr_b16 v[78:79], v231 offset:2560
	ds_read_b64_tr_b16 v[220:221], v231 offset:1024
	ds_read_b64_tr_b16 v[222:223], v231 offset:1536
	ds_read_b64_tr_b16 v[224:225], v231 offset:3072
	ds_read_b64_tr_b16 v[226:227], v231 offset:3584
	s_waitcnt vmcnt(8)
	ds_write_b128 v247, v[116:119]
	ds_write_b128 v247, v[120:123] offset:1024
	ds_write_b128 v111, v[124:127] offset:2048
	ds_write_b128 v111, v[128:131] offset:3072
	ds_read_b128 v[116:119], v248
	ds_read_b128 v[120:123], v249
	ds_read_b128 v[124:127], v250
	ds_read_b128 v[128:131], v251
	ds_write_b128 v112, v[132:135]
	ds_write_b128 v112, v[136:139] offset:1024
	ds_write_b128 v112, v[140:143] offset:2048
	ds_write_b128 v112, v[144:147] offset:3072
	v_exp_f32_e32 v188, v188
	v_exp_f32_e32 v189, v189
	v_exp_f32_e32 v190, v190
	v_exp_f32_e32 v191, v191
	v_exp_f32_e32 v192, v192
	v_exp_f32_e32 v193, v193
	s_waitcnt lgkmcnt(4)
	v_mfma_f32_32x32x16_bf16 v[32:47], v[116:119], v[48:51], v[32:47]
	v_exp_f32_e32 v194, v194
	v_exp_f32_e32 v195, v195
	v_mfma_f32_32x32x16_bf16 v[32:47], v[120:123], v[52:55], v[32:47]
	v_exp_f32_e32 v196, v196
	v_exp_f32_e32 v197, v197
	v_exp_f32_e32 v198, v198
	v_mfma_f32_32x32x16_bf16 v[32:47], v[124:127], v[56:59], v[32:47]
	v_exp_f32_e32 v199, v199
	v_exp_f32_e32 v200, v200
	v_mfma_f32_32x32x16_bf16 v[32:47], v[128:131], v[60:63], v[32:47]
	v_exp_f32_e32 v201, v201
	v_exp_f32_e32 v202, v202
	v_exp_f32_e32 v203, v203
	s_add_i32 s90, s76, 384
	v_lshlrev_b32_e32 v84, 2, v107
	v_add_u32_e32 v84, s90, v84
	v_add_u32_e32 v85, 0, v84
	v_add_u32_e32 v86, 4, v84
	v_add_u32_e32 v87, 8, v84
	v_add_u32_e32 v88, 12, v84
	v_cmp_gt_u32_e64 s[30:31], s98, v85
	v_cmp_gt_u32_e64 s[36:37], s98, v86
	v_cmp_gt_u32_e64 s[78:79], s98, v87
	v_cmp_gt_u32_e64 s[50:51], s98, v88
	v_cndmask_b32_e64 v188, 0, v188, s[30:31]
	v_add_u32_e32 v85, 32, v84
	v_cmp_gt_u32_e64 s[30:31], s98, v85
	v_cndmask_b32_e64 v189, 0, v189, s[36:37]
	v_add_u32_e32 v86, 36, v84
	v_cmp_gt_u32_e64 s[36:37], s98, v86
	v_cndmask_b32_e64 v190, 0, v190, s[78:79]
	v_add_u32_e32 v87, 40, v84
	v_cmp_gt_u32_e64 s[78:79], s98, v87
	v_cndmask_b32_e64 v191, 0, v191, s[50:51]
	v_add_u32_e32 v88, 44, v84
	v_cmp_gt_u32_e64 s[50:51], s98, v88
	v_cndmask_b32_e64 v192, 0, v192, s[30:31]
	v_add_u32_e32 v85, 64, v84
	v_cmp_gt_u32_e64 s[30:31], s98, v85
	v_cndmask_b32_e64 v193, 0, v193, s[36:37]
	v_add_u32_e32 v86, 68, v84
	v_cmp_gt_u32_e64 s[36:37], s98, v86
	v_cndmask_b32_e64 v194, 0, v194, s[78:79]
	v_add_u32_e32 v87, 72, v84
	v_cmp_gt_u32_e64 s[78:79], s98, v87
	v_cndmask_b32_e64 v195, 0, v195, s[50:51]
	v_add_u32_e32 v88, 76, v84
	v_cmp_gt_u32_e64 s[50:51], s98, v88
	v_cndmask_b32_e64 v196, 0, v196, s[30:31]
	v_add_u32_e32 v85, 96, v84
	v_cmp_gt_u32_e64 s[30:31], s98, v85
	v_cndmask_b32_e64 v197, 0, v197, s[36:37]
	v_add_u32_e32 v86, 100, v84
	v_cmp_gt_u32_e64 s[36:37], s98, v86
	v_cndmask_b32_e64 v198, 0, v198, s[78:79]
	v_add_u32_e32 v87, 104, v84
	v_cmp_gt_u32_e64 s[78:79], s98, v87
	v_cndmask_b32_e64 v199, 0, v199, s[50:51]
	v_add_u32_e32 v88, 108, v84
	v_cmp_gt_u32_e64 s[50:51], s98, v88
	v_nop
	v_cndmask_b32_e64 v200, 0, v200, s[30:31]
	v_cndmask_b32_e64 v201, 0, v201, s[36:37]
	v_cndmask_b32_e64 v202, 0, v202, s[78:79]
	v_cndmask_b32_e64 v203, 0, v203, s[50:51]
	v_cvt_pk_bf16_f32 v64, v188, v189
	v_cvt_pk_bf16_f32 v65, v190, v191
	v_cvt_pk_bf16_f32 v66, v192, v193
	v_cvt_pk_bf16_f32 v67, v194, v195
	v_cvt_pk_bf16_f32 v68, v196, v197
	v_cvt_pk_bf16_f32 v69, v198, v199
	v_cvt_pk_bf16_f32 v70, v200, v201
	v_cvt_pk_bf16_f32 v71, v202, v203
	v_pk_add_f32 v[232:233], v[232:233], v[188:189]
	v_pk_add_f32 v[232:233], v[232:233], v[190:191]
	v_pk_add_f32 v[232:233], v[232:233], v[192:193]
	v_pk_add_f32 v[232:233], v[232:233], v[194:195]
	v_pk_add_f32 v[232:233], v[232:233], v[196:197]
	v_pk_add_f32 v[232:233], v[232:233], v[198:199]
	v_pk_add_f32 v[232:233], v[232:233], v[200:201]
	v_pk_add_f32 v[232:233], v[232:233], v[202:203]
	ds_read2_b32 v[188:189], v115 offset0:120 offset1:121
	ds_read2_b32 v[190:191], v115 offset0:122 offset1:123
	ds_read2_b32 v[192:193], v115 offset0:130 offset1:131
	ds_read2_b32 v[194:195], v115 offset0:132 offset1:133
	ds_read2_b32 v[196:197], v115 offset0:140 offset1:141
	ds_read2_b32 v[198:199], v115 offset0:142 offset1:143
	ds_read2_b32 v[200:201], v115 offset0:150 offset1:151
	ds_read2_b32 v[202:203], v115 offset0:152 offset1:153
	v_mfma_f32_32x32x16_bf16 v[0:15], v[64:67], v[72:75], v[0:15]
	v_mfma_f32_32x32x16_bf16 v[16:31], v[64:67], v[76:79], v[16:31]
	v_mfma_f32_32x32x16_bf16 v[0:15], v[68:71], v[220:223], v[0:15]
	v_mfma_f32_32x32x16_bf16 v[16:31], v[68:71], v[224:227], v[16:31]
	s_add_i32 s90, s76, -1024
	v_add_u32_e32 v80, s90, v243
	v_add_u32_e32 v83, s90, v244
	v_add_u32_e32 v99, s90, v245
	v_add_u32_e32 v253, s90, v246
	v_add_u32_e32 v254, s90, v148
	v_add_u32_e32 v255, s90, v151
	v_med3_i32 v80, v80, 0, s99
	v_med3_i32 v83, v83, 0, s99
	v_med3_i32 v99, v99, 0, s99
	v_med3_i32 v253, v253, 0, s99
	v_med3_i32 v254, v254, 0, s99
	v_med3_i32 v255, v255, 0, s99
	v_mad_u32_u24 v80, v80, s100, v252
	v_mad_u32_u24 v83, v83, s100, v252
	v_mad_u32_u24 v99, v99, s100, v252
	v_mad_u32_u24 v253, v253, s100, v252
	v_mad_u32_u24 v254, v254, s100, v153
	v_mad_u32_u24 v255, v255, s100, v153
	global_load_dwordx4 v[116:119], v80, s[82:83]
	global_load_dwordx4 v[120:123], v83, s[82:83]
	global_load_dwordx4 v[124:127], v99, s[82:83]
	global_load_dwordx4 v[128:131], v253, s[82:83]
	global_load_dwordx4 v[132:135], v254, s[82:83] offset:768
	global_load_dwordx4 v[136:139], v255, s[82:83] offset:768
	global_load_dwordx4 v[140:143], v254, s[82:83] offset:832
	global_load_dwordx4 v[144:147], v255, s[82:83] offset:832
	ds_read_b64_tr_b16 v[72:73], v231
	ds_read_b64_tr_b16 v[74:75], v231 offset:512
	ds_read_b64_tr_b16 v[76:77], v231 offset:2048
	ds_read_b64_tr_b16 v[78:79], v231 offset:2560
	ds_read_b64_tr_b16 v[220:221], v231 offset:1024
	ds_read_b64_tr_b16 v[222:223], v231 offset:1536
	ds_read_b64_tr_b16 v[224:225], v231 offset:3072
	ds_read_b64_tr_b16 v[226:227], v231 offset:3584
	s_waitcnt vmcnt(8)
	ds_write_b128 v247, v[156:159]
	ds_write_b128 v247, v[160:163] offset:1024
	ds_write_b128 v111, v[164:167] offset:2048
	ds_write_b128 v111, v[168:171] offset:3072
	ds_read_b128 v[156:159], v248
	ds_read_b128 v[160:163], v249
	ds_read_b128 v[164:167], v250
	ds_read_b128 v[168:171], v251
	ds_write_b128 v112, v[172:175]
	ds_write_b128 v112, v[176:179] offset:1024
	ds_write_b128 v112, v[180:183] offset:2048
	ds_write_b128 v112, v[184:187] offset:3072
	v_exp_f32_e32 v32, v32
	v_exp_f32_e32 v33, v33
	v_exp_f32_e32 v34, v34
	v_exp_f32_e32 v35, v35
	v_exp_f32_e32 v36, v36
	v_exp_f32_e32 v37, v37
	s_waitcnt lgkmcnt(4)
	v_mfma_f32_32x32x16_bf16 v[188:203], v[156:159], v[48:51], v[188:203]
	v_exp_f32_e32 v38, v38
	v_exp_f32_e32 v39, v39
	v_mfma_f32_32x32x16_bf16 v[188:203], v[160:163], v[52:55], v[188:203]
	v_exp_f32_e32 v40, v40
	v_exp_f32_e32 v41, v41
	v_exp_f32_e32 v42, v42
	v_mfma_f32_32x32x16_bf16 v[188:203], v[164:167], v[56:59], v[188:203]
	v_exp_f32_e32 v43, v43
	v_exp_f32_e32 v44, v44
	v_mfma_f32_32x32x16_bf16 v[188:203], v[168:171], v[60:63], v[188:203]
	v_exp_f32_e32 v45, v45
	v_exp_f32_e32 v46, v46
	v_exp_f32_e32 v47, v47
	s_add_i32 s90, s76, 512
	v_lshlrev_b32_e32 v84, 2, v107
	v_add_u32_e32 v84, s90, v84
	v_add_u32_e32 v85, 0, v84
	v_add_u32_e32 v86, 4, v84
	v_add_u32_e32 v87, 8, v84
	v_add_u32_e32 v88, 12, v84
	v_cmp_gt_u32_e64 s[30:31], s98, v85
	v_cmp_gt_u32_e64 s[36:37], s98, v86
	v_cmp_gt_u32_e64 s[78:79], s98, v87
	v_cmp_gt_u32_e64 s[50:51], s98, v88
	v_cndmask_b32_e64 v32, 0, v32, s[30:31]
	v_add_u32_e32 v85, 32, v84
	v_cmp_gt_u32_e64 s[30:31], s98, v85
	v_cndmask_b32_e64 v33, 0, v33, s[36:37]
	v_add_u32_e32 v86, 36, v84
	v_cmp_gt_u32_e64 s[36:37], s98, v86
	v_cndmask_b32_e64 v34, 0, v34, s[78:79]
	v_add_u32_e32 v87, 40, v84
	v_cmp_gt_u32_e64 s[78:79], s98, v87
	v_cndmask_b32_e64 v35, 0, v35, s[50:51]
	v_add_u32_e32 v88, 44, v84
	v_cmp_gt_u32_e64 s[50:51], s98, v88
	v_cndmask_b32_e64 v36, 0, v36, s[30:31]
	v_add_u32_e32 v85, 64, v84
	v_cmp_gt_u32_e64 s[30:31], s98, v85
	v_cndmask_b32_e64 v37, 0, v37, s[36:37]
	v_add_u32_e32 v86, 68, v84
	v_cmp_gt_u32_e64 s[36:37], s98, v86
	v_cndmask_b32_e64 v38, 0, v38, s[78:79]
	v_add_u32_e32 v87, 72, v84
	v_cmp_gt_u32_e64 s[78:79], s98, v87
	v_cndmask_b32_e64 v39, 0, v39, s[50:51]
	v_add_u32_e32 v88, 76, v84
	v_cmp_gt_u32_e64 s[50:51], s98, v88
	v_cndmask_b32_e64 v40, 0, v40, s[30:31]
	v_add_u32_e32 v85, 96, v84
	v_cmp_gt_u32_e64 s[30:31], s98, v85
	v_cndmask_b32_e64 v41, 0, v41, s[36:37]
	v_add_u32_e32 v86, 100, v84
	v_cmp_gt_u32_e64 s[36:37], s98, v86
	v_cndmask_b32_e64 v42, 0, v42, s[78:79]
	v_add_u32_e32 v87, 104, v84
	v_cmp_gt_u32_e64 s[78:79], s98, v87
	v_cndmask_b32_e64 v43, 0, v43, s[50:51]
	v_add_u32_e32 v88, 108, v84
	v_cmp_gt_u32_e64 s[50:51], s98, v88
	v_nop
	v_cndmask_b32_e64 v44, 0, v44, s[30:31]
	v_cndmask_b32_e64 v45, 0, v45, s[36:37]
	v_cndmask_b32_e64 v46, 0, v46, s[78:79]
	v_cndmask_b32_e64 v47, 0, v47, s[50:51]
	v_cvt_pk_bf16_f32 v64, v32, v33
	v_cvt_pk_bf16_f32 v65, v34, v35
	v_cvt_pk_bf16_f32 v66, v36, v37
	v_cvt_pk_bf16_f32 v67, v38, v39
	v_cvt_pk_bf16_f32 v68, v40, v41
	v_cvt_pk_bf16_f32 v69, v42, v43
	v_cvt_pk_bf16_f32 v70, v44, v45
	v_cvt_pk_bf16_f32 v71, v46, v47
	v_pk_add_f32 v[232:233], v[232:233], v[32:33]
	v_pk_add_f32 v[232:233], v[232:233], v[34:35]
	v_pk_add_f32 v[232:233], v[232:233], v[36:37]
	v_pk_add_f32 v[232:233], v[232:233], v[38:39]
	v_pk_add_f32 v[232:233], v[232:233], v[40:41]
	v_pk_add_f32 v[232:233], v[232:233], v[42:43]
	v_pk_add_f32 v[232:233], v[232:233], v[44:45]
	v_pk_add_f32 v[232:233], v[232:233], v[46:47]
	v_mov_b32_e32 v115, v230
	ds_read2_b32 v[32:33], v115 offset0:0 offset1:1
	ds_read2_b32 v[34:35], v115 offset0:2 offset1:3
	ds_read2_b32 v[36:37], v115 offset0:8 offset1:9
	ds_read2_b32 v[38:39], v115 offset0:10 offset1:11
	ds_read2_b32 v[40:41], v115 offset0:16 offset1:17
	ds_read2_b32 v[42:43], v115 offset0:18 offset1:19
	ds_read2_b32 v[44:45], v115 offset0:24 offset1:25
	ds_read2_b32 v[46:47], v115 offset0:26 offset1:27
	v_mfma_f32_32x32x16_bf16 v[0:15], v[64:67], v[72:75], v[0:15]
	v_mfma_f32_32x32x16_bf16 v[16:31], v[64:67], v[76:79], v[16:31]
	v_mfma_f32_32x32x16_bf16 v[0:15], v[68:71], v[220:223], v[0:15]
	v_mfma_f32_32x32x16_bf16 v[16:31], v[68:71], v[224:227], v[16:31]
	s_add_i32 s90, s76, -512
	v_add_u32_e32 v80, s90, v243
	v_add_u32_e32 v83, s90, v244
	v_add_u32_e32 v99, s90, v245
	v_add_u32_e32 v253, s90, v246
	v_add_u32_e32 v254, s90, v148
	v_add_u32_e32 v255, s90, v151
	v_med3_i32 v80, v80, 0, s99
	v_med3_i32 v83, v83, 0, s99
	v_med3_i32 v99, v99, 0, s99
	v_med3_i32 v253, v253, 0, s99
	v_med3_i32 v254, v254, 0, s99
	v_med3_i32 v255, v255, 0, s99
	v_mad_u32_u24 v80, v80, s100, v252
	v_mad_u32_u24 v83, v83, s100, v252
	v_mad_u32_u24 v99, v99, s100, v252
	v_mad_u32_u24 v253, v253, s100, v252
	v_mad_u32_u24 v254, v254, s100, v153
	v_mad_u32_u24 v255, v255, s100, v153
	global_load_dwordx4 v[156:159], v80, s[82:83]
	global_load_dwordx4 v[160:163], v83, s[82:83]
	global_load_dwordx4 v[164:167], v99, s[82:83]
	global_load_dwordx4 v[168:171], v253, s[82:83]
	global_load_dwordx4 v[172:175], v254, s[82:83] offset:768
	global_load_dwordx4 v[176:179], v255, s[82:83] offset:768
	global_load_dwordx4 v[180:183], v254, s[82:83] offset:832
	global_load_dwordx4 v[184:187], v255, s[82:83] offset:832
	ds_read_b64_tr_b16 v[72:73], v231
	ds_read_b64_tr_b16 v[74:75], v231 offset:512
	ds_read_b64_tr_b16 v[76:77], v231 offset:2048
	ds_read_b64_tr_b16 v[78:79], v231 offset:2560
	ds_read_b64_tr_b16 v[220:221], v231 offset:1024
	ds_read_b64_tr_b16 v[222:223], v231 offset:1536
	ds_read_b64_tr_b16 v[224:225], v231 offset:3072
	ds_read_b64_tr_b16 v[226:227], v231 offset:3584
	s_waitcnt vmcnt(8)
	ds_write_b128 v247, v[116:119]
	ds_write_b128 v247, v[120:123] offset:1024
	ds_write_b128 v111, v[124:127] offset:2048
	ds_write_b128 v111, v[128:131] offset:3072
	ds_read_b128 v[116:119], v248
	ds_read_b128 v[120:123], v249
	ds_read_b128 v[124:127], v250
	ds_read_b128 v[128:131], v251
	ds_write_b128 v112, v[132:135]
	ds_write_b128 v112, v[136:139] offset:1024
	ds_write_b128 v112, v[140:143] offset:2048
	ds_write_b128 v112, v[144:147] offset:3072
	v_exp_f32_e32 v188, v188
	v_exp_f32_e32 v189, v189
	v_exp_f32_e32 v190, v190
	v_exp_f32_e32 v191, v191
	v_exp_f32_e32 v192, v192
	v_exp_f32_e32 v193, v193
	s_waitcnt lgkmcnt(4)
	v_mfma_f32_32x32x16_bf16 v[32:47], v[116:119], v[48:51], v[32:47]
	v_exp_f32_e32 v194, v194
	v_exp_f32_e32 v195, v195
	v_mfma_f32_32x32x16_bf16 v[32:47], v[120:123], v[52:55], v[32:47]
	v_exp_f32_e32 v196, v196
	v_exp_f32_e32 v197, v197
	v_exp_f32_e32 v198, v198
	v_mfma_f32_32x32x16_bf16 v[32:47], v[124:127], v[56:59], v[32:47]
	v_exp_f32_e32 v199, v199
	v_exp_f32_e32 v200, v200
	v_mfma_f32_32x32x16_bf16 v[32:47], v[128:131], v[60:63], v[32:47]
	v_exp_f32_e32 v201, v201
	v_exp_f32_e32 v202, v202
	v_exp_f32_e32 v203, v203
	s_add_i32 s90, s76, 640
	v_lshlrev_b32_e32 v84, 2, v107
	v_add_u32_e32 v84, s90, v84
	v_add_u32_e32 v85, 0, v84
	v_add_u32_e32 v86, 4, v84
	v_add_u32_e32 v87, 8, v84
	v_add_u32_e32 v88, 12, v84
	v_cmp_gt_u32_e64 s[30:31], s98, v85
	v_cmp_gt_u32_e64 s[36:37], s98, v86
	v_cmp_gt_u32_e64 s[78:79], s98, v87
	v_cmp_gt_u32_e64 s[50:51], s98, v88
	v_cndmask_b32_e64 v188, 0, v188, s[30:31]
	v_add_u32_e32 v85, 32, v84
	v_cmp_gt_u32_e64 s[30:31], s98, v85
	v_cndmask_b32_e64 v189, 0, v189, s[36:37]
	v_add_u32_e32 v86, 36, v84
	v_cmp_gt_u32_e64 s[36:37], s98, v86
	v_cndmask_b32_e64 v190, 0, v190, s[78:79]
	v_add_u32_e32 v87, 40, v84
	v_cmp_gt_u32_e64 s[78:79], s98, v87
	v_cndmask_b32_e64 v191, 0, v191, s[50:51]
	v_add_u32_e32 v88, 44, v84
	v_cmp_gt_u32_e64 s[50:51], s98, v88
	v_cndmask_b32_e64 v192, 0, v192, s[30:31]
	v_add_u32_e32 v85, 64, v84
	v_cmp_gt_u32_e64 s[30:31], s98, v85
	v_cndmask_b32_e64 v193, 0, v193, s[36:37]
	v_add_u32_e32 v86, 68, v84
	v_cmp_gt_u32_e64 s[36:37], s98, v86
	v_cndmask_b32_e64 v194, 0, v194, s[78:79]
	v_add_u32_e32 v87, 72, v84
	v_cmp_gt_u32_e64 s[78:79], s98, v87
	v_cndmask_b32_e64 v195, 0, v195, s[50:51]
	v_add_u32_e32 v88, 76, v84
	v_cmp_gt_u32_e64 s[50:51], s98, v88
	v_cndmask_b32_e64 v196, 0, v196, s[30:31]
	v_add_u32_e32 v85, 96, v84
	v_cmp_gt_u32_e64 s[30:31], s98, v85
	v_cndmask_b32_e64 v197, 0, v197, s[36:37]
	v_add_u32_e32 v86, 100, v84
	v_cmp_gt_u32_e64 s[36:37], s98, v86
	v_cndmask_b32_e64 v198, 0, v198, s[78:79]
	v_add_u32_e32 v87, 104, v84
	v_cmp_gt_u32_e64 s[78:79], s98, v87
	v_cndmask_b32_e64 v199, 0, v199, s[50:51]
	v_add_u32_e32 v88, 108, v84
	v_cmp_gt_u32_e64 s[50:51], s98, v88
	v_nop
	v_cndmask_b32_e64 v200, 0, v200, s[30:31]
	v_cndmask_b32_e64 v201, 0, v201, s[36:37]
	v_cndmask_b32_e64 v202, 0, v202, s[78:79]
	v_cndmask_b32_e64 v203, 0, v203, s[50:51]
	v_cvt_pk_bf16_f32 v64, v188, v189
	v_cvt_pk_bf16_f32 v65, v190, v191
	v_cvt_pk_bf16_f32 v66, v192, v193
	v_cvt_pk_bf16_f32 v67, v194, v195
	v_cvt_pk_bf16_f32 v68, v196, v197
	v_cvt_pk_bf16_f32 v69, v198, v199
	v_cvt_pk_bf16_f32 v70, v200, v201
	v_cvt_pk_bf16_f32 v71, v202, v203
	v_pk_add_f32 v[232:233], v[232:233], v[188:189]
	v_pk_add_f32 v[232:233], v[232:233], v[190:191]
	v_pk_add_f32 v[232:233], v[232:233], v[192:193]
	v_pk_add_f32 v[232:233], v[232:233], v[194:195]
	v_pk_add_f32 v[232:233], v[232:233], v[196:197]
	v_pk_add_f32 v[232:233], v[232:233], v[198:199]
	v_pk_add_f32 v[232:233], v[232:233], v[200:201]
	v_pk_add_f32 v[232:233], v[232:233], v[202:203]
	ds_read2_b32 v[188:189], v115 offset0:32 offset1:33
	ds_read2_b32 v[190:191], v115 offset0:34 offset1:35
	ds_read2_b32 v[192:193], v115 offset0:40 offset1:41
	ds_read2_b32 v[194:195], v115 offset0:42 offset1:43
	ds_read2_b32 v[196:197], v115 offset0:48 offset1:49
	ds_read2_b32 v[198:199], v115 offset0:50 offset1:51
	ds_read2_b32 v[200:201], v115 offset0:56 offset1:57
	ds_read2_b32 v[202:203], v115 offset0:58 offset1:59
	v_mfma_f32_32x32x16_bf16 v[0:15], v[64:67], v[72:75], v[0:15]
	v_mfma_f32_32x32x16_bf16 v[16:31], v[64:67], v[76:79], v[16:31]
	v_mfma_f32_32x32x16_bf16 v[0:15], v[68:71], v[220:223], v[0:15]
	v_mfma_f32_32x32x16_bf16 v[16:31], v[68:71], v[224:227], v[16:31]
	s_add_i32 s90, s76, 0
	v_add_u32_e32 v80, s90, v243
	v_add_u32_e32 v83, s90, v244
	v_add_u32_e32 v99, s90, v245
	v_add_u32_e32 v253, s90, v246
	v_add_u32_e32 v254, s90, v148
	v_add_u32_e32 v255, s90, v151
	v_med3_i32 v80, v80, 0, s99
	v_med3_i32 v83, v83, 0, s99
	v_med3_i32 v99, v99, 0, s99
	v_med3_i32 v253, v253, 0, s99
	v_med3_i32 v254, v254, 0, s99
	v_med3_i32 v255, v255, 0, s99
	v_mad_u32_u24 v80, v80, s100, v252
	v_mad_u32_u24 v83, v83, s100, v252
	v_mad_u32_u24 v99, v99, s100, v252
	v_mad_u32_u24 v253, v253, s100, v252
	v_mad_u32_u24 v254, v254, s100, v153
	v_mad_u32_u24 v255, v255, s100, v153
	global_load_dwordx4 v[116:119], v80, s[82:83]
	global_load_dwordx4 v[120:123], v83, s[82:83]
	global_load_dwordx4 v[124:127], v99, s[82:83]
	global_load_dwordx4 v[128:131], v253, s[82:83]
	global_load_dwordx4 v[132:135], v254, s[82:83] offset:768
	global_load_dwordx4 v[136:139], v255, s[82:83] offset:768
	global_load_dwordx4 v[140:143], v254, s[82:83] offset:832
	global_load_dwordx4 v[144:147], v255, s[82:83] offset:832
	ds_read_b64_tr_b16 v[72:73], v231
	ds_read_b64_tr_b16 v[74:75], v231 offset:512
	ds_read_b64_tr_b16 v[76:77], v231 offset:2048
	ds_read_b64_tr_b16 v[78:79], v231 offset:2560
	ds_read_b64_tr_b16 v[220:221], v231 offset:1024
	ds_read_b64_tr_b16 v[222:223], v231 offset:1536
	ds_read_b64_tr_b16 v[224:225], v231 offset:3072
	ds_read_b64_tr_b16 v[226:227], v231 offset:3584
	s_waitcnt vmcnt(8)
	ds_write_b128 v247, v[156:159]
	ds_write_b128 v247, v[160:163] offset:1024
	ds_write_b128 v111, v[164:167] offset:2048
	ds_write_b128 v111, v[168:171] offset:3072
	ds_read_b128 v[156:159], v248
	ds_read_b128 v[160:163], v249
	ds_read_b128 v[164:167], v250
	ds_read_b128 v[168:171], v251
	ds_write_b128 v112, v[172:175]
	ds_write_b128 v112, v[176:179] offset:1024
	ds_write_b128 v112, v[180:183] offset:2048
	ds_write_b128 v112, v[184:187] offset:3072
	v_exp_f32_e32 v32, v32
	v_exp_f32_e32 v33, v33
	v_exp_f32_e32 v34, v34
	v_exp_f32_e32 v35, v35
	v_exp_f32_e32 v36, v36
	v_exp_f32_e32 v37, v37
	s_waitcnt lgkmcnt(4)
	v_mfma_f32_32x32x16_bf16 v[188:203], v[156:159], v[48:51], v[188:203]
	v_exp_f32_e32 v38, v38
	v_exp_f32_e32 v39, v39
	v_mfma_f32_32x32x16_bf16 v[188:203], v[160:163], v[52:55], v[188:203]
	v_exp_f32_e32 v40, v40
	v_exp_f32_e32 v41, v41
	v_exp_f32_e32 v42, v42
	v_mfma_f32_32x32x16_bf16 v[188:203], v[164:167], v[56:59], v[188:203]
	v_exp_f32_e32 v43, v43
	v_exp_f32_e32 v44, v44
	v_mfma_f32_32x32x16_bf16 v[188:203], v[168:171], v[60:63], v[188:203]
	v_exp_f32_e32 v45, v45
	v_exp_f32_e32 v46, v46
	v_exp_f32_e32 v47, v47
	s_add_i32 s90, s76, -1024
	v_lshlrev_b32_e32 v84, 4, v107
	v_add_u32_e32 v84, s90, v84
	v_add_u32_e32 v85, 0, v84
	v_add_u32_e32 v86, 16, v84
	v_add_u32_e32 v87, 32, v84
	v_add_u32_e32 v88, 48, v84
	v_cmp_gt_u32_e64 s[30:31], s98, v85
	v_cmp_gt_u32_e64 s[36:37], s98, v86
	v_cmp_gt_u32_e64 s[78:79], s98, v87
	v_cmp_gt_u32_e64 s[50:51], s98, v88
	v_cndmask_b32_e64 v32, 0, v32, s[30:31]
	v_add_u32_e32 v85, 128, v84
	v_cmp_gt_u32_e64 s[30:31], s98, v85
	v_cndmask_b32_e64 v33, 0, v33, s[36:37]
	v_add_u32_e32 v86, 144, v84
	v_cmp_gt_u32_e64 s[36:37], s98, v86
	v_cndmask_b32_e64 v34, 0, v34, s[78:79]
	v_add_u32_e32 v87, 160, v84
	v_cmp_gt_u32_e64 s[78:79], s98, v87
	v_cndmask_b32_e64 v35, 0, v35, s[50:51]
	v_add_u32_e32 v88, 176, v84
	v_cmp_gt_u32_e64 s[50:51], s98, v88
	v_cndmask_b32_e64 v36, 0, v36, s[30:31]
	v_add_u32_e32 v85, 256, v84
	v_cmp_gt_u32_e64 s[30:31], s98, v85
	v_cndmask_b32_e64 v37, 0, v37, s[36:37]
	v_add_u32_e32 v86, 272, v84
	v_cmp_gt_u32_e64 s[36:37], s98, v86
	v_cndmask_b32_e64 v38, 0, v38, s[78:79]
	v_add_u32_e32 v87, 288, v84
	v_cmp_gt_u32_e64 s[78:79], s98, v87
	v_cndmask_b32_e64 v39, 0, v39, s[50:51]
	v_add_u32_e32 v88, 304, v84
	v_cmp_gt_u32_e64 s[50:51], s98, v88
	v_cndmask_b32_e64 v40, 0, v40, s[30:31]
	v_add_u32_e32 v85, 384, v84
	v_cmp_gt_u32_e64 s[30:31], s98, v85
	v_cndmask_b32_e64 v41, 0, v41, s[36:37]
	v_add_u32_e32 v86, 400, v84
	v_cmp_gt_u32_e64 s[36:37], s98, v86
	v_cndmask_b32_e64 v42, 0, v42, s[78:79]
	v_add_u32_e32 v87, 416, v84
	v_cmp_gt_u32_e64 s[78:79], s98, v87
	v_cndmask_b32_e64 v43, 0, v43, s[50:51]
	v_add_u32_e32 v88, 432, v84
	v_cmp_gt_u32_e64 s[50:51], s98, v88
	v_nop
	v_cndmask_b32_e64 v44, 0, v44, s[30:31]
	v_cndmask_b32_e64 v45, 0, v45, s[36:37]
	v_cndmask_b32_e64 v46, 0, v46, s[78:79]
	v_cndmask_b32_e64 v47, 0, v47, s[50:51]
	v_cvt_pk_bf16_f32 v64, v32, v33
	v_cvt_pk_bf16_f32 v65, v34, v35
	v_cvt_pk_bf16_f32 v66, v36, v37
	v_cvt_pk_bf16_f32 v67, v38, v39
	v_cvt_pk_bf16_f32 v68, v40, v41
	v_cvt_pk_bf16_f32 v69, v42, v43
	v_cvt_pk_bf16_f32 v70, v44, v45
	v_cvt_pk_bf16_f32 v71, v46, v47
	v_pk_add_f32 v[232:233], v[232:233], v[32:33]
	v_pk_add_f32 v[232:233], v[232:233], v[34:35]
	v_pk_add_f32 v[232:233], v[232:233], v[36:37]
	v_pk_add_f32 v[232:233], v[232:233], v[38:39]
	v_pk_add_f32 v[232:233], v[232:233], v[40:41]
	v_pk_add_f32 v[232:233], v[232:233], v[42:43]
	v_pk_add_f32 v[232:233], v[232:233], v[44:45]
	v_pk_add_f32 v[232:233], v[232:233], v[46:47]
	ds_read2_b32 v[32:33], v115 offset0:64 offset1:65
	ds_read2_b32 v[34:35], v115 offset0:66 offset1:67
	ds_read2_b32 v[36:37], v115 offset0:72 offset1:73
	ds_read2_b32 v[38:39], v115 offset0:74 offset1:75
	ds_read2_b32 v[40:41], v115 offset0:80 offset1:81
	ds_read2_b32 v[42:43], v115 offset0:82 offset1:83
	ds_read2_b32 v[44:45], v115 offset0:88 offset1:89
	ds_read2_b32 v[46:47], v115 offset0:90 offset1:91
	v_mfma_f32_32x32x16_bf16 v[0:15], v[64:67], v[72:75], v[0:15]
	v_mfma_f32_32x32x16_bf16 v[16:31], v[64:67], v[76:79], v[16:31]
	v_mfma_f32_32x32x16_bf16 v[0:15], v[68:71], v[220:223], v[0:15]
	v_mfma_f32_32x32x16_bf16 v[16:31], v[68:71], v[224:227], v[16:31]
	s_add_i32 s90, s76, 512
	v_add_u32_e32 v80, s90, v243
	v_add_u32_e32 v83, s90, v244
	v_add_u32_e32 v99, s90, v245
	v_add_u32_e32 v253, s90, v246
	v_add_u32_e32 v254, s90, v148
	v_add_u32_e32 v255, s90, v151
	v_med3_i32 v80, v80, 0, s99
	v_med3_i32 v83, v83, 0, s99
	v_med3_i32 v99, v99, 0, s99
	v_med3_i32 v253, v253, 0, s99
	v_med3_i32 v254, v254, 0, s99
	v_med3_i32 v255, v255, 0, s99
	v_mad_u32_u24 v80, v80, s100, v252
	v_mad_u32_u24 v83, v83, s100, v252
	v_mad_u32_u24 v99, v99, s100, v252
	v_mad_u32_u24 v253, v253, s100, v252
	v_mad_u32_u24 v254, v254, s100, v153
	v_mad_u32_u24 v255, v255, s100, v153
	global_load_dwordx4 v[156:159], v80, s[82:83]
	global_load_dwordx4 v[160:163], v83, s[82:83]
	global_load_dwordx4 v[164:167], v99, s[82:83]
	global_load_dwordx4 v[168:171], v253, s[82:83]
	global_load_dwordx4 v[172:175], v254, s[82:83] offset:768
	global_load_dwordx4 v[176:179], v255, s[82:83] offset:768
	global_load_dwordx4 v[180:183], v254, s[82:83] offset:832
	global_load_dwordx4 v[184:187], v255, s[82:83] offset:832
	ds_read_b64_tr_b16 v[72:73], v231
	ds_read_b64_tr_b16 v[74:75], v231 offset:512
	ds_read_b64_tr_b16 v[76:77], v231 offset:2048
	ds_read_b64_tr_b16 v[78:79], v231 offset:2560
	ds_read_b64_tr_b16 v[220:221], v231 offset:1024
	ds_read_b64_tr_b16 v[222:223], v231 offset:1536
	ds_read_b64_tr_b16 v[224:225], v231 offset:3072
	ds_read_b64_tr_b16 v[226:227], v231 offset:3584
	s_waitcnt vmcnt(8)
	ds_write_b128 v247, v[116:119]
	ds_write_b128 v247, v[120:123] offset:1024
	ds_write_b128 v111, v[124:127] offset:2048
	ds_write_b128 v111, v[128:131] offset:3072
	ds_read_b128 v[116:119], v248
	ds_read_b128 v[120:123], v249
	ds_read_b128 v[124:127], v250
	ds_read_b128 v[128:131], v251
	ds_write_b128 v112, v[132:135]
	ds_write_b128 v112, v[136:139] offset:1024
	ds_write_b128 v112, v[140:143] offset:2048
	ds_write_b128 v112, v[144:147] offset:3072
	v_exp_f32_e32 v188, v188
	v_exp_f32_e32 v189, v189
	v_exp_f32_e32 v190, v190
	v_exp_f32_e32 v191, v191
	v_exp_f32_e32 v192, v192
	v_exp_f32_e32 v193, v193
	s_waitcnt lgkmcnt(4)
	v_mfma_f32_32x32x16_bf16 v[32:47], v[116:119], v[48:51], v[32:47]
	v_exp_f32_e32 v194, v194
	v_exp_f32_e32 v195, v195
	v_mfma_f32_32x32x16_bf16 v[32:47], v[120:123], v[52:55], v[32:47]
	v_exp_f32_e32 v196, v196
	v_exp_f32_e32 v197, v197
	v_exp_f32_e32 v198, v198
	v_mfma_f32_32x32x16_bf16 v[32:47], v[124:127], v[56:59], v[32:47]
	v_exp_f32_e32 v199, v199
	v_exp_f32_e32 v200, v200
	v_mfma_f32_32x32x16_bf16 v[32:47], v[128:131], v[60:63], v[32:47]
	v_exp_f32_e32 v201, v201
	v_exp_f32_e32 v202, v202
	v_exp_f32_e32 v203, v203
	s_add_i32 s90, s76, -512
	v_lshlrev_b32_e32 v84, 4, v107
	v_add_u32_e32 v84, s90, v84
	v_add_u32_e32 v85, 0, v84
	v_add_u32_e32 v86, 16, v84
	v_add_u32_e32 v87, 32, v84
	v_add_u32_e32 v88, 48, v84
	v_cmp_gt_u32_e64 s[30:31], s98, v85
	v_cmp_gt_u32_e64 s[36:37], s98, v86
	v_cmp_gt_u32_e64 s[78:79], s98, v87
	v_cmp_gt_u32_e64 s[50:51], s98, v88
	v_cndmask_b32_e64 v188, 0, v188, s[30:31]
	v_add_u32_e32 v85, 128, v84
	v_cmp_gt_u32_e64 s[30:31], s98, v85
	v_cndmask_b32_e64 v189, 0, v189, s[36:37]
	v_add_u32_e32 v86, 144, v84
	v_cmp_gt_u32_e64 s[36:37], s98, v86
	v_cndmask_b32_e64 v190, 0, v190, s[78:79]
	v_add_u32_e32 v87, 160, v84
	v_cmp_gt_u32_e64 s[78:79], s98, v87
	v_cndmask_b32_e64 v191, 0, v191, s[50:51]
	v_add_u32_e32 v88, 176, v84
	v_cmp_gt_u32_e64 s[50:51], s98, v88
	v_cndmask_b32_e64 v192, 0, v192, s[30:31]
	v_add_u32_e32 v85, 256, v84
	v_cmp_gt_u32_e64 s[30:31], s98, v85
	v_cndmask_b32_e64 v193, 0, v193, s[36:37]
	v_add_u32_e32 v86, 272, v84
	v_cmp_gt_u32_e64 s[36:37], s98, v86
	v_cndmask_b32_e64 v194, 0, v194, s[78:79]
	v_add_u32_e32 v87, 288, v84
	v_cmp_gt_u32_e64 s[78:79], s98, v87
	v_cndmask_b32_e64 v195, 0, v195, s[50:51]
	v_add_u32_e32 v88, 304, v84
	v_cmp_gt_u32_e64 s[50:51], s98, v88
	v_cndmask_b32_e64 v196, 0, v196, s[30:31]
	v_add_u32_e32 v85, 384, v84
	v_cmp_gt_u32_e64 s[30:31], s98, v85
	v_cndmask_b32_e64 v197, 0, v197, s[36:37]
	v_add_u32_e32 v86, 400, v84
	v_cmp_gt_u32_e64 s[36:37], s98, v86
	v_cndmask_b32_e64 v198, 0, v198, s[78:79]
	v_add_u32_e32 v87, 416, v84
	v_cmp_gt_u32_e64 s[78:79], s98, v87
	v_cndmask_b32_e64 v199, 0, v199, s[50:51]
	v_add_u32_e32 v88, 432, v84
	v_cmp_gt_u32_e64 s[50:51], s98, v88
	v_nop
	v_cndmask_b32_e64 v200, 0, v200, s[30:31]
	v_cndmask_b32_e64 v201, 0, v201, s[36:37]
	v_cndmask_b32_e64 v202, 0, v202, s[78:79]
	v_cndmask_b32_e64 v203, 0, v203, s[50:51]
	v_cvt_pk_bf16_f32 v64, v188, v189
	v_cvt_pk_bf16_f32 v65, v190, v191
	v_cvt_pk_bf16_f32 v66, v192, v193
	v_cvt_pk_bf16_f32 v67, v194, v195
	v_cvt_pk_bf16_f32 v68, v196, v197
	v_cvt_pk_bf16_f32 v69, v198, v199
	v_cvt_pk_bf16_f32 v70, v200, v201
	v_cvt_pk_bf16_f32 v71, v202, v203
	v_pk_add_f32 v[232:233], v[232:233], v[188:189]
	v_pk_add_f32 v[232:233], v[232:233], v[190:191]
	v_pk_add_f32 v[232:233], v[232:233], v[192:193]
	v_pk_add_f32 v[232:233], v[232:233], v[194:195]
	v_pk_add_f32 v[232:233], v[232:233], v[196:197]
	v_pk_add_f32 v[232:233], v[232:233], v[198:199]
	v_pk_add_f32 v[232:233], v[232:233], v[200:201]
	v_pk_add_f32 v[232:233], v[232:233], v[202:203]
	ds_read2_b32 v[188:189], v115 offset0:96 offset1:97
	ds_read2_b32 v[190:191], v115 offset0:98 offset1:99
	ds_read2_b32 v[192:193], v115 offset0:104 offset1:105
	ds_read2_b32 v[194:195], v115 offset0:106 offset1:107
	ds_read2_b32 v[196:197], v115 offset0:112 offset1:113
	ds_read2_b32 v[198:199], v115 offset0:114 offset1:115
	ds_read2_b32 v[200:201], v115 offset0:120 offset1:121
	ds_read2_b32 v[202:203], v115 offset0:122 offset1:123
	v_mfma_f32_32x32x16_bf16 v[0:15], v[64:67], v[72:75], v[0:15]
	v_mfma_f32_32x32x16_bf16 v[16:31], v[64:67], v[76:79], v[16:31]
	v_mfma_f32_32x32x16_bf16 v[0:15], v[68:71], v[220:223], v[0:15]
	v_mfma_f32_32x32x16_bf16 v[16:31], v[68:71], v[224:227], v[16:31]
	s_add_i32 s90, s76, 1024
	v_add_u32_e32 v80, s90, v243
	v_add_u32_e32 v83, s90, v244
	v_add_u32_e32 v99, s90, v245
	v_add_u32_e32 v253, s90, v246
	v_add_u32_e32 v254, s90, v148
	v_add_u32_e32 v255, s90, v151
	v_med3_i32 v80, v80, 0, s99
	v_med3_i32 v83, v83, 0, s99
	v_med3_i32 v99, v99, 0, s99
	v_med3_i32 v253, v253, 0, s99
	v_med3_i32 v254, v254, 0, s99
	v_med3_i32 v255, v255, 0, s99
	v_mad_u32_u24 v80, v80, s100, v252
	v_mad_u32_u24 v83, v83, s100, v252
	v_mad_u32_u24 v99, v99, s100, v252
	v_mad_u32_u24 v253, v253, s100, v252
	v_mad_u32_u24 v254, v254, s100, v153
	v_mad_u32_u24 v255, v255, s100, v153
	global_load_dwordx4 v[116:119], v80, s[82:83]
	global_load_dwordx4 v[120:123], v83, s[82:83]
	global_load_dwordx4 v[124:127], v99, s[82:83]
	global_load_dwordx4 v[128:131], v253, s[82:83]
	global_load_dwordx4 v[132:135], v254, s[82:83] offset:768
	global_load_dwordx4 v[136:139], v255, s[82:83] offset:768
	global_load_dwordx4 v[140:143], v254, s[82:83] offset:832
	global_load_dwordx4 v[144:147], v255, s[82:83] offset:832
	ds_read_b64_tr_b16 v[72:73], v231
	ds_read_b64_tr_b16 v[74:75], v231 offset:512
	ds_read_b64_tr_b16 v[76:77], v231 offset:2048
	ds_read_b64_tr_b16 v[78:79], v231 offset:2560
	ds_read_b64_tr_b16 v[220:221], v231 offset:1024
	ds_read_b64_tr_b16 v[222:223], v231 offset:1536
	ds_read_b64_tr_b16 v[224:225], v231 offset:3072
	ds_read_b64_tr_b16 v[226:227], v231 offset:3584
	s_waitcnt vmcnt(8)
	ds_write_b128 v247, v[156:159]
	ds_write_b128 v247, v[160:163] offset:1024
	ds_write_b128 v111, v[164:167] offset:2048
	ds_write_b128 v111, v[168:171] offset:3072
	ds_read_b128 v[156:159], v248
	ds_read_b128 v[160:163], v249
	ds_read_b128 v[164:167], v250
	ds_read_b128 v[168:171], v251
	ds_write_b128 v112, v[172:175]
	ds_write_b128 v112, v[176:179] offset:1024
	ds_write_b128 v112, v[180:183] offset:2048
	ds_write_b128 v112, v[184:187] offset:3072
	v_exp_f32_e32 v32, v32
	v_exp_f32_e32 v33, v33
	v_exp_f32_e32 v34, v34
	v_exp_f32_e32 v35, v35
	v_exp_f32_e32 v36, v36
	v_exp_f32_e32 v37, v37
	s_waitcnt lgkmcnt(4)
	v_mfma_f32_32x32x16_bf16 v[188:203], v[156:159], v[48:51], v[188:203]
	v_exp_f32_e32 v38, v38
	v_exp_f32_e32 v39, v39
	v_mfma_f32_32x32x16_bf16 v[188:203], v[160:163], v[52:55], v[188:203]
	v_exp_f32_e32 v40, v40
	v_exp_f32_e32 v41, v41
	v_exp_f32_e32 v42, v42
	v_mfma_f32_32x32x16_bf16 v[188:203], v[164:167], v[56:59], v[188:203]
	v_exp_f32_e32 v43, v43
	v_exp_f32_e32 v44, v44
	v_mfma_f32_32x32x16_bf16 v[188:203], v[168:171], v[60:63], v[188:203]
	v_exp_f32_e32 v45, v45
	v_exp_f32_e32 v46, v46
	v_exp_f32_e32 v47, v47
	s_add_i32 s90, s76, 0
	v_lshlrev_b32_e32 v84, 4, v107
	v_add_u32_e32 v84, s90, v84
	v_add_u32_e32 v85, 0, v84
	v_add_u32_e32 v86, 16, v84
	v_add_u32_e32 v87, 32, v84
	v_add_u32_e32 v88, 48, v84
	v_cmp_gt_u32_e64 s[30:31], s98, v85
	v_cmp_gt_u32_e64 s[36:37], s98, v86
	v_cmp_gt_u32_e64 s[78:79], s98, v87
	v_cmp_gt_u32_e64 s[50:51], s98, v88
	v_cndmask_b32_e64 v32, 0, v32, s[30:31]
	v_add_u32_e32 v85, 128, v84
	v_cmp_gt_u32_e64 s[30:31], s98, v85
	v_cndmask_b32_e64 v33, 0, v33, s[36:37]
	v_add_u32_e32 v86, 144, v84
	v_cmp_gt_u32_e64 s[36:37], s98, v86
	v_cndmask_b32_e64 v34, 0, v34, s[78:79]
	v_add_u32_e32 v87, 160, v84
	v_cmp_gt_u32_e64 s[78:79], s98, v87
	v_cndmask_b32_e64 v35, 0, v35, s[50:51]
	v_add_u32_e32 v88, 176, v84
	v_cmp_gt_u32_e64 s[50:51], s98, v88
	v_cndmask_b32_e64 v36, 0, v36, s[30:31]
	v_add_u32_e32 v85, 256, v84
	v_cmp_gt_u32_e64 s[30:31], s98, v85
	v_cndmask_b32_e64 v37, 0, v37, s[36:37]
	v_add_u32_e32 v86, 272, v84
	v_cmp_gt_u32_e64 s[36:37], s98, v86
	v_cndmask_b32_e64 v38, 0, v38, s[78:79]
	v_add_u32_e32 v87, 288, v84
	v_cmp_gt_u32_e64 s[78:79], s98, v87
	v_cndmask_b32_e64 v39, 0, v39, s[50:51]
	v_add_u32_e32 v88, 304, v84
	v_cmp_gt_u32_e64 s[50:51], s98, v88
	v_cndmask_b32_e64 v40, 0, v40, s[30:31]
	v_add_u32_e32 v85, 384, v84
	v_cmp_gt_u32_e64 s[30:31], s98, v85
	v_cndmask_b32_e64 v41, 0, v41, s[36:37]
	v_add_u32_e32 v86, 400, v84
	v_cmp_gt_u32_e64 s[36:37], s98, v86
	v_cndmask_b32_e64 v42, 0, v42, s[78:79]
	v_add_u32_e32 v87, 416, v84
	v_cmp_gt_u32_e64 s[78:79], s98, v87
	v_cndmask_b32_e64 v43, 0, v43, s[50:51]
	v_add_u32_e32 v88, 432, v84
	v_cmp_gt_u32_e64 s[50:51], s98, v88
	v_nop
	v_cndmask_b32_e64 v44, 0, v44, s[30:31]
	v_cndmask_b32_e64 v45, 0, v45, s[36:37]
	v_cndmask_b32_e64 v46, 0, v46, s[78:79]
	v_cndmask_b32_e64 v47, 0, v47, s[50:51]
	v_cvt_pk_bf16_f32 v64, v32, v33
	v_cvt_pk_bf16_f32 v65, v34, v35
	v_cvt_pk_bf16_f32 v66, v36, v37
	v_cvt_pk_bf16_f32 v67, v38, v39
	v_cvt_pk_bf16_f32 v68, v40, v41
	v_cvt_pk_bf16_f32 v69, v42, v43
	v_cvt_pk_bf16_f32 v70, v44, v45
	v_cvt_pk_bf16_f32 v71, v46, v47
	v_pk_add_f32 v[232:233], v[232:233], v[32:33]
	v_pk_add_f32 v[232:233], v[232:233], v[34:35]
	v_pk_add_f32 v[232:233], v[232:233], v[36:37]
	v_pk_add_f32 v[232:233], v[232:233], v[38:39]
	v_pk_add_f32 v[232:233], v[232:233], v[40:41]
	v_pk_add_f32 v[232:233], v[232:233], v[42:43]
	v_pk_add_f32 v[232:233], v[232:233], v[44:45]
	v_pk_add_f32 v[232:233], v[232:233], v[46:47]
	ds_read2_b32 v[32:33], v115 offset0:128 offset1:129
	ds_read2_b32 v[34:35], v115 offset0:130 offset1:131
	ds_read2_b32 v[36:37], v115 offset0:136 offset1:137
	ds_read2_b32 v[38:39], v115 offset0:138 offset1:139
	ds_read2_b32 v[40:41], v115 offset0:144 offset1:145
	ds_read2_b32 v[42:43], v115 offset0:146 offset1:147
	ds_read2_b32 v[44:45], v115 offset0:152 offset1:153
	ds_read2_b32 v[46:47], v115 offset0:154 offset1:155
	v_mfma_f32_32x32x16_bf16 v[0:15], v[64:67], v[72:75], v[0:15]
	v_mfma_f32_32x32x16_bf16 v[16:31], v[64:67], v[76:79], v[16:31]
	v_mfma_f32_32x32x16_bf16 v[0:15], v[68:71], v[220:223], v[0:15]
	v_mfma_f32_32x32x16_bf16 v[16:31], v[68:71], v[224:227], v[16:31]
	ds_read_b64_tr_b16 v[72:73], v231
	ds_read_b64_tr_b16 v[74:75], v231 offset:512
	ds_read_b64_tr_b16 v[76:77], v231 offset:2048
	ds_read_b64_tr_b16 v[78:79], v231 offset:2560
	ds_read_b64_tr_b16 v[220:221], v231 offset:1024
	ds_read_b64_tr_b16 v[222:223], v231 offset:1536
	ds_read_b64_tr_b16 v[224:225], v231 offset:3072
	ds_read_b64_tr_b16 v[226:227], v231 offset:3584
	s_waitcnt vmcnt(0)
	ds_write_b128 v247, v[116:119]
	ds_write_b128 v247, v[120:123] offset:1024
	ds_write_b128 v111, v[124:127] offset:2048
	ds_write_b128 v111, v[128:131] offset:3072
	ds_read_b128 v[116:119], v248
	ds_read_b128 v[120:123], v249
	ds_read_b128 v[124:127], v250
	ds_read_b128 v[128:131], v251
	ds_write_b128 v112, v[132:135]
	ds_write_b128 v112, v[136:139] offset:1024
	ds_write_b128 v112, v[140:143] offset:2048
	ds_write_b128 v112, v[144:147] offset:3072
	v_exp_f32_e32 v188, v188
	v_exp_f32_e32 v189, v189
	v_exp_f32_e32 v190, v190
	v_exp_f32_e32 v191, v191
	v_exp_f32_e32 v192, v192
	v_exp_f32_e32 v193, v193
	s_waitcnt lgkmcnt(4)
	v_mfma_f32_32x32x16_bf16 v[32:47], v[116:119], v[48:51], v[32:47]
	v_exp_f32_e32 v194, v194
	v_exp_f32_e32 v195, v195
	v_mfma_f32_32x32x16_bf16 v[32:47], v[120:123], v[52:55], v[32:47]
	v_exp_f32_e32 v196, v196
	v_exp_f32_e32 v197, v197
	v_exp_f32_e32 v198, v198
	v_mfma_f32_32x32x16_bf16 v[32:47], v[124:127], v[56:59], v[32:47]
	v_exp_f32_e32 v199, v199
	v_exp_f32_e32 v200, v200
	v_mfma_f32_32x32x16_bf16 v[32:47], v[128:131], v[60:63], v[32:47]
	v_exp_f32_e32 v201, v201
	v_exp_f32_e32 v202, v202
	v_exp_f32_e32 v203, v203
	s_add_i32 s90, s76, 512
	v_lshlrev_b32_e32 v84, 4, v107
	v_add_u32_e32 v84, s90, v84
	v_add_u32_e32 v85, 0, v84
	v_add_u32_e32 v86, 16, v84
	v_add_u32_e32 v87, 32, v84
	v_add_u32_e32 v88, 48, v84
	v_cmp_gt_u32_e64 s[30:31], s98, v85
	v_cmp_gt_u32_e64 s[36:37], s98, v86
	v_cmp_gt_u32_e64 s[78:79], s98, v87
	v_cmp_gt_u32_e64 s[50:51], s98, v88
	v_cndmask_b32_e64 v188, 0, v188, s[30:31]
	v_add_u32_e32 v85, 128, v84
	v_cmp_gt_u32_e64 s[30:31], s98, v85
	v_cndmask_b32_e64 v189, 0, v189, s[36:37]
	v_add_u32_e32 v86, 144, v84
	v_cmp_gt_u32_e64 s[36:37], s98, v86
	v_cndmask_b32_e64 v190, 0, v190, s[78:79]
	v_add_u32_e32 v87, 160, v84
	v_cmp_gt_u32_e64 s[78:79], s98, v87
	v_cndmask_b32_e64 v191, 0, v191, s[50:51]
	v_add_u32_e32 v88, 176, v84
	v_cmp_gt_u32_e64 s[50:51], s98, v88
	v_cndmask_b32_e64 v192, 0, v192, s[30:31]
	v_add_u32_e32 v85, 256, v84
	v_cmp_gt_u32_e64 s[30:31], s98, v85
	v_cndmask_b32_e64 v193, 0, v193, s[36:37]
	v_add_u32_e32 v86, 272, v84
	v_cmp_gt_u32_e64 s[36:37], s98, v86
	v_cndmask_b32_e64 v194, 0, v194, s[78:79]
	v_add_u32_e32 v87, 288, v84
	v_cmp_gt_u32_e64 s[78:79], s98, v87
	v_cndmask_b32_e64 v195, 0, v195, s[50:51]
	v_add_u32_e32 v88, 304, v84
	v_cmp_gt_u32_e64 s[50:51], s98, v88
	v_cndmask_b32_e64 v196, 0, v196, s[30:31]
	v_add_u32_e32 v85, 384, v84
	v_cmp_gt_u32_e64 s[30:31], s98, v85
	v_cndmask_b32_e64 v197, 0, v197, s[36:37]
	v_add_u32_e32 v86, 400, v84
	v_cmp_gt_u32_e64 s[36:37], s98, v86
	v_cndmask_b32_e64 v198, 0, v198, s[78:79]
	v_add_u32_e32 v87, 416, v84
	v_cmp_gt_u32_e64 s[78:79], s98, v87
	v_cndmask_b32_e64 v199, 0, v199, s[50:51]
	v_add_u32_e32 v88, 432, v84
	v_cmp_gt_u32_e64 s[50:51], s98, v88
	v_nop
	v_cndmask_b32_e64 v200, 0, v200, s[30:31]
	v_cndmask_b32_e64 v201, 0, v201, s[36:37]
	v_cndmask_b32_e64 v202, 0, v202, s[78:79]
	v_cndmask_b32_e64 v203, 0, v203, s[50:51]
	v_cvt_pk_bf16_f32 v64, v188, v189
	v_cvt_pk_bf16_f32 v65, v190, v191
	v_cvt_pk_bf16_f32 v66, v192, v193
	v_cvt_pk_bf16_f32 v67, v194, v195
	v_cvt_pk_bf16_f32 v68, v196, v197
	v_cvt_pk_bf16_f32 v69, v198, v199
	v_cvt_pk_bf16_f32 v70, v200, v201
	v_cvt_pk_bf16_f32 v71, v202, v203
	v_pk_add_f32 v[232:233], v[232:233], v[188:189]
	v_pk_add_f32 v[232:233], v[232:233], v[190:191]
	v_pk_add_f32 v[232:233], v[232:233], v[192:193]
	v_pk_add_f32 v[232:233], v[232:233], v[194:195]
	v_pk_add_f32 v[232:233], v[232:233], v[196:197]
	v_pk_add_f32 v[232:233], v[232:233], v[198:199]
	v_pk_add_f32 v[232:233], v[232:233], v[200:201]
	v_pk_add_f32 v[232:233], v[232:233], v[202:203]
	v_mfma_f32_32x32x16_bf16 v[0:15], v[64:67], v[72:75], v[0:15]
	v_mfma_f32_32x32x16_bf16 v[16:31], v[64:67], v[76:79], v[16:31]
	v_mfma_f32_32x32x16_bf16 v[0:15], v[68:71], v[220:223], v[0:15]
	v_mfma_f32_32x32x16_bf16 v[16:31], v[68:71], v[224:227], v[16:31]
	ds_read_b64_tr_b16 v[72:73], v231
	ds_read_b64_tr_b16 v[74:75], v231 offset:512
	ds_read_b64_tr_b16 v[76:77], v231 offset:2048
	ds_read_b64_tr_b16 v[78:79], v231 offset:2560
	ds_read_b64_tr_b16 v[220:221], v231 offset:1024
	ds_read_b64_tr_b16 v[222:223], v231 offset:1536
	ds_read_b64_tr_b16 v[224:225], v231 offset:3072
	ds_read_b64_tr_b16 v[226:227], v231 offset:3584
	s_waitcnt lgkmcnt(0)
; __device__ __forceinline__ int crow(int r, int hi) { return (r & 3) + 8 * (r >> 2) + 4 * hi; }
; __device__ __forceinline__ void dil_unit(LAS unsigned char* lds, bf16_t* proj, int seq, int hd, int T0, int rho) {
;     ...
;     l += __shfl_xor(l, 32);
; #pragma unroll
;     for (int rr = 0; rr < 16; ++rr) {
;         const int j = crow(rr, hi);
;         const float il = __builtin_amdgcn_rcpf(__shfl(l, j));
	v_exp_f32_e32 v32, v32
	v_exp_f32_e32 v33, v33
	v_exp_f32_e32 v34, v34
	v_exp_f32_e32 v35, v35
	v_exp_f32_e32 v36, v36
	v_exp_f32_e32 v37, v37
	v_exp_f32_e32 v38, v38
	v_exp_f32_e32 v39, v39
	v_exp_f32_e32 v40, v40
	v_exp_f32_e32 v41, v41
	v_exp_f32_e32 v42, v42
	v_exp_f32_e32 v43, v43
	v_exp_f32_e32 v44, v44
	v_exp_f32_e32 v45, v45
	v_exp_f32_e32 v46, v46
	v_exp_f32_e32 v47, v47
	s_add_i32 s90, s76, 1024
	v_lshlrev_b32_e32 v84, 4, v107
	v_add_u32_e32 v84, s90, v84
	v_add_u32_e32 v85, 0, v84
	v_add_u32_e32 v86, 16, v84
	v_add_u32_e32 v87, 32, v84
	v_add_u32_e32 v88, 48, v84
	v_cmp_gt_u32_e64 s[30:31], s98, v85
	v_cmp_gt_u32_e64 s[36:37], s98, v86
	v_cmp_gt_u32_e64 s[78:79], s98, v87
	v_cmp_gt_u32_e64 s[50:51], s98, v88
	v_cndmask_b32_e64 v32, 0, v32, s[30:31]
	v_add_u32_e32 v85, 128, v84
	v_cmp_gt_u32_e64 s[30:31], s98, v85
	v_cndmask_b32_e64 v33, 0, v33, s[36:37]
	v_add_u32_e32 v86, 144, v84
	v_cmp_gt_u32_e64 s[36:37], s98, v86
	v_cndmask_b32_e64 v34, 0, v34, s[78:79]
	v_add_u32_e32 v87, 160, v84
	v_cmp_gt_u32_e64 s[78:79], s98, v87
	v_cndmask_b32_e64 v35, 0, v35, s[50:51]
	v_add_u32_e32 v88, 176, v84
	v_cmp_gt_u32_e64 s[50:51], s98, v88
	v_cndmask_b32_e64 v36, 0, v36, s[30:31]
	v_add_u32_e32 v85, 256, v84
	v_cmp_gt_u32_e64 s[30:31], s98, v85
	v_cndmask_b32_e64 v37, 0, v37, s[36:37]
	v_add_u32_e32 v86, 272, v84
	v_cmp_gt_u32_e64 s[36:37], s98, v86
	v_cndmask_b32_e64 v38, 0, v38, s[78:79]
	v_add_u32_e32 v87, 288, v84
	v_cmp_gt_u32_e64 s[78:79], s98, v87
	v_cndmask_b32_e64 v39, 0, v39, s[50:51]
	v_add_u32_e32 v88, 304, v84
	v_cmp_gt_u32_e64 s[50:51], s98, v88
	v_cndmask_b32_e64 v40, 0, v40, s[30:31]
	v_add_u32_e32 v85, 384, v84
	v_cmp_gt_u32_e64 s[30:31], s98, v85
	v_cndmask_b32_e64 v41, 0, v41, s[36:37]
	v_add_u32_e32 v86, 400, v84
	v_cmp_gt_u32_e64 s[36:37], s98, v86
	v_cndmask_b32_e64 v42, 0, v42, s[78:79]
	v_add_u32_e32 v87, 416, v84
	v_cmp_gt_u32_e64 s[78:79], s98, v87
	v_cndmask_b32_e64 v43, 0, v43, s[50:51]
	v_add_u32_e32 v88, 432, v84
	v_cmp_gt_u32_e64 s[50:51], s98, v88
	v_nop
	v_cndmask_b32_e64 v44, 0, v44, s[30:31]
	v_cndmask_b32_e64 v45, 0, v45, s[36:37]
	v_cndmask_b32_e64 v46, 0, v46, s[78:79]
	v_cndmask_b32_e64 v47, 0, v47, s[50:51]
	v_cvt_pk_bf16_f32 v64, v32, v33
	v_cvt_pk_bf16_f32 v65, v34, v35
	v_cvt_pk_bf16_f32 v66, v36, v37
	v_cvt_pk_bf16_f32 v67, v38, v39
	v_cvt_pk_bf16_f32 v68, v40, v41
	v_cvt_pk_bf16_f32 v69, v42, v43
	v_cvt_pk_bf16_f32 v70, v44, v45
	v_cvt_pk_bf16_f32 v71, v46, v47
	v_pk_add_f32 v[232:233], v[232:233], v[32:33]
	v_pk_add_f32 v[232:233], v[232:233], v[34:35]
	v_pk_add_f32 v[232:233], v[232:233], v[36:37]
	v_pk_add_f32 v[232:233], v[232:233], v[38:39]
	v_pk_add_f32 v[232:233], v[232:233], v[40:41]
	v_pk_add_f32 v[232:233], v[232:233], v[42:43]
	v_pk_add_f32 v[232:233], v[232:233], v[44:45]
	v_pk_add_f32 v[232:233], v[232:233], v[46:47]
	v_mfma_f32_32x32x16_bf16 v[0:15], v[64:67], v[72:75], v[0:15]
	v_mfma_f32_32x32x16_bf16 v[16:31], v[64:67], v[76:79], v[16:31]
	v_mfma_f32_32x32x16_bf16 v[0:15], v[68:71], v[220:223], v[0:15]
	v_mfma_f32_32x32x16_bf16 v[16:31], v[68:71], v[224:227], v[16:31]
	v_add_f32_e32 v113, v232, v233
	v_or_b32_e32 v114, 1, v107
	v_or_b32_e32 v97, 2, v107
	v_or_b32_e32 v96, 3, v107
	v_or_b32_e32 v95, 8, v107
	v_or_b32_e32 v94, 9, v107
	v_or_b32_e32 v93, 10, v107
	v_or_b32_e32 v92, 11, v107
	v_or_b32_e32 v91, 16, v107
	v_or_b32_e32 v90, 17, v107
	v_or_b32_e32 v89, 18, v107
	v_or_b32_e32 v88, 19, v107
	v_or_b32_e32 v87, 24, v107
	v_or_b32_e32 v86, 25, v107
	v_or_b32_e32 v85, 26, v107
	v_or_b32_e32 v84, 27, v107
	s_nop 11
	s_branch .LBB0_553

; #define LAS __attribute__((address_space(3)))
; #define GAS __attribute__((address_space(1)))
; __device__ __forceinline__ void dil_unit(LAS unsigned char* lds, bf16_t* proj, int seq, int hd, int T0, int rho) {
;     ...
;     const int tid = tid_, lane = tid & 63, r32 = lane & 31, hi = lane >> 5, wid = __builtin_amdgcn_readfirstlane(tid >> 6);
;     bf16_t* base = proj + (size_t)seq * SEQ * NIN;
;     LAS unsigned char* wbuf = lds + wid * 4096;
;     const LAS unsigned char* vp = wbuf + ((lane >> 4) & 1) * 32 + (lane & 3) * 8 + (4 * hi + ((lane & 15) >> 2)) * 64;
;     const int P0 = T0 + rho;
;     bf16x8 qr[4];
; #pragma unroll
;     for (int ks = 0; ks < 4; ++ks) qr[ks] = *(const GAS bf16x8*)(base + (size_t)(P0 + 16 * r32) * NIN + PC_LQ + hd * 64 + 16 * ks + 8 * hi);
;     f32x16 o0 = {}, o1 = {}; float l = 0.f;
;     const bool bound = (T0 < 1024) || (T0 >= 15360);
.LBB0_1266:
	s_lshr_b32 s82, s60, 8
	s_mul_i32 s82, s82, 13
	s_add_i32 s82, s82, s60
	s_ashr_i32 s4, s60, 6
	s_mul_hi_i32 s9, s4, 0x2aaaaaab
	s_lshl_b32 s5, s82, 8
	s_lshr_b32 s10, s9, 31
	s_and_b32 s8, s5, 0x3e00
	s_lshl_b32 s5, s82, 3
	s_add_i32 s9, s9, s10
	s_and_b32 s5, s5, 8
	s_mul_i32 s10, s9, 6
	s_add_i32 s5, s5, s61
	s_sub_i32 s10, s4, s10
	s_mul_hi_i32 s4, s9, 0x6000000
	s_mul_i32 s9, s9, 0x6000000
	v_mov_b32_e32 v2, v154
	s_add_u32 s52, s44, s9
	s_addc_u32 s53, s45, s4
	v_and_b32_e32 v105, 31, v2
	s_add_i32 s67, s5, s8
	v_lshl_add_u32 v3, v105, 4, s67
	v_mov_b64_e32 v[0:1], s[52:53]
	s_lshl_b32 s54, s10, 6
	v_bfe_u32 v106, v2, 5, 1
	v_mad_u64_u32 v[0:1], s[4:5], v3, s62, v[0:1]
	s_ashr_i32 s55, s54, 31
	v_lshl_add_u64 v[0:1], s[54:55], 1, v[0:1]
	v_lshlrev_b32_e32 v80, 4, v106
	v_lshl_add_u64 v[0:1], v[0:1], 0, v[80:81]
	global_load_dwordx4 v[48:51], v[0:1], off offset:1280
	global_load_dwordx4 v[52:55], v[0:1], off offset:1312
	global_load_dwordx4 v[56:59], v[0:1], off offset:1344
	global_load_dwordx4 v[60:63], v[0:1], off offset:1376
	v_readfirstlane_b32 s4, v2
	s_lshl_b32 s4, s4, 6
	s_and_b32 s4, s4, 0xfffff000
	v_lshlrev_b32_e32 v0, 1, v2
	v_lshlrev_b32_e32 v104, 3, v2
	v_lshlrev_b32_e32 v107, 2, v106
	v_lshrrev_b32_e32 v1, 2, v2
	v_and_b32_e32 v103, 63, v2
	v_and_b32_e32 v0, 32, v0
	v_and_b32_e32 v98, 24, v104
	v_and_or_b32 v1, v1, 3, v107
	s_add_i32 s69, s4, 0
	v_lshlrev_b32_e32 v108, 6, v1
	v_lshlrev_b32_e32 v1, 3, v106
	v_add3_u32 v109, s69, v0, v98
	s_addk_i32 s8, 0xc400
	v_lshrrev_b32_e32 v110, 2, v103
	v_lshlrev_b32_e32 v0, 4, v103
	s_mov_b64 s[4:5], -1
	s_cmp_gt_u32 s8, 0xffffc7ff
	v_lshlrev_b32_e32 v100, 1, v98
	s_mul_i32 s8, s10, 0x1c00
	v_lshlrev_b32_e32 v82, 1, v1
	v_or_b32_e32 v111, 16, v110
	v_add_u32_e32 v112, s69, v0
	s_cbranch_scc0 .LBB0_1270
	s_movk_i32 s100, 0x1800
	s_add_i32 s101, s8, 0x15c00
	s_lshl_b32 s90, s54, 1
	s_add_u32 s82, s52, s90
	s_addc_u32 s83, s53, 0
	s_add_u32 s82, s82, 0x1200
	s_addc_u32 s83, s83, 0
	s_sub_i32 s90, s67, 64
	s_mul_i32 s90, s90, 0x1800
	s_add_u32 s84, s82, s90
	s_addc_u32 s85, s83, 0
	s_sub_i32 s90, s67, 256
	s_mul_i32 s90, s90, 0x1800
	s_add_u32 s86, s82, s90
	s_addc_u32 s87, s83, 0
	s_sub_i32 s90, s67, 1024
	s_mul_i32 s90, s90, 0x1800
	s_add_u32 s88, s82, s90
	s_addc_u32 s89, s83, 0
	v_lshlrev_b32_e32 v153, 1, v98
	v_mad_u32_u24 v80, v105, s100, v82
	v_mad_u32_u24 v100, v110, s100, v153
	v_add_u32_e32 v149, 0x18000, v100
	v_lshlrev_b32_e32 v83, 2, v105
	v_mad_u32_u24 v83, v83, s100, v82
	v_lshlrev_b32_e32 v101, 2, v110
	v_mad_u32_u24 v101, v101, s100, v153
	v_add_u32_e32 v150, 0x60000, v101
	v_lshlrev_b32_e32 v99, 4, v105
	v_mad_u32_u24 v99, v99, s100, v82
	v_lshlrev_b32_e32 v148, 4, v110
	v_mad_u32_u24 v148, v148, s100, v153
	v_add_u32_e32 v151, 0x180000, v148
	v_lshrrev_b32_e32 v249, 3, v103
	v_and_b32_e32 v250, 7, v103
	v_lshlrev_b32_e32 v250, 4, v250
	v_add_u32_e32 v235, 0, v249
	v_mad_u32_u24 v235, v235, s100, v250
	v_add_u32_e32 v236, 8, v249
	v_mad_u32_u24 v236, v236, s100, v250
	v_add_u32_e32 v237, 16, v249
	v_mad_u32_u24 v237, v237, s100, v250
	v_add_u32_e32 v238, 24, v249
	v_mad_u32_u24 v238, v238, s100, v250
	v_add_u32_e32 v239, 0, v249
	v_lshlrev_b32_e32 v239, 2, v239
	v_mad_u32_u24 v239, v239, s100, v250
	v_add_u32_e32 v240, 8, v249
	v_lshlrev_b32_e32 v240, 2, v240
	v_mad_u32_u24 v240, v240, s100, v250
	v_add_u32_e32 v241, 16, v249
	v_lshlrev_b32_e32 v241, 2, v241
	v_mad_u32_u24 v241, v241, s100, v250
	v_add_u32_e32 v242, 24, v249
	v_lshlrev_b32_e32 v242, 2, v242
	v_mad_u32_u24 v242, v242, s100, v250
	v_add_u32_e32 v243, 0, v249
	v_lshlrev_b32_e32 v243, 4, v243
	v_mad_u32_u24 v243, v243, s100, v250
	v_add_u32_e32 v244, 8, v249
	v_lshlrev_b32_e32 v244, 4, v244
	v_mad_u32_u24 v244, v244, s100, v250
	v_add_u32_e32 v245, 16, v249
	v_lshlrev_b32_e32 v245, 4, v245
	v_mad_u32_u24 v245, v245, s100, v250
	v_add_u32_e32 v246, 24, v249
	v_lshlrev_b32_e32 v246, 4, v246
	v_mad_u32_u24 v246, v246, s100, v250
	v_and_b32_e32 v247, 7, v249
	v_lshlrev_b32_e32 v247, 4, v247
	v_xor_b32_e32 v247, v247, v112
	v_xor_b32_e32 v111, 16, v247
	v_and_b32_e32 v153, 7, v105
	v_lshrrev_b32_e32 v248, 4, v105
	v_xor_b32_e32 v153, v153, v248
	v_or_b32_e32 v248, 0, v106
	v_xor_b32_e32 v248, v248, v153
	v_lshlrev_b32_e32 v248, 4, v248
	v_lshl_add_u32 v248, v105, 7, v248
	v_add_u32_e32 v248, s69, v248
	v_or_b32_e32 v249, 2, v106
	v_xor_b32_e32 v249, v249, v153
	v_lshlrev_b32_e32 v249, 4, v249
	v_lshl_add_u32 v249, v105, 7, v249
	v_add_u32_e32 v249, s69, v249
	v_or_b32_e32 v250, 4, v106
	v_xor_b32_e32 v250, v250, v153
	v_lshlrev_b32_e32 v250, 4, v250
	v_lshl_add_u32 v250, v105, 7, v250
	v_add_u32_e32 v250, s69, v250
	v_or_b32_e32 v251, 6, v106
	v_xor_b32_e32 v251, v251, v153
	v_lshlrev_b32_e32 v251, 4, v251
	v_lshl_add_u32 v251, v105, 7, v251
	v_add_u32_e32 v251, s69, v251
	v_lshlrev_b32_e32 v153, 1, v98
	v_mul_u32_u24_e32 v228, 17, v105
	v_sub_u32_e32 v228, v107, v228
	s_mul_i32 s90, s54, 153
	s_lshr_b32 s90, s90, 1
	s_add_i32 s90, s90, 34876
	v_lshl_add_u32 v228, v228, 2, s90
	v_mul_u32_u24_e32 v229, 5, v105
	v_sub_u32_e32 v229, v107, v229
	v_add_u32_e32 v229, v229, v106
	s_mul_i32 s90, s54, 30
	s_add_i32 s90, s90, 66156
	v_lshl_add_u32 v229, v229, 2, s90
	v_sub_u32_e32 v230, v107, v105
	s_add_i32 s90, s101, 6364
	v_lshl_add_u32 v230, v230, 2, s90
	v_add_u32_e32 v231, v109, v108
	v_mov_b64_e32 v[232:233], 0
	v_mov_b64_e32 v[0:1], 0
	v_mov_b64_e32 v[2:3], 0
	v_mov_b64_e32 v[4:5], 0
	v_mov_b64_e32 v[6:7], 0
	v_mov_b64_e32 v[8:9], 0
	v_mov_b64_e32 v[10:11], 0
	v_mov_b64_e32 v[12:13], 0
	v_mov_b64_e32 v[14:15], 0
	v_mov_b64_e32 v[16:17], 0
	v_mov_b64_e32 v[18:19], 0
	v_mov_b64_e32 v[20:21], 0
	v_mov_b64_e32 v[22:23], 0
	v_mov_b64_e32 v[24:25], 0
	v_mov_b64_e32 v[26:27], 0
	v_mov_b64_e32 v[28:29], 0
	v_mov_b64_e32 v[30:31], 0
	global_load_dwordx4 v[116:119], v235, s[84:85]
	global_load_dwordx4 v[120:123], v236, s[84:85]
	global_load_dwordx4 v[124:127], v237, s[84:85]
	global_load_dwordx4 v[128:131], v238, s[84:85]
	global_load_dwordx4 v[132:135], v100, s[84:85] offset:768
	global_load_dwordx4 v[136:139], v149, s[84:85] offset:768
	global_load_dwordx4 v[140:143], v100, s[84:85] offset:832
	global_load_dwordx4 v[144:147], v149, s[84:85] offset:832
	s_add_u32 s84, s84, 0x30000
	s_addc_u32 s85, s85, 0
	global_load_dwordx4 v[156:159], v235, s[84:85]
	global_load_dwordx4 v[160:163], v236, s[84:85]
	global_load_dwordx4 v[164:167], v237, s[84:85]
	global_load_dwordx4 v[168:171], v238, s[84:85]
	global_load_dwordx4 v[172:175], v100, s[84:85] offset:768
	global_load_dwordx4 v[176:179], v149, s[84:85] offset:768
	global_load_dwordx4 v[180:183], v100, s[84:85] offset:832
	global_load_dwordx4 v[184:187], v149, s[84:85] offset:832
	s_add_u32 s84, s84, 0x30000
	s_addc_u32 s85, s85, 0
	v_mov_b32_e32 v115, v228
	ds_read2_b32 v[32:33], v115 offset0:0 offset1:1
	ds_read2_b32 v[34:35], v115 offset0:2 offset1:3
	ds_read2_b32 v[36:37], v115 offset0:8 offset1:9
	ds_read2_b32 v[38:39], v115 offset0:10 offset1:11
	ds_read2_b32 v[40:41], v115 offset0:17 offset1:18
	ds_read2_b32 v[42:43], v115 offset0:19 offset1:20
	ds_read2_b32 v[44:45], v115 offset0:25 offset1:26
	ds_read2_b32 v[46:47], v115 offset0:27 offset1:28
	s_waitcnt vmcnt(8)
	ds_write_b128 v247, v[116:119]
	ds_write_b128 v247, v[120:123] offset:1024
	ds_write_b128 v111, v[124:127] offset:2048
	ds_write_b128 v111, v[128:131] offset:3072
	ds_read_b128 v[116:119], v248
	ds_read_b128 v[120:123], v249
	ds_read_b128 v[124:127], v250
	ds_read_b128 v[128:131], v251
	ds_write_b128 v112, v[132:135]
	ds_write_b128 v112, v[136:139] offset:1024
	ds_write_b128 v112, v[140:143] offset:2048
	ds_write_b128 v112, v[144:147] offset:3072
	s_waitcnt lgkmcnt(4)
	v_mfma_f32_32x32x16_bf16 v[32:47], v[116:119], v[48:51], v[32:47]
	v_mfma_f32_32x32x16_bf16 v[32:47], v[120:123], v[52:55], v[32:47]
	v_mfma_f32_32x32x16_bf16 v[32:47], v[124:127], v[56:59], v[32:47]
	v_mfma_f32_32x32x16_bf16 v[32:47], v[128:131], v[60:63], v[32:47]
	ds_read2_b32 v[188:189], v115 offset0:34 offset1:35
	ds_read2_b32 v[190:191], v115 offset0:36 offset1:37
	ds_read2_b32 v[192:193], v115 offset0:42 offset1:43
	ds_read2_b32 v[194:195], v115 offset0:44 offset1:45
	ds_read2_b32 v[196:197], v115 offset0:51 offset1:52
	ds_read2_b32 v[198:199], v115 offset0:53 offset1:54
	ds_read2_b32 v[200:201], v115 offset0:59 offset1:60
	ds_read2_b32 v[202:203], v115 offset0:61 offset1:62
	global_load_dwordx4 v[116:119], v235, s[84:85]
	global_load_dwordx4 v[120:123], v236, s[84:85]
	global_load_dwordx4 v[124:127], v237, s[84:85]
	global_load_dwordx4 v[128:131], v238, s[84:85]
	global_load_dwordx4 v[132:135], v100, s[84:85] offset:768
	global_load_dwordx4 v[136:139], v149, s[84:85] offset:768
	global_load_dwordx4 v[140:143], v100, s[84:85] offset:832
	global_load_dwordx4 v[144:147], v149, s[84:85] offset:832
	s_add_u32 s84, s84, 0x30000
	s_addc_u32 s85, s85, 0
	ds_read_b64_tr_b16 v[72:73], v231
	ds_read_b64_tr_b16 v[74:75], v231 offset:512
	ds_read_b64_tr_b16 v[76:77], v231 offset:2048
	ds_read_b64_tr_b16 v[78:79], v231 offset:2560
	ds_read_b64_tr_b16 v[220:221], v231 offset:1024
	ds_read_b64_tr_b16 v[222:223], v231 offset:1536
	ds_read_b64_tr_b16 v[224:225], v231 offset:3072
	ds_read_b64_tr_b16 v[226:227], v231 offset:3584
	s_waitcnt vmcnt(8)
	ds_write_b128 v247, v[156:159]
	ds_write_b128 v247, v[160:163] offset:1024
	ds_write_b128 v111, v[164:167] offset:2048
	ds_write_b128 v111, v[168:171] offset:3072
	ds_read_b128 v[156:159], v248
	ds_read_b128 v[160:163], v249
	ds_read_b128 v[164:167], v250
	ds_read_b128 v[168:171], v251
	ds_write_b128 v112, v[172:175]
	ds_write_b128 v112, v[176:179] offset:1024
	ds_write_b128 v112, v[180:183] offset:2048
	ds_write_b128 v112, v[184:187] offset:3072
	v_exp_f32_e32 v32, v32
	v_exp_f32_e32 v33, v33
	v_exp_f32_e32 v34, v34
	v_exp_f32_e32 v35, v35
	v_exp_f32_e32 v36, v36
	v_exp_f32_e32 v37, v37
	s_waitcnt lgkmcnt(4)
	v_mfma_f32_32x32x16_bf16 v[188:203], v[156:159], v[48:51], v[188:203]
	v_exp_f32_e32 v38, v38
	v_exp_f32_e32 v39, v39
	v_mfma_f32_32x32x16_bf16 v[188:203], v[160:163], v[52:55], v[188:203]
	v_exp_f32_e32 v40, v40
	v_exp_f32_e32 v41, v41
	v_exp_f32_e32 v42, v42
	v_mfma_f32_32x32x16_bf16 v[188:203], v[164:167], v[56:59], v[188:203]
	v_exp_f32_e32 v43, v43
	v_exp_f32_e32 v44, v44
	v_mfma_f32_32x32x16_bf16 v[188:203], v[168:171], v[60:63], v[188:203]
	v_exp_f32_e32 v45, v45
	v_exp_f32_e32 v46, v46
	v_exp_f32_e32 v47, v47
	v_cvt_pk_bf16_f32 v64, v32, v33
	v_cvt_pk_bf16_f32 v65, v34, v35
	v_cvt_pk_bf16_f32 v66, v36, v37
	v_cvt_pk_bf16_f32 v67, v38, v39
	v_cvt_pk_bf16_f32 v68, v40, v41
	v_cvt_pk_bf16_f32 v69, v42, v43
	v_cvt_pk_bf16_f32 v70, v44, v45
	v_cvt_pk_bf16_f32 v71, v46, v47
	v_pk_add_f32 v[232:233], v[232:233], v[32:33]
	v_pk_add_f32 v[232:233], v[232:233], v[34:35]
	v_pk_add_f32 v[232:233], v[232:233], v[36:37]
	v_pk_add_f32 v[232:233], v[232:233], v[38:39]
	v_pk_add_f32 v[232:233], v[232:233], v[40:41]
	v_pk_add_f32 v[232:233], v[232:233], v[42:43]
	v_pk_add_f32 v[232:233], v[232:233], v[44:45]
	v_pk_add_f32 v[232:233], v[232:233], v[46:47]
	ds_read2_b32 v[32:33], v115 offset0:68 offset1:69
	ds_read2_b32 v[34:35], v115 offset0:70 offset1:71
	ds_read2_b32 v[36:37], v115 offset0:76 offset1:77
	ds_read2_b32 v[38:39], v115 offset0:78 offset1:79
	ds_read2_b32 v[40:41], v115 offset0:85 offset1:86
	ds_read2_b32 v[42:43], v115 offset0:87 offset1:88
	ds_read2_b32 v[44:45], v115 offset0:93 offset1:94
	ds_read2_b32 v[46:47], v115 offset0:95 offset1:96
	v_mfma_f32_32x32x16_bf16 v[0:15], v[64:67], v[72:75], v[0:15]
	v_mfma_f32_32x32x16_bf16 v[16:31], v[64:67], v[76:79], v[16:31]
	v_mfma_f32_32x32x16_bf16 v[0:15], v[68:71], v[220:223], v[0:15]
	v_mfma_f32_32x32x16_bf16 v[16:31], v[68:71], v[224:227], v[16:31]
	global_load_dwordx4 v[156:159], v235, s[84:85]
	global_load_dwordx4 v[160:163], v236, s[84:85]
	global_load_dwordx4 v[164:167], v237, s[84:85]
	global_load_dwordx4 v[168:171], v238, s[84:85]
	global_load_dwordx4 v[172:175], v100, s[84:85] offset:768
	global_load_dwordx4 v[176:179], v149, s[84:85] offset:768
	global_load_dwordx4 v[180:183], v100, s[84:85] offset:832
	global_load_dwordx4 v[184:187], v149, s[84:85] offset:832
	s_add_u32 s84, s84, 0x30000
	s_addc_u32 s85, s85, 0
	ds_read_b64_tr_b16 v[72:73], v231
	ds_read_b64_tr_b16 v[74:75], v231 offset:512
	ds_read_b64_tr_b16 v[76:77], v231 offset:2048
	ds_read_b64_tr_b16 v[78:79], v231 offset:2560
	ds_read_b64_tr_b16 v[220:221], v231 offset:1024
	ds_read_b64_tr_b16 v[222:223], v231 offset:1536
	ds_read_b64_tr_b16 v[224:225], v231 offset:3072
	ds_read_b64_tr_b16 v[226:227], v231 offset:3584
	s_waitcnt vmcnt(8)
	ds_write_b128 v247, v[116:119]
	ds_write_b128 v247, v[120:123] offset:1024
	ds_write_b128 v111, v[124:127] offset:2048
	ds_write_b128 v111, v[128:131] offset:3072
	ds_read_b128 v[116:119], v248
	ds_read_b128 v[120:123], v249
	ds_read_b128 v[124:127], v250
	ds_read_b128 v[128:131], v251
	ds_write_b128 v112, v[132:135]
	ds_write_b128 v112, v[136:139] offset:1024
	ds_write_b128 v112, v[140:143] offset:2048
	ds_write_b128 v112, v[144:147] offset:3072
	v_exp_f32_e32 v188, v188
	v_exp_f32_e32 v189, v189
	v_exp_f32_e32 v190, v190
	v_exp_f32_e32 v191, v191
	v_exp_f32_e32 v192, v192
	v_exp_f32_e32 v193, v193
	s_waitcnt lgkmcnt(4)
	v_mfma_f32_32x32x16_bf16 v[32:47], v[116:119], v[48:51], v[32:47]
	v_exp_f32_e32 v194, v194
	v_exp_f32_e32 v195, v195
	v_mfma_f32_32x32x16_bf16 v[32:47], v[120:123], v[52:55], v[32:47]
	v_exp_f32_e32 v196, v196
	v_exp_f32_e32 v197, v197
	v_exp_f32_e32 v198, v198
	v_mfma_f32_32x32x16_bf16 v[32:47], v[124:127], v[56:59], v[32:47]
	v_exp_f32_e32 v199, v199
	v_exp_f32_e32 v200, v200
	v_mfma_f32_32x32x16_bf16 v[32:47], v[128:131], v[60:63], v[32:47]
	v_exp_f32_e32 v201, v201
	v_exp_f32_e32 v202, v202
	v_exp_f32_e32 v203, v203
	v_cvt_pk_bf16_f32 v64, v188, v189
	v_cvt_pk_bf16_f32 v65, v190, v191
	v_cvt_pk_bf16_f32 v66, v192, v193
	v_cvt_pk_bf16_f32 v67, v194, v195
	v_cvt_pk_bf16_f32 v68, v196, v197
	v_cvt_pk_bf16_f32 v69, v198, v199
	v_cvt_pk_bf16_f32 v70, v200, v201
	v_cvt_pk_bf16_f32 v71, v202, v203
	v_pk_add_f32 v[232:233], v[232:233], v[188:189]
	v_pk_add_f32 v[232:233], v[232:233], v[190:191]
	v_pk_add_f32 v[232:233], v[232:233], v[192:193]
	v_pk_add_f32 v[232:233], v[232:233], v[194:195]
	v_pk_add_f32 v[232:233], v[232:233], v[196:197]
	v_pk_add_f32 v[232:233], v[232:233], v[198:199]
	v_pk_add_f32 v[232:233], v[232:233], v[200:201]
	v_pk_add_f32 v[232:233], v[232:233], v[202:203]
	ds_read2_b32 v[188:189], v115 offset0:102 offset1:103
	ds_read2_b32 v[190:191], v115 offset0:104 offset1:105
	ds_read2_b32 v[192:193], v115 offset0:110 offset1:111
	ds_read2_b32 v[194:195], v115 offset0:112 offset1:113
	ds_read2_b32 v[196:197], v115 offset0:119 offset1:120
	ds_read2_b32 v[198:199], v115 offset0:121 offset1:122
	ds_read2_b32 v[200:201], v115 offset0:127 offset1:128
	ds_read2_b32 v[202:203], v115 offset0:129 offset1:130
	v_mfma_f32_32x32x16_bf16 v[0:15], v[64:67], v[72:75], v[0:15]
	v_mfma_f32_32x32x16_bf16 v[16:31], v[64:67], v[76:79], v[16:31]
	v_mfma_f32_32x32x16_bf16 v[0:15], v[68:71], v[220:223], v[0:15]
	v_mfma_f32_32x32x16_bf16 v[16:31], v[68:71], v[224:227], v[16:31]
	global_load_dwordx4 v[116:119], v235, s[84:85]
	global_load_dwordx4 v[120:123], v236, s[84:85]
	global_load_dwordx4 v[124:127], v237, s[84:85]
	global_load_dwordx4 v[128:131], v238, s[84:85]
	global_load_dwordx4 v[132:135], v100, s[84:85] offset:768
	global_load_dwordx4 v[136:139], v149, s[84:85] offset:768
	global_load_dwordx4 v[140:143], v100, s[84:85] offset:832
	global_load_dwordx4 v[144:147], v149, s[84:85] offset:832
	s_add_u32 s84, s84, 0x30000
	s_addc_u32 s85, s85, 0
	ds_read_b64_tr_b16 v[72:73], v231
	ds_read_b64_tr_b16 v[74:75], v231 offset:512
	ds_read_b64_tr_b16 v[76:77], v231 offset:2048
	ds_read_b64_tr_b16 v[78:79], v231 offset:2560
	ds_read_b64_tr_b16 v[220:221], v231 offset:1024
	ds_read_b64_tr_b16 v[222:223], v231 offset:1536
	ds_read_b64_tr_b16 v[224:225], v231 offset:3072
	ds_read_b64_tr_b16 v[226:227], v231 offset:3584
	s_waitcnt vmcnt(8)
	ds_write_b128 v247, v[156:159]
	ds_write_b128 v247, v[160:163] offset:1024
	ds_write_b128 v111, v[164:167] offset:2048
	ds_write_b128 v111, v[168:171] offset:3072
	ds_read_b128 v[156:159], v248
	ds_read_b128 v[160:163], v249
	ds_read_b128 v[164:167], v250
	ds_read_b128 v[168:171], v251
	ds_write_b128 v112, v[172:175]
	ds_write_b128 v112, v[176:179] offset:1024
	ds_write_b128 v112, v[180:183] offset:2048
	ds_write_b128 v112, v[184:187] offset:3072
	v_exp_f32_e32 v32, v32
	v_exp_f32_e32 v33, v33
	v_exp_f32_e32 v34, v34
	v_exp_f32_e32 v35, v35
	v_exp_f32_e32 v36, v36
	v_exp_f32_e32 v37, v37
	s_waitcnt lgkmcnt(4)
	v_mfma_f32_32x32x16_bf16 v[188:203], v[156:159], v[48:51], v[188:203]
	v_exp_f32_e32 v38, v38
	v_exp_f32_e32 v39, v39
	v_mfma_f32_32x32x16_bf16 v[188:203], v[160:163], v[52:55], v[188:203]
	v_exp_f32_e32 v40, v40
	v_exp_f32_e32 v41, v41
	v_exp_f32_e32 v42, v42
	v_mfma_f32_32x32x16_bf16 v[188:203], v[164:167], v[56:59], v[188:203]
	v_exp_f32_e32 v43, v43
	v_exp_f32_e32 v44, v44
	v_mfma_f32_32x32x16_bf16 v[188:203], v[168:171], v[60:63], v[188:203]
	v_exp_f32_e32 v45, v45
	v_exp_f32_e32 v46, v46
	v_exp_f32_e32 v47, v47
	v_cvt_pk_bf16_f32 v64, v32, v33
	v_cvt_pk_bf16_f32 v65, v34, v35
	v_cvt_pk_bf16_f32 v66, v36, v37
	v_cvt_pk_bf16_f32 v67, v38, v39
	v_cvt_pk_bf16_f32 v68, v40, v41
	v_cvt_pk_bf16_f32 v69, v42, v43
	v_cvt_pk_bf16_f32 v70, v44, v45
	v_cvt_pk_bf16_f32 v71, v46, v47
	v_pk_add_f32 v[232:233], v[232:233], v[32:33]
	v_pk_add_f32 v[232:233], v[232:233], v[34:35]
	v_pk_add_f32 v[232:233], v[232:233], v[36:37]
	v_pk_add_f32 v[232:233], v[232:233], v[38:39]
	v_pk_add_f32 v[232:233], v[232:233], v[40:41]
	v_pk_add_f32 v[232:233], v[232:233], v[42:43]
	v_pk_add_f32 v[232:233], v[232:233], v[44:45]
	v_pk_add_f32 v[232:233], v[232:233], v[46:47]
	ds_read2_b32 v[32:33], v115 offset0:136 offset1:137
	ds_read2_b32 v[34:35], v115 offset0:138 offset1:139
	ds_read2_b32 v[36:37], v115 offset0:144 offset1:145
	ds_read2_b32 v[38:39], v115 offset0:146 offset1:147
	ds_read2_b32 v[40:41], v115 offset0:153 offset1:154
	ds_read2_b32 v[42:43], v115 offset0:155 offset1:156
	ds_read2_b32 v[44:45], v115 offset0:161 offset1:162
	ds_read2_b32 v[46:47], v115 offset0:163 offset1:164
	v_mfma_f32_32x32x16_bf16 v[0:15], v[64:67], v[72:75], v[0:15]
	v_mfma_f32_32x32x16_bf16 v[16:31], v[64:67], v[76:79], v[16:31]
	v_mfma_f32_32x32x16_bf16 v[0:15], v[68:71], v[220:223], v[0:15]
	v_mfma_f32_32x32x16_bf16 v[16:31], v[68:71], v[224:227], v[16:31]
	global_load_dwordx4 v[156:159], v235, s[84:85]
	global_load_dwordx4 v[160:163], v236, s[84:85]
	global_load_dwordx4 v[164:167], v237, s[84:85]
	global_load_dwordx4 v[168:171], v238, s[84:85]
	global_load_dwordx4 v[172:175], v100, s[84:85] offset:768
	global_load_dwordx4 v[176:179], v149, s[84:85] offset:768
	global_load_dwordx4 v[180:183], v100, s[84:85] offset:832
	global_load_dwordx4 v[184:187], v149, s[84:85] offset:832
	s_add_u32 s84, s84, 0x30000
	s_addc_u32 s85, s85, 0
	ds_read_b64_tr_b16 v[72:73], v231
	ds_read_b64_tr_b16 v[74:75], v231 offset:512
	ds_read_b64_tr_b16 v[76:77], v231 offset:2048
	ds_read_b64_tr_b16 v[78:79], v231 offset:2560
	ds_read_b64_tr_b16 v[220:221], v231 offset:1024
	ds_read_b64_tr_b16 v[222:223], v231 offset:1536
	ds_read_b64_tr_b16 v[224:225], v231 offset:3072
	ds_read_b64_tr_b16 v[226:227], v231 offset:3584
	s_waitcnt vmcnt(8)
	ds_write_b128 v247, v[116:119]
	ds_write_b128 v247, v[120:123] offset:1024
	ds_write_b128 v111, v[124:127] offset:2048
	ds_write_b128 v111, v[128:131] offset:3072
	ds_read_b128 v[116:119], v248
	ds_read_b128 v[120:123], v249
	ds_read_b128 v[124:127], v250
	ds_read_b128 v[128:131], v251
	ds_write_b128 v112, v[132:135]
	ds_write_b128 v112, v[136:139] offset:1024
	ds_write_b128 v112, v[140:143] offset:2048
	ds_write_b128 v112, v[144:147] offset:3072
	v_exp_f32_e32 v188, v188
	v_exp_f32_e32 v189, v189
	v_exp_f32_e32 v190, v190
	v_exp_f32_e32 v191, v191
	v_exp_f32_e32 v192, v192
	v_exp_f32_e32 v193, v193
	s_waitcnt lgkmcnt(4)
	v_mfma_f32_32x32x16_bf16 v[32:47], v[116:119], v[48:51], v[32:47]
	v_exp_f32_e32 v194, v194
	v_exp_f32_e32 v195, v195
	v_mfma_f32_32x32x16_bf16 v[32:47], v[120:123], v[52:55], v[32:47]
	v_exp_f32_e32 v196, v196
	v_exp_f32_e32 v197, v197
	v_exp_f32_e32 v198, v198
	v_mfma_f32_32x32x16_bf16 v[32:47], v[124:127], v[56:59], v[32:47]
	v_exp_f32_e32 v199, v199
	v_exp_f32_e32 v200, v200
	v_mfma_f32_32x32x16_bf16 v[32:47], v[128:131], v[60:63], v[32:47]
	v_exp_f32_e32 v201, v201
	v_exp_f32_e32 v202, v202
	v_exp_f32_e32 v203, v203
	v_cvt_pk_bf16_f32 v64, v188, v189
	v_cvt_pk_bf16_f32 v65, v190, v191
	v_cvt_pk_bf16_f32 v66, v192, v193
	v_cvt_pk_bf16_f32 v67, v194, v195
	v_cvt_pk_bf16_f32 v68, v196, v197
	v_cvt_pk_bf16_f32 v69, v198, v199
	v_cvt_pk_bf16_f32 v70, v200, v201
	v_cvt_pk_bf16_f32 v71, v202, v203
	v_pk_add_f32 v[232:233], v[232:233], v[188:189]
	v_pk_add_f32 v[232:233], v[232:233], v[190:191]
	v_pk_add_f32 v[232:233], v[232:233], v[192:193]
	v_pk_add_f32 v[232:233], v[232:233], v[194:195]
	v_pk_add_f32 v[232:233], v[232:233], v[196:197]
	v_pk_add_f32 v[232:233], v[232:233], v[198:199]
	v_pk_add_f32 v[232:233], v[232:233], v[200:201]
	v_pk_add_f32 v[232:233], v[232:233], v[202:203]
	ds_read2_b32 v[188:189], v115 offset0:170 offset1:171
	ds_read2_b32 v[190:191], v115 offset0:172 offset1:173
	ds_read2_b32 v[192:193], v115 offset0:178 offset1:179
	ds_read2_b32 v[194:195], v115 offset0:180 offset1:181
	ds_read2_b32 v[196:197], v115 offset0:187 offset1:188
	ds_read2_b32 v[198:199], v115 offset0:189 offset1:190
	ds_read2_b32 v[200:201], v115 offset0:195 offset1:196
	ds_read2_b32 v[202:203], v115 offset0:197 offset1:198
	v_mfma_f32_32x32x16_bf16 v[0:15], v[64:67], v[72:75], v[0:15]
	v_mfma_f32_32x32x16_bf16 v[16:31], v[64:67], v[76:79], v[16:31]
	v_mfma_f32_32x32x16_bf16 v[0:15], v[68:71], v[220:223], v[0:15]
	v_mfma_f32_32x32x16_bf16 v[16:31], v[68:71], v[224:227], v[16:31]
	global_load_dwordx4 v[116:119], v235, s[84:85]
	global_load_dwordx4 v[120:123], v236, s[84:85]
	global_load_dwordx4 v[124:127], v237, s[84:85]
	global_load_dwordx4 v[128:131], v238, s[84:85]
	global_load_dwordx4 v[132:135], v100, s[84:85] offset:768
	global_load_dwordx4 v[136:139], v149, s[84:85] offset:768
	global_load_dwordx4 v[140:143], v100, s[84:85] offset:832
	global_load_dwordx4 v[144:147], v149, s[84:85] offset:832
	s_add_u32 s84, s84, 0x30000
	s_addc_u32 s85, s85, 0
	ds_read_b64_tr_b16 v[72:73], v231
	ds_read_b64_tr_b16 v[74:75], v231 offset:512
	ds_read_b64_tr_b16 v[76:77], v231 offset:2048
	ds_read_b64_tr_b16 v[78:79], v231 offset:2560
	ds_read_b64_tr_b16 v[220:221], v231 offset:1024
	ds_read_b64_tr_b16 v[222:223], v231 offset:1536
	ds_read_b64_tr_b16 v[224:225], v231 offset:3072
	ds_read_b64_tr_b16 v[226:227], v231 offset:3584
	s_waitcnt vmcnt(8)
	ds_write_b128 v247, v[156:159]
	ds_write_b128 v247, v[160:163] offset:1024
	ds_write_b128 v111, v[164:167] offset:2048
	ds_write_b128 v111, v[168:171] offset:3072
	ds_read_b128 v[156:159], v248
	ds_read_b128 v[160:163], v249
	ds_read_b128 v[164:167], v250
	ds_read_b128 v[168:171], v251
	ds_write_b128 v112, v[172:175]
	ds_write_b128 v112, v[176:179] offset:1024
	ds_write_b128 v112, v[180:183] offset:2048
	ds_write_b128 v112, v[184:187] offset:3072
	v_exp_f32_e32 v32, v32
	v_exp_f32_e32 v33, v33
	v_exp_f32_e32 v34, v34
	v_exp_f32_e32 v35, v35
	v_exp_f32_e32 v36, v36
	v_exp_f32_e32 v37, v37
	s_waitcnt lgkmcnt(4)
	v_mfma_f32_32x32x16_bf16 v[188:203], v[156:159], v[48:51], v[188:203]
	v_exp_f32_e32 v38, v38
	v_exp_f32_e32 v39, v39
	v_mfma_f32_32x32x16_bf16 v[188:203], v[160:163], v[52:55], v[188:203]
	v_exp_f32_e32 v40, v40
	v_exp_f32_e32 v41, v41
	v_exp_f32_e32 v42, v42
	v_mfma_f32_32x32x16_bf16 v[188:203], v[164:167], v[56:59], v[188:203]
	v_exp_f32_e32 v43, v43
	v_exp_f32_e32 v44, v44
	v_mfma_f32_32x32x16_bf16 v[188:203], v[168:171], v[60:63], v[188:203]
	v_exp_f32_e32 v45, v45
	v_exp_f32_e32 v46, v46
	v_exp_f32_e32 v47, v47
	v_cvt_pk_bf16_f32 v64, v32, v33
	v_cvt_pk_bf16_f32 v65, v34, v35
	v_cvt_pk_bf16_f32 v66, v36, v37
	v_cvt_pk_bf16_f32 v67, v38, v39
	v_cvt_pk_bf16_f32 v68, v40, v41
	v_cvt_pk_bf16_f32 v69, v42, v43
	v_cvt_pk_bf16_f32 v70, v44, v45
	v_cvt_pk_bf16_f32 v71, v46, v47
	v_pk_add_f32 v[232:233], v[232:233], v[32:33]
	v_pk_add_f32 v[232:233], v[232:233], v[34:35]
	v_pk_add_f32 v[232:233], v[232:233], v[36:37]
	v_pk_add_f32 v[232:233], v[232:233], v[38:39]
	v_pk_add_f32 v[232:233], v[232:233], v[40:41]
	v_pk_add_f32 v[232:233], v[232:233], v[42:43]
	v_pk_add_f32 v[232:233], v[232:233], v[44:45]
	v_pk_add_f32 v[232:233], v[232:233], v[46:47]
	ds_read2_b32 v[32:33], v115 offset0:204 offset1:205
	ds_read2_b32 v[34:35], v115 offset0:206 offset1:207
	ds_read2_b32 v[36:37], v115 offset0:212 offset1:213
	ds_read2_b32 v[38:39], v115 offset0:214 offset1:215
	ds_read2_b32 v[40:41], v115 offset0:221 offset1:222
	ds_read2_b32 v[42:43], v115 offset0:223 offset1:224
	ds_read2_b32 v[44:45], v115 offset0:229 offset1:230
	ds_read2_b32 v[46:47], v115 offset0:231 offset1:232
	v_mfma_f32_32x32x16_bf16 v[0:15], v[64:67], v[72:75], v[0:15]
	v_mfma_f32_32x32x16_bf16 v[16:31], v[64:67], v[76:79], v[16:31]
	v_mfma_f32_32x32x16_bf16 v[0:15], v[68:71], v[220:223], v[0:15]
	v_mfma_f32_32x32x16_bf16 v[16:31], v[68:71], v[224:227], v[16:31]
	global_load_dwordx4 v[156:159], v235, s[84:85]
	global_load_dwordx4 v[160:163], v236, s[84:85]
	global_load_dwordx4 v[164:167], v237, s[84:85]
	global_load_dwordx4 v[168:171], v238, s[84:85]
	global_load_dwordx4 v[172:175], v100, s[84:85] offset:768
	global_load_dwordx4 v[176:179], v149, s[84:85] offset:768
	global_load_dwordx4 v[180:183], v100, s[84:85] offset:832
	global_load_dwordx4 v[184:187], v149, s[84:85] offset:832
	s_add_u32 s84, s84, 0x30000
	s_addc_u32 s85, s85, 0
	ds_read_b64_tr_b16 v[72:73], v231
	ds_read_b64_tr_b16 v[74:75], v231 offset:512
	ds_read_b64_tr_b16 v[76:77], v231 offset:2048
	ds_read_b64_tr_b16 v[78:79], v231 offset:2560
	ds_read_b64_tr_b16 v[220:221], v231 offset:1024
	ds_read_b64_tr_b16 v[222:223], v231 offset:1536
	ds_read_b64_tr_b16 v[224:225], v231 offset:3072
	ds_read_b64_tr_b16 v[226:227], v231 offset:3584
	s_waitcnt vmcnt(8)
	ds_write_b128 v247, v[116:119]
	ds_write_b128 v247, v[120:123] offset:1024
	ds_write_b128 v111, v[124:127] offset:2048
	ds_write_b128 v111, v[128:131] offset:3072
	ds_read_b128 v[116:119], v248
	ds_read_b128 v[120:123], v249
	ds_read_b128 v[124:127], v250
	ds_read_b128 v[128:131], v251
	ds_write_b128 v112, v[132:135]
	ds_write_b128 v112, v[136:139] offset:1024
	ds_write_b128 v112, v[140:143] offset:2048
	ds_write_b128 v112, v[144:147] offset:3072
	v_exp_f32_e32 v188, v188
	v_exp_f32_e32 v189, v189
	v_exp_f32_e32 v190, v190
	v_exp_f32_e32 v191, v191
	v_exp_f32_e32 v192, v192
	v_exp_f32_e32 v193, v193
	s_waitcnt lgkmcnt(4)
	v_mfma_f32_32x32x16_bf16 v[32:47], v[116:119], v[48:51], v[32:47]
	v_exp_f32_e32 v194, v194
	v_exp_f32_e32 v195, v195
	v_mfma_f32_32x32x16_bf16 v[32:47], v[120:123], v[52:55], v[32:47]
	v_exp_f32_e32 v196, v196
	v_exp_f32_e32 v197, v197
	v_exp_f32_e32 v198, v198
	v_mfma_f32_32x32x16_bf16 v[32:47], v[124:127], v[56:59], v[32:47]
	v_exp_f32_e32 v199, v199
	v_exp_f32_e32 v200, v200
	v_mfma_f32_32x32x16_bf16 v[32:47], v[128:131], v[60:63], v[32:47]
	v_exp_f32_e32 v201, v201
	v_exp_f32_e32 v202, v202
	v_exp_f32_e32 v203, v203
	v_cvt_pk_bf16_f32 v64, v188, v189
	v_cvt_pk_bf16_f32 v65, v190, v191
	v_cvt_pk_bf16_f32 v66, v192, v193
	v_cvt_pk_bf16_f32 v67, v194, v195
	v_cvt_pk_bf16_f32 v68, v196, v197
	v_cvt_pk_bf16_f32 v69, v198, v199
	v_cvt_pk_bf16_f32 v70, v200, v201
	v_cvt_pk_bf16_f32 v71, v202, v203
	v_pk_add_f32 v[232:233], v[232:233], v[188:189]
	v_pk_add_f32 v[232:233], v[232:233], v[190:191]
	v_pk_add_f32 v[232:233], v[232:233], v[192:193]
	v_pk_add_f32 v[232:233], v[232:233], v[194:195]
	v_pk_add_f32 v[232:233], v[232:233], v[196:197]
	v_pk_add_f32 v[232:233], v[232:233], v[198:199]
	v_pk_add_f32 v[232:233], v[232:233], v[200:201]
	v_pk_add_f32 v[232:233], v[232:233], v[202:203]
	v_add_u32_e32 v115, 952, v115
	ds_read2_b32 v[188:189], v115 offset0:0 offset1:1
	ds_read2_b32 v[190:191], v115 offset0:2 offset1:3
	ds_read2_b32 v[192:193], v115 offset0:8 offset1:9
	ds_read2_b32 v[194:195], v115 offset0:10 offset1:11
	ds_read2_b32 v[196:197], v115 offset0:17 offset1:18
	ds_read2_b32 v[198:199], v115 offset0:19 offset1:20
	ds_read2_b32 v[200:201], v115 offset0:25 offset1:26
	ds_read2_b32 v[202:203], v115 offset0:27 offset1:28
	v_mfma_f32_32x32x16_bf16 v[0:15], v[64:67], v[72:75], v[0:15]
	v_mfma_f32_32x32x16_bf16 v[16:31], v[64:67], v[76:79], v[16:31]
	v_mfma_f32_32x32x16_bf16 v[0:15], v[68:71], v[220:223], v[0:15]
	v_mfma_f32_32x32x16_bf16 v[16:31], v[68:71], v[224:227], v[16:31]
	global_load_dwordx4 v[116:119], v235, s[84:85]
	global_load_dwordx4 v[120:123], v236, s[84:85]
	global_load_dwordx4 v[124:127], v237, s[84:85]
	global_load_dwordx4 v[128:131], v238, s[84:85]
	global_load_dwordx4 v[132:135], v100, s[84:85] offset:768
	global_load_dwordx4 v[136:139], v149, s[84:85] offset:768
	global_load_dwordx4 v[140:143], v100, s[84:85] offset:832
	global_load_dwordx4 v[144:147], v149, s[84:85] offset:832
	s_add_u32 s84, s84, 0x30000
	s_addc_u32 s85, s85, 0
	ds_read_b64_tr_b16 v[72:73], v231
	ds_read_b64_tr_b16 v[74:75], v231 offset:512
	ds_read_b64_tr_b16 v[76:77], v231 offset:2048
	ds_read_b64_tr_b16 v[78:79], v231 offset:2560
	ds_read_b64_tr_b16 v[220:221], v231 offset:1024
	ds_read_b64_tr_b16 v[222:223], v231 offset:1536
	ds_read_b64_tr_b16 v[224:225], v231 offset:3072
	ds_read_b64_tr_b16 v[226:227], v231 offset:3584
	s_waitcnt vmcnt(8)
	ds_write_b128 v247, v[156:159]
	ds_write_b128 v247, v[160:163] offset:1024
	ds_write_b128 v111, v[164:167] offset:2048
	ds_write_b128 v111, v[168:171] offset:3072
	ds_read_b128 v[156:159], v248
	ds_read_b128 v[160:163], v249
	ds_read_b128 v[164:167], v250
	ds_read_b128 v[168:171], v251
	ds_write_b128 v112, v[172:175]
	ds_write_b128 v112, v[176:179] offset:1024
	ds_write_b128 v112, v[180:183] offset:2048
	ds_write_b128 v112, v[184:187] offset:3072
	v_exp_f32_e32 v32, v32
	v_exp_f32_e32 v33, v33
	v_exp_f32_e32 v34, v34
	v_exp_f32_e32 v35, v35
	v_exp_f32_e32 v36, v36
	v_exp_f32_e32 v37, v37
	s_waitcnt lgkmcnt(4)
	v_mfma_f32_32x32x16_bf16 v[188:203], v[156:159], v[48:51], v[188:203]
	v_exp_f32_e32 v38, v38
	v_exp_f32_e32 v39, v39
	v_mfma_f32_32x32x16_bf16 v[188:203], v[160:163], v[52:55], v[188:203]
	v_exp_f32_e32 v40, v40
	v_exp_f32_e32 v41, v41
	v_exp_f32_e32 v42, v42
	v_mfma_f32_32x32x16_bf16 v[188:203], v[164:167], v[56:59], v[188:203]
	v_exp_f32_e32 v43, v43
	v_exp_f32_e32 v44, v44
	v_mfma_f32_32x32x16_bf16 v[188:203], v[168:171], v[60:63], v[188:203]
	v_exp_f32_e32 v45, v45
	v_exp_f32_e32 v46, v46
	v_exp_f32_e32 v47, v47
	v_cvt_pk_bf16_f32 v64, v32, v33
	v_cvt_pk_bf16_f32 v65, v34, v35
	v_cvt_pk_bf16_f32 v66, v36, v37
	v_cvt_pk_bf16_f32 v67, v38, v39
	v_cvt_pk_bf16_f32 v68, v40, v41
	v_cvt_pk_bf16_f32 v69, v42, v43
	v_cvt_pk_bf16_f32 v70, v44, v45
	v_cvt_pk_bf16_f32 v71, v46, v47
	v_pk_add_f32 v[232:233], v[232:233], v[32:33]
	v_pk_add_f32 v[232:233], v[232:233], v[34:35]
	v_pk_add_f32 v[232:233], v[232:233], v[36:37]
	v_pk_add_f32 v[232:233], v[232:233], v[38:39]
	v_pk_add_f32 v[232:233], v[232:233], v[40:41]
	v_pk_add_f32 v[232:233], v[232:233], v[42:43]
	v_pk_add_f32 v[232:233], v[232:233], v[44:45]
	v_pk_add_f32 v[232:233], v[232:233], v[46:47]
	ds_read2_b32 v[32:33], v115 offset0:34 offset1:35
	ds_read2_b32 v[34:35], v115 offset0:36 offset1:37
	ds_read2_b32 v[36:37], v115 offset0:42 offset1:43
	ds_read2_b32 v[38:39], v115 offset0:44 offset1:45
	ds_read2_b32 v[40:41], v115 offset0:51 offset1:52
	ds_read2_b32 v[42:43], v115 offset0:53 offset1:54
	ds_read2_b32 v[44:45], v115 offset0:59 offset1:60
	ds_read2_b32 v[46:47], v115 offset0:61 offset1:62
	v_mfma_f32_32x32x16_bf16 v[0:15], v[64:67], v[72:75], v[0:15]
	v_mfma_f32_32x32x16_bf16 v[16:31], v[64:67], v[76:79], v[16:31]
	v_mfma_f32_32x32x16_bf16 v[0:15], v[68:71], v[220:223], v[0:15]
	v_mfma_f32_32x32x16_bf16 v[16:31], v[68:71], v[224:227], v[16:31]
	global_load_dwordx4 v[156:159], v235, s[84:85]
	global_load_dwordx4 v[160:163], v236, s[84:85]
	global_load_dwordx4 v[164:167], v237, s[84:85]
	global_load_dwordx4 v[168:171], v238, s[84:85]
	global_load_dwordx4 v[172:175], v100, s[84:85] offset:768
	global_load_dwordx4 v[176:179], v149, s[84:85] offset:768
	global_load_dwordx4 v[180:183], v100, s[84:85] offset:832
	global_load_dwordx4 v[184:187], v149, s[84:85] offset:832
	s_add_u32 s84, s84, 0x30000
	s_addc_u32 s85, s85, 0
	ds_read_b64_tr_b16 v[72:73], v231
	ds_read_b64_tr_b16 v[74:75], v231 offset:512
	ds_read_b64_tr_b16 v[76:77], v231 offset:2048
	ds_read_b64_tr_b16 v[78:79], v231 offset:2560
	ds_read_b64_tr_b16 v[220:221], v231 offset:1024
	ds_read_b64_tr_b16 v[222:223], v231 offset:1536
	ds_read_b64_tr_b16 v[224:225], v231 offset:3072
	ds_read_b64_tr_b16 v[226:227], v231 offset:3584
	s_waitcnt vmcnt(8)
	ds_write_b128 v247, v[116:119]
	ds_write_b128 v247, v[120:123] offset:1024
	ds_write_b128 v111, v[124:127] offset:2048
	ds_write_b128 v111, v[128:131] offset:3072
	ds_read_b128 v[116:119], v248
	ds_read_b128 v[120:123], v249
	ds_read_b128 v[124:127], v250
	ds_read_b128 v[128:131], v251
	ds_write_b128 v112, v[132:135]
	ds_write_b128 v112, v[136:139] offset:1024
	ds_write_b128 v112, v[140:143] offset:2048
	ds_write_b128 v112, v[144:147] offset:3072
	v_exp_f32_e32 v188, v188
	v_exp_f32_e32 v189, v189
	v_exp_f32_e32 v190, v190
	v_exp_f32_e32 v191, v191
	v_exp_f32_e32 v192, v192
	v_exp_f32_e32 v193, v193
	s_waitcnt lgkmcnt(4)
	v_mfma_f32_32x32x16_bf16 v[32:47], v[116:119], v[48:51], v[32:47]
	v_exp_f32_e32 v194, v194
	v_exp_f32_e32 v195, v195
	v_mfma_f32_32x32x16_bf16 v[32:47], v[120:123], v[52:55], v[32:47]
	v_exp_f32_e32 v196, v196
	v_exp_f32_e32 v197, v197
	v_exp_f32_e32 v198, v198
	v_mfma_f32_32x32x16_bf16 v[32:47], v[124:127], v[56:59], v[32:47]
	v_exp_f32_e32 v199, v199
	v_exp_f32_e32 v200, v200
	v_mfma_f32_32x32x16_bf16 v[32:47], v[128:131], v[60:63], v[32:47]
	v_exp_f32_e32 v201, v201
	v_exp_f32_e32 v202, v202
	v_exp_f32_e32 v203, v203
	v_cvt_pk_bf16_f32 v64, v188, v189
	v_cvt_pk_bf16_f32 v65, v190, v191
	v_cvt_pk_bf16_f32 v66, v192, v193
	v_cvt_pk_bf16_f32 v67, v194, v195
	v_cvt_pk_bf16_f32 v68, v196, v197
	v_cvt_pk_bf16_f32 v69, v198, v199
	v_cvt_pk_bf16_f32 v70, v200, v201
	v_cvt_pk_bf16_f32 v71, v202, v203
	v_pk_add_f32 v[232:233], v[232:233], v[188:189]
	v_pk_add_f32 v[232:233], v[232:233], v[190:191]
	v_pk_add_f32 v[232:233], v[232:233], v[192:193]
	v_pk_add_f32 v[232:233], v[232:233], v[194:195]
	v_pk_add_f32 v[232:233], v[232:233], v[196:197]
	v_pk_add_f32 v[232:233], v[232:233], v[198:199]
	v_pk_add_f32 v[232:233], v[232:233], v[200:201]
	v_pk_add_f32 v[232:233], v[232:233], v[202:203]
	ds_read2_b32 v[188:189], v115 offset0:68 offset1:69
	ds_read2_b32 v[190:191], v115 offset0:70 offset1:71
	ds_read2_b32 v[192:193], v115 offset0:76 offset1:77
	ds_read2_b32 v[194:195], v115 offset0:78 offset1:79
	ds_read2_b32 v[196:197], v115 offset0:85 offset1:86
	ds_read2_b32 v[198:199], v115 offset0:87 offset1:88
	ds_read2_b32 v[200:201], v115 offset0:93 offset1:94
	ds_read2_b32 v[202:203], v115 offset0:95 offset1:96
	v_mfma_f32_32x32x16_bf16 v[0:15], v[64:67], v[72:75], v[0:15]
	v_mfma_f32_32x32x16_bf16 v[16:31], v[64:67], v[76:79], v[16:31]
	v_mfma_f32_32x32x16_bf16 v[0:15], v[68:71], v[220:223], v[0:15]
	v_mfma_f32_32x32x16_bf16 v[16:31], v[68:71], v[224:227], v[16:31]
	global_load_dwordx4 v[116:119], v235, s[84:85]
	global_load_dwordx4 v[120:123], v236, s[84:85]
	global_load_dwordx4 v[124:127], v237, s[84:85]
	global_load_dwordx4 v[128:131], v238, s[84:85]
	global_load_dwordx4 v[132:135], v100, s[84:85] offset:768
	global_load_dwordx4 v[136:139], v149, s[84:85] offset:768
	global_load_dwordx4 v[140:143], v100, s[84:85] offset:832
	global_load_dwordx4 v[144:147], v149, s[84:85] offset:832
	s_add_u32 s84, s84, 0x30000
	s_addc_u32 s85, s85, 0
	ds_read_b64_tr_b16 v[72:73], v231
	ds_read_b64_tr_b16 v[74:75], v231 offset:512
	ds_read_b64_tr_b16 v[76:77], v231 offset:2048
	ds_read_b64_tr_b16 v[78:79], v231 offset:2560
	ds_read_b64_tr_b16 v[220:221], v231 offset:1024
	ds_read_b64_tr_b16 v[222:223], v231 offset:1536
	ds_read_b64_tr_b16 v[224:225], v231 offset:3072
	ds_read_b64_tr_b16 v[226:227], v231 offset:3584
	s_waitcnt vmcnt(8)
	ds_write_b128 v247, v[156:159]
	ds_write_b128 v247, v[160:163] offset:1024
	ds_write_b128 v111, v[164:167] offset:2048
	ds_write_b128 v111, v[168:171] offset:3072
	ds_read_b128 v[156:159], v248
	ds_read_b128 v[160:163], v249
	ds_read_b128 v[164:167], v250
	ds_read_b128 v[168:171], v251
	ds_write_b128 v112, v[172:175]
	ds_write_b128 v112, v[176:179] offset:1024
	ds_write_b128 v112, v[180:183] offset:2048
	ds_write_b128 v112, v[184:187] offset:3072
	v_exp_f32_e32 v32, v32
	v_exp_f32_e32 v33, v33
	v_exp_f32_e32 v34, v34
	v_exp_f32_e32 v35, v35
	v_exp_f32_e32 v36, v36
	v_exp_f32_e32 v37, v37
	s_waitcnt lgkmcnt(4)
	v_mfma_f32_32x32x16_bf16 v[188:203], v[156:159], v[48:51], v[188:203]
	v_exp_f32_e32 v38, v38
	v_exp_f32_e32 v39, v39
	v_mfma_f32_32x32x16_bf16 v[188:203], v[160:163], v[52:55], v[188:203]
	v_exp_f32_e32 v40, v40
	v_exp_f32_e32 v41, v41
	v_exp_f32_e32 v42, v42
	v_mfma_f32_32x32x16_bf16 v[188:203], v[164:167], v[56:59], v[188:203]
	v_exp_f32_e32 v43, v43
	v_exp_f32_e32 v44, v44
	v_mfma_f32_32x32x16_bf16 v[188:203], v[168:171], v[60:63], v[188:203]
	v_exp_f32_e32 v45, v45
	v_exp_f32_e32 v46, v46
	v_exp_f32_e32 v47, v47
	v_cvt_pk_bf16_f32 v64, v32, v33
	v_cvt_pk_bf16_f32 v65, v34, v35
	v_cvt_pk_bf16_f32 v66, v36, v37
	v_cvt_pk_bf16_f32 v67, v38, v39
	v_cvt_pk_bf16_f32 v68, v40, v41
	v_cvt_pk_bf16_f32 v69, v42, v43
	v_cvt_pk_bf16_f32 v70, v44, v45
	v_cvt_pk_bf16_f32 v71, v46, v47
	v_pk_add_f32 v[232:233], v[232:233], v[32:33]
	v_pk_add_f32 v[232:233], v[232:233], v[34:35]
	v_pk_add_f32 v[232:233], v[232:233], v[36:37]
	v_pk_add_f32 v[232:233], v[232:233], v[38:39]
	v_pk_add_f32 v[232:233], v[232:233], v[40:41]
	v_pk_add_f32 v[232:233], v[232:233], v[42:43]
	v_pk_add_f32 v[232:233], v[232:233], v[44:45]
	v_pk_add_f32 v[232:233], v[232:233], v[46:47]
	ds_read2_b32 v[32:33], v115 offset0:102 offset1:103
	ds_read2_b32 v[34:35], v115 offset0:104 offset1:105
	ds_read2_b32 v[36:37], v115 offset0:110 offset1:111
	ds_read2_b32 v[38:39], v115 offset0:112 offset1:113
	ds_read2_b32 v[40:41], v115 offset0:119 offset1:120
	ds_read2_b32 v[42:43], v115 offset0:121 offset1:122
	ds_read2_b32 v[44:45], v115 offset0:127 offset1:128
	ds_read2_b32 v[46:47], v115 offset0:129 offset1:130
	v_mfma_f32_32x32x16_bf16 v[0:15], v[64:67], v[72:75], v[0:15]
	v_mfma_f32_32x32x16_bf16 v[16:31], v[64:67], v[76:79], v[16:31]
	v_mfma_f32_32x32x16_bf16 v[0:15], v[68:71], v[220:223], v[0:15]
	v_mfma_f32_32x32x16_bf16 v[16:31], v[68:71], v[224:227], v[16:31]
	global_load_dwordx4 v[156:159], v235, s[84:85]
	global_load_dwordx4 v[160:163], v236, s[84:85]
	global_load_dwordx4 v[164:167], v237, s[84:85]
	global_load_dwordx4 v[168:171], v238, s[84:85]
	global_load_dwordx4 v[172:175], v100, s[84:85] offset:768
	global_load_dwordx4 v[176:179], v149, s[84:85] offset:768
	global_load_dwordx4 v[180:183], v100, s[84:85] offset:832
	global_load_dwordx4 v[184:187], v149, s[84:85] offset:832
	s_add_u32 s84, s84, 0x30000
	s_addc_u32 s85, s85, 0
	ds_read_b64_tr_b16 v[72:73], v231
	ds_read_b64_tr_b16 v[74:75], v231 offset:512
	ds_read_b64_tr_b16 v[76:77], v231 offset:2048
	ds_read_b64_tr_b16 v[78:79], v231 offset:2560
	ds_read_b64_tr_b16 v[220:221], v231 offset:1024
	ds_read_b64_tr_b16 v[222:223], v231 offset:1536
	ds_read_b64_tr_b16 v[224:225], v231 offset:3072
	ds_read_b64_tr_b16 v[226:227], v231 offset:3584
	s_waitcnt vmcnt(8)
	ds_write_b128 v247, v[116:119]
	ds_write_b128 v247, v[120:123] offset:1024
	ds_write_b128 v111, v[124:127] offset:2048
	ds_write_b128 v111, v[128:131] offset:3072
	ds_read_b128 v[116:119], v248
	ds_read_b128 v[120:123], v249
	ds_read_b128 v[124:127], v250
	ds_read_b128 v[128:131], v251
	ds_write_b128 v112, v[132:135]
	ds_write_b128 v112, v[136:139] offset:1024
	ds_write_b128 v112, v[140:143] offset:2048
	ds_write_b128 v112, v[144:147] offset:3072
	v_exp_f32_e32 v188, v188
	v_exp_f32_e32 v189, v189
	v_exp_f32_e32 v190, v190
	v_exp_f32_e32 v191, v191
	v_exp_f32_e32 v192, v192
	v_exp_f32_e32 v193, v193
	s_waitcnt lgkmcnt(4)
	v_mfma_f32_32x32x16_bf16 v[32:47], v[116:119], v[48:51], v[32:47]
	v_exp_f32_e32 v194, v194
	v_exp_f32_e32 v195, v195
	v_mfma_f32_32x32x16_bf16 v[32:47], v[120:123], v[52:55], v[32:47]
	v_exp_f32_e32 v196, v196
	v_exp_f32_e32 v197, v197
	v_exp_f32_e32 v198, v198
	v_mfma_f32_32x32x16_bf16 v[32:47], v[124:127], v[56:59], v[32:47]
	v_exp_f32_e32 v199, v199
	v_exp_f32_e32 v200, v200
	v_mfma_f32_32x32x16_bf16 v[32:47], v[128:131], v[60:63], v[32:47]
	v_exp_f32_e32 v201, v201
	v_exp_f32_e32 v202, v202
	v_exp_f32_e32 v203, v203
	v_cvt_pk_bf16_f32 v64, v188, v189
	v_cvt_pk_bf16_f32 v65, v190, v191
	v_cvt_pk_bf16_f32 v66, v192, v193
	v_cvt_pk_bf16_f32 v67, v194, v195
	v_cvt_pk_bf16_f32 v68, v196, v197
	v_cvt_pk_bf16_f32 v69, v198, v199
	v_cvt_pk_bf16_f32 v70, v200, v201
	v_cvt_pk_bf16_f32 v71, v202, v203
	v_pk_add_f32 v[232:233], v[232:233], v[188:189]
	v_pk_add_f32 v[232:233], v[232:233], v[190:191]
	v_pk_add_f32 v[232:233], v[232:233], v[192:193]
	v_pk_add_f32 v[232:233], v[232:233], v[194:195]
	v_pk_add_f32 v[232:233], v[232:233], v[196:197]
	v_pk_add_f32 v[232:233], v[232:233], v[198:199]
	v_pk_add_f32 v[232:233], v[232:233], v[200:201]
	v_pk_add_f32 v[232:233], v[232:233], v[202:203]
	ds_read2_b32 v[188:189], v115 offset0:136 offset1:137
	ds_read2_b32 v[190:191], v115 offset0:138 offset1:139
	ds_read2_b32 v[192:193], v115 offset0:144 offset1:145
	ds_read2_b32 v[194:195], v115 offset0:146 offset1:147
	ds_read2_b32 v[196:197], v115 offset0:153 offset1:154
	ds_read2_b32 v[198:199], v115 offset0:155 offset1:156
	ds_read2_b32 v[200:201], v115 offset0:161 offset1:162
	ds_read2_b32 v[202:203], v115 offset0:163 offset1:164
	v_mfma_f32_32x32x16_bf16 v[0:15], v[64:67], v[72:75], v[0:15]
	v_mfma_f32_32x32x16_bf16 v[16:31], v[64:67], v[76:79], v[16:31]
	v_mfma_f32_32x32x16_bf16 v[0:15], v[68:71], v[220:223], v[0:15]
	v_mfma_f32_32x32x16_bf16 v[16:31], v[68:71], v[224:227], v[16:31]
	global_load_dwordx4 v[116:119], v235, s[84:85]
	global_load_dwordx4 v[120:123], v236, s[84:85]
	global_load_dwordx4 v[124:127], v237, s[84:85]
	global_load_dwordx4 v[128:131], v238, s[84:85]
	global_load_dwordx4 v[132:135], v100, s[84:85] offset:768
	global_load_dwordx4 v[136:139], v149, s[84:85] offset:768
	global_load_dwordx4 v[140:143], v100, s[84:85] offset:832
	global_load_dwordx4 v[144:147], v149, s[84:85] offset:832
	s_add_u32 s84, s84, 0x30000
	s_addc_u32 s85, s85, 0
	ds_read_b64_tr_b16 v[72:73], v231
	ds_read_b64_tr_b16 v[74:75], v231 offset:512
	ds_read_b64_tr_b16 v[76:77], v231 offset:2048
	ds_read_b64_tr_b16 v[78:79], v231 offset:2560
	ds_read_b64_tr_b16 v[220:221], v231 offset:1024
	ds_read_b64_tr_b16 v[222:223], v231 offset:1536
	ds_read_b64_tr_b16 v[224:225], v231 offset:3072
	ds_read_b64_tr_b16 v[226:227], v231 offset:3584
	s_waitcnt vmcnt(8)
	ds_write_b128 v247, v[156:159]
	ds_write_b128 v247, v[160:163] offset:1024
	ds_write_b128 v111, v[164:167] offset:2048
	ds_write_b128 v111, v[168:171] offset:3072
	ds_read_b128 v[156:159], v248
	ds_read_b128 v[160:163], v249
	ds_read_b128 v[164:167], v250
	ds_read_b128 v[168:171], v251
	ds_write_b128 v112, v[172:175]
	ds_write_b128 v112, v[176:179] offset:1024
	ds_write_b128 v112, v[180:183] offset:2048
	ds_write_b128 v112, v[184:187] offset:3072
	v_exp_f32_e32 v32, v32
	v_exp_f32_e32 v33, v33
	v_exp_f32_e32 v34, v34
	v_exp_f32_e32 v35, v35
	v_exp_f32_e32 v36, v36
	v_exp_f32_e32 v37, v37
	s_waitcnt lgkmcnt(4)
	v_mfma_f32_32x32x16_bf16 v[188:203], v[156:159], v[48:51], v[188:203]
	v_exp_f32_e32 v38, v38
	v_exp_f32_e32 v39, v39
	v_mfma_f32_32x32x16_bf16 v[188:203], v[160:163], v[52:55], v[188:203]
	v_exp_f32_e32 v40, v40
	v_exp_f32_e32 v41, v41
	v_exp_f32_e32 v42, v42
	v_mfma_f32_32x32x16_bf16 v[188:203], v[164:167], v[56:59], v[188:203]
	v_exp_f32_e32 v43, v43
	v_exp_f32_e32 v44, v44
	v_mfma_f32_32x32x16_bf16 v[188:203], v[168:171], v[60:63], v[188:203]
	v_exp_f32_e32 v45, v45
	v_exp_f32_e32 v46, v46
	v_exp_f32_e32 v47, v47
	v_cvt_pk_bf16_f32 v64, v32, v33
	v_cvt_pk_bf16_f32 v65, v34, v35
	v_cvt_pk_bf16_f32 v66, v36, v37
	v_cvt_pk_bf16_f32 v67, v38, v39
	v_cvt_pk_bf16_f32 v68, v40, v41
	v_cvt_pk_bf16_f32 v69, v42, v43
	v_cvt_pk_bf16_f32 v70, v44, v45
	v_cvt_pk_bf16_f32 v71, v46, v47
	v_pk_add_f32 v[232:233], v[232:233], v[32:33]
	v_pk_add_f32 v[232:233], v[232:233], v[34:35]
	v_pk_add_f32 v[232:233], v[232:233], v[36:37]
	v_pk_add_f32 v[232:233], v[232:233], v[38:39]
	v_pk_add_f32 v[232:233], v[232:233], v[40:41]
	v_pk_add_f32 v[232:233], v[232:233], v[42:43]
	v_pk_add_f32 v[232:233], v[232:233], v[44:45]
	v_pk_add_f32 v[232:233], v[232:233], v[46:47]
	ds_read2_b32 v[32:33], v115 offset0:170 offset1:171
	ds_read2_b32 v[34:35], v115 offset0:172 offset1:173
	ds_read2_b32 v[36:37], v115 offset0:178 offset1:179
	ds_read2_b32 v[38:39], v115 offset0:180 offset1:181
	ds_read2_b32 v[40:41], v115 offset0:187 offset1:188
	ds_read2_b32 v[42:43], v115 offset0:189 offset1:190
	ds_read2_b32 v[44:45], v115 offset0:195 offset1:196
	ds_read2_b32 v[46:47], v115 offset0:197 offset1:198
	v_mfma_f32_32x32x16_bf16 v[0:15], v[64:67], v[72:75], v[0:15]
	v_mfma_f32_32x32x16_bf16 v[16:31], v[64:67], v[76:79], v[16:31]
	v_mfma_f32_32x32x16_bf16 v[0:15], v[68:71], v[220:223], v[0:15]
	v_mfma_f32_32x32x16_bf16 v[16:31], v[68:71], v[224:227], v[16:31]
	global_load_dwordx4 v[156:159], v235, s[84:85]
	global_load_dwordx4 v[160:163], v236, s[84:85]
	global_load_dwordx4 v[164:167], v237, s[84:85]
	global_load_dwordx4 v[168:171], v238, s[84:85]
	global_load_dwordx4 v[172:175], v100, s[84:85] offset:768
	global_load_dwordx4 v[176:179], v149, s[84:85] offset:768
	global_load_dwordx4 v[180:183], v100, s[84:85] offset:832
	global_load_dwordx4 v[184:187], v149, s[84:85] offset:832
	s_add_u32 s84, s84, 0x30000
	s_addc_u32 s85, s85, 0
	ds_read_b64_tr_b16 v[72:73], v231
	ds_read_b64_tr_b16 v[74:75], v231 offset:512
	ds_read_b64_tr_b16 v[76:77], v231 offset:2048
	ds_read_b64_tr_b16 v[78:79], v231 offset:2560
	ds_read_b64_tr_b16 v[220:221], v231 offset:1024
	ds_read_b64_tr_b16 v[222:223], v231 offset:1536
	ds_read_b64_tr_b16 v[224:225], v231 offset:3072
	ds_read_b64_tr_b16 v[226:227], v231 offset:3584
	s_waitcnt vmcnt(8)
	ds_write_b128 v247, v[116:119]
	ds_write_b128 v247, v[120:123] offset:1024
	ds_write_b128 v111, v[124:127] offset:2048
	ds_write_b128 v111, v[128:131] offset:3072
	ds_read_b128 v[116:119], v248
	ds_read_b128 v[120:123], v249
	ds_read_b128 v[124:127], v250
	ds_read_b128 v[128:131], v251
	ds_write_b128 v112, v[132:135]
	ds_write_b128 v112, v[136:139] offset:1024
	ds_write_b128 v112, v[140:143] offset:2048
	ds_write_b128 v112, v[144:147] offset:3072
	v_exp_f32_e32 v188, v188
	v_exp_f32_e32 v189, v189
	v_exp_f32_e32 v190, v190
	v_exp_f32_e32 v191, v191
	v_exp_f32_e32 v192, v192
	v_exp_f32_e32 v193, v193
	s_waitcnt lgkmcnt(4)
	v_mfma_f32_32x32x16_bf16 v[32:47], v[116:119], v[48:51], v[32:47]
	v_exp_f32_e32 v194, v194
	v_exp_f32_e32 v195, v195
	v_mfma_f32_32x32x16_bf16 v[32:47], v[120:123], v[52:55], v[32:47]
	v_exp_f32_e32 v196, v196
	v_exp_f32_e32 v197, v197
	v_exp_f32_e32 v198, v198
	v_mfma_f32_32x32x16_bf16 v[32:47], v[124:127], v[56:59], v[32:47]
	v_exp_f32_e32 v199, v199
	v_exp_f32_e32 v200, v200
	v_mfma_f32_32x32x16_bf16 v[32:47], v[128:131], v[60:63], v[32:47]
	v_exp_f32_e32 v201, v201
	v_exp_f32_e32 v202, v202
	v_exp_f32_e32 v203, v203
	v_cvt_pk_bf16_f32 v64, v188, v189
	v_cvt_pk_bf16_f32 v65, v190, v191
	v_cvt_pk_bf16_f32 v66, v192, v193
	v_cvt_pk_bf16_f32 v67, v194, v195
	v_cvt_pk_bf16_f32 v68, v196, v197
	v_cvt_pk_bf16_f32 v69, v198, v199
	v_cvt_pk_bf16_f32 v70, v200, v201
	v_cvt_pk_bf16_f32 v71, v202, v203
	v_pk_add_f32 v[232:233], v[232:233], v[188:189]
	v_pk_add_f32 v[232:233], v[232:233], v[190:191]
	v_pk_add_f32 v[232:233], v[232:233], v[192:193]
	v_pk_add_f32 v[232:233], v[232:233], v[194:195]
	v_pk_add_f32 v[232:233], v[232:233], v[196:197]
	v_pk_add_f32 v[232:233], v[232:233], v[198:199]
	v_pk_add_f32 v[232:233], v[232:233], v[200:201]
	v_pk_add_f32 v[232:233], v[232:233], v[202:203]
	ds_read2_b32 v[188:189], v115 offset0:204 offset1:205
	ds_read2_b32 v[190:191], v115 offset0:206 offset1:207
	ds_read2_b32 v[192:193], v115 offset0:212 offset1:213
	ds_read2_b32 v[194:195], v115 offset0:214 offset1:215
	ds_read2_b32 v[196:197], v115 offset0:221 offset1:222
	ds_read2_b32 v[198:199], v115 offset0:223 offset1:224
	ds_read2_b32 v[200:201], v115 offset0:229 offset1:230
	ds_read2_b32 v[202:203], v115 offset0:231 offset1:232
	v_mfma_f32_32x32x16_bf16 v[0:15], v[64:67], v[72:75], v[0:15]
	v_mfma_f32_32x32x16_bf16 v[16:31], v[64:67], v[76:79], v[16:31]
	v_mfma_f32_32x32x16_bf16 v[0:15], v[68:71], v[220:223], v[0:15]
	v_mfma_f32_32x32x16_bf16 v[16:31], v[68:71], v[224:227], v[16:31]
	global_load_dwordx4 v[116:119], v235, s[84:85]
	global_load_dwordx4 v[120:123], v236, s[84:85]
	global_load_dwordx4 v[124:127], v237, s[84:85]
	global_load_dwordx4 v[128:131], v238, s[84:85]
	global_load_dwordx4 v[132:135], v100, s[84:85] offset:768
	global_load_dwordx4 v[136:139], v149, s[84:85] offset:768
	global_load_dwordx4 v[140:143], v100, s[84:85] offset:832
	global_load_dwordx4 v[144:147], v149, s[84:85] offset:832
	s_add_u32 s84, s84, 0x30000
	s_addc_u32 s85, s85, 0
	ds_read_b64_tr_b16 v[72:73], v231
	ds_read_b64_tr_b16 v[74:75], v231 offset:512
	ds_read_b64_tr_b16 v[76:77], v231 offset:2048
	ds_read_b64_tr_b16 v[78:79], v231 offset:2560
	ds_read_b64_tr_b16 v[220:221], v231 offset:1024
	ds_read_b64_tr_b16 v[222:223], v231 offset:1536
	ds_read_b64_tr_b16 v[224:225], v231 offset:3072
	ds_read_b64_tr_b16 v[226:227], v231 offset:3584
	s_waitcnt vmcnt(8)
	ds_write_b128 v247, v[156:159]
	ds_write_b128 v247, v[160:163] offset:1024
	ds_write_b128 v111, v[164:167] offset:2048
	ds_write_b128 v111, v[168:171] offset:3072
	ds_read_b128 v[156:159], v248
	ds_read_b128 v[160:163], v249
	ds_read_b128 v[164:167], v250
	ds_read_b128 v[168:171], v251
	ds_write_b128 v112, v[172:175]
	ds_write_b128 v112, v[176:179] offset:1024
	ds_write_b128 v112, v[180:183] offset:2048
	ds_write_b128 v112, v[184:187] offset:3072
	v_exp_f32_e32 v32, v32
	v_exp_f32_e32 v33, v33
	v_exp_f32_e32 v34, v34
	v_exp_f32_e32 v35, v35
	v_exp_f32_e32 v36, v36
	v_exp_f32_e32 v37, v37
	s_waitcnt lgkmcnt(4)
	v_mfma_f32_32x32x16_bf16 v[188:203], v[156:159], v[48:51], v[188:203]
	v_exp_f32_e32 v38, v38
	v_exp_f32_e32 v39, v39
	v_mfma_f32_32x32x16_bf16 v[188:203], v[160:163], v[52:55], v[188:203]
	v_exp_f32_e32 v40, v40
	v_exp_f32_e32 v41, v41
	v_exp_f32_e32 v42, v42
	v_mfma_f32_32x32x16_bf16 v[188:203], v[164:167], v[56:59], v[188:203]
	v_exp_f32_e32 v43, v43
	v_exp_f32_e32 v44, v44
	v_mfma_f32_32x32x16_bf16 v[188:203], v[168:171], v[60:63], v[188:203]
	v_exp_f32_e32 v45, v45
	v_exp_f32_e32 v46, v46
	v_exp_f32_e32 v47, v47
	v_cvt_pk_bf16_f32 v64, v32, v33
	v_cvt_pk_bf16_f32 v65, v34, v35
	v_cvt_pk_bf16_f32 v66, v36, v37
	v_cvt_pk_bf16_f32 v67, v38, v39
	v_cvt_pk_bf16_f32 v68, v40, v41
	v_cvt_pk_bf16_f32 v69, v42, v43
	v_cvt_pk_bf16_f32 v70, v44, v45
	v_cvt_pk_bf16_f32 v71, v46, v47
	v_pk_add_f32 v[232:233], v[232:233], v[32:33]
	v_pk_add_f32 v[232:233], v[232:233], v[34:35]
	v_pk_add_f32 v[232:233], v[232:233], v[36:37]
	v_pk_add_f32 v[232:233], v[232:233], v[38:39]
	v_pk_add_f32 v[232:233], v[232:233], v[40:41]
	v_pk_add_f32 v[232:233], v[232:233], v[42:43]
	v_pk_add_f32 v[232:233], v[232:233], v[44:45]
	v_pk_add_f32 v[232:233], v[232:233], v[46:47]
	v_add_u32_e32 v115, 952, v115
	ds_read2_b32 v[32:33], v115 offset0:0 offset1:1
	ds_read2_b32 v[34:35], v115 offset0:2 offset1:3
	ds_read2_b32 v[36:37], v115 offset0:8 offset1:9
	ds_read2_b32 v[38:39], v115 offset0:10 offset1:11
	ds_read2_b32 v[40:41], v115 offset0:17 offset1:18
	ds_read2_b32 v[42:43], v115 offset0:19 offset1:20
	ds_read2_b32 v[44:45], v115 offset0:25 offset1:26
	ds_read2_b32 v[46:47], v115 offset0:27 offset1:28
	v_mfma_f32_32x32x16_bf16 v[0:15], v[64:67], v[72:75], v[0:15]
	v_mfma_f32_32x32x16_bf16 v[16:31], v[64:67], v[76:79], v[16:31]
	v_mfma_f32_32x32x16_bf16 v[0:15], v[68:71], v[220:223], v[0:15]
	v_mfma_f32_32x32x16_bf16 v[16:31], v[68:71], v[224:227], v[16:31]
	global_load_dwordx4 v[156:159], v235, s[84:85]
	global_load_dwordx4 v[160:163], v236, s[84:85]
	global_load_dwordx4 v[164:167], v237, s[84:85]
	global_load_dwordx4 v[168:171], v238, s[84:85]
	global_load_dwordx4 v[172:175], v100, s[84:85] offset:768
	global_load_dwordx4 v[176:179], v149, s[84:85] offset:768
	global_load_dwordx4 v[180:183], v100, s[84:85] offset:832
	global_load_dwordx4 v[184:187], v149, s[84:85] offset:832
	s_add_u32 s84, s84, 0x30000
	s_addc_u32 s85, s85, 0
	ds_read_b64_tr_b16 v[72:73], v231
	ds_read_b64_tr_b16 v[74:75], v231 offset:512
	ds_read_b64_tr_b16 v[76:77], v231 offset:2048
	ds_read_b64_tr_b16 v[78:79], v231 offset:2560
	ds_read_b64_tr_b16 v[220:221], v231 offset:1024
	ds_read_b64_tr_b16 v[222:223], v231 offset:1536
	ds_read_b64_tr_b16 v[224:225], v231 offset:3072
	ds_read_b64_tr_b16 v[226:227], v231 offset:3584
	s_waitcnt vmcnt(8)
	ds_write_b128 v247, v[116:119]
	ds_write_b128 v247, v[120:123] offset:1024
	ds_write_b128 v111, v[124:127] offset:2048
	ds_write_b128 v111, v[128:131] offset:3072
	ds_read_b128 v[116:119], v248
	ds_read_b128 v[120:123], v249
	ds_read_b128 v[124:127], v250
	ds_read_b128 v[128:131], v251
	ds_write_b128 v112, v[132:135]
	ds_write_b128 v112, v[136:139] offset:1024
	ds_write_b128 v112, v[140:143] offset:2048
	ds_write_b128 v112, v[144:147] offset:3072
	v_exp_f32_e32 v188, v188
	v_exp_f32_e32 v189, v189
	v_exp_f32_e32 v190, v190
	v_exp_f32_e32 v191, v191
	v_exp_f32_e32 v192, v192
	v_exp_f32_e32 v193, v193
	s_waitcnt lgkmcnt(4)
	v_mfma_f32_32x32x16_bf16 v[32:47], v[116:119], v[48:51], v[32:47]
	v_exp_f32_e32 v194, v194
	v_exp_f32_e32 v195, v195
	v_mfma_f32_32x32x16_bf16 v[32:47], v[120:123], v[52:55], v[32:47]
	v_exp_f32_e32 v196, v196
	v_exp_f32_e32 v197, v197
	v_exp_f32_e32 v198, v198
	v_mfma_f32_32x32x16_bf16 v[32:47], v[124:127], v[56:59], v[32:47]
	v_exp_f32_e32 v199, v199
	v_exp_f32_e32 v200, v200
	v_mfma_f32_32x32x16_bf16 v[32:47], v[128:131], v[60:63], v[32:47]
	v_exp_f32_e32 v201, v201
	v_exp_f32_e32 v202, v202
	v_exp_f32_e32 v203, v203
	v_cvt_pk_bf16_f32 v64, v188, v189
	v_cvt_pk_bf16_f32 v65, v190, v191
	v_cvt_pk_bf16_f32 v66, v192, v193
	v_cvt_pk_bf16_f32 v67, v194, v195
	v_cvt_pk_bf16_f32 v68, v196, v197
	v_cvt_pk_bf16_f32 v69, v198, v199
	v_cvt_pk_bf16_f32 v70, v200, v201
	v_cvt_pk_bf16_f32 v71, v202, v203
	v_pk_add_f32 v[232:233], v[232:233], v[188:189]
	v_pk_add_f32 v[232:233], v[232:233], v[190:191]
	v_pk_add_f32 v[232:233], v[232:233], v[192:193]
	v_pk_add_f32 v[232:233], v[232:233], v[194:195]
	v_pk_add_f32 v[232:233], v[232:233], v[196:197]
	v_pk_add_f32 v[232:233], v[232:233], v[198:199]
	v_pk_add_f32 v[232:233], v[232:233], v[200:201]
	v_pk_add_f32 v[232:233], v[232:233], v[202:203]
	ds_read2_b32 v[188:189], v115 offset0:34 offset1:35
	ds_read2_b32 v[190:191], v115 offset0:36 offset1:37
	ds_read2_b32 v[192:193], v115 offset0:42 offset1:43
	ds_read2_b32 v[194:195], v115 offset0:44 offset1:45
	ds_read2_b32 v[196:197], v115 offset0:51 offset1:52
	ds_read2_b32 v[198:199], v115 offset0:53 offset1:54
	ds_read2_b32 v[200:201], v115 offset0:59 offset1:60
	ds_read2_b32 v[202:203], v115 offset0:61 offset1:62
	v_mfma_f32_32x32x16_bf16 v[0:15], v[64:67], v[72:75], v[0:15]
	v_mfma_f32_32x32x16_bf16 v[16:31], v[64:67], v[76:79], v[16:31]
	v_mfma_f32_32x32x16_bf16 v[0:15], v[68:71], v[220:223], v[0:15]
	v_mfma_f32_32x32x16_bf16 v[16:31], v[68:71], v[224:227], v[16:31]
	global_load_dwordx4 v[116:119], v235, s[84:85]
	global_load_dwordx4 v[120:123], v236, s[84:85]
	global_load_dwordx4 v[124:127], v237, s[84:85]
	global_load_dwordx4 v[128:131], v238, s[84:85]
	global_load_dwordx4 v[132:135], v100, s[84:85] offset:768
	global_load_dwordx4 v[136:139], v149, s[84:85] offset:768
	global_load_dwordx4 v[140:143], v100, s[84:85] offset:832
	global_load_dwordx4 v[144:147], v149, s[84:85] offset:832
	s_add_u32 s84, s84, 0x30000
	s_addc_u32 s85, s85, 0
	ds_read_b64_tr_b16 v[72:73], v231
	ds_read_b64_tr_b16 v[74:75], v231 offset:512
	ds_read_b64_tr_b16 v[76:77], v231 offset:2048
	ds_read_b64_tr_b16 v[78:79], v231 offset:2560
	ds_read_b64_tr_b16 v[220:221], v231 offset:1024
	ds_read_b64_tr_b16 v[222:223], v231 offset:1536
	ds_read_b64_tr_b16 v[224:225], v231 offset:3072
	ds_read_b64_tr_b16 v[226:227], v231 offset:3584
	s_waitcnt vmcnt(8)
	ds_write_b128 v247, v[156:159]
	ds_write_b128 v247, v[160:163] offset:1024
	ds_write_b128 v111, v[164:167] offset:2048
	ds_write_b128 v111, v[168:171] offset:3072
	ds_read_b128 v[156:159], v248
	ds_read_b128 v[160:163], v249
	ds_read_b128 v[164:167], v250
	ds_read_b128 v[168:171], v251
	ds_write_b128 v112, v[172:175]
	ds_write_b128 v112, v[176:179] offset:1024
	ds_write_b128 v112, v[180:183] offset:2048
	ds_write_b128 v112, v[184:187] offset:3072
	v_exp_f32_e32 v32, v32
	v_exp_f32_e32 v33, v33
	v_exp_f32_e32 v34, v34
	v_exp_f32_e32 v35, v35
	v_exp_f32_e32 v36, v36
	v_exp_f32_e32 v37, v37
	s_waitcnt lgkmcnt(4)
	v_mfma_f32_32x32x16_bf16 v[188:203], v[156:159], v[48:51], v[188:203]
	v_exp_f32_e32 v38, v38
	v_exp_f32_e32 v39, v39
	v_mfma_f32_32x32x16_bf16 v[188:203], v[160:163], v[52:55], v[188:203]
	v_exp_f32_e32 v40, v40
	v_exp_f32_e32 v41, v41
	v_exp_f32_e32 v42, v42
	v_mfma_f32_32x32x16_bf16 v[188:203], v[164:167], v[56:59], v[188:203]
	v_exp_f32_e32 v43, v43
	v_exp_f32_e32 v44, v44
	v_mfma_f32_32x32x16_bf16 v[188:203], v[168:171], v[60:63], v[188:203]
	v_exp_f32_e32 v45, v45
	v_exp_f32_e32 v46, v46
	v_exp_f32_e32 v47, v47
	v_cvt_pk_bf16_f32 v64, v32, v33
	v_cvt_pk_bf16_f32 v65, v34, v35
	v_cvt_pk_bf16_f32 v66, v36, v37
	v_cvt_pk_bf16_f32 v67, v38, v39
	v_cvt_pk_bf16_f32 v68, v40, v41
	v_cvt_pk_bf16_f32 v69, v42, v43
	v_cvt_pk_bf16_f32 v70, v44, v45
	v_cvt_pk_bf16_f32 v71, v46, v47
	v_pk_add_f32 v[232:233], v[232:233], v[32:33]
	v_pk_add_f32 v[232:233], v[232:233], v[34:35]
	v_pk_add_f32 v[232:233], v[232:233], v[36:37]
	v_pk_add_f32 v[232:233], v[232:233], v[38:39]
	v_pk_add_f32 v[232:233], v[232:233], v[40:41]
	v_pk_add_f32 v[232:233], v[232:233], v[42:43]
	v_pk_add_f32 v[232:233], v[232:233], v[44:45]
	v_pk_add_f32 v[232:233], v[232:233], v[46:47]
	ds_read2_b32 v[32:33], v115 offset0:68 offset1:69
	ds_read2_b32 v[34:35], v115 offset0:70 offset1:71
	ds_read2_b32 v[36:37], v115 offset0:76 offset1:77
	ds_read2_b32 v[38:39], v115 offset0:78 offset1:79
	ds_read2_b32 v[40:41], v115 offset0:85 offset1:86
	ds_read2_b32 v[42:43], v115 offset0:87 offset1:88
	ds_read2_b32 v[44:45], v115 offset0:93 offset1:94
	ds_read2_b32 v[46:47], v115 offset0:95 offset1:96
	v_mfma_f32_32x32x16_bf16 v[0:15], v[64:67], v[72:75], v[0:15]
	v_mfma_f32_32x32x16_bf16 v[16:31], v[64:67], v[76:79], v[16:31]
	v_mfma_f32_32x32x16_bf16 v[0:15], v[68:71], v[220:223], v[0:15]
	v_mfma_f32_32x32x16_bf16 v[16:31], v[68:71], v[224:227], v[16:31]
	global_load_dwordx4 v[156:159], v235, s[84:85]
	global_load_dwordx4 v[160:163], v236, s[84:85]
	global_load_dwordx4 v[164:167], v237, s[84:85]
	global_load_dwordx4 v[168:171], v238, s[84:85]
	global_load_dwordx4 v[172:175], v100, s[84:85] offset:768
	global_load_dwordx4 v[176:179], v149, s[84:85] offset:768
	global_load_dwordx4 v[180:183], v100, s[84:85] offset:832
	global_load_dwordx4 v[184:187], v149, s[84:85] offset:832
	s_add_u32 s84, s84, 0x30000
	s_addc_u32 s85, s85, 0
	ds_read_b64_tr_b16 v[72:73], v231
	ds_read_b64_tr_b16 v[74:75], v231 offset:512
	ds_read_b64_tr_b16 v[76:77], v231 offset:2048
	ds_read_b64_tr_b16 v[78:79], v231 offset:2560
	ds_read_b64_tr_b16 v[220:221], v231 offset:1024
	ds_read_b64_tr_b16 v[222:223], v231 offset:1536
	ds_read_b64_tr_b16 v[224:225], v231 offset:3072
	ds_read_b64_tr_b16 v[226:227], v231 offset:3584
	s_waitcnt vmcnt(8)
	ds_write_b128 v247, v[116:119]
	ds_write_b128 v247, v[120:123] offset:1024
	ds_write_b128 v111, v[124:127] offset:2048
	ds_write_b128 v111, v[128:131] offset:3072
	ds_read_b128 v[116:119], v248
	ds_read_b128 v[120:123], v249
	ds_read_b128 v[124:127], v250
	ds_read_b128 v[128:131], v251
	ds_write_b128 v112, v[132:135]
	ds_write_b128 v112, v[136:139] offset:1024
	ds_write_b128 v112, v[140:143] offset:2048
	ds_write_b128 v112, v[144:147] offset:3072
	v_exp_f32_e32 v188, v188
	v_exp_f32_e32 v189, v189
	v_exp_f32_e32 v190, v190
	v_exp_f32_e32 v191, v191
	v_exp_f32_e32 v192, v192
	v_exp_f32_e32 v193, v193
	s_waitcnt lgkmcnt(4)
	v_mfma_f32_32x32x16_bf16 v[32:47], v[116:119], v[48:51], v[32:47]
	v_exp_f32_e32 v194, v194
	v_exp_f32_e32 v195, v195
	v_mfma_f32_32x32x16_bf16 v[32:47], v[120:123], v[52:55], v[32:47]
	v_exp_f32_e32 v196, v196
	v_exp_f32_e32 v197, v197
	v_exp_f32_e32 v198, v198
	v_mfma_f32_32x32x16_bf16 v[32:47], v[124:127], v[56:59], v[32:47]
	v_exp_f32_e32 v199, v199
	v_exp_f32_e32 v200, v200
	v_mfma_f32_32x32x16_bf16 v[32:47], v[128:131], v[60:63], v[32:47]
	v_exp_f32_e32 v201, v201
	v_exp_f32_e32 v202, v202
	v_exp_f32_e32 v203, v203
	v_cvt_pk_bf16_f32 v64, v188, v189
	v_cvt_pk_bf16_f32 v65, v190, v191
	v_cvt_pk_bf16_f32 v66, v192, v193
	v_cvt_pk_bf16_f32 v67, v194, v195
	v_cvt_pk_bf16_f32 v68, v196, v197
	v_cvt_pk_bf16_f32 v69, v198, v199
	v_cvt_pk_bf16_f32 v70, v200, v201
	v_cvt_pk_bf16_f32 v71, v202, v203
	v_pk_add_f32 v[232:233], v[232:233], v[188:189]
	v_pk_add_f32 v[232:233], v[232:233], v[190:191]
	v_pk_add_f32 v[232:233], v[232:233], v[192:193]
	v_pk_add_f32 v[232:233], v[232:233], v[194:195]
	v_pk_add_f32 v[232:233], v[232:233], v[196:197]
	v_pk_add_f32 v[232:233], v[232:233], v[198:199]
	v_pk_add_f32 v[232:233], v[232:233], v[200:201]
	v_pk_add_f32 v[232:233], v[232:233], v[202:203]
	ds_read2_b32 v[188:189], v115 offset0:102 offset1:103
	ds_read2_b32 v[190:191], v115 offset0:104 offset1:105
	ds_read2_b32 v[192:193], v115 offset0:110 offset1:111
	ds_read2_b32 v[194:195], v115 offset0:112 offset1:113
	ds_read2_b32 v[196:197], v115 offset0:119 offset1:120
	ds_read2_b32 v[198:199], v115 offset0:121 offset1:122
	ds_read2_b32 v[200:201], v115 offset0:127 offset1:128
	ds_read2_b32 v[202:203], v115 offset0:129 offset1:130
	v_mfma_f32_32x32x16_bf16 v[0:15], v[64:67], v[72:75], v[0:15]
	v_mfma_f32_32x32x16_bf16 v[16:31], v[64:67], v[76:79], v[16:31]
	v_mfma_f32_32x32x16_bf16 v[0:15], v[68:71], v[220:223], v[0:15]
	v_mfma_f32_32x32x16_bf16 v[16:31], v[68:71], v[224:227], v[16:31]
	global_load_dwordx4 v[116:119], v235, s[84:85]
	global_load_dwordx4 v[120:123], v236, s[84:85]
	global_load_dwordx4 v[124:127], v237, s[84:85]
	global_load_dwordx4 v[128:131], v238, s[84:85]
	global_load_dwordx4 v[132:135], v100, s[84:85] offset:768
	global_load_dwordx4 v[136:139], v149, s[84:85] offset:768
	global_load_dwordx4 v[140:143], v100, s[84:85] offset:832
	global_load_dwordx4 v[144:147], v149, s[84:85] offset:832
	s_add_u32 s84, s84, 0x30000
	s_addc_u32 s85, s85, 0
	ds_read_b64_tr_b16 v[72:73], v231
	ds_read_b64_tr_b16 v[74:75], v231 offset:512
	ds_read_b64_tr_b16 v[76:77], v231 offset:2048
	ds_read_b64_tr_b16 v[78:79], v231 offset:2560
	ds_read_b64_tr_b16 v[220:221], v231 offset:1024
	ds_read_b64_tr_b16 v[222:223], v231 offset:1536
	ds_read_b64_tr_b16 v[224:225], v231 offset:3072
	ds_read_b64_tr_b16 v[226:227], v231 offset:3584
	s_waitcnt vmcnt(8)
	ds_write_b128 v247, v[156:159]
	ds_write_b128 v247, v[160:163] offset:1024
	ds_write_b128 v111, v[164:167] offset:2048
	ds_write_b128 v111, v[168:171] offset:3072
	ds_read_b128 v[156:159], v248
	ds_read_b128 v[160:163], v249
	ds_read_b128 v[164:167], v250
	ds_read_b128 v[168:171], v251
	ds_write_b128 v112, v[172:175]
	ds_write_b128 v112, v[176:179] offset:1024
	ds_write_b128 v112, v[180:183] offset:2048
	ds_write_b128 v112, v[184:187] offset:3072
	v_exp_f32_e32 v32, v32
	v_exp_f32_e32 v33, v33
	v_exp_f32_e32 v34, v34
	v_exp_f32_e32 v35, v35
	v_exp_f32_e32 v36, v36
	v_exp_f32_e32 v37, v37
	s_waitcnt lgkmcnt(4)
	v_mfma_f32_32x32x16_bf16 v[188:203], v[156:159], v[48:51], v[188:203]
	v_exp_f32_e32 v38, v38
	v_exp_f32_e32 v39, v39
	v_mfma_f32_32x32x16_bf16 v[188:203], v[160:163], v[52:55], v[188:203]
	v_exp_f32_e32 v40, v40
	v_exp_f32_e32 v41, v41
	v_exp_f32_e32 v42, v42
	v_mfma_f32_32x32x16_bf16 v[188:203], v[164:167], v[56:59], v[188:203]
	v_exp_f32_e32 v43, v43
	v_exp_f32_e32 v44, v44
	v_mfma_f32_32x32x16_bf16 v[188:203], v[168:171], v[60:63], v[188:203]
	v_exp_f32_e32 v45, v45
	v_exp_f32_e32 v46, v46
	v_exp_f32_e32 v47, v47
	v_cvt_pk_bf16_f32 v64, v32, v33
	v_cvt_pk_bf16_f32 v65, v34, v35
	v_cvt_pk_bf16_f32 v66, v36, v37
	v_cvt_pk_bf16_f32 v67, v38, v39
	v_cvt_pk_bf16_f32 v68, v40, v41
	v_cvt_pk_bf16_f32 v69, v42, v43
	v_cvt_pk_bf16_f32 v70, v44, v45
	v_cvt_pk_bf16_f32 v71, v46, v47
	v_pk_add_f32 v[232:233], v[232:233], v[32:33]
	v_pk_add_f32 v[232:233], v[232:233], v[34:35]
	v_pk_add_f32 v[232:233], v[232:233], v[36:37]
	v_pk_add_f32 v[232:233], v[232:233], v[38:39]
	v_pk_add_f32 v[232:233], v[232:233], v[40:41]
	v_pk_add_f32 v[232:233], v[232:233], v[42:43]
	v_pk_add_f32 v[232:233], v[232:233], v[44:45]
	v_pk_add_f32 v[232:233], v[232:233], v[46:47]
	ds_read2_b32 v[32:33], v115 offset0:136 offset1:137
	ds_read2_b32 v[34:35], v115 offset0:138 offset1:139
	ds_read2_b32 v[36:37], v115 offset0:144 offset1:145
	ds_read2_b32 v[38:39], v115 offset0:146 offset1:147
	ds_read2_b32 v[40:41], v115 offset0:153 offset1:154
	ds_read2_b32 v[42:43], v115 offset0:155 offset1:156
	ds_read2_b32 v[44:45], v115 offset0:161 offset1:162
	ds_read2_b32 v[46:47], v115 offset0:163 offset1:164
	v_mfma_f32_32x32x16_bf16 v[0:15], v[64:67], v[72:75], v[0:15]
	v_mfma_f32_32x32x16_bf16 v[16:31], v[64:67], v[76:79], v[16:31]
	v_mfma_f32_32x32x16_bf16 v[0:15], v[68:71], v[220:223], v[0:15]
	v_mfma_f32_32x32x16_bf16 v[16:31], v[68:71], v[224:227], v[16:31]
	global_load_dwordx4 v[156:159], v235, s[84:85]
	global_load_dwordx4 v[160:163], v236, s[84:85]
	global_load_dwordx4 v[164:167], v237, s[84:85]
	global_load_dwordx4 v[168:171], v238, s[84:85]
	global_load_dwordx4 v[172:175], v100, s[84:85] offset:768
	global_load_dwordx4 v[176:179], v149, s[84:85] offset:768
	global_load_dwordx4 v[180:183], v100, s[84:85] offset:832
	global_load_dwordx4 v[184:187], v149, s[84:85] offset:832
	ds_read_b64_tr_b16 v[72:73], v231
	ds_read_b64_tr_b16 v[74:75], v231 offset:512
	ds_read_b64_tr_b16 v[76:77], v231 offset:2048
	ds_read_b64_tr_b16 v[78:79], v231 offset:2560
	ds_read_b64_tr_b16 v[220:221], v231 offset:1024
	ds_read_b64_tr_b16 v[222:223], v231 offset:1536
	ds_read_b64_tr_b16 v[224:225], v231 offset:3072
	ds_read_b64_tr_b16 v[226:227], v231 offset:3584
	s_waitcnt vmcnt(8)
	ds_write_b128 v247, v[116:119]
	ds_write_b128 v247, v[120:123] offset:1024
	ds_write_b128 v111, v[124:127] offset:2048
	ds_write_b128 v111, v[128:131] offset:3072
	ds_read_b128 v[116:119], v248
	ds_read_b128 v[120:123], v249
	ds_read_b128 v[124:127], v250
	ds_read_b128 v[128:131], v251
	ds_write_b128 v112, v[132:135]
	ds_write_b128 v112, v[136:139] offset:1024
	ds_write_b128 v112, v[140:143] offset:2048
	ds_write_b128 v112, v[144:147] offset:3072
	v_exp_f32_e32 v188, v188
	v_exp_f32_e32 v189, v189
	v_exp_f32_e32 v190, v190
	v_exp_f32_e32 v191, v191
	v_exp_f32_e32 v192, v192
	v_exp_f32_e32 v193, v193
	s_waitcnt lgkmcnt(4)
	v_mfma_f32_32x32x16_bf16 v[32:47], v[116:119], v[48:51], v[32:47]
	v_exp_f32_e32 v194, v194
	v_exp_f32_e32 v195, v195
	v_mfma_f32_32x32x16_bf16 v[32:47], v[120:123], v[52:55], v[32:47]
	v_exp_f32_e32 v196, v196
	v_exp_f32_e32 v197, v197
	v_exp_f32_e32 v198, v198
	v_mfma_f32_32x32x16_bf16 v[32:47], v[124:127], v[56:59], v[32:47]
	v_exp_f32_e32 v199, v199
	v_exp_f32_e32 v200, v200
	v_mfma_f32_32x32x16_bf16 v[32:47], v[128:131], v[60:63], v[32:47]
	v_exp_f32_e32 v201, v201
	v_exp_f32_e32 v202, v202
	v_exp_f32_e32 v203, v203
	v_cvt_pk_bf16_f32 v64, v188, v189
	v_cvt_pk_bf16_f32 v65, v190, v191
	v_cvt_pk_bf16_f32 v66, v192, v193
	v_cvt_pk_bf16_f32 v67, v194, v195
	v_cvt_pk_bf16_f32 v68, v196, v197
	v_cvt_pk_bf16_f32 v69, v198, v199
	v_cvt_pk_bf16_f32 v70, v200, v201
	v_cvt_pk_bf16_f32 v71, v202, v203
	v_pk_add_f32 v[232:233], v[232:233], v[188:189]
	v_pk_add_f32 v[232:233], v[232:233], v[190:191]
	v_pk_add_f32 v[232:233], v[232:233], v[192:193]
	v_pk_add_f32 v[232:233], v[232:233], v[194:195]
	v_pk_add_f32 v[232:233], v[232:233], v[196:197]
	v_pk_add_f32 v[232:233], v[232:233], v[198:199]
	v_pk_add_f32 v[232:233], v[232:233], v[200:201]
	v_pk_add_f32 v[232:233], v[232:233], v[202:203]
	ds_read2_b32 v[188:189], v115 offset0:170 offset1:171
	ds_read2_b32 v[190:191], v115 offset0:172 offset1:173
	ds_read2_b32 v[192:193], v115 offset0:178 offset1:179
	ds_read2_b32 v[194:195], v115 offset0:180 offset1:181
	ds_read2_b32 v[196:197], v115 offset0:187 offset1:188
	ds_read2_b32 v[198:199], v115 offset0:189 offset1:190
	ds_read2_b32 v[200:201], v115 offset0:195 offset1:196
	ds_read2_b32 v[202:203], v115 offset0:197 offset1:198
	v_mfma_f32_32x32x16_bf16 v[0:15], v[64:67], v[72:75], v[0:15]
	v_mfma_f32_32x32x16_bf16 v[16:31], v[64:67], v[76:79], v[16:31]
	v_mfma_f32_32x32x16_bf16 v[0:15], v[68:71], v[220:223], v[0:15]
	v_mfma_f32_32x32x16_bf16 v[16:31], v[68:71], v[224:227], v[16:31]
	global_load_dwordx4 v[116:119], v239, s[86:87]
	global_load_dwordx4 v[120:123], v240, s[86:87]
	global_load_dwordx4 v[124:127], v241, s[86:87]
	global_load_dwordx4 v[128:131], v242, s[86:87]
	global_load_dwordx4 v[132:135], v101, s[86:87] offset:768
	global_load_dwordx4 v[136:139], v150, s[86:87] offset:768
	global_load_dwordx4 v[140:143], v101, s[86:87] offset:832
	global_load_dwordx4 v[144:147], v150, s[86:87] offset:832
	s_add_u32 s86, s86, 0xc0000
	s_addc_u32 s87, s87, 0
	ds_read_b64_tr_b16 v[72:73], v231
	ds_read_b64_tr_b16 v[74:75], v231 offset:512
	ds_read_b64_tr_b16 v[76:77], v231 offset:2048
	ds_read_b64_tr_b16 v[78:79], v231 offset:2560
	ds_read_b64_tr_b16 v[220:221], v231 offset:1024
	ds_read_b64_tr_b16 v[222:223], v231 offset:1536
	ds_read_b64_tr_b16 v[224:225], v231 offset:3072
	ds_read_b64_tr_b16 v[226:227], v231 offset:3584
	s_waitcnt vmcnt(8)
	ds_write_b128 v247, v[156:159]
	ds_write_b128 v247, v[160:163] offset:1024
	ds_write_b128 v111, v[164:167] offset:2048
	ds_write_b128 v111, v[168:171] offset:3072
	ds_read_b128 v[156:159], v248
	ds_read_b128 v[160:163], v249
	ds_read_b128 v[164:167], v250
	ds_read_b128 v[168:171], v251
	ds_write_b128 v112, v[172:175]
	ds_write_b128 v112, v[176:179] offset:1024
	ds_write_b128 v112, v[180:183] offset:2048
	ds_write_b128 v112, v[184:187] offset:3072
	v_exp_f32_e32 v32, v32
	v_exp_f32_e32 v33, v33
	v_exp_f32_e32 v34, v34
	v_exp_f32_e32 v35, v35
	v_exp_f32_e32 v36, v36
	v_exp_f32_e32 v37, v37
	s_waitcnt lgkmcnt(4)
	v_mfma_f32_32x32x16_bf16 v[188:203], v[156:159], v[48:51], v[188:203]
	v_exp_f32_e32 v38, v38
	v_exp_f32_e32 v39, v39
	v_mfma_f32_32x32x16_bf16 v[188:203], v[160:163], v[52:55], v[188:203]
	v_exp_f32_e32 v40, v40
	v_exp_f32_e32 v41, v41
	v_exp_f32_e32 v42, v42
	v_mfma_f32_32x32x16_bf16 v[188:203], v[164:167], v[56:59], v[188:203]
	v_exp_f32_e32 v43, v43
	v_exp_f32_e32 v44, v44
	v_mfma_f32_32x32x16_bf16 v[188:203], v[168:171], v[60:63], v[188:203]
	v_exp_f32_e32 v45, v45
	v_exp_f32_e32 v46, v46
	v_exp_f32_e32 v47, v47
	v_cvt_pk_bf16_f32 v64, v32, v33
	v_cvt_pk_bf16_f32 v65, v34, v35
	v_cvt_pk_bf16_f32 v66, v36, v37
	v_cvt_pk_bf16_f32 v67, v38, v39
	v_cvt_pk_bf16_f32 v68, v40, v41
	v_cvt_pk_bf16_f32 v69, v42, v43
	v_cvt_pk_bf16_f32 v70, v44, v45
	v_cvt_pk_bf16_f32 v71, v46, v47
	v_pk_add_f32 v[232:233], v[232:233], v[32:33]
	v_pk_add_f32 v[232:233], v[232:233], v[34:35]
	v_pk_add_f32 v[232:233], v[232:233], v[36:37]
	v_pk_add_f32 v[232:233], v[232:233], v[38:39]
	v_pk_add_f32 v[232:233], v[232:233], v[40:41]
	v_pk_add_f32 v[232:233], v[232:233], v[42:43]
	v_pk_add_f32 v[232:233], v[232:233], v[44:45]
	v_pk_add_f32 v[232:233], v[232:233], v[46:47]
	v_mov_b32_e32 v115, v229
	ds_read2_b32 v[32:33], v115 offset0:0 offset1:1
	ds_read2_b32 v[34:35], v115 offset0:2 offset1:3
	ds_read2_b32 v[36:37], v115 offset0:10 offset1:11
	ds_read2_b32 v[38:39], v115 offset0:12 offset1:13
	ds_read2_b32 v[40:41], v115 offset0:20 offset1:21
	ds_read2_b32 v[42:43], v115 offset0:22 offset1:23
	ds_read2_b32 v[44:45], v115 offset0:30 offset1:31
	ds_read2_b32 v[46:47], v115 offset0:32 offset1:33
	v_mfma_f32_32x32x16_bf16 v[0:15], v[64:67], v[72:75], v[0:15]
	v_mfma_f32_32x32x16_bf16 v[16:31], v[64:67], v[76:79], v[16:31]
	v_mfma_f32_32x32x16_bf16 v[0:15], v[68:71], v[220:223], v[0:15]
	v_mfma_f32_32x32x16_bf16 v[16:31], v[68:71], v[224:227], v[16:31]
	global_load_dwordx4 v[156:159], v239, s[86:87]
	global_load_dwordx4 v[160:163], v240, s[86:87]
	global_load_dwordx4 v[164:167], v241, s[86:87]
	global_load_dwordx4 v[168:171], v242, s[86:87]
	global_load_dwordx4 v[172:175], v101, s[86:87] offset:768
	global_load_dwordx4 v[176:179], v150, s[86:87] offset:768
	global_load_dwordx4 v[180:183], v101, s[86:87] offset:832
	global_load_dwordx4 v[184:187], v150, s[86:87] offset:832
	s_add_u32 s86, s86, 0xc0000
	s_addc_u32 s87, s87, 0
	ds_read_b64_tr_b16 v[72:73], v231
	ds_read_b64_tr_b16 v[74:75], v231 offset:512
	ds_read_b64_tr_b16 v[76:77], v231 offset:2048
	ds_read_b64_tr_b16 v[78:79], v231 offset:2560
	ds_read_b64_tr_b16 v[220:221], v231 offset:1024
	ds_read_b64_tr_b16 v[222:223], v231 offset:1536
	ds_read_b64_tr_b16 v[224:225], v231 offset:3072
	ds_read_b64_tr_b16 v[226:227], v231 offset:3584
	s_waitcnt vmcnt(8)
	ds_write_b128 v247, v[116:119]
	ds_write_b128 v247, v[120:123] offset:1024
	ds_write_b128 v111, v[124:127] offset:2048
	ds_write_b128 v111, v[128:131] offset:3072
	ds_read_b128 v[116:119], v248
	ds_read_b128 v[120:123], v249
	ds_read_b128 v[124:127], v250
	ds_read_b128 v[128:131], v251
	ds_write_b128 v112, v[132:135]
	ds_write_b128 v112, v[136:139] offset:1024
	ds_write_b128 v112, v[140:143] offset:2048
	ds_write_b128 v112, v[144:147] offset:3072
	v_exp_f32_e32 v188, v188
	v_exp_f32_e32 v189, v189
	v_exp_f32_e32 v190, v190
	v_exp_f32_e32 v191, v191
	v_exp_f32_e32 v192, v192
	v_exp_f32_e32 v193, v193
	s_waitcnt lgkmcnt(4)
	v_mfma_f32_32x32x16_bf16 v[32:47], v[116:119], v[48:51], v[32:47]
	v_exp_f32_e32 v194, v194
	v_exp_f32_e32 v195, v195
	v_mfma_f32_32x32x16_bf16 v[32:47], v[120:123], v[52:55], v[32:47]
	v_exp_f32_e32 v196, v196
	v_exp_f32_e32 v197, v197
	v_exp_f32_e32 v198, v198
	v_mfma_f32_32x32x16_bf16 v[32:47], v[124:127], v[56:59], v[32:47]
	v_exp_f32_e32 v199, v199
	v_exp_f32_e32 v200, v200
	v_mfma_f32_32x32x16_bf16 v[32:47], v[128:131], v[60:63], v[32:47]
	v_exp_f32_e32 v201, v201
	v_exp_f32_e32 v202, v202
	v_exp_f32_e32 v203, v203
	v_cvt_pk_bf16_f32 v64, v188, v189
	v_cvt_pk_bf16_f32 v65, v190, v191
	v_cvt_pk_bf16_f32 v66, v192, v193
	v_cvt_pk_bf16_f32 v67, v194, v195
	v_cvt_pk_bf16_f32 v68, v196, v197
	v_cvt_pk_bf16_f32 v69, v198, v199
	v_cvt_pk_bf16_f32 v70, v200, v201
	v_cvt_pk_bf16_f32 v71, v202, v203
	v_pk_add_f32 v[232:233], v[232:233], v[188:189]
	v_pk_add_f32 v[232:233], v[232:233], v[190:191]
	v_pk_add_f32 v[232:233], v[232:233], v[192:193]
	v_pk_add_f32 v[232:233], v[232:233], v[194:195]
	v_pk_add_f32 v[232:233], v[232:233], v[196:197]
	v_pk_add_f32 v[232:233], v[232:233], v[198:199]
	v_pk_add_f32 v[232:233], v[232:233], v[200:201]
	v_pk_add_f32 v[232:233], v[232:233], v[202:203]
	ds_read2_b32 v[188:189], v115 offset0:40 offset1:41
	ds_read2_b32 v[190:191], v115 offset0:42 offset1:43
	ds_read2_b32 v[192:193], v115 offset0:50 offset1:51
	ds_read2_b32 v[194:195], v115 offset0:52 offset1:53
	ds_read2_b32 v[196:197], v115 offset0:60 offset1:61
	ds_read2_b32 v[198:199], v115 offset0:62 offset1:63
	ds_read2_b32 v[200:201], v115 offset0:70 offset1:71
	ds_read2_b32 v[202:203], v115 offset0:72 offset1:73
	v_mfma_f32_32x32x16_bf16 v[0:15], v[64:67], v[72:75], v[0:15]
	v_mfma_f32_32x32x16_bf16 v[16:31], v[64:67], v[76:79], v[16:31]
	v_mfma_f32_32x32x16_bf16 v[0:15], v[68:71], v[220:223], v[0:15]
	v_mfma_f32_32x32x16_bf16 v[16:31], v[68:71], v[224:227], v[16:31]
	global_load_dwordx4 v[116:119], v239, s[86:87]
	global_load_dwordx4 v[120:123], v240, s[86:87]
	global_load_dwordx4 v[124:127], v241, s[86:87]
	global_load_dwordx4 v[128:131], v242, s[86:87]
	global_load_dwordx4 v[132:135], v101, s[86:87] offset:768
	global_load_dwordx4 v[136:139], v150, s[86:87] offset:768
	global_load_dwordx4 v[140:143], v101, s[86:87] offset:832
	global_load_dwordx4 v[144:147], v150, s[86:87] offset:832
	s_add_u32 s86, s86, 0xc0000
	s_addc_u32 s87, s87, 0
	ds_read_b64_tr_b16 v[72:73], v231
	ds_read_b64_tr_b16 v[74:75], v231 offset:512
	ds_read_b64_tr_b16 v[76:77], v231 offset:2048
	ds_read_b64_tr_b16 v[78:79], v231 offset:2560
	ds_read_b64_tr_b16 v[220:221], v231 offset:1024
	ds_read_b64_tr_b16 v[222:223], v231 offset:1536
	ds_read_b64_tr_b16 v[224:225], v231 offset:3072
	ds_read_b64_tr_b16 v[226:227], v231 offset:3584
	s_waitcnt vmcnt(8)
	ds_write_b128 v247, v[156:159]
	ds_write_b128 v247, v[160:163] offset:1024
	ds_write_b128 v111, v[164:167] offset:2048
	ds_write_b128 v111, v[168:171] offset:3072
	ds_read_b128 v[156:159], v248
	ds_read_b128 v[160:163], v249
	ds_read_b128 v[164:167], v250
	ds_read_b128 v[168:171], v251
	ds_write_b128 v112, v[172:175]
	ds_write_b128 v112, v[176:179] offset:1024
	ds_write_b128 v112, v[180:183] offset:2048
	ds_write_b128 v112, v[184:187] offset:3072
	v_exp_f32_e32 v32, v32
	v_exp_f32_e32 v33, v33
	v_exp_f32_e32 v34, v34
	v_exp_f32_e32 v35, v35
	v_exp_f32_e32 v36, v36
	v_exp_f32_e32 v37, v37
	s_waitcnt lgkmcnt(4)
	v_mfma_f32_32x32x16_bf16 v[188:203], v[156:159], v[48:51], v[188:203]
	v_exp_f32_e32 v38, v38
	v_exp_f32_e32 v39, v39
	v_mfma_f32_32x32x16_bf16 v[188:203], v[160:163], v[52:55], v[188:203]
	v_exp_f32_e32 v40, v40
	v_exp_f32_e32 v41, v41
	v_exp_f32_e32 v42, v42
	v_mfma_f32_32x32x16_bf16 v[188:203], v[164:167], v[56:59], v[188:203]
	v_exp_f32_e32 v43, v43
	v_exp_f32_e32 v44, v44
	v_mfma_f32_32x32x16_bf16 v[188:203], v[168:171], v[60:63], v[188:203]
	v_exp_f32_e32 v45, v45
	v_exp_f32_e32 v46, v46
	v_exp_f32_e32 v47, v47
	v_cvt_pk_bf16_f32 v64, v32, v33
	v_cvt_pk_bf16_f32 v65, v34, v35
	v_cvt_pk_bf16_f32 v66, v36, v37
	v_cvt_pk_bf16_f32 v67, v38, v39
	v_cvt_pk_bf16_f32 v68, v40, v41
	v_cvt_pk_bf16_f32 v69, v42, v43
	v_cvt_pk_bf16_f32 v70, v44, v45
	v_cvt_pk_bf16_f32 v71, v46, v47
	v_pk_add_f32 v[232:233], v[232:233], v[32:33]
	v_pk_add_f32 v[232:233], v[232:233], v[34:35]
	v_pk_add_f32 v[232:233], v[232:233], v[36:37]
	v_pk_add_f32 v[232:233], v[232:233], v[38:39]
	v_pk_add_f32 v[232:233], v[232:233], v[40:41]
	v_pk_add_f32 v[232:233], v[232:233], v[42:43]
	v_pk_add_f32 v[232:233], v[232:233], v[44:45]
	v_pk_add_f32 v[232:233], v[232:233], v[46:47]
	ds_read2_b32 v[32:33], v115 offset0:80 offset1:81
	ds_read2_b32 v[34:35], v115 offset0:82 offset1:83
	ds_read2_b32 v[36:37], v115 offset0:90 offset1:91
	ds_read2_b32 v[38:39], v115 offset0:92 offset1:93
	ds_read2_b32 v[40:41], v115 offset0:100 offset1:101
	ds_read2_b32 v[42:43], v115 offset0:102 offset1:103
	ds_read2_b32 v[44:45], v115 offset0:110 offset1:111
	ds_read2_b32 v[46:47], v115 offset0:112 offset1:113
	v_mfma_f32_32x32x16_bf16 v[0:15], v[64:67], v[72:75], v[0:15]
	v_mfma_f32_32x32x16_bf16 v[16:31], v[64:67], v[76:79], v[16:31]
	v_mfma_f32_32x32x16_bf16 v[0:15], v[68:71], v[220:223], v[0:15]
	v_mfma_f32_32x32x16_bf16 v[16:31], v[68:71], v[224:227], v[16:31]
	global_load_dwordx4 v[156:159], v239, s[86:87]
	global_load_dwordx4 v[160:163], v240, s[86:87]
	global_load_dwordx4 v[164:167], v241, s[86:87]
	global_load_dwordx4 v[168:171], v242, s[86:87]
	global_load_dwordx4 v[172:175], v101, s[86:87] offset:768
	global_load_dwordx4 v[176:179], v150, s[86:87] offset:768
	global_load_dwordx4 v[180:183], v101, s[86:87] offset:832
	global_load_dwordx4 v[184:187], v150, s[86:87] offset:832
	s_add_u32 s86, s86, 0xc0000
	s_addc_u32 s87, s87, 0
	ds_read_b64_tr_b16 v[72:73], v231
	ds_read_b64_tr_b16 v[74:75], v231 offset:512
	ds_read_b64_tr_b16 v[76:77], v231 offset:2048
	ds_read_b64_tr_b16 v[78:79], v231 offset:2560
	ds_read_b64_tr_b16 v[220:221], v231 offset:1024
	ds_read_b64_tr_b16 v[222:223], v231 offset:1536
	ds_read_b64_tr_b16 v[224:225], v231 offset:3072
	ds_read_b64_tr_b16 v[226:227], v231 offset:3584
	s_waitcnt vmcnt(8)
	ds_write_b128 v247, v[116:119]
	ds_write_b128 v247, v[120:123] offset:1024
	ds_write_b128 v111, v[124:127] offset:2048
	ds_write_b128 v111, v[128:131] offset:3072
	ds_read_b128 v[116:119], v248
	ds_read_b128 v[120:123], v249
	ds_read_b128 v[124:127], v250
	ds_read_b128 v[128:131], v251
	ds_write_b128 v112, v[132:135]
	ds_write_b128 v112, v[136:139] offset:1024
	ds_write_b128 v112, v[140:143] offset:2048
	ds_write_b128 v112, v[144:147] offset:3072
	v_exp_f32_e32 v188, v188
	v_exp_f32_e32 v189, v189
	v_exp_f32_e32 v190, v190
	v_exp_f32_e32 v191, v191
	v_exp_f32_e32 v192, v192
	v_exp_f32_e32 v193, v193
	s_waitcnt lgkmcnt(4)
	v_mfma_f32_32x32x16_bf16 v[32:47], v[116:119], v[48:51], v[32:47]
	v_exp_f32_e32 v194, v194
	v_exp_f32_e32 v195, v195
	v_mfma_f32_32x32x16_bf16 v[32:47], v[120:123], v[52:55], v[32:47]
	v_exp_f32_e32 v196, v196
	v_exp_f32_e32 v197, v197
	v_exp_f32_e32 v198, v198
	v_mfma_f32_32x32x16_bf16 v[32:47], v[124:127], v[56:59], v[32:47]
	v_exp_f32_e32 v199, v199
	v_exp_f32_e32 v200, v200
	v_mfma_f32_32x32x16_bf16 v[32:47], v[128:131], v[60:63], v[32:47]
	v_exp_f32_e32 v201, v201
	v_exp_f32_e32 v202, v202
	v_exp_f32_e32 v203, v203
	v_cvt_pk_bf16_f32 v64, v188, v189
	v_cvt_pk_bf16_f32 v65, v190, v191
	v_cvt_pk_bf16_f32 v66, v192, v193
	v_cvt_pk_bf16_f32 v67, v194, v195
	v_cvt_pk_bf16_f32 v68, v196, v197
	v_cvt_pk_bf16_f32 v69, v198, v199
	v_cvt_pk_bf16_f32 v70, v200, v201
	v_cvt_pk_bf16_f32 v71, v202, v203
	v_pk_add_f32 v[232:233], v[232:233], v[188:189]
	v_pk_add_f32 v[232:233], v[232:233], v[190:191]
	v_pk_add_f32 v[232:233], v[232:233], v[192:193]
	v_pk_add_f32 v[232:233], v[232:233], v[194:195]
	v_pk_add_f32 v[232:233], v[232:233], v[196:197]
	v_pk_add_f32 v[232:233], v[232:233], v[198:199]
	v_pk_add_f32 v[232:233], v[232:233], v[200:201]
	v_pk_add_f32 v[232:233], v[232:233], v[202:203]
	ds_read2_b32 v[188:189], v115 offset0:120 offset1:121
	ds_read2_b32 v[190:191], v115 offset0:122 offset1:123
	ds_read2_b32 v[192:193], v115 offset0:130 offset1:131
	ds_read2_b32 v[194:195], v115 offset0:132 offset1:133
	ds_read2_b32 v[196:197], v115 offset0:140 offset1:141
	ds_read2_b32 v[198:199], v115 offset0:142 offset1:143
	ds_read2_b32 v[200:201], v115 offset0:150 offset1:151
	ds_read2_b32 v[202:203], v115 offset0:152 offset1:153
	v_mfma_f32_32x32x16_bf16 v[0:15], v[64:67], v[72:75], v[0:15]
	v_mfma_f32_32x32x16_bf16 v[16:31], v[64:67], v[76:79], v[16:31]
	v_mfma_f32_32x32x16_bf16 v[0:15], v[68:71], v[220:223], v[0:15]
	v_mfma_f32_32x32x16_bf16 v[16:31], v[68:71], v[224:227], v[16:31]
	global_load_dwordx4 v[116:119], v239, s[86:87]
	global_load_dwordx4 v[120:123], v240, s[86:87]
	global_load_dwordx4 v[124:127], v241, s[86:87]
	global_load_dwordx4 v[128:131], v242, s[86:87]
	global_load_dwordx4 v[132:135], v101, s[86:87] offset:768
	global_load_dwordx4 v[136:139], v150, s[86:87] offset:768
	global_load_dwordx4 v[140:143], v101, s[86:87] offset:832
	global_load_dwordx4 v[144:147], v150, s[86:87] offset:832
	s_add_u32 s86, s86, 0xc0000
	s_addc_u32 s87, s87, 0
	ds_read_b64_tr_b16 v[72:73], v231
	ds_read_b64_tr_b16 v[74:75], v231 offset:512
	ds_read_b64_tr_b16 v[76:77], v231 offset:2048
	ds_read_b64_tr_b16 v[78:79], v231 offset:2560
	ds_read_b64_tr_b16 v[220:221], v231 offset:1024
	ds_read_b64_tr_b16 v[222:223], v231 offset:1536
	ds_read_b64_tr_b16 v[224:225], v231 offset:3072
	ds_read_b64_tr_b16 v[226:227], v231 offset:3584
	s_waitcnt vmcnt(8)
	ds_write_b128 v247, v[156:159]
	ds_write_b128 v247, v[160:163] offset:1024
	ds_write_b128 v111, v[164:167] offset:2048
	ds_write_b128 v111, v[168:171] offset:3072
	ds_read_b128 v[156:159], v248
	ds_read_b128 v[160:163], v249
	ds_read_b128 v[164:167], v250
	ds_read_b128 v[168:171], v251
	ds_write_b128 v112, v[172:175]
	ds_write_b128 v112, v[176:179] offset:1024
	ds_write_b128 v112, v[180:183] offset:2048
	ds_write_b128 v112, v[184:187] offset:3072
	v_exp_f32_e32 v32, v32
	v_exp_f32_e32 v33, v33
	v_exp_f32_e32 v34, v34
	v_exp_f32_e32 v35, v35
	v_exp_f32_e32 v36, v36
	v_exp_f32_e32 v37, v37
	s_waitcnt lgkmcnt(4)
	v_mfma_f32_32x32x16_bf16 v[188:203], v[156:159], v[48:51], v[188:203]
	v_exp_f32_e32 v38, v38
	v_exp_f32_e32 v39, v39
	v_mfma_f32_32x32x16_bf16 v[188:203], v[160:163], v[52:55], v[188:203]
	v_exp_f32_e32 v40, v40
	v_exp_f32_e32 v41, v41
	v_exp_f32_e32 v42, v42
	v_mfma_f32_32x32x16_bf16 v[188:203], v[164:167], v[56:59], v[188:203]
	v_exp_f32_e32 v43, v43
	v_exp_f32_e32 v44, v44
	v_mfma_f32_32x32x16_bf16 v[188:203], v[168:171], v[60:63], v[188:203]
	v_exp_f32_e32 v45, v45
	v_exp_f32_e32 v46, v46
	v_exp_f32_e32 v47, v47
	v_cvt_pk_bf16_f32 v64, v32, v33
	v_cvt_pk_bf16_f32 v65, v34, v35
	v_cvt_pk_bf16_f32 v66, v36, v37
	v_cvt_pk_bf16_f32 v67, v38, v39
	v_cvt_pk_bf16_f32 v68, v40, v41
	v_cvt_pk_bf16_f32 v69, v42, v43
	v_cvt_pk_bf16_f32 v70, v44, v45
	v_cvt_pk_bf16_f32 v71, v46, v47
	v_pk_add_f32 v[232:233], v[232:233], v[32:33]
	v_pk_add_f32 v[232:233], v[232:233], v[34:35]
	v_pk_add_f32 v[232:233], v[232:233], v[36:37]
	v_pk_add_f32 v[232:233], v[232:233], v[38:39]
	v_pk_add_f32 v[232:233], v[232:233], v[40:41]
	v_pk_add_f32 v[232:233], v[232:233], v[42:43]
	v_pk_add_f32 v[232:233], v[232:233], v[44:45]
	v_pk_add_f32 v[232:233], v[232:233], v[46:47]
	v_add_u32_e32 v115, 640, v115
	ds_read2_b32 v[32:33], v115 offset0:0 offset1:1
	ds_read2_b32 v[34:35], v115 offset0:2 offset1:3
	ds_read2_b32 v[36:37], v115 offset0:10 offset1:11
	ds_read2_b32 v[38:39], v115 offset0:12 offset1:13
	ds_read2_b32 v[40:41], v115 offset0:20 offset1:21
	ds_read2_b32 v[42:43], v115 offset0:22 offset1:23
	ds_read2_b32 v[44:45], v115 offset0:30 offset1:31
	ds_read2_b32 v[46:47], v115 offset0:32 offset1:33
	v_mfma_f32_32x32x16_bf16 v[0:15], v[64:67], v[72:75], v[0:15]
	v_mfma_f32_32x32x16_bf16 v[16:31], v[64:67], v[76:79], v[16:31]
	v_mfma_f32_32x32x16_bf16 v[0:15], v[68:71], v[220:223], v[0:15]
	v_mfma_f32_32x32x16_bf16 v[16:31], v[68:71], v[224:227], v[16:31]
	global_load_dwordx4 v[156:159], v239, s[86:87]
	global_load_dwordx4 v[160:163], v240, s[86:87]
	global_load_dwordx4 v[164:167], v241, s[86:87]
	global_load_dwordx4 v[168:171], v242, s[86:87]
	global_load_dwordx4 v[172:175], v101, s[86:87] offset:768
	global_load_dwordx4 v[176:179], v150, s[86:87] offset:768
	global_load_dwordx4 v[180:183], v101, s[86:87] offset:832
	global_load_dwordx4 v[184:187], v150, s[86:87] offset:832
	s_add_u32 s86, s86, 0xc0000
	s_addc_u32 s87, s87, 0
	ds_read_b64_tr_b16 v[72:73], v231
	ds_read_b64_tr_b16 v[74:75], v231 offset:512
	ds_read_b64_tr_b16 v[76:77], v231 offset:2048
	ds_read_b64_tr_b16 v[78:79], v231 offset:2560
	ds_read_b64_tr_b16 v[220:221], v231 offset:1024
	ds_read_b64_tr_b16 v[222:223], v231 offset:1536
	ds_read_b64_tr_b16 v[224:225], v231 offset:3072
	ds_read_b64_tr_b16 v[226:227], v231 offset:3584
	s_waitcnt vmcnt(8)
	ds_write_b128 v247, v[116:119]
	ds_write_b128 v247, v[120:123] offset:1024
	ds_write_b128 v111, v[124:127] offset:2048
	ds_write_b128 v111, v[128:131] offset:3072
	ds_read_b128 v[116:119], v248
	ds_read_b128 v[120:123], v249
	ds_read_b128 v[124:127], v250
	ds_read_b128 v[128:131], v251
	ds_write_b128 v112, v[132:135]
	ds_write_b128 v112, v[136:139] offset:1024
	ds_write_b128 v112, v[140:143] offset:2048
	ds_write_b128 v112, v[144:147] offset:3072
	v_exp_f32_e32 v188, v188
	v_exp_f32_e32 v189, v189
	v_exp_f32_e32 v190, v190
	v_exp_f32_e32 v191, v191
	v_exp_f32_e32 v192, v192
	v_exp_f32_e32 v193, v193
	s_waitcnt lgkmcnt(4)
	v_mfma_f32_32x32x16_bf16 v[32:47], v[116:119], v[48:51], v[32:47]
	v_exp_f32_e32 v194, v194
	v_exp_f32_e32 v195, v195
	v_mfma_f32_32x32x16_bf16 v[32:47], v[120:123], v[52:55], v[32:47]
	v_exp_f32_e32 v196, v196
	v_exp_f32_e32 v197, v197
	v_exp_f32_e32 v198, v198
	v_mfma_f32_32x32x16_bf16 v[32:47], v[124:127], v[56:59], v[32:47]
	v_exp_f32_e32 v199, v199
	v_exp_f32_e32 v200, v200
	v_mfma_f32_32x32x16_bf16 v[32:47], v[128:131], v[60:63], v[32:47]
	v_exp_f32_e32 v201, v201
	v_exp_f32_e32 v202, v202
	v_exp_f32_e32 v203, v203
	v_cvt_pk_bf16_f32 v64, v188, v189
	v_cvt_pk_bf16_f32 v65, v190, v191
	v_cvt_pk_bf16_f32 v66, v192, v193
	v_cvt_pk_bf16_f32 v67, v194, v195
	v_cvt_pk_bf16_f32 v68, v196, v197
	v_cvt_pk_bf16_f32 v69, v198, v199
	v_cvt_pk_bf16_f32 v70, v200, v201
	v_cvt_pk_bf16_f32 v71, v202, v203
	v_pk_add_f32 v[232:233], v[232:233], v[188:189]
	v_pk_add_f32 v[232:233], v[232:233], v[190:191]
	v_pk_add_f32 v[232:233], v[232:233], v[192:193]
	v_pk_add_f32 v[232:233], v[232:233], v[194:195]
	v_pk_add_f32 v[232:233], v[232:233], v[196:197]
	v_pk_add_f32 v[232:233], v[232:233], v[198:199]
	v_pk_add_f32 v[232:233], v[232:233], v[200:201]
	v_pk_add_f32 v[232:233], v[232:233], v[202:203]
	ds_read2_b32 v[188:189], v115 offset0:40 offset1:41
	ds_read2_b32 v[190:191], v115 offset0:42 offset1:43
	ds_read2_b32 v[192:193], v115 offset0:50 offset1:51
	ds_read2_b32 v[194:195], v115 offset0:52 offset1:53
	ds_read2_b32 v[196:197], v115 offset0:60 offset1:61
	ds_read2_b32 v[198:199], v115 offset0:62 offset1:63
	ds_read2_b32 v[200:201], v115 offset0:70 offset1:71
	ds_read2_b32 v[202:203], v115 offset0:72 offset1:73
	v_mfma_f32_32x32x16_bf16 v[0:15], v[64:67], v[72:75], v[0:15]
	v_mfma_f32_32x32x16_bf16 v[16:31], v[64:67], v[76:79], v[16:31]
	v_mfma_f32_32x32x16_bf16 v[0:15], v[68:71], v[220:223], v[0:15]
	v_mfma_f32_32x32x16_bf16 v[16:31], v[68:71], v[224:227], v[16:31]
	global_load_dwordx4 v[116:119], v239, s[86:87]
	global_load_dwordx4 v[120:123], v240, s[86:87]
	global_load_dwordx4 v[124:127], v241, s[86:87]
	global_load_dwordx4 v[128:131], v242, s[86:87]
	global_load_dwordx4 v[132:135], v101, s[86:87] offset:768
	global_load_dwordx4 v[136:139], v150, s[86:87] offset:768
	global_load_dwordx4 v[140:143], v101, s[86:87] offset:832
	global_load_dwordx4 v[144:147], v150, s[86:87] offset:832
	s_add_u32 s86, s86, 0xc0000
	s_addc_u32 s87, s87, 0
	ds_read_b64_tr_b16 v[72:73], v231
	ds_read_b64_tr_b16 v[74:75], v231 offset:512
	ds_read_b64_tr_b16 v[76:77], v231 offset:2048
	ds_read_b64_tr_b16 v[78:79], v231 offset:2560
	ds_read_b64_tr_b16 v[220:221], v231 offset:1024
	ds_read_b64_tr_b16 v[222:223], v231 offset:1536
	ds_read_b64_tr_b16 v[224:225], v231 offset:3072
	ds_read_b64_tr_b16 v[226:227], v231 offset:3584
	s_waitcnt vmcnt(8)
	ds_write_b128 v247, v[156:159]
	ds_write_b128 v247, v[160:163] offset:1024
	ds_write_b128 v111, v[164:167] offset:2048
	ds_write_b128 v111, v[168:171] offset:3072
	ds_read_b128 v[156:159], v248
	ds_read_b128 v[160:163], v249
	ds_read_b128 v[164:167], v250
	ds_read_b128 v[168:171], v251
	ds_write_b128 v112, v[172:175]
	ds_write_b128 v112, v[176:179] offset:1024
	ds_write_b128 v112, v[180:183] offset:2048
	ds_write_b128 v112, v[184:187] offset:3072
	v_exp_f32_e32 v32, v32
	v_exp_f32_e32 v33, v33
	v_exp_f32_e32 v34, v34
	v_exp_f32_e32 v35, v35
	v_exp_f32_e32 v36, v36
	v_exp_f32_e32 v37, v37
	s_waitcnt lgkmcnt(4)
	v_mfma_f32_32x32x16_bf16 v[188:203], v[156:159], v[48:51], v[188:203]
	v_exp_f32_e32 v38, v38
	v_exp_f32_e32 v39, v39
	v_mfma_f32_32x32x16_bf16 v[188:203], v[160:163], v[52:55], v[188:203]
	v_exp_f32_e32 v40, v40
	v_exp_f32_e32 v41, v41
	v_exp_f32_e32 v42, v42
	v_mfma_f32_32x32x16_bf16 v[188:203], v[164:167], v[56:59], v[188:203]
	v_exp_f32_e32 v43, v43
	v_exp_f32_e32 v44, v44
	v_mfma_f32_32x32x16_bf16 v[188:203], v[168:171], v[60:63], v[188:203]
	v_exp_f32_e32 v45, v45
	v_exp_f32_e32 v46, v46
	v_exp_f32_e32 v47, v47
	v_cvt_pk_bf16_f32 v64, v32, v33
	v_cvt_pk_bf16_f32 v65, v34, v35
	v_cvt_pk_bf16_f32 v66, v36, v37
	v_cvt_pk_bf16_f32 v67, v38, v39
	v_cvt_pk_bf16_f32 v68, v40, v41
	v_cvt_pk_bf16_f32 v69, v42, v43
	v_cvt_pk_bf16_f32 v70, v44, v45
	v_cvt_pk_bf16_f32 v71, v46, v47
	v_pk_add_f32 v[232:233], v[232:233], v[32:33]
	v_pk_add_f32 v[232:233], v[232:233], v[34:35]
	v_pk_add_f32 v[232:233], v[232:233], v[36:37]
	v_pk_add_f32 v[232:233], v[232:233], v[38:39]
	v_pk_add_f32 v[232:233], v[232:233], v[40:41]
	v_pk_add_f32 v[232:233], v[232:233], v[42:43]
	v_pk_add_f32 v[232:233], v[232:233], v[44:45]
	v_pk_add_f32 v[232:233], v[232:233], v[46:47]
	ds_read2_b32 v[32:33], v115 offset0:80 offset1:81
	ds_read2_b32 v[34:35], v115 offset0:82 offset1:83
	ds_read2_b32 v[36:37], v115 offset0:90 offset1:91
	ds_read2_b32 v[38:39], v115 offset0:92 offset1:93
	ds_read2_b32 v[40:41], v115 offset0:100 offset1:101
	ds_read2_b32 v[42:43], v115 offset0:102 offset1:103
	ds_read2_b32 v[44:45], v115 offset0:110 offset1:111
	ds_read2_b32 v[46:47], v115 offset0:112 offset1:113
	v_mfma_f32_32x32x16_bf16 v[0:15], v[64:67], v[72:75], v[0:15]
	v_mfma_f32_32x32x16_bf16 v[16:31], v[64:67], v[76:79], v[16:31]
	v_mfma_f32_32x32x16_bf16 v[0:15], v[68:71], v[220:223], v[0:15]
	v_mfma_f32_32x32x16_bf16 v[16:31], v[68:71], v[224:227], v[16:31]
	global_load_dwordx4 v[156:159], v239, s[86:87]
	global_load_dwordx4 v[160:163], v240, s[86:87]
	global_load_dwordx4 v[164:167], v241, s[86:87]
	global_load_dwordx4 v[168:171], v242, s[86:87]
	global_load_dwordx4 v[172:175], v101, s[86:87] offset:768
	global_load_dwordx4 v[176:179], v150, s[86:87] offset:768
	global_load_dwordx4 v[180:183], v101, s[86:87] offset:832
	global_load_dwordx4 v[184:187], v150, s[86:87] offset:832
	ds_read_b64_tr_b16 v[72:73], v231
	ds_read_b64_tr_b16 v[74:75], v231 offset:512
	ds_read_b64_tr_b16 v[76:77], v231 offset:2048
	ds_read_b64_tr_b16 v[78:79], v231 offset:2560
	ds_read_b64_tr_b16 v[220:221], v231 offset:1024
	ds_read_b64_tr_b16 v[222:223], v231 offset:1536
	ds_read_b64_tr_b16 v[224:225], v231 offset:3072
	ds_read_b64_tr_b16 v[226:227], v231 offset:3584
	s_waitcnt vmcnt(8)
	ds_write_b128 v247, v[116:119]
	ds_write_b128 v247, v[120:123] offset:1024
	ds_write_b128 v111, v[124:127] offset:2048
	ds_write_b128 v111, v[128:131] offset:3072
	ds_read_b128 v[116:119], v248
	ds_read_b128 v[120:123], v249
	ds_read_b128 v[124:127], v250
	ds_read_b128 v[128:131], v251
	ds_write_b128 v112, v[132:135]
	ds_write_b128 v112, v[136:139] offset:1024
	ds_write_b128 v112, v[140:143] offset:2048
	ds_write_b128 v112, v[144:147] offset:3072
	v_exp_f32_e32 v188, v188
	v_exp_f32_e32 v189, v189
	v_exp_f32_e32 v190, v190
	v_exp_f32_e32 v191, v191
	v_exp_f32_e32 v192, v192
	v_exp_f32_e32 v193, v193
	s_waitcnt lgkmcnt(4)
	v_mfma_f32_32x32x16_bf16 v[32:47], v[116:119], v[48:51], v[32:47]
	v_exp_f32_e32 v194, v194
	v_exp_f32_e32 v195, v195
	v_mfma_f32_32x32x16_bf16 v[32:47], v[120:123], v[52:55], v[32:47]
	v_exp_f32_e32 v196, v196
	v_exp_f32_e32 v197, v197
	v_exp_f32_e32 v198, v198
	v_mfma_f32_32x32x16_bf16 v[32:47], v[124:127], v[56:59], v[32:47]
	v_exp_f32_e32 v199, v199
	v_exp_f32_e32 v200, v200
	v_mfma_f32_32x32x16_bf16 v[32:47], v[128:131], v[60:63], v[32:47]
	v_exp_f32_e32 v201, v201
	v_exp_f32_e32 v202, v202
	v_exp_f32_e32 v203, v203
	v_cvt_pk_bf16_f32 v64, v188, v189
	v_cvt_pk_bf16_f32 v65, v190, v191
	v_cvt_pk_bf16_f32 v66, v192, v193
	v_cvt_pk_bf16_f32 v67, v194, v195
	v_cvt_pk_bf16_f32 v68, v196, v197
	v_cvt_pk_bf16_f32 v69, v198, v199
	v_cvt_pk_bf16_f32 v70, v200, v201
	v_cvt_pk_bf16_f32 v71, v202, v203
	v_pk_add_f32 v[232:233], v[232:233], v[188:189]
	v_pk_add_f32 v[232:233], v[232:233], v[190:191]
	v_pk_add_f32 v[232:233], v[232:233], v[192:193]
	v_pk_add_f32 v[232:233], v[232:233], v[194:195]
	v_pk_add_f32 v[232:233], v[232:233], v[196:197]
	v_pk_add_f32 v[232:233], v[232:233], v[198:199]
	v_pk_add_f32 v[232:233], v[232:233], v[200:201]
	v_pk_add_f32 v[232:233], v[232:233], v[202:203]
	ds_read2_b32 v[188:189], v115 offset0:120 offset1:121
	ds_read2_b32 v[190:191], v115 offset0:122 offset1:123
	ds_read2_b32 v[192:193], v115 offset0:130 offset1:131
	ds_read2_b32 v[194:195], v115 offset0:132 offset1:133
	ds_read2_b32 v[196:197], v115 offset0:140 offset1:141
	ds_read2_b32 v[198:199], v115 offset0:142 offset1:143
	ds_read2_b32 v[200:201], v115 offset0:150 offset1:151
	ds_read2_b32 v[202:203], v115 offset0:152 offset1:153
	v_mfma_f32_32x32x16_bf16 v[0:15], v[64:67], v[72:75], v[0:15]
	v_mfma_f32_32x32x16_bf16 v[16:31], v[64:67], v[76:79], v[16:31]
	v_mfma_f32_32x32x16_bf16 v[0:15], v[68:71], v[220:223], v[0:15]
	v_mfma_f32_32x32x16_bf16 v[16:31], v[68:71], v[224:227], v[16:31]
	global_load_dwordx4 v[116:119], v243, s[88:89]
	global_load_dwordx4 v[120:123], v244, s[88:89]
	global_load_dwordx4 v[124:127], v245, s[88:89]
	global_load_dwordx4 v[128:131], v246, s[88:89]
	global_load_dwordx4 v[132:135], v148, s[88:89] offset:768
	global_load_dwordx4 v[136:139], v151, s[88:89] offset:768
	global_load_dwordx4 v[140:143], v148, s[88:89] offset:832
	global_load_dwordx4 v[144:147], v151, s[88:89] offset:832
	s_add_u32 s88, s88, 0x300000
	s_addc_u32 s89, s89, 0
	ds_read_b64_tr_b16 v[72:73], v231
	ds_read_b64_tr_b16 v[74:75], v231 offset:512
	ds_read_b64_tr_b16 v[76:77], v231 offset:2048
	ds_read_b64_tr_b16 v[78:79], v231 offset:2560
	ds_read_b64_tr_b16 v[220:221], v231 offset:1024
	ds_read_b64_tr_b16 v[222:223], v231 offset:1536
	ds_read_b64_tr_b16 v[224:225], v231 offset:3072
	ds_read_b64_tr_b16 v[226:227], v231 offset:3584
	s_waitcnt vmcnt(8)
	ds_write_b128 v247, v[156:159]
	ds_write_b128 v247, v[160:163] offset:1024
	ds_write_b128 v111, v[164:167] offset:2048
	ds_write_b128 v111, v[168:171] offset:3072
	ds_read_b128 v[156:159], v248
	ds_read_b128 v[160:163], v249
	ds_read_b128 v[164:167], v250
	ds_read_b128 v[168:171], v251
	ds_write_b128 v112, v[172:175]
	ds_write_b128 v112, v[176:179] offset:1024
	ds_write_b128 v112, v[180:183] offset:2048
	ds_write_b128 v112, v[184:187] offset:3072
	v_exp_f32_e32 v32, v32
	v_exp_f32_e32 v33, v33
	v_exp_f32_e32 v34, v34
	v_exp_f32_e32 v35, v35
	v_exp_f32_e32 v36, v36
	v_exp_f32_e32 v37, v37
	s_waitcnt lgkmcnt(4)
	v_mfma_f32_32x32x16_bf16 v[188:203], v[156:159], v[48:51], v[188:203]
	v_exp_f32_e32 v38, v38
	v_exp_f32_e32 v39, v39
	v_mfma_f32_32x32x16_bf16 v[188:203], v[160:163], v[52:55], v[188:203]
	v_exp_f32_e32 v40, v40
	v_exp_f32_e32 v41, v41
	v_exp_f32_e32 v42, v42
	v_mfma_f32_32x32x16_bf16 v[188:203], v[164:167], v[56:59], v[188:203]
	v_exp_f32_e32 v43, v43
	v_exp_f32_e32 v44, v44
	v_mfma_f32_32x32x16_bf16 v[188:203], v[168:171], v[60:63], v[188:203]
	v_exp_f32_e32 v45, v45
	v_exp_f32_e32 v46, v46
	v_exp_f32_e32 v47, v47
	v_cvt_pk_bf16_f32 v64, v32, v33
	v_cvt_pk_bf16_f32 v65, v34, v35
	v_cvt_pk_bf16_f32 v66, v36, v37
	v_cvt_pk_bf16_f32 v67, v38, v39
	v_cvt_pk_bf16_f32 v68, v40, v41
	v_cvt_pk_bf16_f32 v69, v42, v43
	v_cvt_pk_bf16_f32 v70, v44, v45
	v_cvt_pk_bf16_f32 v71, v46, v47
	v_pk_add_f32 v[232:233], v[232:233], v[32:33]
	v_pk_add_f32 v[232:233], v[232:233], v[34:35]
	v_pk_add_f32 v[232:233], v[232:233], v[36:37]
	v_pk_add_f32 v[232:233], v[232:233], v[38:39]
	v_pk_add_f32 v[232:233], v[232:233], v[40:41]
	v_pk_add_f32 v[232:233], v[232:233], v[42:43]
	v_pk_add_f32 v[232:233], v[232:233], v[44:45]
	v_pk_add_f32 v[232:233], v[232:233], v[46:47]
	v_mov_b32_e32 v115, v230
	ds_read2_b32 v[32:33], v115 offset0:0 offset1:1
	ds_read2_b32 v[34:35], v115 offset0:2 offset1:3
	ds_read2_b32 v[36:37], v115 offset0:8 offset1:9
	ds_read2_b32 v[38:39], v115 offset0:10 offset1:11
	ds_read2_b32 v[40:41], v115 offset0:16 offset1:17
	ds_read2_b32 v[42:43], v115 offset0:18 offset1:19
	ds_read2_b32 v[44:45], v115 offset0:24 offset1:25
	ds_read2_b32 v[46:47], v115 offset0:26 offset1:27
	v_mfma_f32_32x32x16_bf16 v[0:15], v[64:67], v[72:75], v[0:15]
	v_mfma_f32_32x32x16_bf16 v[16:31], v[64:67], v[76:79], v[16:31]
	v_mfma_f32_32x32x16_bf16 v[0:15], v[68:71], v[220:223], v[0:15]
	v_mfma_f32_32x32x16_bf16 v[16:31], v[68:71], v[224:227], v[16:31]
	global_load_dwordx4 v[156:159], v243, s[88:89]
	global_load_dwordx4 v[160:163], v244, s[88:89]
	global_load_dwordx4 v[164:167], v245, s[88:89]
	global_load_dwordx4 v[168:171], v246, s[88:89]
	global_load_dwordx4 v[172:175], v148, s[88:89] offset:768
	global_load_dwordx4 v[176:179], v151, s[88:89] offset:768
	global_load_dwordx4 v[180:183], v148, s[88:89] offset:832
	global_load_dwordx4 v[184:187], v151, s[88:89] offset:832
	s_add_u32 s88, s88, 0x300000
	s_addc_u32 s89, s89, 0
	ds_read_b64_tr_b16 v[72:73], v231
	ds_read_b64_tr_b16 v[74:75], v231 offset:512
	ds_read_b64_tr_b16 v[76:77], v231 offset:2048
	ds_read_b64_tr_b16 v[78:79], v231 offset:2560
	ds_read_b64_tr_b16 v[220:221], v231 offset:1024
	ds_read_b64_tr_b16 v[222:223], v231 offset:1536
	ds_read_b64_tr_b16 v[224:225], v231 offset:3072
	ds_read_b64_tr_b16 v[226:227], v231 offset:3584
	s_waitcnt vmcnt(8)
	ds_write_b128 v247, v[116:119]
	ds_write_b128 v247, v[120:123] offset:1024
	ds_write_b128 v111, v[124:127] offset:2048
	ds_write_b128 v111, v[128:131] offset:3072
	ds_read_b128 v[116:119], v248
	ds_read_b128 v[120:123], v249
	ds_read_b128 v[124:127], v250
	ds_read_b128 v[128:131], v251
	ds_write_b128 v112, v[132:135]
	ds_write_b128 v112, v[136:139] offset:1024
	ds_write_b128 v112, v[140:143] offset:2048
	ds_write_b128 v112, v[144:147] offset:3072
	v_exp_f32_e32 v188, v188
	v_exp_f32_e32 v189, v189
	v_exp_f32_e32 v190, v190
	v_exp_f32_e32 v191, v191
	v_exp_f32_e32 v192, v192
	v_exp_f32_e32 v193, v193
	s_waitcnt lgkmcnt(4)
	v_mfma_f32_32x32x16_bf16 v[32:47], v[116:119], v[48:51], v[32:47]
	v_exp_f32_e32 v194, v194
	v_exp_f32_e32 v195, v195
	v_mfma_f32_32x32x16_bf16 v[32:47], v[120:123], v[52:55], v[32:47]
	v_exp_f32_e32 v196, v196
	v_exp_f32_e32 v197, v197
	v_exp_f32_e32 v198, v198
	v_mfma_f32_32x32x16_bf16 v[32:47], v[124:127], v[56:59], v[32:47]
	v_exp_f32_e32 v199, v199
	v_exp_f32_e32 v200, v200
	v_mfma_f32_32x32x16_bf16 v[32:47], v[128:131], v[60:63], v[32:47]
	v_exp_f32_e32 v201, v201
	v_exp_f32_e32 v202, v202
	v_exp_f32_e32 v203, v203
	v_cvt_pk_bf16_f32 v64, v188, v189
	v_cvt_pk_bf16_f32 v65, v190, v191
	v_cvt_pk_bf16_f32 v66, v192, v193
	v_cvt_pk_bf16_f32 v67, v194, v195
	v_cvt_pk_bf16_f32 v68, v196, v197
	v_cvt_pk_bf16_f32 v69, v198, v199
	v_cvt_pk_bf16_f32 v70, v200, v201
	v_cvt_pk_bf16_f32 v71, v202, v203
	v_pk_add_f32 v[232:233], v[232:233], v[188:189]
	v_pk_add_f32 v[232:233], v[232:233], v[190:191]
	v_pk_add_f32 v[232:233], v[232:233], v[192:193]
	v_pk_add_f32 v[232:233], v[232:233], v[194:195]
	v_pk_add_f32 v[232:233], v[232:233], v[196:197]
	v_pk_add_f32 v[232:233], v[232:233], v[198:199]
	v_pk_add_f32 v[232:233], v[232:233], v[200:201]
	v_pk_add_f32 v[232:233], v[232:233], v[202:203]
	ds_read2_b32 v[188:189], v115 offset0:32 offset1:33
	ds_read2_b32 v[190:191], v115 offset0:34 offset1:35
	ds_read2_b32 v[192:193], v115 offset0:40 offset1:41
	ds_read2_b32 v[194:195], v115 offset0:42 offset1:43
	ds_read2_b32 v[196:197], v115 offset0:48 offset1:49
	ds_read2_b32 v[198:199], v115 offset0:50 offset1:51
	ds_read2_b32 v[200:201], v115 offset0:56 offset1:57
	ds_read2_b32 v[202:203], v115 offset0:58 offset1:59
	v_mfma_f32_32x32x16_bf16 v[0:15], v[64:67], v[72:75], v[0:15]
	v_mfma_f32_32x32x16_bf16 v[16:31], v[64:67], v[76:79], v[16:31]
	v_mfma_f32_32x32x16_bf16 v[0:15], v[68:71], v[220:223], v[0:15]
	v_mfma_f32_32x32x16_bf16 v[16:31], v[68:71], v[224:227], v[16:31]
	global_load_dwordx4 v[116:119], v243, s[88:89]
	global_load_dwordx4 v[120:123], v244, s[88:89]
	global_load_dwordx4 v[124:127], v245, s[88:89]
	global_load_dwordx4 v[128:131], v246, s[88:89]
	global_load_dwordx4 v[132:135], v148, s[88:89] offset:768
	global_load_dwordx4 v[136:139], v151, s[88:89] offset:768
	global_load_dwordx4 v[140:143], v148, s[88:89] offset:832
	global_load_dwordx4 v[144:147], v151, s[88:89] offset:832
	s_add_u32 s88, s88, 0x300000
	s_addc_u32 s89, s89, 0
	ds_read_b64_tr_b16 v[72:73], v231
	ds_read_b64_tr_b16 v[74:75], v231 offset:512
	ds_read_b64_tr_b16 v[76:77], v231 offset:2048
	ds_read_b64_tr_b16 v[78:79], v231 offset:2560
	ds_read_b64_tr_b16 v[220:221], v231 offset:1024
	ds_read_b64_tr_b16 v[222:223], v231 offset:1536
	ds_read_b64_tr_b16 v[224:225], v231 offset:3072
	ds_read_b64_tr_b16 v[226:227], v231 offset:3584
	s_waitcnt vmcnt(8)
	ds_write_b128 v247, v[156:159]
	ds_write_b128 v247, v[160:163] offset:1024
	ds_write_b128 v111, v[164:167] offset:2048
	ds_write_b128 v111, v[168:171] offset:3072
	ds_read_b128 v[156:159], v248
	ds_read_b128 v[160:163], v249
	ds_read_b128 v[164:167], v250
	ds_read_b128 v[168:171], v251
	ds_write_b128 v112, v[172:175]
	ds_write_b128 v112, v[176:179] offset:1024
	ds_write_b128 v112, v[180:183] offset:2048
	ds_write_b128 v112, v[184:187] offset:3072
	v_exp_f32_e32 v32, v32
	v_exp_f32_e32 v33, v33
	v_exp_f32_e32 v34, v34
	v_exp_f32_e32 v35, v35
	v_exp_f32_e32 v36, v36
	v_exp_f32_e32 v37, v37
	s_waitcnt lgkmcnt(4)
	v_mfma_f32_32x32x16_bf16 v[188:203], v[156:159], v[48:51], v[188:203]
	v_exp_f32_e32 v38, v38
	v_exp_f32_e32 v39, v39
	v_mfma_f32_32x32x16_bf16 v[188:203], v[160:163], v[52:55], v[188:203]
	v_exp_f32_e32 v40, v40
	v_exp_f32_e32 v41, v41
	v_exp_f32_e32 v42, v42
	v_mfma_f32_32x32x16_bf16 v[188:203], v[164:167], v[56:59], v[188:203]
	v_exp_f32_e32 v43, v43
	v_exp_f32_e32 v44, v44
	v_mfma_f32_32x32x16_bf16 v[188:203], v[168:171], v[60:63], v[188:203]
	v_exp_f32_e32 v45, v45
	v_exp_f32_e32 v46, v46
	v_exp_f32_e32 v47, v47
	v_cvt_pk_bf16_f32 v64, v32, v33
	v_cvt_pk_bf16_f32 v65, v34, v35
	v_cvt_pk_bf16_f32 v66, v36, v37
	v_cvt_pk_bf16_f32 v67, v38, v39
	v_cvt_pk_bf16_f32 v68, v40, v41
	v_cvt_pk_bf16_f32 v69, v42, v43
	v_cvt_pk_bf16_f32 v70, v44, v45
	v_cvt_pk_bf16_f32 v71, v46, v47
	v_pk_add_f32 v[232:233], v[232:233], v[32:33]
	v_pk_add_f32 v[232:233], v[232:233], v[34:35]
	v_pk_add_f32 v[232:233], v[232:233], v[36:37]
	v_pk_add_f32 v[232:233], v[232:233], v[38:39]
	v_pk_add_f32 v[232:233], v[232:233], v[40:41]
	v_pk_add_f32 v[232:233], v[232:233], v[42:43]
	v_pk_add_f32 v[232:233], v[232:233], v[44:45]
	v_pk_add_f32 v[232:233], v[232:233], v[46:47]
	ds_read2_b32 v[32:33], v115 offset0:64 offset1:65
	ds_read2_b32 v[34:35], v115 offset0:66 offset1:67
	ds_read2_b32 v[36:37], v115 offset0:72 offset1:73
	ds_read2_b32 v[38:39], v115 offset0:74 offset1:75
	ds_read2_b32 v[40:41], v115 offset0:80 offset1:81
	ds_read2_b32 v[42:43], v115 offset0:82 offset1:83
	ds_read2_b32 v[44:45], v115 offset0:88 offset1:89
	ds_read2_b32 v[46:47], v115 offset0:90 offset1:91
	v_mfma_f32_32x32x16_bf16 v[0:15], v[64:67], v[72:75], v[0:15]
	v_mfma_f32_32x32x16_bf16 v[16:31], v[64:67], v[76:79], v[16:31]
	v_mfma_f32_32x32x16_bf16 v[0:15], v[68:71], v[220:223], v[0:15]
	v_mfma_f32_32x32x16_bf16 v[16:31], v[68:71], v[224:227], v[16:31]
	global_load_dwordx4 v[156:159], v243, s[88:89]
	global_load_dwordx4 v[160:163], v244, s[88:89]
	global_load_dwordx4 v[164:167], v245, s[88:89]
	global_load_dwordx4 v[168:171], v246, s[88:89]
	global_load_dwordx4 v[172:175], v148, s[88:89] offset:768
	global_load_dwordx4 v[176:179], v151, s[88:89] offset:768
	global_load_dwordx4 v[180:183], v148, s[88:89] offset:832
	global_load_dwordx4 v[184:187], v151, s[88:89] offset:832
	s_add_u32 s88, s88, 0x300000
	s_addc_u32 s89, s89, 0
	ds_read_b64_tr_b16 v[72:73], v231
	ds_read_b64_tr_b16 v[74:75], v231 offset:512
	ds_read_b64_tr_b16 v[76:77], v231 offset:2048
	ds_read_b64_tr_b16 v[78:79], v231 offset:2560
	ds_read_b64_tr_b16 v[220:221], v231 offset:1024
	ds_read_b64_tr_b16 v[222:223], v231 offset:1536
	ds_read_b64_tr_b16 v[224:225], v231 offset:3072
	ds_read_b64_tr_b16 v[226:227], v231 offset:3584
	s_waitcnt vmcnt(8)
	ds_write_b128 v247, v[116:119]
	ds_write_b128 v247, v[120:123] offset:1024
	ds_write_b128 v111, v[124:127] offset:2048
	ds_write_b128 v111, v[128:131] offset:3072
	ds_read_b128 v[116:119], v248
	ds_read_b128 v[120:123], v249
	ds_read_b128 v[124:127], v250
	ds_read_b128 v[128:131], v251
	ds_write_b128 v112, v[132:135]
	ds_write_b128 v112, v[136:139] offset:1024
	ds_write_b128 v112, v[140:143] offset:2048
	ds_write_b128 v112, v[144:147] offset:3072
	v_exp_f32_e32 v188, v188
	v_exp_f32_e32 v189, v189
	v_exp_f32_e32 v190, v190
	v_exp_f32_e32 v191, v191
	v_exp_f32_e32 v192, v192
	v_exp_f32_e32 v193, v193
	s_waitcnt lgkmcnt(4)
	v_mfma_f32_32x32x16_bf16 v[32:47], v[116:119], v[48:51], v[32:47]
	v_exp_f32_e32 v194, v194
	v_exp_f32_e32 v195, v195
	v_mfma_f32_32x32x16_bf16 v[32:47], v[120:123], v[52:55], v[32:47]
	v_exp_f32_e32 v196, v196
	v_exp_f32_e32 v197, v197
	v_exp_f32_e32 v198, v198
	v_mfma_f32_32x32x16_bf16 v[32:47], v[124:127], v[56:59], v[32:47]
	v_exp_f32_e32 v199, v199
	v_exp_f32_e32 v200, v200
	v_mfma_f32_32x32x16_bf16 v[32:47], v[128:131], v[60:63], v[32:47]
	v_exp_f32_e32 v201, v201
	v_exp_f32_e32 v202, v202
	v_exp_f32_e32 v203, v203
	v_cvt_pk_bf16_f32 v64, v188, v189
	v_cvt_pk_bf16_f32 v65, v190, v191
	v_cvt_pk_bf16_f32 v66, v192, v193
	v_cvt_pk_bf16_f32 v67, v194, v195
	v_cvt_pk_bf16_f32 v68, v196, v197
	v_cvt_pk_bf16_f32 v69, v198, v199
	v_cvt_pk_bf16_f32 v70, v200, v201
	v_cvt_pk_bf16_f32 v71, v202, v203
	v_pk_add_f32 v[232:233], v[232:233], v[188:189]
	v_pk_add_f32 v[232:233], v[232:233], v[190:191]
	v_pk_add_f32 v[232:233], v[232:233], v[192:193]
	v_pk_add_f32 v[232:233], v[232:233], v[194:195]
	v_pk_add_f32 v[232:233], v[232:233], v[196:197]
	v_pk_add_f32 v[232:233], v[232:233], v[198:199]
	v_pk_add_f32 v[232:233], v[232:233], v[200:201]
	v_pk_add_f32 v[232:233], v[232:233], v[202:203]
	ds_read2_b32 v[188:189], v115 offset0:96 offset1:97
	ds_read2_b32 v[190:191], v115 offset0:98 offset1:99
	ds_read2_b32 v[192:193], v115 offset0:104 offset1:105
	ds_read2_b32 v[194:195], v115 offset0:106 offset1:107
	ds_read2_b32 v[196:197], v115 offset0:112 offset1:113
	ds_read2_b32 v[198:199], v115 offset0:114 offset1:115
	ds_read2_b32 v[200:201], v115 offset0:120 offset1:121
	ds_read2_b32 v[202:203], v115 offset0:122 offset1:123
	v_mfma_f32_32x32x16_bf16 v[0:15], v[64:67], v[72:75], v[0:15]
	v_mfma_f32_32x32x16_bf16 v[16:31], v[64:67], v[76:79], v[16:31]
	v_mfma_f32_32x32x16_bf16 v[0:15], v[68:71], v[220:223], v[0:15]
	v_mfma_f32_32x32x16_bf16 v[16:31], v[68:71], v[224:227], v[16:31]
	global_load_dwordx4 v[116:119], v243, s[88:89]
	global_load_dwordx4 v[120:123], v244, s[88:89]
	global_load_dwordx4 v[124:127], v245, s[88:89]
	global_load_dwordx4 v[128:131], v246, s[88:89]
	global_load_dwordx4 v[132:135], v148, s[88:89] offset:768
	global_load_dwordx4 v[136:139], v151, s[88:89] offset:768
	global_load_dwordx4 v[140:143], v148, s[88:89] offset:832
	global_load_dwordx4 v[144:147], v151, s[88:89] offset:832
	ds_read_b64_tr_b16 v[72:73], v231
	ds_read_b64_tr_b16 v[74:75], v231 offset:512
	ds_read_b64_tr_b16 v[76:77], v231 offset:2048
	ds_read_b64_tr_b16 v[78:79], v231 offset:2560
	ds_read_b64_tr_b16 v[220:221], v231 offset:1024
	ds_read_b64_tr_b16 v[222:223], v231 offset:1536
	ds_read_b64_tr_b16 v[224:225], v231 offset:3072
	ds_read_b64_tr_b16 v[226:227], v231 offset:3584
	s_waitcnt vmcnt(8)
	ds_write_b128 v247, v[156:159]
	ds_write_b128 v247, v[160:163] offset:1024
	ds_write_b128 v111, v[164:167] offset:2048
	ds_write_b128 v111, v[168:171] offset:3072
	ds_read_b128 v[156:159], v248
	ds_read_b128 v[160:163], v249
	ds_read_b128 v[164:167], v250
	ds_read_b128 v[168:171], v251
	ds_write_b128 v112, v[172:175]
	ds_write_b128 v112, v[176:179] offset:1024
	ds_write_b128 v112, v[180:183] offset:2048
	ds_write_b128 v112, v[184:187] offset:3072
	v_exp_f32_e32 v32, v32
	v_exp_f32_e32 v33, v33
	v_exp_f32_e32 v34, v34
	v_exp_f32_e32 v35, v35
	v_exp_f32_e32 v36, v36
	v_exp_f32_e32 v37, v37
	s_waitcnt lgkmcnt(4)
	v_mfma_f32_32x32x16_bf16 v[188:203], v[156:159], v[48:51], v[188:203]
	v_exp_f32_e32 v38, v38
	v_exp_f32_e32 v39, v39
	v_mfma_f32_32x32x16_bf16 v[188:203], v[160:163], v[52:55], v[188:203]
	v_exp_f32_e32 v40, v40
	v_exp_f32_e32 v41, v41
	v_exp_f32_e32 v42, v42
	v_mfma_f32_32x32x16_bf16 v[188:203], v[164:167], v[56:59], v[188:203]
	v_exp_f32_e32 v43, v43
	v_exp_f32_e32 v44, v44
	v_mfma_f32_32x32x16_bf16 v[188:203], v[168:171], v[60:63], v[188:203]
	v_exp_f32_e32 v45, v45
	v_exp_f32_e32 v46, v46
	v_exp_f32_e32 v47, v47
	v_cvt_pk_bf16_f32 v64, v32, v33
	v_cvt_pk_bf16_f32 v65, v34, v35
	v_cvt_pk_bf16_f32 v66, v36, v37
	v_cvt_pk_bf16_f32 v67, v38, v39
	v_cvt_pk_bf16_f32 v68, v40, v41
	v_cvt_pk_bf16_f32 v69, v42, v43
	v_cvt_pk_bf16_f32 v70, v44, v45
	v_cvt_pk_bf16_f32 v71, v46, v47
	v_pk_add_f32 v[232:233], v[232:233], v[32:33]
	v_pk_add_f32 v[232:233], v[232:233], v[34:35]
	v_pk_add_f32 v[232:233], v[232:233], v[36:37]
	v_pk_add_f32 v[232:233], v[232:233], v[38:39]
	v_pk_add_f32 v[232:233], v[232:233], v[40:41]
	v_pk_add_f32 v[232:233], v[232:233], v[42:43]
	v_pk_add_f32 v[232:233], v[232:233], v[44:45]
	v_pk_add_f32 v[232:233], v[232:233], v[46:47]
	ds_read2_b32 v[32:33], v115 offset0:128 offset1:129
	ds_read2_b32 v[34:35], v115 offset0:130 offset1:131
	ds_read2_b32 v[36:37], v115 offset0:136 offset1:137
	ds_read2_b32 v[38:39], v115 offset0:138 offset1:139
	ds_read2_b32 v[40:41], v115 offset0:144 offset1:145
	ds_read2_b32 v[42:43], v115 offset0:146 offset1:147
	ds_read2_b32 v[44:45], v115 offset0:152 offset1:153
	ds_read2_b32 v[46:47], v115 offset0:154 offset1:155
	v_mfma_f32_32x32x16_bf16 v[0:15], v[64:67], v[72:75], v[0:15]
	v_mfma_f32_32x32x16_bf16 v[16:31], v[64:67], v[76:79], v[16:31]
	v_mfma_f32_32x32x16_bf16 v[0:15], v[68:71], v[220:223], v[0:15]
	v_mfma_f32_32x32x16_bf16 v[16:31], v[68:71], v[224:227], v[16:31]
	ds_read_b64_tr_b16 v[72:73], v231
	ds_read_b64_tr_b16 v[74:75], v231 offset:512
	ds_read_b64_tr_b16 v[76:77], v231 offset:2048
	ds_read_b64_tr_b16 v[78:79], v231 offset:2560
	ds_read_b64_tr_b16 v[220:221], v231 offset:1024
	ds_read_b64_tr_b16 v[222:223], v231 offset:1536
	ds_read_b64_tr_b16 v[224:225], v231 offset:3072
	ds_read_b64_tr_b16 v[226:227], v231 offset:3584
	s_waitcnt vmcnt(0)
; __device__ __forceinline__ int crow(int r, int hi) { return (r & 3) + 8 * (r >> 2) + 4 * hi; }
; __device__ __forceinline__ void dil_unit(LAS unsigned char* lds, bf16_t* proj, int seq, int hd, int T0, int rho) {
;     ...
;     l += __shfl_xor(l, 32);
; #pragma unroll
;     for (int rr = 0; rr < 16; ++rr) {
;         const int j = crow(rr, hi);
	ds_write_b128 v247, v[116:119]
	ds_write_b128 v247, v[120:123] offset:1024
	ds_write_b128 v111, v[124:127] offset:2048
	ds_write_b128 v111, v[128:131] offset:3072
	ds_read_b128 v[116:119], v248
	ds_read_b128 v[120:123], v249
	ds_read_b128 v[124:127], v250
	ds_read_b128 v[128:131], v251
	ds_write_b128 v112, v[132:135]
	ds_write_b128 v112, v[136:139] offset:1024
	ds_write_b128 v112, v[140:143] offset:2048
	ds_write_b128 v112, v[144:147] offset:3072
	v_exp_f32_e32 v188, v188
	v_exp_f32_e32 v189, v189
	v_exp_f32_e32 v190, v190
	v_exp_f32_e32 v191, v191
	v_exp_f32_e32 v192, v192
	v_exp_f32_e32 v193, v193
	s_waitcnt lgkmcnt(4)
	v_mfma_f32_32x32x16_bf16 v[32:47], v[116:119], v[48:51], v[32:47]
	v_exp_f32_e32 v194, v194
	v_exp_f32_e32 v195, v195
	v_mfma_f32_32x32x16_bf16 v[32:47], v[120:123], v[52:55], v[32:47]
	v_exp_f32_e32 v196, v196
	v_exp_f32_e32 v197, v197
	v_exp_f32_e32 v198, v198
	v_mfma_f32_32x32x16_bf16 v[32:47], v[124:127], v[56:59], v[32:47]
	v_exp_f32_e32 v199, v199
	v_exp_f32_e32 v200, v200
	v_mfma_f32_32x32x16_bf16 v[32:47], v[128:131], v[60:63], v[32:47]
	v_exp_f32_e32 v201, v201
	v_exp_f32_e32 v202, v202
	v_exp_f32_e32 v203, v203
	v_cvt_pk_bf16_f32 v64, v188, v189
	v_cvt_pk_bf16_f32 v65, v190, v191
	v_cvt_pk_bf16_f32 v66, v192, v193
	v_cvt_pk_bf16_f32 v67, v194, v195
	v_cvt_pk_bf16_f32 v68, v196, v197
	v_cvt_pk_bf16_f32 v69, v198, v199
	v_cvt_pk_bf16_f32 v70, v200, v201
	v_cvt_pk_bf16_f32 v71, v202, v203
	v_pk_add_f32 v[232:233], v[232:233], v[188:189]
	v_pk_add_f32 v[232:233], v[232:233], v[190:191]
	v_pk_add_f32 v[232:233], v[232:233], v[192:193]
	v_pk_add_f32 v[232:233], v[232:233], v[194:195]
	v_pk_add_f32 v[232:233], v[232:233], v[196:197]
	v_pk_add_f32 v[232:233], v[232:233], v[198:199]
	v_pk_add_f32 v[232:233], v[232:233], v[200:201]
	v_pk_add_f32 v[232:233], v[232:233], v[202:203]
	v_mfma_f32_32x32x16_bf16 v[0:15], v[64:67], v[72:75], v[0:15]
	v_mfma_f32_32x32x16_bf16 v[16:31], v[64:67], v[76:79], v[16:31]
	v_mfma_f32_32x32x16_bf16 v[0:15], v[68:71], v[220:223], v[0:15]
	v_mfma_f32_32x32x16_bf16 v[16:31], v[68:71], v[224:227], v[16:31]
	ds_read_b64_tr_b16 v[72:73], v231
	ds_read_b64_tr_b16 v[74:75], v231 offset:512
	ds_read_b64_tr_b16 v[76:77], v231 offset:2048
	ds_read_b64_tr_b16 v[78:79], v231 offset:2560
	ds_read_b64_tr_b16 v[220:221], v231 offset:1024
	ds_read_b64_tr_b16 v[222:223], v231 offset:1536
	ds_read_b64_tr_b16 v[224:225], v231 offset:3072
	ds_read_b64_tr_b16 v[226:227], v231 offset:3584
	s_waitcnt lgkmcnt(0)
	v_exp_f32_e32 v32, v32
	v_exp_f32_e32 v33, v33
	v_exp_f32_e32 v34, v34
	v_exp_f32_e32 v35, v35
	v_exp_f32_e32 v36, v36
	v_exp_f32_e32 v37, v37
	v_exp_f32_e32 v38, v38
	v_exp_f32_e32 v39, v39
	v_exp_f32_e32 v40, v40
	v_exp_f32_e32 v41, v41
	v_exp_f32_e32 v42, v42
	v_exp_f32_e32 v43, v43
	v_exp_f32_e32 v44, v44
	v_exp_f32_e32 v45, v45
	v_exp_f32_e32 v46, v46
	v_exp_f32_e32 v47, v47
	v_cvt_pk_bf16_f32 v64, v32, v33
	v_cvt_pk_bf16_f32 v65, v34, v35
	v_cvt_pk_bf16_f32 v66, v36, v37
	v_cvt_pk_bf16_f32 v67, v38, v39
	v_cvt_pk_bf16_f32 v68, v40, v41
	v_cvt_pk_bf16_f32 v69, v42, v43
	v_cvt_pk_bf16_f32 v70, v44, v45
	v_cvt_pk_bf16_f32 v71, v46, v47
	v_pk_add_f32 v[232:233], v[232:233], v[32:33]
	v_pk_add_f32 v[232:233], v[232:233], v[34:35]
	v_pk_add_f32 v[232:233], v[232:233], v[36:37]
	v_pk_add_f32 v[232:233], v[232:233], v[38:39]
	v_pk_add_f32 v[232:233], v[232:233], v[40:41]
	v_pk_add_f32 v[232:233], v[232:233], v[42:43]
	v_pk_add_f32 v[232:233], v[232:233], v[44:45]
	v_pk_add_f32 v[232:233], v[232:233], v[46:47]
	v_mfma_f32_32x32x16_bf16 v[0:15], v[64:67], v[72:75], v[0:15]
	v_mfma_f32_32x32x16_bf16 v[16:31], v[64:67], v[76:79], v[16:31]
	v_mfma_f32_32x32x16_bf16 v[0:15], v[68:71], v[220:223], v[0:15]
	v_mfma_f32_32x32x16_bf16 v[16:31], v[68:71], v[224:227], v[16:31]
	v_add_f32_e32 v113, v232, v233
	v_or_b32_e32 v114, 1, v107
	v_or_b32_e32 v97, 2, v107
	v_or_b32_e32 v96, 3, v107
	v_or_b32_e32 v95, 8, v107
	v_or_b32_e32 v94, 9, v107
	v_or_b32_e32 v93, 10, v107
	v_or_b32_e32 v92, 11, v107
	v_or_b32_e32 v91, 16, v107
	v_or_b32_e32 v90, 17, v107
	v_or_b32_e32 v89, 18, v107
	v_or_b32_e32 v88, 19, v107
	v_or_b32_e32 v87, 24, v107
	v_or_b32_e32 v86, 25, v107
	v_or_b32_e32 v85, 26, v107
	v_or_b32_e32 v84, 27, v107
	s_nop 11
	s_branch .LBB0_1265
; #define LAS __attribute__((address_space(3)))
; #define GAS __attribute__((address_space(1)))
; __device__ __forceinline__ void dil_unit(LAS unsigned char* lds, bf16_t* proj, int seq, int hd, int T0, int rho) {
;     int tid_ = threadIdx.x; asm volatile("" : "+v"(tid_));
;     const int tid = tid_, lane = tid & 63, r32 = lane & 31, hi = lane >> 5, wid = __builtin_amdgcn_readfirstlane(tid >> 6);
;     bf16_t* base = proj + (size_t)seq * SEQ * NIN;
;     LAS unsigned char* wbuf = lds + wid * 4096;
;     const LAS unsigned char* vp = wbuf + ((lane >> 4) & 1) * 32 + (lane & 3) * 8 + (4 * hi + ((lane & 15) >> 2)) * 64;
;     const int P0 = T0 + rho;
;     bf16x8 qr[4];
; #pragma unroll
;     for (int ks = 0; ks < 4; ++ks) qr[ks] = *(const GAS bf16x8*)(base + (size_t)(P0 + 16 * r32) * NIN + PC_LQ + hd * 64 + 16 * ks + 8 * hi);
;     f32x16 o0 = {}, o1 = {}; float l = 0.f;
;     const bool bound = (T0 < 1024) || (T0 >= 15360);
.LBB0_1270:
	s_movk_i32 s100, 0x1800
	s_add_i32 s101, s8, 0x15c00
	s_lshl_b32 s90, s54, 1
	s_add_u32 s82, s52, s90
	s_addc_u32 s83, s53, 0
	s_add_u32 s82, s82, 0x1200
	s_addc_u32 s83, s83, 0
	s_sub_i32 s90, s67, 64
	s_mul_i32 s90, s90, 0x1800
	s_add_u32 s84, s82, s90
	s_addc_u32 s85, s83, 0
	s_sub_i32 s90, s67, 256
	s_mul_i32 s90, s90, 0x1800
	s_add_u32 s86, s82, s90
	s_addc_u32 s87, s83, 0
	s_sub_i32 s90, s67, 1024
	s_mul_i32 s90, s90, 0x1800
	s_add_u32 s88, s82, s90
	s_addc_u32 s89, s83, 0
	v_lshlrev_b32_e32 v153, 1, v98
	v_mad_u32_u24 v80, v105, s100, v82
	v_mad_u32_u24 v100, v110, s100, v153
	v_add_u32_e32 v149, 0x18000, v100
	v_lshlrev_b32_e32 v83, 2, v105
	v_mad_u32_u24 v83, v83, s100, v82
	v_lshlrev_b32_e32 v101, 2, v110
	v_mad_u32_u24 v101, v101, s100, v153
	v_add_u32_e32 v150, 0x60000, v101
	v_lshlrev_b32_e32 v99, 4, v105
	v_mad_u32_u24 v99, v99, s100, v82
	v_lshlrev_b32_e32 v148, 4, v110
	v_mad_u32_u24 v148, v148, s100, v153
	v_add_u32_e32 v151, 0x180000, v148
	v_lshrrev_b32_e32 v249, 3, v103
	v_and_b32_e32 v250, 7, v103
	v_lshlrev_b32_e32 v250, 4, v250
	v_add_u32_e32 v235, 0, v249
	v_add_u32_e32 v236, 8, v249
	v_add_u32_e32 v237, 16, v249
	v_add_u32_e32 v238, 24, v249
	v_add_u32_e32 v239, 0, v249
	v_lshlrev_b32_e32 v239, 2, v239
	v_add_u32_e32 v240, 8, v249
	v_lshlrev_b32_e32 v240, 2, v240
	v_add_u32_e32 v241, 16, v249
	v_lshlrev_b32_e32 v241, 2, v241
	v_add_u32_e32 v242, 24, v249
	v_lshlrev_b32_e32 v242, 2, v242
	v_add_u32_e32 v243, 0, v249
	v_lshlrev_b32_e32 v243, 4, v243
	v_add_u32_e32 v244, 8, v249
	v_lshlrev_b32_e32 v244, 4, v244
	v_add_u32_e32 v245, 16, v249
	v_lshlrev_b32_e32 v245, 4, v245
	v_add_u32_e32 v246, 24, v249
	v_lshlrev_b32_e32 v246, 4, v246
	v_mov_b32_e32 v252, v250
	v_mov_b32_e32 v100, v110
	v_add_u32_e32 v149, 16, v100
	v_lshlrev_b32_e32 v101, 2, v110
	v_add_u32_e32 v150, 64, v101
	v_lshlrev_b32_e32 v148, 4, v110
	v_add_u32_e32 v151, 256, v148
	s_mov_b32 s98, 0x4000
	s_mov_b32 s99, 0x3fff
	v_and_b32_e32 v247, 7, v249
	v_lshlrev_b32_e32 v247, 4, v247
	v_xor_b32_e32 v247, v247, v112
	v_xor_b32_e32 v111, 16, v247
	v_and_b32_e32 v153, 7, v105
	v_lshrrev_b32_e32 v248, 4, v105
	v_xor_b32_e32 v153, v153, v248
	v_or_b32_e32 v248, 0, v106
	v_xor_b32_e32 v248, v248, v153
	v_lshlrev_b32_e32 v248, 4, v248
	v_lshl_add_u32 v248, v105, 7, v248
	v_add_u32_e32 v248, s69, v248
	v_or_b32_e32 v249, 2, v106
	v_xor_b32_e32 v249, v249, v153
	v_lshlrev_b32_e32 v249, 4, v249
	v_lshl_add_u32 v249, v105, 7, v249
	v_add_u32_e32 v249, s69, v249
	v_or_b32_e32 v250, 4, v106
	v_xor_b32_e32 v250, v250, v153
	v_lshlrev_b32_e32 v250, 4, v250
	v_lshl_add_u32 v250, v105, 7, v250
	v_add_u32_e32 v250, s69, v250
	v_or_b32_e32 v251, 6, v106
	v_xor_b32_e32 v251, v251, v153
	v_lshlrev_b32_e32 v251, 4, v251
	v_lshl_add_u32 v251, v105, 7, v251
	v_add_u32_e32 v251, s69, v251
	v_lshlrev_b32_e32 v153, 1, v98
	v_mul_u32_u24_e32 v228, 17, v105
	v_sub_u32_e32 v228, v107, v228
	s_mul_i32 s90, s54, 153
	s_lshr_b32 s90, s90, 1
	s_add_i32 s90, s90, 34876
	v_lshl_add_u32 v228, v228, 2, s90
	v_mul_u32_u24_e32 v229, 5, v105
	v_sub_u32_e32 v229, v107, v229
	v_add_u32_e32 v229, v229, v106
	s_mul_i32 s90, s54, 30
	s_add_i32 s90, s90, 66156
	v_lshl_add_u32 v229, v229, 2, s90
	v_sub_u32_e32 v230, v107, v105
	s_add_i32 s90, s101, 6364
	v_lshl_add_u32 v230, v230, 2, s90
	v_add_u32_e32 v231, v109, v108
	v_mov_b64_e32 v[232:233], 0
	v_mov_b64_e32 v[0:1], 0
	v_mov_b64_e32 v[2:3], 0
	v_mov_b64_e32 v[4:5], 0
	v_mov_b64_e32 v[6:7], 0
	v_mov_b64_e32 v[8:9], 0
	v_mov_b64_e32 v[10:11], 0
	v_mov_b64_e32 v[12:13], 0
	v_mov_b64_e32 v[14:15], 0
	v_mov_b64_e32 v[16:17], 0
	v_mov_b64_e32 v[18:19], 0
	v_mov_b64_e32 v[20:21], 0
	v_mov_b64_e32 v[22:23], 0
	v_mov_b64_e32 v[24:25], 0
	v_mov_b64_e32 v[26:27], 0
	v_mov_b64_e32 v[28:29], 0
	v_mov_b64_e32 v[30:31], 0
	s_add_i32 s90, s67, -64
	v_add_u32_e32 v80, s90, v235
	v_add_u32_e32 v83, s90, v236
	v_add_u32_e32 v99, s90, v237
	v_add_u32_e32 v253, s90, v238
	v_add_u32_e32 v254, s90, v100
	v_add_u32_e32 v255, s90, v149
	v_med3_i32 v80, v80, 0, s99
	v_med3_i32 v83, v83, 0, s99
	v_med3_i32 v99, v99, 0, s99
	v_med3_i32 v253, v253, 0, s99
	v_med3_i32 v254, v254, 0, s99
	v_med3_i32 v255, v255, 0, s99
	v_mad_u32_u24 v80, v80, s100, v252
	v_mad_u32_u24 v83, v83, s100, v252
	v_mad_u32_u24 v99, v99, s100, v252
	v_mad_u32_u24 v253, v253, s100, v252
	v_mad_u32_u24 v254, v254, s100, v153
	v_mad_u32_u24 v255, v255, s100, v153
	global_load_dwordx4 v[116:119], v80, s[82:83]
	global_load_dwordx4 v[120:123], v83, s[82:83]
	global_load_dwordx4 v[124:127], v99, s[82:83]
	global_load_dwordx4 v[128:131], v253, s[82:83]
	global_load_dwordx4 v[132:135], v254, s[82:83] offset:768
	global_load_dwordx4 v[136:139], v255, s[82:83] offset:768
	global_load_dwordx4 v[140:143], v254, s[82:83] offset:832
	global_load_dwordx4 v[144:147], v255, s[82:83] offset:832
	s_add_i32 s90, s67, -32
	v_add_u32_e32 v80, s90, v235
	v_add_u32_e32 v83, s90, v236
	v_add_u32_e32 v99, s90, v237
	v_add_u32_e32 v253, s90, v238
	v_add_u32_e32 v254, s90, v100
	v_add_u32_e32 v255, s90, v149
	v_med3_i32 v80, v80, 0, s99
	v_med3_i32 v83, v83, 0, s99
	v_med3_i32 v99, v99, 0, s99
	v_med3_i32 v253, v253, 0, s99
	v_med3_i32 v254, v254, 0, s99
	v_med3_i32 v255, v255, 0, s99
	v_mad_u32_u24 v80, v80, s100, v252
	v_mad_u32_u24 v83, v83, s100, v252
	v_mad_u32_u24 v99, v99, s100, v252
	v_mad_u32_u24 v253, v253, s100, v252
	v_mad_u32_u24 v254, v254, s100, v153
	v_mad_u32_u24 v255, v255, s100, v153
	global_load_dwordx4 v[156:159], v80, s[82:83]
	global_load_dwordx4 v[160:163], v83, s[82:83]
	global_load_dwordx4 v[164:167], v99, s[82:83]
	global_load_dwordx4 v[168:171], v253, s[82:83]
	global_load_dwordx4 v[172:175], v254, s[82:83] offset:768
	global_load_dwordx4 v[176:179], v255, s[82:83] offset:768
	global_load_dwordx4 v[180:183], v254, s[82:83] offset:832
	global_load_dwordx4 v[184:187], v255, s[82:83] offset:832
	v_mov_b32_e32 v115, v228
	ds_read2_b32 v[32:33], v115 offset0:0 offset1:1
	ds_read2_b32 v[34:35], v115 offset0:2 offset1:3
	ds_read2_b32 v[36:37], v115 offset0:8 offset1:9
	ds_read2_b32 v[38:39], v115 offset0:10 offset1:11
	ds_read2_b32 v[40:41], v115 offset0:17 offset1:18
	ds_read2_b32 v[42:43], v115 offset0:19 offset1:20
	ds_read2_b32 v[44:45], v115 offset0:25 offset1:26
	ds_read2_b32 v[46:47], v115 offset0:27 offset1:28
	s_waitcnt vmcnt(8)
	ds_write_b128 v247, v[116:119]
	ds_write_b128 v247, v[120:123] offset:1024
	ds_write_b128 v111, v[124:127] offset:2048
	ds_write_b128 v111, v[128:131] offset:3072
	ds_read_b128 v[116:119], v248
	ds_read_b128 v[120:123], v249
	ds_read_b128 v[124:127], v250
	ds_read_b128 v[128:131], v251
	ds_write_b128 v112, v[132:135]
	ds_write_b128 v112, v[136:139] offset:1024
	ds_write_b128 v112, v[140:143] offset:2048
	ds_write_b128 v112, v[144:147] offset:3072
	s_waitcnt lgkmcnt(4)
	v_mfma_f32_32x32x16_bf16 v[32:47], v[116:119], v[48:51], v[32:47]
	v_mfma_f32_32x32x16_bf16 v[32:47], v[120:123], v[52:55], v[32:47]
	v_mfma_f32_32x32x16_bf16 v[32:47], v[124:127], v[56:59], v[32:47]
	v_mfma_f32_32x32x16_bf16 v[32:47], v[128:131], v[60:63], v[32:47]
	ds_read2_b32 v[188:189], v115 offset0:34 offset1:35
	ds_read2_b32 v[190:191], v115 offset0:36 offset1:37
	ds_read2_b32 v[192:193], v115 offset0:42 offset1:43
	ds_read2_b32 v[194:195], v115 offset0:44 offset1:45
	ds_read2_b32 v[196:197], v115 offset0:51 offset1:52
	ds_read2_b32 v[198:199], v115 offset0:53 offset1:54
	ds_read2_b32 v[200:201], v115 offset0:59 offset1:60
	ds_read2_b32 v[202:203], v115 offset0:61 offset1:62
	s_add_i32 s90, s67, 0
	v_add_u32_e32 v80, s90, v235
	v_add_u32_e32 v83, s90, v236
	v_add_u32_e32 v99, s90, v237
	v_add_u32_e32 v253, s90, v238
	v_add_u32_e32 v254, s90, v100
	v_add_u32_e32 v255, s90, v149
	v_med3_i32 v80, v80, 0, s99
	v_med3_i32 v83, v83, 0, s99
	v_med3_i32 v99, v99, 0, s99
	v_med3_i32 v253, v253, 0, s99
	v_med3_i32 v254, v254, 0, s99
	v_med3_i32 v255, v255, 0, s99
	v_mad_u32_u24 v80, v80, s100, v252
	v_mad_u32_u24 v83, v83, s100, v252
	v_mad_u32_u24 v99, v99, s100, v252
	v_mad_u32_u24 v253, v253, s100, v252
	v_mad_u32_u24 v254, v254, s100, v153
	v_mad_u32_u24 v255, v255, s100, v153
	global_load_dwordx4 v[116:119], v80, s[82:83]
	global_load_dwordx4 v[120:123], v83, s[82:83]
	global_load_dwordx4 v[124:127], v99, s[82:83]
	global_load_dwordx4 v[128:131], v253, s[82:83]
	global_load_dwordx4 v[132:135], v254, s[82:83] offset:768
	global_load_dwordx4 v[136:139], v255, s[82:83] offset:768
	global_load_dwordx4 v[140:143], v254, s[82:83] offset:832
	global_load_dwordx4 v[144:147], v255, s[82:83] offset:832
	ds_read_b64_tr_b16 v[72:73], v231
	ds_read_b64_tr_b16 v[74:75], v231 offset:512
	ds_read_b64_tr_b16 v[76:77], v231 offset:2048
	ds_read_b64_tr_b16 v[78:79], v231 offset:2560
	ds_read_b64_tr_b16 v[220:221], v231 offset:1024
	ds_read_b64_tr_b16 v[222:223], v231 offset:1536
	ds_read_b64_tr_b16 v[224:225], v231 offset:3072
	ds_read_b64_tr_b16 v[226:227], v231 offset:3584
	s_waitcnt vmcnt(8)
	ds_write_b128 v247, v[156:159]
	ds_write_b128 v247, v[160:163] offset:1024
	ds_write_b128 v111, v[164:167] offset:2048
	ds_write_b128 v111, v[168:171] offset:3072
	ds_read_b128 v[156:159], v248
	ds_read_b128 v[160:163], v249
	ds_read_b128 v[164:167], v250
	ds_read_b128 v[168:171], v251
	ds_write_b128 v112, v[172:175]
	ds_write_b128 v112, v[176:179] offset:1024
	ds_write_b128 v112, v[180:183] offset:2048
	ds_write_b128 v112, v[184:187] offset:3072
	v_exp_f32_e32 v32, v32
	v_exp_f32_e32 v33, v33
	v_exp_f32_e32 v34, v34
	v_exp_f32_e32 v35, v35
	v_exp_f32_e32 v36, v36
	v_exp_f32_e32 v37, v37
	s_waitcnt lgkmcnt(4)
	v_mfma_f32_32x32x16_bf16 v[188:203], v[156:159], v[48:51], v[188:203]
	v_exp_f32_e32 v38, v38
	v_exp_f32_e32 v39, v39
	v_mfma_f32_32x32x16_bf16 v[188:203], v[160:163], v[52:55], v[188:203]
	v_exp_f32_e32 v40, v40
	v_exp_f32_e32 v41, v41
	v_exp_f32_e32 v42, v42
	v_mfma_f32_32x32x16_bf16 v[188:203], v[164:167], v[56:59], v[188:203]
	v_exp_f32_e32 v43, v43
	v_exp_f32_e32 v44, v44
	v_mfma_f32_32x32x16_bf16 v[188:203], v[168:171], v[60:63], v[188:203]
	v_exp_f32_e32 v45, v45
	v_exp_f32_e32 v46, v46
	v_exp_f32_e32 v47, v47
	s_add_i32 s90, s67, -64
	v_add_u32_e32 v84, s90, v107
	v_add_u32_e32 v85, 0, v84
	v_add_u32_e32 v86, 1, v84
	v_add_u32_e32 v87, 2, v84
	v_add_u32_e32 v88, 3, v84
	v_cmp_gt_u32_e64 s[30:31], s98, v85
	v_cmp_gt_u32_e64 s[36:37], s98, v86
	v_cmp_gt_u32_e64 s[78:79], s98, v87
	v_cmp_gt_u32_e64 s[50:51], s98, v88
	v_cndmask_b32_e64 v32, 0, v32, s[30:31]
	v_add_u32_e32 v85, 8, v84
	v_cmp_gt_u32_e64 s[30:31], s98, v85
	v_cndmask_b32_e64 v33, 0, v33, s[36:37]
	v_add_u32_e32 v86, 9, v84
	v_cmp_gt_u32_e64 s[36:37], s98, v86
	v_cndmask_b32_e64 v34, 0, v34, s[78:79]
	v_add_u32_e32 v87, 10, v84
	v_cmp_gt_u32_e64 s[78:79], s98, v87
	v_cndmask_b32_e64 v35, 0, v35, s[50:51]
	v_add_u32_e32 v88, 11, v84
	v_cmp_gt_u32_e64 s[50:51], s98, v88
	v_cndmask_b32_e64 v36, 0, v36, s[30:31]
	v_add_u32_e32 v85, 16, v84
	v_cmp_gt_u32_e64 s[30:31], s98, v85
	v_cndmask_b32_e64 v37, 0, v37, s[36:37]
	v_add_u32_e32 v86, 17, v84
	v_cmp_gt_u32_e64 s[36:37], s98, v86
	v_cndmask_b32_e64 v38, 0, v38, s[78:79]
	v_add_u32_e32 v87, 18, v84
	v_cmp_gt_u32_e64 s[78:79], s98, v87
	v_cndmask_b32_e64 v39, 0, v39, s[50:51]
	v_add_u32_e32 v88, 19, v84
	v_cmp_gt_u32_e64 s[50:51], s98, v88
	v_cndmask_b32_e64 v40, 0, v40, s[30:31]
	v_add_u32_e32 v85, 24, v84
	v_cmp_gt_u32_e64 s[30:31], s98, v85
	v_cndmask_b32_e64 v41, 0, v41, s[36:37]
	v_add_u32_e32 v86, 25, v84
	v_cmp_gt_u32_e64 s[36:37], s98, v86
	v_cndmask_b32_e64 v42, 0, v42, s[78:79]
	v_add_u32_e32 v87, 26, v84
	v_cmp_gt_u32_e64 s[78:79], s98, v87
	v_cndmask_b32_e64 v43, 0, v43, s[50:51]
	v_add_u32_e32 v88, 27, v84
	v_cmp_gt_u32_e64 s[50:51], s98, v88
	v_nop
	v_cndmask_b32_e64 v44, 0, v44, s[30:31]
	v_cndmask_b32_e64 v45, 0, v45, s[36:37]
	v_cndmask_b32_e64 v46, 0, v46, s[78:79]
	v_cndmask_b32_e64 v47, 0, v47, s[50:51]
	v_cvt_pk_bf16_f32 v64, v32, v33
	v_cvt_pk_bf16_f32 v65, v34, v35
	v_cvt_pk_bf16_f32 v66, v36, v37
	v_cvt_pk_bf16_f32 v67, v38, v39
	v_cvt_pk_bf16_f32 v68, v40, v41
	v_cvt_pk_bf16_f32 v69, v42, v43
	v_cvt_pk_bf16_f32 v70, v44, v45
	v_cvt_pk_bf16_f32 v71, v46, v47
	v_pk_add_f32 v[232:233], v[232:233], v[32:33]
	v_pk_add_f32 v[232:233], v[232:233], v[34:35]
	v_pk_add_f32 v[232:233], v[232:233], v[36:37]
	v_pk_add_f32 v[232:233], v[232:233], v[38:39]
	v_pk_add_f32 v[232:233], v[232:233], v[40:41]
	v_pk_add_f32 v[232:233], v[232:233], v[42:43]
	v_pk_add_f32 v[232:233], v[232:233], v[44:45]
	v_pk_add_f32 v[232:233], v[232:233], v[46:47]
	ds_read2_b32 v[32:33], v115 offset0:68 offset1:69
	ds_read2_b32 v[34:35], v115 offset0:70 offset1:71
	ds_read2_b32 v[36:37], v115 offset0:76 offset1:77
	ds_read2_b32 v[38:39], v115 offset0:78 offset1:79
	ds_read2_b32 v[40:41], v115 offset0:85 offset1:86
	ds_read2_b32 v[42:43], v115 offset0:87 offset1:88
	ds_read2_b32 v[44:45], v115 offset0:93 offset1:94
	ds_read2_b32 v[46:47], v115 offset0:95 offset1:96
	v_mfma_f32_32x32x16_bf16 v[0:15], v[64:67], v[72:75], v[0:15]
	v_mfma_f32_32x32x16_bf16 v[16:31], v[64:67], v[76:79], v[16:31]
	v_mfma_f32_32x32x16_bf16 v[0:15], v[68:71], v[220:223], v[0:15]
	v_mfma_f32_32x32x16_bf16 v[16:31], v[68:71], v[224:227], v[16:31]
	s_add_i32 s90, s67, 32
	v_add_u32_e32 v80, s90, v235
	v_add_u32_e32 v83, s90, v236
	v_add_u32_e32 v99, s90, v237
	v_add_u32_e32 v253, s90, v238
	v_add_u32_e32 v254, s90, v100
	v_add_u32_e32 v255, s90, v149
	v_med3_i32 v80, v80, 0, s99
	v_med3_i32 v83, v83, 0, s99
	v_med3_i32 v99, v99, 0, s99
	v_med3_i32 v253, v253, 0, s99
	v_med3_i32 v254, v254, 0, s99
	v_med3_i32 v255, v255, 0, s99
	v_mad_u32_u24 v80, v80, s100, v252
	v_mad_u32_u24 v83, v83, s100, v252
	v_mad_u32_u24 v99, v99, s100, v252
	v_mad_u32_u24 v253, v253, s100, v252
	v_mad_u32_u24 v254, v254, s100, v153
	v_mad_u32_u24 v255, v255, s100, v153
	global_load_dwordx4 v[156:159], v80, s[82:83]
	global_load_dwordx4 v[160:163], v83, s[82:83]
	global_load_dwordx4 v[164:167], v99, s[82:83]
	global_load_dwordx4 v[168:171], v253, s[82:83]
	global_load_dwordx4 v[172:175], v254, s[82:83] offset:768
	global_load_dwordx4 v[176:179], v255, s[82:83] offset:768
	global_load_dwordx4 v[180:183], v254, s[82:83] offset:832
	global_load_dwordx4 v[184:187], v255, s[82:83] offset:832
	ds_read_b64_tr_b16 v[72:73], v231
	ds_read_b64_tr_b16 v[74:75], v231 offset:512
	ds_read_b64_tr_b16 v[76:77], v231 offset:2048
	ds_read_b64_tr_b16 v[78:79], v231 offset:2560
	ds_read_b64_tr_b16 v[220:221], v231 offset:1024
	ds_read_b64_tr_b16 v[222:223], v231 offset:1536
	ds_read_b64_tr_b16 v[224:225], v231 offset:3072
	ds_read_b64_tr_b16 v[226:227], v231 offset:3584
	s_waitcnt vmcnt(8)
	ds_write_b128 v247, v[116:119]
	ds_write_b128 v247, v[120:123] offset:1024
	ds_write_b128 v111, v[124:127] offset:2048
	ds_write_b128 v111, v[128:131] offset:3072
	ds_read_b128 v[116:119], v248
	ds_read_b128 v[120:123], v249
	ds_read_b128 v[124:127], v250
	ds_read_b128 v[128:131], v251
	ds_write_b128 v112, v[132:135]
	ds_write_b128 v112, v[136:139] offset:1024
	ds_write_b128 v112, v[140:143] offset:2048
	ds_write_b128 v112, v[144:147] offset:3072
	v_exp_f32_e32 v188, v188
	v_exp_f32_e32 v189, v189
	v_exp_f32_e32 v190, v190
	v_exp_f32_e32 v191, v191
	v_exp_f32_e32 v192, v192
	v_exp_f32_e32 v193, v193
	s_waitcnt lgkmcnt(4)
	v_mfma_f32_32x32x16_bf16 v[32:47], v[116:119], v[48:51], v[32:47]
	v_exp_f32_e32 v194, v194
	v_exp_f32_e32 v195, v195
	v_mfma_f32_32x32x16_bf16 v[32:47], v[120:123], v[52:55], v[32:47]
	v_exp_f32_e32 v196, v196
	v_exp_f32_e32 v197, v197
	v_exp_f32_e32 v198, v198
	v_mfma_f32_32x32x16_bf16 v[32:47], v[124:127], v[56:59], v[32:47]
	v_exp_f32_e32 v199, v199
	v_exp_f32_e32 v200, v200
	v_mfma_f32_32x32x16_bf16 v[32:47], v[128:131], v[60:63], v[32:47]
	v_exp_f32_e32 v201, v201
	v_exp_f32_e32 v202, v202
	v_exp_f32_e32 v203, v203
	s_add_i32 s90, s67, -32
	v_add_u32_e32 v84, s90, v107
	v_add_u32_e32 v85, 0, v84
	v_add_u32_e32 v86, 1, v84
	v_add_u32_e32 v87, 2, v84
	v_add_u32_e32 v88, 3, v84
	v_cmp_gt_u32_e64 s[30:31], s98, v85
	v_cmp_gt_u32_e64 s[36:37], s98, v86
	v_cmp_gt_u32_e64 s[78:79], s98, v87
	v_cmp_gt_u32_e64 s[50:51], s98, v88
	v_cndmask_b32_e64 v188, 0, v188, s[30:31]
	v_add_u32_e32 v85, 8, v84
	v_cmp_gt_u32_e64 s[30:31], s98, v85
	v_cndmask_b32_e64 v189, 0, v189, s[36:37]
	v_add_u32_e32 v86, 9, v84
	v_cmp_gt_u32_e64 s[36:37], s98, v86
	v_cndmask_b32_e64 v190, 0, v190, s[78:79]
	v_add_u32_e32 v87, 10, v84
	v_cmp_gt_u32_e64 s[78:79], s98, v87
	v_cndmask_b32_e64 v191, 0, v191, s[50:51]
	v_add_u32_e32 v88, 11, v84
	v_cmp_gt_u32_e64 s[50:51], s98, v88
	v_cndmask_b32_e64 v192, 0, v192, s[30:31]
	v_add_u32_e32 v85, 16, v84
	v_cmp_gt_u32_e64 s[30:31], s98, v85
	v_cndmask_b32_e64 v193, 0, v193, s[36:37]
	v_add_u32_e32 v86, 17, v84
	v_cmp_gt_u32_e64 s[36:37], s98, v86
	v_cndmask_b32_e64 v194, 0, v194, s[78:79]
	v_add_u32_e32 v87, 18, v84
	v_cmp_gt_u32_e64 s[78:79], s98, v87
	v_cndmask_b32_e64 v195, 0, v195, s[50:51]
	v_add_u32_e32 v88, 19, v84
	v_cmp_gt_u32_e64 s[50:51], s98, v88
	v_cndmask_b32_e64 v196, 0, v196, s[30:31]
	v_add_u32_e32 v85, 24, v84
	v_cmp_gt_u32_e64 s[30:31], s98, v85
	v_cndmask_b32_e64 v197, 0, v197, s[36:37]
	v_add_u32_e32 v86, 25, v84
	v_cmp_gt_u32_e64 s[36:37], s98, v86
	v_cndmask_b32_e64 v198, 0, v198, s[78:79]
	v_add_u32_e32 v87, 26, v84
	v_cmp_gt_u32_e64 s[78:79], s98, v87
	v_cndmask_b32_e64 v199, 0, v199, s[50:51]
	v_add_u32_e32 v88, 27, v84
	v_cmp_gt_u32_e64 s[50:51], s98, v88
	v_nop
	v_cndmask_b32_e64 v200, 0, v200, s[30:31]
	v_cndmask_b32_e64 v201, 0, v201, s[36:37]
	v_cndmask_b32_e64 v202, 0, v202, s[78:79]
	v_cndmask_b32_e64 v203, 0, v203, s[50:51]
	v_cvt_pk_bf16_f32 v64, v188, v189
	v_cvt_pk_bf16_f32 v65, v190, v191
	v_cvt_pk_bf16_f32 v66, v192, v193
	v_cvt_pk_bf16_f32 v67, v194, v195
	v_cvt_pk_bf16_f32 v68, v196, v197
	v_cvt_pk_bf16_f32 v69, v198, v199
	v_cvt_pk_bf16_f32 v70, v200, v201
	v_cvt_pk_bf16_f32 v71, v202, v203
	v_pk_add_f32 v[232:233], v[232:233], v[188:189]
	v_pk_add_f32 v[232:233], v[232:233], v[190:191]
	v_pk_add_f32 v[232:233], v[232:233], v[192:193]
	v_pk_add_f32 v[232:233], v[232:233], v[194:195]
	v_pk_add_f32 v[232:233], v[232:233], v[196:197]
	v_pk_add_f32 v[232:233], v[232:233], v[198:199]
	v_pk_add_f32 v[232:233], v[232:233], v[200:201]
	v_pk_add_f32 v[232:233], v[232:233], v[202:203]
	ds_read2_b32 v[188:189], v115 offset0:102 offset1:103
	ds_read2_b32 v[190:191], v115 offset0:104 offset1:105
	ds_read2_b32 v[192:193], v115 offset0:110 offset1:111
	ds_read2_b32 v[194:195], v115 offset0:112 offset1:113
	ds_read2_b32 v[196:197], v115 offset0:119 offset1:120
	ds_read2_b32 v[198:199], v115 offset0:121 offset1:122
	ds_read2_b32 v[200:201], v115 offset0:127 offset1:128
	ds_read2_b32 v[202:203], v115 offset0:129 offset1:130
	v_mfma_f32_32x32x16_bf16 v[0:15], v[64:67], v[72:75], v[0:15]
	v_mfma_f32_32x32x16_bf16 v[16:31], v[64:67], v[76:79], v[16:31]
	v_mfma_f32_32x32x16_bf16 v[0:15], v[68:71], v[220:223], v[0:15]
	v_mfma_f32_32x32x16_bf16 v[16:31], v[68:71], v[224:227], v[16:31]
	s_add_i32 s90, s67, 64
	v_add_u32_e32 v80, s90, v235
	v_add_u32_e32 v83, s90, v236
	v_add_u32_e32 v99, s90, v237
	v_add_u32_e32 v253, s90, v238
	v_add_u32_e32 v254, s90, v100
	v_add_u32_e32 v255, s90, v149
	v_med3_i32 v80, v80, 0, s99
	v_med3_i32 v83, v83, 0, s99
	v_med3_i32 v99, v99, 0, s99
	v_med3_i32 v253, v253, 0, s99
	v_med3_i32 v254, v254, 0, s99
	v_med3_i32 v255, v255, 0, s99
	v_mad_u32_u24 v80, v80, s100, v252
	v_mad_u32_u24 v83, v83, s100, v252
	v_mad_u32_u24 v99, v99, s100, v252
	v_mad_u32_u24 v253, v253, s100, v252
	v_mad_u32_u24 v254, v254, s100, v153
	v_mad_u32_u24 v255, v255, s100, v153
	global_load_dwordx4 v[116:119], v80, s[82:83]
	global_load_dwordx4 v[120:123], v83, s[82:83]
	global_load_dwordx4 v[124:127], v99, s[82:83]
	global_load_dwordx4 v[128:131], v253, s[82:83]
	global_load_dwordx4 v[132:135], v254, s[82:83] offset:768
	global_load_dwordx4 v[136:139], v255, s[82:83] offset:768
	global_load_dwordx4 v[140:143], v254, s[82:83] offset:832
	global_load_dwordx4 v[144:147], v255, s[82:83] offset:832
	ds_read_b64_tr_b16 v[72:73], v231
	ds_read_b64_tr_b16 v[74:75], v231 offset:512
	ds_read_b64_tr_b16 v[76:77], v231 offset:2048
	ds_read_b64_tr_b16 v[78:79], v231 offset:2560
	ds_read_b64_tr_b16 v[220:221], v231 offset:1024
	ds_read_b64_tr_b16 v[222:223], v231 offset:1536
	ds_read_b64_tr_b16 v[224:225], v231 offset:3072
	ds_read_b64_tr_b16 v[226:227], v231 offset:3584
	s_waitcnt vmcnt(8)
	ds_write_b128 v247, v[156:159]
	ds_write_b128 v247, v[160:163] offset:1024
	ds_write_b128 v111, v[164:167] offset:2048
	ds_write_b128 v111, v[168:171] offset:3072
	ds_read_b128 v[156:159], v248
	ds_read_b128 v[160:163], v249
	ds_read_b128 v[164:167], v250
	ds_read_b128 v[168:171], v251
	ds_write_b128 v112, v[172:175]
	ds_write_b128 v112, v[176:179] offset:1024
	ds_write_b128 v112, v[180:183] offset:2048
	ds_write_b128 v112, v[184:187] offset:3072
	v_exp_f32_e32 v32, v32
	v_exp_f32_e32 v33, v33
	v_exp_f32_e32 v34, v34
	v_exp_f32_e32 v35, v35
	v_exp_f32_e32 v36, v36
	v_exp_f32_e32 v37, v37
	s_waitcnt lgkmcnt(4)
	v_mfma_f32_32x32x16_bf16 v[188:203], v[156:159], v[48:51], v[188:203]
	v_exp_f32_e32 v38, v38
	v_exp_f32_e32 v39, v39
	v_mfma_f32_32x32x16_bf16 v[188:203], v[160:163], v[52:55], v[188:203]
	v_exp_f32_e32 v40, v40
	v_exp_f32_e32 v41, v41
	v_exp_f32_e32 v42, v42
	v_mfma_f32_32x32x16_bf16 v[188:203], v[164:167], v[56:59], v[188:203]
	v_exp_f32_e32 v43, v43
	v_exp_f32_e32 v44, v44
	v_mfma_f32_32x32x16_bf16 v[188:203], v[168:171], v[60:63], v[188:203]
	v_exp_f32_e32 v45, v45
	v_exp_f32_e32 v46, v46
	v_exp_f32_e32 v47, v47
	s_add_i32 s90, s67, 0
	v_add_u32_e32 v84, s90, v107
	v_add_u32_e32 v85, 0, v84
	v_add_u32_e32 v86, 1, v84
	v_add_u32_e32 v87, 2, v84
	v_add_u32_e32 v88, 3, v84
	v_cmp_gt_u32_e64 s[30:31], s98, v85
	v_cmp_gt_u32_e64 s[36:37], s98, v86
	v_cmp_gt_u32_e64 s[78:79], s98, v87
	v_cmp_gt_u32_e64 s[50:51], s98, v88
	v_cndmask_b32_e64 v32, 0, v32, s[30:31]
	v_add_u32_e32 v85, 8, v84
	v_cmp_gt_u32_e64 s[30:31], s98, v85
	v_cndmask_b32_e64 v33, 0, v33, s[36:37]
	v_add_u32_e32 v86, 9, v84
	v_cmp_gt_u32_e64 s[36:37], s98, v86
	v_cndmask_b32_e64 v34, 0, v34, s[78:79]
	v_add_u32_e32 v87, 10, v84
	v_cmp_gt_u32_e64 s[78:79], s98, v87
	v_cndmask_b32_e64 v35, 0, v35, s[50:51]
	v_add_u32_e32 v88, 11, v84
	v_cmp_gt_u32_e64 s[50:51], s98, v88
	v_cndmask_b32_e64 v36, 0, v36, s[30:31]
	v_add_u32_e32 v85, 16, v84
	v_cmp_gt_u32_e64 s[30:31], s98, v85
	v_cndmask_b32_e64 v37, 0, v37, s[36:37]
	v_add_u32_e32 v86, 17, v84
	v_cmp_gt_u32_e64 s[36:37], s98, v86
	v_cndmask_b32_e64 v38, 0, v38, s[78:79]
	v_add_u32_e32 v87, 18, v84
	v_cmp_gt_u32_e64 s[78:79], s98, v87
	v_cndmask_b32_e64 v39, 0, v39, s[50:51]
	v_add_u32_e32 v88, 19, v84
	v_cmp_gt_u32_e64 s[50:51], s98, v88
	v_cndmask_b32_e64 v40, 0, v40, s[30:31]
	v_add_u32_e32 v85, 24, v84
	v_cmp_gt_u32_e64 s[30:31], s98, v85
	v_cndmask_b32_e64 v41, 0, v41, s[36:37]
	v_add_u32_e32 v86, 25, v84
	v_cmp_gt_u32_e64 s[36:37], s98, v86
	v_cndmask_b32_e64 v42, 0, v42, s[78:79]
	v_add_u32_e32 v87, 26, v84
	v_cmp_gt_u32_e64 s[78:79], s98, v87
	v_cndmask_b32_e64 v43, 0, v43, s[50:51]
	v_add_u32_e32 v88, 27, v84
	v_cmp_gt_u32_e64 s[50:51], s98, v88
	v_nop
	v_cndmask_b32_e64 v44, 0, v44, s[30:31]
	v_cndmask_b32_e64 v45, 0, v45, s[36:37]
	v_cndmask_b32_e64 v46, 0, v46, s[78:79]
	v_cndmask_b32_e64 v47, 0, v47, s[50:51]
	v_cvt_pk_bf16_f32 v64, v32, v33
	v_cvt_pk_bf16_f32 v65, v34, v35
	v_cvt_pk_bf16_f32 v66, v36, v37
	v_cvt_pk_bf16_f32 v67, v38, v39
	v_cvt_pk_bf16_f32 v68, v40, v41
	v_cvt_pk_bf16_f32 v69, v42, v43
	v_cvt_pk_bf16_f32 v70, v44, v45
	v_cvt_pk_bf16_f32 v71, v46, v47
	v_pk_add_f32 v[232:233], v[232:233], v[32:33]
	v_pk_add_f32 v[232:233], v[232:233], v[34:35]
	v_pk_add_f32 v[232:233], v[232:233], v[36:37]
	v_pk_add_f32 v[232:233], v[232:233], v[38:39]
	v_pk_add_f32 v[232:233], v[232:233], v[40:41]
	v_pk_add_f32 v[232:233], v[232:233], v[42:43]
	v_pk_add_f32 v[232:233], v[232:233], v[44:45]
	v_pk_add_f32 v[232:233], v[232:233], v[46:47]
	ds_read2_b32 v[32:33], v115 offset0:136 offset1:137
	ds_read2_b32 v[34:35], v115 offset0:138 offset1:139
	ds_read2_b32 v[36:37], v115 offset0:144 offset1:145
	ds_read2_b32 v[38:39], v115 offset0:146 offset1:147
	ds_read2_b32 v[40:41], v115 offset0:153 offset1:154
	ds_read2_b32 v[42:43], v115 offset0:155 offset1:156
	ds_read2_b32 v[44:45], v115 offset0:161 offset1:162
	ds_read2_b32 v[46:47], v115 offset0:163 offset1:164
	v_mfma_f32_32x32x16_bf16 v[0:15], v[64:67], v[72:75], v[0:15]
	v_mfma_f32_32x32x16_bf16 v[16:31], v[64:67], v[76:79], v[16:31]
	v_mfma_f32_32x32x16_bf16 v[0:15], v[68:71], v[220:223], v[0:15]
	v_mfma_f32_32x32x16_bf16 v[16:31], v[68:71], v[224:227], v[16:31]
	s_add_i32 s90, s67, 96
	v_add_u32_e32 v80, s90, v235
	v_add_u32_e32 v83, s90, v236
	v_add_u32_e32 v99, s90, v237
	v_add_u32_e32 v253, s90, v238
	v_add_u32_e32 v254, s90, v100
	v_add_u32_e32 v255, s90, v149
	v_med3_i32 v80, v80, 0, s99
	v_med3_i32 v83, v83, 0, s99
	v_med3_i32 v99, v99, 0, s99
	v_med3_i32 v253, v253, 0, s99
	v_med3_i32 v254, v254, 0, s99
	v_med3_i32 v255, v255, 0, s99
	v_mad_u32_u24 v80, v80, s100, v252
	v_mad_u32_u24 v83, v83, s100, v252
	v_mad_u32_u24 v99, v99, s100, v252
	v_mad_u32_u24 v253, v253, s100, v252
	v_mad_u32_u24 v254, v254, s100, v153
	v_mad_u32_u24 v255, v255, s100, v153
	global_load_dwordx4 v[156:159], v80, s[82:83]
	global_load_dwordx4 v[160:163], v83, s[82:83]
	global_load_dwordx4 v[164:167], v99, s[82:83]
	global_load_dwordx4 v[168:171], v253, s[82:83]
	global_load_dwordx4 v[172:175], v254, s[82:83] offset:768
	global_load_dwordx4 v[176:179], v255, s[82:83] offset:768
	global_load_dwordx4 v[180:183], v254, s[82:83] offset:832
	global_load_dwordx4 v[184:187], v255, s[82:83] offset:832
	ds_read_b64_tr_b16 v[72:73], v231
	ds_read_b64_tr_b16 v[74:75], v231 offset:512
	ds_read_b64_tr_b16 v[76:77], v231 offset:2048
	ds_read_b64_tr_b16 v[78:79], v231 offset:2560
	ds_read_b64_tr_b16 v[220:221], v231 offset:1024
	ds_read_b64_tr_b16 v[222:223], v231 offset:1536
	ds_read_b64_tr_b16 v[224:225], v231 offset:3072
	ds_read_b64_tr_b16 v[226:227], v231 offset:3584
	s_waitcnt vmcnt(8)
	ds_write_b128 v247, v[116:119]
	ds_write_b128 v247, v[120:123] offset:1024
	ds_write_b128 v111, v[124:127] offset:2048
	ds_write_b128 v111, v[128:131] offset:3072
	ds_read_b128 v[116:119], v248
	ds_read_b128 v[120:123], v249
	ds_read_b128 v[124:127], v250
	ds_read_b128 v[128:131], v251
	ds_write_b128 v112, v[132:135]
	ds_write_b128 v112, v[136:139] offset:1024
	ds_write_b128 v112, v[140:143] offset:2048
	ds_write_b128 v112, v[144:147] offset:3072
	v_exp_f32_e32 v188, v188
	v_exp_f32_e32 v189, v189
	v_exp_f32_e32 v190, v190
	v_exp_f32_e32 v191, v191
	v_exp_f32_e32 v192, v192
	v_exp_f32_e32 v193, v193
	s_waitcnt lgkmcnt(4)
	v_mfma_f32_32x32x16_bf16 v[32:47], v[116:119], v[48:51], v[32:47]
	v_exp_f32_e32 v194, v194
	v_exp_f32_e32 v195, v195
	v_mfma_f32_32x32x16_bf16 v[32:47], v[120:123], v[52:55], v[32:47]
	v_exp_f32_e32 v196, v196
	v_exp_f32_e32 v197, v197
	v_exp_f32_e32 v198, v198
	v_mfma_f32_32x32x16_bf16 v[32:47], v[124:127], v[56:59], v[32:47]
	v_exp_f32_e32 v199, v199
	v_exp_f32_e32 v200, v200
	v_mfma_f32_32x32x16_bf16 v[32:47], v[128:131], v[60:63], v[32:47]
	v_exp_f32_e32 v201, v201
	v_exp_f32_e32 v202, v202
	v_exp_f32_e32 v203, v203
	s_add_i32 s90, s67, 32
	v_add_u32_e32 v84, s90, v107
	v_add_u32_e32 v85, 0, v84
	v_add_u32_e32 v86, 1, v84
	v_add_u32_e32 v87, 2, v84
	v_add_u32_e32 v88, 3, v84
	v_cmp_gt_u32_e64 s[30:31], s98, v85
	v_cmp_gt_u32_e64 s[36:37], s98, v86
	v_cmp_gt_u32_e64 s[78:79], s98, v87
	v_cmp_gt_u32_e64 s[50:51], s98, v88
	v_cndmask_b32_e64 v188, 0, v188, s[30:31]
	v_add_u32_e32 v85, 8, v84
	v_cmp_gt_u32_e64 s[30:31], s98, v85
	v_cndmask_b32_e64 v189, 0, v189, s[36:37]
	v_add_u32_e32 v86, 9, v84
	v_cmp_gt_u32_e64 s[36:37], s98, v86
	v_cndmask_b32_e64 v190, 0, v190, s[78:79]
	v_add_u32_e32 v87, 10, v84
	v_cmp_gt_u32_e64 s[78:79], s98, v87
	v_cndmask_b32_e64 v191, 0, v191, s[50:51]
	v_add_u32_e32 v88, 11, v84
	v_cmp_gt_u32_e64 s[50:51], s98, v88
	v_cndmask_b32_e64 v192, 0, v192, s[30:31]
	v_add_u32_e32 v85, 16, v84
	v_cmp_gt_u32_e64 s[30:31], s98, v85
	v_cndmask_b32_e64 v193, 0, v193, s[36:37]
	v_add_u32_e32 v86, 17, v84
	v_cmp_gt_u32_e64 s[36:37], s98, v86
	v_cndmask_b32_e64 v194, 0, v194, s[78:79]
	v_add_u32_e32 v87, 18, v84
	v_cmp_gt_u32_e64 s[78:79], s98, v87
	v_cndmask_b32_e64 v195, 0, v195, s[50:51]
	v_add_u32_e32 v88, 19, v84
	v_cmp_gt_u32_e64 s[50:51], s98, v88
	v_cndmask_b32_e64 v196, 0, v196, s[30:31]
	v_add_u32_e32 v85, 24, v84
	v_cmp_gt_u32_e64 s[30:31], s98, v85
	v_cndmask_b32_e64 v197, 0, v197, s[36:37]
	v_add_u32_e32 v86, 25, v84
	v_cmp_gt_u32_e64 s[36:37], s98, v86
	v_cndmask_b32_e64 v198, 0, v198, s[78:79]
	v_add_u32_e32 v87, 26, v84
	v_cmp_gt_u32_e64 s[78:79], s98, v87
	v_cndmask_b32_e64 v199, 0, v199, s[50:51]
	v_add_u32_e32 v88, 27, v84
	v_cmp_gt_u32_e64 s[50:51], s98, v88
	v_nop
	v_cndmask_b32_e64 v200, 0, v200, s[30:31]
	v_cndmask_b32_e64 v201, 0, v201, s[36:37]
	v_cndmask_b32_e64 v202, 0, v202, s[78:79]
	v_cndmask_b32_e64 v203, 0, v203, s[50:51]
	v_cvt_pk_bf16_f32 v64, v188, v189
	v_cvt_pk_bf16_f32 v65, v190, v191
	v_cvt_pk_bf16_f32 v66, v192, v193
	v_cvt_pk_bf16_f32 v67, v194, v195
	v_cvt_pk_bf16_f32 v68, v196, v197
	v_cvt_pk_bf16_f32 v69, v198, v199
	v_cvt_pk_bf16_f32 v70, v200, v201
	v_cvt_pk_bf16_f32 v71, v202, v203
	v_pk_add_f32 v[232:233], v[232:233], v[188:189]
	v_pk_add_f32 v[232:233], v[232:233], v[190:191]
	v_pk_add_f32 v[232:233], v[232:233], v[192:193]
	v_pk_add_f32 v[232:233], v[232:233], v[194:195]
	v_pk_add_f32 v[232:233], v[232:233], v[196:197]
	v_pk_add_f32 v[232:233], v[232:233], v[198:199]
	v_pk_add_f32 v[232:233], v[232:233], v[200:201]
	v_pk_add_f32 v[232:233], v[232:233], v[202:203]
	ds_read2_b32 v[188:189], v115 offset0:170 offset1:171
	ds_read2_b32 v[190:191], v115 offset0:172 offset1:173
	ds_read2_b32 v[192:193], v115 offset0:178 offset1:179
	ds_read2_b32 v[194:195], v115 offset0:180 offset1:181
	ds_read2_b32 v[196:197], v115 offset0:187 offset1:188
	ds_read2_b32 v[198:199], v115 offset0:189 offset1:190
	ds_read2_b32 v[200:201], v115 offset0:195 offset1:196
	ds_read2_b32 v[202:203], v115 offset0:197 offset1:198
	v_mfma_f32_32x32x16_bf16 v[0:15], v[64:67], v[72:75], v[0:15]
	v_mfma_f32_32x32x16_bf16 v[16:31], v[64:67], v[76:79], v[16:31]
	v_mfma_f32_32x32x16_bf16 v[0:15], v[68:71], v[220:223], v[0:15]
	v_mfma_f32_32x32x16_bf16 v[16:31], v[68:71], v[224:227], v[16:31]
	s_add_i32 s90, s67, 128
	v_add_u32_e32 v80, s90, v235
	v_add_u32_e32 v83, s90, v236
	v_add_u32_e32 v99, s90, v237
	v_add_u32_e32 v253, s90, v238
	v_add_u32_e32 v254, s90, v100
	v_add_u32_e32 v255, s90, v149
	v_med3_i32 v80, v80, 0, s99
	v_med3_i32 v83, v83, 0, s99
	v_med3_i32 v99, v99, 0, s99
	v_med3_i32 v253, v253, 0, s99
	v_med3_i32 v254, v254, 0, s99
	v_med3_i32 v255, v255, 0, s99
	v_mad_u32_u24 v80, v80, s100, v252
	v_mad_u32_u24 v83, v83, s100, v252
	v_mad_u32_u24 v99, v99, s100, v252
	v_mad_u32_u24 v253, v253, s100, v252
	v_mad_u32_u24 v254, v254, s100, v153
	v_mad_u32_u24 v255, v255, s100, v153
	global_load_dwordx4 v[116:119], v80, s[82:83]
	global_load_dwordx4 v[120:123], v83, s[82:83]
	global_load_dwordx4 v[124:127], v99, s[82:83]
	global_load_dwordx4 v[128:131], v253, s[82:83]
	global_load_dwordx4 v[132:135], v254, s[82:83] offset:768
	global_load_dwordx4 v[136:139], v255, s[82:83] offset:768
	global_load_dwordx4 v[140:143], v254, s[82:83] offset:832
	global_load_dwordx4 v[144:147], v255, s[82:83] offset:832
	ds_read_b64_tr_b16 v[72:73], v231
	ds_read_b64_tr_b16 v[74:75], v231 offset:512
	ds_read_b64_tr_b16 v[76:77], v231 offset:2048
	ds_read_b64_tr_b16 v[78:79], v231 offset:2560
	ds_read_b64_tr_b16 v[220:221], v231 offset:1024
	ds_read_b64_tr_b16 v[222:223], v231 offset:1536
	ds_read_b64_tr_b16 v[224:225], v231 offset:3072
	ds_read_b64_tr_b16 v[226:227], v231 offset:3584
	s_waitcnt vmcnt(8)
	ds_write_b128 v247, v[156:159]
	ds_write_b128 v247, v[160:163] offset:1024
	ds_write_b128 v111, v[164:167] offset:2048
	ds_write_b128 v111, v[168:171] offset:3072
	ds_read_b128 v[156:159], v248
	ds_read_b128 v[160:163], v249
	ds_read_b128 v[164:167], v250
	ds_read_b128 v[168:171], v251
	ds_write_b128 v112, v[172:175]
	ds_write_b128 v112, v[176:179] offset:1024
	ds_write_b128 v112, v[180:183] offset:2048
	ds_write_b128 v112, v[184:187] offset:3072
	v_exp_f32_e32 v32, v32
	v_exp_f32_e32 v33, v33
	v_exp_f32_e32 v34, v34
	v_exp_f32_e32 v35, v35
	v_exp_f32_e32 v36, v36
	v_exp_f32_e32 v37, v37
	s_waitcnt lgkmcnt(4)
	v_mfma_f32_32x32x16_bf16 v[188:203], v[156:159], v[48:51], v[188:203]
	v_exp_f32_e32 v38, v38
	v_exp_f32_e32 v39, v39
	v_mfma_f32_32x32x16_bf16 v[188:203], v[160:163], v[52:55], v[188:203]
	v_exp_f32_e32 v40, v40
	v_exp_f32_e32 v41, v41
	v_exp_f32_e32 v42, v42
	v_mfma_f32_32x32x16_bf16 v[188:203], v[164:167], v[56:59], v[188:203]
	v_exp_f32_e32 v43, v43
	v_exp_f32_e32 v44, v44
	v_mfma_f32_32x32x16_bf16 v[188:203], v[168:171], v[60:63], v[188:203]
	v_exp_f32_e32 v45, v45
	v_exp_f32_e32 v46, v46
	v_exp_f32_e32 v47, v47
	s_add_i32 s90, s67, 64
	v_add_u32_e32 v84, s90, v107
	v_add_u32_e32 v85, 0, v84
	v_add_u32_e32 v86, 1, v84
	v_add_u32_e32 v87, 2, v84
	v_add_u32_e32 v88, 3, v84
	v_cmp_gt_u32_e64 s[30:31], s98, v85
	v_cmp_gt_u32_e64 s[36:37], s98, v86
	v_cmp_gt_u32_e64 s[78:79], s98, v87
	v_cmp_gt_u32_e64 s[50:51], s98, v88
	v_cndmask_b32_e64 v32, 0, v32, s[30:31]
	v_add_u32_e32 v85, 8, v84
	v_cmp_gt_u32_e64 s[30:31], s98, v85
	v_cndmask_b32_e64 v33, 0, v33, s[36:37]
	v_add_u32_e32 v86, 9, v84
	v_cmp_gt_u32_e64 s[36:37], s98, v86
	v_cndmask_b32_e64 v34, 0, v34, s[78:79]
	v_add_u32_e32 v87, 10, v84
	v_cmp_gt_u32_e64 s[78:79], s98, v87
	v_cndmask_b32_e64 v35, 0, v35, s[50:51]
	v_add_u32_e32 v88, 11, v84
	v_cmp_gt_u32_e64 s[50:51], s98, v88
	v_cndmask_b32_e64 v36, 0, v36, s[30:31]
	v_add_u32_e32 v85, 16, v84
	v_cmp_gt_u32_e64 s[30:31], s98, v85
	v_cndmask_b32_e64 v37, 0, v37, s[36:37]
	v_add_u32_e32 v86, 17, v84
	v_cmp_gt_u32_e64 s[36:37], s98, v86
	v_cndmask_b32_e64 v38, 0, v38, s[78:79]
	v_add_u32_e32 v87, 18, v84
	v_cmp_gt_u32_e64 s[78:79], s98, v87
	v_cndmask_b32_e64 v39, 0, v39, s[50:51]
	v_add_u32_e32 v88, 19, v84
	v_cmp_gt_u32_e64 s[50:51], s98, v88
	v_cndmask_b32_e64 v40, 0, v40, s[30:31]
	v_add_u32_e32 v85, 24, v84
	v_cmp_gt_u32_e64 s[30:31], s98, v85
	v_cndmask_b32_e64 v41, 0, v41, s[36:37]
	v_add_u32_e32 v86, 25, v84
	v_cmp_gt_u32_e64 s[36:37], s98, v86
	v_cndmask_b32_e64 v42, 0, v42, s[78:79]
	v_add_u32_e32 v87, 26, v84
	v_cmp_gt_u32_e64 s[78:79], s98, v87
	v_cndmask_b32_e64 v43, 0, v43, s[50:51]
	v_add_u32_e32 v88, 27, v84
	v_cmp_gt_u32_e64 s[50:51], s98, v88
	v_nop
	v_cndmask_b32_e64 v44, 0, v44, s[30:31]
	v_cndmask_b32_e64 v45, 0, v45, s[36:37]
	v_cndmask_b32_e64 v46, 0, v46, s[78:79]
	v_cndmask_b32_e64 v47, 0, v47, s[50:51]
	v_cvt_pk_bf16_f32 v64, v32, v33
	v_cvt_pk_bf16_f32 v65, v34, v35
	v_cvt_pk_bf16_f32 v66, v36, v37
	v_cvt_pk_bf16_f32 v67, v38, v39
	v_cvt_pk_bf16_f32 v68, v40, v41
	v_cvt_pk_bf16_f32 v69, v42, v43
	v_cvt_pk_bf16_f32 v70, v44, v45
	v_cvt_pk_bf16_f32 v71, v46, v47
	v_pk_add_f32 v[232:233], v[232:233], v[32:33]
	v_pk_add_f32 v[232:233], v[232:233], v[34:35]
	v_pk_add_f32 v[232:233], v[232:233], v[36:37]
	v_pk_add_f32 v[232:233], v[232:233], v[38:39]
	v_pk_add_f32 v[232:233], v[232:233], v[40:41]
	v_pk_add_f32 v[232:233], v[232:233], v[42:43]
	v_pk_add_f32 v[232:233], v[232:233], v[44:45]
	v_pk_add_f32 v[232:233], v[232:233], v[46:47]
	ds_read2_b32 v[32:33], v115 offset0:204 offset1:205
	ds_read2_b32 v[34:35], v115 offset0:206 offset1:207
	ds_read2_b32 v[36:37], v115 offset0:212 offset1:213
	ds_read2_b32 v[38:39], v115 offset0:214 offset1:215
	ds_read2_b32 v[40:41], v115 offset0:221 offset1:222
	ds_read2_b32 v[42:43], v115 offset0:223 offset1:224
	ds_read2_b32 v[44:45], v115 offset0:229 offset1:230
	ds_read2_b32 v[46:47], v115 offset0:231 offset1:232
	v_mfma_f32_32x32x16_bf16 v[0:15], v[64:67], v[72:75], v[0:15]
	v_mfma_f32_32x32x16_bf16 v[16:31], v[64:67], v[76:79], v[16:31]
	v_mfma_f32_32x32x16_bf16 v[0:15], v[68:71], v[220:223], v[0:15]
	v_mfma_f32_32x32x16_bf16 v[16:31], v[68:71], v[224:227], v[16:31]
	s_add_i32 s90, s67, 160
	v_add_u32_e32 v80, s90, v235
	v_add_u32_e32 v83, s90, v236
	v_add_u32_e32 v99, s90, v237
	v_add_u32_e32 v253, s90, v238
	v_add_u32_e32 v254, s90, v100
	v_add_u32_e32 v255, s90, v149
	v_med3_i32 v80, v80, 0, s99
	v_med3_i32 v83, v83, 0, s99
	v_med3_i32 v99, v99, 0, s99
	v_med3_i32 v253, v253, 0, s99
	v_med3_i32 v254, v254, 0, s99
	v_med3_i32 v255, v255, 0, s99
	v_mad_u32_u24 v80, v80, s100, v252
	v_mad_u32_u24 v83, v83, s100, v252
	v_mad_u32_u24 v99, v99, s100, v252
	v_mad_u32_u24 v253, v253, s100, v252
	v_mad_u32_u24 v254, v254, s100, v153
	v_mad_u32_u24 v255, v255, s100, v153
	global_load_dwordx4 v[156:159], v80, s[82:83]
	global_load_dwordx4 v[160:163], v83, s[82:83]
	global_load_dwordx4 v[164:167], v99, s[82:83]
	global_load_dwordx4 v[168:171], v253, s[82:83]
	global_load_dwordx4 v[172:175], v254, s[82:83] offset:768
	global_load_dwordx4 v[176:179], v255, s[82:83] offset:768
	global_load_dwordx4 v[180:183], v254, s[82:83] offset:832
	global_load_dwordx4 v[184:187], v255, s[82:83] offset:832
	ds_read_b64_tr_b16 v[72:73], v231
	ds_read_b64_tr_b16 v[74:75], v231 offset:512
	ds_read_b64_tr_b16 v[76:77], v231 offset:2048
	ds_read_b64_tr_b16 v[78:79], v231 offset:2560
	ds_read_b64_tr_b16 v[220:221], v231 offset:1024
	ds_read_b64_tr_b16 v[222:223], v231 offset:1536
	ds_read_b64_tr_b16 v[224:225], v231 offset:3072
	ds_read_b64_tr_b16 v[226:227], v231 offset:3584
	s_waitcnt vmcnt(8)
	ds_write_b128 v247, v[116:119]
	ds_write_b128 v247, v[120:123] offset:1024
	ds_write_b128 v111, v[124:127] offset:2048
	ds_write_b128 v111, v[128:131] offset:3072
	ds_read_b128 v[116:119], v248
	ds_read_b128 v[120:123], v249
	ds_read_b128 v[124:127], v250
	ds_read_b128 v[128:131], v251
	ds_write_b128 v112, v[132:135]
	ds_write_b128 v112, v[136:139] offset:1024
	ds_write_b128 v112, v[140:143] offset:2048
	ds_write_b128 v112, v[144:147] offset:3072
	v_exp_f32_e32 v188, v188
	v_exp_f32_e32 v189, v189
	v_exp_f32_e32 v190, v190
	v_exp_f32_e32 v191, v191
	v_exp_f32_e32 v192, v192
	v_exp_f32_e32 v193, v193
	s_waitcnt lgkmcnt(4)
	v_mfma_f32_32x32x16_bf16 v[32:47], v[116:119], v[48:51], v[32:47]
	v_exp_f32_e32 v194, v194
	v_exp_f32_e32 v195, v195
	v_mfma_f32_32x32x16_bf16 v[32:47], v[120:123], v[52:55], v[32:47]
	v_exp_f32_e32 v196, v196
	v_exp_f32_e32 v197, v197
	v_exp_f32_e32 v198, v198
	v_mfma_f32_32x32x16_bf16 v[32:47], v[124:127], v[56:59], v[32:47]
	v_exp_f32_e32 v199, v199
	v_exp_f32_e32 v200, v200
	v_mfma_f32_32x32x16_bf16 v[32:47], v[128:131], v[60:63], v[32:47]
	v_exp_f32_e32 v201, v201
	v_exp_f32_e32 v202, v202
	v_exp_f32_e32 v203, v203
	s_add_i32 s90, s67, 96
	v_add_u32_e32 v84, s90, v107
	v_add_u32_e32 v85, 0, v84
	v_add_u32_e32 v86, 1, v84
	v_add_u32_e32 v87, 2, v84
	v_add_u32_e32 v88, 3, v84
	v_cmp_gt_u32_e64 s[30:31], s98, v85
	v_cmp_gt_u32_e64 s[36:37], s98, v86
	v_cmp_gt_u32_e64 s[78:79], s98, v87
	v_cmp_gt_u32_e64 s[50:51], s98, v88
	v_cndmask_b32_e64 v188, 0, v188, s[30:31]
	v_add_u32_e32 v85, 8, v84
	v_cmp_gt_u32_e64 s[30:31], s98, v85
	v_cndmask_b32_e64 v189, 0, v189, s[36:37]
	v_add_u32_e32 v86, 9, v84
	v_cmp_gt_u32_e64 s[36:37], s98, v86
	v_cndmask_b32_e64 v190, 0, v190, s[78:79]
	v_add_u32_e32 v87, 10, v84
	v_cmp_gt_u32_e64 s[78:79], s98, v87
	v_cndmask_b32_e64 v191, 0, v191, s[50:51]
	v_add_u32_e32 v88, 11, v84
	v_cmp_gt_u32_e64 s[50:51], s98, v88
	v_cndmask_b32_e64 v192, 0, v192, s[30:31]
	v_add_u32_e32 v85, 16, v84
	v_cmp_gt_u32_e64 s[30:31], s98, v85
	v_cndmask_b32_e64 v193, 0, v193, s[36:37]
	v_add_u32_e32 v86, 17, v84
	v_cmp_gt_u32_e64 s[36:37], s98, v86
	v_cndmask_b32_e64 v194, 0, v194, s[78:79]
	v_add_u32_e32 v87, 18, v84
	v_cmp_gt_u32_e64 s[78:79], s98, v87
	v_cndmask_b32_e64 v195, 0, v195, s[50:51]
	v_add_u32_e32 v88, 19, v84
	v_cmp_gt_u32_e64 s[50:51], s98, v88
	v_cndmask_b32_e64 v196, 0, v196, s[30:31]
	v_add_u32_e32 v85, 24, v84
	v_cmp_gt_u32_e64 s[30:31], s98, v85
	v_cndmask_b32_e64 v197, 0, v197, s[36:37]
	v_add_u32_e32 v86, 25, v84
	v_cmp_gt_u32_e64 s[36:37], s98, v86
	v_cndmask_b32_e64 v198, 0, v198, s[78:79]
	v_add_u32_e32 v87, 26, v84
	v_cmp_gt_u32_e64 s[78:79], s98, v87
	v_cndmask_b32_e64 v199, 0, v199, s[50:51]
	v_add_u32_e32 v88, 27, v84
	v_cmp_gt_u32_e64 s[50:51], s98, v88
	v_nop
	v_cndmask_b32_e64 v200, 0, v200, s[30:31]
	v_cndmask_b32_e64 v201, 0, v201, s[36:37]
	v_cndmask_b32_e64 v202, 0, v202, s[78:79]
	v_cndmask_b32_e64 v203, 0, v203, s[50:51]
	v_cvt_pk_bf16_f32 v64, v188, v189
	v_cvt_pk_bf16_f32 v65, v190, v191
	v_cvt_pk_bf16_f32 v66, v192, v193
	v_cvt_pk_bf16_f32 v67, v194, v195
	v_cvt_pk_bf16_f32 v68, v196, v197
	v_cvt_pk_bf16_f32 v69, v198, v199
	v_cvt_pk_bf16_f32 v70, v200, v201
	v_cvt_pk_bf16_f32 v71, v202, v203
	v_pk_add_f32 v[232:233], v[232:233], v[188:189]
	v_pk_add_f32 v[232:233], v[232:233], v[190:191]
	v_pk_add_f32 v[232:233], v[232:233], v[192:193]
	v_pk_add_f32 v[232:233], v[232:233], v[194:195]
	v_pk_add_f32 v[232:233], v[232:233], v[196:197]
	v_pk_add_f32 v[232:233], v[232:233], v[198:199]
	v_pk_add_f32 v[232:233], v[232:233], v[200:201]
	v_pk_add_f32 v[232:233], v[232:233], v[202:203]
	v_add_u32_e32 v115, 952, v115
	ds_read2_b32 v[188:189], v115 offset0:0 offset1:1
	ds_read2_b32 v[190:191], v115 offset0:2 offset1:3
	ds_read2_b32 v[192:193], v115 offset0:8 offset1:9
	ds_read2_b32 v[194:195], v115 offset0:10 offset1:11
	ds_read2_b32 v[196:197], v115 offset0:17 offset1:18
	ds_read2_b32 v[198:199], v115 offset0:19 offset1:20
	ds_read2_b32 v[200:201], v115 offset0:25 offset1:26
	ds_read2_b32 v[202:203], v115 offset0:27 offset1:28
	v_mfma_f32_32x32x16_bf16 v[0:15], v[64:67], v[72:75], v[0:15]
	v_mfma_f32_32x32x16_bf16 v[16:31], v[64:67], v[76:79], v[16:31]
	v_mfma_f32_32x32x16_bf16 v[0:15], v[68:71], v[220:223], v[0:15]
	v_mfma_f32_32x32x16_bf16 v[16:31], v[68:71], v[224:227], v[16:31]
	s_add_i32 s90, s67, 192
	v_add_u32_e32 v80, s90, v235
	v_add_u32_e32 v83, s90, v236
	v_add_u32_e32 v99, s90, v237
	v_add_u32_e32 v253, s90, v238
	v_add_u32_e32 v254, s90, v100
	v_add_u32_e32 v255, s90, v149
	v_med3_i32 v80, v80, 0, s99
	v_med3_i32 v83, v83, 0, s99
	v_med3_i32 v99, v99, 0, s99
	v_med3_i32 v253, v253, 0, s99
	v_med3_i32 v254, v254, 0, s99
	v_med3_i32 v255, v255, 0, s99
	v_mad_u32_u24 v80, v80, s100, v252
	v_mad_u32_u24 v83, v83, s100, v252
	v_mad_u32_u24 v99, v99, s100, v252
	v_mad_u32_u24 v253, v253, s100, v252
	v_mad_u32_u24 v254, v254, s100, v153
	v_mad_u32_u24 v255, v255, s100, v153
	global_load_dwordx4 v[116:119], v80, s[82:83]
	global_load_dwordx4 v[120:123], v83, s[82:83]
	global_load_dwordx4 v[124:127], v99, s[82:83]
	global_load_dwordx4 v[128:131], v253, s[82:83]
	global_load_dwordx4 v[132:135], v254, s[82:83] offset:768
	global_load_dwordx4 v[136:139], v255, s[82:83] offset:768
	global_load_dwordx4 v[140:143], v254, s[82:83] offset:832
	global_load_dwordx4 v[144:147], v255, s[82:83] offset:832
	ds_read_b64_tr_b16 v[72:73], v231
	ds_read_b64_tr_b16 v[74:75], v231 offset:512
	ds_read_b64_tr_b16 v[76:77], v231 offset:2048
	ds_read_b64_tr_b16 v[78:79], v231 offset:2560
	ds_read_b64_tr_b16 v[220:221], v231 offset:1024
	ds_read_b64_tr_b16 v[222:223], v231 offset:1536
	ds_read_b64_tr_b16 v[224:225], v231 offset:3072
	ds_read_b64_tr_b16 v[226:227], v231 offset:3584
	s_waitcnt vmcnt(8)
	ds_write_b128 v247, v[156:159]
	ds_write_b128 v247, v[160:163] offset:1024
	ds_write_b128 v111, v[164:167] offset:2048
	ds_write_b128 v111, v[168:171] offset:3072
	ds_read_b128 v[156:159], v248
	ds_read_b128 v[160:163], v249
	ds_read_b128 v[164:167], v250
	ds_read_b128 v[168:171], v251
	ds_write_b128 v112, v[172:175]
	ds_write_b128 v112, v[176:179] offset:1024
	ds_write_b128 v112, v[180:183] offset:2048
	ds_write_b128 v112, v[184:187] offset:3072
	v_exp_f32_e32 v32, v32
	v_exp_f32_e32 v33, v33
	v_exp_f32_e32 v34, v34
	v_exp_f32_e32 v35, v35
	v_exp_f32_e32 v36, v36
	v_exp_f32_e32 v37, v37
	s_waitcnt lgkmcnt(4)
	v_mfma_f32_32x32x16_bf16 v[188:203], v[156:159], v[48:51], v[188:203]
	v_exp_f32_e32 v38, v38
	v_exp_f32_e32 v39, v39
	v_mfma_f32_32x32x16_bf16 v[188:203], v[160:163], v[52:55], v[188:203]
	v_exp_f32_e32 v40, v40
	v_exp_f32_e32 v41, v41
	v_exp_f32_e32 v42, v42
	v_mfma_f32_32x32x16_bf16 v[188:203], v[164:167], v[56:59], v[188:203]
	v_exp_f32_e32 v43, v43
	v_exp_f32_e32 v44, v44
	v_mfma_f32_32x32x16_bf16 v[188:203], v[168:171], v[60:63], v[188:203]
	v_exp_f32_e32 v45, v45
	v_exp_f32_e32 v46, v46
	v_exp_f32_e32 v47, v47
	s_add_i32 s90, s67, 128
	v_add_u32_e32 v84, s90, v107
	v_add_u32_e32 v85, 0, v84
	v_add_u32_e32 v86, 1, v84
	v_add_u32_e32 v87, 2, v84
	v_add_u32_e32 v88, 3, v84
	v_cmp_gt_u32_e64 s[30:31], s98, v85
	v_cmp_gt_u32_e64 s[36:37], s98, v86
	v_cmp_gt_u32_e64 s[78:79], s98, v87
	v_cmp_gt_u32_e64 s[50:51], s98, v88
	v_cndmask_b32_e64 v32, 0, v32, s[30:31]
	v_add_u32_e32 v85, 8, v84
	v_cmp_gt_u32_e64 s[30:31], s98, v85
	v_cndmask_b32_e64 v33, 0, v33, s[36:37]
	v_add_u32_e32 v86, 9, v84
	v_cmp_gt_u32_e64 s[36:37], s98, v86
	v_cndmask_b32_e64 v34, 0, v34, s[78:79]
	v_add_u32_e32 v87, 10, v84
	v_cmp_gt_u32_e64 s[78:79], s98, v87
	v_cndmask_b32_e64 v35, 0, v35, s[50:51]
	v_add_u32_e32 v88, 11, v84
	v_cmp_gt_u32_e64 s[50:51], s98, v88
	v_cndmask_b32_e64 v36, 0, v36, s[30:31]
	v_add_u32_e32 v85, 16, v84
	v_cmp_gt_u32_e64 s[30:31], s98, v85
	v_cndmask_b32_e64 v37, 0, v37, s[36:37]
	v_add_u32_e32 v86, 17, v84
	v_cmp_gt_u32_e64 s[36:37], s98, v86
	v_cndmask_b32_e64 v38, 0, v38, s[78:79]
	v_add_u32_e32 v87, 18, v84
	v_cmp_gt_u32_e64 s[78:79], s98, v87
	v_cndmask_b32_e64 v39, 0, v39, s[50:51]
	v_add_u32_e32 v88, 19, v84
	v_cmp_gt_u32_e64 s[50:51], s98, v88
	v_cndmask_b32_e64 v40, 0, v40, s[30:31]
	v_add_u32_e32 v85, 24, v84
	v_cmp_gt_u32_e64 s[30:31], s98, v85
	v_cndmask_b32_e64 v41, 0, v41, s[36:37]
	v_add_u32_e32 v86, 25, v84
	v_cmp_gt_u32_e64 s[36:37], s98, v86
	v_cndmask_b32_e64 v42, 0, v42, s[78:79]
	v_add_u32_e32 v87, 26, v84
	v_cmp_gt_u32_e64 s[78:79], s98, v87
	v_cndmask_b32_e64 v43, 0, v43, s[50:51]
	v_add_u32_e32 v88, 27, v84
	v_cmp_gt_u32_e64 s[50:51], s98, v88
	v_nop
	v_cndmask_b32_e64 v44, 0, v44, s[30:31]
	v_cndmask_b32_e64 v45, 0, v45, s[36:37]
	v_cndmask_b32_e64 v46, 0, v46, s[78:79]
	v_cndmask_b32_e64 v47, 0, v47, s[50:51]
	v_cvt_pk_bf16_f32 v64, v32, v33
	v_cvt_pk_bf16_f32 v65, v34, v35
	v_cvt_pk_bf16_f32 v66, v36, v37
	v_cvt_pk_bf16_f32 v67, v38, v39
	v_cvt_pk_bf16_f32 v68, v40, v41
	v_cvt_pk_bf16_f32 v69, v42, v43
	v_cvt_pk_bf16_f32 v70, v44, v45
	v_cvt_pk_bf16_f32 v71, v46, v47
	v_pk_add_f32 v[232:233], v[232:233], v[32:33]
	v_pk_add_f32 v[232:233], v[232:233], v[34:35]
	v_pk_add_f32 v[232:233], v[232:233], v[36:37]
	v_pk_add_f32 v[232:233], v[232:233], v[38:39]
	v_pk_add_f32 v[232:233], v[232:233], v[40:41]
	v_pk_add_f32 v[232:233], v[232:233], v[42:43]
	v_pk_add_f32 v[232:233], v[232:233], v[44:45]
	v_pk_add_f32 v[232:233], v[232:233], v[46:47]
	ds_read2_b32 v[32:33], v115 offset0:34 offset1:35
	ds_read2_b32 v[34:35], v115 offset0:36 offset1:37
	ds_read2_b32 v[36:37], v115 offset0:42 offset1:43
	ds_read2_b32 v[38:39], v115 offset0:44 offset1:45
	ds_read2_b32 v[40:41], v115 offset0:51 offset1:52
	ds_read2_b32 v[42:43], v115 offset0:53 offset1:54
	ds_read2_b32 v[44:45], v115 offset0:59 offset1:60
	ds_read2_b32 v[46:47], v115 offset0:61 offset1:62
	v_mfma_f32_32x32x16_bf16 v[0:15], v[64:67], v[72:75], v[0:15]
	v_mfma_f32_32x32x16_bf16 v[16:31], v[64:67], v[76:79], v[16:31]
	v_mfma_f32_32x32x16_bf16 v[0:15], v[68:71], v[220:223], v[0:15]
	v_mfma_f32_32x32x16_bf16 v[16:31], v[68:71], v[224:227], v[16:31]
	s_add_i32 s90, s67, 224
	v_add_u32_e32 v80, s90, v235
	v_add_u32_e32 v83, s90, v236
	v_add_u32_e32 v99, s90, v237
	v_add_u32_e32 v253, s90, v238
	v_add_u32_e32 v254, s90, v100
	v_add_u32_e32 v255, s90, v149
	v_med3_i32 v80, v80, 0, s99
	v_med3_i32 v83, v83, 0, s99
	v_med3_i32 v99, v99, 0, s99
	v_med3_i32 v253, v253, 0, s99
	v_med3_i32 v254, v254, 0, s99
	v_med3_i32 v255, v255, 0, s99
	v_mad_u32_u24 v80, v80, s100, v252
	v_mad_u32_u24 v83, v83, s100, v252
	v_mad_u32_u24 v99, v99, s100, v252
	v_mad_u32_u24 v253, v253, s100, v252
	v_mad_u32_u24 v254, v254, s100, v153
	v_mad_u32_u24 v255, v255, s100, v153
	global_load_dwordx4 v[156:159], v80, s[82:83]
	global_load_dwordx4 v[160:163], v83, s[82:83]
	global_load_dwordx4 v[164:167], v99, s[82:83]
	global_load_dwordx4 v[168:171], v253, s[82:83]
	global_load_dwordx4 v[172:175], v254, s[82:83] offset:768
	global_load_dwordx4 v[176:179], v255, s[82:83] offset:768
	global_load_dwordx4 v[180:183], v254, s[82:83] offset:832
	global_load_dwordx4 v[184:187], v255, s[82:83] offset:832
	ds_read_b64_tr_b16 v[72:73], v231
	ds_read_b64_tr_b16 v[74:75], v231 offset:512
	ds_read_b64_tr_b16 v[76:77], v231 offset:2048
	ds_read_b64_tr_b16 v[78:79], v231 offset:2560
	ds_read_b64_tr_b16 v[220:221], v231 offset:1024
	ds_read_b64_tr_b16 v[222:223], v231 offset:1536
	ds_read_b64_tr_b16 v[224:225], v231 offset:3072
	ds_read_b64_tr_b16 v[226:227], v231 offset:3584
	s_waitcnt vmcnt(8)
	ds_write_b128 v247, v[116:119]
	ds_write_b128 v247, v[120:123] offset:1024
	ds_write_b128 v111, v[124:127] offset:2048
	ds_write_b128 v111, v[128:131] offset:3072
	ds_read_b128 v[116:119], v248
	ds_read_b128 v[120:123], v249
	ds_read_b128 v[124:127], v250
	ds_read_b128 v[128:131], v251
	ds_write_b128 v112, v[132:135]
	ds_write_b128 v112, v[136:139] offset:1024
	ds_write_b128 v112, v[140:143] offset:2048
	ds_write_b128 v112, v[144:147] offset:3072
	v_exp_f32_e32 v188, v188
	v_exp_f32_e32 v189, v189
	v_exp_f32_e32 v190, v190
	v_exp_f32_e32 v191, v191
	v_exp_f32_e32 v192, v192
	v_exp_f32_e32 v193, v193
	s_waitcnt lgkmcnt(4)
	v_mfma_f32_32x32x16_bf16 v[32:47], v[116:119], v[48:51], v[32:47]
	v_exp_f32_e32 v194, v194
	v_exp_f32_e32 v195, v195
	v_mfma_f32_32x32x16_bf16 v[32:47], v[120:123], v[52:55], v[32:47]
	v_exp_f32_e32 v196, v196
	v_exp_f32_e32 v197, v197
	v_exp_f32_e32 v198, v198
	v_mfma_f32_32x32x16_bf16 v[32:47], v[124:127], v[56:59], v[32:47]
	v_exp_f32_e32 v199, v199
	v_exp_f32_e32 v200, v200
	v_mfma_f32_32x32x16_bf16 v[32:47], v[128:131], v[60:63], v[32:47]
	v_exp_f32_e32 v201, v201
	v_exp_f32_e32 v202, v202
	v_exp_f32_e32 v203, v203
	s_add_i32 s90, s67, 160
	v_add_u32_e32 v84, s90, v107
	v_add_u32_e32 v85, 0, v84
	v_add_u32_e32 v86, 1, v84
	v_add_u32_e32 v87, 2, v84
	v_add_u32_e32 v88, 3, v84
	v_cmp_gt_u32_e64 s[30:31], s98, v85
	v_cmp_gt_u32_e64 s[36:37], s98, v86
	v_cmp_gt_u32_e64 s[78:79], s98, v87
	v_cmp_gt_u32_e64 s[50:51], s98, v88
	v_cndmask_b32_e64 v188, 0, v188, s[30:31]
	v_add_u32_e32 v85, 8, v84
	v_cmp_gt_u32_e64 s[30:31], s98, v85
	v_cndmask_b32_e64 v189, 0, v189, s[36:37]
	v_add_u32_e32 v86, 9, v84
	v_cmp_gt_u32_e64 s[36:37], s98, v86
	v_cndmask_b32_e64 v190, 0, v190, s[78:79]
	v_add_u32_e32 v87, 10, v84
	v_cmp_gt_u32_e64 s[78:79], s98, v87
	v_cndmask_b32_e64 v191, 0, v191, s[50:51]
	v_add_u32_e32 v88, 11, v84
	v_cmp_gt_u32_e64 s[50:51], s98, v88
	v_cndmask_b32_e64 v192, 0, v192, s[30:31]
	v_add_u32_e32 v85, 16, v84
	v_cmp_gt_u32_e64 s[30:31], s98, v85
	v_cndmask_b32_e64 v193, 0, v193, s[36:37]
	v_add_u32_e32 v86, 17, v84
	v_cmp_gt_u32_e64 s[36:37], s98, v86
	v_cndmask_b32_e64 v194, 0, v194, s[78:79]
	v_add_u32_e32 v87, 18, v84
	v_cmp_gt_u32_e64 s[78:79], s98, v87
	v_cndmask_b32_e64 v195, 0, v195, s[50:51]
	v_add_u32_e32 v88, 19, v84
	v_cmp_gt_u32_e64 s[50:51], s98, v88
	v_cndmask_b32_e64 v196, 0, v196, s[30:31]
	v_add_u32_e32 v85, 24, v84
	v_cmp_gt_u32_e64 s[30:31], s98, v85
	v_cndmask_b32_e64 v197, 0, v197, s[36:37]
	v_add_u32_e32 v86, 25, v84
	v_cmp_gt_u32_e64 s[36:37], s98, v86
	v_cndmask_b32_e64 v198, 0, v198, s[78:79]
	v_add_u32_e32 v87, 26, v84
	v_cmp_gt_u32_e64 s[78:79], s98, v87
	v_cndmask_b32_e64 v199, 0, v199, s[50:51]
	v_add_u32_e32 v88, 27, v84
	v_cmp_gt_u32_e64 s[50:51], s98, v88
	v_nop
	v_cndmask_b32_e64 v200, 0, v200, s[30:31]
	v_cndmask_b32_e64 v201, 0, v201, s[36:37]
	v_cndmask_b32_e64 v202, 0, v202, s[78:79]
	v_cndmask_b32_e64 v203, 0, v203, s[50:51]
	v_cvt_pk_bf16_f32 v64, v188, v189
	v_cvt_pk_bf16_f32 v65, v190, v191
	v_cvt_pk_bf16_f32 v66, v192, v193
	v_cvt_pk_bf16_f32 v67, v194, v195
	v_cvt_pk_bf16_f32 v68, v196, v197
	v_cvt_pk_bf16_f32 v69, v198, v199
	v_cvt_pk_bf16_f32 v70, v200, v201
	v_cvt_pk_bf16_f32 v71, v202, v203
	v_pk_add_f32 v[232:233], v[232:233], v[188:189]
	v_pk_add_f32 v[232:233], v[232:233], v[190:191]
	v_pk_add_f32 v[232:233], v[232:233], v[192:193]
	v_pk_add_f32 v[232:233], v[232:233], v[194:195]
	v_pk_add_f32 v[232:233], v[232:233], v[196:197]
	v_pk_add_f32 v[232:233], v[232:233], v[198:199]
	v_pk_add_f32 v[232:233], v[232:233], v[200:201]
	v_pk_add_f32 v[232:233], v[232:233], v[202:203]
	ds_read2_b32 v[188:189], v115 offset0:68 offset1:69
	ds_read2_b32 v[190:191], v115 offset0:70 offset1:71
	ds_read2_b32 v[192:193], v115 offset0:76 offset1:77
	ds_read2_b32 v[194:195], v115 offset0:78 offset1:79
	ds_read2_b32 v[196:197], v115 offset0:85 offset1:86
	ds_read2_b32 v[198:199], v115 offset0:87 offset1:88
	ds_read2_b32 v[200:201], v115 offset0:93 offset1:94
	ds_read2_b32 v[202:203], v115 offset0:95 offset1:96
	v_mfma_f32_32x32x16_bf16 v[0:15], v[64:67], v[72:75], v[0:15]
	v_mfma_f32_32x32x16_bf16 v[16:31], v[64:67], v[76:79], v[16:31]
	v_mfma_f32_32x32x16_bf16 v[0:15], v[68:71], v[220:223], v[0:15]
	v_mfma_f32_32x32x16_bf16 v[16:31], v[68:71], v[224:227], v[16:31]
	s_add_i32 s90, s67, 256
	v_add_u32_e32 v80, s90, v235
	v_add_u32_e32 v83, s90, v236
	v_add_u32_e32 v99, s90, v237
	v_add_u32_e32 v253, s90, v238
	v_add_u32_e32 v254, s90, v100
	v_add_u32_e32 v255, s90, v149
	v_med3_i32 v80, v80, 0, s99
	v_med3_i32 v83, v83, 0, s99
	v_med3_i32 v99, v99, 0, s99
	v_med3_i32 v253, v253, 0, s99
	v_med3_i32 v254, v254, 0, s99
	v_med3_i32 v255, v255, 0, s99
	v_mad_u32_u24 v80, v80, s100, v252
	v_mad_u32_u24 v83, v83, s100, v252
	v_mad_u32_u24 v99, v99, s100, v252
	v_mad_u32_u24 v253, v253, s100, v252
	v_mad_u32_u24 v254, v254, s100, v153
	v_mad_u32_u24 v255, v255, s100, v153
	global_load_dwordx4 v[116:119], v80, s[82:83]
	global_load_dwordx4 v[120:123], v83, s[82:83]
	global_load_dwordx4 v[124:127], v99, s[82:83]
	global_load_dwordx4 v[128:131], v253, s[82:83]
	global_load_dwordx4 v[132:135], v254, s[82:83] offset:768
	global_load_dwordx4 v[136:139], v255, s[82:83] offset:768
	global_load_dwordx4 v[140:143], v254, s[82:83] offset:832
	global_load_dwordx4 v[144:147], v255, s[82:83] offset:832
	ds_read_b64_tr_b16 v[72:73], v231
	ds_read_b64_tr_b16 v[74:75], v231 offset:512
	ds_read_b64_tr_b16 v[76:77], v231 offset:2048
	ds_read_b64_tr_b16 v[78:79], v231 offset:2560
	ds_read_b64_tr_b16 v[220:221], v231 offset:1024
	ds_read_b64_tr_b16 v[222:223], v231 offset:1536
	ds_read_b64_tr_b16 v[224:225], v231 offset:3072
	ds_read_b64_tr_b16 v[226:227], v231 offset:3584
	s_waitcnt vmcnt(8)
	ds_write_b128 v247, v[156:159]
	ds_write_b128 v247, v[160:163] offset:1024
	ds_write_b128 v111, v[164:167] offset:2048
	ds_write_b128 v111, v[168:171] offset:3072
	ds_read_b128 v[156:159], v248
	ds_read_b128 v[160:163], v249
	ds_read_b128 v[164:167], v250
	ds_read_b128 v[168:171], v251
	ds_write_b128 v112, v[172:175]
	ds_write_b128 v112, v[176:179] offset:1024
	ds_write_b128 v112, v[180:183] offset:2048
	ds_write_b128 v112, v[184:187] offset:3072
	v_exp_f32_e32 v32, v32
	v_exp_f32_e32 v33, v33
	v_exp_f32_e32 v34, v34
	v_exp_f32_e32 v35, v35
	v_exp_f32_e32 v36, v36
	v_exp_f32_e32 v37, v37
	s_waitcnt lgkmcnt(4)
	v_mfma_f32_32x32x16_bf16 v[188:203], v[156:159], v[48:51], v[188:203]
	v_exp_f32_e32 v38, v38
	v_exp_f32_e32 v39, v39
	v_mfma_f32_32x32x16_bf16 v[188:203], v[160:163], v[52:55], v[188:203]
	v_exp_f32_e32 v40, v40
	v_exp_f32_e32 v41, v41
	v_exp_f32_e32 v42, v42
	v_mfma_f32_32x32x16_bf16 v[188:203], v[164:167], v[56:59], v[188:203]
	v_exp_f32_e32 v43, v43
	v_exp_f32_e32 v44, v44
	v_mfma_f32_32x32x16_bf16 v[188:203], v[168:171], v[60:63], v[188:203]
	v_exp_f32_e32 v45, v45
	v_exp_f32_e32 v46, v46
	v_exp_f32_e32 v47, v47
	s_add_i32 s90, s67, 192
	v_add_u32_e32 v84, s90, v107
	v_add_u32_e32 v85, 0, v84
	v_add_u32_e32 v86, 1, v84
	v_add_u32_e32 v87, 2, v84
	v_add_u32_e32 v88, 3, v84
	v_cmp_gt_u32_e64 s[30:31], s98, v85
	v_cmp_gt_u32_e64 s[36:37], s98, v86
	v_cmp_gt_u32_e64 s[78:79], s98, v87
	v_cmp_gt_u32_e64 s[50:51], s98, v88
	v_cndmask_b32_e64 v32, 0, v32, s[30:31]
	v_add_u32_e32 v85, 8, v84
	v_cmp_gt_u32_e64 s[30:31], s98, v85
	v_cndmask_b32_e64 v33, 0, v33, s[36:37]
	v_add_u32_e32 v86, 9, v84
	v_cmp_gt_u32_e64 s[36:37], s98, v86
	v_cndmask_b32_e64 v34, 0, v34, s[78:79]
	v_add_u32_e32 v87, 10, v84
	v_cmp_gt_u32_e64 s[78:79], s98, v87
	v_cndmask_b32_e64 v35, 0, v35, s[50:51]
	v_add_u32_e32 v88, 11, v84
	v_cmp_gt_u32_e64 s[50:51], s98, v88
	v_cndmask_b32_e64 v36, 0, v36, s[30:31]
	v_add_u32_e32 v85, 16, v84
	v_cmp_gt_u32_e64 s[30:31], s98, v85
	v_cndmask_b32_e64 v37, 0, v37, s[36:37]
	v_add_u32_e32 v86, 17, v84
	v_cmp_gt_u32_e64 s[36:37], s98, v86
	v_cndmask_b32_e64 v38, 0, v38, s[78:79]
	v_add_u32_e32 v87, 18, v84
	v_cmp_gt_u32_e64 s[78:79], s98, v87
	v_cndmask_b32_e64 v39, 0, v39, s[50:51]
	v_add_u32_e32 v88, 19, v84
	v_cmp_gt_u32_e64 s[50:51], s98, v88
	v_cndmask_b32_e64 v40, 0, v40, s[30:31]
	v_add_u32_e32 v85, 24, v84
	v_cmp_gt_u32_e64 s[30:31], s98, v85
	v_cndmask_b32_e64 v41, 0, v41, s[36:37]
	v_add_u32_e32 v86, 25, v84
	v_cmp_gt_u32_e64 s[36:37], s98, v86
	v_cndmask_b32_e64 v42, 0, v42, s[78:79]
	v_add_u32_e32 v87, 26, v84
	v_cmp_gt_u32_e64 s[78:79], s98, v87
	v_cndmask_b32_e64 v43, 0, v43, s[50:51]
	v_add_u32_e32 v88, 27, v84
	v_cmp_gt_u32_e64 s[50:51], s98, v88
	v_nop
	v_cndmask_b32_e64 v44, 0, v44, s[30:31]
	v_cndmask_b32_e64 v45, 0, v45, s[36:37]
	v_cndmask_b32_e64 v46, 0, v46, s[78:79]
	v_cndmask_b32_e64 v47, 0, v47, s[50:51]
	v_cvt_pk_bf16_f32 v64, v32, v33
	v_cvt_pk_bf16_f32 v65, v34, v35
	v_cvt_pk_bf16_f32 v66, v36, v37
	v_cvt_pk_bf16_f32 v67, v38, v39
	v_cvt_pk_bf16_f32 v68, v40, v41
	v_cvt_pk_bf16_f32 v69, v42, v43
	v_cvt_pk_bf16_f32 v70, v44, v45
	v_cvt_pk_bf16_f32 v71, v46, v47
	v_pk_add_f32 v[232:233], v[232:233], v[32:33]
	v_pk_add_f32 v[232:233], v[232:233], v[34:35]
	v_pk_add_f32 v[232:233], v[232:233], v[36:37]
	v_pk_add_f32 v[232:233], v[232:233], v[38:39]
	v_pk_add_f32 v[232:233], v[232:233], v[40:41]
	v_pk_add_f32 v[232:233], v[232:233], v[42:43]
	v_pk_add_f32 v[232:233], v[232:233], v[44:45]
	v_pk_add_f32 v[232:233], v[232:233], v[46:47]
	ds_read2_b32 v[32:33], v115 offset0:102 offset1:103
	ds_read2_b32 v[34:35], v115 offset0:104 offset1:105
	ds_read2_b32 v[36:37], v115 offset0:110 offset1:111
	ds_read2_b32 v[38:39], v115 offset0:112 offset1:113
	ds_read2_b32 v[40:41], v115 offset0:119 offset1:120
	ds_read2_b32 v[42:43], v115 offset0:121 offset1:122
	ds_read2_b32 v[44:45], v115 offset0:127 offset1:128
	ds_read2_b32 v[46:47], v115 offset0:129 offset1:130
	v_mfma_f32_32x32x16_bf16 v[0:15], v[64:67], v[72:75], v[0:15]
	v_mfma_f32_32x32x16_bf16 v[16:31], v[64:67], v[76:79], v[16:31]
	v_mfma_f32_32x32x16_bf16 v[0:15], v[68:71], v[220:223], v[0:15]
	v_mfma_f32_32x32x16_bf16 v[16:31], v[68:71], v[224:227], v[16:31]
	s_add_i32 s90, s67, 288
	v_add_u32_e32 v80, s90, v235
	v_add_u32_e32 v83, s90, v236
	v_add_u32_e32 v99, s90, v237
	v_add_u32_e32 v253, s90, v238
	v_add_u32_e32 v254, s90, v100
	v_add_u32_e32 v255, s90, v149
	v_med3_i32 v80, v80, 0, s99
	v_med3_i32 v83, v83, 0, s99
	v_med3_i32 v99, v99, 0, s99
	v_med3_i32 v253, v253, 0, s99
	v_med3_i32 v254, v254, 0, s99
	v_med3_i32 v255, v255, 0, s99
	v_mad_u32_u24 v80, v80, s100, v252
	v_mad_u32_u24 v83, v83, s100, v252
	v_mad_u32_u24 v99, v99, s100, v252
	v_mad_u32_u24 v253, v253, s100, v252
	v_mad_u32_u24 v254, v254, s100, v153
	v_mad_u32_u24 v255, v255, s100, v153
	global_load_dwordx4 v[156:159], v80, s[82:83]
	global_load_dwordx4 v[160:163], v83, s[82:83]
	global_load_dwordx4 v[164:167], v99, s[82:83]
	global_load_dwordx4 v[168:171], v253, s[82:83]
	global_load_dwordx4 v[172:175], v254, s[82:83] offset:768
	global_load_dwordx4 v[176:179], v255, s[82:83] offset:768
	global_load_dwordx4 v[180:183], v254, s[82:83] offset:832
	global_load_dwordx4 v[184:187], v255, s[82:83] offset:832
	ds_read_b64_tr_b16 v[72:73], v231
	ds_read_b64_tr_b16 v[74:75], v231 offset:512
	ds_read_b64_tr_b16 v[76:77], v231 offset:2048
	ds_read_b64_tr_b16 v[78:79], v231 offset:2560
	ds_read_b64_tr_b16 v[220:221], v231 offset:1024
	ds_read_b64_tr_b16 v[222:223], v231 offset:1536
	ds_read_b64_tr_b16 v[224:225], v231 offset:3072
	ds_read_b64_tr_b16 v[226:227], v231 offset:3584
	s_waitcnt vmcnt(8)
	ds_write_b128 v247, v[116:119]
	ds_write_b128 v247, v[120:123] offset:1024
	ds_write_b128 v111, v[124:127] offset:2048
	ds_write_b128 v111, v[128:131] offset:3072
	ds_read_b128 v[116:119], v248
	ds_read_b128 v[120:123], v249
	ds_read_b128 v[124:127], v250
	ds_read_b128 v[128:131], v251
	ds_write_b128 v112, v[132:135]
	ds_write_b128 v112, v[136:139] offset:1024
	ds_write_b128 v112, v[140:143] offset:2048
	ds_write_b128 v112, v[144:147] offset:3072
	v_exp_f32_e32 v188, v188
	v_exp_f32_e32 v189, v189
	v_exp_f32_e32 v190, v190
	v_exp_f32_e32 v191, v191
	v_exp_f32_e32 v192, v192
	v_exp_f32_e32 v193, v193
	s_waitcnt lgkmcnt(4)
	v_mfma_f32_32x32x16_bf16 v[32:47], v[116:119], v[48:51], v[32:47]
	v_exp_f32_e32 v194, v194
	v_exp_f32_e32 v195, v195
	v_mfma_f32_32x32x16_bf16 v[32:47], v[120:123], v[52:55], v[32:47]
	v_exp_f32_e32 v196, v196
	v_exp_f32_e32 v197, v197
	v_exp_f32_e32 v198, v198
	v_mfma_f32_32x32x16_bf16 v[32:47], v[124:127], v[56:59], v[32:47]
	v_exp_f32_e32 v199, v199
	v_exp_f32_e32 v200, v200
	v_mfma_f32_32x32x16_bf16 v[32:47], v[128:131], v[60:63], v[32:47]
	v_exp_f32_e32 v201, v201
	v_exp_f32_e32 v202, v202
	v_exp_f32_e32 v203, v203
	s_add_i32 s90, s67, 224
	v_add_u32_e32 v84, s90, v107
	v_add_u32_e32 v85, 0, v84
	v_add_u32_e32 v86, 1, v84
	v_add_u32_e32 v87, 2, v84
	v_add_u32_e32 v88, 3, v84
	v_cmp_gt_u32_e64 s[30:31], s98, v85
	v_cmp_gt_u32_e64 s[36:37], s98, v86
	v_cmp_gt_u32_e64 s[78:79], s98, v87
	v_cmp_gt_u32_e64 s[50:51], s98, v88
	v_cndmask_b32_e64 v188, 0, v188, s[30:31]
	v_add_u32_e32 v85, 8, v84
	v_cmp_gt_u32_e64 s[30:31], s98, v85
	v_cndmask_b32_e64 v189, 0, v189, s[36:37]
	v_add_u32_e32 v86, 9, v84
	v_cmp_gt_u32_e64 s[36:37], s98, v86
	v_cndmask_b32_e64 v190, 0, v190, s[78:79]
	v_add_u32_e32 v87, 10, v84
	v_cmp_gt_u32_e64 s[78:79], s98, v87
	v_cndmask_b32_e64 v191, 0, v191, s[50:51]
	v_add_u32_e32 v88, 11, v84
	v_cmp_gt_u32_e64 s[50:51], s98, v88
	v_cndmask_b32_e64 v192, 0, v192, s[30:31]
	v_add_u32_e32 v85, 16, v84
	v_cmp_gt_u32_e64 s[30:31], s98, v85
	v_cndmask_b32_e64 v193, 0, v193, s[36:37]
	v_add_u32_e32 v86, 17, v84
	v_cmp_gt_u32_e64 s[36:37], s98, v86
	v_cndmask_b32_e64 v194, 0, v194, s[78:79]
	v_add_u32_e32 v87, 18, v84
	v_cmp_gt_u32_e64 s[78:79], s98, v87
	v_cndmask_b32_e64 v195, 0, v195, s[50:51]
	v_add_u32_e32 v88, 19, v84
	v_cmp_gt_u32_e64 s[50:51], s98, v88
	v_cndmask_b32_e64 v196, 0, v196, s[30:31]
	v_add_u32_e32 v85, 24, v84
	v_cmp_gt_u32_e64 s[30:31], s98, v85
	v_cndmask_b32_e64 v197, 0, v197, s[36:37]
	v_add_u32_e32 v86, 25, v84
	v_cmp_gt_u32_e64 s[36:37], s98, v86
	v_cndmask_b32_e64 v198, 0, v198, s[78:79]
	v_add_u32_e32 v87, 26, v84
	v_cmp_gt_u32_e64 s[78:79], s98, v87
	v_cndmask_b32_e64 v199, 0, v199, s[50:51]
	v_add_u32_e32 v88, 27, v84
	v_cmp_gt_u32_e64 s[50:51], s98, v88
	v_nop
	v_cndmask_b32_e64 v200, 0, v200, s[30:31]
	v_cndmask_b32_e64 v201, 0, v201, s[36:37]
	v_cndmask_b32_e64 v202, 0, v202, s[78:79]
	v_cndmask_b32_e64 v203, 0, v203, s[50:51]
	v_cvt_pk_bf16_f32 v64, v188, v189
	v_cvt_pk_bf16_f32 v65, v190, v191
	v_cvt_pk_bf16_f32 v66, v192, v193
	v_cvt_pk_bf16_f32 v67, v194, v195
	v_cvt_pk_bf16_f32 v68, v196, v197
	v_cvt_pk_bf16_f32 v69, v198, v199
	v_cvt_pk_bf16_f32 v70, v200, v201
	v_cvt_pk_bf16_f32 v71, v202, v203
	v_pk_add_f32 v[232:233], v[232:233], v[188:189]
	v_pk_add_f32 v[232:233], v[232:233], v[190:191]
	v_pk_add_f32 v[232:233], v[232:233], v[192:193]
	v_pk_add_f32 v[232:233], v[232:233], v[194:195]
	v_pk_add_f32 v[232:233], v[232:233], v[196:197]
	v_pk_add_f32 v[232:233], v[232:233], v[198:199]
	v_pk_add_f32 v[232:233], v[232:233], v[200:201]
	v_pk_add_f32 v[232:233], v[232:233], v[202:203]
	ds_read2_b32 v[188:189], v115 offset0:136 offset1:137
	ds_read2_b32 v[190:191], v115 offset0:138 offset1:139
	ds_read2_b32 v[192:193], v115 offset0:144 offset1:145
	ds_read2_b32 v[194:195], v115 offset0:146 offset1:147
	ds_read2_b32 v[196:197], v115 offset0:153 offset1:154
	ds_read2_b32 v[198:199], v115 offset0:155 offset1:156
	ds_read2_b32 v[200:201], v115 offset0:161 offset1:162
	ds_read2_b32 v[202:203], v115 offset0:163 offset1:164
	v_mfma_f32_32x32x16_bf16 v[0:15], v[64:67], v[72:75], v[0:15]
	v_mfma_f32_32x32x16_bf16 v[16:31], v[64:67], v[76:79], v[16:31]
	v_mfma_f32_32x32x16_bf16 v[0:15], v[68:71], v[220:223], v[0:15]
	v_mfma_f32_32x32x16_bf16 v[16:31], v[68:71], v[224:227], v[16:31]
	s_add_i32 s90, s67, 320
	v_add_u32_e32 v80, s90, v235
	v_add_u32_e32 v83, s90, v236
	v_add_u32_e32 v99, s90, v237
	v_add_u32_e32 v253, s90, v238
	v_add_u32_e32 v254, s90, v100
	v_add_u32_e32 v255, s90, v149
	v_med3_i32 v80, v80, 0, s99
	v_med3_i32 v83, v83, 0, s99
	v_med3_i32 v99, v99, 0, s99
	v_med3_i32 v253, v253, 0, s99
	v_med3_i32 v254, v254, 0, s99
	v_med3_i32 v255, v255, 0, s99
	v_mad_u32_u24 v80, v80, s100, v252
	v_mad_u32_u24 v83, v83, s100, v252
	v_mad_u32_u24 v99, v99, s100, v252
	v_mad_u32_u24 v253, v253, s100, v252
	v_mad_u32_u24 v254, v254, s100, v153
	v_mad_u32_u24 v255, v255, s100, v153
	global_load_dwordx4 v[116:119], v80, s[82:83]
	global_load_dwordx4 v[120:123], v83, s[82:83]
	global_load_dwordx4 v[124:127], v99, s[82:83]
	global_load_dwordx4 v[128:131], v253, s[82:83]
	global_load_dwordx4 v[132:135], v254, s[82:83] offset:768
	global_load_dwordx4 v[136:139], v255, s[82:83] offset:768
	global_load_dwordx4 v[140:143], v254, s[82:83] offset:832
	global_load_dwordx4 v[144:147], v255, s[82:83] offset:832
	ds_read_b64_tr_b16 v[72:73], v231
	ds_read_b64_tr_b16 v[74:75], v231 offset:512
	ds_read_b64_tr_b16 v[76:77], v231 offset:2048
	ds_read_b64_tr_b16 v[78:79], v231 offset:2560
	ds_read_b64_tr_b16 v[220:221], v231 offset:1024
	ds_read_b64_tr_b16 v[222:223], v231 offset:1536
	ds_read_b64_tr_b16 v[224:225], v231 offset:3072
	ds_read_b64_tr_b16 v[226:227], v231 offset:3584
	s_waitcnt vmcnt(8)
	ds_write_b128 v247, v[156:159]
	ds_write_b128 v247, v[160:163] offset:1024
	ds_write_b128 v111, v[164:167] offset:2048
	ds_write_b128 v111, v[168:171] offset:3072
	ds_read_b128 v[156:159], v248
	ds_read_b128 v[160:163], v249
	ds_read_b128 v[164:167], v250
	ds_read_b128 v[168:171], v251
	ds_write_b128 v112, v[172:175]
	ds_write_b128 v112, v[176:179] offset:1024
	ds_write_b128 v112, v[180:183] offset:2048
	ds_write_b128 v112, v[184:187] offset:3072
	v_exp_f32_e32 v32, v32
	v_exp_f32_e32 v33, v33
	v_exp_f32_e32 v34, v34
	v_exp_f32_e32 v35, v35
	v_exp_f32_e32 v36, v36
	v_exp_f32_e32 v37, v37
	s_waitcnt lgkmcnt(4)
	v_mfma_f32_32x32x16_bf16 v[188:203], v[156:159], v[48:51], v[188:203]
	v_exp_f32_e32 v38, v38
	v_exp_f32_e32 v39, v39
	v_mfma_f32_32x32x16_bf16 v[188:203], v[160:163], v[52:55], v[188:203]
	v_exp_f32_e32 v40, v40
	v_exp_f32_e32 v41, v41
	v_exp_f32_e32 v42, v42
	v_mfma_f32_32x32x16_bf16 v[188:203], v[164:167], v[56:59], v[188:203]
	v_exp_f32_e32 v43, v43
	v_exp_f32_e32 v44, v44
	v_mfma_f32_32x32x16_bf16 v[188:203], v[168:171], v[60:63], v[188:203]
	v_exp_f32_e32 v45, v45
	v_exp_f32_e32 v46, v46
	v_exp_f32_e32 v47, v47
	s_add_i32 s90, s67, 256
	v_add_u32_e32 v84, s90, v107
	v_add_u32_e32 v85, 0, v84
	v_add_u32_e32 v86, 1, v84
	v_add_u32_e32 v87, 2, v84
	v_add_u32_e32 v88, 3, v84
	v_cmp_gt_u32_e64 s[30:31], s98, v85
	v_cmp_gt_u32_e64 s[36:37], s98, v86
	v_cmp_gt_u32_e64 s[78:79], s98, v87
	v_cmp_gt_u32_e64 s[50:51], s98, v88
	v_cndmask_b32_e64 v32, 0, v32, s[30:31]
	v_add_u32_e32 v85, 8, v84
	v_cmp_gt_u32_e64 s[30:31], s98, v85
	v_cndmask_b32_e64 v33, 0, v33, s[36:37]
	v_add_u32_e32 v86, 9, v84
	v_cmp_gt_u32_e64 s[36:37], s98, v86
	v_cndmask_b32_e64 v34, 0, v34, s[78:79]
	v_add_u32_e32 v87, 10, v84
	v_cmp_gt_u32_e64 s[78:79], s98, v87
	v_cndmask_b32_e64 v35, 0, v35, s[50:51]
	v_add_u32_e32 v88, 11, v84
	v_cmp_gt_u32_e64 s[50:51], s98, v88
	v_cndmask_b32_e64 v36, 0, v36, s[30:31]
	v_add_u32_e32 v85, 16, v84
	v_cmp_gt_u32_e64 s[30:31], s98, v85
	v_cndmask_b32_e64 v37, 0, v37, s[36:37]
	v_add_u32_e32 v86, 17, v84
	v_cmp_gt_u32_e64 s[36:37], s98, v86
	v_cndmask_b32_e64 v38, 0, v38, s[78:79]
	v_add_u32_e32 v87, 18, v84
	v_cmp_gt_u32_e64 s[78:79], s98, v87
	v_cndmask_b32_e64 v39, 0, v39, s[50:51]
	v_add_u32_e32 v88, 19, v84
	v_cmp_gt_u32_e64 s[50:51], s98, v88
	v_cndmask_b32_e64 v40, 0, v40, s[30:31]
	v_add_u32_e32 v85, 24, v84
	v_cmp_gt_u32_e64 s[30:31], s98, v85
	v_cndmask_b32_e64 v41, 0, v41, s[36:37]
	v_add_u32_e32 v86, 25, v84
	v_cmp_gt_u32_e64 s[36:37], s98, v86
	v_cndmask_b32_e64 v42, 0, v42, s[78:79]
	v_add_u32_e32 v87, 26, v84
	v_cmp_gt_u32_e64 s[78:79], s98, v87
	v_cndmask_b32_e64 v43, 0, v43, s[50:51]
	v_add_u32_e32 v88, 27, v84
	v_cmp_gt_u32_e64 s[50:51], s98, v88
	v_nop
	v_cndmask_b32_e64 v44, 0, v44, s[30:31]
	v_cndmask_b32_e64 v45, 0, v45, s[36:37]
	v_cndmask_b32_e64 v46, 0, v46, s[78:79]
	v_cndmask_b32_e64 v47, 0, v47, s[50:51]
	v_cvt_pk_bf16_f32 v64, v32, v33
	v_cvt_pk_bf16_f32 v65, v34, v35
	v_cvt_pk_bf16_f32 v66, v36, v37
	v_cvt_pk_bf16_f32 v67, v38, v39
	v_cvt_pk_bf16_f32 v68, v40, v41
	v_cvt_pk_bf16_f32 v69, v42, v43
	v_cvt_pk_bf16_f32 v70, v44, v45
	v_cvt_pk_bf16_f32 v71, v46, v47
	v_pk_add_f32 v[232:233], v[232:233], v[32:33]
	v_pk_add_f32 v[232:233], v[232:233], v[34:35]
	v_pk_add_f32 v[232:233], v[232:233], v[36:37]
	v_pk_add_f32 v[232:233], v[232:233], v[38:39]
	v_pk_add_f32 v[232:233], v[232:233], v[40:41]
	v_pk_add_f32 v[232:233], v[232:233], v[42:43]
	v_pk_add_f32 v[232:233], v[232:233], v[44:45]
	v_pk_add_f32 v[232:233], v[232:233], v[46:47]
	ds_read2_b32 v[32:33], v115 offset0:170 offset1:171
	ds_read2_b32 v[34:35], v115 offset0:172 offset1:173
	ds_read2_b32 v[36:37], v115 offset0:178 offset1:179
	ds_read2_b32 v[38:39], v115 offset0:180 offset1:181
	ds_read2_b32 v[40:41], v115 offset0:187 offset1:188
	ds_read2_b32 v[42:43], v115 offset0:189 offset1:190
	ds_read2_b32 v[44:45], v115 offset0:195 offset1:196
	ds_read2_b32 v[46:47], v115 offset0:197 offset1:198
	v_mfma_f32_32x32x16_bf16 v[0:15], v[64:67], v[72:75], v[0:15]
	v_mfma_f32_32x32x16_bf16 v[16:31], v[64:67], v[76:79], v[16:31]
	v_mfma_f32_32x32x16_bf16 v[0:15], v[68:71], v[220:223], v[0:15]
	v_mfma_f32_32x32x16_bf16 v[16:31], v[68:71], v[224:227], v[16:31]
	s_add_i32 s90, s67, 352
	v_add_u32_e32 v80, s90, v235
	v_add_u32_e32 v83, s90, v236
	v_add_u32_e32 v99, s90, v237
	v_add_u32_e32 v253, s90, v238
	v_add_u32_e32 v254, s90, v100
	v_add_u32_e32 v255, s90, v149
	v_med3_i32 v80, v80, 0, s99
	v_med3_i32 v83, v83, 0, s99
	v_med3_i32 v99, v99, 0, s99
	v_med3_i32 v253, v253, 0, s99
	v_med3_i32 v254, v254, 0, s99
	v_med3_i32 v255, v255, 0, s99
	v_mad_u32_u24 v80, v80, s100, v252
	v_mad_u32_u24 v83, v83, s100, v252
	v_mad_u32_u24 v99, v99, s100, v252
	v_mad_u32_u24 v253, v253, s100, v252
	v_mad_u32_u24 v254, v254, s100, v153
	v_mad_u32_u24 v255, v255, s100, v153
	global_load_dwordx4 v[156:159], v80, s[82:83]
	global_load_dwordx4 v[160:163], v83, s[82:83]
	global_load_dwordx4 v[164:167], v99, s[82:83]
	global_load_dwordx4 v[168:171], v253, s[82:83]
	global_load_dwordx4 v[172:175], v254, s[82:83] offset:768
	global_load_dwordx4 v[176:179], v255, s[82:83] offset:768
	global_load_dwordx4 v[180:183], v254, s[82:83] offset:832
	global_load_dwordx4 v[184:187], v255, s[82:83] offset:832
	ds_read_b64_tr_b16 v[72:73], v231
	ds_read_b64_tr_b16 v[74:75], v231 offset:512
	ds_read_b64_tr_b16 v[76:77], v231 offset:2048
	ds_read_b64_tr_b16 v[78:79], v231 offset:2560
	ds_read_b64_tr_b16 v[220:221], v231 offset:1024
	ds_read_b64_tr_b16 v[222:223], v231 offset:1536
	ds_read_b64_tr_b16 v[224:225], v231 offset:3072
	ds_read_b64_tr_b16 v[226:227], v231 offset:3584
	s_waitcnt vmcnt(8)
	ds_write_b128 v247, v[116:119]
	ds_write_b128 v247, v[120:123] offset:1024
	ds_write_b128 v111, v[124:127] offset:2048
	ds_write_b128 v111, v[128:131] offset:3072
	ds_read_b128 v[116:119], v248
	ds_read_b128 v[120:123], v249
	ds_read_b128 v[124:127], v250
	ds_read_b128 v[128:131], v251
	ds_write_b128 v112, v[132:135]
	ds_write_b128 v112, v[136:139] offset:1024
	ds_write_b128 v112, v[140:143] offset:2048
	ds_write_b128 v112, v[144:147] offset:3072
	v_exp_f32_e32 v188, v188
	v_exp_f32_e32 v189, v189
	v_exp_f32_e32 v190, v190
	v_exp_f32_e32 v191, v191
	v_exp_f32_e32 v192, v192
	v_exp_f32_e32 v193, v193
	s_waitcnt lgkmcnt(4)
	v_mfma_f32_32x32x16_bf16 v[32:47], v[116:119], v[48:51], v[32:47]
	v_exp_f32_e32 v194, v194
	v_exp_f32_e32 v195, v195
	v_mfma_f32_32x32x16_bf16 v[32:47], v[120:123], v[52:55], v[32:47]
	v_exp_f32_e32 v196, v196
	v_exp_f32_e32 v197, v197
	v_exp_f32_e32 v198, v198
	v_mfma_f32_32x32x16_bf16 v[32:47], v[124:127], v[56:59], v[32:47]
	v_exp_f32_e32 v199, v199
	v_exp_f32_e32 v200, v200
	v_mfma_f32_32x32x16_bf16 v[32:47], v[128:131], v[60:63], v[32:47]
	v_exp_f32_e32 v201, v201
	v_exp_f32_e32 v202, v202
	v_exp_f32_e32 v203, v203
	s_add_i32 s90, s67, 288
	v_add_u32_e32 v84, s90, v107
	v_add_u32_e32 v85, 0, v84
	v_add_u32_e32 v86, 1, v84
	v_add_u32_e32 v87, 2, v84
	v_add_u32_e32 v88, 3, v84
	v_cmp_gt_u32_e64 s[30:31], s98, v85
	v_cmp_gt_u32_e64 s[36:37], s98, v86
	v_cmp_gt_u32_e64 s[78:79], s98, v87
	v_cmp_gt_u32_e64 s[50:51], s98, v88
	v_cndmask_b32_e64 v188, 0, v188, s[30:31]
	v_add_u32_e32 v85, 8, v84
	v_cmp_gt_u32_e64 s[30:31], s98, v85
	v_cndmask_b32_e64 v189, 0, v189, s[36:37]
	v_add_u32_e32 v86, 9, v84
	v_cmp_gt_u32_e64 s[36:37], s98, v86
	v_cndmask_b32_e64 v190, 0, v190, s[78:79]
	v_add_u32_e32 v87, 10, v84
	v_cmp_gt_u32_e64 s[78:79], s98, v87
	v_cndmask_b32_e64 v191, 0, v191, s[50:51]
	v_add_u32_e32 v88, 11, v84
	v_cmp_gt_u32_e64 s[50:51], s98, v88
	v_cndmask_b32_e64 v192, 0, v192, s[30:31]
	v_add_u32_e32 v85, 16, v84
	v_cmp_gt_u32_e64 s[30:31], s98, v85
	v_cndmask_b32_e64 v193, 0, v193, s[36:37]
	v_add_u32_e32 v86, 17, v84
	v_cmp_gt_u32_e64 s[36:37], s98, v86
	v_cndmask_b32_e64 v194, 0, v194, s[78:79]
	v_add_u32_e32 v87, 18, v84
	v_cmp_gt_u32_e64 s[78:79], s98, v87
	v_cndmask_b32_e64 v195, 0, v195, s[50:51]
	v_add_u32_e32 v88, 19, v84
	v_cmp_gt_u32_e64 s[50:51], s98, v88
	v_cndmask_b32_e64 v196, 0, v196, s[30:31]
	v_add_u32_e32 v85, 24, v84
	v_cmp_gt_u32_e64 s[30:31], s98, v85
	v_cndmask_b32_e64 v197, 0, v197, s[36:37]
	v_add_u32_e32 v86, 25, v84
	v_cmp_gt_u32_e64 s[36:37], s98, v86
	v_cndmask_b32_e64 v198, 0, v198, s[78:79]
	v_add_u32_e32 v87, 26, v84
	v_cmp_gt_u32_e64 s[78:79], s98, v87
	v_cndmask_b32_e64 v199, 0, v199, s[50:51]
	v_add_u32_e32 v88, 27, v84
	v_cmp_gt_u32_e64 s[50:51], s98, v88
	v_nop
	v_cndmask_b32_e64 v200, 0, v200, s[30:31]
	v_cndmask_b32_e64 v201, 0, v201, s[36:37]
	v_cndmask_b32_e64 v202, 0, v202, s[78:79]
	v_cndmask_b32_e64 v203, 0, v203, s[50:51]
	v_cvt_pk_bf16_f32 v64, v188, v189
	v_cvt_pk_bf16_f32 v65, v190, v191
	v_cvt_pk_bf16_f32 v66, v192, v193
	v_cvt_pk_bf16_f32 v67, v194, v195
	v_cvt_pk_bf16_f32 v68, v196, v197
	v_cvt_pk_bf16_f32 v69, v198, v199
	v_cvt_pk_bf16_f32 v70, v200, v201
	v_cvt_pk_bf16_f32 v71, v202, v203
	v_pk_add_f32 v[232:233], v[232:233], v[188:189]
	v_pk_add_f32 v[232:233], v[232:233], v[190:191]
	v_pk_add_f32 v[232:233], v[232:233], v[192:193]
	v_pk_add_f32 v[232:233], v[232:233], v[194:195]
	v_pk_add_f32 v[232:233], v[232:233], v[196:197]
	v_pk_add_f32 v[232:233], v[232:233], v[198:199]
	v_pk_add_f32 v[232:233], v[232:233], v[200:201]
	v_pk_add_f32 v[232:233], v[232:233], v[202:203]
	ds_read2_b32 v[188:189], v115 offset0:204 offset1:205
	ds_read2_b32 v[190:191], v115 offset0:206 offset1:207
	ds_read2_b32 v[192:193], v115 offset0:212 offset1:213
	ds_read2_b32 v[194:195], v115 offset0:214 offset1:215
	ds_read2_b32 v[196:197], v115 offset0:221 offset1:222
	ds_read2_b32 v[198:199], v115 offset0:223 offset1:224
	ds_read2_b32 v[200:201], v115 offset0:229 offset1:230
	ds_read2_b32 v[202:203], v115 offset0:231 offset1:232
	v_mfma_f32_32x32x16_bf16 v[0:15], v[64:67], v[72:75], v[0:15]
	v_mfma_f32_32x32x16_bf16 v[16:31], v[64:67], v[76:79], v[16:31]
	v_mfma_f32_32x32x16_bf16 v[0:15], v[68:71], v[220:223], v[0:15]
	v_mfma_f32_32x32x16_bf16 v[16:31], v[68:71], v[224:227], v[16:31]
	s_add_i32 s90, s67, 384
	v_add_u32_e32 v80, s90, v235
	v_add_u32_e32 v83, s90, v236
	v_add_u32_e32 v99, s90, v237
	v_add_u32_e32 v253, s90, v238
	v_add_u32_e32 v254, s90, v100
	v_add_u32_e32 v255, s90, v149
	v_med3_i32 v80, v80, 0, s99
	v_med3_i32 v83, v83, 0, s99
	v_med3_i32 v99, v99, 0, s99
	v_med3_i32 v253, v253, 0, s99
	v_med3_i32 v254, v254, 0, s99
	v_med3_i32 v255, v255, 0, s99
	v_mad_u32_u24 v80, v80, s100, v252
	v_mad_u32_u24 v83, v83, s100, v252
	v_mad_u32_u24 v99, v99, s100, v252
	v_mad_u32_u24 v253, v253, s100, v252
	v_mad_u32_u24 v254, v254, s100, v153
	v_mad_u32_u24 v255, v255, s100, v153
	global_load_dwordx4 v[116:119], v80, s[82:83]
	global_load_dwordx4 v[120:123], v83, s[82:83]
	global_load_dwordx4 v[124:127], v99, s[82:83]
	global_load_dwordx4 v[128:131], v253, s[82:83]
	global_load_dwordx4 v[132:135], v254, s[82:83] offset:768
	global_load_dwordx4 v[136:139], v255, s[82:83] offset:768
	global_load_dwordx4 v[140:143], v254, s[82:83] offset:832
	global_load_dwordx4 v[144:147], v255, s[82:83] offset:832
	ds_read_b64_tr_b16 v[72:73], v231
	ds_read_b64_tr_b16 v[74:75], v231 offset:512
	ds_read_b64_tr_b16 v[76:77], v231 offset:2048
	ds_read_b64_tr_b16 v[78:79], v231 offset:2560
	ds_read_b64_tr_b16 v[220:221], v231 offset:1024
	ds_read_b64_tr_b16 v[222:223], v231 offset:1536
	ds_read_b64_tr_b16 v[224:225], v231 offset:3072
	ds_read_b64_tr_b16 v[226:227], v231 offset:3584
	s_waitcnt vmcnt(8)
	ds_write_b128 v247, v[156:159]
	ds_write_b128 v247, v[160:163] offset:1024
	ds_write_b128 v111, v[164:167] offset:2048
	ds_write_b128 v111, v[168:171] offset:3072
	ds_read_b128 v[156:159], v248
	ds_read_b128 v[160:163], v249
	ds_read_b128 v[164:167], v250
	ds_read_b128 v[168:171], v251
	ds_write_b128 v112, v[172:175]
	ds_write_b128 v112, v[176:179] offset:1024
	ds_write_b128 v112, v[180:183] offset:2048
	ds_write_b128 v112, v[184:187] offset:3072
	v_exp_f32_e32 v32, v32
	v_exp_f32_e32 v33, v33
	v_exp_f32_e32 v34, v34
	v_exp_f32_e32 v35, v35
	v_exp_f32_e32 v36, v36
	v_exp_f32_e32 v37, v37
	s_waitcnt lgkmcnt(4)
	v_mfma_f32_32x32x16_bf16 v[188:203], v[156:159], v[48:51], v[188:203]
	v_exp_f32_e32 v38, v38
	v_exp_f32_e32 v39, v39
	v_mfma_f32_32x32x16_bf16 v[188:203], v[160:163], v[52:55], v[188:203]
	v_exp_f32_e32 v40, v40
	v_exp_f32_e32 v41, v41
	v_exp_f32_e32 v42, v42
	v_mfma_f32_32x32x16_bf16 v[188:203], v[164:167], v[56:59], v[188:203]
	v_exp_f32_e32 v43, v43
	v_exp_f32_e32 v44, v44
	v_mfma_f32_32x32x16_bf16 v[188:203], v[168:171], v[60:63], v[188:203]
	v_exp_f32_e32 v45, v45
	v_exp_f32_e32 v46, v46
	v_exp_f32_e32 v47, v47
	s_add_i32 s90, s67, 320
	v_add_u32_e32 v84, s90, v107
	v_add_u32_e32 v85, 0, v84
	v_add_u32_e32 v86, 1, v84
	v_add_u32_e32 v87, 2, v84
	v_add_u32_e32 v88, 3, v84
	v_cmp_gt_u32_e64 s[30:31], s98, v85
	v_cmp_gt_u32_e64 s[36:37], s98, v86
	v_cmp_gt_u32_e64 s[78:79], s98, v87
	v_cmp_gt_u32_e64 s[50:51], s98, v88
	v_cndmask_b32_e64 v32, 0, v32, s[30:31]
	v_add_u32_e32 v85, 8, v84
	v_cmp_gt_u32_e64 s[30:31], s98, v85
	v_cndmask_b32_e64 v33, 0, v33, s[36:37]
	v_add_u32_e32 v86, 9, v84
	v_cmp_gt_u32_e64 s[36:37], s98, v86
	v_cndmask_b32_e64 v34, 0, v34, s[78:79]
	v_add_u32_e32 v87, 10, v84
	v_cmp_gt_u32_e64 s[78:79], s98, v87
	v_cndmask_b32_e64 v35, 0, v35, s[50:51]
	v_add_u32_e32 v88, 11, v84
	v_cmp_gt_u32_e64 s[50:51], s98, v88
	v_cndmask_b32_e64 v36, 0, v36, s[30:31]
	v_add_u32_e32 v85, 16, v84
	v_cmp_gt_u32_e64 s[30:31], s98, v85
	v_cndmask_b32_e64 v37, 0, v37, s[36:37]
	v_add_u32_e32 v86, 17, v84
	v_cmp_gt_u32_e64 s[36:37], s98, v86
	v_cndmask_b32_e64 v38, 0, v38, s[78:79]
	v_add_u32_e32 v87, 18, v84
	v_cmp_gt_u32_e64 s[78:79], s98, v87
	v_cndmask_b32_e64 v39, 0, v39, s[50:51]
	v_add_u32_e32 v88, 19, v84
	v_cmp_gt_u32_e64 s[50:51], s98, v88
	v_cndmask_b32_e64 v40, 0, v40, s[30:31]
	v_add_u32_e32 v85, 24, v84
	v_cmp_gt_u32_e64 s[30:31], s98, v85
	v_cndmask_b32_e64 v41, 0, v41, s[36:37]
	v_add_u32_e32 v86, 25, v84
	v_cmp_gt_u32_e64 s[36:37], s98, v86
	v_cndmask_b32_e64 v42, 0, v42, s[78:79]
	v_add_u32_e32 v87, 26, v84
	v_cmp_gt_u32_e64 s[78:79], s98, v87
	v_cndmask_b32_e64 v43, 0, v43, s[50:51]
	v_add_u32_e32 v88, 27, v84
	v_cmp_gt_u32_e64 s[50:51], s98, v88
	v_nop
	v_cndmask_b32_e64 v44, 0, v44, s[30:31]
	v_cndmask_b32_e64 v45, 0, v45, s[36:37]
	v_cndmask_b32_e64 v46, 0, v46, s[78:79]
	v_cndmask_b32_e64 v47, 0, v47, s[50:51]
	v_cvt_pk_bf16_f32 v64, v32, v33
	v_cvt_pk_bf16_f32 v65, v34, v35
	v_cvt_pk_bf16_f32 v66, v36, v37
	v_cvt_pk_bf16_f32 v67, v38, v39
	v_cvt_pk_bf16_f32 v68, v40, v41
	v_cvt_pk_bf16_f32 v69, v42, v43
	v_cvt_pk_bf16_f32 v70, v44, v45
	v_cvt_pk_bf16_f32 v71, v46, v47
	v_pk_add_f32 v[232:233], v[232:233], v[32:33]
	v_pk_add_f32 v[232:233], v[232:233], v[34:35]
	v_pk_add_f32 v[232:233], v[232:233], v[36:37]
	v_pk_add_f32 v[232:233], v[232:233], v[38:39]
	v_pk_add_f32 v[232:233], v[232:233], v[40:41]
	v_pk_add_f32 v[232:233], v[232:233], v[42:43]
	v_pk_add_f32 v[232:233], v[232:233], v[44:45]
	v_pk_add_f32 v[232:233], v[232:233], v[46:47]
	v_add_u32_e32 v115, 952, v115
	ds_read2_b32 v[32:33], v115 offset0:0 offset1:1
	ds_read2_b32 v[34:35], v115 offset0:2 offset1:3
	ds_read2_b32 v[36:37], v115 offset0:8 offset1:9
	ds_read2_b32 v[38:39], v115 offset0:10 offset1:11
	ds_read2_b32 v[40:41], v115 offset0:17 offset1:18
	ds_read2_b32 v[42:43], v115 offset0:19 offset1:20
	ds_read2_b32 v[44:45], v115 offset0:25 offset1:26
	ds_read2_b32 v[46:47], v115 offset0:27 offset1:28
	v_mfma_f32_32x32x16_bf16 v[0:15], v[64:67], v[72:75], v[0:15]
	v_mfma_f32_32x32x16_bf16 v[16:31], v[64:67], v[76:79], v[16:31]
	v_mfma_f32_32x32x16_bf16 v[0:15], v[68:71], v[220:223], v[0:15]
	v_mfma_f32_32x32x16_bf16 v[16:31], v[68:71], v[224:227], v[16:31]
	s_add_i32 s90, s67, 416
	v_add_u32_e32 v80, s90, v235
	v_add_u32_e32 v83, s90, v236
	v_add_u32_e32 v99, s90, v237
	v_add_u32_e32 v253, s90, v238
	v_add_u32_e32 v254, s90, v100
	v_add_u32_e32 v255, s90, v149
	v_med3_i32 v80, v80, 0, s99
	v_med3_i32 v83, v83, 0, s99
	v_med3_i32 v99, v99, 0, s99
	v_med3_i32 v253, v253, 0, s99
	v_med3_i32 v254, v254, 0, s99
	v_med3_i32 v255, v255, 0, s99
	v_mad_u32_u24 v80, v80, s100, v252
	v_mad_u32_u24 v83, v83, s100, v252
	v_mad_u32_u24 v99, v99, s100, v252
	v_mad_u32_u24 v253, v253, s100, v252
	v_mad_u32_u24 v254, v254, s100, v153
	v_mad_u32_u24 v255, v255, s100, v153
	global_load_dwordx4 v[156:159], v80, s[82:83]
	global_load_dwordx4 v[160:163], v83, s[82:83]
	global_load_dwordx4 v[164:167], v99, s[82:83]
	global_load_dwordx4 v[168:171], v253, s[82:83]
	global_load_dwordx4 v[172:175], v254, s[82:83] offset:768
	global_load_dwordx4 v[176:179], v255, s[82:83] offset:768
	global_load_dwordx4 v[180:183], v254, s[82:83] offset:832
	global_load_dwordx4 v[184:187], v255, s[82:83] offset:832
	ds_read_b64_tr_b16 v[72:73], v231
	ds_read_b64_tr_b16 v[74:75], v231 offset:512
	ds_read_b64_tr_b16 v[76:77], v231 offset:2048
	ds_read_b64_tr_b16 v[78:79], v231 offset:2560
	ds_read_b64_tr_b16 v[220:221], v231 offset:1024
	ds_read_b64_tr_b16 v[222:223], v231 offset:1536
	ds_read_b64_tr_b16 v[224:225], v231 offset:3072
	ds_read_b64_tr_b16 v[226:227], v231 offset:3584
	s_waitcnt vmcnt(8)
	ds_write_b128 v247, v[116:119]
	ds_write_b128 v247, v[120:123] offset:1024
	ds_write_b128 v111, v[124:127] offset:2048
	ds_write_b128 v111, v[128:131] offset:3072
	ds_read_b128 v[116:119], v248
	ds_read_b128 v[120:123], v249
	ds_read_b128 v[124:127], v250
	ds_read_b128 v[128:131], v251
	ds_write_b128 v112, v[132:135]
	ds_write_b128 v112, v[136:139] offset:1024
	ds_write_b128 v112, v[140:143] offset:2048
	ds_write_b128 v112, v[144:147] offset:3072
	v_exp_f32_e32 v188, v188
	v_exp_f32_e32 v189, v189
	v_exp_f32_e32 v190, v190
	v_exp_f32_e32 v191, v191
	v_exp_f32_e32 v192, v192
	v_exp_f32_e32 v193, v193
	s_waitcnt lgkmcnt(4)
	v_mfma_f32_32x32x16_bf16 v[32:47], v[116:119], v[48:51], v[32:47]
	v_exp_f32_e32 v194, v194
	v_exp_f32_e32 v195, v195
	v_mfma_f32_32x32x16_bf16 v[32:47], v[120:123], v[52:55], v[32:47]
	v_exp_f32_e32 v196, v196
	v_exp_f32_e32 v197, v197
	v_exp_f32_e32 v198, v198
	v_mfma_f32_32x32x16_bf16 v[32:47], v[124:127], v[56:59], v[32:47]
	v_exp_f32_e32 v199, v199
	v_exp_f32_e32 v200, v200
	v_mfma_f32_32x32x16_bf16 v[32:47], v[128:131], v[60:63], v[32:47]
	v_exp_f32_e32 v201, v201
	v_exp_f32_e32 v202, v202
	v_exp_f32_e32 v203, v203
	s_add_i32 s90, s67, 352
	v_add_u32_e32 v84, s90, v107
	v_add_u32_e32 v85, 0, v84
	v_add_u32_e32 v86, 1, v84
	v_add_u32_e32 v87, 2, v84
	v_add_u32_e32 v88, 3, v84
	v_cmp_gt_u32_e64 s[30:31], s98, v85
	v_cmp_gt_u32_e64 s[36:37], s98, v86
	v_cmp_gt_u32_e64 s[78:79], s98, v87
	v_cmp_gt_u32_e64 s[50:51], s98, v88
	v_cndmask_b32_e64 v188, 0, v188, s[30:31]
	v_add_u32_e32 v85, 8, v84
	v_cmp_gt_u32_e64 s[30:31], s98, v85
	v_cndmask_b32_e64 v189, 0, v189, s[36:37]
	v_add_u32_e32 v86, 9, v84
	v_cmp_gt_u32_e64 s[36:37], s98, v86
	v_cndmask_b32_e64 v190, 0, v190, s[78:79]
	v_add_u32_e32 v87, 10, v84
	v_cmp_gt_u32_e64 s[78:79], s98, v87
	v_cndmask_b32_e64 v191, 0, v191, s[50:51]
	v_add_u32_e32 v88, 11, v84
	v_cmp_gt_u32_e64 s[50:51], s98, v88
	v_cndmask_b32_e64 v192, 0, v192, s[30:31]
	v_add_u32_e32 v85, 16, v84
	v_cmp_gt_u32_e64 s[30:31], s98, v85
	v_cndmask_b32_e64 v193, 0, v193, s[36:37]
	v_add_u32_e32 v86, 17, v84
	v_cmp_gt_u32_e64 s[36:37], s98, v86
	v_cndmask_b32_e64 v194, 0, v194, s[78:79]
	v_add_u32_e32 v87, 18, v84
	v_cmp_gt_u32_e64 s[78:79], s98, v87
	v_cndmask_b32_e64 v195, 0, v195, s[50:51]
	v_add_u32_e32 v88, 19, v84
	v_cmp_gt_u32_e64 s[50:51], s98, v88
	v_cndmask_b32_e64 v196, 0, v196, s[30:31]
	v_add_u32_e32 v85, 24, v84
	v_cmp_gt_u32_e64 s[30:31], s98, v85
	v_cndmask_b32_e64 v197, 0, v197, s[36:37]
	v_add_u32_e32 v86, 25, v84
	v_cmp_gt_u32_e64 s[36:37], s98, v86
	v_cndmask_b32_e64 v198, 0, v198, s[78:79]
	v_add_u32_e32 v87, 26, v84
	v_cmp_gt_u32_e64 s[78:79], s98, v87
	v_cndmask_b32_e64 v199, 0, v199, s[50:51]
	v_add_u32_e32 v88, 27, v84
	v_cmp_gt_u32_e64 s[50:51], s98, v88
	v_nop
	v_cndmask_b32_e64 v200, 0, v200, s[30:31]
	v_cndmask_b32_e64 v201, 0, v201, s[36:37]
	v_cndmask_b32_e64 v202, 0, v202, s[78:79]
	v_cndmask_b32_e64 v203, 0, v203, s[50:51]
	v_cvt_pk_bf16_f32 v64, v188, v189
	v_cvt_pk_bf16_f32 v65, v190, v191
	v_cvt_pk_bf16_f32 v66, v192, v193
	v_cvt_pk_bf16_f32 v67, v194, v195
	v_cvt_pk_bf16_f32 v68, v196, v197
	v_cvt_pk_bf16_f32 v69, v198, v199
	v_cvt_pk_bf16_f32 v70, v200, v201
	v_cvt_pk_bf16_f32 v71, v202, v203
	v_pk_add_f32 v[232:233], v[232:233], v[188:189]
	v_pk_add_f32 v[232:233], v[232:233], v[190:191]
	v_pk_add_f32 v[232:233], v[232:233], v[192:193]
	v_pk_add_f32 v[232:233], v[232:233], v[194:195]
	v_pk_add_f32 v[232:233], v[232:233], v[196:197]
	v_pk_add_f32 v[232:233], v[232:233], v[198:199]
	v_pk_add_f32 v[232:233], v[232:233], v[200:201]
	v_pk_add_f32 v[232:233], v[232:233], v[202:203]
	ds_read2_b32 v[188:189], v115 offset0:34 offset1:35
	ds_read2_b32 v[190:191], v115 offset0:36 offset1:37
	ds_read2_b32 v[192:193], v115 offset0:42 offset1:43
	ds_read2_b32 v[194:195], v115 offset0:44 offset1:45
	ds_read2_b32 v[196:197], v115 offset0:51 offset1:52
	ds_read2_b32 v[198:199], v115 offset0:53 offset1:54
	ds_read2_b32 v[200:201], v115 offset0:59 offset1:60
	ds_read2_b32 v[202:203], v115 offset0:61 offset1:62
	v_mfma_f32_32x32x16_bf16 v[0:15], v[64:67], v[72:75], v[0:15]
	v_mfma_f32_32x32x16_bf16 v[16:31], v[64:67], v[76:79], v[16:31]
	v_mfma_f32_32x32x16_bf16 v[0:15], v[68:71], v[220:223], v[0:15]
	v_mfma_f32_32x32x16_bf16 v[16:31], v[68:71], v[224:227], v[16:31]
	s_add_i32 s90, s67, 448
	v_add_u32_e32 v80, s90, v235
	v_add_u32_e32 v83, s90, v236
	v_add_u32_e32 v99, s90, v237
	v_add_u32_e32 v253, s90, v238
	v_add_u32_e32 v254, s90, v100
	v_add_u32_e32 v255, s90, v149
	v_med3_i32 v80, v80, 0, s99
	v_med3_i32 v83, v83, 0, s99
	v_med3_i32 v99, v99, 0, s99
	v_med3_i32 v253, v253, 0, s99
	v_med3_i32 v254, v254, 0, s99
	v_med3_i32 v255, v255, 0, s99
	v_mad_u32_u24 v80, v80, s100, v252
	v_mad_u32_u24 v83, v83, s100, v252
	v_mad_u32_u24 v99, v99, s100, v252
	v_mad_u32_u24 v253, v253, s100, v252
	v_mad_u32_u24 v254, v254, s100, v153
	v_mad_u32_u24 v255, v255, s100, v153
	global_load_dwordx4 v[116:119], v80, s[82:83]
	global_load_dwordx4 v[120:123], v83, s[82:83]
	global_load_dwordx4 v[124:127], v99, s[82:83]
	global_load_dwordx4 v[128:131], v253, s[82:83]
	global_load_dwordx4 v[132:135], v254, s[82:83] offset:768
	global_load_dwordx4 v[136:139], v255, s[82:83] offset:768
	global_load_dwordx4 v[140:143], v254, s[82:83] offset:832
	global_load_dwordx4 v[144:147], v255, s[82:83] offset:832
	ds_read_b64_tr_b16 v[72:73], v231
	ds_read_b64_tr_b16 v[74:75], v231 offset:512
	ds_read_b64_tr_b16 v[76:77], v231 offset:2048
	ds_read_b64_tr_b16 v[78:79], v231 offset:2560
	ds_read_b64_tr_b16 v[220:221], v231 offset:1024
	ds_read_b64_tr_b16 v[222:223], v231 offset:1536
	ds_read_b64_tr_b16 v[224:225], v231 offset:3072
	ds_read_b64_tr_b16 v[226:227], v231 offset:3584
	s_waitcnt vmcnt(8)
	ds_write_b128 v247, v[156:159]
	ds_write_b128 v247, v[160:163] offset:1024
	ds_write_b128 v111, v[164:167] offset:2048
	ds_write_b128 v111, v[168:171] offset:3072
	ds_read_b128 v[156:159], v248
	ds_read_b128 v[160:163], v249
	ds_read_b128 v[164:167], v250
	ds_read_b128 v[168:171], v251
	ds_write_b128 v112, v[172:175]
	ds_write_b128 v112, v[176:179] offset:1024
	ds_write_b128 v112, v[180:183] offset:2048
	ds_write_b128 v112, v[184:187] offset:3072
	v_exp_f32_e32 v32, v32
	v_exp_f32_e32 v33, v33
	v_exp_f32_e32 v34, v34
	v_exp_f32_e32 v35, v35
	v_exp_f32_e32 v36, v36
	v_exp_f32_e32 v37, v37
	s_waitcnt lgkmcnt(4)
	v_mfma_f32_32x32x16_bf16 v[188:203], v[156:159], v[48:51], v[188:203]
	v_exp_f32_e32 v38, v38
	v_exp_f32_e32 v39, v39
	v_mfma_f32_32x32x16_bf16 v[188:203], v[160:163], v[52:55], v[188:203]
	v_exp_f32_e32 v40, v40
	v_exp_f32_e32 v41, v41
	v_exp_f32_e32 v42, v42
	v_mfma_f32_32x32x16_bf16 v[188:203], v[164:167], v[56:59], v[188:203]
	v_exp_f32_e32 v43, v43
	v_exp_f32_e32 v44, v44
	v_mfma_f32_32x32x16_bf16 v[188:203], v[168:171], v[60:63], v[188:203]
	v_exp_f32_e32 v45, v45
	v_exp_f32_e32 v46, v46
	v_exp_f32_e32 v47, v47
	s_add_i32 s90, s67, 384
	v_add_u32_e32 v84, s90, v107
	v_add_u32_e32 v85, 0, v84
	v_add_u32_e32 v86, 1, v84
	v_add_u32_e32 v87, 2, v84
	v_add_u32_e32 v88, 3, v84
	v_cmp_gt_u32_e64 s[30:31], s98, v85
	v_cmp_gt_u32_e64 s[36:37], s98, v86
	v_cmp_gt_u32_e64 s[78:79], s98, v87
	v_cmp_gt_u32_e64 s[50:51], s98, v88
	v_cndmask_b32_e64 v32, 0, v32, s[30:31]
	v_add_u32_e32 v85, 8, v84
	v_cmp_gt_u32_e64 s[30:31], s98, v85
	v_cndmask_b32_e64 v33, 0, v33, s[36:37]
	v_add_u32_e32 v86, 9, v84
	v_cmp_gt_u32_e64 s[36:37], s98, v86
	v_cndmask_b32_e64 v34, 0, v34, s[78:79]
	v_add_u32_e32 v87, 10, v84
	v_cmp_gt_u32_e64 s[78:79], s98, v87
	v_cndmask_b32_e64 v35, 0, v35, s[50:51]
	v_add_u32_e32 v88, 11, v84
	v_cmp_gt_u32_e64 s[50:51], s98, v88
	v_cndmask_b32_e64 v36, 0, v36, s[30:31]
	v_add_u32_e32 v85, 16, v84
	v_cmp_gt_u32_e64 s[30:31], s98, v85
	v_cndmask_b32_e64 v37, 0, v37, s[36:37]
	v_add_u32_e32 v86, 17, v84
	v_cmp_gt_u32_e64 s[36:37], s98, v86
	v_cndmask_b32_e64 v38, 0, v38, s[78:79]
	v_add_u32_e32 v87, 18, v84
	v_cmp_gt_u32_e64 s[78:79], s98, v87
	v_cndmask_b32_e64 v39, 0, v39, s[50:51]
	v_add_u32_e32 v88, 19, v84
	v_cmp_gt_u32_e64 s[50:51], s98, v88
	v_cndmask_b32_e64 v40, 0, v40, s[30:31]
	v_add_u32_e32 v85, 24, v84
	v_cmp_gt_u32_e64 s[30:31], s98, v85
	v_cndmask_b32_e64 v41, 0, v41, s[36:37]
	v_add_u32_e32 v86, 25, v84
	v_cmp_gt_u32_e64 s[36:37], s98, v86
	v_cndmask_b32_e64 v42, 0, v42, s[78:79]
	v_add_u32_e32 v87, 26, v84
	v_cmp_gt_u32_e64 s[78:79], s98, v87
	v_cndmask_b32_e64 v43, 0, v43, s[50:51]
	v_add_u32_e32 v88, 27, v84
	v_cmp_gt_u32_e64 s[50:51], s98, v88
	v_nop
	v_cndmask_b32_e64 v44, 0, v44, s[30:31]
	v_cndmask_b32_e64 v45, 0, v45, s[36:37]
	v_cndmask_b32_e64 v46, 0, v46, s[78:79]
	v_cndmask_b32_e64 v47, 0, v47, s[50:51]
	v_cvt_pk_bf16_f32 v64, v32, v33
	v_cvt_pk_bf16_f32 v65, v34, v35
	v_cvt_pk_bf16_f32 v66, v36, v37
	v_cvt_pk_bf16_f32 v67, v38, v39
	v_cvt_pk_bf16_f32 v68, v40, v41
	v_cvt_pk_bf16_f32 v69, v42, v43
	v_cvt_pk_bf16_f32 v70, v44, v45
	v_cvt_pk_bf16_f32 v71, v46, v47
	v_pk_add_f32 v[232:233], v[232:233], v[32:33]
	v_pk_add_f32 v[232:233], v[232:233], v[34:35]
	v_pk_add_f32 v[232:233], v[232:233], v[36:37]
	v_pk_add_f32 v[232:233], v[232:233], v[38:39]
	v_pk_add_f32 v[232:233], v[232:233], v[40:41]
	v_pk_add_f32 v[232:233], v[232:233], v[42:43]
	v_pk_add_f32 v[232:233], v[232:233], v[44:45]
	v_pk_add_f32 v[232:233], v[232:233], v[46:47]
	ds_read2_b32 v[32:33], v115 offset0:68 offset1:69
	ds_read2_b32 v[34:35], v115 offset0:70 offset1:71
	ds_read2_b32 v[36:37], v115 offset0:76 offset1:77
	ds_read2_b32 v[38:39], v115 offset0:78 offset1:79
	ds_read2_b32 v[40:41], v115 offset0:85 offset1:86
	ds_read2_b32 v[42:43], v115 offset0:87 offset1:88
	ds_read2_b32 v[44:45], v115 offset0:93 offset1:94
	ds_read2_b32 v[46:47], v115 offset0:95 offset1:96
	v_mfma_f32_32x32x16_bf16 v[0:15], v[64:67], v[72:75], v[0:15]
	v_mfma_f32_32x32x16_bf16 v[16:31], v[64:67], v[76:79], v[16:31]
	v_mfma_f32_32x32x16_bf16 v[0:15], v[68:71], v[220:223], v[0:15]
	v_mfma_f32_32x32x16_bf16 v[16:31], v[68:71], v[224:227], v[16:31]
	s_add_i32 s90, s67, 480
	v_add_u32_e32 v80, s90, v235
	v_add_u32_e32 v83, s90, v236
	v_add_u32_e32 v99, s90, v237
	v_add_u32_e32 v253, s90, v238
	v_add_u32_e32 v254, s90, v100
	v_add_u32_e32 v255, s90, v149
	v_med3_i32 v80, v80, 0, s99
	v_med3_i32 v83, v83, 0, s99
	v_med3_i32 v99, v99, 0, s99
	v_med3_i32 v253, v253, 0, s99
	v_med3_i32 v254, v254, 0, s99
	v_med3_i32 v255, v255, 0, s99
	v_mad_u32_u24 v80, v80, s100, v252
	v_mad_u32_u24 v83, v83, s100, v252
	v_mad_u32_u24 v99, v99, s100, v252
	v_mad_u32_u24 v253, v253, s100, v252
	v_mad_u32_u24 v254, v254, s100, v153
	v_mad_u32_u24 v255, v255, s100, v153
	global_load_dwordx4 v[156:159], v80, s[82:83]
	global_load_dwordx4 v[160:163], v83, s[82:83]
	global_load_dwordx4 v[164:167], v99, s[82:83]
	global_load_dwordx4 v[168:171], v253, s[82:83]
	global_load_dwordx4 v[172:175], v254, s[82:83] offset:768
	global_load_dwordx4 v[176:179], v255, s[82:83] offset:768
	global_load_dwordx4 v[180:183], v254, s[82:83] offset:832
	global_load_dwordx4 v[184:187], v255, s[82:83] offset:832
	ds_read_b64_tr_b16 v[72:73], v231
	ds_read_b64_tr_b16 v[74:75], v231 offset:512
	ds_read_b64_tr_b16 v[76:77], v231 offset:2048
	ds_read_b64_tr_b16 v[78:79], v231 offset:2560
	ds_read_b64_tr_b16 v[220:221], v231 offset:1024
	ds_read_b64_tr_b16 v[222:223], v231 offset:1536
	ds_read_b64_tr_b16 v[224:225], v231 offset:3072
	ds_read_b64_tr_b16 v[226:227], v231 offset:3584
	s_waitcnt vmcnt(8)
	ds_write_b128 v247, v[116:119]
	ds_write_b128 v247, v[120:123] offset:1024
	ds_write_b128 v111, v[124:127] offset:2048
	ds_write_b128 v111, v[128:131] offset:3072
	ds_read_b128 v[116:119], v248
	ds_read_b128 v[120:123], v249
	ds_read_b128 v[124:127], v250
	ds_read_b128 v[128:131], v251
	ds_write_b128 v112, v[132:135]
	ds_write_b128 v112, v[136:139] offset:1024
	ds_write_b128 v112, v[140:143] offset:2048
	ds_write_b128 v112, v[144:147] offset:3072
	v_exp_f32_e32 v188, v188
	v_exp_f32_e32 v189, v189
	v_exp_f32_e32 v190, v190
	v_exp_f32_e32 v191, v191
	v_exp_f32_e32 v192, v192
	v_exp_f32_e32 v193, v193
	s_waitcnt lgkmcnt(4)
	v_mfma_f32_32x32x16_bf16 v[32:47], v[116:119], v[48:51], v[32:47]
	v_exp_f32_e32 v194, v194
	v_exp_f32_e32 v195, v195
	v_mfma_f32_32x32x16_bf16 v[32:47], v[120:123], v[52:55], v[32:47]
	v_exp_f32_e32 v196, v196
	v_exp_f32_e32 v197, v197
	v_exp_f32_e32 v198, v198
	v_mfma_f32_32x32x16_bf16 v[32:47], v[124:127], v[56:59], v[32:47]
	v_exp_f32_e32 v199, v199
	v_exp_f32_e32 v200, v200
	v_mfma_f32_32x32x16_bf16 v[32:47], v[128:131], v[60:63], v[32:47]
	v_exp_f32_e32 v201, v201
	v_exp_f32_e32 v202, v202
	v_exp_f32_e32 v203, v203
	s_add_i32 s90, s67, 416
	v_add_u32_e32 v84, s90, v107
	v_add_u32_e32 v85, 0, v84
	v_add_u32_e32 v86, 1, v84
	v_add_u32_e32 v87, 2, v84
	v_add_u32_e32 v88, 3, v84
	v_cmp_gt_u32_e64 s[30:31], s98, v85
	v_cmp_gt_u32_e64 s[36:37], s98, v86
	v_cmp_gt_u32_e64 s[78:79], s98, v87
	v_cmp_gt_u32_e64 s[50:51], s98, v88
	v_cndmask_b32_e64 v188, 0, v188, s[30:31]
	v_add_u32_e32 v85, 8, v84
	v_cmp_gt_u32_e64 s[30:31], s98, v85
	v_cndmask_b32_e64 v189, 0, v189, s[36:37]
	v_add_u32_e32 v86, 9, v84
	v_cmp_gt_u32_e64 s[36:37], s98, v86
	v_cndmask_b32_e64 v190, 0, v190, s[78:79]
	v_add_u32_e32 v87, 10, v84
	v_cmp_gt_u32_e64 s[78:79], s98, v87
	v_cndmask_b32_e64 v191, 0, v191, s[50:51]
	v_add_u32_e32 v88, 11, v84
	v_cmp_gt_u32_e64 s[50:51], s98, v88
	v_cndmask_b32_e64 v192, 0, v192, s[30:31]
	v_add_u32_e32 v85, 16, v84
	v_cmp_gt_u32_e64 s[30:31], s98, v85
	v_cndmask_b32_e64 v193, 0, v193, s[36:37]
	v_add_u32_e32 v86, 17, v84
	v_cmp_gt_u32_e64 s[36:37], s98, v86
	v_cndmask_b32_e64 v194, 0, v194, s[78:79]
	v_add_u32_e32 v87, 18, v84
	v_cmp_gt_u32_e64 s[78:79], s98, v87
	v_cndmask_b32_e64 v195, 0, v195, s[50:51]
	v_add_u32_e32 v88, 19, v84
	v_cmp_gt_u32_e64 s[50:51], s98, v88
	v_cndmask_b32_e64 v196, 0, v196, s[30:31]
	v_add_u32_e32 v85, 24, v84
	v_cmp_gt_u32_e64 s[30:31], s98, v85
	v_cndmask_b32_e64 v197, 0, v197, s[36:37]
	v_add_u32_e32 v86, 25, v84
	v_cmp_gt_u32_e64 s[36:37], s98, v86
	v_cndmask_b32_e64 v198, 0, v198, s[78:79]
	v_add_u32_e32 v87, 26, v84
	v_cmp_gt_u32_e64 s[78:79], s98, v87
	v_cndmask_b32_e64 v199, 0, v199, s[50:51]
	v_add_u32_e32 v88, 27, v84
	v_cmp_gt_u32_e64 s[50:51], s98, v88
	v_nop
	v_cndmask_b32_e64 v200, 0, v200, s[30:31]
	v_cndmask_b32_e64 v201, 0, v201, s[36:37]
	v_cndmask_b32_e64 v202, 0, v202, s[78:79]
	v_cndmask_b32_e64 v203, 0, v203, s[50:51]
	v_cvt_pk_bf16_f32 v64, v188, v189
	v_cvt_pk_bf16_f32 v65, v190, v191
	v_cvt_pk_bf16_f32 v66, v192, v193
	v_cvt_pk_bf16_f32 v67, v194, v195
	v_cvt_pk_bf16_f32 v68, v196, v197
	v_cvt_pk_bf16_f32 v69, v198, v199
	v_cvt_pk_bf16_f32 v70, v200, v201
	v_cvt_pk_bf16_f32 v71, v202, v203
	v_pk_add_f32 v[232:233], v[232:233], v[188:189]
	v_pk_add_f32 v[232:233], v[232:233], v[190:191]
	v_pk_add_f32 v[232:233], v[232:233], v[192:193]
	v_pk_add_f32 v[232:233], v[232:233], v[194:195]
	v_pk_add_f32 v[232:233], v[232:233], v[196:197]
	v_pk_add_f32 v[232:233], v[232:233], v[198:199]
	v_pk_add_f32 v[232:233], v[232:233], v[200:201]
	v_pk_add_f32 v[232:233], v[232:233], v[202:203]
	ds_read2_b32 v[188:189], v115 offset0:102 offset1:103
	ds_read2_b32 v[190:191], v115 offset0:104 offset1:105
	ds_read2_b32 v[192:193], v115 offset0:110 offset1:111
	ds_read2_b32 v[194:195], v115 offset0:112 offset1:113
	ds_read2_b32 v[196:197], v115 offset0:119 offset1:120
	ds_read2_b32 v[198:199], v115 offset0:121 offset1:122
	ds_read2_b32 v[200:201], v115 offset0:127 offset1:128
	ds_read2_b32 v[202:203], v115 offset0:129 offset1:130
	v_mfma_f32_32x32x16_bf16 v[0:15], v[64:67], v[72:75], v[0:15]
	v_mfma_f32_32x32x16_bf16 v[16:31], v[64:67], v[76:79], v[16:31]
	v_mfma_f32_32x32x16_bf16 v[0:15], v[68:71], v[220:223], v[0:15]
	v_mfma_f32_32x32x16_bf16 v[16:31], v[68:71], v[224:227], v[16:31]
	s_add_i32 s90, s67, 512
	v_add_u32_e32 v80, s90, v235
	v_add_u32_e32 v83, s90, v236
	v_add_u32_e32 v99, s90, v237
	v_add_u32_e32 v253, s90, v238
	v_add_u32_e32 v254, s90, v100
	v_add_u32_e32 v255, s90, v149
	v_med3_i32 v80, v80, 0, s99
	v_med3_i32 v83, v83, 0, s99
	v_med3_i32 v99, v99, 0, s99
	v_med3_i32 v253, v253, 0, s99
	v_med3_i32 v254, v254, 0, s99
	v_med3_i32 v255, v255, 0, s99
	v_mad_u32_u24 v80, v80, s100, v252
	v_mad_u32_u24 v83, v83, s100, v252
	v_mad_u32_u24 v99, v99, s100, v252
	v_mad_u32_u24 v253, v253, s100, v252
	v_mad_u32_u24 v254, v254, s100, v153
	v_mad_u32_u24 v255, v255, s100, v153
	global_load_dwordx4 v[116:119], v80, s[82:83]
	global_load_dwordx4 v[120:123], v83, s[82:83]
	global_load_dwordx4 v[124:127], v99, s[82:83]
	global_load_dwordx4 v[128:131], v253, s[82:83]
	global_load_dwordx4 v[132:135], v254, s[82:83] offset:768
	global_load_dwordx4 v[136:139], v255, s[82:83] offset:768
	global_load_dwordx4 v[140:143], v254, s[82:83] offset:832
	global_load_dwordx4 v[144:147], v255, s[82:83] offset:832
	ds_read_b64_tr_b16 v[72:73], v231
	ds_read_b64_tr_b16 v[74:75], v231 offset:512
	ds_read_b64_tr_b16 v[76:77], v231 offset:2048
	ds_read_b64_tr_b16 v[78:79], v231 offset:2560
	ds_read_b64_tr_b16 v[220:221], v231 offset:1024
	ds_read_b64_tr_b16 v[222:223], v231 offset:1536
	ds_read_b64_tr_b16 v[224:225], v231 offset:3072
	ds_read_b64_tr_b16 v[226:227], v231 offset:3584
	s_waitcnt vmcnt(8)
	ds_write_b128 v247, v[156:159]
	ds_write_b128 v247, v[160:163] offset:1024
	ds_write_b128 v111, v[164:167] offset:2048
	ds_write_b128 v111, v[168:171] offset:3072
	ds_read_b128 v[156:159], v248
	ds_read_b128 v[160:163], v249
	ds_read_b128 v[164:167], v250
	ds_read_b128 v[168:171], v251
	ds_write_b128 v112, v[172:175]
	ds_write_b128 v112, v[176:179] offset:1024
	ds_write_b128 v112, v[180:183] offset:2048
	ds_write_b128 v112, v[184:187] offset:3072
	v_exp_f32_e32 v32, v32
	v_exp_f32_e32 v33, v33
	v_exp_f32_e32 v34, v34
	v_exp_f32_e32 v35, v35
	v_exp_f32_e32 v36, v36
	v_exp_f32_e32 v37, v37
	s_waitcnt lgkmcnt(4)
	v_mfma_f32_32x32x16_bf16 v[188:203], v[156:159], v[48:51], v[188:203]
	v_exp_f32_e32 v38, v38
	v_exp_f32_e32 v39, v39
	v_mfma_f32_32x32x16_bf16 v[188:203], v[160:163], v[52:55], v[188:203]
	v_exp_f32_e32 v40, v40
	v_exp_f32_e32 v41, v41
	v_exp_f32_e32 v42, v42
	v_mfma_f32_32x32x16_bf16 v[188:203], v[164:167], v[56:59], v[188:203]
	v_exp_f32_e32 v43, v43
	v_exp_f32_e32 v44, v44
	v_mfma_f32_32x32x16_bf16 v[188:203], v[168:171], v[60:63], v[188:203]
	v_exp_f32_e32 v45, v45
	v_exp_f32_e32 v46, v46
	v_exp_f32_e32 v47, v47
	s_add_i32 s90, s67, 448
	v_add_u32_e32 v84, s90, v107
	v_add_u32_e32 v85, 0, v84
	v_add_u32_e32 v86, 1, v84
	v_add_u32_e32 v87, 2, v84
	v_add_u32_e32 v88, 3, v84
	v_cmp_gt_u32_e64 s[30:31], s98, v85
	v_cmp_gt_u32_e64 s[36:37], s98, v86
	v_cmp_gt_u32_e64 s[78:79], s98, v87
	v_cmp_gt_u32_e64 s[50:51], s98, v88
	v_cndmask_b32_e64 v32, 0, v32, s[30:31]
	v_add_u32_e32 v85, 8, v84
	v_cmp_gt_u32_e64 s[30:31], s98, v85
	v_cndmask_b32_e64 v33, 0, v33, s[36:37]
	v_add_u32_e32 v86, 9, v84
	v_cmp_gt_u32_e64 s[36:37], s98, v86
	v_cndmask_b32_e64 v34, 0, v34, s[78:79]
	v_add_u32_e32 v87, 10, v84
	v_cmp_gt_u32_e64 s[78:79], s98, v87
	v_cndmask_b32_e64 v35, 0, v35, s[50:51]
	v_add_u32_e32 v88, 11, v84
	v_cmp_gt_u32_e64 s[50:51], s98, v88
	v_cndmask_b32_e64 v36, 0, v36, s[30:31]
	v_add_u32_e32 v85, 16, v84
	v_cmp_gt_u32_e64 s[30:31], s98, v85
	v_cndmask_b32_e64 v37, 0, v37, s[36:37]
	v_add_u32_e32 v86, 17, v84
	v_cmp_gt_u32_e64 s[36:37], s98, v86
	v_cndmask_b32_e64 v38, 0, v38, s[78:79]
	v_add_u32_e32 v87, 18, v84
	v_cmp_gt_u32_e64 s[78:79], s98, v87
	v_cndmask_b32_e64 v39, 0, v39, s[50:51]
	v_add_u32_e32 v88, 19, v84
	v_cmp_gt_u32_e64 s[50:51], s98, v88
	v_cndmask_b32_e64 v40, 0, v40, s[30:31]
	v_add_u32_e32 v85, 24, v84
	v_cmp_gt_u32_e64 s[30:31], s98, v85
	v_cndmask_b32_e64 v41, 0, v41, s[36:37]
	v_add_u32_e32 v86, 25, v84
	v_cmp_gt_u32_e64 s[36:37], s98, v86
	v_cndmask_b32_e64 v42, 0, v42, s[78:79]
	v_add_u32_e32 v87, 26, v84
	v_cmp_gt_u32_e64 s[78:79], s98, v87
	v_cndmask_b32_e64 v43, 0, v43, s[50:51]
	v_add_u32_e32 v88, 27, v84
	v_cmp_gt_u32_e64 s[50:51], s98, v88
	v_nop
	v_cndmask_b32_e64 v44, 0, v44, s[30:31]
	v_cndmask_b32_e64 v45, 0, v45, s[36:37]
	v_cndmask_b32_e64 v46, 0, v46, s[78:79]
	v_cndmask_b32_e64 v47, 0, v47, s[50:51]
	v_cvt_pk_bf16_f32 v64, v32, v33
	v_cvt_pk_bf16_f32 v65, v34, v35
	v_cvt_pk_bf16_f32 v66, v36, v37
	v_cvt_pk_bf16_f32 v67, v38, v39
	v_cvt_pk_bf16_f32 v68, v40, v41
	v_cvt_pk_bf16_f32 v69, v42, v43
	v_cvt_pk_bf16_f32 v70, v44, v45
	v_cvt_pk_bf16_f32 v71, v46, v47
	v_pk_add_f32 v[232:233], v[232:233], v[32:33]
	v_pk_add_f32 v[232:233], v[232:233], v[34:35]
	v_pk_add_f32 v[232:233], v[232:233], v[36:37]
	v_pk_add_f32 v[232:233], v[232:233], v[38:39]
	v_pk_add_f32 v[232:233], v[232:233], v[40:41]
	v_pk_add_f32 v[232:233], v[232:233], v[42:43]
	v_pk_add_f32 v[232:233], v[232:233], v[44:45]
	v_pk_add_f32 v[232:233], v[232:233], v[46:47]
	ds_read2_b32 v[32:33], v115 offset0:136 offset1:137
	ds_read2_b32 v[34:35], v115 offset0:138 offset1:139
	ds_read2_b32 v[36:37], v115 offset0:144 offset1:145
	ds_read2_b32 v[38:39], v115 offset0:146 offset1:147
	ds_read2_b32 v[40:41], v115 offset0:153 offset1:154
	ds_read2_b32 v[42:43], v115 offset0:155 offset1:156
	ds_read2_b32 v[44:45], v115 offset0:161 offset1:162
	ds_read2_b32 v[46:47], v115 offset0:163 offset1:164
	v_mfma_f32_32x32x16_bf16 v[0:15], v[64:67], v[72:75], v[0:15]
	v_mfma_f32_32x32x16_bf16 v[16:31], v[64:67], v[76:79], v[16:31]
	v_mfma_f32_32x32x16_bf16 v[0:15], v[68:71], v[220:223], v[0:15]
	v_mfma_f32_32x32x16_bf16 v[16:31], v[68:71], v[224:227], v[16:31]
	s_add_i32 s90, s67, 544
	v_add_u32_e32 v80, s90, v235
	v_add_u32_e32 v83, s90, v236
	v_add_u32_e32 v99, s90, v237
	v_add_u32_e32 v253, s90, v238
	v_add_u32_e32 v254, s90, v100
	v_add_u32_e32 v255, s90, v149
	v_med3_i32 v80, v80, 0, s99
	v_med3_i32 v83, v83, 0, s99
	v_med3_i32 v99, v99, 0, s99
	v_med3_i32 v253, v253, 0, s99
	v_med3_i32 v254, v254, 0, s99
	v_med3_i32 v255, v255, 0, s99
	v_mad_u32_u24 v80, v80, s100, v252
	v_mad_u32_u24 v83, v83, s100, v252
	v_mad_u32_u24 v99, v99, s100, v252
	v_mad_u32_u24 v253, v253, s100, v252
	v_mad_u32_u24 v254, v254, s100, v153
	v_mad_u32_u24 v255, v255, s100, v153
	global_load_dwordx4 v[156:159], v80, s[82:83]
	global_load_dwordx4 v[160:163], v83, s[82:83]
	global_load_dwordx4 v[164:167], v99, s[82:83]
	global_load_dwordx4 v[168:171], v253, s[82:83]
	global_load_dwordx4 v[172:175], v254, s[82:83] offset:768
	global_load_dwordx4 v[176:179], v255, s[82:83] offset:768
	global_load_dwordx4 v[180:183], v254, s[82:83] offset:832
	global_load_dwordx4 v[184:187], v255, s[82:83] offset:832
	ds_read_b64_tr_b16 v[72:73], v231
	ds_read_b64_tr_b16 v[74:75], v231 offset:512
	ds_read_b64_tr_b16 v[76:77], v231 offset:2048
	ds_read_b64_tr_b16 v[78:79], v231 offset:2560
	ds_read_b64_tr_b16 v[220:221], v231 offset:1024
	ds_read_b64_tr_b16 v[222:223], v231 offset:1536
	ds_read_b64_tr_b16 v[224:225], v231 offset:3072
	ds_read_b64_tr_b16 v[226:227], v231 offset:3584
	s_waitcnt vmcnt(8)
	ds_write_b128 v247, v[116:119]
	ds_write_b128 v247, v[120:123] offset:1024
	ds_write_b128 v111, v[124:127] offset:2048
	ds_write_b128 v111, v[128:131] offset:3072
	ds_read_b128 v[116:119], v248
	ds_read_b128 v[120:123], v249
	ds_read_b128 v[124:127], v250
	ds_read_b128 v[128:131], v251
	ds_write_b128 v112, v[132:135]
	ds_write_b128 v112, v[136:139] offset:1024
	ds_write_b128 v112, v[140:143] offset:2048
	ds_write_b128 v112, v[144:147] offset:3072
	v_exp_f32_e32 v188, v188
	v_exp_f32_e32 v189, v189
	v_exp_f32_e32 v190, v190
	v_exp_f32_e32 v191, v191
	v_exp_f32_e32 v192, v192
	v_exp_f32_e32 v193, v193
	s_waitcnt lgkmcnt(4)
	v_mfma_f32_32x32x16_bf16 v[32:47], v[116:119], v[48:51], v[32:47]
	v_exp_f32_e32 v194, v194
	v_exp_f32_e32 v195, v195
	v_mfma_f32_32x32x16_bf16 v[32:47], v[120:123], v[52:55], v[32:47]
	v_exp_f32_e32 v196, v196
	v_exp_f32_e32 v197, v197
	v_exp_f32_e32 v198, v198
	v_mfma_f32_32x32x16_bf16 v[32:47], v[124:127], v[56:59], v[32:47]
	v_exp_f32_e32 v199, v199
	v_exp_f32_e32 v200, v200
	v_mfma_f32_32x32x16_bf16 v[32:47], v[128:131], v[60:63], v[32:47]
	v_exp_f32_e32 v201, v201
	v_exp_f32_e32 v202, v202
	v_exp_f32_e32 v203, v203
	s_add_i32 s90, s67, 480
	v_add_u32_e32 v84, s90, v107
	v_add_u32_e32 v85, 0, v84
	v_add_u32_e32 v86, 1, v84
	v_add_u32_e32 v87, 2, v84
	v_add_u32_e32 v88, 3, v84
	v_cmp_gt_u32_e64 s[30:31], s98, v85
	v_cmp_gt_u32_e64 s[36:37], s98, v86
	v_cmp_gt_u32_e64 s[78:79], s98, v87
	v_cmp_gt_u32_e64 s[50:51], s98, v88
	v_cndmask_b32_e64 v188, 0, v188, s[30:31]
	v_add_u32_e32 v85, 8, v84
	v_cmp_gt_u32_e64 s[30:31], s98, v85
	v_cndmask_b32_e64 v189, 0, v189, s[36:37]
	v_add_u32_e32 v86, 9, v84
	v_cmp_gt_u32_e64 s[36:37], s98, v86
	v_cndmask_b32_e64 v190, 0, v190, s[78:79]
	v_add_u32_e32 v87, 10, v84
	v_cmp_gt_u32_e64 s[78:79], s98, v87
	v_cndmask_b32_e64 v191, 0, v191, s[50:51]
	v_add_u32_e32 v88, 11, v84
	v_cmp_gt_u32_e64 s[50:51], s98, v88
	v_cndmask_b32_e64 v192, 0, v192, s[30:31]
	v_add_u32_e32 v85, 16, v84
	v_cmp_gt_u32_e64 s[30:31], s98, v85
	v_cndmask_b32_e64 v193, 0, v193, s[36:37]
	v_add_u32_e32 v86, 17, v84
	v_cmp_gt_u32_e64 s[36:37], s98, v86
	v_cndmask_b32_e64 v194, 0, v194, s[78:79]
	v_add_u32_e32 v87, 18, v84
	v_cmp_gt_u32_e64 s[78:79], s98, v87
	v_cndmask_b32_e64 v195, 0, v195, s[50:51]
	v_add_u32_e32 v88, 19, v84
	v_cmp_gt_u32_e64 s[50:51], s98, v88
	v_cndmask_b32_e64 v196, 0, v196, s[30:31]
	v_add_u32_e32 v85, 24, v84
	v_cmp_gt_u32_e64 s[30:31], s98, v85
	v_cndmask_b32_e64 v197, 0, v197, s[36:37]
	v_add_u32_e32 v86, 25, v84
	v_cmp_gt_u32_e64 s[36:37], s98, v86
	v_cndmask_b32_e64 v198, 0, v198, s[78:79]
	v_add_u32_e32 v87, 26, v84
	v_cmp_gt_u32_e64 s[78:79], s98, v87
	v_cndmask_b32_e64 v199, 0, v199, s[50:51]
	v_add_u32_e32 v88, 27, v84
	v_cmp_gt_u32_e64 s[50:51], s98, v88
	v_nop
	v_cndmask_b32_e64 v200, 0, v200, s[30:31]
	v_cndmask_b32_e64 v201, 0, v201, s[36:37]
	v_cndmask_b32_e64 v202, 0, v202, s[78:79]
	v_cndmask_b32_e64 v203, 0, v203, s[50:51]
	v_cvt_pk_bf16_f32 v64, v188, v189
	v_cvt_pk_bf16_f32 v65, v190, v191
	v_cvt_pk_bf16_f32 v66, v192, v193
	v_cvt_pk_bf16_f32 v67, v194, v195
	v_cvt_pk_bf16_f32 v68, v196, v197
	v_cvt_pk_bf16_f32 v69, v198, v199
	v_cvt_pk_bf16_f32 v70, v200, v201
	v_cvt_pk_bf16_f32 v71, v202, v203
	v_pk_add_f32 v[232:233], v[232:233], v[188:189]
	v_pk_add_f32 v[232:233], v[232:233], v[190:191]
	v_pk_add_f32 v[232:233], v[232:233], v[192:193]
	v_pk_add_f32 v[232:233], v[232:233], v[194:195]
	v_pk_add_f32 v[232:233], v[232:233], v[196:197]
	v_pk_add_f32 v[232:233], v[232:233], v[198:199]
	v_pk_add_f32 v[232:233], v[232:233], v[200:201]
	v_pk_add_f32 v[232:233], v[232:233], v[202:203]
	ds_read2_b32 v[188:189], v115 offset0:170 offset1:171
	ds_read2_b32 v[190:191], v115 offset0:172 offset1:173
	ds_read2_b32 v[192:193], v115 offset0:178 offset1:179
	ds_read2_b32 v[194:195], v115 offset0:180 offset1:181
	ds_read2_b32 v[196:197], v115 offset0:187 offset1:188
	ds_read2_b32 v[198:199], v115 offset0:189 offset1:190
	ds_read2_b32 v[200:201], v115 offset0:195 offset1:196
	ds_read2_b32 v[202:203], v115 offset0:197 offset1:198
	v_mfma_f32_32x32x16_bf16 v[0:15], v[64:67], v[72:75], v[0:15]
	v_mfma_f32_32x32x16_bf16 v[16:31], v[64:67], v[76:79], v[16:31]
	v_mfma_f32_32x32x16_bf16 v[0:15], v[68:71], v[220:223], v[0:15]
	v_mfma_f32_32x32x16_bf16 v[16:31], v[68:71], v[224:227], v[16:31]
	s_add_i32 s90, s67, -256
	v_add_u32_e32 v80, s90, v239
	v_add_u32_e32 v83, s90, v240
	v_add_u32_e32 v99, s90, v241
	v_add_u32_e32 v253, s90, v242
	v_add_u32_e32 v254, s90, v101
	v_add_u32_e32 v255, s90, v150
	v_med3_i32 v80, v80, 0, s99
	v_med3_i32 v83, v83, 0, s99
	v_med3_i32 v99, v99, 0, s99
	v_med3_i32 v253, v253, 0, s99
	v_med3_i32 v254, v254, 0, s99
	v_med3_i32 v255, v255, 0, s99
	v_mad_u32_u24 v80, v80, s100, v252
	v_mad_u32_u24 v83, v83, s100, v252
	v_mad_u32_u24 v99, v99, s100, v252
	v_mad_u32_u24 v253, v253, s100, v252
	v_mad_u32_u24 v254, v254, s100, v153
	v_mad_u32_u24 v255, v255, s100, v153
	global_load_dwordx4 v[116:119], v80, s[82:83]
	global_load_dwordx4 v[120:123], v83, s[82:83]
	global_load_dwordx4 v[124:127], v99, s[82:83]
	global_load_dwordx4 v[128:131], v253, s[82:83]
	global_load_dwordx4 v[132:135], v254, s[82:83] offset:768
	global_load_dwordx4 v[136:139], v255, s[82:83] offset:768
	global_load_dwordx4 v[140:143], v254, s[82:83] offset:832
	global_load_dwordx4 v[144:147], v255, s[82:83] offset:832
	ds_read_b64_tr_b16 v[72:73], v231
	ds_read_b64_tr_b16 v[74:75], v231 offset:512
	ds_read_b64_tr_b16 v[76:77], v231 offset:2048
	ds_read_b64_tr_b16 v[78:79], v231 offset:2560
	ds_read_b64_tr_b16 v[220:221], v231 offset:1024
	ds_read_b64_tr_b16 v[222:223], v231 offset:1536
	ds_read_b64_tr_b16 v[224:225], v231 offset:3072
	ds_read_b64_tr_b16 v[226:227], v231 offset:3584
	s_waitcnt vmcnt(8)
	ds_write_b128 v247, v[156:159]
	ds_write_b128 v247, v[160:163] offset:1024
	ds_write_b128 v111, v[164:167] offset:2048
	ds_write_b128 v111, v[168:171] offset:3072
	ds_read_b128 v[156:159], v248
	ds_read_b128 v[160:163], v249
	ds_read_b128 v[164:167], v250
	ds_read_b128 v[168:171], v251
	ds_write_b128 v112, v[172:175]
	ds_write_b128 v112, v[176:179] offset:1024
	ds_write_b128 v112, v[180:183] offset:2048
	ds_write_b128 v112, v[184:187] offset:3072
	v_exp_f32_e32 v32, v32
	v_exp_f32_e32 v33, v33
	v_exp_f32_e32 v34, v34
	v_exp_f32_e32 v35, v35
	v_exp_f32_e32 v36, v36
	v_exp_f32_e32 v37, v37
	s_waitcnt lgkmcnt(4)
	v_mfma_f32_32x32x16_bf16 v[188:203], v[156:159], v[48:51], v[188:203]
	v_exp_f32_e32 v38, v38
	v_exp_f32_e32 v39, v39
	v_mfma_f32_32x32x16_bf16 v[188:203], v[160:163], v[52:55], v[188:203]
	v_exp_f32_e32 v40, v40
	v_exp_f32_e32 v41, v41
	v_exp_f32_e32 v42, v42
	v_mfma_f32_32x32x16_bf16 v[188:203], v[164:167], v[56:59], v[188:203]
	v_exp_f32_e32 v43, v43
	v_exp_f32_e32 v44, v44
	v_mfma_f32_32x32x16_bf16 v[188:203], v[168:171], v[60:63], v[188:203]
	v_exp_f32_e32 v45, v45
	v_exp_f32_e32 v46, v46
	v_exp_f32_e32 v47, v47
	s_add_i32 s90, s67, 512
	v_add_u32_e32 v84, s90, v107
	v_add_u32_e32 v85, 0, v84
	v_add_u32_e32 v86, 1, v84
	v_add_u32_e32 v87, 2, v84
	v_add_u32_e32 v88, 3, v84
	v_cmp_gt_u32_e64 s[30:31], s98, v85
	v_cmp_gt_u32_e64 s[36:37], s98, v86
	v_cmp_gt_u32_e64 s[78:79], s98, v87
	v_cmp_gt_u32_e64 s[50:51], s98, v88
	v_cndmask_b32_e64 v32, 0, v32, s[30:31]
	v_add_u32_e32 v85, 8, v84
	v_cmp_gt_u32_e64 s[30:31], s98, v85
	v_cndmask_b32_e64 v33, 0, v33, s[36:37]
	v_add_u32_e32 v86, 9, v84
	v_cmp_gt_u32_e64 s[36:37], s98, v86
	v_cndmask_b32_e64 v34, 0, v34, s[78:79]
	v_add_u32_e32 v87, 10, v84
	v_cmp_gt_u32_e64 s[78:79], s98, v87
	v_cndmask_b32_e64 v35, 0, v35, s[50:51]
	v_add_u32_e32 v88, 11, v84
	v_cmp_gt_u32_e64 s[50:51], s98, v88
	v_cndmask_b32_e64 v36, 0, v36, s[30:31]
	v_add_u32_e32 v85, 16, v84
	v_cmp_gt_u32_e64 s[30:31], s98, v85
	v_cndmask_b32_e64 v37, 0, v37, s[36:37]
	v_add_u32_e32 v86, 17, v84
	v_cmp_gt_u32_e64 s[36:37], s98, v86
	v_cndmask_b32_e64 v38, 0, v38, s[78:79]
	v_add_u32_e32 v87, 18, v84
	v_cmp_gt_u32_e64 s[78:79], s98, v87
	v_cndmask_b32_e64 v39, 0, v39, s[50:51]
	v_add_u32_e32 v88, 19, v84
	v_cmp_gt_u32_e64 s[50:51], s98, v88
	v_cndmask_b32_e64 v40, 0, v40, s[30:31]
	v_add_u32_e32 v85, 24, v84
	v_cmp_gt_u32_e64 s[30:31], s98, v85
	v_cndmask_b32_e64 v41, 0, v41, s[36:37]
	v_add_u32_e32 v86, 25, v84
	v_cmp_gt_u32_e64 s[36:37], s98, v86
	v_cndmask_b32_e64 v42, 0, v42, s[78:79]
	v_add_u32_e32 v87, 26, v84
	v_cmp_gt_u32_e64 s[78:79], s98, v87
	v_cndmask_b32_e64 v43, 0, v43, s[50:51]
	v_add_u32_e32 v88, 27, v84
	v_cmp_gt_u32_e64 s[50:51], s98, v88
	v_nop
	v_cndmask_b32_e64 v44, 0, v44, s[30:31]
	v_cndmask_b32_e64 v45, 0, v45, s[36:37]
	v_cndmask_b32_e64 v46, 0, v46, s[78:79]
	v_cndmask_b32_e64 v47, 0, v47, s[50:51]
	v_cvt_pk_bf16_f32 v64, v32, v33
	v_cvt_pk_bf16_f32 v65, v34, v35
	v_cvt_pk_bf16_f32 v66, v36, v37
	v_cvt_pk_bf16_f32 v67, v38, v39
	v_cvt_pk_bf16_f32 v68, v40, v41
	v_cvt_pk_bf16_f32 v69, v42, v43
	v_cvt_pk_bf16_f32 v70, v44, v45
	v_cvt_pk_bf16_f32 v71, v46, v47
	v_pk_add_f32 v[232:233], v[232:233], v[32:33]
	v_pk_add_f32 v[232:233], v[232:233], v[34:35]
	v_pk_add_f32 v[232:233], v[232:233], v[36:37]
	v_pk_add_f32 v[232:233], v[232:233], v[38:39]
	v_pk_add_f32 v[232:233], v[232:233], v[40:41]
	v_pk_add_f32 v[232:233], v[232:233], v[42:43]
	v_pk_add_f32 v[232:233], v[232:233], v[44:45]
	v_pk_add_f32 v[232:233], v[232:233], v[46:47]
	v_mov_b32_e32 v115, v229
	ds_read2_b32 v[32:33], v115 offset0:0 offset1:1
	ds_read2_b32 v[34:35], v115 offset0:2 offset1:3
	ds_read2_b32 v[36:37], v115 offset0:10 offset1:11
	ds_read2_b32 v[38:39], v115 offset0:12 offset1:13
	ds_read2_b32 v[40:41], v115 offset0:20 offset1:21
	ds_read2_b32 v[42:43], v115 offset0:22 offset1:23
	ds_read2_b32 v[44:45], v115 offset0:30 offset1:31
	ds_read2_b32 v[46:47], v115 offset0:32 offset1:33
	v_mfma_f32_32x32x16_bf16 v[0:15], v[64:67], v[72:75], v[0:15]
	v_mfma_f32_32x32x16_bf16 v[16:31], v[64:67], v[76:79], v[16:31]
	v_mfma_f32_32x32x16_bf16 v[0:15], v[68:71], v[220:223], v[0:15]
	v_mfma_f32_32x32x16_bf16 v[16:31], v[68:71], v[224:227], v[16:31]
	s_add_i32 s90, s67, -128
	v_add_u32_e32 v80, s90, v239
	v_add_u32_e32 v83, s90, v240
	v_add_u32_e32 v99, s90, v241
	v_add_u32_e32 v253, s90, v242
	v_add_u32_e32 v254, s90, v101
	v_add_u32_e32 v255, s90, v150
	v_med3_i32 v80, v80, 0, s99
	v_med3_i32 v83, v83, 0, s99
	v_med3_i32 v99, v99, 0, s99
	v_med3_i32 v253, v253, 0, s99
	v_med3_i32 v254, v254, 0, s99
	v_med3_i32 v255, v255, 0, s99
	v_mad_u32_u24 v80, v80, s100, v252
	v_mad_u32_u24 v83, v83, s100, v252
	v_mad_u32_u24 v99, v99, s100, v252
	v_mad_u32_u24 v253, v253, s100, v252
	v_mad_u32_u24 v254, v254, s100, v153
	v_mad_u32_u24 v255, v255, s100, v153
	global_load_dwordx4 v[156:159], v80, s[82:83]
	global_load_dwordx4 v[160:163], v83, s[82:83]
	global_load_dwordx4 v[164:167], v99, s[82:83]
	global_load_dwordx4 v[168:171], v253, s[82:83]
	global_load_dwordx4 v[172:175], v254, s[82:83] offset:768
	global_load_dwordx4 v[176:179], v255, s[82:83] offset:768
	global_load_dwordx4 v[180:183], v254, s[82:83] offset:832
	global_load_dwordx4 v[184:187], v255, s[82:83] offset:832
	ds_read_b64_tr_b16 v[72:73], v231
	ds_read_b64_tr_b16 v[74:75], v231 offset:512
	ds_read_b64_tr_b16 v[76:77], v231 offset:2048
	ds_read_b64_tr_b16 v[78:79], v231 offset:2560
	ds_read_b64_tr_b16 v[220:221], v231 offset:1024
	ds_read_b64_tr_b16 v[222:223], v231 offset:1536
	ds_read_b64_tr_b16 v[224:225], v231 offset:3072
	ds_read_b64_tr_b16 v[226:227], v231 offset:3584
	s_waitcnt vmcnt(8)
	ds_write_b128 v247, v[116:119]
	ds_write_b128 v247, v[120:123] offset:1024
	ds_write_b128 v111, v[124:127] offset:2048
	ds_write_b128 v111, v[128:131] offset:3072
	ds_read_b128 v[116:119], v248
	ds_read_b128 v[120:123], v249
	ds_read_b128 v[124:127], v250
	ds_read_b128 v[128:131], v251
	ds_write_b128 v112, v[132:135]
	ds_write_b128 v112, v[136:139] offset:1024
	ds_write_b128 v112, v[140:143] offset:2048
	ds_write_b128 v112, v[144:147] offset:3072
	v_exp_f32_e32 v188, v188
	v_exp_f32_e32 v189, v189
	v_exp_f32_e32 v190, v190
	v_exp_f32_e32 v191, v191
	v_exp_f32_e32 v192, v192
	v_exp_f32_e32 v193, v193
	s_waitcnt lgkmcnt(4)
	v_mfma_f32_32x32x16_bf16 v[32:47], v[116:119], v[48:51], v[32:47]
	v_exp_f32_e32 v194, v194
	v_exp_f32_e32 v195, v195
	v_mfma_f32_32x32x16_bf16 v[32:47], v[120:123], v[52:55], v[32:47]
	v_exp_f32_e32 v196, v196
	v_exp_f32_e32 v197, v197
	v_exp_f32_e32 v198, v198
	v_mfma_f32_32x32x16_bf16 v[32:47], v[124:127], v[56:59], v[32:47]
	v_exp_f32_e32 v199, v199
	v_exp_f32_e32 v200, v200
	v_mfma_f32_32x32x16_bf16 v[32:47], v[128:131], v[60:63], v[32:47]
	v_exp_f32_e32 v201, v201
	v_exp_f32_e32 v202, v202
	v_exp_f32_e32 v203, v203
	s_add_i32 s90, s67, 544
	v_add_u32_e32 v84, s90, v107
	v_add_u32_e32 v85, 0, v84
	v_add_u32_e32 v86, 1, v84
	v_add_u32_e32 v87, 2, v84
	v_add_u32_e32 v88, 3, v84
	v_cmp_gt_u32_e64 s[30:31], s98, v85
	v_cmp_gt_u32_e64 s[36:37], s98, v86
	v_cmp_gt_u32_e64 s[78:79], s98, v87
	v_cmp_gt_u32_e64 s[50:51], s98, v88
	v_cndmask_b32_e64 v188, 0, v188, s[30:31]
	v_add_u32_e32 v85, 8, v84
	v_cmp_gt_u32_e64 s[30:31], s98, v85
	v_cndmask_b32_e64 v189, 0, v189, s[36:37]
	v_add_u32_e32 v86, 9, v84
	v_cmp_gt_u32_e64 s[36:37], s98, v86
	v_cndmask_b32_e64 v190, 0, v190, s[78:79]
	v_add_u32_e32 v87, 10, v84
	v_cmp_gt_u32_e64 s[78:79], s98, v87
	v_cndmask_b32_e64 v191, 0, v191, s[50:51]
	v_add_u32_e32 v88, 11, v84
	v_cmp_gt_u32_e64 s[50:51], s98, v88
	v_cndmask_b32_e64 v192, 0, v192, s[30:31]
	v_add_u32_e32 v85, 16, v84
	v_cmp_gt_u32_e64 s[30:31], s98, v85
	v_cndmask_b32_e64 v193, 0, v193, s[36:37]
	v_add_u32_e32 v86, 17, v84
	v_cmp_gt_u32_e64 s[36:37], s98, v86
	v_cndmask_b32_e64 v194, 0, v194, s[78:79]
	v_add_u32_e32 v87, 18, v84
	v_cmp_gt_u32_e64 s[78:79], s98, v87
	v_cndmask_b32_e64 v195, 0, v195, s[50:51]
	v_add_u32_e32 v88, 19, v84
	v_cmp_gt_u32_e64 s[50:51], s98, v88
	v_cndmask_b32_e64 v196, 0, v196, s[30:31]
	v_add_u32_e32 v85, 24, v84
	v_cmp_gt_u32_e64 s[30:31], s98, v85
	v_cndmask_b32_e64 v197, 0, v197, s[36:37]
	v_add_u32_e32 v86, 25, v84
	v_cmp_gt_u32_e64 s[36:37], s98, v86
	v_cndmask_b32_e64 v198, 0, v198, s[78:79]
	v_add_u32_e32 v87, 26, v84
	v_cmp_gt_u32_e64 s[78:79], s98, v87
	v_cndmask_b32_e64 v199, 0, v199, s[50:51]
	v_add_u32_e32 v88, 27, v84
	v_cmp_gt_u32_e64 s[50:51], s98, v88
	v_nop
	v_cndmask_b32_e64 v200, 0, v200, s[30:31]
	v_cndmask_b32_e64 v201, 0, v201, s[36:37]
	v_cndmask_b32_e64 v202, 0, v202, s[78:79]
	v_cndmask_b32_e64 v203, 0, v203, s[50:51]
	v_cvt_pk_bf16_f32 v64, v188, v189
	v_cvt_pk_bf16_f32 v65, v190, v191
	v_cvt_pk_bf16_f32 v66, v192, v193
	v_cvt_pk_bf16_f32 v67, v194, v195
	v_cvt_pk_bf16_f32 v68, v196, v197
	v_cvt_pk_bf16_f32 v69, v198, v199
	v_cvt_pk_bf16_f32 v70, v200, v201
	v_cvt_pk_bf16_f32 v71, v202, v203
	v_pk_add_f32 v[232:233], v[232:233], v[188:189]
	v_pk_add_f32 v[232:233], v[232:233], v[190:191]
	v_pk_add_f32 v[232:233], v[232:233], v[192:193]
	v_pk_add_f32 v[232:233], v[232:233], v[194:195]
	v_pk_add_f32 v[232:233], v[232:233], v[196:197]
	v_pk_add_f32 v[232:233], v[232:233], v[198:199]
	v_pk_add_f32 v[232:233], v[232:233], v[200:201]
	v_pk_add_f32 v[232:233], v[232:233], v[202:203]
	ds_read2_b32 v[188:189], v115 offset0:40 offset1:41
	ds_read2_b32 v[190:191], v115 offset0:42 offset1:43
	ds_read2_b32 v[192:193], v115 offset0:50 offset1:51
	ds_read2_b32 v[194:195], v115 offset0:52 offset1:53
	ds_read2_b32 v[196:197], v115 offset0:60 offset1:61
	ds_read2_b32 v[198:199], v115 offset0:62 offset1:63
	ds_read2_b32 v[200:201], v115 offset0:70 offset1:71
	ds_read2_b32 v[202:203], v115 offset0:72 offset1:73
	v_mfma_f32_32x32x16_bf16 v[0:15], v[64:67], v[72:75], v[0:15]
	v_mfma_f32_32x32x16_bf16 v[16:31], v[64:67], v[76:79], v[16:31]
	v_mfma_f32_32x32x16_bf16 v[0:15], v[68:71], v[220:223], v[0:15]
	v_mfma_f32_32x32x16_bf16 v[16:31], v[68:71], v[224:227], v[16:31]
	s_add_i32 s90, s67, 0
	v_add_u32_e32 v80, s90, v239
	v_add_u32_e32 v83, s90, v240
	v_add_u32_e32 v99, s90, v241
	v_add_u32_e32 v253, s90, v242
	v_add_u32_e32 v254, s90, v101
	v_add_u32_e32 v255, s90, v150
	v_med3_i32 v80, v80, 0, s99
	v_med3_i32 v83, v83, 0, s99
	v_med3_i32 v99, v99, 0, s99
	v_med3_i32 v253, v253, 0, s99
	v_med3_i32 v254, v254, 0, s99
	v_med3_i32 v255, v255, 0, s99
	v_mad_u32_u24 v80, v80, s100, v252
	v_mad_u32_u24 v83, v83, s100, v252
	v_mad_u32_u24 v99, v99, s100, v252
	v_mad_u32_u24 v253, v253, s100, v252
	v_mad_u32_u24 v254, v254, s100, v153
	v_mad_u32_u24 v255, v255, s100, v153
	global_load_dwordx4 v[116:119], v80, s[82:83]
	global_load_dwordx4 v[120:123], v83, s[82:83]
	global_load_dwordx4 v[124:127], v99, s[82:83]
	global_load_dwordx4 v[128:131], v253, s[82:83]
	global_load_dwordx4 v[132:135], v254, s[82:83] offset:768
	global_load_dwordx4 v[136:139], v255, s[82:83] offset:768
	global_load_dwordx4 v[140:143], v254, s[82:83] offset:832
	global_load_dwordx4 v[144:147], v255, s[82:83] offset:832
	ds_read_b64_tr_b16 v[72:73], v231
	ds_read_b64_tr_b16 v[74:75], v231 offset:512
	ds_read_b64_tr_b16 v[76:77], v231 offset:2048
	ds_read_b64_tr_b16 v[78:79], v231 offset:2560
	ds_read_b64_tr_b16 v[220:221], v231 offset:1024
	ds_read_b64_tr_b16 v[222:223], v231 offset:1536
	ds_read_b64_tr_b16 v[224:225], v231 offset:3072
	ds_read_b64_tr_b16 v[226:227], v231 offset:3584
	s_waitcnt vmcnt(8)
	ds_write_b128 v247, v[156:159]
	ds_write_b128 v247, v[160:163] offset:1024
	ds_write_b128 v111, v[164:167] offset:2048
	ds_write_b128 v111, v[168:171] offset:3072
	ds_read_b128 v[156:159], v248
	ds_read_b128 v[160:163], v249
	ds_read_b128 v[164:167], v250
	ds_read_b128 v[168:171], v251
	ds_write_b128 v112, v[172:175]
	ds_write_b128 v112, v[176:179] offset:1024
	ds_write_b128 v112, v[180:183] offset:2048
	ds_write_b128 v112, v[184:187] offset:3072
	v_exp_f32_e32 v32, v32
	v_exp_f32_e32 v33, v33
	v_exp_f32_e32 v34, v34
	v_exp_f32_e32 v35, v35
	v_exp_f32_e32 v36, v36
	v_exp_f32_e32 v37, v37
	s_waitcnt lgkmcnt(4)
	v_mfma_f32_32x32x16_bf16 v[188:203], v[156:159], v[48:51], v[188:203]
	v_exp_f32_e32 v38, v38
	v_exp_f32_e32 v39, v39
	v_mfma_f32_32x32x16_bf16 v[188:203], v[160:163], v[52:55], v[188:203]
	v_exp_f32_e32 v40, v40
	v_exp_f32_e32 v41, v41
	v_exp_f32_e32 v42, v42
	v_mfma_f32_32x32x16_bf16 v[188:203], v[164:167], v[56:59], v[188:203]
	v_exp_f32_e32 v43, v43
	v_exp_f32_e32 v44, v44
	v_mfma_f32_32x32x16_bf16 v[188:203], v[168:171], v[60:63], v[188:203]
	v_exp_f32_e32 v45, v45
	v_exp_f32_e32 v46, v46
	v_exp_f32_e32 v47, v47
	s_add_i32 s90, s67, -256
	v_lshlrev_b32_e32 v84, 2, v107
	v_add_u32_e32 v84, s90, v84
	v_add_u32_e32 v85, 0, v84
	v_add_u32_e32 v86, 4, v84
	v_add_u32_e32 v87, 8, v84
	v_add_u32_e32 v88, 12, v84
	v_cmp_gt_u32_e64 s[30:31], s98, v85
	v_cmp_gt_u32_e64 s[36:37], s98, v86
	v_cmp_gt_u32_e64 s[78:79], s98, v87
	v_cmp_gt_u32_e64 s[50:51], s98, v88
	v_cndmask_b32_e64 v32, 0, v32, s[30:31]
	v_add_u32_e32 v85, 32, v84
	v_cmp_gt_u32_e64 s[30:31], s98, v85
	v_cndmask_b32_e64 v33, 0, v33, s[36:37]
	v_add_u32_e32 v86, 36, v84
	v_cmp_gt_u32_e64 s[36:37], s98, v86
	v_cndmask_b32_e64 v34, 0, v34, s[78:79]
	v_add_u32_e32 v87, 40, v84
	v_cmp_gt_u32_e64 s[78:79], s98, v87
	v_cndmask_b32_e64 v35, 0, v35, s[50:51]
	v_add_u32_e32 v88, 44, v84
	v_cmp_gt_u32_e64 s[50:51], s98, v88
	v_cndmask_b32_e64 v36, 0, v36, s[30:31]
	v_add_u32_e32 v85, 64, v84
	v_cmp_gt_u32_e64 s[30:31], s98, v85
	v_cndmask_b32_e64 v37, 0, v37, s[36:37]
	v_add_u32_e32 v86, 68, v84
	v_cmp_gt_u32_e64 s[36:37], s98, v86
	v_cndmask_b32_e64 v38, 0, v38, s[78:79]
	v_add_u32_e32 v87, 72, v84
	v_cmp_gt_u32_e64 s[78:79], s98, v87
	v_cndmask_b32_e64 v39, 0, v39, s[50:51]
	v_add_u32_e32 v88, 76, v84
	v_cmp_gt_u32_e64 s[50:51], s98, v88
	v_cndmask_b32_e64 v40, 0, v40, s[30:31]
	v_add_u32_e32 v85, 96, v84
	v_cmp_gt_u32_e64 s[30:31], s98, v85
	v_cndmask_b32_e64 v41, 0, v41, s[36:37]
	v_add_u32_e32 v86, 100, v84
	v_cmp_gt_u32_e64 s[36:37], s98, v86
	v_cndmask_b32_e64 v42, 0, v42, s[78:79]
	v_add_u32_e32 v87, 104, v84
	v_cmp_gt_u32_e64 s[78:79], s98, v87
	v_cndmask_b32_e64 v43, 0, v43, s[50:51]
	v_add_u32_e32 v88, 108, v84
	v_cmp_gt_u32_e64 s[50:51], s98, v88
	v_nop
	v_cndmask_b32_e64 v44, 0, v44, s[30:31]
	v_cndmask_b32_e64 v45, 0, v45, s[36:37]
	v_cndmask_b32_e64 v46, 0, v46, s[78:79]
	v_cndmask_b32_e64 v47, 0, v47, s[50:51]
	v_cvt_pk_bf16_f32 v64, v32, v33
	v_cvt_pk_bf16_f32 v65, v34, v35
	v_cvt_pk_bf16_f32 v66, v36, v37
	v_cvt_pk_bf16_f32 v67, v38, v39
	v_cvt_pk_bf16_f32 v68, v40, v41
	v_cvt_pk_bf16_f32 v69, v42, v43
	v_cvt_pk_bf16_f32 v70, v44, v45
	v_cvt_pk_bf16_f32 v71, v46, v47
	v_pk_add_f32 v[232:233], v[232:233], v[32:33]
	v_pk_add_f32 v[232:233], v[232:233], v[34:35]
	v_pk_add_f32 v[232:233], v[232:233], v[36:37]
	v_pk_add_f32 v[232:233], v[232:233], v[38:39]
	v_pk_add_f32 v[232:233], v[232:233], v[40:41]
	v_pk_add_f32 v[232:233], v[232:233], v[42:43]
	v_pk_add_f32 v[232:233], v[232:233], v[44:45]
	v_pk_add_f32 v[232:233], v[232:233], v[46:47]
	ds_read2_b32 v[32:33], v115 offset0:80 offset1:81
	ds_read2_b32 v[34:35], v115 offset0:82 offset1:83
	ds_read2_b32 v[36:37], v115 offset0:90 offset1:91
	ds_read2_b32 v[38:39], v115 offset0:92 offset1:93
	ds_read2_b32 v[40:41], v115 offset0:100 offset1:101
	ds_read2_b32 v[42:43], v115 offset0:102 offset1:103
	ds_read2_b32 v[44:45], v115 offset0:110 offset1:111
	ds_read2_b32 v[46:47], v115 offset0:112 offset1:113
	v_mfma_f32_32x32x16_bf16 v[0:15], v[64:67], v[72:75], v[0:15]
	v_mfma_f32_32x32x16_bf16 v[16:31], v[64:67], v[76:79], v[16:31]
	v_mfma_f32_32x32x16_bf16 v[0:15], v[68:71], v[220:223], v[0:15]
	v_mfma_f32_32x32x16_bf16 v[16:31], v[68:71], v[224:227], v[16:31]
	s_add_i32 s90, s67, 128
	v_add_u32_e32 v80, s90, v239
	v_add_u32_e32 v83, s90, v240
	v_add_u32_e32 v99, s90, v241
	v_add_u32_e32 v253, s90, v242
	v_add_u32_e32 v254, s90, v101
	v_add_u32_e32 v255, s90, v150
	v_med3_i32 v80, v80, 0, s99
	v_med3_i32 v83, v83, 0, s99
	v_med3_i32 v99, v99, 0, s99
	v_med3_i32 v253, v253, 0, s99
	v_med3_i32 v254, v254, 0, s99
	v_med3_i32 v255, v255, 0, s99
	v_mad_u32_u24 v80, v80, s100, v252
	v_mad_u32_u24 v83, v83, s100, v252
	v_mad_u32_u24 v99, v99, s100, v252
	v_mad_u32_u24 v253, v253, s100, v252
	v_mad_u32_u24 v254, v254, s100, v153
	v_mad_u32_u24 v255, v255, s100, v153
	global_load_dwordx4 v[156:159], v80, s[82:83]
	global_load_dwordx4 v[160:163], v83, s[82:83]
	global_load_dwordx4 v[164:167], v99, s[82:83]
	global_load_dwordx4 v[168:171], v253, s[82:83]
	global_load_dwordx4 v[172:175], v254, s[82:83] offset:768
	global_load_dwordx4 v[176:179], v255, s[82:83] offset:768
	global_load_dwordx4 v[180:183], v254, s[82:83] offset:832
	global_load_dwordx4 v[184:187], v255, s[82:83] offset:832
	ds_read_b64_tr_b16 v[72:73], v231
	ds_read_b64_tr_b16 v[74:75], v231 offset:512
	ds_read_b64_tr_b16 v[76:77], v231 offset:2048
	ds_read_b64_tr_b16 v[78:79], v231 offset:2560
	ds_read_b64_tr_b16 v[220:221], v231 offset:1024
	ds_read_b64_tr_b16 v[222:223], v231 offset:1536
	ds_read_b64_tr_b16 v[224:225], v231 offset:3072
	ds_read_b64_tr_b16 v[226:227], v231 offset:3584
	s_waitcnt vmcnt(8)
	ds_write_b128 v247, v[116:119]
	ds_write_b128 v247, v[120:123] offset:1024
	ds_write_b128 v111, v[124:127] offset:2048
	ds_write_b128 v111, v[128:131] offset:3072
	ds_read_b128 v[116:119], v248
	ds_read_b128 v[120:123], v249
	ds_read_b128 v[124:127], v250
	ds_read_b128 v[128:131], v251
	ds_write_b128 v112, v[132:135]
	ds_write_b128 v112, v[136:139] offset:1024
	ds_write_b128 v112, v[140:143] offset:2048
	ds_write_b128 v112, v[144:147] offset:3072
	v_exp_f32_e32 v188, v188
	v_exp_f32_e32 v189, v189
	v_exp_f32_e32 v190, v190
	v_exp_f32_e32 v191, v191
	v_exp_f32_e32 v192, v192
	v_exp_f32_e32 v193, v193
	s_waitcnt lgkmcnt(4)
	v_mfma_f32_32x32x16_bf16 v[32:47], v[116:119], v[48:51], v[32:47]
	v_exp_f32_e32 v194, v194
	v_exp_f32_e32 v195, v195
	v_mfma_f32_32x32x16_bf16 v[32:47], v[120:123], v[52:55], v[32:47]
	v_exp_f32_e32 v196, v196
	v_exp_f32_e32 v197, v197
	v_exp_f32_e32 v198, v198
	v_mfma_f32_32x32x16_bf16 v[32:47], v[124:127], v[56:59], v[32:47]
	v_exp_f32_e32 v199, v199
	v_exp_f32_e32 v200, v200
	v_mfma_f32_32x32x16_bf16 v[32:47], v[128:131], v[60:63], v[32:47]
	v_exp_f32_e32 v201, v201
	v_exp_f32_e32 v202, v202
	v_exp_f32_e32 v203, v203
	s_add_i32 s90, s67, -128
	v_lshlrev_b32_e32 v84, 2, v107
	v_add_u32_e32 v84, s90, v84
	v_add_u32_e32 v85, 0, v84
	v_add_u32_e32 v86, 4, v84
	v_add_u32_e32 v87, 8, v84
	v_add_u32_e32 v88, 12, v84
	v_cmp_gt_u32_e64 s[30:31], s98, v85
	v_cmp_gt_u32_e64 s[36:37], s98, v86
	v_cmp_gt_u32_e64 s[78:79], s98, v87
	v_cmp_gt_u32_e64 s[50:51], s98, v88
	v_cndmask_b32_e64 v188, 0, v188, s[30:31]
	v_add_u32_e32 v85, 32, v84
	v_cmp_gt_u32_e64 s[30:31], s98, v85
	v_cndmask_b32_e64 v189, 0, v189, s[36:37]
	v_add_u32_e32 v86, 36, v84
	v_cmp_gt_u32_e64 s[36:37], s98, v86
	v_cndmask_b32_e64 v190, 0, v190, s[78:79]
	v_add_u32_e32 v87, 40, v84
	v_cmp_gt_u32_e64 s[78:79], s98, v87
	v_cndmask_b32_e64 v191, 0, v191, s[50:51]
	v_add_u32_e32 v88, 44, v84
	v_cmp_gt_u32_e64 s[50:51], s98, v88
	v_cndmask_b32_e64 v192, 0, v192, s[30:31]
	v_add_u32_e32 v85, 64, v84
	v_cmp_gt_u32_e64 s[30:31], s98, v85
	v_cndmask_b32_e64 v193, 0, v193, s[36:37]
	v_add_u32_e32 v86, 68, v84
	v_cmp_gt_u32_e64 s[36:37], s98, v86
	v_cndmask_b32_e64 v194, 0, v194, s[78:79]
	v_add_u32_e32 v87, 72, v84
	v_cmp_gt_u32_e64 s[78:79], s98, v87
	v_cndmask_b32_e64 v195, 0, v195, s[50:51]
	v_add_u32_e32 v88, 76, v84
	v_cmp_gt_u32_e64 s[50:51], s98, v88
	v_cndmask_b32_e64 v196, 0, v196, s[30:31]
	v_add_u32_e32 v85, 96, v84
	v_cmp_gt_u32_e64 s[30:31], s98, v85
	v_cndmask_b32_e64 v197, 0, v197, s[36:37]
	v_add_u32_e32 v86, 100, v84
	v_cmp_gt_u32_e64 s[36:37], s98, v86
	v_cndmask_b32_e64 v198, 0, v198, s[78:79]
	v_add_u32_e32 v87, 104, v84
	v_cmp_gt_u32_e64 s[78:79], s98, v87
	v_cndmask_b32_e64 v199, 0, v199, s[50:51]
	v_add_u32_e32 v88, 108, v84
	v_cmp_gt_u32_e64 s[50:51], s98, v88
	v_nop
	v_cndmask_b32_e64 v200, 0, v200, s[30:31]
	v_cndmask_b32_e64 v201, 0, v201, s[36:37]
	v_cndmask_b32_e64 v202, 0, v202, s[78:79]
	v_cndmask_b32_e64 v203, 0, v203, s[50:51]
	v_cvt_pk_bf16_f32 v64, v188, v189
	v_cvt_pk_bf16_f32 v65, v190, v191
	v_cvt_pk_bf16_f32 v66, v192, v193
	v_cvt_pk_bf16_f32 v67, v194, v195
	v_cvt_pk_bf16_f32 v68, v196, v197
	v_cvt_pk_bf16_f32 v69, v198, v199
	v_cvt_pk_bf16_f32 v70, v200, v201
	v_cvt_pk_bf16_f32 v71, v202, v203
	v_pk_add_f32 v[232:233], v[232:233], v[188:189]
	v_pk_add_f32 v[232:233], v[232:233], v[190:191]
	v_pk_add_f32 v[232:233], v[232:233], v[192:193]
	v_pk_add_f32 v[232:233], v[232:233], v[194:195]
	v_pk_add_f32 v[232:233], v[232:233], v[196:197]
	v_pk_add_f32 v[232:233], v[232:233], v[198:199]
	v_pk_add_f32 v[232:233], v[232:233], v[200:201]
	v_pk_add_f32 v[232:233], v[232:233], v[202:203]
	ds_read2_b32 v[188:189], v115 offset0:120 offset1:121
	ds_read2_b32 v[190:191], v115 offset0:122 offset1:123
	ds_read2_b32 v[192:193], v115 offset0:130 offset1:131
	ds_read2_b32 v[194:195], v115 offset0:132 offset1:133
	ds_read2_b32 v[196:197], v115 offset0:140 offset1:141
	ds_read2_b32 v[198:199], v115 offset0:142 offset1:143
	ds_read2_b32 v[200:201], v115 offset0:150 offset1:151
	ds_read2_b32 v[202:203], v115 offset0:152 offset1:153
	v_mfma_f32_32x32x16_bf16 v[0:15], v[64:67], v[72:75], v[0:15]
	v_mfma_f32_32x32x16_bf16 v[16:31], v[64:67], v[76:79], v[16:31]
	v_mfma_f32_32x32x16_bf16 v[0:15], v[68:71], v[220:223], v[0:15]
	v_mfma_f32_32x32x16_bf16 v[16:31], v[68:71], v[224:227], v[16:31]
	s_add_i32 s90, s67, 256
	v_add_u32_e32 v80, s90, v239
	v_add_u32_e32 v83, s90, v240
	v_add_u32_e32 v99, s90, v241
	v_add_u32_e32 v253, s90, v242
	v_add_u32_e32 v254, s90, v101
	v_add_u32_e32 v255, s90, v150
	v_med3_i32 v80, v80, 0, s99
	v_med3_i32 v83, v83, 0, s99
	v_med3_i32 v99, v99, 0, s99
	v_med3_i32 v253, v253, 0, s99
	v_med3_i32 v254, v254, 0, s99
	v_med3_i32 v255, v255, 0, s99
	v_mad_u32_u24 v80, v80, s100, v252
	v_mad_u32_u24 v83, v83, s100, v252
	v_mad_u32_u24 v99, v99, s100, v252
	v_mad_u32_u24 v253, v253, s100, v252
	v_mad_u32_u24 v254, v254, s100, v153
	v_mad_u32_u24 v255, v255, s100, v153
	global_load_dwordx4 v[116:119], v80, s[82:83]
	global_load_dwordx4 v[120:123], v83, s[82:83]
	global_load_dwordx4 v[124:127], v99, s[82:83]
	global_load_dwordx4 v[128:131], v253, s[82:83]
	global_load_dwordx4 v[132:135], v254, s[82:83] offset:768
	global_load_dwordx4 v[136:139], v255, s[82:83] offset:768
	global_load_dwordx4 v[140:143], v254, s[82:83] offset:832
	global_load_dwordx4 v[144:147], v255, s[82:83] offset:832
	ds_read_b64_tr_b16 v[72:73], v231
	ds_read_b64_tr_b16 v[74:75], v231 offset:512
	ds_read_b64_tr_b16 v[76:77], v231 offset:2048
	ds_read_b64_tr_b16 v[78:79], v231 offset:2560
	ds_read_b64_tr_b16 v[220:221], v231 offset:1024
	ds_read_b64_tr_b16 v[222:223], v231 offset:1536
	ds_read_b64_tr_b16 v[224:225], v231 offset:3072
	ds_read_b64_tr_b16 v[226:227], v231 offset:3584
	s_waitcnt vmcnt(8)
	ds_write_b128 v247, v[156:159]
	ds_write_b128 v247, v[160:163] offset:1024
	ds_write_b128 v111, v[164:167] offset:2048
	ds_write_b128 v111, v[168:171] offset:3072
	ds_read_b128 v[156:159], v248
	ds_read_b128 v[160:163], v249
	ds_read_b128 v[164:167], v250
	ds_read_b128 v[168:171], v251
	ds_write_b128 v112, v[172:175]
	ds_write_b128 v112, v[176:179] offset:1024
	ds_write_b128 v112, v[180:183] offset:2048
	ds_write_b128 v112, v[184:187] offset:3072
	v_exp_f32_e32 v32, v32
	v_exp_f32_e32 v33, v33
	v_exp_f32_e32 v34, v34
	v_exp_f32_e32 v35, v35
	v_exp_f32_e32 v36, v36
	v_exp_f32_e32 v37, v37
	s_waitcnt lgkmcnt(4)
	v_mfma_f32_32x32x16_bf16 v[188:203], v[156:159], v[48:51], v[188:203]
	v_exp_f32_e32 v38, v38
	v_exp_f32_e32 v39, v39
	v_mfma_f32_32x32x16_bf16 v[188:203], v[160:163], v[52:55], v[188:203]
	v_exp_f32_e32 v40, v40
	v_exp_f32_e32 v41, v41
	v_exp_f32_e32 v42, v42
	v_mfma_f32_32x32x16_bf16 v[188:203], v[164:167], v[56:59], v[188:203]
	v_exp_f32_e32 v43, v43
	v_exp_f32_e32 v44, v44
	v_mfma_f32_32x32x16_bf16 v[188:203], v[168:171], v[60:63], v[188:203]
	v_exp_f32_e32 v45, v45
	v_exp_f32_e32 v46, v46
	v_exp_f32_e32 v47, v47
	s_add_i32 s90, s67, 0
	v_lshlrev_b32_e32 v84, 2, v107
	v_add_u32_e32 v84, s90, v84
	v_add_u32_e32 v85, 0, v84
	v_add_u32_e32 v86, 4, v84
	v_add_u32_e32 v87, 8, v84
	v_add_u32_e32 v88, 12, v84
	v_cmp_gt_u32_e64 s[30:31], s98, v85
	v_cmp_gt_u32_e64 s[36:37], s98, v86
	v_cmp_gt_u32_e64 s[78:79], s98, v87
	v_cmp_gt_u32_e64 s[50:51], s98, v88
	v_cndmask_b32_e64 v32, 0, v32, s[30:31]
	v_add_u32_e32 v85, 32, v84
	v_cmp_gt_u32_e64 s[30:31], s98, v85
	v_cndmask_b32_e64 v33, 0, v33, s[36:37]
	v_add_u32_e32 v86, 36, v84
	v_cmp_gt_u32_e64 s[36:37], s98, v86
	v_cndmask_b32_e64 v34, 0, v34, s[78:79]
	v_add_u32_e32 v87, 40, v84
	v_cmp_gt_u32_e64 s[78:79], s98, v87
	v_cndmask_b32_e64 v35, 0, v35, s[50:51]
	v_add_u32_e32 v88, 44, v84
	v_cmp_gt_u32_e64 s[50:51], s98, v88
	v_cndmask_b32_e64 v36, 0, v36, s[30:31]
	v_add_u32_e32 v85, 64, v84
	v_cmp_gt_u32_e64 s[30:31], s98, v85
	v_cndmask_b32_e64 v37, 0, v37, s[36:37]
	v_add_u32_e32 v86, 68, v84
	v_cmp_gt_u32_e64 s[36:37], s98, v86
	v_cndmask_b32_e64 v38, 0, v38, s[78:79]
	v_add_u32_e32 v87, 72, v84
	v_cmp_gt_u32_e64 s[78:79], s98, v87
	v_cndmask_b32_e64 v39, 0, v39, s[50:51]
	v_add_u32_e32 v88, 76, v84
	v_cmp_gt_u32_e64 s[50:51], s98, v88
	v_cndmask_b32_e64 v40, 0, v40, s[30:31]
	v_add_u32_e32 v85, 96, v84
	v_cmp_gt_u32_e64 s[30:31], s98, v85
	v_cndmask_b32_e64 v41, 0, v41, s[36:37]
	v_add_u32_e32 v86, 100, v84
	v_cmp_gt_u32_e64 s[36:37], s98, v86
	v_cndmask_b32_e64 v42, 0, v42, s[78:79]
	v_add_u32_e32 v87, 104, v84
	v_cmp_gt_u32_e64 s[78:79], s98, v87
	v_cndmask_b32_e64 v43, 0, v43, s[50:51]
	v_add_u32_e32 v88, 108, v84
	v_cmp_gt_u32_e64 s[50:51], s98, v88
	v_nop
	v_cndmask_b32_e64 v44, 0, v44, s[30:31]
	v_cndmask_b32_e64 v45, 0, v45, s[36:37]
	v_cndmask_b32_e64 v46, 0, v46, s[78:79]
	v_cndmask_b32_e64 v47, 0, v47, s[50:51]
	v_cvt_pk_bf16_f32 v64, v32, v33
	v_cvt_pk_bf16_f32 v65, v34, v35
	v_cvt_pk_bf16_f32 v66, v36, v37
	v_cvt_pk_bf16_f32 v67, v38, v39
	v_cvt_pk_bf16_f32 v68, v40, v41
	v_cvt_pk_bf16_f32 v69, v42, v43
	v_cvt_pk_bf16_f32 v70, v44, v45
	v_cvt_pk_bf16_f32 v71, v46, v47
	v_pk_add_f32 v[232:233], v[232:233], v[32:33]
	v_pk_add_f32 v[232:233], v[232:233], v[34:35]
	v_pk_add_f32 v[232:233], v[232:233], v[36:37]
	v_pk_add_f32 v[232:233], v[232:233], v[38:39]
	v_pk_add_f32 v[232:233], v[232:233], v[40:41]
	v_pk_add_f32 v[232:233], v[232:233], v[42:43]
	v_pk_add_f32 v[232:233], v[232:233], v[44:45]
	v_pk_add_f32 v[232:233], v[232:233], v[46:47]
	v_add_u32_e32 v115, 640, v115
	ds_read2_b32 v[32:33], v115 offset0:0 offset1:1
	ds_read2_b32 v[34:35], v115 offset0:2 offset1:3
	ds_read2_b32 v[36:37], v115 offset0:10 offset1:11
	ds_read2_b32 v[38:39], v115 offset0:12 offset1:13
	ds_read2_b32 v[40:41], v115 offset0:20 offset1:21
	ds_read2_b32 v[42:43], v115 offset0:22 offset1:23
	ds_read2_b32 v[44:45], v115 offset0:30 offset1:31
	ds_read2_b32 v[46:47], v115 offset0:32 offset1:33
	v_mfma_f32_32x32x16_bf16 v[0:15], v[64:67], v[72:75], v[0:15]
	v_mfma_f32_32x32x16_bf16 v[16:31], v[64:67], v[76:79], v[16:31]
	v_mfma_f32_32x32x16_bf16 v[0:15], v[68:71], v[220:223], v[0:15]
	v_mfma_f32_32x32x16_bf16 v[16:31], v[68:71], v[224:227], v[16:31]
	s_add_i32 s90, s67, 384
	v_add_u32_e32 v80, s90, v239
	v_add_u32_e32 v83, s90, v240
	v_add_u32_e32 v99, s90, v241
	v_add_u32_e32 v253, s90, v242
	v_add_u32_e32 v254, s90, v101
	v_add_u32_e32 v255, s90, v150
	v_med3_i32 v80, v80, 0, s99
	v_med3_i32 v83, v83, 0, s99
	v_med3_i32 v99, v99, 0, s99
	v_med3_i32 v253, v253, 0, s99
	v_med3_i32 v254, v254, 0, s99
	v_med3_i32 v255, v255, 0, s99
	v_mad_u32_u24 v80, v80, s100, v252
	v_mad_u32_u24 v83, v83, s100, v252
	v_mad_u32_u24 v99, v99, s100, v252
	v_mad_u32_u24 v253, v253, s100, v252
	v_mad_u32_u24 v254, v254, s100, v153
	v_mad_u32_u24 v255, v255, s100, v153
	global_load_dwordx4 v[156:159], v80, s[82:83]
	global_load_dwordx4 v[160:163], v83, s[82:83]
	global_load_dwordx4 v[164:167], v99, s[82:83]
	global_load_dwordx4 v[168:171], v253, s[82:83]
	global_load_dwordx4 v[172:175], v254, s[82:83] offset:768
	global_load_dwordx4 v[176:179], v255, s[82:83] offset:768
	global_load_dwordx4 v[180:183], v254, s[82:83] offset:832
	global_load_dwordx4 v[184:187], v255, s[82:83] offset:832
	ds_read_b64_tr_b16 v[72:73], v231
	ds_read_b64_tr_b16 v[74:75], v231 offset:512
	ds_read_b64_tr_b16 v[76:77], v231 offset:2048
	ds_read_b64_tr_b16 v[78:79], v231 offset:2560
	ds_read_b64_tr_b16 v[220:221], v231 offset:1024
	ds_read_b64_tr_b16 v[222:223], v231 offset:1536
	ds_read_b64_tr_b16 v[224:225], v231 offset:3072
	ds_read_b64_tr_b16 v[226:227], v231 offset:3584
	s_waitcnt vmcnt(8)
	ds_write_b128 v247, v[116:119]
	ds_write_b128 v247, v[120:123] offset:1024
	ds_write_b128 v111, v[124:127] offset:2048
	ds_write_b128 v111, v[128:131] offset:3072
	ds_read_b128 v[116:119], v248
	ds_read_b128 v[120:123], v249
	ds_read_b128 v[124:127], v250
	ds_read_b128 v[128:131], v251
	ds_write_b128 v112, v[132:135]
	ds_write_b128 v112, v[136:139] offset:1024
	ds_write_b128 v112, v[140:143] offset:2048
	ds_write_b128 v112, v[144:147] offset:3072
	v_exp_f32_e32 v188, v188
	v_exp_f32_e32 v189, v189
	v_exp_f32_e32 v190, v190
	v_exp_f32_e32 v191, v191
	v_exp_f32_e32 v192, v192
	v_exp_f32_e32 v193, v193
	s_waitcnt lgkmcnt(4)
	v_mfma_f32_32x32x16_bf16 v[32:47], v[116:119], v[48:51], v[32:47]
	v_exp_f32_e32 v194, v194
	v_exp_f32_e32 v195, v195
	v_mfma_f32_32x32x16_bf16 v[32:47], v[120:123], v[52:55], v[32:47]
	v_exp_f32_e32 v196, v196
	v_exp_f32_e32 v197, v197
	v_exp_f32_e32 v198, v198
	v_mfma_f32_32x32x16_bf16 v[32:47], v[124:127], v[56:59], v[32:47]
	v_exp_f32_e32 v199, v199
	v_exp_f32_e32 v200, v200
	v_mfma_f32_32x32x16_bf16 v[32:47], v[128:131], v[60:63], v[32:47]
	v_exp_f32_e32 v201, v201
	v_exp_f32_e32 v202, v202
	v_exp_f32_e32 v203, v203
	s_add_i32 s90, s67, 128
	v_lshlrev_b32_e32 v84, 2, v107
	v_add_u32_e32 v84, s90, v84
	v_add_u32_e32 v85, 0, v84
	v_add_u32_e32 v86, 4, v84
	v_add_u32_e32 v87, 8, v84
	v_add_u32_e32 v88, 12, v84
	v_cmp_gt_u32_e64 s[30:31], s98, v85
	v_cmp_gt_u32_e64 s[36:37], s98, v86
	v_cmp_gt_u32_e64 s[78:79], s98, v87
	v_cmp_gt_u32_e64 s[50:51], s98, v88
	v_cndmask_b32_e64 v188, 0, v188, s[30:31]
	v_add_u32_e32 v85, 32, v84
	v_cmp_gt_u32_e64 s[30:31], s98, v85
	v_cndmask_b32_e64 v189, 0, v189, s[36:37]
	v_add_u32_e32 v86, 36, v84
	v_cmp_gt_u32_e64 s[36:37], s98, v86
	v_cndmask_b32_e64 v190, 0, v190, s[78:79]
	v_add_u32_e32 v87, 40, v84
	v_cmp_gt_u32_e64 s[78:79], s98, v87
	v_cndmask_b32_e64 v191, 0, v191, s[50:51]
	v_add_u32_e32 v88, 44, v84
	v_cmp_gt_u32_e64 s[50:51], s98, v88
	v_cndmask_b32_e64 v192, 0, v192, s[30:31]
	v_add_u32_e32 v85, 64, v84
	v_cmp_gt_u32_e64 s[30:31], s98, v85
	v_cndmask_b32_e64 v193, 0, v193, s[36:37]
	v_add_u32_e32 v86, 68, v84
	v_cmp_gt_u32_e64 s[36:37], s98, v86
	v_cndmask_b32_e64 v194, 0, v194, s[78:79]
	v_add_u32_e32 v87, 72, v84
	v_cmp_gt_u32_e64 s[78:79], s98, v87
	v_cndmask_b32_e64 v195, 0, v195, s[50:51]
	v_add_u32_e32 v88, 76, v84
	v_cmp_gt_u32_e64 s[50:51], s98, v88
	v_cndmask_b32_e64 v196, 0, v196, s[30:31]
	v_add_u32_e32 v85, 96, v84
	v_cmp_gt_u32_e64 s[30:31], s98, v85
	v_cndmask_b32_e64 v197, 0, v197, s[36:37]
	v_add_u32_e32 v86, 100, v84
	v_cmp_gt_u32_e64 s[36:37], s98, v86
	v_cndmask_b32_e64 v198, 0, v198, s[78:79]
	v_add_u32_e32 v87, 104, v84
	v_cmp_gt_u32_e64 s[78:79], s98, v87
	v_cndmask_b32_e64 v199, 0, v199, s[50:51]
	v_add_u32_e32 v88, 108, v84
	v_cmp_gt_u32_e64 s[50:51], s98, v88
	v_nop
	v_cndmask_b32_e64 v200, 0, v200, s[30:31]
	v_cndmask_b32_e64 v201, 0, v201, s[36:37]
	v_cndmask_b32_e64 v202, 0, v202, s[78:79]
	v_cndmask_b32_e64 v203, 0, v203, s[50:51]
	v_cvt_pk_bf16_f32 v64, v188, v189
	v_cvt_pk_bf16_f32 v65, v190, v191
	v_cvt_pk_bf16_f32 v66, v192, v193
	v_cvt_pk_bf16_f32 v67, v194, v195
	v_cvt_pk_bf16_f32 v68, v196, v197
	v_cvt_pk_bf16_f32 v69, v198, v199
	v_cvt_pk_bf16_f32 v70, v200, v201
	v_cvt_pk_bf16_f32 v71, v202, v203
	v_pk_add_f32 v[232:233], v[232:233], v[188:189]
	v_pk_add_f32 v[232:233], v[232:233], v[190:191]
	v_pk_add_f32 v[232:233], v[232:233], v[192:193]
	v_pk_add_f32 v[232:233], v[232:233], v[194:195]
	v_pk_add_f32 v[232:233], v[232:233], v[196:197]
	v_pk_add_f32 v[232:233], v[232:233], v[198:199]
	v_pk_add_f32 v[232:233], v[232:233], v[200:201]
	v_pk_add_f32 v[232:233], v[232:233], v[202:203]
	ds_read2_b32 v[188:189], v115 offset0:40 offset1:41
	ds_read2_b32 v[190:191], v115 offset0:42 offset1:43
	ds_read2_b32 v[192:193], v115 offset0:50 offset1:51
	ds_read2_b32 v[194:195], v115 offset0:52 offset1:53
	ds_read2_b32 v[196:197], v115 offset0:60 offset1:61
	ds_read2_b32 v[198:199], v115 offset0:62 offset1:63
	ds_read2_b32 v[200:201], v115 offset0:70 offset1:71
	ds_read2_b32 v[202:203], v115 offset0:72 offset1:73
	v_mfma_f32_32x32x16_bf16 v[0:15], v[64:67], v[72:75], v[0:15]
	v_mfma_f32_32x32x16_bf16 v[16:31], v[64:67], v[76:79], v[16:31]
	v_mfma_f32_32x32x16_bf16 v[0:15], v[68:71], v[220:223], v[0:15]
	v_mfma_f32_32x32x16_bf16 v[16:31], v[68:71], v[224:227], v[16:31]
	s_add_i32 s90, s67, 512
	v_add_u32_e32 v80, s90, v239
	v_add_u32_e32 v83, s90, v240
	v_add_u32_e32 v99, s90, v241
	v_add_u32_e32 v253, s90, v242
	v_add_u32_e32 v254, s90, v101
	v_add_u32_e32 v255, s90, v150
	v_med3_i32 v80, v80, 0, s99
	v_med3_i32 v83, v83, 0, s99
	v_med3_i32 v99, v99, 0, s99
	v_med3_i32 v253, v253, 0, s99
	v_med3_i32 v254, v254, 0, s99
	v_med3_i32 v255, v255, 0, s99
	v_mad_u32_u24 v80, v80, s100, v252
	v_mad_u32_u24 v83, v83, s100, v252
	v_mad_u32_u24 v99, v99, s100, v252
	v_mad_u32_u24 v253, v253, s100, v252
	v_mad_u32_u24 v254, v254, s100, v153
	v_mad_u32_u24 v255, v255, s100, v153
	global_load_dwordx4 v[116:119], v80, s[82:83]
	global_load_dwordx4 v[120:123], v83, s[82:83]
	global_load_dwordx4 v[124:127], v99, s[82:83]
	global_load_dwordx4 v[128:131], v253, s[82:83]
	global_load_dwordx4 v[132:135], v254, s[82:83] offset:768
	global_load_dwordx4 v[136:139], v255, s[82:83] offset:768
	global_load_dwordx4 v[140:143], v254, s[82:83] offset:832
	global_load_dwordx4 v[144:147], v255, s[82:83] offset:832
	ds_read_b64_tr_b16 v[72:73], v231
	ds_read_b64_tr_b16 v[74:75], v231 offset:512
	ds_read_b64_tr_b16 v[76:77], v231 offset:2048
	ds_read_b64_tr_b16 v[78:79], v231 offset:2560
	ds_read_b64_tr_b16 v[220:221], v231 offset:1024
	ds_read_b64_tr_b16 v[222:223], v231 offset:1536
	ds_read_b64_tr_b16 v[224:225], v231 offset:3072
	ds_read_b64_tr_b16 v[226:227], v231 offset:3584
	s_waitcnt vmcnt(8)
	ds_write_b128 v247, v[156:159]
	ds_write_b128 v247, v[160:163] offset:1024
	ds_write_b128 v111, v[164:167] offset:2048
	ds_write_b128 v111, v[168:171] offset:3072
	ds_read_b128 v[156:159], v248
	ds_read_b128 v[160:163], v249
	ds_read_b128 v[164:167], v250
	ds_read_b128 v[168:171], v251
	ds_write_b128 v112, v[172:175]
	ds_write_b128 v112, v[176:179] offset:1024
	ds_write_b128 v112, v[180:183] offset:2048
	ds_write_b128 v112, v[184:187] offset:3072
	v_exp_f32_e32 v32, v32
	v_exp_f32_e32 v33, v33
	v_exp_f32_e32 v34, v34
	v_exp_f32_e32 v35, v35
	v_exp_f32_e32 v36, v36
	v_exp_f32_e32 v37, v37
	s_waitcnt lgkmcnt(4)
	v_mfma_f32_32x32x16_bf16 v[188:203], v[156:159], v[48:51], v[188:203]
	v_exp_f32_e32 v38, v38
	v_exp_f32_e32 v39, v39
	v_mfma_f32_32x32x16_bf16 v[188:203], v[160:163], v[52:55], v[188:203]
	v_exp_f32_e32 v40, v40
	v_exp_f32_e32 v41, v41
	v_exp_f32_e32 v42, v42
	v_mfma_f32_32x32x16_bf16 v[188:203], v[164:167], v[56:59], v[188:203]
	v_exp_f32_e32 v43, v43
	v_exp_f32_e32 v44, v44
	v_mfma_f32_32x32x16_bf16 v[188:203], v[168:171], v[60:63], v[188:203]
	v_exp_f32_e32 v45, v45
	v_exp_f32_e32 v46, v46
	v_exp_f32_e32 v47, v47
	s_add_i32 s90, s67, 256
	v_lshlrev_b32_e32 v84, 2, v107
	v_add_u32_e32 v84, s90, v84
	v_add_u32_e32 v85, 0, v84
	v_add_u32_e32 v86, 4, v84
	v_add_u32_e32 v87, 8, v84
	v_add_u32_e32 v88, 12, v84
	v_cmp_gt_u32_e64 s[30:31], s98, v85
	v_cmp_gt_u32_e64 s[36:37], s98, v86
	v_cmp_gt_u32_e64 s[78:79], s98, v87
	v_cmp_gt_u32_e64 s[50:51], s98, v88
	v_cndmask_b32_e64 v32, 0, v32, s[30:31]
	v_add_u32_e32 v85, 32, v84
	v_cmp_gt_u32_e64 s[30:31], s98, v85
	v_cndmask_b32_e64 v33, 0, v33, s[36:37]
	v_add_u32_e32 v86, 36, v84
	v_cmp_gt_u32_e64 s[36:37], s98, v86
	v_cndmask_b32_e64 v34, 0, v34, s[78:79]
	v_add_u32_e32 v87, 40, v84
	v_cmp_gt_u32_e64 s[78:79], s98, v87
	v_cndmask_b32_e64 v35, 0, v35, s[50:51]
	v_add_u32_e32 v88, 44, v84
	v_cmp_gt_u32_e64 s[50:51], s98, v88
	v_cndmask_b32_e64 v36, 0, v36, s[30:31]
	v_add_u32_e32 v85, 64, v84
	v_cmp_gt_u32_e64 s[30:31], s98, v85
	v_cndmask_b32_e64 v37, 0, v37, s[36:37]
	v_add_u32_e32 v86, 68, v84
	v_cmp_gt_u32_e64 s[36:37], s98, v86
	v_cndmask_b32_e64 v38, 0, v38, s[78:79]
	v_add_u32_e32 v87, 72, v84
	v_cmp_gt_u32_e64 s[78:79], s98, v87
	v_cndmask_b32_e64 v39, 0, v39, s[50:51]
	v_add_u32_e32 v88, 76, v84
	v_cmp_gt_u32_e64 s[50:51], s98, v88
	v_cndmask_b32_e64 v40, 0, v40, s[30:31]
	v_add_u32_e32 v85, 96, v84
	v_cmp_gt_u32_e64 s[30:31], s98, v85
	v_cndmask_b32_e64 v41, 0, v41, s[36:37]
	v_add_u32_e32 v86, 100, v84
	v_cmp_gt_u32_e64 s[36:37], s98, v86
	v_cndmask_b32_e64 v42, 0, v42, s[78:79]
	v_add_u32_e32 v87, 104, v84
	v_cmp_gt_u32_e64 s[78:79], s98, v87
	v_cndmask_b32_e64 v43, 0, v43, s[50:51]
	v_add_u32_e32 v88, 108, v84
	v_cmp_gt_u32_e64 s[50:51], s98, v88
	v_nop
	v_cndmask_b32_e64 v44, 0, v44, s[30:31]
	v_cndmask_b32_e64 v45, 0, v45, s[36:37]
	v_cndmask_b32_e64 v46, 0, v46, s[78:79]
	v_cndmask_b32_e64 v47, 0, v47, s[50:51]
	v_cvt_pk_bf16_f32 v64, v32, v33
	v_cvt_pk_bf16_f32 v65, v34, v35
	v_cvt_pk_bf16_f32 v66, v36, v37
	v_cvt_pk_bf16_f32 v67, v38, v39
	v_cvt_pk_bf16_f32 v68, v40, v41
	v_cvt_pk_bf16_f32 v69, v42, v43
	v_cvt_pk_bf16_f32 v70, v44, v45
	v_cvt_pk_bf16_f32 v71, v46, v47
	v_pk_add_f32 v[232:233], v[232:233], v[32:33]
	v_pk_add_f32 v[232:233], v[232:233], v[34:35]
	v_pk_add_f32 v[232:233], v[232:233], v[36:37]
	v_pk_add_f32 v[232:233], v[232:233], v[38:39]
	v_pk_add_f32 v[232:233], v[232:233], v[40:41]
	v_pk_add_f32 v[232:233], v[232:233], v[42:43]
	v_pk_add_f32 v[232:233], v[232:233], v[44:45]
	v_pk_add_f32 v[232:233], v[232:233], v[46:47]
	ds_read2_b32 v[32:33], v115 offset0:80 offset1:81
	ds_read2_b32 v[34:35], v115 offset0:82 offset1:83
	ds_read2_b32 v[36:37], v115 offset0:90 offset1:91
	ds_read2_b32 v[38:39], v115 offset0:92 offset1:93
	ds_read2_b32 v[40:41], v115 offset0:100 offset1:101
	ds_read2_b32 v[42:43], v115 offset0:102 offset1:103
	ds_read2_b32 v[44:45], v115 offset0:110 offset1:111
	ds_read2_b32 v[46:47], v115 offset0:112 offset1:113
	v_mfma_f32_32x32x16_bf16 v[0:15], v[64:67], v[72:75], v[0:15]
	v_mfma_f32_32x32x16_bf16 v[16:31], v[64:67], v[76:79], v[16:31]
	v_mfma_f32_32x32x16_bf16 v[0:15], v[68:71], v[220:223], v[0:15]
	v_mfma_f32_32x32x16_bf16 v[16:31], v[68:71], v[224:227], v[16:31]
	s_add_i32 s90, s67, 640
	v_add_u32_e32 v80, s90, v239
	v_add_u32_e32 v83, s90, v240
	v_add_u32_e32 v99, s90, v241
	v_add_u32_e32 v253, s90, v242
	v_add_u32_e32 v254, s90, v101
	v_add_u32_e32 v255, s90, v150
	v_med3_i32 v80, v80, 0, s99
	v_med3_i32 v83, v83, 0, s99
	v_med3_i32 v99, v99, 0, s99
	v_med3_i32 v253, v253, 0, s99
	v_med3_i32 v254, v254, 0, s99
	v_med3_i32 v255, v255, 0, s99
	v_mad_u32_u24 v80, v80, s100, v252
	v_mad_u32_u24 v83, v83, s100, v252
	v_mad_u32_u24 v99, v99, s100, v252
	v_mad_u32_u24 v253, v253, s100, v252
	v_mad_u32_u24 v254, v254, s100, v153
	v_mad_u32_u24 v255, v255, s100, v153
	global_load_dwordx4 v[156:159], v80, s[82:83]
	global_load_dwordx4 v[160:163], v83, s[82:83]
	global_load_dwordx4 v[164:167], v99, s[82:83]
	global_load_dwordx4 v[168:171], v253, s[82:83]
	global_load_dwordx4 v[172:175], v254, s[82:83] offset:768
	global_load_dwordx4 v[176:179], v255, s[82:83] offset:768
	global_load_dwordx4 v[180:183], v254, s[82:83] offset:832
	global_load_dwordx4 v[184:187], v255, s[82:83] offset:832
	ds_read_b64_tr_b16 v[72:73], v231
	ds_read_b64_tr_b16 v[74:75], v231 offset:512
	ds_read_b64_tr_b16 v[76:77], v231 offset:2048
	ds_read_b64_tr_b16 v[78:79], v231 offset:2560
	ds_read_b64_tr_b16 v[220:221], v231 offset:1024
	ds_read_b64_tr_b16 v[222:223], v231 offset:1536
	ds_read_b64_tr_b16 v[224:225], v231 offset:3072
	ds_read_b64_tr_b16 v[226:227], v231 offset:3584
	s_waitcnt vmcnt(8)
	ds_write_b128 v247, v[116:119]
	ds_write_b128 v247, v[120:123] offset:1024
	ds_write_b128 v111, v[124:127] offset:2048
	ds_write_b128 v111, v[128:131] offset:3072
	ds_read_b128 v[116:119], v248
	ds_read_b128 v[120:123], v249
	ds_read_b128 v[124:127], v250
	ds_read_b128 v[128:131], v251
	ds_write_b128 v112, v[132:135]
	ds_write_b128 v112, v[136:139] offset:1024
	ds_write_b128 v112, v[140:143] offset:2048
	ds_write_b128 v112, v[144:147] offset:3072
	v_exp_f32_e32 v188, v188
	v_exp_f32_e32 v189, v189
	v_exp_f32_e32 v190, v190
	v_exp_f32_e32 v191, v191
	v_exp_f32_e32 v192, v192
	v_exp_f32_e32 v193, v193
	s_waitcnt lgkmcnt(4)
	v_mfma_f32_32x32x16_bf16 v[32:47], v[116:119], v[48:51], v[32:47]
	v_exp_f32_e32 v194, v194
	v_exp_f32_e32 v195, v195
	v_mfma_f32_32x32x16_bf16 v[32:47], v[120:123], v[52:55], v[32:47]
	v_exp_f32_e32 v196, v196
	v_exp_f32_e32 v197, v197
	v_exp_f32_e32 v198, v198
	v_mfma_f32_32x32x16_bf16 v[32:47], v[124:127], v[56:59], v[32:47]
	v_exp_f32_e32 v199, v199
	v_exp_f32_e32 v200, v200
	v_mfma_f32_32x32x16_bf16 v[32:47], v[128:131], v[60:63], v[32:47]
	v_exp_f32_e32 v201, v201
	v_exp_f32_e32 v202, v202
	v_exp_f32_e32 v203, v203
	s_add_i32 s90, s67, 384
	v_lshlrev_b32_e32 v84, 2, v107
	v_add_u32_e32 v84, s90, v84
	v_add_u32_e32 v85, 0, v84
	v_add_u32_e32 v86, 4, v84
	v_add_u32_e32 v87, 8, v84
	v_add_u32_e32 v88, 12, v84
	v_cmp_gt_u32_e64 s[30:31], s98, v85
	v_cmp_gt_u32_e64 s[36:37], s98, v86
	v_cmp_gt_u32_e64 s[78:79], s98, v87
	v_cmp_gt_u32_e64 s[50:51], s98, v88
	v_cndmask_b32_e64 v188, 0, v188, s[30:31]
	v_add_u32_e32 v85, 32, v84
	v_cmp_gt_u32_e64 s[30:31], s98, v85
	v_cndmask_b32_e64 v189, 0, v189, s[36:37]
	v_add_u32_e32 v86, 36, v84
	v_cmp_gt_u32_e64 s[36:37], s98, v86
	v_cndmask_b32_e64 v190, 0, v190, s[78:79]
	v_add_u32_e32 v87, 40, v84
	v_cmp_gt_u32_e64 s[78:79], s98, v87
	v_cndmask_b32_e64 v191, 0, v191, s[50:51]
	v_add_u32_e32 v88, 44, v84
	v_cmp_gt_u32_e64 s[50:51], s98, v88
	v_cndmask_b32_e64 v192, 0, v192, s[30:31]
	v_add_u32_e32 v85, 64, v84
	v_cmp_gt_u32_e64 s[30:31], s98, v85
	v_cndmask_b32_e64 v193, 0, v193, s[36:37]
	v_add_u32_e32 v86, 68, v84
	v_cmp_gt_u32_e64 s[36:37], s98, v86
	v_cndmask_b32_e64 v194, 0, v194, s[78:79]
	v_add_u32_e32 v87, 72, v84
	v_cmp_gt_u32_e64 s[78:79], s98, v87
	v_cndmask_b32_e64 v195, 0, v195, s[50:51]
	v_add_u32_e32 v88, 76, v84
	v_cmp_gt_u32_e64 s[50:51], s98, v88
	v_cndmask_b32_e64 v196, 0, v196, s[30:31]
	v_add_u32_e32 v85, 96, v84
	v_cmp_gt_u32_e64 s[30:31], s98, v85
	v_cndmask_b32_e64 v197, 0, v197, s[36:37]
	v_add_u32_e32 v86, 100, v84
	v_cmp_gt_u32_e64 s[36:37], s98, v86
	v_cndmask_b32_e64 v198, 0, v198, s[78:79]
	v_add_u32_e32 v87, 104, v84
	v_cmp_gt_u32_e64 s[78:79], s98, v87
	v_cndmask_b32_e64 v199, 0, v199, s[50:51]
	v_add_u32_e32 v88, 108, v84
	v_cmp_gt_u32_e64 s[50:51], s98, v88
	v_nop
	v_cndmask_b32_e64 v200, 0, v200, s[30:31]
	v_cndmask_b32_e64 v201, 0, v201, s[36:37]
	v_cndmask_b32_e64 v202, 0, v202, s[78:79]
	v_cndmask_b32_e64 v203, 0, v203, s[50:51]
	v_cvt_pk_bf16_f32 v64, v188, v189
	v_cvt_pk_bf16_f32 v65, v190, v191
	v_cvt_pk_bf16_f32 v66, v192, v193
	v_cvt_pk_bf16_f32 v67, v194, v195
	v_cvt_pk_bf16_f32 v68, v196, v197
	v_cvt_pk_bf16_f32 v69, v198, v199
	v_cvt_pk_bf16_f32 v70, v200, v201
	v_cvt_pk_bf16_f32 v71, v202, v203
	v_pk_add_f32 v[232:233], v[232:233], v[188:189]
	v_pk_add_f32 v[232:233], v[232:233], v[190:191]
	v_pk_add_f32 v[232:233], v[232:233], v[192:193]
	v_pk_add_f32 v[232:233], v[232:233], v[194:195]
	v_pk_add_f32 v[232:233], v[232:233], v[196:197]
	v_pk_add_f32 v[232:233], v[232:233], v[198:199]
	v_pk_add_f32 v[232:233], v[232:233], v[200:201]
	v_pk_add_f32 v[232:233], v[232:233], v[202:203]
	ds_read2_b32 v[188:189], v115 offset0:120 offset1:121
	ds_read2_b32 v[190:191], v115 offset0:122 offset1:123
	ds_read2_b32 v[192:193], v115 offset0:130 offset1:131
	ds_read2_b32 v[194:195], v115 offset0:132 offset1:133
	ds_read2_b32 v[196:197], v115 offset0:140 offset1:141
	ds_read2_b32 v[198:199], v115 offset0:142 offset1:143
	ds_read2_b32 v[200:201], v115 offset0:150 offset1:151
	ds_read2_b32 v[202:203], v115 offset0:152 offset1:153
	v_mfma_f32_32x32x16_bf16 v[0:15], v[64:67], v[72:75], v[0:15]
	v_mfma_f32_32x32x16_bf16 v[16:31], v[64:67], v[76:79], v[16:31]
	v_mfma_f32_32x32x16_bf16 v[0:15], v[68:71], v[220:223], v[0:15]
	v_mfma_f32_32x32x16_bf16 v[16:31], v[68:71], v[224:227], v[16:31]
	s_add_i32 s90, s67, -1024
	v_add_u32_e32 v80, s90, v243
	v_add_u32_e32 v83, s90, v244
	v_add_u32_e32 v99, s90, v245
	v_add_u32_e32 v253, s90, v246
	v_add_u32_e32 v254, s90, v148
	v_add_u32_e32 v255, s90, v151
	v_med3_i32 v80, v80, 0, s99
	v_med3_i32 v83, v83, 0, s99
	v_med3_i32 v99, v99, 0, s99
	v_med3_i32 v253, v253, 0, s99
	v_med3_i32 v254, v254, 0, s99
	v_med3_i32 v255, v255, 0, s99
	v_mad_u32_u24 v80, v80, s100, v252
	v_mad_u32_u24 v83, v83, s100, v252
	v_mad_u32_u24 v99, v99, s100, v252
	v_mad_u32_u24 v253, v253, s100, v252
	v_mad_u32_u24 v254, v254, s100, v153
	v_mad_u32_u24 v255, v255, s100, v153
	global_load_dwordx4 v[116:119], v80, s[82:83]
	global_load_dwordx4 v[120:123], v83, s[82:83]
	global_load_dwordx4 v[124:127], v99, s[82:83]
	global_load_dwordx4 v[128:131], v253, s[82:83]
	global_load_dwordx4 v[132:135], v254, s[82:83] offset:768
	global_load_dwordx4 v[136:139], v255, s[82:83] offset:768
	global_load_dwordx4 v[140:143], v254, s[82:83] offset:832
	global_load_dwordx4 v[144:147], v255, s[82:83] offset:832
	ds_read_b64_tr_b16 v[72:73], v231
	ds_read_b64_tr_b16 v[74:75], v231 offset:512
	ds_read_b64_tr_b16 v[76:77], v231 offset:2048
	ds_read_b64_tr_b16 v[78:79], v231 offset:2560
	ds_read_b64_tr_b16 v[220:221], v231 offset:1024
	ds_read_b64_tr_b16 v[222:223], v231 offset:1536
	ds_read_b64_tr_b16 v[224:225], v231 offset:3072
	ds_read_b64_tr_b16 v[226:227], v231 offset:3584
	s_waitcnt vmcnt(8)
	ds_write_b128 v247, v[156:159]
	ds_write_b128 v247, v[160:163] offset:1024
	ds_write_b128 v111, v[164:167] offset:2048
	ds_write_b128 v111, v[168:171] offset:3072
	ds_read_b128 v[156:159], v248
	ds_read_b128 v[160:163], v249
	ds_read_b128 v[164:167], v250
	ds_read_b128 v[168:171], v251
	ds_write_b128 v112, v[172:175]
	ds_write_b128 v112, v[176:179] offset:1024
	ds_write_b128 v112, v[180:183] offset:2048
	ds_write_b128 v112, v[184:187] offset:3072
	v_exp_f32_e32 v32, v32
	v_exp_f32_e32 v33, v33
	v_exp_f32_e32 v34, v34
	v_exp_f32_e32 v35, v35
	v_exp_f32_e32 v36, v36
	v_exp_f32_e32 v37, v37
	s_waitcnt lgkmcnt(4)
	v_mfma_f32_32x32x16_bf16 v[188:203], v[156:159], v[48:51], v[188:203]
	v_exp_f32_e32 v38, v38
	v_exp_f32_e32 v39, v39
	v_mfma_f32_32x32x16_bf16 v[188:203], v[160:163], v[52:55], v[188:203]
	v_exp_f32_e32 v40, v40
	v_exp_f32_e32 v41, v41
	v_exp_f32_e32 v42, v42
	v_mfma_f32_32x32x16_bf16 v[188:203], v[164:167], v[56:59], v[188:203]
	v_exp_f32_e32 v43, v43
	v_exp_f32_e32 v44, v44
	v_mfma_f32_32x32x16_bf16 v[188:203], v[168:171], v[60:63], v[188:203]
	v_exp_f32_e32 v45, v45
	v_exp_f32_e32 v46, v46
	v_exp_f32_e32 v47, v47
	s_add_i32 s90, s67, 512
	v_lshlrev_b32_e32 v84, 2, v107
	v_add_u32_e32 v84, s90, v84
	v_add_u32_e32 v85, 0, v84
	v_add_u32_e32 v86, 4, v84
	v_add_u32_e32 v87, 8, v84
	v_add_u32_e32 v88, 12, v84
	v_cmp_gt_u32_e64 s[30:31], s98, v85
	v_cmp_gt_u32_e64 s[36:37], s98, v86
	v_cmp_gt_u32_e64 s[78:79], s98, v87
	v_cmp_gt_u32_e64 s[50:51], s98, v88
	v_cndmask_b32_e64 v32, 0, v32, s[30:31]
	v_add_u32_e32 v85, 32, v84
	v_cmp_gt_u32_e64 s[30:31], s98, v85
	v_cndmask_b32_e64 v33, 0, v33, s[36:37]
	v_add_u32_e32 v86, 36, v84
	v_cmp_gt_u32_e64 s[36:37], s98, v86
	v_cndmask_b32_e64 v34, 0, v34, s[78:79]
	v_add_u32_e32 v87, 40, v84
	v_cmp_gt_u32_e64 s[78:79], s98, v87
	v_cndmask_b32_e64 v35, 0, v35, s[50:51]
	v_add_u32_e32 v88, 44, v84
	v_cmp_gt_u32_e64 s[50:51], s98, v88
	v_cndmask_b32_e64 v36, 0, v36, s[30:31]
	v_add_u32_e32 v85, 64, v84
	v_cmp_gt_u32_e64 s[30:31], s98, v85
	v_cndmask_b32_e64 v37, 0, v37, s[36:37]
	v_add_u32_e32 v86, 68, v84
	v_cmp_gt_u32_e64 s[36:37], s98, v86
	v_cndmask_b32_e64 v38, 0, v38, s[78:79]
	v_add_u32_e32 v87, 72, v84
	v_cmp_gt_u32_e64 s[78:79], s98, v87
	v_cndmask_b32_e64 v39, 0, v39, s[50:51]
	v_add_u32_e32 v88, 76, v84
	v_cmp_gt_u32_e64 s[50:51], s98, v88
	v_cndmask_b32_e64 v40, 0, v40, s[30:31]
	v_add_u32_e32 v85, 96, v84
	v_cmp_gt_u32_e64 s[30:31], s98, v85
	v_cndmask_b32_e64 v41, 0, v41, s[36:37]
	v_add_u32_e32 v86, 100, v84
	v_cmp_gt_u32_e64 s[36:37], s98, v86
	v_cndmask_b32_e64 v42, 0, v42, s[78:79]
	v_add_u32_e32 v87, 104, v84
	v_cmp_gt_u32_e64 s[78:79], s98, v87
	v_cndmask_b32_e64 v43, 0, v43, s[50:51]
	v_add_u32_e32 v88, 108, v84
	v_cmp_gt_u32_e64 s[50:51], s98, v88
	v_nop
	v_cndmask_b32_e64 v44, 0, v44, s[30:31]
	v_cndmask_b32_e64 v45, 0, v45, s[36:37]
	v_cndmask_b32_e64 v46, 0, v46, s[78:79]
	v_cndmask_b32_e64 v47, 0, v47, s[50:51]
	v_cvt_pk_bf16_f32 v64, v32, v33
	v_cvt_pk_bf16_f32 v65, v34, v35
	v_cvt_pk_bf16_f32 v66, v36, v37
	v_cvt_pk_bf16_f32 v67, v38, v39
	v_cvt_pk_bf16_f32 v68, v40, v41
	v_cvt_pk_bf16_f32 v69, v42, v43
	v_cvt_pk_bf16_f32 v70, v44, v45
	v_cvt_pk_bf16_f32 v71, v46, v47
	v_pk_add_f32 v[232:233], v[232:233], v[32:33]
	v_pk_add_f32 v[232:233], v[232:233], v[34:35]
	v_pk_add_f32 v[232:233], v[232:233], v[36:37]
	v_pk_add_f32 v[232:233], v[232:233], v[38:39]
	v_pk_add_f32 v[232:233], v[232:233], v[40:41]
	v_pk_add_f32 v[232:233], v[232:233], v[42:43]
	v_pk_add_f32 v[232:233], v[232:233], v[44:45]
	v_pk_add_f32 v[232:233], v[232:233], v[46:47]
	v_mov_b32_e32 v115, v230
	ds_read2_b32 v[32:33], v115 offset0:0 offset1:1
	ds_read2_b32 v[34:35], v115 offset0:2 offset1:3
	ds_read2_b32 v[36:37], v115 offset0:8 offset1:9
	ds_read2_b32 v[38:39], v115 offset0:10 offset1:11
	ds_read2_b32 v[40:41], v115 offset0:16 offset1:17
	ds_read2_b32 v[42:43], v115 offset0:18 offset1:19
	ds_read2_b32 v[44:45], v115 offset0:24 offset1:25
	ds_read2_b32 v[46:47], v115 offset0:26 offset1:27
	v_mfma_f32_32x32x16_bf16 v[0:15], v[64:67], v[72:75], v[0:15]
	v_mfma_f32_32x32x16_bf16 v[16:31], v[64:67], v[76:79], v[16:31]
	v_mfma_f32_32x32x16_bf16 v[0:15], v[68:71], v[220:223], v[0:15]
	v_mfma_f32_32x32x16_bf16 v[16:31], v[68:71], v[224:227], v[16:31]
	s_add_i32 s90, s67, -512
	v_add_u32_e32 v80, s90, v243
	v_add_u32_e32 v83, s90, v244
	v_add_u32_e32 v99, s90, v245
	v_add_u32_e32 v253, s90, v246
	v_add_u32_e32 v254, s90, v148
	v_add_u32_e32 v255, s90, v151
	v_med3_i32 v80, v80, 0, s99
	v_med3_i32 v83, v83, 0, s99
	v_med3_i32 v99, v99, 0, s99
	v_med3_i32 v253, v253, 0, s99
	v_med3_i32 v254, v254, 0, s99
	v_med3_i32 v255, v255, 0, s99
	v_mad_u32_u24 v80, v80, s100, v252
	v_mad_u32_u24 v83, v83, s100, v252
	v_mad_u32_u24 v99, v99, s100, v252
	v_mad_u32_u24 v253, v253, s100, v252
	v_mad_u32_u24 v254, v254, s100, v153
	v_mad_u32_u24 v255, v255, s100, v153
	global_load_dwordx4 v[156:159], v80, s[82:83]
	global_load_dwordx4 v[160:163], v83, s[82:83]
	global_load_dwordx4 v[164:167], v99, s[82:83]
	global_load_dwordx4 v[168:171], v253, s[82:83]
	global_load_dwordx4 v[172:175], v254, s[82:83] offset:768
	global_load_dwordx4 v[176:179], v255, s[82:83] offset:768
	global_load_dwordx4 v[180:183], v254, s[82:83] offset:832
	global_load_dwordx4 v[184:187], v255, s[82:83] offset:832
	ds_read_b64_tr_b16 v[72:73], v231
	ds_read_b64_tr_b16 v[74:75], v231 offset:512
	ds_read_b64_tr_b16 v[76:77], v231 offset:2048
	ds_read_b64_tr_b16 v[78:79], v231 offset:2560
	ds_read_b64_tr_b16 v[220:221], v231 offset:1024
	ds_read_b64_tr_b16 v[222:223], v231 offset:1536
	ds_read_b64_tr_b16 v[224:225], v231 offset:3072
	ds_read_b64_tr_b16 v[226:227], v231 offset:3584
	s_waitcnt vmcnt(8)
	ds_write_b128 v247, v[116:119]
	ds_write_b128 v247, v[120:123] offset:1024
	ds_write_b128 v111, v[124:127] offset:2048
	ds_write_b128 v111, v[128:131] offset:3072
	ds_read_b128 v[116:119], v248
	ds_read_b128 v[120:123], v249
	ds_read_b128 v[124:127], v250
	ds_read_b128 v[128:131], v251
	ds_write_b128 v112, v[132:135]
	ds_write_b128 v112, v[136:139] offset:1024
	ds_write_b128 v112, v[140:143] offset:2048
	ds_write_b128 v112, v[144:147] offset:3072
	v_exp_f32_e32 v188, v188
	v_exp_f32_e32 v189, v189
	v_exp_f32_e32 v190, v190
	v_exp_f32_e32 v191, v191
	v_exp_f32_e32 v192, v192
	v_exp_f32_e32 v193, v193
	s_waitcnt lgkmcnt(4)
	v_mfma_f32_32x32x16_bf16 v[32:47], v[116:119], v[48:51], v[32:47]
	v_exp_f32_e32 v194, v194
	v_exp_f32_e32 v195, v195
	v_mfma_f32_32x32x16_bf16 v[32:47], v[120:123], v[52:55], v[32:47]
	v_exp_f32_e32 v196, v196
	v_exp_f32_e32 v197, v197
	v_exp_f32_e32 v198, v198
	v_mfma_f32_32x32x16_bf16 v[32:47], v[124:127], v[56:59], v[32:47]
	v_exp_f32_e32 v199, v199
	v_exp_f32_e32 v200, v200
	v_mfma_f32_32x32x16_bf16 v[32:47], v[128:131], v[60:63], v[32:47]
	v_exp_f32_e32 v201, v201
	v_exp_f32_e32 v202, v202
	v_exp_f32_e32 v203, v203
	s_add_i32 s90, s67, 640
	v_lshlrev_b32_e32 v84, 2, v107
	v_add_u32_e32 v84, s90, v84
	v_add_u32_e32 v85, 0, v84
	v_add_u32_e32 v86, 4, v84
	v_add_u32_e32 v87, 8, v84
	v_add_u32_e32 v88, 12, v84
	v_cmp_gt_u32_e64 s[30:31], s98, v85
	v_cmp_gt_u32_e64 s[36:37], s98, v86
	v_cmp_gt_u32_e64 s[78:79], s98, v87
	v_cmp_gt_u32_e64 s[50:51], s98, v88
	v_cndmask_b32_e64 v188, 0, v188, s[30:31]
	v_add_u32_e32 v85, 32, v84
	v_cmp_gt_u32_e64 s[30:31], s98, v85
	v_cndmask_b32_e64 v189, 0, v189, s[36:37]
	v_add_u32_e32 v86, 36, v84
	v_cmp_gt_u32_e64 s[36:37], s98, v86
	v_cndmask_b32_e64 v190, 0, v190, s[78:79]
	v_add_u32_e32 v87, 40, v84
	v_cmp_gt_u32_e64 s[78:79], s98, v87
	v_cndmask_b32_e64 v191, 0, v191, s[50:51]
	v_add_u32_e32 v88, 44, v84
	v_cmp_gt_u32_e64 s[50:51], s98, v88
	v_cndmask_b32_e64 v192, 0, v192, s[30:31]
	v_add_u32_e32 v85, 64, v84
	v_cmp_gt_u32_e64 s[30:31], s98, v85
	v_cndmask_b32_e64 v193, 0, v193, s[36:37]
	v_add_u32_e32 v86, 68, v84
	v_cmp_gt_u32_e64 s[36:37], s98, v86
	v_cndmask_b32_e64 v194, 0, v194, s[78:79]
	v_add_u32_e32 v87, 72, v84
	v_cmp_gt_u32_e64 s[78:79], s98, v87
	v_cndmask_b32_e64 v195, 0, v195, s[50:51]
	v_add_u32_e32 v88, 76, v84
	v_cmp_gt_u32_e64 s[50:51], s98, v88
	v_cndmask_b32_e64 v196, 0, v196, s[30:31]
	v_add_u32_e32 v85, 96, v84
	v_cmp_gt_u32_e64 s[30:31], s98, v85
	v_cndmask_b32_e64 v197, 0, v197, s[36:37]
	v_add_u32_e32 v86, 100, v84
	v_cmp_gt_u32_e64 s[36:37], s98, v86
	v_cndmask_b32_e64 v198, 0, v198, s[78:79]
	v_add_u32_e32 v87, 104, v84
	v_cmp_gt_u32_e64 s[78:79], s98, v87
	v_cndmask_b32_e64 v199, 0, v199, s[50:51]
	v_add_u32_e32 v88, 108, v84
	v_cmp_gt_u32_e64 s[50:51], s98, v88
	v_nop
	v_cndmask_b32_e64 v200, 0, v200, s[30:31]
	v_cndmask_b32_e64 v201, 0, v201, s[36:37]
	v_cndmask_b32_e64 v202, 0, v202, s[78:79]
	v_cndmask_b32_e64 v203, 0, v203, s[50:51]
	v_cvt_pk_bf16_f32 v64, v188, v189
	v_cvt_pk_bf16_f32 v65, v190, v191
	v_cvt_pk_bf16_f32 v66, v192, v193
	v_cvt_pk_bf16_f32 v67, v194, v195
	v_cvt_pk_bf16_f32 v68, v196, v197
	v_cvt_pk_bf16_f32 v69, v198, v199
	v_cvt_pk_bf16_f32 v70, v200, v201
	v_cvt_pk_bf16_f32 v71, v202, v203
	v_pk_add_f32 v[232:233], v[232:233], v[188:189]
	v_pk_add_f32 v[232:233], v[232:233], v[190:191]
	v_pk_add_f32 v[232:233], v[232:233], v[192:193]
	v_pk_add_f32 v[232:233], v[232:233], v[194:195]
	v_pk_add_f32 v[232:233], v[232:233], v[196:197]
	v_pk_add_f32 v[232:233], v[232:233], v[198:199]
	v_pk_add_f32 v[232:233], v[232:233], v[200:201]
	v_pk_add_f32 v[232:233], v[232:233], v[202:203]
	ds_read2_b32 v[188:189], v115 offset0:32 offset1:33
	ds_read2_b32 v[190:191], v115 offset0:34 offset1:35
	ds_read2_b32 v[192:193], v115 offset0:40 offset1:41
	ds_read2_b32 v[194:195], v115 offset0:42 offset1:43
	ds_read2_b32 v[196:197], v115 offset0:48 offset1:49
	ds_read2_b32 v[198:199], v115 offset0:50 offset1:51
	ds_read2_b32 v[200:201], v115 offset0:56 offset1:57
	ds_read2_b32 v[202:203], v115 offset0:58 offset1:59
	v_mfma_f32_32x32x16_bf16 v[0:15], v[64:67], v[72:75], v[0:15]
	v_mfma_f32_32x32x16_bf16 v[16:31], v[64:67], v[76:79], v[16:31]
	v_mfma_f32_32x32x16_bf16 v[0:15], v[68:71], v[220:223], v[0:15]
	v_mfma_f32_32x32x16_bf16 v[16:31], v[68:71], v[224:227], v[16:31]
	s_add_i32 s90, s67, 0
	v_add_u32_e32 v80, s90, v243
	v_add_u32_e32 v83, s90, v244
	v_add_u32_e32 v99, s90, v245
	v_add_u32_e32 v253, s90, v246
	v_add_u32_e32 v254, s90, v148
	v_add_u32_e32 v255, s90, v151
	v_med3_i32 v80, v80, 0, s99
	v_med3_i32 v83, v83, 0, s99
	v_med3_i32 v99, v99, 0, s99
	v_med3_i32 v253, v253, 0, s99
	v_med3_i32 v254, v254, 0, s99
	v_med3_i32 v255, v255, 0, s99
	v_mad_u32_u24 v80, v80, s100, v252
	v_mad_u32_u24 v83, v83, s100, v252
	v_mad_u32_u24 v99, v99, s100, v252
	v_mad_u32_u24 v253, v253, s100, v252
	v_mad_u32_u24 v254, v254, s100, v153
	v_mad_u32_u24 v255, v255, s100, v153
	global_load_dwordx4 v[116:119], v80, s[82:83]
	global_load_dwordx4 v[120:123], v83, s[82:83]
	global_load_dwordx4 v[124:127], v99, s[82:83]
	global_load_dwordx4 v[128:131], v253, s[82:83]
	global_load_dwordx4 v[132:135], v254, s[82:83] offset:768
	global_load_dwordx4 v[136:139], v255, s[82:83] offset:768
	global_load_dwordx4 v[140:143], v254, s[82:83] offset:832
	global_load_dwordx4 v[144:147], v255, s[82:83] offset:832
	ds_read_b64_tr_b16 v[72:73], v231
	ds_read_b64_tr_b16 v[74:75], v231 offset:512
	ds_read_b64_tr_b16 v[76:77], v231 offset:2048
	ds_read_b64_tr_b16 v[78:79], v231 offset:2560
	ds_read_b64_tr_b16 v[220:221], v231 offset:1024
	ds_read_b64_tr_b16 v[222:223], v231 offset:1536
	ds_read_b64_tr_b16 v[224:225], v231 offset:3072
	ds_read_b64_tr_b16 v[226:227], v231 offset:3584
	s_waitcnt vmcnt(8)
	ds_write_b128 v247, v[156:159]
	ds_write_b128 v247, v[160:163] offset:1024
	ds_write_b128 v111, v[164:167] offset:2048
	ds_write_b128 v111, v[168:171] offset:3072
	ds_read_b128 v[156:159], v248
	ds_read_b128 v[160:163], v249
	ds_read_b128 v[164:167], v250
	ds_read_b128 v[168:171], v251
	ds_write_b128 v112, v[172:175]
	ds_write_b128 v112, v[176:179] offset:1024
	ds_write_b128 v112, v[180:183] offset:2048
	ds_write_b128 v112, v[184:187] offset:3072
	v_exp_f32_e32 v32, v32
	v_exp_f32_e32 v33, v33
	v_exp_f32_e32 v34, v34
	v_exp_f32_e32 v35, v35
	v_exp_f32_e32 v36, v36
	v_exp_f32_e32 v37, v37
	s_waitcnt lgkmcnt(4)
	v_mfma_f32_32x32x16_bf16 v[188:203], v[156:159], v[48:51], v[188:203]
	v_exp_f32_e32 v38, v38
	v_exp_f32_e32 v39, v39
	v_mfma_f32_32x32x16_bf16 v[188:203], v[160:163], v[52:55], v[188:203]
	v_exp_f32_e32 v40, v40
	v_exp_f32_e32 v41, v41
	v_exp_f32_e32 v42, v42
	v_mfma_f32_32x32x16_bf16 v[188:203], v[164:167], v[56:59], v[188:203]
	v_exp_f32_e32 v43, v43
	v_exp_f32_e32 v44, v44
	v_mfma_f32_32x32x16_bf16 v[188:203], v[168:171], v[60:63], v[188:203]
	v_exp_f32_e32 v45, v45
	v_exp_f32_e32 v46, v46
	v_exp_f32_e32 v47, v47
	s_add_i32 s90, s67, -1024
	v_lshlrev_b32_e32 v84, 4, v107
	v_add_u32_e32 v84, s90, v84
	v_add_u32_e32 v85, 0, v84
	v_add_u32_e32 v86, 16, v84
	v_add_u32_e32 v87, 32, v84
	v_add_u32_e32 v88, 48, v84
	v_cmp_gt_u32_e64 s[30:31], s98, v85
	v_cmp_gt_u32_e64 s[36:37], s98, v86
	v_cmp_gt_u32_e64 s[78:79], s98, v87
	v_cmp_gt_u32_e64 s[50:51], s98, v88
	v_cndmask_b32_e64 v32, 0, v32, s[30:31]
	v_add_u32_e32 v85, 128, v84
	v_cmp_gt_u32_e64 s[30:31], s98, v85
	v_cndmask_b32_e64 v33, 0, v33, s[36:37]
	v_add_u32_e32 v86, 144, v84
	v_cmp_gt_u32_e64 s[36:37], s98, v86
	v_cndmask_b32_e64 v34, 0, v34, s[78:79]
	v_add_u32_e32 v87, 160, v84
	v_cmp_gt_u32_e64 s[78:79], s98, v87
	v_cndmask_b32_e64 v35, 0, v35, s[50:51]
	v_add_u32_e32 v88, 176, v84
	v_cmp_gt_u32_e64 s[50:51], s98, v88
	v_cndmask_b32_e64 v36, 0, v36, s[30:31]
	v_add_u32_e32 v85, 256, v84
	v_cmp_gt_u32_e64 s[30:31], s98, v85
	v_cndmask_b32_e64 v37, 0, v37, s[36:37]
	v_add_u32_e32 v86, 272, v84
	v_cmp_gt_u32_e64 s[36:37], s98, v86
	v_cndmask_b32_e64 v38, 0, v38, s[78:79]
	v_add_u32_e32 v87, 288, v84
	v_cmp_gt_u32_e64 s[78:79], s98, v87
	v_cndmask_b32_e64 v39, 0, v39, s[50:51]
	v_add_u32_e32 v88, 304, v84
	v_cmp_gt_u32_e64 s[50:51], s98, v88
	v_cndmask_b32_e64 v40, 0, v40, s[30:31]
	v_add_u32_e32 v85, 384, v84
	v_cmp_gt_u32_e64 s[30:31], s98, v85
	v_cndmask_b32_e64 v41, 0, v41, s[36:37]
	v_add_u32_e32 v86, 400, v84
	v_cmp_gt_u32_e64 s[36:37], s98, v86
	v_cndmask_b32_e64 v42, 0, v42, s[78:79]
	v_add_u32_e32 v87, 416, v84
	v_cmp_gt_u32_e64 s[78:79], s98, v87
	v_cndmask_b32_e64 v43, 0, v43, s[50:51]
	v_add_u32_e32 v88, 432, v84
	v_cmp_gt_u32_e64 s[50:51], s98, v88
	v_nop
	v_cndmask_b32_e64 v44, 0, v44, s[30:31]
	v_cndmask_b32_e64 v45, 0, v45, s[36:37]
	v_cndmask_b32_e64 v46, 0, v46, s[78:79]
	v_cndmask_b32_e64 v47, 0, v47, s[50:51]
	v_cvt_pk_bf16_f32 v64, v32, v33
	v_cvt_pk_bf16_f32 v65, v34, v35
	v_cvt_pk_bf16_f32 v66, v36, v37
	v_cvt_pk_bf16_f32 v67, v38, v39
	v_cvt_pk_bf16_f32 v68, v40, v41
	v_cvt_pk_bf16_f32 v69, v42, v43
	v_cvt_pk_bf16_f32 v70, v44, v45
	v_cvt_pk_bf16_f32 v71, v46, v47
	v_pk_add_f32 v[232:233], v[232:233], v[32:33]
	v_pk_add_f32 v[232:233], v[232:233], v[34:35]
	v_pk_add_f32 v[232:233], v[232:233], v[36:37]
	v_pk_add_f32 v[232:233], v[232:233], v[38:39]
	v_pk_add_f32 v[232:233], v[232:233], v[40:41]
	v_pk_add_f32 v[232:233], v[232:233], v[42:43]
	v_pk_add_f32 v[232:233], v[232:233], v[44:45]
	v_pk_add_f32 v[232:233], v[232:233], v[46:47]
	ds_read2_b32 v[32:33], v115 offset0:64 offset1:65
	ds_read2_b32 v[34:35], v115 offset0:66 offset1:67
	ds_read2_b32 v[36:37], v115 offset0:72 offset1:73
	ds_read2_b32 v[38:39], v115 offset0:74 offset1:75
	ds_read2_b32 v[40:41], v115 offset0:80 offset1:81
	ds_read2_b32 v[42:43], v115 offset0:82 offset1:83
	ds_read2_b32 v[44:45], v115 offset0:88 offset1:89
	ds_read2_b32 v[46:47], v115 offset0:90 offset1:91
	v_mfma_f32_32x32x16_bf16 v[0:15], v[64:67], v[72:75], v[0:15]
	v_mfma_f32_32x32x16_bf16 v[16:31], v[64:67], v[76:79], v[16:31]
	v_mfma_f32_32x32x16_bf16 v[0:15], v[68:71], v[220:223], v[0:15]
	v_mfma_f32_32x32x16_bf16 v[16:31], v[68:71], v[224:227], v[16:31]
	s_add_i32 s90, s67, 512
	v_add_u32_e32 v80, s90, v243
	v_add_u32_e32 v83, s90, v244
	v_add_u32_e32 v99, s90, v245
	v_add_u32_e32 v253, s90, v246
	v_add_u32_e32 v254, s90, v148
	v_add_u32_e32 v255, s90, v151
	v_med3_i32 v80, v80, 0, s99
	v_med3_i32 v83, v83, 0, s99
	v_med3_i32 v99, v99, 0, s99
	v_med3_i32 v253, v253, 0, s99
	v_med3_i32 v254, v254, 0, s99
	v_med3_i32 v255, v255, 0, s99
	v_mad_u32_u24 v80, v80, s100, v252
	v_mad_u32_u24 v83, v83, s100, v252
	v_mad_u32_u24 v99, v99, s100, v252
	v_mad_u32_u24 v253, v253, s100, v252
	v_mad_u32_u24 v254, v254, s100, v153
	v_mad_u32_u24 v255, v255, s100, v153
	global_load_dwordx4 v[156:159], v80, s[82:83]
	global_load_dwordx4 v[160:163], v83, s[82:83]
	global_load_dwordx4 v[164:167], v99, s[82:83]
	global_load_dwordx4 v[168:171], v253, s[82:83]
	global_load_dwordx4 v[172:175], v254, s[82:83] offset:768
	global_load_dwordx4 v[176:179], v255, s[82:83] offset:768
	global_load_dwordx4 v[180:183], v254, s[82:83] offset:832
	global_load_dwordx4 v[184:187], v255, s[82:83] offset:832
	ds_read_b64_tr_b16 v[72:73], v231
	ds_read_b64_tr_b16 v[74:75], v231 offset:512
	ds_read_b64_tr_b16 v[76:77], v231 offset:2048
	ds_read_b64_tr_b16 v[78:79], v231 offset:2560
	ds_read_b64_tr_b16 v[220:221], v231 offset:1024
	ds_read_b64_tr_b16 v[222:223], v231 offset:1536
	ds_read_b64_tr_b16 v[224:225], v231 offset:3072
	ds_read_b64_tr_b16 v[226:227], v231 offset:3584
	s_waitcnt vmcnt(8)
	ds_write_b128 v247, v[116:119]
	ds_write_b128 v247, v[120:123] offset:1024
	ds_write_b128 v111, v[124:127] offset:2048
	ds_write_b128 v111, v[128:131] offset:3072
	ds_read_b128 v[116:119], v248
	ds_read_b128 v[120:123], v249
	ds_read_b128 v[124:127], v250
	ds_read_b128 v[128:131], v251
	ds_write_b128 v112, v[132:135]
	ds_write_b128 v112, v[136:139] offset:1024
	ds_write_b128 v112, v[140:143] offset:2048
	ds_write_b128 v112, v[144:147] offset:3072
	v_exp_f32_e32 v188, v188
	v_exp_f32_e32 v189, v189
	v_exp_f32_e32 v190, v190
	v_exp_f32_e32 v191, v191
	v_exp_f32_e32 v192, v192
	v_exp_f32_e32 v193, v193
	s_waitcnt lgkmcnt(4)
	v_mfma_f32_32x32x16_bf16 v[32:47], v[116:119], v[48:51], v[32:47]
	v_exp_f32_e32 v194, v194
	v_exp_f32_e32 v195, v195
	v_mfma_f32_32x32x16_bf16 v[32:47], v[120:123], v[52:55], v[32:47]
	v_exp_f32_e32 v196, v196
	v_exp_f32_e32 v197, v197
	v_exp_f32_e32 v198, v198
	v_mfma_f32_32x32x16_bf16 v[32:47], v[124:127], v[56:59], v[32:47]
	v_exp_f32_e32 v199, v199
	v_exp_f32_e32 v200, v200
	v_mfma_f32_32x32x16_bf16 v[32:47], v[128:131], v[60:63], v[32:47]
	v_exp_f32_e32 v201, v201
	v_exp_f32_e32 v202, v202
	v_exp_f32_e32 v203, v203
	s_add_i32 s90, s67, -512
	v_lshlrev_b32_e32 v84, 4, v107
	v_add_u32_e32 v84, s90, v84
	v_add_u32_e32 v85, 0, v84
	v_add_u32_e32 v86, 16, v84
	v_add_u32_e32 v87, 32, v84
	v_add_u32_e32 v88, 48, v84
	v_cmp_gt_u32_e64 s[30:31], s98, v85
	v_cmp_gt_u32_e64 s[36:37], s98, v86
	v_cmp_gt_u32_e64 s[78:79], s98, v87
	v_cmp_gt_u32_e64 s[50:51], s98, v88
	v_cndmask_b32_e64 v188, 0, v188, s[30:31]
	v_add_u32_e32 v85, 128, v84
	v_cmp_gt_u32_e64 s[30:31], s98, v85
	v_cndmask_b32_e64 v189, 0, v189, s[36:37]
	v_add_u32_e32 v86, 144, v84
	v_cmp_gt_u32_e64 s[36:37], s98, v86
	v_cndmask_b32_e64 v190, 0, v190, s[78:79]
	v_add_u32_e32 v87, 160, v84
	v_cmp_gt_u32_e64 s[78:79], s98, v87
	v_cndmask_b32_e64 v191, 0, v191, s[50:51]
	v_add_u32_e32 v88, 176, v84
	v_cmp_gt_u32_e64 s[50:51], s98, v88
	v_cndmask_b32_e64 v192, 0, v192, s[30:31]
	v_add_u32_e32 v85, 256, v84
	v_cmp_gt_u32_e64 s[30:31], s98, v85
	v_cndmask_b32_e64 v193, 0, v193, s[36:37]
	v_add_u32_e32 v86, 272, v84
	v_cmp_gt_u32_e64 s[36:37], s98, v86
	v_cndmask_b32_e64 v194, 0, v194, s[78:79]
	v_add_u32_e32 v87, 288, v84
	v_cmp_gt_u32_e64 s[78:79], s98, v87
	v_cndmask_b32_e64 v195, 0, v195, s[50:51]
	v_add_u32_e32 v88, 304, v84
	v_cmp_gt_u32_e64 s[50:51], s98, v88
	v_cndmask_b32_e64 v196, 0, v196, s[30:31]
	v_add_u32_e32 v85, 384, v84
	v_cmp_gt_u32_e64 s[30:31], s98, v85
	v_cndmask_b32_e64 v197, 0, v197, s[36:37]
	v_add_u32_e32 v86, 400, v84
	v_cmp_gt_u32_e64 s[36:37], s98, v86
	v_cndmask_b32_e64 v198, 0, v198, s[78:79]
	v_add_u32_e32 v87, 416, v84
	v_cmp_gt_u32_e64 s[78:79], s98, v87
	v_cndmask_b32_e64 v199, 0, v199, s[50:51]
	v_add_u32_e32 v88, 432, v84
	v_cmp_gt_u32_e64 s[50:51], s98, v88
	v_nop
	v_cndmask_b32_e64 v200, 0, v200, s[30:31]
	v_cndmask_b32_e64 v201, 0, v201, s[36:37]
	v_cndmask_b32_e64 v202, 0, v202, s[78:79]
	v_cndmask_b32_e64 v203, 0, v203, s[50:51]
	v_cvt_pk_bf16_f32 v64, v188, v189
	v_cvt_pk_bf16_f32 v65, v190, v191
	v_cvt_pk_bf16_f32 v66, v192, v193
	v_cvt_pk_bf16_f32 v67, v194, v195
	v_cvt_pk_bf16_f32 v68, v196, v197
	v_cvt_pk_bf16_f32 v69, v198, v199
	v_cvt_pk_bf16_f32 v70, v200, v201
	v_cvt_pk_bf16_f32 v71, v202, v203
	v_pk_add_f32 v[232:233], v[232:233], v[188:189]
	v_pk_add_f32 v[232:233], v[232:233], v[190:191]
	v_pk_add_f32 v[232:233], v[232:233], v[192:193]
	v_pk_add_f32 v[232:233], v[232:233], v[194:195]
	v_pk_add_f32 v[232:233], v[232:233], v[196:197]
	v_pk_add_f32 v[232:233], v[232:233], v[198:199]
	v_pk_add_f32 v[232:233], v[232:233], v[200:201]
	v_pk_add_f32 v[232:233], v[232:233], v[202:203]
	ds_read2_b32 v[188:189], v115 offset0:96 offset1:97
	ds_read2_b32 v[190:191], v115 offset0:98 offset1:99
	ds_read2_b32 v[192:193], v115 offset0:104 offset1:105
	ds_read2_b32 v[194:195], v115 offset0:106 offset1:107
	ds_read2_b32 v[196:197], v115 offset0:112 offset1:113
	ds_read2_b32 v[198:199], v115 offset0:114 offset1:115
	ds_read2_b32 v[200:201], v115 offset0:120 offset1:121
	ds_read2_b32 v[202:203], v115 offset0:122 offset1:123
	v_mfma_f32_32x32x16_bf16 v[0:15], v[64:67], v[72:75], v[0:15]
	v_mfma_f32_32x32x16_bf16 v[16:31], v[64:67], v[76:79], v[16:31]
	v_mfma_f32_32x32x16_bf16 v[0:15], v[68:71], v[220:223], v[0:15]
	v_mfma_f32_32x32x16_bf16 v[16:31], v[68:71], v[224:227], v[16:31]
	s_add_i32 s90, s67, 1024
	v_add_u32_e32 v80, s90, v243
	v_add_u32_e32 v83, s90, v244
	v_add_u32_e32 v99, s90, v245
	v_add_u32_e32 v253, s90, v246
	v_add_u32_e32 v254, s90, v148
	v_add_u32_e32 v255, s90, v151
	v_med3_i32 v80, v80, 0, s99
	v_med3_i32 v83, v83, 0, s99
	v_med3_i32 v99, v99, 0, s99
	v_med3_i32 v253, v253, 0, s99
	v_med3_i32 v254, v254, 0, s99
	v_med3_i32 v255, v255, 0, s99
	v_mad_u32_u24 v80, v80, s100, v252
	v_mad_u32_u24 v83, v83, s100, v252
	v_mad_u32_u24 v99, v99, s100, v252
	v_mad_u32_u24 v253, v253, s100, v252
	v_mad_u32_u24 v254, v254, s100, v153
	v_mad_u32_u24 v255, v255, s100, v153
	global_load_dwordx4 v[116:119], v80, s[82:83]
	global_load_dwordx4 v[120:123], v83, s[82:83]
	global_load_dwordx4 v[124:127], v99, s[82:83]
	global_load_dwordx4 v[128:131], v253, s[82:83]
	global_load_dwordx4 v[132:135], v254, s[82:83] offset:768
	global_load_dwordx4 v[136:139], v255, s[82:83] offset:768
	global_load_dwordx4 v[140:143], v254, s[82:83] offset:832
	global_load_dwordx4 v[144:147], v255, s[82:83] offset:832
	ds_read_b64_tr_b16 v[72:73], v231
	ds_read_b64_tr_b16 v[74:75], v231 offset:512
	ds_read_b64_tr_b16 v[76:77], v231 offset:2048
	ds_read_b64_tr_b16 v[78:79], v231 offset:2560
	ds_read_b64_tr_b16 v[220:221], v231 offset:1024
	ds_read_b64_tr_b16 v[222:223], v231 offset:1536
	ds_read_b64_tr_b16 v[224:225], v231 offset:3072
	ds_read_b64_tr_b16 v[226:227], v231 offset:3584
	s_waitcnt vmcnt(8)
	ds_write_b128 v247, v[156:159]
	ds_write_b128 v247, v[160:163] offset:1024
	ds_write_b128 v111, v[164:167] offset:2048
	ds_write_b128 v111, v[168:171] offset:3072
	ds_read_b128 v[156:159], v248
	ds_read_b128 v[160:163], v249
	ds_read_b128 v[164:167], v250
	ds_read_b128 v[168:171], v251
	ds_write_b128 v112, v[172:175]
	ds_write_b128 v112, v[176:179] offset:1024
	ds_write_b128 v112, v[180:183] offset:2048
	ds_write_b128 v112, v[184:187] offset:3072
	v_exp_f32_e32 v32, v32
	v_exp_f32_e32 v33, v33
	v_exp_f32_e32 v34, v34
	v_exp_f32_e32 v35, v35
	v_exp_f32_e32 v36, v36
	v_exp_f32_e32 v37, v37
	s_waitcnt lgkmcnt(4)
	v_mfma_f32_32x32x16_bf16 v[188:203], v[156:159], v[48:51], v[188:203]
	v_exp_f32_e32 v38, v38
	v_exp_f32_e32 v39, v39
	v_mfma_f32_32x32x16_bf16 v[188:203], v[160:163], v[52:55], v[188:203]
	v_exp_f32_e32 v40, v40
	v_exp_f32_e32 v41, v41
	v_exp_f32_e32 v42, v42
	v_mfma_f32_32x32x16_bf16 v[188:203], v[164:167], v[56:59], v[188:203]
	v_exp_f32_e32 v43, v43
	v_exp_f32_e32 v44, v44
	v_mfma_f32_32x32x16_bf16 v[188:203], v[168:171], v[60:63], v[188:203]
	v_exp_f32_e32 v45, v45
	v_exp_f32_e32 v46, v46
	v_exp_f32_e32 v47, v47
	s_add_i32 s90, s67, 0
	v_lshlrev_b32_e32 v84, 4, v107
	v_add_u32_e32 v84, s90, v84
	v_add_u32_e32 v85, 0, v84
	v_add_u32_e32 v86, 16, v84
	v_add_u32_e32 v87, 32, v84
	v_add_u32_e32 v88, 48, v84
	v_cmp_gt_u32_e64 s[30:31], s98, v85
	v_cmp_gt_u32_e64 s[36:37], s98, v86
	v_cmp_gt_u32_e64 s[78:79], s98, v87
	v_cmp_gt_u32_e64 s[50:51], s98, v88
	v_cndmask_b32_e64 v32, 0, v32, s[30:31]
	v_add_u32_e32 v85, 128, v84
	v_cmp_gt_u32_e64 s[30:31], s98, v85
	v_cndmask_b32_e64 v33, 0, v33, s[36:37]
	v_add_u32_e32 v86, 144, v84
	v_cmp_gt_u32_e64 s[36:37], s98, v86
	v_cndmask_b32_e64 v34, 0, v34, s[78:79]
	v_add_u32_e32 v87, 160, v84
	v_cmp_gt_u32_e64 s[78:79], s98, v87
	v_cndmask_b32_e64 v35, 0, v35, s[50:51]
	v_add_u32_e32 v88, 176, v84
	v_cmp_gt_u32_e64 s[50:51], s98, v88
	v_cndmask_b32_e64 v36, 0, v36, s[30:31]
	v_add_u32_e32 v85, 256, v84
	v_cmp_gt_u32_e64 s[30:31], s98, v85
	v_cndmask_b32_e64 v37, 0, v37, s[36:37]
	v_add_u32_e32 v86, 272, v84
	v_cmp_gt_u32_e64 s[36:37], s98, v86
	v_cndmask_b32_e64 v38, 0, v38, s[78:79]
	v_add_u32_e32 v87, 288, v84
	v_cmp_gt_u32_e64 s[78:79], s98, v87
	v_cndmask_b32_e64 v39, 0, v39, s[50:51]
	v_add_u32_e32 v88, 304, v84
	v_cmp_gt_u32_e64 s[50:51], s98, v88
	v_cndmask_b32_e64 v40, 0, v40, s[30:31]
	v_add_u32_e32 v85, 384, v84
	v_cmp_gt_u32_e64 s[30:31], s98, v85
	v_cndmask_b32_e64 v41, 0, v41, s[36:37]
	v_add_u32_e32 v86, 400, v84
	v_cmp_gt_u32_e64 s[36:37], s98, v86
	v_cndmask_b32_e64 v42, 0, v42, s[78:79]
	v_add_u32_e32 v87, 416, v84
	v_cmp_gt_u32_e64 s[78:79], s98, v87
	v_cndmask_b32_e64 v43, 0, v43, s[50:51]
	v_add_u32_e32 v88, 432, v84
	v_cmp_gt_u32_e64 s[50:51], s98, v88
	v_nop
	v_cndmask_b32_e64 v44, 0, v44, s[30:31]
	v_cndmask_b32_e64 v45, 0, v45, s[36:37]
	v_cndmask_b32_e64 v46, 0, v46, s[78:79]
	v_cndmask_b32_e64 v47, 0, v47, s[50:51]
	v_cvt_pk_bf16_f32 v64, v32, v33
	v_cvt_pk_bf16_f32 v65, v34, v35
	v_cvt_pk_bf16_f32 v66, v36, v37
	v_cvt_pk_bf16_f32 v67, v38, v39
	v_cvt_pk_bf16_f32 v68, v40, v41
	v_cvt_pk_bf16_f32 v69, v42, v43
	v_cvt_pk_bf16_f32 v70, v44, v45
	v_cvt_pk_bf16_f32 v71, v46, v47
	v_pk_add_f32 v[232:233], v[232:233], v[32:33]
	v_pk_add_f32 v[232:233], v[232:233], v[34:35]
	v_pk_add_f32 v[232:233], v[232:233], v[36:37]
	v_pk_add_f32 v[232:233], v[232:233], v[38:39]
	v_pk_add_f32 v[232:233], v[232:233], v[40:41]
	v_pk_add_f32 v[232:233], v[232:233], v[42:43]
	v_pk_add_f32 v[232:233], v[232:233], v[44:45]
	v_pk_add_f32 v[232:233], v[232:233], v[46:47]
	ds_read2_b32 v[32:33], v115 offset0:128 offset1:129
	ds_read2_b32 v[34:35], v115 offset0:130 offset1:131
	ds_read2_b32 v[36:37], v115 offset0:136 offset1:137
	ds_read2_b32 v[38:39], v115 offset0:138 offset1:139
	ds_read2_b32 v[40:41], v115 offset0:144 offset1:145
	ds_read2_b32 v[42:43], v115 offset0:146 offset1:147
	ds_read2_b32 v[44:45], v115 offset0:152 offset1:153
	ds_read2_b32 v[46:47], v115 offset0:154 offset1:155
	v_mfma_f32_32x32x16_bf16 v[0:15], v[64:67], v[72:75], v[0:15]
	v_mfma_f32_32x32x16_bf16 v[16:31], v[64:67], v[76:79], v[16:31]
	v_mfma_f32_32x32x16_bf16 v[0:15], v[68:71], v[220:223], v[0:15]
	v_mfma_f32_32x32x16_bf16 v[16:31], v[68:71], v[224:227], v[16:31]
	ds_read_b64_tr_b16 v[72:73], v231
	ds_read_b64_tr_b16 v[74:75], v231 offset:512
	ds_read_b64_tr_b16 v[76:77], v231 offset:2048
	ds_read_b64_tr_b16 v[78:79], v231 offset:2560
	ds_read_b64_tr_b16 v[220:221], v231 offset:1024
	ds_read_b64_tr_b16 v[222:223], v231 offset:1536
	ds_read_b64_tr_b16 v[224:225], v231 offset:3072
	ds_read_b64_tr_b16 v[226:227], v231 offset:3584
	s_waitcnt vmcnt(0)
	ds_write_b128 v247, v[116:119]
	ds_write_b128 v247, v[120:123] offset:1024
	ds_write_b128 v111, v[124:127] offset:2048
	ds_write_b128 v111, v[128:131] offset:3072
	ds_read_b128 v[116:119], v248
	ds_read_b128 v[120:123], v249
	ds_read_b128 v[124:127], v250
	ds_read_b128 v[128:131], v251
	ds_write_b128 v112, v[132:135]
	ds_write_b128 v112, v[136:139] offset:1024
	ds_write_b128 v112, v[140:143] offset:2048
	ds_write_b128 v112, v[144:147] offset:3072
	v_exp_f32_e32 v188, v188
	v_exp_f32_e32 v189, v189
	v_exp_f32_e32 v190, v190
	v_exp_f32_e32 v191, v191
	v_exp_f32_e32 v192, v192
	v_exp_f32_e32 v193, v193
	s_waitcnt lgkmcnt(4)
	v_mfma_f32_32x32x16_bf16 v[32:47], v[116:119], v[48:51], v[32:47]
	v_exp_f32_e32 v194, v194
	v_exp_f32_e32 v195, v195
	v_mfma_f32_32x32x16_bf16 v[32:47], v[120:123], v[52:55], v[32:47]
	v_exp_f32_e32 v196, v196
	v_exp_f32_e32 v197, v197
	v_exp_f32_e32 v198, v198
	v_mfma_f32_32x32x16_bf16 v[32:47], v[124:127], v[56:59], v[32:47]
	v_exp_f32_e32 v199, v199
	v_exp_f32_e32 v200, v200
	v_mfma_f32_32x32x16_bf16 v[32:47], v[128:131], v[60:63], v[32:47]
	v_exp_f32_e32 v201, v201
	v_exp_f32_e32 v202, v202
	v_exp_f32_e32 v203, v203
	s_add_i32 s90, s67, 512
	v_lshlrev_b32_e32 v84, 4, v107
	v_add_u32_e32 v84, s90, v84
	v_add_u32_e32 v85, 0, v84
	v_add_u32_e32 v86, 16, v84
	v_add_u32_e32 v87, 32, v84
	v_add_u32_e32 v88, 48, v84
	v_cmp_gt_u32_e64 s[30:31], s98, v85
	v_cmp_gt_u32_e64 s[36:37], s98, v86
	v_cmp_gt_u32_e64 s[78:79], s98, v87
	v_cmp_gt_u32_e64 s[50:51], s98, v88
	v_cndmask_b32_e64 v188, 0, v188, s[30:31]
	v_add_u32_e32 v85, 128, v84
	v_cmp_gt_u32_e64 s[30:31], s98, v85
	v_cndmask_b32_e64 v189, 0, v189, s[36:37]
	v_add_u32_e32 v86, 144, v84
	v_cmp_gt_u32_e64 s[36:37], s98, v86
	v_cndmask_b32_e64 v190, 0, v190, s[78:79]
	v_add_u32_e32 v87, 160, v84
	v_cmp_gt_u32_e64 s[78:79], s98, v87
	v_cndmask_b32_e64 v191, 0, v191, s[50:51]
	v_add_u32_e32 v88, 176, v84
	v_cmp_gt_u32_e64 s[50:51], s98, v88
	v_cndmask_b32_e64 v192, 0, v192, s[30:31]
	v_add_u32_e32 v85, 256, v84
	v_cmp_gt_u32_e64 s[30:31], s98, v85
	v_cndmask_b32_e64 v193, 0, v193, s[36:37]
	v_add_u32_e32 v86, 272, v84
	v_cmp_gt_u32_e64 s[36:37], s98, v86
	v_cndmask_b32_e64 v194, 0, v194, s[78:79]
	v_add_u32_e32 v87, 288, v84
	v_cmp_gt_u32_e64 s[78:79], s98, v87
	v_cndmask_b32_e64 v195, 0, v195, s[50:51]
	v_add_u32_e32 v88, 304, v84
	v_cmp_gt_u32_e64 s[50:51], s98, v88
	v_cndmask_b32_e64 v196, 0, v196, s[30:31]
	v_add_u32_e32 v85, 384, v84
	v_cmp_gt_u32_e64 s[30:31], s98, v85
	v_cndmask_b32_e64 v197, 0, v197, s[36:37]
	v_add_u32_e32 v86, 400, v84
	v_cmp_gt_u32_e64 s[36:37], s98, v86
	v_cndmask_b32_e64 v198, 0, v198, s[78:79]
	v_add_u32_e32 v87, 416, v84
	v_cmp_gt_u32_e64 s[78:79], s98, v87
	v_cndmask_b32_e64 v199, 0, v199, s[50:51]
	v_add_u32_e32 v88, 432, v84
	v_cmp_gt_u32_e64 s[50:51], s98, v88
	v_nop
	v_cndmask_b32_e64 v200, 0, v200, s[30:31]
	v_cndmask_b32_e64 v201, 0, v201, s[36:37]
	v_cndmask_b32_e64 v202, 0, v202, s[78:79]
	v_cndmask_b32_e64 v203, 0, v203, s[50:51]
	v_cvt_pk_bf16_f32 v64, v188, v189
	v_cvt_pk_bf16_f32 v65, v190, v191
	v_cvt_pk_bf16_f32 v66, v192, v193
	v_cvt_pk_bf16_f32 v67, v194, v195
	v_cvt_pk_bf16_f32 v68, v196, v197
	v_cvt_pk_bf16_f32 v69, v198, v199
	v_cvt_pk_bf16_f32 v70, v200, v201
	v_cvt_pk_bf16_f32 v71, v202, v203
	v_pk_add_f32 v[232:233], v[232:233], v[188:189]
	v_pk_add_f32 v[232:233], v[232:233], v[190:191]
	v_pk_add_f32 v[232:233], v[232:233], v[192:193]
	v_pk_add_f32 v[232:233], v[232:233], v[194:195]
	v_pk_add_f32 v[232:233], v[232:233], v[196:197]
	v_pk_add_f32 v[232:233], v[232:233], v[198:199]
	v_pk_add_f32 v[232:233], v[232:233], v[200:201]
	v_pk_add_f32 v[232:233], v[232:233], v[202:203]
	v_mfma_f32_32x32x16_bf16 v[0:15], v[64:67], v[72:75], v[0:15]
	v_mfma_f32_32x32x16_bf16 v[16:31], v[64:67], v[76:79], v[16:31]
	v_mfma_f32_32x32x16_bf16 v[0:15], v[68:71], v[220:223], v[0:15]
	v_mfma_f32_32x32x16_bf16 v[16:31], v[68:71], v[224:227], v[16:31]
	ds_read_b64_tr_b16 v[72:73], v231
	ds_read_b64_tr_b16 v[74:75], v231 offset:512
	ds_read_b64_tr_b16 v[76:77], v231 offset:2048
	ds_read_b64_tr_b16 v[78:79], v231 offset:2560
	ds_read_b64_tr_b16 v[220:221], v231 offset:1024
	ds_read_b64_tr_b16 v[222:223], v231 offset:1536
	ds_read_b64_tr_b16 v[224:225], v231 offset:3072
	ds_read_b64_tr_b16 v[226:227], v231 offset:3584
	s_waitcnt lgkmcnt(0)
; __device__ __forceinline__ int crow(int r, int hi) { return (r & 3) + 8 * (r >> 2) + 4 * hi; }
; __device__ __forceinline__ void dil_unit(LAS unsigned char* lds, bf16_t* proj, int seq, int hd, int T0, int rho) {
;     ...
;     l += __shfl_xor(l, 32);
; #pragma unroll
;     for (int rr = 0; rr < 16; ++rr) {
;         const int j = crow(rr, hi);
;         const float il = __builtin_amdgcn_rcpf(__shfl(l, j));
	v_exp_f32_e32 v32, v32
	v_exp_f32_e32 v33, v33
	v_exp_f32_e32 v34, v34
	v_exp_f32_e32 v35, v35
	v_exp_f32_e32 v36, v36
	v_exp_f32_e32 v37, v37
	v_exp_f32_e32 v38, v38
	v_exp_f32_e32 v39, v39
	v_exp_f32_e32 v40, v40
	v_exp_f32_e32 v41, v41
	v_exp_f32_e32 v42, v42
	v_exp_f32_e32 v43, v43
	v_exp_f32_e32 v44, v44
	v_exp_f32_e32 v45, v45
	v_exp_f32_e32 v46, v46
	v_exp_f32_e32 v47, v47
	s_add_i32 s90, s67, 1024
	v_lshlrev_b32_e32 v84, 4, v107
	v_add_u32_e32 v84, s90, v84
	v_add_u32_e32 v85, 0, v84
	v_add_u32_e32 v86, 16, v84
	v_add_u32_e32 v87, 32, v84
	v_add_u32_e32 v88, 48, v84
	v_cmp_gt_u32_e64 s[30:31], s98, v85
	v_cmp_gt_u32_e64 s[36:37], s98, v86
	v_cmp_gt_u32_e64 s[78:79], s98, v87
	v_cmp_gt_u32_e64 s[50:51], s98, v88
	v_cndmask_b32_e64 v32, 0, v32, s[30:31]
	v_add_u32_e32 v85, 128, v84
	v_cmp_gt_u32_e64 s[30:31], s98, v85
	v_cndmask_b32_e64 v33, 0, v33, s[36:37]
	v_add_u32_e32 v86, 144, v84
	v_cmp_gt_u32_e64 s[36:37], s98, v86
	v_cndmask_b32_e64 v34, 0, v34, s[78:79]
	v_add_u32_e32 v87, 160, v84
	v_cmp_gt_u32_e64 s[78:79], s98, v87
	v_cndmask_b32_e64 v35, 0, v35, s[50:51]
	v_add_u32_e32 v88, 176, v84
	v_cmp_gt_u32_e64 s[50:51], s98, v88
	v_cndmask_b32_e64 v36, 0, v36, s[30:31]
	v_add_u32_e32 v85, 256, v84
	v_cmp_gt_u32_e64 s[30:31], s98, v85
	v_cndmask_b32_e64 v37, 0, v37, s[36:37]
	v_add_u32_e32 v86, 272, v84
	v_cmp_gt_u32_e64 s[36:37], s98, v86
	v_cndmask_b32_e64 v38, 0, v38, s[78:79]
	v_add_u32_e32 v87, 288, v84
	v_cmp_gt_u32_e64 s[78:79], s98, v87
	v_cndmask_b32_e64 v39, 0, v39, s[50:51]
	v_add_u32_e32 v88, 304, v84
	v_cmp_gt_u32_e64 s[50:51], s98, v88
	v_cndmask_b32_e64 v40, 0, v40, s[30:31]
	v_add_u32_e32 v85, 384, v84
	v_cmp_gt_u32_e64 s[30:31], s98, v85
	v_cndmask_b32_e64 v41, 0, v41, s[36:37]
	v_add_u32_e32 v86, 400, v84
	v_cmp_gt_u32_e64 s[36:37], s98, v86
	v_cndmask_b32_e64 v42, 0, v42, s[78:79]
	v_add_u32_e32 v87, 416, v84
	v_cmp_gt_u32_e64 s[78:79], s98, v87
	v_cndmask_b32_e64 v43, 0, v43, s[50:51]
	v_add_u32_e32 v88, 432, v84
	v_cmp_gt_u32_e64 s[50:51], s98, v88
	v_nop
	v_cndmask_b32_e64 v44, 0, v44, s[30:31]
	v_cndmask_b32_e64 v45, 0, v45, s[36:37]
	v_cndmask_b32_e64 v46, 0, v46, s[78:79]
	v_cndmask_b32_e64 v47, 0, v47, s[50:51]
	v_cvt_pk_bf16_f32 v64, v32, v33
	v_cvt_pk_bf16_f32 v65, v34, v35
	v_cvt_pk_bf16_f32 v66, v36, v37
	v_cvt_pk_bf16_f32 v67, v38, v39
	v_cvt_pk_bf16_f32 v68, v40, v41
	v_cvt_pk_bf16_f32 v69, v42, v43
	v_cvt_pk_bf16_f32 v70, v44, v45
	v_cvt_pk_bf16_f32 v71, v46, v47
	v_pk_add_f32 v[232:233], v[232:233], v[32:33]
	v_pk_add_f32 v[232:233], v[232:233], v[34:35]
	v_pk_add_f32 v[232:233], v[232:233], v[36:37]
	v_pk_add_f32 v[232:233], v[232:233], v[38:39]
	v_pk_add_f32 v[232:233], v[232:233], v[40:41]
	v_pk_add_f32 v[232:233], v[232:233], v[42:43]
	v_pk_add_f32 v[232:233], v[232:233], v[44:45]
	v_pk_add_f32 v[232:233], v[232:233], v[46:47]
	v_mfma_f32_32x32x16_bf16 v[0:15], v[64:67], v[72:75], v[0:15]
	v_mfma_f32_32x32x16_bf16 v[16:31], v[64:67], v[76:79], v[16:31]
	v_mfma_f32_32x32x16_bf16 v[0:15], v[68:71], v[220:223], v[0:15]
	v_mfma_f32_32x32x16_bf16 v[16:31], v[68:71], v[224:227], v[16:31]
	v_add_f32_e32 v113, v232, v233
	v_or_b32_e32 v114, 1, v107
	v_or_b32_e32 v97, 2, v107
	v_or_b32_e32 v96, 3, v107
	v_or_b32_e32 v95, 8, v107
	v_or_b32_e32 v94, 9, v107
	v_or_b32_e32 v93, 10, v107
	v_or_b32_e32 v92, 11, v107
	v_or_b32_e32 v91, 16, v107
	v_or_b32_e32 v90, 17, v107
	v_or_b32_e32 v89, 18, v107
	v_or_b32_e32 v88, 19, v107
	v_or_b32_e32 v87, 24, v107
	v_or_b32_e32 v86, 25, v107
	v_or_b32_e32 v85, 26, v107
	v_or_b32_e32 v84, 27, v107
	s_nop 11
	s_branch .LBB0_1265
